# copy-forwarding of 95 plain VGPR copies into their VALU consumers + 73 self-canonicalising v_max dropped, then hazard-checked nop removal (149 more issue slots)
# baseline (speedup 1.0000x reference)
.LBB0_209:
	v_readlane_b32 s3, v248, 11
	s_mul_i32 s1, s3, 0x51000
	v_readlane_b32 s2, v251, 61
	v_mov_b32_e32 v1, v162
	s_nop 0
	s_mul_hi_u32 s0, s3, 0x51000
	s_add_u32 s16, s2, s1
	v_readlane_b32 s1, v251, 62
	s_addc_u32 s17, s1, s0
	v_ashrrev_i32_e32 v0, 6, v162
	v_readlane_b32 s0, v251, 60
	v_readlane_b32 s100, v251, 36
	s_cmpk_lg_u32 s94, 0x200
	s_cbranch_scc1 .Lnrm_orig0
	s_lshr_b32 s101, s100, 3
	s_lshl_b32 s101, s101, 2
	v_add_u32_e32 v0, s101, v0
	s_and_b32 s100, s100, 7
	s_lshl_b32 s100, s100, 7
	v_lshrrev_b32_e32 v255, 7, v0
	v_and_b32_e32 v0, 0x7f, v0
	v_lshl_add_u32 v0, v255, 10, v0
	v_add_u32_e32 v0, s100, v0
	s_branch .Lnrm_done0

.LBB0_537:
	s_cmpk_gt_i32 s2, 0x47f
	s_mov_b64 s[0:1], -1
	s_cbranch_scc0 .LBB0_586
	s_cmpk_gt_u32 s2, 0xd7f
	s_cbranch_scc0 .LBB0_544
	s_nop 0
	v_readlane_b32 s8, v251, 20
	v_and_b32_e32 v4, 63, v162
	v_or_b32_e32 v96, s44, v4
	s_waitcnt lgkmcnt(0)
	v_lshlrev_b64 v[0:1], 2, v[96:97]
	v_readlane_b32 s16, v251, 28
	v_readlane_b32 s17, v251, 29
	v_readlane_b32 s18, v251, 30
	v_readlane_b32 s19, v251, 31
	v_mov_b32_e32 v6, v162
	v_lshl_add_u64 v[2:3], s[16:17], 0, v[0:1]
	v_lshl_add_u64 v[0:1], s[18:19], 0, v[0:1]
	global_load_dword v12, v[2:3], off
	global_load_dword v13, v[0:1], off
	v_and_b32_e32 v0, 15, v162
	v_cvt_f32_ubyte0_e32 v0, v0
	v_mul_f32_e32 v1, 0xbf549a78, v0
	s_mov_b32 s0, 0xc2fc0000
	v_cmp_gt_f32_e32 vcc, s0, v1
	s_lshl_b32 s0, s2, 5
	s_add_i32 s0, s0, 0xfffe5000
	v_cndmask_b32_e32 v1, 0, v197, vcc
	v_fmac_f32_e32 v1, 0xbf549a78, v0
	v_exp_f32_e32 v0, v1
	v_cndmask_b32_e32 v1, 0, v198, vcc
	v_mbcnt_hi_u32_b32 v2, -1, v195
	v_and_b32_e32 v3, 64, v2
	v_ldexp_f32 v14, v0, v1
	v_ashrrev_i32_e32 v0, 3, v6
	v_and_b32_e32 v6, -8, v0
	v_add_u32_e32 v7, s0, v6
	v_readlane_b32 s0, v249, 13
	v_and_b32_e32 v0, 16, v162
	v_lshlrev_b32_e32 v96, 1, v4
	v_readlane_b32 s1, v249, 14
	v_add_u32_e32 v3, 64, v3
	v_xor_b32_e32 v5, 32, v2
	v_cmp_eq_u32_e32 vcc, 0, v0
	v_lshl_add_u64 v[0:1], s[0:1], 0, v[96:97]
	v_cmp_lt_i32_e64 s[0:1], v5, v3
	v_readlane_b32 s10, v251, 22
	s_mov_b32 s3, 0
	v_cndmask_b32_e64 v5, v2, v5, s[0:1]
	v_lshlrev_b32_e32 v15, 2, v5
	v_xor_b32_e32 v5, 16, v2
	v_cmp_lt_i32_e64 s[0:1], v5, v3
	v_cmp_gt_u32_e64 s[38:39], 32, v4
	v_bfe_u32 v21, v7, 6, 5
	v_cndmask_b32_e64 v5, v2, v5, s[0:1]
	v_lshlrev_b32_e32 v16, 2, v5
	v_xor_b32_e32 v5, 8, v2
	v_cmp_lt_i32_e64 s[0:1], v5, v3
	v_add_u32_e32 v22, s42, v6
	s_movk_i32 s8, 0x4000
	v_cndmask_b32_e64 v5, v2, v5, s[0:1]
	v_lshlrev_b32_e32 v17, 2, v5
	v_xor_b32_e32 v5, 4, v2
	v_cmp_lt_i32_e64 s[0:1], v5, v3
	s_mov_b32 s10, 0x3c800000
	v_readlane_b32 s9, v251, 21
	v_cndmask_b32_e64 v5, v2, v5, s[0:1]
	v_lshlrev_b32_e32 v18, 2, v5
	v_xor_b32_e32 v5, 2, v2
	v_cmp_lt_i32_e64 s[0:1], v5, v3
	v_readlane_b32 s11, v251, 23
	v_readlane_b32 s12, v251, 24
	v_cndmask_b32_e64 v5, v2, v5, s[0:1]
	v_lshlrev_b32_e32 v19, 2, v5
	v_xor_b32_e32 v5, 1, v2
	v_cmp_lt_i32_e64 s[0:1], v5, v3
	v_readlane_b32 s13, v251, 25
	v_readlane_b32 s14, v251, 26
	v_cndmask_b32_e64 v2, v2, v5, s[0:1]
	v_readlane_b32 s0, v249, 11
	v_readlane_b32 s1, v249, 12
	v_lshlrev_b32_e32 v20, 2, v2
	v_readlane_b32 s15, v251, 27
	v_lshl_add_u64 v[2:3], s[0:1], 0, v[96:97]
	v_lshlrev_b32_e32 v96, 1, v4
	v_readlane_b32 s20, v251, 32
	v_readlane_b32 s21, v251, 33
	v_readlane_b32 s22, v251, 34
	v_readlane_b32 s23, v251, 35
	s_branch .LBB0_541
.LBB0_540:
	s_or_b64 exec, exec, s[6:7]
	v_ashrrev_i32_e32 v9, 31, v8
	v_mad_i64_i32 v[6:7], s[0:1], v8, s74, v[0:1]
	v_lshlrev_b64 v[4:5], 8, v[8:9]
	v_lshlrev_b64 v[8:9], 10, v[8:9]
	v_lshl_add_u64 v[10:11], v[2:3], 0, v[8:9]
	global_load_ushort v8, v[6:7], off
	global_load_ushort v9, v[6:7], off offset:128
	global_load_ushort v78, v[6:7], off offset:256
	global_load_ushort v79, v[6:7], off offset:384
	global_load_ushort v80, v[6:7], off offset:512
	global_load_ushort v81, v[6:7], off offset:640
	global_load_ushort v82, v[6:7], off offset:768
	global_load_ushort v83, v[6:7], off offset:896
	global_load_ushort v84, v[6:7], off offset:1024
	global_load_ushort v85, v[6:7], off offset:1152
	s_mov_b32 s0, 0x358637bd
	v_lshl_add_u64 v[4:5], s[92:93], 0, v[4:5]
	v_lshl_add_u64 v[4:5], v[4:5], 0, v[96:97]
	s_mov_b32 s4, 0xc600000
	s_add_i32 s3, s3, 1
	s_cmp_lg_u32 s3, 8
	s_waitcnt vmcnt(9)
	v_lshlrev_b32_e32 v27, 16, v8
	s_waitcnt vmcnt(8)
	v_lshlrev_b32_e32 v26, 16, v9
	v_pk_mul_f32 v[8:9], v[26:27], v[26:27]
	v_mov_b32_e32 v255, v9
	s_nop 1
	v_permlane32_swap_b32_e32 v9, v255
	s_nop 1
	v_mov_b32_dpp v9, v255 quad_perm:[0,1,2,3] row_mask:0x3 bank_mask:0xf
	v_mov_b32_e32 v255, v8
	s_nop 1
	v_permlane32_swap_b32_e32 v8, v255
	s_nop 1
	v_mov_b32_dpp v8, v255 quad_perm:[0,1,2,3] row_mask:0x3 bank_mask:0xf
	s_waitcnt lgkmcnt(0)
	v_pk_fma_f32 v[8:9], v[26:27], v[26:27], v[8:9]
	v_mov_b32_e32 v29, v9
	v_mov_b32_e32 v255, v9
	s_nop 1
	v_permlane16_swap_b32_e32 v29, v255
	s_nop 1
	v_mov_b32_dpp v29, v255 quad_perm:[0,1,2,3] row_mask:0x5 bank_mask:0xf
	v_mov_b32_e32 v28, v8
	v_mov_b32_e32 v255, v8
	s_nop 1
	v_permlane16_swap_b32_e32 v28, v255
	s_nop 1
	v_mov_b32_dpp v28, v255 quad_perm:[0,1,2,3] row_mask:0x5 bank_mask:0xf
	v_pk_add_f32 v[8:9], v[8:9], v[28:29]
	s_nop 1
	v_mov_b32_dpp v29, v9 row_ror:8 row_mask:0xf bank_mask:0xf
	v_mov_b32_dpp v28, v8 row_ror:8 row_mask:0xf bank_mask:0xf
	v_pk_add_f32 v[8:9], v[8:9], v[28:29]
	s_nop 1
	v_mov_b32_dpp v29, v9 row_shl:4 row_mask:0xf bank_mask:0x5
	v_mov_b32_dpp v29, v9 row_shr:4 row_mask:0xf bank_mask:0xa
	v_mov_b32_dpp v28, v8 row_shl:4 row_mask:0xf bank_mask:0x5
	v_mov_b32_dpp v28, v8 row_shr:4 row_mask:0xf bank_mask:0xa
	v_pk_add_f32 v[8:9], v[8:9], v[28:29]
	s_nop 1
	v_mov_b32_dpp v29, v9 quad_perm:[2,3,0,1] row_mask:0xf bank_mask:0xf
	v_mov_b32_dpp v28, v8 quad_perm:[2,3,0,1] row_mask:0xf bank_mask:0xf
	v_pk_add_f32 v[8:9], v[8:9], v[28:29]
	s_nop 1
	v_mov_b32_dpp v29, v9 quad_perm:[1,0,3,2] row_mask:0xf bank_mask:0xf
	v_mov_b32_dpp v28, v8 quad_perm:[1,0,3,2] row_mask:0xf bank_mask:0xf
	v_pk_add_f32 v[28:29], v[8:9], v[28:29]
	v_mov_b64_e32 v[8:9], s[0:1]
	v_pk_fma_f32 v[28:29], v[28:29], s[10:11], v[8:9] op_sel_hi:[1,0,0]
	v_mul_f32_e32 v25, 0x4b800000, v29
	v_cmp_gt_f32_e64 s[40:41], s86, v29
	v_cmp_gt_f32_e64 s[0:1], s86, v28
	s_nop 0
	v_cndmask_b32_e64 v25, v29, v25, s[40:41]
	v_rsq_f32_e32 v25, v25
	s_nop 0
	v_mul_f32_e32 v29, 0x45800000, v25
	v_cndmask_b32_e64 v25, v25, v29, s[40:41]
	v_mul_f32_e32 v25, v25, v27
	v_mul_f32_e32 v25, v12, v25
	v_mov_b32_e32 v27, v25
	v_mov_b32_e32 v255, v25
	s_nop 1
	v_permlane16_swap_b32_e32 v27, v255
	s_nop 1
	v_mov_b32_dpp v27, v255 quad_perm:[0,1,2,3] row_mask:0x5 bank_mask:0xf
	v_mul_f32_e32 v25, v23, v25
	v_cndmask_b32_e64 v27, v27, -v27, vcc
	v_fmac_f32_e32 v25, v24, v27
	v_mul_f32_e32 v25, 0x3e000000, v25
	v_cvt_pk_bf16_f32 v25, v25, s0
	global_store_short v[10:11], v25, off
	v_mul_f32_e32 v25, 0x4b800000, v28
	v_cndmask_b32_e64 v25, v28, v25, s[0:1]
	v_rsq_f32_e32 v25, v25
	s_nop 0
	v_mul_f32_e32 v27, 0x45800000, v25
	v_cndmask_b32_e64 v25, v25, v27, s[0:1]
	v_mul_f32_e32 v25, v25, v26
	v_mul_f32_e32 v25, v12, v25
	v_mov_b32_e32 v26, v25
	v_mov_b32_e32 v255, v25
	s_nop 1
	v_permlane16_swap_b32_e32 v26, v255
	s_nop 1
	v_mov_b32_dpp v26, v255 quad_perm:[0,1,2,3] row_mask:0x5 bank_mask:0xf
	v_mul_f32_e32 v25, v23, v25
	v_cndmask_b32_e64 v26, v26, -v26, vcc
	v_fmac_f32_e32 v25, v24, v26
	v_mul_f32_e32 v25, 0x3e000000, v25
	v_cvt_pk_bf16_f32 v25, v25, s0
	global_store_short v[10:11], v25, off offset:128
	s_waitcnt vmcnt(9)
	v_lshlrev_b32_e32 v27, 16, v78
	s_waitcnt vmcnt(8)
	v_lshlrev_b32_e32 v26, 16, v79
	v_pk_mul_f32 v[28:29], v[26:27], v[26:27]
	v_mov_b32_e32 v255, v29
	s_nop 1
	v_permlane32_swap_b32_e32 v29, v255
	s_nop 1
	v_mov_b32_dpp v29, v255 quad_perm:[0,1,2,3] row_mask:0x3 bank_mask:0xf
	v_mov_b32_e32 v255, v28
	s_nop 1
	v_permlane32_swap_b32_e32 v28, v255
	s_nop 1
	v_mov_b32_dpp v28, v255 quad_perm:[0,1,2,3] row_mask:0x3 bank_mask:0xf
	v_pk_fma_f32 v[28:29], v[26:27], v[26:27], v[28:29]
	v_mov_b32_e32 v31, v29
	v_mov_b32_e32 v255, v29
	s_nop 1
	v_permlane16_swap_b32_e32 v31, v255
	s_nop 1
	v_mov_b32_dpp v31, v255 quad_perm:[0,1,2,3] row_mask:0x5 bank_mask:0xf
	v_mov_b32_e32 v30, v28
	v_mov_b32_e32 v255, v28
	s_nop 1
	v_permlane16_swap_b32_e32 v30, v255
	s_nop 1
	v_mov_b32_dpp v30, v255 quad_perm:[0,1,2,3] row_mask:0x5 bank_mask:0xf
	v_pk_add_f32 v[28:29], v[28:29], v[30:31]
	s_nop 1
	v_mov_b32_dpp v31, v29 row_ror:8 row_mask:0xf bank_mask:0xf
	v_mov_b32_dpp v30, v28 row_ror:8 row_mask:0xf bank_mask:0xf
	v_pk_add_f32 v[28:29], v[28:29], v[30:31]
	s_nop 1
	v_mov_b32_dpp v31, v29 row_shl:4 row_mask:0xf bank_mask:0x5
	v_mov_b32_dpp v31, v29 row_shr:4 row_mask:0xf bank_mask:0xa
	v_mov_b32_dpp v30, v28 row_shl:4 row_mask:0xf bank_mask:0x5
	v_mov_b32_dpp v30, v28 row_shr:4 row_mask:0xf bank_mask:0xa
	v_pk_add_f32 v[28:29], v[28:29], v[30:31]
	s_nop 1
	v_mov_b32_dpp v31, v29 quad_perm:[2,3,0,1] row_mask:0xf bank_mask:0xf
	v_mov_b32_dpp v30, v28 quad_perm:[2,3,0,1] row_mask:0xf bank_mask:0xf
	v_pk_add_f32 v[28:29], v[28:29], v[30:31]
	s_nop 1
	v_mov_b32_dpp v31, v29 quad_perm:[1,0,3,2] row_mask:0xf bank_mask:0xf
	v_mov_b32_dpp v30, v28 quad_perm:[1,0,3,2] row_mask:0xf bank_mask:0xf
	v_pk_add_f32 v[28:29], v[28:29], v[30:31]
	v_pk_fma_f32 v[28:29], v[28:29], s[10:11], v[8:9] op_sel_hi:[1,0,0]
	v_mul_f32_e32 v25, 0x4b800000, v29
	v_cmp_gt_f32_e64 s[40:41], s86, v29
	v_cmp_gt_f32_e64 s[0:1], s86, v28
	s_nop 0
	v_cndmask_b32_e64 v25, v29, v25, s[40:41]
	v_rsq_f32_e32 v25, v25
	s_nop 0
	v_mul_f32_e32 v29, 0x45800000, v25
	v_cndmask_b32_e64 v25, v25, v29, s[40:41]
	v_mul_f32_e32 v25, v25, v27
	v_mul_f32_e32 v25, v12, v25
	v_mov_b32_e32 v27, v25
	v_mov_b32_e32 v255, v25
	s_nop 1
	v_permlane16_swap_b32_e32 v27, v255
	s_nop 1
	v_mov_b32_dpp v27, v255 quad_perm:[0,1,2,3] row_mask:0x5 bank_mask:0xf
	v_mul_f32_e32 v25, v23, v25
	v_cndmask_b32_e64 v27, v27, -v27, vcc
	v_fmac_f32_e32 v25, v24, v27
	v_mul_f32_e32 v25, 0x3e000000, v25
	v_cvt_pk_bf16_f32 v25, v25, s0
	global_store_short v[10:11], v25, off offset:256
	v_mul_f32_e32 v25, 0x4b800000, v28
	v_cndmask_b32_e64 v25, v28, v25, s[0:1]
	v_rsq_f32_e32 v25, v25
	s_nop 0
	v_mul_f32_e32 v27, 0x45800000, v25
	v_cndmask_b32_e64 v25, v25, v27, s[0:1]
	v_mul_f32_e32 v25, v25, v26
	v_mul_f32_e32 v25, v12, v25
	v_mov_b32_e32 v26, v25
	v_mov_b32_e32 v255, v25
	s_nop 1
	v_permlane16_swap_b32_e32 v26, v255
	s_nop 1
	v_mov_b32_dpp v26, v255 quad_perm:[0,1,2,3] row_mask:0x5 bank_mask:0xf
	v_mul_f32_e32 v25, v23, v25
	v_cndmask_b32_e64 v26, v26, -v26, vcc
	v_fmac_f32_e32 v25, v24, v26
	v_mul_f32_e32 v25, 0x3e000000, v25
	v_cvt_pk_bf16_f32 v25, v25, s0
	global_store_short v[10:11], v25, off offset:384
	s_waitcnt vmcnt(9)
	v_lshlrev_b32_e32 v27, 16, v80
	s_waitcnt vmcnt(8)
	v_lshlrev_b32_e32 v26, 16, v81
	v_pk_mul_f32 v[28:29], v[26:27], v[26:27]
	v_mov_b32_e32 v255, v29
	s_nop 1
	v_permlane32_swap_b32_e32 v29, v255
	s_nop 1
	v_mov_b32_dpp v29, v255 quad_perm:[0,1,2,3] row_mask:0x3 bank_mask:0xf
	v_mov_b32_e32 v255, v28
	s_nop 1
	v_permlane32_swap_b32_e32 v28, v255
	s_nop 1
	v_mov_b32_dpp v28, v255 quad_perm:[0,1,2,3] row_mask:0x3 bank_mask:0xf
	v_pk_fma_f32 v[28:29], v[26:27], v[26:27], v[28:29]
	v_mov_b32_e32 v31, v29
	v_mov_b32_e32 v255, v29
	s_nop 1
	v_permlane16_swap_b32_e32 v31, v255
	s_nop 1
	v_mov_b32_dpp v31, v255 quad_perm:[0,1,2,3] row_mask:0x5 bank_mask:0xf
	v_mov_b32_e32 v30, v28
	v_mov_b32_e32 v255, v28
	s_nop 1
	v_permlane16_swap_b32_e32 v30, v255
	s_nop 1
	v_mov_b32_dpp v30, v255 quad_perm:[0,1,2,3] row_mask:0x5 bank_mask:0xf
	v_pk_add_f32 v[28:29], v[28:29], v[30:31]
	s_nop 1
	v_mov_b32_dpp v31, v29 row_ror:8 row_mask:0xf bank_mask:0xf
	v_mov_b32_dpp v30, v28 row_ror:8 row_mask:0xf bank_mask:0xf
	v_pk_add_f32 v[28:29], v[28:29], v[30:31]
	s_nop 1
	v_mov_b32_dpp v31, v29 row_shl:4 row_mask:0xf bank_mask:0x5
	v_mov_b32_dpp v31, v29 row_shr:4 row_mask:0xf bank_mask:0xa
	v_mov_b32_dpp v30, v28 row_shl:4 row_mask:0xf bank_mask:0x5
	v_mov_b32_dpp v30, v28 row_shr:4 row_mask:0xf bank_mask:0xa
	v_pk_add_f32 v[28:29], v[28:29], v[30:31]
	s_nop 1
	v_mov_b32_dpp v31, v29 quad_perm:[2,3,0,1] row_mask:0xf bank_mask:0xf
	v_mov_b32_dpp v30, v28 quad_perm:[2,3,0,1] row_mask:0xf bank_mask:0xf
	v_pk_add_f32 v[28:29], v[28:29], v[30:31]
	s_nop 1
	v_mov_b32_dpp v31, v29 quad_perm:[1,0,3,2] row_mask:0xf bank_mask:0xf
	v_mov_b32_dpp v30, v28 quad_perm:[1,0,3,2] row_mask:0xf bank_mask:0xf
	v_pk_add_f32 v[28:29], v[28:29], v[30:31]
	v_pk_fma_f32 v[28:29], v[28:29], s[10:11], v[8:9] op_sel_hi:[1,0,0]
	v_mul_f32_e32 v25, 0x4b800000, v29
	v_cmp_gt_f32_e64 s[40:41], s86, v29
	v_cmp_gt_f32_e64 s[0:1], s86, v28
	s_nop 0
	v_cndmask_b32_e64 v25, v29, v25, s[40:41]
	v_rsq_f32_e32 v25, v25
	s_nop 0
	v_mul_f32_e32 v29, 0x45800000, v25
	v_cndmask_b32_e64 v25, v25, v29, s[40:41]
	v_mul_f32_e32 v25, v25, v27
	v_mul_f32_e32 v25, v12, v25
	v_mov_b32_e32 v27, v25
	v_mov_b32_e32 v255, v25
	s_nop 1
	v_permlane16_swap_b32_e32 v27, v255
	s_nop 1
	v_mov_b32_dpp v27, v255 quad_perm:[0,1,2,3] row_mask:0x5 bank_mask:0xf
	v_mul_f32_e32 v25, v23, v25
	v_cndmask_b32_e64 v27, v27, -v27, vcc
	v_fmac_f32_e32 v25, v24, v27
	v_mul_f32_e32 v25, 0x3e000000, v25
	v_cvt_pk_bf16_f32 v25, v25, s0
	global_store_short v[10:11], v25, off offset:512
	v_mul_f32_e32 v25, 0x4b800000, v28
	v_cndmask_b32_e64 v25, v28, v25, s[0:1]
	v_rsq_f32_e32 v25, v25
	s_nop 0
	v_mul_f32_e32 v27, 0x45800000, v25
	v_cndmask_b32_e64 v25, v25, v27, s[0:1]
	v_mul_f32_e32 v25, v25, v26
	v_mul_f32_e32 v25, v12, v25
	v_mov_b32_e32 v26, v25
	v_mov_b32_e32 v255, v25
	s_nop 1
	v_permlane16_swap_b32_e32 v26, v255
	s_nop 1
	v_mov_b32_dpp v26, v255 quad_perm:[0,1,2,3] row_mask:0x5 bank_mask:0xf
	v_mul_f32_e32 v25, v23, v25
	v_cndmask_b32_e64 v26, v26, -v26, vcc
	v_fmac_f32_e32 v25, v24, v26
	v_mul_f32_e32 v25, 0x3e000000, v25
	v_cvt_pk_bf16_f32 v25, v25, s0
	global_store_short v[10:11], v25, off offset:640
	s_waitcnt vmcnt(9)
	v_lshlrev_b32_e32 v27, 16, v82
	s_waitcnt vmcnt(8)
	v_lshlrev_b32_e32 v26, 16, v83
	v_pk_mul_f32 v[28:29], v[26:27], v[26:27]
	v_mov_b32_e32 v255, v29
	s_nop 1
	v_permlane32_swap_b32_e32 v29, v255
	s_nop 1
	v_mov_b32_dpp v29, v255 quad_perm:[0,1,2,3] row_mask:0x3 bank_mask:0xf
	v_mov_b32_e32 v255, v28
	s_nop 1
	v_permlane32_swap_b32_e32 v28, v255
	s_nop 1
	v_mov_b32_dpp v28, v255 quad_perm:[0,1,2,3] row_mask:0x3 bank_mask:0xf
	v_pk_fma_f32 v[28:29], v[26:27], v[26:27], v[28:29]
	v_mov_b32_e32 v31, v29
	v_mov_b32_e32 v255, v29
	s_nop 1
	v_permlane16_swap_b32_e32 v31, v255
	s_nop 1
	v_mov_b32_dpp v31, v255 quad_perm:[0,1,2,3] row_mask:0x5 bank_mask:0xf
	v_mov_b32_e32 v30, v28
	v_mov_b32_e32 v255, v28
	s_nop 1
	v_permlane16_swap_b32_e32 v30, v255
	s_nop 1
	v_mov_b32_dpp v30, v255 quad_perm:[0,1,2,3] row_mask:0x5 bank_mask:0xf
	v_pk_add_f32 v[28:29], v[28:29], v[30:31]
	s_nop 1
	v_mov_b32_dpp v31, v29 row_ror:8 row_mask:0xf bank_mask:0xf
	v_mov_b32_dpp v30, v28 row_ror:8 row_mask:0xf bank_mask:0xf
	v_pk_add_f32 v[28:29], v[28:29], v[30:31]
	s_nop 1
	v_mov_b32_dpp v31, v29 row_shl:4 row_mask:0xf bank_mask:0x5
	v_mov_b32_dpp v31, v29 row_shr:4 row_mask:0xf bank_mask:0xa
	v_mov_b32_dpp v30, v28 row_shl:4 row_mask:0xf bank_mask:0x5
	v_mov_b32_dpp v30, v28 row_shr:4 row_mask:0xf bank_mask:0xa
	v_pk_add_f32 v[28:29], v[28:29], v[30:31]
	s_nop 1
	v_mov_b32_dpp v31, v29 quad_perm:[2,3,0,1] row_mask:0xf bank_mask:0xf
	v_mov_b32_dpp v30, v28 quad_perm:[2,3,0,1] row_mask:0xf bank_mask:0xf
	v_pk_add_f32 v[28:29], v[28:29], v[30:31]
	s_nop 1
	v_mov_b32_dpp v31, v29 quad_perm:[1,0,3,2] row_mask:0xf bank_mask:0xf
	v_mov_b32_dpp v30, v28 quad_perm:[1,0,3,2] row_mask:0xf bank_mask:0xf
	v_pk_add_f32 v[28:29], v[28:29], v[30:31]
	v_pk_fma_f32 v[28:29], v[28:29], s[10:11], v[8:9] op_sel_hi:[1,0,0]
	v_mul_f32_e32 v25, 0x4b800000, v29
	v_cmp_gt_f32_e64 s[40:41], s86, v29
	v_cmp_gt_f32_e64 s[0:1], s86, v28
	s_nop 0
	v_cndmask_b32_e64 v25, v29, v25, s[40:41]
	v_rsq_f32_e32 v25, v25
	s_nop 0
	v_mul_f32_e32 v29, 0x45800000, v25
	v_cndmask_b32_e64 v25, v25, v29, s[40:41]
	v_mul_f32_e32 v25, v25, v27
	v_mul_f32_e32 v25, v12, v25
	v_mov_b32_e32 v27, v25
	v_mov_b32_e32 v255, v25
	s_nop 1
	v_permlane16_swap_b32_e32 v27, v255
	s_nop 1
	v_mov_b32_dpp v27, v255 quad_perm:[0,1,2,3] row_mask:0x5 bank_mask:0xf
	v_mul_f32_e32 v25, v23, v25
	v_cndmask_b32_e64 v27, v27, -v27, vcc
	v_fmac_f32_e32 v25, v24, v27
	v_mul_f32_e32 v25, 0x3e000000, v25
	v_cvt_pk_bf16_f32 v25, v25, s0
	global_store_short v[10:11], v25, off offset:768
	v_mul_f32_e32 v25, 0x4b800000, v28
	v_cndmask_b32_e64 v25, v28, v25, s[0:1]
	v_rsq_f32_e32 v25, v25
	s_nop 0
	v_mul_f32_e32 v27, 0x45800000, v25
	v_cndmask_b32_e64 v25, v25, v27, s[0:1]
	v_mul_f32_e32 v25, v25, v26
	v_mul_f32_e32 v25, v12, v25
	v_mov_b32_e32 v26, v25
	v_mov_b32_e32 v255, v25
	s_nop 1
	v_permlane16_swap_b32_e32 v26, v255
	s_nop 1
	v_mov_b32_dpp v26, v255 quad_perm:[0,1,2,3] row_mask:0x5 bank_mask:0xf
	v_mul_f32_e32 v25, v23, v25
	v_cndmask_b32_e64 v26, v26, -v26, vcc
	v_fmac_f32_e32 v25, v24, v26
	v_mul_f32_e32 v25, 0x3e000000, v25
	v_cvt_pk_bf16_f32 v25, v25, s0
	global_store_short v[10:11], v25, off offset:896
	s_waitcnt vmcnt(9)
	v_lshlrev_b32_e32 v7, 16, v84
	s_waitcnt vmcnt(8)
	v_lshlrev_b32_e32 v6, 16, v85
	v_pk_mul_f32 v[10:11], v[6:7], v[6:7]
	v_mov_b32_e32 v255, v11
	s_nop 1
	v_permlane32_swap_b32_e32 v11, v255
	s_nop 1
	v_mov_b32_dpp v11, v255 quad_perm:[0,1,2,3] row_mask:0x3 bank_mask:0xf
	v_mov_b32_e32 v255, v10
	s_nop 1
	v_permlane32_swap_b32_e32 v10, v255
	s_nop 1
	v_mov_b32_dpp v10, v255 quad_perm:[0,1,2,3] row_mask:0x3 bank_mask:0xf
	v_pk_fma_f32 v[10:11], v[6:7], v[6:7], v[10:11]
	v_mov_b32_e32 v27, v11
	v_mov_b32_e32 v255, v11
	s_nop 1
	v_permlane16_swap_b32_e32 v27, v255
	s_nop 1
	v_mov_b32_dpp v27, v255 quad_perm:[0,1,2,3] row_mask:0x5 bank_mask:0xf
	v_mov_b32_e32 v26, v10
	v_mov_b32_e32 v255, v10
	s_nop 1
	v_permlane16_swap_b32_e32 v26, v255
	s_nop 1
	v_mov_b32_dpp v26, v255 quad_perm:[0,1,2,3] row_mask:0x5 bank_mask:0xf
	v_pk_add_f32 v[10:11], v[10:11], v[26:27]
	s_nop 1
	v_mov_b32_dpp v27, v11 row_ror:8 row_mask:0xf bank_mask:0xf
	v_mov_b32_dpp v26, v10 row_ror:8 row_mask:0xf bank_mask:0xf
	v_pk_add_f32 v[10:11], v[10:11], v[26:27]
	s_nop 1
	v_mov_b32_dpp v27, v11 row_shl:4 row_mask:0xf bank_mask:0x5
	v_mov_b32_dpp v27, v11 row_shr:4 row_mask:0xf bank_mask:0xa
	v_mov_b32_dpp v26, v10 row_shl:4 row_mask:0xf bank_mask:0x5
	v_mov_b32_dpp v26, v10 row_shr:4 row_mask:0xf bank_mask:0xa
	v_pk_add_f32 v[10:11], v[10:11], v[26:27]
	s_nop 1
	v_mov_b32_dpp v27, v11 quad_perm:[2,3,0,1] row_mask:0xf bank_mask:0xf
	v_mov_b32_dpp v26, v10 quad_perm:[2,3,0,1] row_mask:0xf bank_mask:0xf
	v_pk_add_f32 v[10:11], v[10:11], v[26:27]
	s_nop 1
	v_mov_b32_dpp v27, v11 quad_perm:[1,0,3,2] row_mask:0xf bank_mask:0xf
	v_mov_b32_dpp v26, v10 quad_perm:[1,0,3,2] row_mask:0xf bank_mask:0xf
	v_pk_add_f32 v[10:11], v[10:11], v[26:27]
	v_pk_fma_f32 v[8:9], v[10:11], s[10:11], v[8:9] op_sel_hi:[1,0,0]
	v_mul_f32_e32 v10, 0x4b800000, v9
	v_cmp_gt_f32_e64 s[40:41], s86, v9
	v_cmp_gt_f32_e64 s[0:1], s86, v8
	s_nop 0
	v_cndmask_b32_e64 v9, v9, v10, s[40:41]
	v_rsq_f32_e32 v9, v9
	s_nop 0
	v_mul_f32_e32 v10, 0x45800000, v9
	v_cndmask_b32_e64 v9, v9, v10, s[40:41]
	v_mul_f32_e32 v7, v9, v7
	v_mul_f32_e32 v7, v13, v7
	v_mov_b32_e32 v9, v7
	v_mov_b32_e32 v255, v7
	s_nop 1
	v_permlane16_swap_b32_e32 v9, v255
	s_nop 1
	v_mov_b32_dpp v9, v255 quad_perm:[0,1,2,3] row_mask:0x5 bank_mask:0xf
	v_mul_f32_e32 v7, v23, v7
	v_add_co_u32_e64 v4, s[40:41], s4, v4
	v_cndmask_b32_e64 v9, v9, -v9, vcc
	v_fmac_f32_e32 v7, v24, v9
	v_cvt_pk_bf16_f32 v7, v7, s0
	v_addc_co_u32_e64 v5, s[40:41], 0, v5, s[40:41]
	global_store_short v[4:5], v7, off
	v_mul_f32_e32 v7, 0x4b800000, v8
	v_cndmask_b32_e64 v7, v8, v7, s[0:1]
	v_rsq_f32_e32 v7, v7
	s_nop 0
	v_mul_f32_e32 v8, 0x45800000, v7
	v_cndmask_b32_e64 v7, v7, v8, s[0:1]
	v_mul_f32_e32 v6, v7, v6
	v_mul_f32_e32 v6, v13, v6
	v_mov_b32_e32 v7, v6
	v_mov_b32_e32 v255, v6
	s_nop 1
	v_permlane16_swap_b32_e32 v7, v255
	s_nop 1
	v_mov_b32_dpp v7, v255 quad_perm:[0,1,2,3] row_mask:0x5 bank_mask:0xf
	v_mul_f32_e32 v6, v23, v6
	v_cndmask_b32_e64 v7, v7, -v7, vcc
	v_fmac_f32_e32 v6, v24, v7
	v_cvt_pk_bf16_f32 v6, v6, s0
	global_store_short v[4:5], v6, off offset:128
	s_cbranch_scc0 .LBB0_543

.Lrg4_i:
	s_or_b64 exec, exec, s[0:1]
	s_waitcnt vmcnt(0)
	s_nop 0
	v_mov_b32_e32 v9, v207
	v_mov_b32_e32 v10, v208
	v_mov_b32_e32 v11, v209
	v_lshlrev_b32_e32 v54, 16, v206
	v_and_b32_e32 v55, 0xffff0000, v206
	v_lshlrev_b32_e32 v8, 16, v9
	v_and_b32_e32 v9, 0xffff0000, v9
	v_lshlrev_b32_e32 v12, 16, v10
	v_and_b32_e32 v13, 0xffff0000, v10
	v_lshlrev_b32_e32 v10, 16, v11
	v_and_b32_e32 v11, 0xffff0000, v11
	v_pk_fma_f32 v[14:15], v[46:47], v[10:11], v[6:7]
	v_pk_fma_f32 v[12:13], v[44:45], v[12:13], v[4:5]
	v_pk_fma_f32 v[10:11], v[42:43], v[8:9], v[2:3]
	v_pk_fma_f32 v[8:9], v[40:41], v[54:55], v[0:1]
	v_mov_b32_e32 v55, v211
	v_mov_b32_e32 v56, v212
	v_mov_b32_e32 v57, v213
	v_lshlrev_b32_e32 v58, 16, v210
	v_and_b32_e32 v59, 0xffff0000, v210
	v_lshlrev_b32_e32 v54, 16, v55
	v_and_b32_e32 v55, 0xffff0000, v55
	v_lshlrev_b32_e32 v60, 16, v56
	v_and_b32_e32 v61, 0xffff0000, v56
	v_lshlrev_b32_e32 v56, 16, v57
	v_and_b32_e32 v57, 0xffff0000, v57
	v_pk_fma_f32 v[14:15], v[38:39], v[56:57], v[14:15]
	v_pk_fma_f32 v[12:13], v[36:37], v[60:61], v[12:13]
	v_pk_fma_f32 v[10:11], v[34:35], v[54:55], v[10:11]
	v_pk_fma_f32 v[8:9], v[32:33], v[58:59], v[8:9]
	v_mov_b32_e32 v55, v215
	v_mov_b32_e32 v56, v216
	v_mov_b32_e32 v57, v217
	v_lshlrev_b32_e32 v58, 16, v214
	v_and_b32_e32 v59, 0xffff0000, v214
	v_lshlrev_b32_e32 v54, 16, v55
	v_and_b32_e32 v55, 0xffff0000, v55
	v_lshlrev_b32_e32 v60, 16, v56
	v_and_b32_e32 v61, 0xffff0000, v56
	v_lshlrev_b32_e32 v56, 16, v57
	v_and_b32_e32 v57, 0xffff0000, v57
	v_pk_fma_f32 v[14:15], v[30:31], v[56:57], v[14:15]
	v_pk_fma_f32 v[12:13], v[28:29], v[60:61], v[12:13]
	v_pk_fma_f32 v[10:11], v[26:27], v[54:55], v[10:11]
	v_pk_fma_f32 v[8:9], v[24:25], v[58:59], v[8:9]
	v_mov_b32_e32 v55, v219
	v_mov_b32_e32 v56, v220
	v_mov_b32_e32 v57, v221
	v_lshlrev_b32_e32 v58, 16, v218
	v_and_b32_e32 v59, 0xffff0000, v218
	v_lshlrev_b32_e32 v54, 16, v55
	v_and_b32_e32 v55, 0xffff0000, v55
	v_lshlrev_b32_e32 v60, 16, v56
	v_and_b32_e32 v61, 0xffff0000, v56
	v_lshlrev_b32_e32 v56, 16, v57
	v_and_b32_e32 v57, 0xffff0000, v57
	v_pk_fma_f32 v[14:15], v[22:23], v[56:57], v[14:15]
	v_pk_fma_f32 v[12:13], v[20:21], v[60:61], v[12:13]
	v_pk_fma_f32 v[10:11], v[18:19], v[54:55], v[10:11]
	v_pk_fma_f32 v[8:9], v[16:17], v[58:59], v[8:9]
	v_lshl_add_u32 v53, v50, 2, 0
	v_lshl_add_u32 v54, v52, 8, v53
	v_lshlrev_b32_e32 v50, 1, v50
	ds_write_b128 v54, v[8:11] offset:36864
	ds_write_b128 v54, v[12:15] offset:36880
	v_add_u32_e32 v54, 32, v52
	v_sub_u32_e32 v50, v53, v50
	s_movk_i32 s0, 0x90
	v_add_u32_e32 v55, s38, v54
	v_cvt_pk_bf16_f32 v8, v8, v9
	v_cvt_pk_bf16_f32 v9, v10, v11
	v_cvt_pk_bf16_f32 v10, v12, v13
	v_cvt_pk_bf16_f32 v11, v14, v15
	v_mad_u64_u32 v[12:13], s[0:1], v52, s0, v[50:51]
	v_add_u32_e32 v56, -2, v55
	ds_write_b128 v12, v[8:11]
	v_cmp_lt_i32_e32 vcc, 1, v55
	v_cmp_gt_u32_e64 s[0:1], s7, v56
	v_mov_b64_e32 v[14:15], v[6:7]
	s_and_b64 s[40:41], vcc, s[0:1]
	v_mov_b64_e32 v[12:13], v[4:5]
	v_mov_b64_e32 v[10:11], v[2:3]
	v_mov_b64_e32 v[8:9], v[0:1]
	v_mov_b32_e32 v206, 0
	v_mov_b32_e32 v207, 0
	v_mov_b32_e32 v208, 0
	v_mov_b32_e32 v209, 0
	s_and_saveexec_b64 s[0:1], s[40:41]
	s_cbranch_execz .Lrg5_i
	v_add_u32_e32 v8, s6, v56
	v_mad_u64_u32 v[8:9], s[40:41], v8, s74, v[48:49]
	global_load_dwordx4 v[206:209], v[8:9], off

.Lrg8_i:
	s_or_b64 exec, exec, s[0:1]
	s_waitcnt vmcnt(0)
	s_nop 0
	v_mov_b32_e32 v9, v207
	v_mov_b32_e32 v10, v208
	v_mov_b32_e32 v11, v209
	v_lshlrev_b32_e32 v56, 16, v206
	v_and_b32_e32 v57, 0xffff0000, v206
	v_lshlrev_b32_e32 v8, 16, v9
	v_and_b32_e32 v9, 0xffff0000, v9
	v_lshlrev_b32_e32 v12, 16, v10
	v_and_b32_e32 v13, 0xffff0000, v10
	v_lshlrev_b32_e32 v10, 16, v11
	v_and_b32_e32 v11, 0xffff0000, v11
	v_pk_fma_f32 v[14:15], v[46:47], v[10:11], v[6:7]
	v_pk_fma_f32 v[12:13], v[44:45], v[12:13], v[4:5]
	v_pk_fma_f32 v[10:11], v[42:43], v[8:9], v[2:3]
	v_pk_fma_f32 v[8:9], v[40:41], v[56:57], v[0:1]
	v_mov_b32_e32 v57, v211
	v_mov_b32_e32 v58, v212
	v_mov_b32_e32 v59, v213
	v_lshlrev_b32_e32 v60, 16, v210
	v_and_b32_e32 v61, 0xffff0000, v210
	v_lshlrev_b32_e32 v56, 16, v57
	v_and_b32_e32 v57, 0xffff0000, v57
	v_lshlrev_b32_e32 v62, 16, v58
	v_and_b32_e32 v63, 0xffff0000, v58
	v_lshlrev_b32_e32 v58, 16, v59
	v_and_b32_e32 v59, 0xffff0000, v59
	v_pk_fma_f32 v[14:15], v[38:39], v[58:59], v[14:15]
	v_pk_fma_f32 v[12:13], v[36:37], v[62:63], v[12:13]
	v_pk_fma_f32 v[10:11], v[34:35], v[56:57], v[10:11]
	v_pk_fma_f32 v[8:9], v[32:33], v[60:61], v[8:9]
	v_mov_b32_e32 v57, v215
	v_mov_b32_e32 v58, v216
	v_mov_b32_e32 v59, v217
	v_lshlrev_b32_e32 v60, 16, v214
	v_and_b32_e32 v61, 0xffff0000, v214
	v_lshlrev_b32_e32 v56, 16, v57
	v_and_b32_e32 v57, 0xffff0000, v57
	v_lshlrev_b32_e32 v62, 16, v58
	v_and_b32_e32 v63, 0xffff0000, v58
	v_lshlrev_b32_e32 v58, 16, v59
	v_and_b32_e32 v59, 0xffff0000, v59
	v_pk_fma_f32 v[14:15], v[30:31], v[58:59], v[14:15]
	v_pk_fma_f32 v[12:13], v[28:29], v[62:63], v[12:13]
	v_pk_fma_f32 v[10:11], v[26:27], v[56:57], v[10:11]
	v_pk_fma_f32 v[8:9], v[24:25], v[60:61], v[8:9]
	v_mov_b32_e32 v57, v219
	v_mov_b32_e32 v58, v220
	v_mov_b32_e32 v59, v221
	v_lshlrev_b32_e32 v60, 16, v218
	v_and_b32_e32 v61, 0xffff0000, v218
	v_lshlrev_b32_e32 v56, 16, v57
	v_and_b32_e32 v57, 0xffff0000, v57
	v_lshlrev_b32_e32 v62, 16, v58
	v_and_b32_e32 v63, 0xffff0000, v58
	v_lshlrev_b32_e32 v58, 16, v59
	v_and_b32_e32 v59, 0xffff0000, v59
	v_pk_fma_f32 v[14:15], v[22:23], v[58:59], v[14:15]
	v_pk_fma_f32 v[12:13], v[20:21], v[62:63], v[12:13]
	v_pk_fma_f32 v[10:11], v[18:19], v[56:57], v[10:11]
	v_pk_fma_f32 v[8:9], v[16:17], v[60:61], v[8:9]
	v_lshl_add_u32 v55, v54, 8, v53
	s_movk_i32 s0, 0x90
	ds_write_b128 v55, v[8:11] offset:36864
	ds_write_b128 v55, v[12:15] offset:36880
	v_cvt_pk_bf16_f32 v8, v8, v9
	v_cvt_pk_bf16_f32 v9, v10, v11
	v_cvt_pk_bf16_f32 v10, v12, v13
	v_mad_u64_u32 v[12:13], s[0:1], v54, s0, v[50:51]
	v_add_u32_e32 v54, 64, v52
	v_add_u32_e32 v55, s38, v54
	v_cvt_pk_bf16_f32 v11, v14, v15
	v_add_u32_e32 v56, -2, v55
	ds_write_b128 v12, v[8:11]
	v_cmp_lt_i32_e32 vcc, 1, v55
	v_cmp_gt_u32_e64 s[0:1], s7, v56
	v_mov_b64_e32 v[14:15], v[6:7]
	s_and_b64 s[40:41], vcc, s[0:1]
	v_mov_b64_e32 v[12:13], v[4:5]
	v_mov_b64_e32 v[10:11], v[2:3]
	v_mov_b64_e32 v[8:9], v[0:1]
	v_mov_b32_e32 v206, 0
	v_mov_b32_e32 v207, 0
	v_mov_b32_e32 v208, 0
	v_mov_b32_e32 v209, 0
	s_and_saveexec_b64 s[0:1], s[40:41]
	s_cbranch_execz .Lrg9_i
	v_add_u32_e32 v8, s6, v56
	v_mad_u64_u32 v[8:9], s[40:41], v8, s74, v[48:49]
	global_load_dwordx4 v[206:209], v[8:9], off

.Lrg12_i:
	s_or_b64 exec, exec, s[0:1]
	s_waitcnt vmcnt(0)
	s_nop 0
	v_mov_b32_e32 v9, v207
	v_mov_b32_e32 v10, v208
	v_mov_b32_e32 v11, v209
	v_lshlrev_b32_e32 v56, 16, v206
	v_and_b32_e32 v57, 0xffff0000, v206
	v_lshlrev_b32_e32 v8, 16, v9
	v_and_b32_e32 v9, 0xffff0000, v9
	v_lshlrev_b32_e32 v12, 16, v10
	v_and_b32_e32 v13, 0xffff0000, v10
	v_lshlrev_b32_e32 v10, 16, v11
	v_and_b32_e32 v11, 0xffff0000, v11
	v_pk_fma_f32 v[14:15], v[46:47], v[10:11], v[6:7]
	v_pk_fma_f32 v[12:13], v[44:45], v[12:13], v[4:5]
	v_pk_fma_f32 v[10:11], v[42:43], v[8:9], v[2:3]
	v_pk_fma_f32 v[8:9], v[40:41], v[56:57], v[0:1]
	v_mov_b32_e32 v57, v211
	v_mov_b32_e32 v58, v212
	v_mov_b32_e32 v59, v213
	v_lshlrev_b32_e32 v60, 16, v210
	v_and_b32_e32 v61, 0xffff0000, v210
	v_lshlrev_b32_e32 v56, 16, v57
	v_and_b32_e32 v57, 0xffff0000, v57
	v_lshlrev_b32_e32 v62, 16, v58
	v_and_b32_e32 v63, 0xffff0000, v58
	v_lshlrev_b32_e32 v58, 16, v59
	v_and_b32_e32 v59, 0xffff0000, v59
	v_pk_fma_f32 v[14:15], v[38:39], v[58:59], v[14:15]
	v_pk_fma_f32 v[12:13], v[36:37], v[62:63], v[12:13]
	v_pk_fma_f32 v[10:11], v[34:35], v[56:57], v[10:11]
	v_pk_fma_f32 v[8:9], v[32:33], v[60:61], v[8:9]
	v_mov_b32_e32 v57, v215
	v_mov_b32_e32 v58, v216
	v_mov_b32_e32 v59, v217
	v_lshlrev_b32_e32 v60, 16, v214
	v_and_b32_e32 v61, 0xffff0000, v214
	v_lshlrev_b32_e32 v56, 16, v57
	v_and_b32_e32 v57, 0xffff0000, v57
	v_lshlrev_b32_e32 v62, 16, v58
	v_and_b32_e32 v63, 0xffff0000, v58
	v_lshlrev_b32_e32 v58, 16, v59
	v_and_b32_e32 v59, 0xffff0000, v59
	v_pk_fma_f32 v[14:15], v[30:31], v[58:59], v[14:15]
	v_pk_fma_f32 v[12:13], v[28:29], v[62:63], v[12:13]
	v_pk_fma_f32 v[10:11], v[26:27], v[56:57], v[10:11]
	v_pk_fma_f32 v[8:9], v[24:25], v[60:61], v[8:9]
	v_mov_b32_e32 v57, v219
	v_mov_b32_e32 v58, v220
	v_mov_b32_e32 v59, v221
	v_lshlrev_b32_e32 v60, 16, v218
	v_and_b32_e32 v61, 0xffff0000, v218
	v_lshlrev_b32_e32 v56, 16, v57
	v_and_b32_e32 v57, 0xffff0000, v57
	v_lshlrev_b32_e32 v62, 16, v58
	v_and_b32_e32 v63, 0xffff0000, v58
	v_lshlrev_b32_e32 v58, 16, v59
	v_and_b32_e32 v59, 0xffff0000, v59
	v_pk_fma_f32 v[14:15], v[22:23], v[58:59], v[14:15]
	v_pk_fma_f32 v[12:13], v[20:21], v[62:63], v[12:13]
	v_pk_fma_f32 v[10:11], v[18:19], v[56:57], v[10:11]
	v_pk_fma_f32 v[8:9], v[16:17], v[60:61], v[8:9]
	v_lshl_add_u32 v55, v54, 8, v53
	s_movk_i32 s0, 0x90
	ds_write_b128 v55, v[8:11] offset:36864
	ds_write_b128 v55, v[12:15] offset:36880
	v_cvt_pk_bf16_f32 v8, v8, v9
	v_cvt_pk_bf16_f32 v9, v10, v11
	v_cvt_pk_bf16_f32 v10, v12, v13
	v_cvt_pk_bf16_f32 v11, v14, v15
	v_mad_u64_u32 v[12:13], s[0:1], v54, s0, v[50:51]
	ds_write_b128 v12, v[8:11]
	v_add_u32_e32 v8, 0x60, v52
	v_add_u32_e32 v9, s38, v8
	v_add_u32_e32 v10, -2, v9
	v_cmp_lt_i32_e32 vcc, 1, v9
	v_cmp_gt_u32_e64 s[0:1], s7, v10
	s_and_b64 s[38:39], vcc, s[0:1]
	v_mov_b32_e32 v206, 0
	v_mov_b32_e32 v207, 0
	v_mov_b32_e32 v208, 0
	v_mov_b32_e32 v209, 0
	s_and_saveexec_b64 s[0:1], s[38:39]
	s_cbranch_execz .Lrg13_i
	v_add_u32_e32 v10, s6, v10
	v_mad_u64_u32 v[10:11], s[38:39], v10, s74, v[48:49]
	global_load_dwordx4 v[206:209], v[10:11], off

.Lrg16_i:
	s_or_b64 exec, exec, s[0:1]
	s_waitcnt vmcnt(0)
	s_nop 0
	v_mov_b32_e32 v11, v207
	v_mov_b32_e32 v12, v208
	v_mov_b32_e32 v13, v209
	v_lshlrev_b32_e32 v14, 16, v206
	v_and_b32_e32 v15, 0xffff0000, v206
	v_lshlrev_b32_e32 v10, 16, v11
	v_and_b32_e32 v11, 0xffff0000, v11
	v_lshlrev_b32_e32 v54, 16, v12
	v_and_b32_e32 v55, 0xffff0000, v12
	v_lshlrev_b32_e32 v12, 16, v13
	v_and_b32_e32 v13, 0xffff0000, v13
	v_pk_fma_f32 v[6:7], v[46:47], v[12:13], v[6:7]
	v_pk_fma_f32 v[4:5], v[44:45], v[54:55], v[4:5]
	v_pk_fma_f32 v[2:3], v[42:43], v[10:11], v[2:3]
	v_pk_fma_f32 v[0:1], v[40:41], v[14:15], v[0:1]
	v_mov_b32_e32 v11, v211
	v_mov_b32_e32 v12, v212
	v_mov_b32_e32 v13, v213
	v_lshlrev_b32_e32 v14, 16, v210
	v_and_b32_e32 v15, 0xffff0000, v210
	v_lshlrev_b32_e32 v10, 16, v11
	v_and_b32_e32 v11, 0xffff0000, v11
	v_lshlrev_b32_e32 v40, 16, v12
	v_and_b32_e32 v41, 0xffff0000, v12
	v_lshlrev_b32_e32 v12, 16, v13
	v_and_b32_e32 v13, 0xffff0000, v13
	v_pk_fma_f32 v[6:7], v[38:39], v[12:13], v[6:7]
	v_pk_fma_f32 v[4:5], v[36:37], v[40:41], v[4:5]
	v_pk_fma_f32 v[2:3], v[34:35], v[10:11], v[2:3]
	v_pk_fma_f32 v[0:1], v[32:33], v[14:15], v[0:1]
	v_mov_b32_e32 v11, v215
	v_mov_b32_e32 v12, v216
	v_mov_b32_e32 v13, v217
	v_lshlrev_b32_e32 v14, 16, v214
	v_and_b32_e32 v15, 0xffff0000, v214
	v_lshlrev_b32_e32 v10, 16, v11
	v_and_b32_e32 v11, 0xffff0000, v11
	v_lshlrev_b32_e32 v32, 16, v12
	v_and_b32_e32 v33, 0xffff0000, v12
	v_lshlrev_b32_e32 v12, 16, v13
	v_and_b32_e32 v13, 0xffff0000, v13
	v_pk_fma_f32 v[6:7], v[30:31], v[12:13], v[6:7]
	v_pk_fma_f32 v[4:5], v[28:29], v[32:33], v[4:5]
	v_pk_fma_f32 v[2:3], v[26:27], v[10:11], v[2:3]
	v_pk_fma_f32 v[0:1], v[24:25], v[14:15], v[0:1]
	v_mov_b32_e32 v11, v219
	v_mov_b32_e32 v12, v220
	v_mov_b32_e32 v13, v221
	v_lshlrev_b32_e32 v14, 16, v218
	v_and_b32_e32 v15, 0xffff0000, v218
	v_lshlrev_b32_e32 v10, 16, v11
	v_and_b32_e32 v11, 0xffff0000, v11
	v_lshlrev_b32_e32 v24, 16, v12
	v_and_b32_e32 v25, 0xffff0000, v12
	v_lshlrev_b32_e32 v12, 16, v13
	v_and_b32_e32 v13, 0xffff0000, v13
	v_pk_fma_f32 v[6:7], v[22:23], v[12:13], v[6:7]
	v_pk_fma_f32 v[4:5], v[20:21], v[24:25], v[4:5]
	v_pk_fma_f32 v[2:3], v[18:19], v[10:11], v[2:3]
	v_pk_fma_f32 v[0:1], v[16:17], v[14:15], v[0:1]
	s_and_b32 s38, s2, 1
	v_lshl_add_u32 v10, v8, 8, v53
	s_movk_i32 s0, 0x90
	ds_write_b128 v10, v[0:3] offset:36864
	ds_write_b128 v10, v[4:7] offset:36880
	v_cvt_pk_bf16_f32 v0, v0, v1
	v_cvt_pk_bf16_f32 v1, v2, v3
	v_cvt_pk_bf16_f32 v2, v4, v5
	v_mad_u64_u32 v[4:5], s[0:1], v8, s0, v[50:51]
	s_or_b32 s39, s38, s46
	s_lshl_b32 s0, s39, 15
	s_lshl_b32 s1, s4, 12
	s_or_b32 s4, s0, s1
	v_readlane_b32 s8, v251, 4
	s_lshl_b64 s[6:7], s[4:5], 2
	v_readlane_b32 s18, v251, 14
	v_readlane_b32 s19, v251, 15
	s_add_u32 s0, s18, s6
	v_readlane_b32 s22, v251, 18
	s_addc_u32 s1, s19, s7
	v_and_b32_e32 v9, 63, v51
	v_cvt_pk_bf16_f32 v3, v6, v7
	v_ashrrev_i32_e32 v64, 6, v51
	v_readlane_b32 s23, v251, 19
	s_add_u32 s6, s22, s6
	ds_write_b128 v4, v[0:3]
	s_addc_u32 s7, s23, s7
	v_mul_u32_u24_e32 v1, 0x90, v9
	v_lshlrev_b32_e32 v2, 2, v64
	s_add_i32 s4, 0, 0x4800
	v_lshl_or_b32 v0, v64, 7, v9
	v_add3_u32 v1, v1, v2, s4
	s_mov_b32 s4, 0
	v_readlane_b32 s9, v251, 5
	v_readlane_b32 s10, v251, 6
	v_readlane_b32 s11, v251, 7
	v_readlane_b32 s12, v251, 8
	v_readlane_b32 s13, v251, 9
	v_readlane_b32 s14, v251, 10
	v_readlane_b32 s15, v251, 11
	v_readlane_b32 s16, v251, 12
	v_readlane_b32 s17, v251, 13
	v_readlane_b32 s20, v251, 16
	v_readlane_b32 s21, v251, 17

.LBB0_580:
	v_add_u32_e32 v68, v67, v65
	ds_read_b128 v[72:75], v67 offset:18432
	ds_read_b128 v[76:79], v68
	s_add_i32 s0, s0, 32
	s_cmp_lt_u32 s0, 48
	s_waitcnt lgkmcnt(0)
	v_mfma_f32_32x32x16_bf16 v[48:63], v[76:79], v[72:75], v[48:63]
	ds_read_b128 v[72:75], v67 offset:23040
	s_waitcnt lgkmcnt(0)
	v_mfma_f32_32x32x16_bf16 v[16:31], v[76:79], v[72:75], v[16:31]
	ds_read_b128 v[72:75], v67 offset:27648
	s_waitcnt lgkmcnt(0)
	v_mfma_f32_32x32x16_bf16 v[32:47], v[76:79], v[72:75], v[32:47]
	ds_read_b128 v[72:75], v67 offset:32256
	ds_read_b128 v[80:83], v67 offset:18464
	s_waitcnt lgkmcnt(1)
	v_mfma_f32_32x32x16_bf16 v[0:15], v[76:79], v[72:75], v[0:15]
	ds_read_b128 v[72:75], v68 offset:32
	ds_read_b128 v[76:79], v67 offset:23072
	s_waitcnt lgkmcnt(0)
	v_mfma_f32_32x32x16_bf16 v[16:31], v[72:75], v[76:79], v[16:31]
	ds_read_b128 v[76:79], v67 offset:27680
	s_waitcnt lgkmcnt(0)
	v_mfma_f32_32x32x16_bf16 v[32:47], v[72:75], v[76:79], v[32:47]
	ds_read_b128 v[76:79], v67 offset:32288
	v_add_u32_e32 v67, 64, v67
	v_mfma_f32_32x32x16_bf16 v[48:63], v[72:75], v[80:83], v[48:63]
	s_waitcnt lgkmcnt(0)
	v_mfma_f32_32x32x16_bf16 v[0:15], v[72:75], v[76:79], v[0:15]
	s_cbranch_scc1 .LBB0_580
	s_lshl_b32 s0, s39, 9
	s_or_b32 s6, s0, s3
	v_or_b32_e32 v96, s6, v71
	v_readlane_b32 s8, v251, 20
	v_lshlrev_b32_e32 v67, 11, v64
	v_lshlrev_b64 v[64:65], 2, v[96:97]
	v_readlane_b32 s10, v251, 22
	v_readlane_b32 s11, v251, 23
	s_barrier
	s_nop 0
	v_lshl_add_u64 v[68:69], s[10:11], 0, v[64:65]
	v_readlane_b32 s100, v251, 16
	v_readlane_b32 s101, v251, 17
	s_nop 1
	v_lshl_add_u64 v[220:221], s[100:101], 0, v[64:65]
	v_readlane_b32 s100, v251, 20
	v_readlane_b32 s101, v251, 21
	s_nop 1
	v_lshl_add_u64 v[222:223], s[100:101], 0, v[64:65]
	global_load_dword v224, v[220:221], off
	global_load_dword v225, v[222:223], off
	global_load_dword v226, v[68:69], off offset:128
	global_load_dword v227, v[222:223], off offset:128
	global_load_dword v228, v[220:221], off offset:128
	global_load_dword v68, v[68:69], off
	s_mov_b32 s7, 0x3f2aaaab
	s_mov_b32 s39, 0x3f317218
	v_readlane_b32 s12, v251, 24
	v_readlane_b32 s13, v251, 25
	v_readlane_b32 s14, v251, 26
	v_readlane_b32 s15, v251, 27
	v_readlane_b32 s16, v251, 28
	v_readlane_b32 s17, v251, 29
	v_readlane_b32 s18, v251, 30
	v_readlane_b32 s19, v251, 31
	v_readlane_b32 s20, v251, 32
	v_readlane_b32 s21, v251, 33
	v_readlane_b32 s22, v251, 34
	v_readlane_b32 s23, v251, 35
	v_readlane_b32 s12, v251, 4
	v_readlane_b32 s24, v251, 16
	v_readlane_b32 s25, v251, 17
	v_readlane_b32 s9, v251, 21
	s_mov_b32 s40, 0x7f800000
	s_mov_b32 s41, 0x33800000
	v_readlane_b32 s15, v251, 7
	s_mov_b32 s15, 0x43000000
	v_readlane_b32 s16, v251, 8
	s_mov_b32 s16, 0x42b17217
	v_readlane_b32 s17, v251, 9
	s_mov_b32 s17, 0xf800000
	v_readlane_b32 s18, v251, 10
	s_mov_b32 s18, 0xc1880000
	v_add_u32_e32 v96, s6, v71
	s_cmp_eq_u32 s38, 0
	s_mov_b32 s4, 0
	v_readlane_b32 s13, v251, 5
	v_readlane_b32 s14, v251, 6
	v_readlane_b32 s19, v251, 11
	v_readlane_b32 s20, v251, 12
	v_readlane_b32 s21, v251, 13
	v_readlane_b32 s22, v251, 14
	v_readlane_b32 s23, v251, 15
	v_readlane_b32 s26, v251, 18
	v_readlane_b32 s27, v251, 19
	s_waitcnt vmcnt(0)
	v_mul_f32_e32 v68, 0xbfb8aa3b, v68
	v_exp_f32_e32 v70, v68
	s_nop 0
	v_add_f32_e32 v72, 1.0, v70
	v_add_f32_e32 v68, -1.0, v72
	v_sub_f32_e32 v69, v68, v72
	v_add_f32_e32 v69, 1.0, v69
	v_sub_f32_e32 v68, v70, v68
	v_add_f32_e32 v73, v68, v69
	v_frexp_mant_f32_e32 v68, v72
	v_cmp_gt_f32_e32 vcc, s7, v68
	v_cvt_f64_f32_e32 v[68:69], v72
	v_frexp_exp_i32_f64_e32 v68, v[68:69]
	v_subbrev_co_u32_e32 v78, vcc, 0, v68, vcc
	v_sub_u32_e32 v68, 0, v78
	v_ldexp_f32 v69, v72, v68
	v_add_f32_e32 v72, -1.0, v69
	v_add_f32_e32 v74, 1.0, v69
	v_ldexp_f32 v68, v73, v68
	v_add_f32_e32 v73, 1.0, v72
	v_add_f32_e32 v75, -1.0, v74
	v_sub_f32_e32 v73, v69, v73
	v_sub_f32_e32 v69, v69, v75
	v_add_f32_e32 v73, v68, v73
	v_add_f32_e32 v68, v68, v69
	v_add_f32_e32 v79, v74, v68
	v_rcp_f32_e32 v81, v79
	v_sub_f32_e32 v69, v79, v74
	v_sub_f32_e32 v80, v68, v69
	v_add_f32_e32 v69, v72, v73
	v_mul_f32_e32 v83, v69, v81
	v_sub_f32_e32 v68, v69, v72
	v_mul_f32_e32 v72, v79, v83
	v_fma_f32 v74, v83, v79, -v72
	v_fmac_f32_e32 v74, v83, v80
	v_sub_f32_e32 v82, v73, v68
	v_add_f32_e32 v68, v72, v74
	v_sub_f32_e32 v73, v69, v68
	v_pk_add_f32 v[76:77], v[68:69], v[72:73] neg_lo:[0,1] neg_hi:[0,1]
	v_mov_b32_e32 v75, v68
	v_pk_add_f32 v[68:69], v[76:77], v[74:75] neg_lo:[0,1] neg_hi:[0,1]
	v_cmp_neq_f32_e32 vcc, s40, v70
	v_add_f32_e32 v69, v82, v69
	v_add_f32_e32 v68, v68, v69
	v_add_f32_e32 v69, v73, v68
	v_mul_f32_e32 v82, v81, v69
	v_mul_f32_e32 v72, v79, v82
	v_fma_f32 v74, v82, v79, -v72
	v_fmac_f32_e32 v74, v82, v80
	v_sub_f32_e32 v73, v73, v69
	v_add_f32_e32 v79, v68, v73
	v_add_f32_e32 v68, v72, v74
	v_sub_f32_e32 v73, v69, v68
	v_pk_add_f32 v[76:77], v[68:69], v[72:73] neg_lo:[0,1] neg_hi:[0,1]
	v_mov_b32_e32 v75, v68
	v_pk_add_f32 v[68:69], v[76:77], v[74:75] neg_lo:[0,1] neg_hi:[0,1]
	v_add_f32_e32 v69, v79, v69
	v_add_f32_e32 v68, v68, v69
	v_add_f32_e32 v69, v83, v82
	v_add_f32_e32 v68, v73, v68
	v_sub_f32_e32 v72, v69, v83
	v_mul_f32_e32 v68, v81, v68
	v_sub_f32_e32 v72, v82, v72
	v_add_f32_e32 v72, v72, v68
	v_add_f32_e32 v74, v69, v72
	v_mul_f32_e32 v75, v74, v74
	v_fmamk_f32 v68, v75, 0x3e9b6dac, v191
	v_fmaak_f32 v169, v75, v68, 0x3f2aaada
	v_cvt_f32_i32_e32 v68, v78
	v_sub_f32_e32 v69, v74, v69
	v_sub_f32_e32 v69, v72, v69
	v_ldexp_f32 v76, v69, 1
	v_mul_f32_e32 v69, v74, v75
	v_ldexp_f32 v73, v74, 1
	v_pk_mul_f32 v[74:75], v[68:69], v[168:169]
	v_fma_f32 v72, v68, s39, -v74
	v_fmac_f32_e32 v72, 0xb102e308, v68
	v_pk_add_f32 v[68:69], v[74:75], v[72:73]
	v_sub_f32_e32 v73, v69, v73
	v_sub_f32_e32 v73, v75, v73
	v_add_f32_e32 v77, v76, v73
	v_mov_b32_e32 v76, v74
	v_pk_add_f32 v[74:75], v[68:69], v[74:75] neg_lo:[0,1] neg_hi:[0,1]
	v_pk_add_f32 v[78:79], v[68:69], v[76:77]
	v_mov_b32_e32 v73, v68
	v_mov_b32_e32 v75, v79
	v_pk_add_f32 v[80:81], v[72:73], v[74:75] neg_lo:[0,1] neg_hi:[0,1]
	v_pk_add_f32 v[72:73], v[72:73], v[74:75]
	v_mov_b32_e32 v76, v77
	v_pk_add_f32 v[74:75], v[72:73], v[68:69] op_sel:[1,0] op_sel_hi:[0,1] neg_lo:[0,1] neg_hi:[0,1]
	v_pk_add_f32 v[82:83], v[78:79], v[74:75] op_sel_hi:[1,0] neg_lo:[0,1] neg_hi:[0,1]
	v_mov_b32_e32 v78, v79
	v_mov_b32_e32 v79, v73
	v_pk_mov_b32 v[74:75], v[68:69], v[74:75] op_sel:[1,0]
	v_mov_b32_e32 v77, v68
	v_pk_add_f32 v[74:75], v[78:79], v[74:75] neg_lo:[0,1] neg_hi:[0,1]
	v_mov_b32_e32 v82, v80
	v_pk_add_f32 v[68:69], v[76:77], v[74:75] neg_lo:[0,1] neg_hi:[0,1]
	v_mov_b32_e32 v81, v73
	v_pk_add_f32 v[74:75], v[82:83], v[68:69]
	v_pk_add_f32 v[76:77], v[74:75], v[74:75] op_sel:[0,1] op_sel_hi:[1,0]
	v_pk_add_f32 v[72:73], v[72:73], v[76:77] op_sel:[1,0] op_sel_hi:[0,1]
	v_mov_b32_e32 v75, v72
	v_pk_add_f32 v[78:79], v[74:75], v[80:81] neg_lo:[0,1] neg_hi:[0,1]
	v_mov_b32_e32 v69, v76
	v_sub_f32_e32 v73, v74, v78
	v_pk_add_f32 v[68:69], v[68:69], v[78:79] neg_lo:[0,1] neg_hi:[0,1]
	v_sub_f32_e32 v73, v80, v73
	v_add_f32_e32 v68, v68, v73
	v_add_f32_e32 v68, v68, v69
	v_add_f32_e32 v68, v72, v68
	v_lshl_add_u64 v[72:73], s[24:25], 0, v[64:65]
	v_mov_b32_e32 v74, v224
	v_lshl_add_u64 v[64:65], s[8:9], 0, v[64:65]
	v_mov_b32_e32 v73, v225
	v_cndmask_b32_e32 v68, v199, v68, vcc
	v_cmp_ngt_f32_e32 vcc, -1.0, v70
	s_waitcnt vmcnt(1)
	v_add_f32_e32 v48, v48, v74
	v_mul_f32_e32 v48, 0xbfb8aa3b, v48
	v_exp_f32_e32 v48, v48
	v_cndmask_b32_e32 v68, v200, v68, vcc
	v_cmp_neq_f32_e32 vcc, -1.0, v70
	s_waitcnt vmcnt(0)
	v_add_f32_e32 v32, v32, v73
	v_add_f32_e32 v48, 1.0, v48
	v_rcp_f32_e32 v48, v48
	v_cndmask_b32_e32 v68, v201, v68, vcc
	v_cmp_lt_f32_e64 vcc, |v70|, s41
	v_mul_f32_e32 v32, 0xbfb8aa3b, v32
	v_exp_f32_e32 v32, v32
	v_cndmask_b32_e32 v68, v68, v70, vcc
	v_mul_f32_e32 v72, 0xc1000000, v68
	v_mul_f32_e32 v48, v48, v72
	v_mul_f32_e32 v64, 0x3fb8aa3b, v48
	v_add_f32_e32 v48, v48, v48
	v_exp_f32_e32 v68, v64
	v_mul_f32_e32 v64, 0x3fb8aa3b, v48
	v_rndne_f32_e32 v64, v64
	v_fmamk_f32 v65, v64, 0xbf317218, v48
	v_fmac_f32_e32 v65, 0x3102e308, v64
	v_fmamk_f32 v69, v65, 0x395133b1, v192
	v_cmp_eq_f32_e32 vcc, s15, v64
	v_cvt_i32_f32_e32 v64, v64
	v_fmaak_f32 v69, v65, v69, 0x3c0887f9
	v_fmaak_f32 v69, v65, v69, 0x3d2aaa81
	v_fmaak_f32 v69, v65, v69, 0x3e2aaaab
	v_fma_f32 v69, v65, v69, 0.5
	v_ldexp_f32 v64, 1.0, v64
	v_mul_f32_e32 v69, v65, v69
	v_cndmask_b32_e32 v64, v64, v202, vcc
	v_fmac_f32_e32 v65, v65, v69
	v_add_f32_e32 v69, -1.0, v64
	v_fmac_f32_e32 v69, v64, v65
	v_add_f32_e32 v64, v69, v69
	v_cndmask_b32_e32 v64, v69, v64, vcc
	v_cmp_nlt_f32_e32 vcc, s16, v48
	v_add_f32_e32 v32, 1.0, v32
	v_rcp_f32_e32 v32, v32
	v_cndmask_b32_e64 v64, v201, -v64, vcc
	v_cmp_gt_f32_e32 vcc, s17, v64
	v_mul_f32_e32 v65, 0x4f800000, v64
	v_add_f32_e32 v33, v33, v73
	v_cndmask_b32_e32 v64, v64, v65, vcc
	v_sqrt_f32_e32 v65, v64
	v_mul_f32_e32 v33, 0xbfb8aa3b, v33
	v_exp_f32_e32 v33, v33
	v_add_f32_e32 v34, v34, v73
	v_add_u32_e32 v69, -1, v65
	v_fma_f32 v70, -v69, v65, v64
	v_cmp_ge_f32_e64 s[0:1], 0, v70
	v_add_u32_e32 v70, 1, v65
	v_add_f32_e32 v33, 1.0, v33
	v_cndmask_b32_e64 v69, v65, v69, s[0:1]
	v_fma_f32 v65, -v70, v65, v64
	v_cmp_lt_f32_e64 s[0:1], 0, v65
	v_rcp_f32_e32 v33, v33
	v_mul_f32_e32 v34, 0xbfb8aa3b, v34
	v_cndmask_b32_e64 v65, v69, v70, s[0:1]
	v_mul_f32_e32 v69, 0x37800000, v65
	v_cndmask_b32_e32 v65, v65, v69, vcc
	v_cmp_class_f32_e32 vcc, v64, v193
	v_exp_f32_e32 v34, v34
	s_nop 0
	v_cndmask_b32_e32 v64, v65, v64, vcc
	v_cmp_ngt_f32_e32 vcc, s18, v48
	v_add_f32_e32 v34, 1.0, v34
	v_rcp_f32_e32 v34, v34
	v_cndmask_b32_e32 v48, 1.0, v64, vcc
	v_mul_f32_e32 v48, v32, v48
	v_and_b32_e32 v32, 0x100, v66
	v_or3_b32 v32, v67, v71, v32
	v_lshl_add_u32 v70, v32, 2, 0
	v_add_u32_e32 v32, 0x9000, v70
	ds_read2_b32 v[64:65], v32 offset1:32
	s_waitcnt lgkmcnt(0)
	v_mul_f32_e32 v48, v64, v48
	ds_write_b32 v70, v68
	ds_write_b32 v70, v48 offset:36864
	v_add_f32_e32 v48, v49, v74
	v_mul_f32_e32 v48, 0xbfb8aa3b, v48
	v_exp_f32_e32 v48, v48
	s_nop 0
	v_add_f32_e32 v48, 1.0, v48
	v_rcp_f32_e32 v48, v48
	s_nop 0
	v_mul_f32_e32 v48, v48, v72
	v_mul_f32_e32 v49, 0x3fb8aa3b, v48
	v_add_f32_e32 v48, v48, v48
	v_exp_f32_e32 v64, v49
	v_mul_f32_e32 v49, 0x3fb8aa3b, v48
	v_rndne_f32_e32 v49, v49
	v_fmamk_f32 v66, v49, 0xbf317218, v48
	v_fmac_f32_e32 v66, 0x3102e308, v49
	v_fmamk_f32 v67, v66, 0x395133b1, v192
	v_cmp_eq_f32_e32 vcc, s15, v49
	v_cvt_i32_f32_e32 v49, v49
	v_fmaak_f32 v67, v66, v67, 0x3c0887f9
	v_fmaak_f32 v67, v66, v67, 0x3d2aaa81
	v_fmaak_f32 v67, v66, v67, 0x3e2aaaab
	v_fma_f32 v67, v66, v67, 0.5
	v_ldexp_f32 v49, 1.0, v49
	v_mul_f32_e32 v67, v66, v67
	v_cndmask_b32_e32 v49, v49, v202, vcc
	v_fmac_f32_e32 v66, v66, v67
	v_add_f32_e32 v67, -1.0, v49
	v_fmac_f32_e32 v67, v49, v66
	v_add_f32_e32 v49, v67, v67
	v_cndmask_b32_e32 v49, v67, v49, vcc
	v_cmp_nlt_f32_e32 vcc, s16, v48
	s_nop 1
	v_cndmask_b32_e64 v49, v201, -v49, vcc
	v_cmp_gt_f32_e32 vcc, s17, v49
	v_mul_f32_e32 v66, 0x4f800000, v49
	s_nop 0
	v_cndmask_b32_e32 v49, v49, v66, vcc
	v_sqrt_f32_e32 v66, v49
	s_nop 0
	v_add_u32_e32 v67, -1, v66
	v_fma_f32 v68, -v67, v66, v49
	v_cmp_ge_f32_e64 s[0:1], 0, v68
	v_add_u32_e32 v68, 1, v66
	s_nop 0
	v_cndmask_b32_e64 v67, v66, v67, s[0:1]
	v_fma_f32 v66, -v68, v66, v49
	v_cmp_lt_f32_e64 s[0:1], 0, v66
	s_nop 1
	v_cndmask_b32_e64 v66, v67, v68, s[0:1]
	v_mul_f32_e32 v67, 0x37800000, v66
	v_cndmask_b32_e32 v66, v66, v67, vcc
	v_cmp_class_f32_e32 vcc, v49, v193
	s_nop 1
	v_cndmask_b32_e32 v49, v66, v49, vcc
	v_cmp_ngt_f32_e32 vcc, s18, v48
	s_nop 1
	v_cndmask_b32_e32 v48, 1.0, v49, vcc
	v_mul_f32_e32 v33, v33, v48
	ds_read2_b32 v[48:49], v32 offset0:64 offset1:96
	s_waitcnt lgkmcnt(0)
	v_mul_f32_e32 v33, v48, v33
	ds_write_b32 v70, v64 offset:256
	ds_write_b32 v70, v33 offset:37120
	v_add_f32_e32 v33, v50, v74
	v_mul_f32_e32 v33, 0xbfb8aa3b, v33
	v_exp_f32_e32 v33, v33
	s_nop 0
	v_add_f32_e32 v33, 1.0, v33
	v_rcp_f32_e32 v33, v33
	s_nop 0
	v_mul_f32_e32 v33, v33, v72
	v_mul_f32_e32 v48, 0x3fb8aa3b, v33
	v_add_f32_e32 v33, v33, v33
	v_mul_f32_e32 v50, 0x3fb8aa3b, v33
	v_rndne_f32_e32 v50, v50
	v_fmamk_f32 v64, v50, 0xbf317218, v33
	v_fmac_f32_e32 v64, 0x3102e308, v50
	v_fmamk_f32 v66, v64, 0x395133b1, v192
	v_cmp_eq_f32_e32 vcc, s15, v50
	v_cvt_i32_f32_e32 v50, v50
	v_fmaak_f32 v66, v64, v66, 0x3c0887f9
	v_fmaak_f32 v66, v64, v66, 0x3d2aaa81
	v_fmaak_f32 v66, v64, v66, 0x3e2aaaab
	v_fma_f32 v66, v64, v66, 0.5
	v_ldexp_f32 v50, 1.0, v50
	v_mul_f32_e32 v66, v64, v66
	v_cndmask_b32_e32 v50, v50, v202, vcc
	v_fmac_f32_e32 v64, v64, v66
	v_add_f32_e32 v66, -1.0, v50
	v_fmac_f32_e32 v66, v50, v64
	v_add_f32_e32 v50, v66, v66
	v_cndmask_b32_e32 v50, v66, v50, vcc
	v_cmp_nlt_f32_e32 vcc, s16, v33
	v_exp_f32_e32 v48, v48
	s_nop 0
	v_cndmask_b32_e64 v50, v201, -v50, vcc
	v_cmp_gt_f32_e32 vcc, s17, v50
	v_mul_f32_e32 v64, 0x4f800000, v50
	s_nop 0
	v_cndmask_b32_e32 v50, v50, v64, vcc
	v_sqrt_f32_e32 v64, v50
	s_nop 0
	v_add_u32_e32 v66, -1, v64
	v_fma_f32 v67, -v66, v64, v50
	v_cmp_ge_f32_e64 s[0:1], 0, v67
	v_add_u32_e32 v67, 1, v64
	s_nop 0
	v_cndmask_b32_e64 v66, v64, v66, s[0:1]
	v_fma_f32 v64, -v67, v64, v50
	v_cmp_lt_f32_e64 s[0:1], 0, v64
	s_nop 1
	v_cndmask_b32_e64 v64, v66, v67, s[0:1]
	v_mul_f32_e32 v66, 0x37800000, v64
	v_cndmask_b32_e32 v64, v64, v66, vcc
	ds_read2_b32 v[66:67], v32 offset0:128 offset1:160
	v_cmp_class_f32_e32 vcc, v50, v193
	s_nop 1
	v_cndmask_b32_e32 v50, v64, v50, vcc
	v_cmp_ngt_f32_e32 vcc, s18, v33
	s_nop 1
	v_cndmask_b32_e32 v33, 1.0, v50, vcc
	v_mul_f32_e32 v33, v34, v33
	s_waitcnt lgkmcnt(0)
	v_mul_f32_e32 v33, v66, v33
	ds_write_b32 v70, v48 offset:512
	ds_write_b32 v70, v33 offset:37376
	v_add_f32_e32 v33, v51, v74
	v_mul_f32_e32 v33, 0xbfb8aa3b, v33
	v_exp_f32_e32 v33, v33
	v_add_f32_e32 v34, v35, v73
	v_mul_f32_e32 v34, 0xbfb8aa3b, v34
	v_exp_f32_e32 v34, v34
	v_add_f32_e32 v33, 1.0, v33
	v_rcp_f32_e32 v33, v33
	v_add_f32_e32 v34, 1.0, v34
	v_rcp_f32_e32 v34, v34
	v_mul_f32_e32 v33, v33, v72
	v_mul_f32_e32 v35, 0x3fb8aa3b, v33
	v_add_f32_e32 v33, v33, v33
	v_mul_f32_e32 v48, 0x3fb8aa3b, v33
	v_rndne_f32_e32 v48, v48
	v_fmamk_f32 v50, v48, 0xbf317218, v33
	v_fmac_f32_e32 v50, 0x3102e308, v48
	v_fmamk_f32 v51, v50, 0x395133b1, v192
	v_cmp_eq_f32_e32 vcc, s15, v48
	v_cvt_i32_f32_e32 v48, v48
	v_fmaak_f32 v51, v50, v51, 0x3c0887f9
	v_fmaak_f32 v51, v50, v51, 0x3d2aaa81
	v_fmaak_f32 v51, v50, v51, 0x3e2aaaab
	v_fma_f32 v51, v50, v51, 0.5
	v_ldexp_f32 v48, 1.0, v48
	v_mul_f32_e32 v51, v50, v51
	v_cndmask_b32_e32 v48, v48, v202, vcc
	v_fmac_f32_e32 v50, v50, v51
	v_add_f32_e32 v51, -1.0, v48
	v_fmac_f32_e32 v51, v48, v50
	v_add_f32_e32 v48, v51, v51
	v_cndmask_b32_e32 v48, v51, v48, vcc
	v_cmp_nlt_f32_e32 vcc, s16, v33
	v_exp_f32_e32 v35, v35
	s_nop 0
	v_cndmask_b32_e64 v48, v201, -v48, vcc
	v_cmp_gt_f32_e32 vcc, s17, v48
	v_mul_f32_e32 v50, 0x4f800000, v48
	s_nop 0
	v_cndmask_b32_e32 v48, v48, v50, vcc
	v_sqrt_f32_e32 v50, v48
	s_nop 0
	v_add_u32_e32 v51, -1, v50
	v_fma_f32 v64, -v51, v50, v48
	v_cmp_ge_f32_e64 s[0:1], 0, v64
	v_add_u32_e32 v64, 1, v50
	s_nop 0
	v_cndmask_b32_e64 v51, v50, v51, s[0:1]
	v_fma_f32 v50, -v64, v50, v48
	v_cmp_lt_f32_e64 s[0:1], 0, v50
	s_nop 1
	v_cndmask_b32_e64 v50, v51, v64, s[0:1]
	v_mul_f32_e32 v51, 0x37800000, v50
	v_cndmask_b32_e32 v50, v50, v51, vcc
	v_cmp_class_f32_e32 vcc, v48, v193
	s_nop 1
	v_cndmask_b32_e32 v48, v50, v48, vcc
	ds_read2_b32 v[50:51], v32 offset0:192 offset1:224
	v_cmp_ngt_f32_e32 vcc, s18, v33
	s_nop 1
	v_cndmask_b32_e32 v33, 1.0, v48, vcc
	v_mul_f32_e32 v33, v34, v33
	s_waitcnt lgkmcnt(0)
	v_mul_f32_e32 v32, v50, v33
	ds_write_b32 v70, v35 offset:768
	ds_write_b32 v70, v32 offset:37632
	v_add_f32_e32 v32, v52, v74
	v_mul_f32_e32 v32, 0xbfb8aa3b, v32
	v_exp_f32_e32 v32, v32
	v_add_f32_e32 v33, v36, v73
	v_mul_f32_e32 v33, 0xbfb8aa3b, v33
	v_exp_f32_e32 v33, v33
	v_add_f32_e32 v32, 1.0, v32
	v_rcp_f32_e32 v32, v32
	v_add_f32_e32 v33, 1.0, v33
	v_rcp_f32_e32 v33, v33
	v_mul_f32_e32 v32, v32, v72
	v_mul_f32_e32 v34, 0x3fb8aa3b, v32
	v_add_f32_e32 v32, v32, v32
	v_mul_f32_e32 v35, 0x3fb8aa3b, v32
	v_rndne_f32_e32 v35, v35
	v_fmamk_f32 v36, v35, 0xbf317218, v32
	v_fmac_f32_e32 v36, 0x3102e308, v35
	v_fmamk_f32 v48, v36, 0x395133b1, v192
	v_cmp_eq_f32_e32 vcc, s15, v35
	v_cvt_i32_f32_e32 v35, v35
	v_fmaak_f32 v48, v36, v48, 0x3c0887f9
	v_fmaak_f32 v48, v36, v48, 0x3d2aaa81
	v_fmaak_f32 v48, v36, v48, 0x3e2aaaab
	v_fma_f32 v48, v36, v48, 0.5
	v_ldexp_f32 v35, 1.0, v35
	v_mul_f32_e32 v48, v36, v48
	v_cndmask_b32_e32 v35, v35, v202, vcc
	v_fmac_f32_e32 v36, v36, v48
	v_add_f32_e32 v48, -1.0, v35
	v_fmac_f32_e32 v48, v35, v36
	v_add_f32_e32 v35, v48, v48
	v_cndmask_b32_e32 v35, v48, v35, vcc
	v_cmp_nlt_f32_e32 vcc, s16, v32
	v_exp_f32_e32 v34, v34
	s_nop 0
	v_cndmask_b32_e64 v35, v201, -v35, vcc
	v_cmp_gt_f32_e32 vcc, s17, v35
	v_mul_f32_e32 v36, 0x4f800000, v35
	s_nop 0
	v_cndmask_b32_e32 v35, v35, v36, vcc
	v_sqrt_f32_e32 v36, v35
	s_nop 0
	v_add_u32_e32 v48, -1, v36
	v_fma_f32 v50, -v48, v36, v35
	v_cmp_ge_f32_e64 s[0:1], 0, v50
	v_add_u32_e32 v50, 1, v36
	s_nop 0
	v_cndmask_b32_e64 v48, v36, v48, s[0:1]
	v_fma_f32 v36, -v50, v36, v35
	v_cmp_lt_f32_e64 s[0:1], 0, v36
	s_nop 1
	v_cndmask_b32_e64 v36, v48, v50, s[0:1]
	v_mul_f32_e32 v48, 0x37800000, v36
	v_cndmask_b32_e32 v36, v36, v48, vcc
	v_cmp_class_f32_e32 vcc, v35, v193
	s_nop 1
	v_cndmask_b32_e32 v35, v36, v35, vcc
	v_cmp_ngt_f32_e32 vcc, s18, v32
	s_nop 1
	v_cndmask_b32_e32 v32, 1.0, v35, vcc
	v_mul_f32_e32 v33, v33, v32
	v_add_u32_e32 v32, 0x9800, v70
	ds_read2_b32 v[68:69], v32 offset1:32
	s_waitcnt lgkmcnt(0)
	v_mul_f32_e32 v33, v68, v33
	ds_write_b32 v70, v34 offset:2048
	ds_write_b32 v70, v33 offset:38912
	v_add_f32_e32 v33, v53, v74
	v_mul_f32_e32 v33, 0xbfb8aa3b, v33
	v_exp_f32_e32 v33, v33
	v_add_f32_e32 v34, v37, v73
	v_mul_f32_e32 v34, 0xbfb8aa3b, v34
	v_exp_f32_e32 v34, v34
	v_add_f32_e32 v33, 1.0, v33
	v_rcp_f32_e32 v33, v33
	v_add_f32_e32 v34, 1.0, v34
	v_rcp_f32_e32 v34, v34
	v_mul_f32_e32 v33, v33, v72
	v_mul_f32_e32 v35, 0x3fb8aa3b, v33
	v_add_f32_e32 v33, v33, v33
	v_mul_f32_e32 v36, 0x3fb8aa3b, v33
	v_rndne_f32_e32 v36, v36
	v_fmamk_f32 v37, v36, 0xbf317218, v33
	v_fmac_f32_e32 v37, 0x3102e308, v36
	v_fmamk_f32 v48, v37, 0x395133b1, v192
	v_cmp_eq_f32_e32 vcc, s15, v36
	v_cvt_i32_f32_e32 v36, v36
	v_fmaak_f32 v48, v37, v48, 0x3c0887f9
	v_fmaak_f32 v48, v37, v48, 0x3d2aaa81
	v_fmaak_f32 v48, v37, v48, 0x3e2aaaab
	v_fma_f32 v48, v37, v48, 0.5
	v_ldexp_f32 v36, 1.0, v36
	v_mul_f32_e32 v48, v37, v48
	v_cndmask_b32_e32 v36, v36, v202, vcc
	v_fmac_f32_e32 v37, v37, v48
	v_add_f32_e32 v48, -1.0, v36
	v_fmac_f32_e32 v48, v36, v37
	v_add_f32_e32 v36, v48, v48
	v_cndmask_b32_e32 v36, v48, v36, vcc
	v_cmp_nlt_f32_e32 vcc, s16, v33
	v_exp_f32_e32 v35, v35
	s_nop 0
	v_cndmask_b32_e64 v36, v201, -v36, vcc
	v_cmp_gt_f32_e32 vcc, s17, v36
	v_mul_f32_e32 v37, 0x4f800000, v36
	s_nop 0
	v_cndmask_b32_e32 v36, v36, v37, vcc
	v_sqrt_f32_e32 v37, v36
	s_nop 0
	v_add_u32_e32 v48, -1, v37
	v_fma_f32 v50, -v48, v37, v36
	v_cmp_ge_f32_e64 s[0:1], 0, v50
	v_add_u32_e32 v50, 1, v37
	s_nop 0
	v_cndmask_b32_e64 v48, v37, v48, s[0:1]
	v_fma_f32 v37, -v50, v37, v36
	v_cmp_lt_f32_e64 s[0:1], 0, v37
	s_nop 1
	v_cndmask_b32_e64 v37, v48, v50, s[0:1]
	v_mul_f32_e32 v48, 0x37800000, v37
	v_cndmask_b32_e32 v37, v37, v48, vcc
	v_cmp_class_f32_e32 vcc, v36, v193
	s_nop 1
	v_cndmask_b32_e32 v36, v37, v36, vcc
	v_cmp_ngt_f32_e32 vcc, s18, v33
	s_nop 1
	v_cndmask_b32_e32 v33, 1.0, v36, vcc
	ds_read2_b32 v[36:37], v32 offset0:64 offset1:96
	v_mul_f32_e32 v33, v34, v33
	v_add_f32_e32 v34, v38, v73
	v_mul_f32_e32 v34, 0xbfb8aa3b, v34
	v_exp_f32_e32 v34, v34
	s_waitcnt lgkmcnt(0)
	v_mul_f32_e32 v33, v36, v33
	ds_write_b32 v70, v35 offset:2304
	ds_write_b32 v70, v33 offset:39168
	v_add_f32_e32 v33, v54, v74
	v_mul_f32_e32 v33, 0xbfb8aa3b, v33
	v_exp_f32_e32 v33, v33
	v_add_f32_e32 v34, 1.0, v34
	v_rcp_f32_e32 v34, v34
	ds_read2_b32 v[52:53], v32 offset0:128 offset1:160
	v_add_f32_e32 v33, 1.0, v33
	v_rcp_f32_e32 v33, v33
	s_nop 0
	v_mul_f32_e32 v33, v33, v72
	v_mul_f32_e32 v35, 0x3fb8aa3b, v33
	v_add_f32_e32 v33, v33, v33
	v_mul_f32_e32 v36, 0x3fb8aa3b, v33
	v_rndne_f32_e32 v36, v36
	v_fmamk_f32 v38, v36, 0xbf317218, v33
	v_fmac_f32_e32 v38, 0x3102e308, v36
	v_fmamk_f32 v48, v38, 0x395133b1, v192
	v_cmp_eq_f32_e32 vcc, s15, v36
	v_cvt_i32_f32_e32 v36, v36
	v_fmaak_f32 v48, v38, v48, 0x3c0887f9
	v_fmaak_f32 v48, v38, v48, 0x3d2aaa81
	v_fmaak_f32 v48, v38, v48, 0x3e2aaaab
	v_fma_f32 v48, v38, v48, 0.5
	v_ldexp_f32 v36, 1.0, v36
	v_mul_f32_e32 v48, v38, v48
	v_cndmask_b32_e32 v36, v36, v202, vcc
	v_fmac_f32_e32 v38, v38, v48
	v_add_f32_e32 v48, -1.0, v36
	v_fmac_f32_e32 v48, v36, v38
	v_add_f32_e32 v36, v48, v48
	v_cndmask_b32_e32 v36, v48, v36, vcc
	v_cmp_nlt_f32_e32 vcc, s16, v33
	v_exp_f32_e32 v35, v35
	s_nop 0
	v_cndmask_b32_e64 v36, v201, -v36, vcc
	v_cmp_gt_f32_e32 vcc, s17, v36
	v_mul_f32_e32 v38, 0x4f800000, v36
	s_nop 0
	v_cndmask_b32_e32 v36, v36, v38, vcc
	v_sqrt_f32_e32 v38, v36
	s_nop 0
	v_add_u32_e32 v48, -1, v38
	v_fma_f32 v50, -v48, v38, v36
	v_cmp_ge_f32_e64 s[0:1], 0, v50
	v_add_u32_e32 v50, 1, v38
	s_nop 0
	v_cndmask_b32_e64 v48, v38, v48, s[0:1]
	v_fma_f32 v38, -v50, v38, v36
	v_cmp_lt_f32_e64 s[0:1], 0, v38
	s_nop 1
	v_cndmask_b32_e64 v38, v48, v50, s[0:1]
	v_mul_f32_e32 v48, 0x37800000, v38
	v_cndmask_b32_e32 v38, v38, v48, vcc
	v_cmp_class_f32_e32 vcc, v36, v193
	s_nop 1
	v_cndmask_b32_e32 v36, v38, v36, vcc
	v_cmp_ngt_f32_e32 vcc, s18, v33
	s_nop 1
	v_cndmask_b32_e32 v33, 1.0, v36, vcc
	v_mul_f32_e32 v33, v34, v33
	s_waitcnt lgkmcnt(0)
	v_mul_f32_e32 v33, v52, v33
	ds_write_b32 v70, v35 offset:2560
	ds_write_b32 v70, v33 offset:39424
	v_add_f32_e32 v33, v55, v74
	v_mul_f32_e32 v33, 0xbfb8aa3b, v33
	v_exp_f32_e32 v33, v33
	v_add_f32_e32 v34, v39, v73
	v_mul_f32_e32 v34, 0xbfb8aa3b, v34
	v_exp_f32_e32 v34, v34
	v_add_f32_e32 v33, 1.0, v33
	v_rcp_f32_e32 v33, v33
	v_add_f32_e32 v34, 1.0, v34
	v_rcp_f32_e32 v34, v34
	v_mul_f32_e32 v33, v33, v72
	v_mul_f32_e32 v35, 0x3fb8aa3b, v33
	v_add_f32_e32 v33, v33, v33
	v_mul_f32_e32 v36, 0x3fb8aa3b, v33
	v_rndne_f32_e32 v36, v36
	v_fmamk_f32 v38, v36, 0xbf317218, v33
	v_fmac_f32_e32 v38, 0x3102e308, v36
	v_fmamk_f32 v39, v38, 0x395133b1, v192
	v_cmp_eq_f32_e32 vcc, s15, v36
	v_cvt_i32_f32_e32 v36, v36
	v_fmaak_f32 v39, v38, v39, 0x3c0887f9
	v_fmaak_f32 v39, v38, v39, 0x3d2aaa81
	v_fmaak_f32 v39, v38, v39, 0x3e2aaaab
	v_fma_f32 v39, v38, v39, 0.5
	v_ldexp_f32 v36, 1.0, v36
	v_mul_f32_e32 v39, v38, v39
	v_cndmask_b32_e32 v36, v36, v202, vcc
	v_fmac_f32_e32 v38, v38, v39
	v_add_f32_e32 v39, -1.0, v36
	v_fmac_f32_e32 v39, v36, v38
	v_add_f32_e32 v36, v39, v39
	v_cndmask_b32_e32 v36, v39, v36, vcc
	v_cmp_nlt_f32_e32 vcc, s16, v33
	v_exp_f32_e32 v35, v35
	s_nop 0
	v_cndmask_b32_e64 v36, v201, -v36, vcc
	v_cmp_gt_f32_e32 vcc, s17, v36
	v_mul_f32_e32 v38, 0x4f800000, v36
	s_nop 0
	v_cndmask_b32_e32 v36, v36, v38, vcc
	v_sqrt_f32_e32 v38, v36
	s_nop 0
	v_add_u32_e32 v39, -1, v38
	v_fma_f32 v48, -v39, v38, v36
	v_cmp_ge_f32_e64 s[0:1], 0, v48
	v_add_u32_e32 v48, 1, v38
	s_nop 0
	v_cndmask_b32_e64 v39, v38, v39, s[0:1]
	v_fma_f32 v38, -v48, v38, v36
	v_cmp_lt_f32_e64 s[0:1], 0, v38
	s_nop 1
	v_cndmask_b32_e64 v38, v39, v48, s[0:1]
	v_mul_f32_e32 v39, 0x37800000, v38
	v_cndmask_b32_e32 v38, v38, v39, vcc
	v_cmp_class_f32_e32 vcc, v36, v193
	s_nop 1
	v_cndmask_b32_e32 v36, v38, v36, vcc
	ds_read2_b32 v[38:39], v32 offset0:192 offset1:224
	v_cmp_ngt_f32_e32 vcc, s18, v33
	s_nop 1
	v_cndmask_b32_e32 v33, 1.0, v36, vcc
	v_mul_f32_e32 v33, v34, v33
	s_waitcnt lgkmcnt(0)
	v_mul_f32_e32 v32, v38, v33
	ds_write_b32 v70, v35 offset:2816
	ds_write_b32 v70, v32 offset:39680
	v_add_f32_e32 v32, v56, v74
	v_mul_f32_e32 v32, 0xbfb8aa3b, v32
	v_exp_f32_e32 v32, v32
	v_add_f32_e32 v33, v40, v73
	v_mul_f32_e32 v33, 0xbfb8aa3b, v33
	v_exp_f32_e32 v33, v33
	v_add_f32_e32 v32, 1.0, v32
	v_rcp_f32_e32 v32, v32
	v_add_f32_e32 v33, 1.0, v33
	v_rcp_f32_e32 v33, v33
	v_mul_f32_e32 v32, v32, v72
	v_mul_f32_e32 v34, 0x3fb8aa3b, v32
	v_add_f32_e32 v32, v32, v32
	v_mul_f32_e32 v35, 0x3fb8aa3b, v32
	v_rndne_f32_e32 v35, v35
	v_fmamk_f32 v36, v35, 0xbf317218, v32
	v_fmac_f32_e32 v36, 0x3102e308, v35
	v_fmamk_f32 v38, v36, 0x395133b1, v192
	v_cmp_eq_f32_e32 vcc, s15, v35
	v_cvt_i32_f32_e32 v35, v35
	v_fmaak_f32 v38, v36, v38, 0x3c0887f9
	v_fmaak_f32 v38, v36, v38, 0x3d2aaa81
	v_fmaak_f32 v38, v36, v38, 0x3e2aaaab
	v_fma_f32 v38, v36, v38, 0.5
	v_ldexp_f32 v35, 1.0, v35
	v_mul_f32_e32 v38, v36, v38
	v_cndmask_b32_e32 v35, v35, v202, vcc
	v_fmac_f32_e32 v36, v36, v38
	v_add_f32_e32 v38, -1.0, v35
	v_fmac_f32_e32 v38, v35, v36
	v_add_f32_e32 v35, v38, v38
	v_cndmask_b32_e32 v35, v38, v35, vcc
	v_cmp_nlt_f32_e32 vcc, s16, v32
	v_exp_f32_e32 v34, v34
	s_nop 0
	v_cndmask_b32_e64 v35, v201, -v35, vcc
	v_cmp_gt_f32_e32 vcc, s17, v35
	v_mul_f32_e32 v36, 0x4f800000, v35
	s_nop 0
	v_cndmask_b32_e32 v35, v35, v36, vcc
	v_sqrt_f32_e32 v36, v35
	s_nop 0
	v_add_u32_e32 v38, -1, v36
	v_fma_f32 v40, -v38, v36, v35
	v_cmp_ge_f32_e64 s[0:1], 0, v40
	v_add_u32_e32 v40, 1, v36
	s_nop 0
	v_cndmask_b32_e64 v38, v36, v38, s[0:1]
	v_fma_f32 v36, -v40, v36, v35
	v_cmp_lt_f32_e64 s[0:1], 0, v36
	s_nop 1
	v_cndmask_b32_e64 v36, v38, v40, s[0:1]
	v_mul_f32_e32 v38, 0x37800000, v36
	v_cndmask_b32_e32 v36, v36, v38, vcc
	v_cmp_class_f32_e32 vcc, v35, v193
	s_nop 1
	v_cndmask_b32_e32 v35, v36, v35, vcc
	v_cmp_ngt_f32_e32 vcc, s18, v32
	s_nop 1
	v_cndmask_b32_e32 v32, 1.0, v35, vcc
	v_mul_f32_e32 v33, v33, v32
	v_add_u32_e32 v32, 0xa000, v70
	ds_read2_b32 v[54:55], v32 offset1:32
	s_waitcnt lgkmcnt(0)
	v_mul_f32_e32 v33, v54, v33
	ds_write_b32 v70, v34 offset:4096
	ds_write_b32 v70, v33 offset:40960
	v_add_f32_e32 v33, v57, v74
	v_mul_f32_e32 v33, 0xbfb8aa3b, v33
	v_exp_f32_e32 v33, v33
	v_add_f32_e32 v34, v41, v73
	v_mul_f32_e32 v34, 0xbfb8aa3b, v34
	v_exp_f32_e32 v34, v34
	v_add_f32_e32 v33, 1.0, v33
	v_rcp_f32_e32 v33, v33
	v_add_f32_e32 v34, 1.0, v34
	v_rcp_f32_e32 v34, v34
	v_mul_f32_e32 v33, v33, v72
	v_mul_f32_e32 v35, 0x3fb8aa3b, v33
	v_add_f32_e32 v33, v33, v33
	v_mul_f32_e32 v36, 0x3fb8aa3b, v33
	v_rndne_f32_e32 v36, v36
	v_fmamk_f32 v38, v36, 0xbf317218, v33
	v_fmac_f32_e32 v38, 0x3102e308, v36
	v_fmamk_f32 v40, v38, 0x395133b1, v192
	v_cmp_eq_f32_e32 vcc, s15, v36
	v_cvt_i32_f32_e32 v36, v36
	v_fmaak_f32 v40, v38, v40, 0x3c0887f9
	v_fmaak_f32 v40, v38, v40, 0x3d2aaa81
	v_fmaak_f32 v40, v38, v40, 0x3e2aaaab
	v_fma_f32 v40, v38, v40, 0.5
	v_ldexp_f32 v36, 1.0, v36
	v_mul_f32_e32 v40, v38, v40
	v_cndmask_b32_e32 v36, v36, v202, vcc
	v_fmac_f32_e32 v38, v38, v40
	v_add_f32_e32 v40, -1.0, v36
	v_fmac_f32_e32 v40, v36, v38
	v_add_f32_e32 v36, v40, v40
	v_cndmask_b32_e32 v36, v40, v36, vcc
	v_cmp_nlt_f32_e32 vcc, s16, v33
	v_exp_f32_e32 v35, v35
	s_nop 0
	v_cndmask_b32_e64 v36, v201, -v36, vcc
	v_cmp_gt_f32_e32 vcc, s17, v36
	v_mul_f32_e32 v38, 0x4f800000, v36
	s_nop 0
	v_cndmask_b32_e32 v36, v36, v38, vcc
	v_sqrt_f32_e32 v38, v36
	s_nop 0
	v_add_u32_e32 v40, -1, v38
	v_fma_f32 v41, -v40, v38, v36
	v_cmp_ge_f32_e64 s[0:1], 0, v41
	v_add_u32_e32 v41, 1, v38
	s_nop 0
	v_cndmask_b32_e64 v40, v38, v40, s[0:1]
	v_fma_f32 v38, -v41, v38, v36
	v_cmp_lt_f32_e64 s[0:1], 0, v38
	s_nop 1
	v_cndmask_b32_e64 v38, v40, v41, s[0:1]
	v_mul_f32_e32 v40, 0x37800000, v38
	v_cndmask_b32_e32 v38, v38, v40, vcc
	ds_read2_b32 v[40:41], v32 offset0:64 offset1:96
	v_cmp_class_f32_e32 vcc, v36, v193
	s_nop 1
	v_cndmask_b32_e32 v36, v38, v36, vcc
	v_cmp_ngt_f32_e32 vcc, s18, v33
	s_nop 1
	v_cndmask_b32_e32 v33, 1.0, v36, vcc
	v_mul_f32_e32 v33, v34, v33
	s_waitcnt lgkmcnt(0)
	v_mul_f32_e32 v33, v40, v33
	ds_write_b32 v70, v35 offset:4352
	ds_write_b32 v70, v33 offset:41216
	v_add_f32_e32 v33, v58, v74
	v_mul_f32_e32 v33, 0xbfb8aa3b, v33
	v_exp_f32_e32 v33, v33
	v_add_f32_e32 v34, v42, v73
	v_mul_f32_e32 v34, 0xbfb8aa3b, v34
	v_exp_f32_e32 v34, v34
	v_add_f32_e32 v33, 1.0, v33
	v_rcp_f32_e32 v33, v33
	ds_read2_b32 v[56:57], v32 offset0:128 offset1:160
	v_add_f32_e32 v34, 1.0, v34
	v_rcp_f32_e32 v34, v34
	v_mul_f32_e32 v33, v33, v72
	v_mul_f32_e32 v35, 0x3fb8aa3b, v33
	v_add_f32_e32 v33, v33, v33
	v_mul_f32_e32 v36, 0x3fb8aa3b, v33
	v_rndne_f32_e32 v36, v36
	v_fmamk_f32 v38, v36, 0xbf317218, v33
	v_fmac_f32_e32 v38, 0x3102e308, v36
	v_fmamk_f32 v40, v38, 0x395133b1, v192
	v_cmp_eq_f32_e32 vcc, s15, v36
	v_cvt_i32_f32_e32 v36, v36
	v_fmaak_f32 v40, v38, v40, 0x3c0887f9
	v_fmaak_f32 v40, v38, v40, 0x3d2aaa81
	v_fmaak_f32 v40, v38, v40, 0x3e2aaaab
	v_fma_f32 v40, v38, v40, 0.5
	v_ldexp_f32 v36, 1.0, v36
	v_mul_f32_e32 v40, v38, v40
	v_cndmask_b32_e32 v36, v36, v202, vcc
	v_fmac_f32_e32 v38, v38, v40
	v_add_f32_e32 v40, -1.0, v36
	v_fmac_f32_e32 v40, v36, v38
	v_add_f32_e32 v36, v40, v40
	v_cndmask_b32_e32 v36, v40, v36, vcc
	v_cmp_nlt_f32_e32 vcc, s16, v33
	v_exp_f32_e32 v35, v35
	s_nop 0
	v_cndmask_b32_e64 v36, v201, -v36, vcc
	v_cmp_gt_f32_e32 vcc, s17, v36
	v_mul_f32_e32 v38, 0x4f800000, v36
	s_nop 0
	v_cndmask_b32_e32 v36, v36, v38, vcc
	v_sqrt_f32_e32 v38, v36
	s_nop 0
	v_add_u32_e32 v40, -1, v38
	v_fma_f32 v42, -v40, v38, v36
	v_cmp_ge_f32_e64 s[0:1], 0, v42
	v_add_u32_e32 v42, 1, v38
	s_nop 0
	v_cndmask_b32_e64 v40, v38, v40, s[0:1]
	v_fma_f32 v38, -v42, v38, v36
	v_cmp_lt_f32_e64 s[0:1], 0, v38
	s_nop 1
	v_cndmask_b32_e64 v38, v40, v42, s[0:1]
	v_mul_f32_e32 v40, 0x37800000, v38
	v_cndmask_b32_e32 v38, v38, v40, vcc
	v_cmp_class_f32_e32 vcc, v36, v193
	s_nop 1
	v_cndmask_b32_e32 v36, v38, v36, vcc
	v_cmp_ngt_f32_e32 vcc, s18, v33
	s_nop 1
	v_cndmask_b32_e32 v33, 1.0, v36, vcc
	v_mul_f32_e32 v33, v34, v33
	s_waitcnt lgkmcnt(0)
	v_mul_f32_e32 v33, v56, v33
	ds_write_b32 v70, v35 offset:4608
	ds_write_b32 v70, v33 offset:41472
	v_add_f32_e32 v33, v59, v74
	v_mul_f32_e32 v33, 0xbfb8aa3b, v33
	v_exp_f32_e32 v33, v33
	v_add_f32_e32 v34, v43, v73
	v_mul_f32_e32 v34, 0xbfb8aa3b, v34
	v_exp_f32_e32 v34, v34
	v_add_f32_e32 v33, 1.0, v33
	v_rcp_f32_e32 v33, v33
	v_add_f32_e32 v34, 1.0, v34
	v_rcp_f32_e32 v34, v34
	v_mul_f32_e32 v33, v33, v72
	v_mul_f32_e32 v35, 0x3fb8aa3b, v33
	v_add_f32_e32 v33, v33, v33
	v_mul_f32_e32 v36, 0x3fb8aa3b, v33
	v_rndne_f32_e32 v36, v36
	v_fmamk_f32 v38, v36, 0xbf317218, v33
	v_fmac_f32_e32 v38, 0x3102e308, v36
	v_fmamk_f32 v40, v38, 0x395133b1, v192
	v_cmp_eq_f32_e32 vcc, s15, v36
	v_cvt_i32_f32_e32 v36, v36
	v_fmaak_f32 v40, v38, v40, 0x3c0887f9
	v_fmaak_f32 v40, v38, v40, 0x3d2aaa81
	v_fmaak_f32 v40, v38, v40, 0x3e2aaaab
	v_fma_f32 v40, v38, v40, 0.5
	v_ldexp_f32 v36, 1.0, v36
	v_mul_f32_e32 v40, v38, v40
	v_cndmask_b32_e32 v36, v36, v202, vcc
	v_fmac_f32_e32 v38, v38, v40
	v_add_f32_e32 v40, -1.0, v36
	v_fmac_f32_e32 v40, v36, v38
	v_add_f32_e32 v36, v40, v40
	v_cndmask_b32_e32 v36, v40, v36, vcc
	v_cmp_nlt_f32_e32 vcc, s16, v33
	v_exp_f32_e32 v35, v35
	s_nop 0
	v_cndmask_b32_e64 v36, v201, -v36, vcc
	v_cmp_gt_f32_e32 vcc, s17, v36
	v_mul_f32_e32 v38, 0x4f800000, v36
	s_nop 0
	v_cndmask_b32_e32 v36, v36, v38, vcc
	v_sqrt_f32_e32 v38, v36
	s_nop 0
	v_add_u32_e32 v40, -1, v38
	v_fma_f32 v42, -v40, v38, v36
	v_cmp_ge_f32_e64 s[0:1], 0, v42
	v_add_u32_e32 v42, 1, v38
	s_nop 0
	v_cndmask_b32_e64 v40, v38, v40, s[0:1]
	v_fma_f32 v38, -v42, v38, v36
	v_cmp_lt_f32_e64 s[0:1], 0, v38
	s_nop 1
	v_cndmask_b32_e64 v38, v40, v42, s[0:1]
	v_mul_f32_e32 v40, 0x37800000, v38
	ds_read2_b32 v[42:43], v32 offset0:192 offset1:224
	v_cndmask_b32_e32 v38, v38, v40, vcc
	v_cmp_class_f32_e32 vcc, v36, v193
	s_nop 1
	v_cndmask_b32_e32 v36, v38, v36, vcc
	v_cmp_ngt_f32_e32 vcc, s18, v33
	s_nop 1
	v_cndmask_b32_e32 v33, 1.0, v36, vcc
	v_mul_f32_e32 v33, v34, v33
	s_waitcnt lgkmcnt(0)
	v_mul_f32_e32 v32, v42, v33
	ds_write_b32 v70, v35 offset:4864
	ds_write_b32 v70, v32 offset:41728
	v_add_f32_e32 v32, v60, v74
	v_mul_f32_e32 v32, 0xbfb8aa3b, v32
	v_exp_f32_e32 v32, v32
	v_add_f32_e32 v33, v44, v73
	v_mul_f32_e32 v33, 0xbfb8aa3b, v33
	v_exp_f32_e32 v33, v33
	v_add_f32_e32 v32, 1.0, v32
	v_rcp_f32_e32 v32, v32
	v_add_f32_e32 v33, 1.0, v33
	v_rcp_f32_e32 v33, v33
	v_mul_f32_e32 v32, v32, v72
	v_mul_f32_e32 v34, 0x3fb8aa3b, v32
	v_add_f32_e32 v32, v32, v32
	v_mul_f32_e32 v35, 0x3fb8aa3b, v32
	v_rndne_f32_e32 v35, v35
	v_fmamk_f32 v36, v35, 0xbf317218, v32
	v_fmac_f32_e32 v36, 0x3102e308, v35
	v_fmamk_f32 v38, v36, 0x395133b1, v192
	v_cmp_eq_f32_e32 vcc, s15, v35
	v_cvt_i32_f32_e32 v35, v35
	v_fmaak_f32 v38, v36, v38, 0x3c0887f9
	v_fmaak_f32 v38, v36, v38, 0x3d2aaa81
	v_fmaak_f32 v38, v36, v38, 0x3e2aaaab
	v_fma_f32 v38, v36, v38, 0.5
	v_ldexp_f32 v35, 1.0, v35
	v_mul_f32_e32 v38, v36, v38
	v_cndmask_b32_e32 v35, v35, v202, vcc
	v_fmac_f32_e32 v36, v36, v38
	v_add_f32_e32 v38, -1.0, v35
	v_fmac_f32_e32 v38, v35, v36
	v_add_f32_e32 v35, v38, v38
	v_cndmask_b32_e32 v35, v38, v35, vcc
	v_cmp_nlt_f32_e32 vcc, s16, v32
	v_exp_f32_e32 v34, v34
	s_nop 0
	v_cndmask_b32_e64 v35, v201, -v35, vcc
	v_cmp_gt_f32_e32 vcc, s17, v35
	v_mul_f32_e32 v36, 0x4f800000, v35
	s_nop 0
	v_cndmask_b32_e32 v35, v35, v36, vcc
	v_sqrt_f32_e32 v36, v35
	s_nop 0
	v_add_u32_e32 v38, -1, v36
	v_fma_f32 v40, -v38, v36, v35
	v_cmp_ge_f32_e64 s[0:1], 0, v40
	v_add_u32_e32 v40, 1, v36
	s_nop 0
	v_cndmask_b32_e64 v38, v36, v38, s[0:1]
	v_fma_f32 v36, -v40, v36, v35
	v_cmp_lt_f32_e64 s[0:1], 0, v36
	s_nop 1
	v_cndmask_b32_e64 v36, v38, v40, s[0:1]
	v_mul_f32_e32 v38, 0x37800000, v36
	v_cndmask_b32_e32 v36, v36, v38, vcc
	v_cmp_class_f32_e32 vcc, v35, v193
	s_nop 1
	v_cndmask_b32_e32 v35, v36, v35, vcc
	v_cmp_ngt_f32_e32 vcc, s18, v32
	s_nop 1
	v_cndmask_b32_e32 v32, 1.0, v35, vcc
	v_mul_f32_e32 v32, v33, v32
	v_add_u32_e32 v33, 0xa800, v70
	ds_read2_b32 v[58:59], v33 offset1:32
	s_waitcnt lgkmcnt(0)
	v_mul_f32_e32 v32, v58, v32
	ds_write_b32 v70, v34 offset:6144
	ds_write_b32 v70, v32 offset:43008
	v_add_f32_e32 v32, v61, v74
	v_mul_f32_e32 v32, 0xbfb8aa3b, v32
	v_exp_f32_e32 v32, v32
	v_add_f32_e32 v34, v45, v73
	v_mul_f32_e32 v34, 0xbfb8aa3b, v34
	v_exp_f32_e32 v34, v34
	v_add_f32_e32 v32, 1.0, v32
	v_rcp_f32_e32 v32, v32
	ds_read2_b32 v[44:45], v33 offset0:64 offset1:96
	v_add_f32_e32 v34, 1.0, v34
	v_rcp_f32_e32 v34, v34
	v_mul_f32_e32 v32, v32, v72
	v_mul_f32_e32 v35, 0x3fb8aa3b, v32
	v_add_f32_e32 v32, v32, v32
	v_mul_f32_e32 v36, 0x3fb8aa3b, v32
	v_rndne_f32_e32 v36, v36
	v_fmamk_f32 v38, v36, 0xbf317218, v32
	v_fmac_f32_e32 v38, 0x3102e308, v36
	v_fmamk_f32 v40, v38, 0x395133b1, v192
	v_cmp_eq_f32_e32 vcc, s15, v36
	v_cvt_i32_f32_e32 v36, v36
	v_fmaak_f32 v40, v38, v40, 0x3c0887f9
	v_fmaak_f32 v40, v38, v40, 0x3d2aaa81
	v_fmaak_f32 v40, v38, v40, 0x3e2aaaab
	v_fma_f32 v40, v38, v40, 0.5
	v_ldexp_f32 v36, 1.0, v36
	v_mul_f32_e32 v40, v38, v40
	v_cndmask_b32_e32 v36, v36, v202, vcc
	v_fmac_f32_e32 v38, v38, v40
	v_add_f32_e32 v40, -1.0, v36
	v_fmac_f32_e32 v40, v36, v38
	v_add_f32_e32 v36, v40, v40
	v_cndmask_b32_e32 v36, v40, v36, vcc
	v_cmp_nlt_f32_e32 vcc, s16, v32
	v_exp_f32_e32 v35, v35
	s_nop 0
	v_cndmask_b32_e64 v36, v201, -v36, vcc
	v_cmp_gt_f32_e32 vcc, s17, v36
	v_mul_f32_e32 v38, 0x4f800000, v36
	s_nop 0
	v_cndmask_b32_e32 v36, v36, v38, vcc
	v_sqrt_f32_e32 v38, v36
	s_nop 0
	v_add_u32_e32 v40, -1, v38
	v_fma_f32 v42, -v40, v38, v36
	v_cmp_ge_f32_e64 s[0:1], 0, v42
	v_add_u32_e32 v42, 1, v38
	s_nop 0
	v_cndmask_b32_e64 v40, v38, v40, s[0:1]
	v_fma_f32 v38, -v42, v38, v36
	v_cmp_lt_f32_e64 s[0:1], 0, v38
	s_nop 1
	v_cndmask_b32_e64 v38, v40, v42, s[0:1]
	v_mul_f32_e32 v40, 0x37800000, v38
	v_cndmask_b32_e32 v38, v38, v40, vcc
	v_cmp_class_f32_e32 vcc, v36, v193
	s_nop 1
	v_cndmask_b32_e32 v36, v38, v36, vcc
	v_cmp_ngt_f32_e32 vcc, s18, v32
	s_nop 1
	v_cndmask_b32_e32 v32, 1.0, v36, vcc
	v_mul_f32_e32 v32, v34, v32
	s_waitcnt lgkmcnt(0)
	v_mul_f32_e32 v32, v44, v32
	ds_write_b32 v70, v35 offset:6400
	ds_write_b32 v70, v32 offset:43264
	v_add_f32_e32 v32, v62, v74
	v_mul_f32_e32 v32, 0xbfb8aa3b, v32
	v_exp_f32_e32 v32, v32
	v_add_f32_e32 v34, v46, v73
	v_mul_f32_e32 v34, 0xbfb8aa3b, v34
	v_exp_f32_e32 v34, v34
	v_add_f32_e32 v32, 1.0, v32
	v_rcp_f32_e32 v32, v32
	v_add_f32_e32 v34, 1.0, v34
	v_rcp_f32_e32 v34, v34
	v_mul_f32_e32 v32, v32, v72
	v_mul_f32_e32 v35, 0x3fb8aa3b, v32
	v_add_f32_e32 v32, v32, v32
	v_exp_f32_e32 v36, v35
	v_mul_f32_e32 v35, 0x3fb8aa3b, v32
	v_rndne_f32_e32 v35, v35
	v_fmamk_f32 v38, v35, 0xbf317218, v32
	v_fmac_f32_e32 v38, 0x3102e308, v35
	v_fmamk_f32 v40, v38, 0x395133b1, v192
	v_cmp_eq_f32_e32 vcc, s15, v35
	v_cvt_i32_f32_e32 v35, v35
	v_fmaak_f32 v40, v38, v40, 0x3c0887f9
	v_fmaak_f32 v40, v38, v40, 0x3d2aaa81
	v_fmaak_f32 v40, v38, v40, 0x3e2aaaab
	v_fma_f32 v40, v38, v40, 0.5
	v_ldexp_f32 v35, 1.0, v35
	v_mul_f32_e32 v40, v38, v40
	v_cndmask_b32_e32 v35, v35, v202, vcc
	v_fmac_f32_e32 v38, v38, v40
	v_add_f32_e32 v40, -1.0, v35
	v_fmac_f32_e32 v40, v35, v38
	v_add_f32_e32 v35, v40, v40
	v_cndmask_b32_e32 v35, v40, v35, vcc
	v_cmp_nlt_f32_e32 vcc, s16, v32
	s_nop 1
	v_cndmask_b32_e64 v35, v201, -v35, vcc
	v_cmp_gt_f32_e32 vcc, s17, v35
	v_mul_f32_e32 v38, 0x4f800000, v35
	s_nop 0
	v_cndmask_b32_e32 v35, v35, v38, vcc
	v_sqrt_f32_e32 v38, v35
	s_nop 0
	v_add_u32_e32 v40, -1, v38
	v_fma_f32 v42, -v40, v38, v35
	v_cmp_ge_f32_e64 s[0:1], 0, v42
	v_add_u32_e32 v42, 1, v38
	s_nop 0
	v_cndmask_b32_e64 v40, v38, v40, s[0:1]
	v_fma_f32 v38, -v42, v38, v35
	v_cmp_lt_f32_e64 s[0:1], 0, v38
	s_nop 1
	v_cndmask_b32_e64 v38, v40, v42, s[0:1]
	v_mul_f32_e32 v40, 0x37800000, v38
	v_cndmask_b32_e32 v38, v38, v40, vcc
	v_cmp_class_f32_e32 vcc, v35, v193
	s_nop 1
	v_cndmask_b32_e32 v35, v38, v35, vcc
	v_cmp_ngt_f32_e32 vcc, s18, v32
	s_nop 1
	v_cndmask_b32_e32 v32, 1.0, v35, vcc
	v_mul_f32_e32 v32, v34, v32
	ds_read2_b32 v[34:35], v33 offset0:128 offset1:160
	s_waitcnt lgkmcnt(0)
	v_mul_f32_e32 v32, v34, v32
	ds_write_b32 v70, v36 offset:6656
	ds_write_b32 v70, v32 offset:43520
	v_add_f32_e32 v32, v63, v74
	v_mul_f32_e32 v32, 0xbfb8aa3b, v32
	v_exp_f32_e32 v32, v32
	v_add_f32_e32 v34, v47, v73
	v_mul_f32_e32 v34, 0xbfb8aa3b, v34
	v_exp_f32_e32 v34, v34
	v_add_f32_e32 v32, 1.0, v32
	v_rcp_f32_e32 v32, v32
	v_lshlrev_b64 v[46:47], 2, v[96:97]
	v_add_f32_e32 v34, 1.0, v34
	v_rcp_f32_e32 v36, v34
	v_mul_f32_e32 v32, v32, v72
	v_mul_f32_e32 v34, 0x3fb8aa3b, v32
	v_add_f32_e32 v32, v32, v32
	v_mul_f32_e32 v38, 0x3fb8aa3b, v32
	v_rndne_f32_e32 v38, v38
	v_fmamk_f32 v40, v38, 0xbf317218, v32
	v_fmac_f32_e32 v40, 0x3102e308, v38
	v_fmamk_f32 v42, v40, 0x395133b1, v192
	v_cmp_eq_f32_e32 vcc, s15, v38
	v_cvt_i32_f32_e32 v38, v38
	v_fmaak_f32 v42, v40, v42, 0x3c0887f9
	v_fmaak_f32 v42, v40, v42, 0x3d2aaa81
	v_fmaak_f32 v42, v40, v42, 0x3e2aaaab
	v_fma_f32 v42, v40, v42, 0.5
	v_ldexp_f32 v38, 1.0, v38
	v_mul_f32_e32 v42, v40, v42
	v_cndmask_b32_e32 v38, v38, v202, vcc
	v_fmac_f32_e32 v40, v40, v42
	v_add_f32_e32 v42, -1.0, v38
	v_fmac_f32_e32 v42, v38, v40
	v_add_f32_e32 v38, v42, v42
	v_cndmask_b32_e32 v38, v42, v38, vcc
	v_cmp_nlt_f32_e32 vcc, s16, v32
	v_lshl_add_u64 v[60:61], s[10:11], 0, v[46:47]
	v_exp_f32_e32 v34, v34
	v_cndmask_b32_e64 v38, v201, -v38, vcc
	v_cmp_gt_f32_e32 vcc, s17, v38
	v_mul_f32_e32 v40, 0x4f800000, v38
	s_nop 0
	v_cndmask_b32_e32 v38, v38, v40, vcc
	v_sqrt_f32_e32 v40, v38
	s_nop 0
	v_add_u32_e32 v42, -1, v40
	v_fma_f32 v44, -v42, v40, v38
	v_cmp_ge_f32_e64 s[0:1], 0, v44
	v_add_u32_e32 v44, 1, v40
	s_nop 0
	v_cndmask_b32_e64 v42, v40, v42, s[0:1]
	v_fma_f32 v40, -v44, v40, v38
	v_cmp_lt_f32_e64 s[0:1], 0, v40
	s_nop 1
	v_cndmask_b32_e64 v40, v42, v44, s[0:1]
	v_mul_f32_e32 v42, 0x37800000, v40
	v_cndmask_b32_e32 v40, v40, v42, vcc
	v_cmp_class_f32_e32 vcc, v38, v193
	s_nop 1
	v_cndmask_b32_e32 v38, v40, v38, vcc
	v_cmp_ngt_f32_e32 vcc, s18, v32
	s_nop 1
	v_cndmask_b32_e32 v32, 1.0, v38, vcc
	v_mul_f32_e32 v36, v36, v32
	ds_read2_b32 v[32:33], v33 offset0:192 offset1:224
	s_waitcnt lgkmcnt(0)
	v_mul_f32_e32 v32, v32, v36
	ds_write_b32 v70, v32 offset:43776
	s_waitcnt vmcnt(0)
	v_mul_f32_e32 v32, 0xbfb8aa3b, v226
	v_exp_f32_e32 v32, v32
	s_nop 0
	v_add_f32_e32 v36, 1.0, v32
	v_add_f32_e32 v38, -1.0, v36
	v_sub_f32_e32 v40, v38, v36
	v_add_f32_e32 v40, 1.0, v40
	v_sub_f32_e32 v38, v32, v38
	v_add_f32_e32 v38, v38, v40
	v_frexp_mant_f32_e32 v40, v36
	v_cvt_f64_f32_e32 v[60:61], v36
	v_cmp_gt_f32_e32 vcc, s7, v40
	v_frexp_exp_i32_f64_e32 v40, v[60:61]
	s_nop 0
	v_subbrev_co_u32_e32 v40, vcc, 0, v40, vcc
	v_sub_u32_e32 v42, 0, v40
	v_ldexp_f32 v36, v36, v42
	v_ldexp_f32 v38, v38, v42
	v_add_f32_e32 v42, -1.0, v36
	v_add_f32_e32 v48, 1.0, v36
	v_add_f32_e32 v44, 1.0, v42
	v_add_f32_e32 v50, -1.0, v48
	v_sub_f32_e32 v44, v36, v44
	v_sub_f32_e32 v36, v36, v50
	v_add_f32_e32 v36, v38, v36
	v_add_f32_e32 v44, v38, v44
	v_add_f32_e32 v38, v48, v36
	v_sub_f32_e32 v48, v38, v48
	v_sub_f32_e32 v36, v36, v48
	v_rcp_f32_e32 v48, v38
	v_add_f32_e32 v61, v42, v44
	v_sub_f32_e32 v42, v61, v42
	v_sub_f32_e32 v42, v44, v42
	v_mul_f32_e32 v44, v61, v48
	v_mul_f32_e32 v62, v38, v44
	v_fma_f32 v72, v44, v38, -v62
	v_fmac_f32_e32 v72, v44, v36
	v_add_f32_e32 v60, v62, v72
	v_sub_f32_e32 v63, v61, v60
	v_pk_add_f32 v[74:75], v[60:61], v[62:63] neg_lo:[0,1] neg_hi:[0,1]
	v_mov_b32_e32 v73, v60
	v_pk_add_f32 v[60:61], v[74:75], v[72:73] neg_lo:[0,1] neg_hi:[0,1]
	v_cmp_neq_f32_e32 vcc, s40, v32
	v_add_f32_e32 v42, v42, v61
	v_add_f32_e32 v42, v60, v42
	v_add_f32_e32 v61, v63, v42
	v_mul_f32_e32 v50, v48, v61
	v_mul_f32_e32 v62, v38, v50
	v_fma_f32 v72, v50, v38, -v62
	v_fmac_f32_e32 v72, v50, v36
	v_add_f32_e32 v60, v62, v72
	v_sub_f32_e32 v36, v63, v61
	v_sub_f32_e32 v63, v61, v60
	v_pk_add_f32 v[74:75], v[60:61], v[62:63] neg_lo:[0,1] neg_hi:[0,1]
	v_mov_b32_e32 v73, v60
	v_add_f32_e32 v36, v42, v36
	v_pk_add_f32 v[60:61], v[74:75], v[72:73] neg_lo:[0,1] neg_hi:[0,1]
	v_add_f32_e32 v38, v44, v50
	v_add_f32_e32 v36, v36, v61
	v_add_f32_e32 v36, v60, v36
	v_add_f32_e32 v36, v63, v36
	v_sub_f32_e32 v42, v38, v44
	v_mul_f32_e32 v36, v48, v36
	v_sub_f32_e32 v42, v50, v42
	v_add_f32_e32 v36, v42, v36
	v_add_f32_e32 v42, v38, v36
	v_cvt_f32_i32_e32 v60, v40
	v_mul_f32_e32 v44, v42, v42
	v_fmamk_f32 v48, v44, 0x3e9b6dac, v191
	v_fmaak_f32 v169, v44, v48, 0x3f2aaada
	v_mul_f32_e32 v61, v42, v44
	v_pk_mul_f32 v[72:73], v[60:61], v[168:169]
	v_ldexp_f32 v63, v42, 1
	v_fma_f32 v62, v60, s39, -v72
	v_fmac_f32_e32 v62, 0xb102e308, v60
	v_sub_f32_e32 v38, v42, v38
	v_pk_add_f32 v[60:61], v[72:73], v[62:63]
	v_sub_f32_e32 v36, v36, v38
	v_sub_f32_e32 v38, v61, v63
	v_ldexp_f32 v36, v36, 1
	v_sub_f32_e32 v38, v73, v38
	v_add_f32_e32 v75, v36, v38
	v_mov_b32_e32 v74, v72
	v_pk_add_f32 v[72:73], v[60:61], v[72:73] neg_lo:[0,1] neg_hi:[0,1]
	v_pk_add_f32 v[76:77], v[60:61], v[74:75]
	v_mov_b32_e32 v63, v60
	v_mov_b32_e32 v73, v77
	v_pk_add_f32 v[78:79], v[62:63], v[72:73] neg_lo:[0,1] neg_hi:[0,1]
	v_pk_add_f32 v[62:63], v[62:63], v[72:73]
	v_mov_b32_e32 v74, v75
	v_pk_add_f32 v[72:73], v[62:63], v[60:61] op_sel:[1,0] op_sel_hi:[0,1] neg_lo:[0,1] neg_hi:[0,1]
	v_pk_add_f32 v[80:81], v[76:77], v[72:73] op_sel_hi:[1,0] neg_lo:[0,1] neg_hi:[0,1]
	v_mov_b32_e32 v76, v77
	v_mov_b32_e32 v77, v63
	v_pk_mov_b32 v[72:73], v[60:61], v[72:73] op_sel:[1,0]
	v_mov_b32_e32 v75, v60
	v_pk_add_f32 v[72:73], v[76:77], v[72:73] neg_lo:[0,1] neg_hi:[0,1]
	v_mov_b32_e32 v80, v78
	v_pk_add_f32 v[60:61], v[74:75], v[72:73] neg_lo:[0,1] neg_hi:[0,1]
	v_mov_b32_e32 v79, v63
	v_pk_add_f32 v[72:73], v[80:81], v[60:61]
	v_pk_add_f32 v[74:75], v[72:73], v[72:73] op_sel:[0,1] op_sel_hi:[1,0]
	v_pk_add_f32 v[62:63], v[62:63], v[74:75] op_sel:[1,0] op_sel_hi:[0,1]
	v_mov_b32_e32 v73, v62
	v_pk_add_f32 v[76:77], v[72:73], v[78:79] neg_lo:[0,1] neg_hi:[0,1]
	v_mov_b32_e32 v61, v74
	v_sub_f32_e32 v36, v72, v76
	v_pk_add_f32 v[60:61], v[60:61], v[76:77] neg_lo:[0,1] neg_hi:[0,1]
	v_sub_f32_e32 v36, v78, v36
	v_add_f32_e32 v36, v60, v36
	v_add_f32_e32 v36, v36, v61
	v_add_f32_e32 v36, v62, v36
	v_cndmask_b32_e32 v36, v199, v36, vcc
	v_cmp_ngt_f32_e32 vcc, -1.0, v32
	v_lshl_add_u64 v[60:61], s[24:25], 0, v[46:47]
	v_lshl_add_u64 v[46:47], s[8:9], 0, v[46:47]
	v_cndmask_b32_e32 v36, v200, v36, vcc
	v_cmp_neq_f32_e32 vcc, -1.0, v32
	v_mov_b32_e32 v38, v227
	s_waitcnt vmcnt(0)
	v_add_f32_e32 v0, v0, v38
	v_cndmask_b32_e32 v36, v201, v36, vcc
	v_cmp_lt_f32_e64 vcc, |v32|, s41
	v_mul_f32_e32 v0, 0xbfb8aa3b, v0
	v_exp_f32_e32 v0, v0
	v_cndmask_b32_e32 v32, v36, v32, vcc
	v_mov_b32_e32 v36, v228
	v_mul_f32_e32 v32, 0xc1000000, v32
	v_add_f32_e32 v0, 1.0, v0
	v_rcp_f32_e32 v0, v0
	v_add_f32_e32 v1, v1, v38
	v_mul_f32_e32 v1, 0xbfb8aa3b, v1
	v_exp_f32_e32 v1, v1
	s_waitcnt vmcnt(0)
	v_add_f32_e32 v16, v16, v36
	v_mul_f32_e32 v16, 0xbfb8aa3b, v16
	v_exp_f32_e32 v16, v16
	v_add_f32_e32 v1, 1.0, v1
	v_rcp_f32_e32 v1, v1
	v_add_f32_e32 v16, 1.0, v16
	v_rcp_f32_e32 v16, v16
	s_nop 0
	v_mul_f32_e32 v16, v16, v32
	v_mul_f32_e32 v40, 0x3fb8aa3b, v16
	v_add_f32_e32 v16, v16, v16
	v_mul_f32_e32 v42, 0x3fb8aa3b, v16
	v_rndne_f32_e32 v42, v42
	v_fmamk_f32 v44, v42, 0xbf317218, v16
	v_fmac_f32_e32 v44, 0x3102e308, v42
	v_fmamk_f32 v46, v44, 0x395133b1, v192
	v_cmp_eq_f32_e32 vcc, s15, v42
	v_cvt_i32_f32_e32 v42, v42
	v_fmaak_f32 v46, v44, v46, 0x3c0887f9
	v_fmaak_f32 v46, v44, v46, 0x3d2aaa81
	v_fmaak_f32 v46, v44, v46, 0x3e2aaaab
	v_fma_f32 v46, v44, v46, 0.5
	v_ldexp_f32 v42, 1.0, v42
	v_mul_f32_e32 v46, v44, v46
	v_cndmask_b32_e32 v42, v42, v202, vcc
	v_fmac_f32_e32 v44, v44, v46
	v_add_f32_e32 v46, -1.0, v42
	v_fmac_f32_e32 v46, v42, v44
	v_add_f32_e32 v42, v46, v46
	v_cndmask_b32_e32 v42, v46, v42, vcc
	v_cmp_nlt_f32_e32 vcc, s16, v16
	v_exp_f32_e32 v40, v40
	s_nop 0
	v_cndmask_b32_e64 v42, v201, -v42, vcc
	v_cmp_gt_f32_e32 vcc, s17, v42
	v_mul_f32_e32 v44, 0x4f800000, v42
	s_nop 0
	v_cndmask_b32_e32 v42, v42, v44, vcc
	v_sqrt_f32_e32 v44, v42
	s_nop 0
	v_add_u32_e32 v46, -1, v44
	v_fma_f32 v47, -v46, v44, v42
	v_cmp_ge_f32_e64 s[0:1], 0, v47
	v_add_u32_e32 v47, 1, v44
	s_nop 0
	v_cndmask_b32_e64 v46, v44, v46, s[0:1]
	v_fma_f32 v44, -v47, v44, v42
	v_cmp_lt_f32_e64 s[0:1], 0, v44
	s_nop 1
	v_cndmask_b32_e64 v44, v46, v47, s[0:1]
	v_mul_f32_e32 v46, 0x37800000, v44
	v_cndmask_b32_e32 v44, v44, v46, vcc
	v_cmp_class_f32_e32 vcc, v42, v193
	s_nop 1
	v_cndmask_b32_e32 v42, v44, v42, vcc
	v_cmp_ngt_f32_e32 vcc, s18, v16
	s_nop 1
	v_cndmask_b32_e32 v16, 1.0, v42, vcc
	v_mul_f32_e32 v0, v0, v16
	v_mul_f32_e32 v0, v65, v0
	ds_write_b32 v70, v40 offset:128
	ds_write_b32 v70, v0 offset:36992
	v_add_f32_e32 v0, v17, v36
	v_mul_f32_e32 v0, 0xbfb8aa3b, v0
	v_exp_f32_e32 v0, v0
	s_nop 0
	v_add_f32_e32 v0, 1.0, v0
	v_rcp_f32_e32 v0, v0
	s_nop 0
	v_mul_f32_e32 v0, v0, v32
	v_mul_f32_e32 v16, 0x3fb8aa3b, v0
	v_add_f32_e32 v0, v0, v0
	v_mul_f32_e32 v17, 0x3fb8aa3b, v0
	v_rndne_f32_e32 v17, v17
	v_fmamk_f32 v40, v17, 0xbf317218, v0
	v_fmac_f32_e32 v40, 0x3102e308, v17
	v_fmamk_f32 v42, v40, 0x395133b1, v192
	v_cmp_eq_f32_e32 vcc, s15, v17
	v_cvt_i32_f32_e32 v17, v17
	v_fmaak_f32 v42, v40, v42, 0x3c0887f9
	v_fmaak_f32 v42, v40, v42, 0x3d2aaa81
	v_fmaak_f32 v42, v40, v42, 0x3e2aaaab
	v_fma_f32 v42, v40, v42, 0.5
	v_ldexp_f32 v17, 1.0, v17
	v_mul_f32_e32 v42, v40, v42
	v_cndmask_b32_e32 v17, v17, v202, vcc
	v_fmac_f32_e32 v40, v40, v42
	v_add_f32_e32 v42, -1.0, v17
	v_fmac_f32_e32 v42, v17, v40
	v_add_f32_e32 v17, v42, v42
	v_cndmask_b32_e32 v17, v42, v17, vcc
	v_cmp_nlt_f32_e32 vcc, s16, v0
	v_exp_f32_e32 v16, v16
	s_nop 0
	v_cndmask_b32_e64 v17, v201, -v17, vcc
	v_cmp_gt_f32_e32 vcc, s17, v17
	v_mul_f32_e32 v40, 0x4f800000, v17
	s_nop 0
	v_cndmask_b32_e32 v17, v17, v40, vcc
	v_sqrt_f32_e32 v40, v17
	s_nop 0
	v_add_u32_e32 v42, -1, v40
	v_fma_f32 v44, -v42, v40, v17
	v_cmp_ge_f32_e64 s[0:1], 0, v44
	v_add_u32_e32 v44, 1, v40
	s_nop 0
	v_cndmask_b32_e64 v42, v40, v42, s[0:1]
	v_fma_f32 v40, -v44, v40, v17
	v_cmp_lt_f32_e64 s[0:1], 0, v40
	s_nop 1
	v_cndmask_b32_e64 v40, v42, v44, s[0:1]
	v_mul_f32_e32 v42, 0x37800000, v40
	v_cndmask_b32_e32 v40, v40, v42, vcc
	v_cmp_class_f32_e32 vcc, v17, v193
	s_nop 1
	v_cndmask_b32_e32 v17, v40, v17, vcc
	v_cmp_ngt_f32_e32 vcc, s18, v0
	s_nop 1
	v_cndmask_b32_e32 v0, 1.0, v17, vcc
	v_mul_f32_e32 v0, v1, v0
	v_mul_f32_e32 v0, v49, v0
	ds_write_b32 v70, v16 offset:384
	ds_write_b32 v70, v0 offset:37248
	v_add_f32_e32 v0, v18, v36
	v_mul_f32_e32 v0, 0xbfb8aa3b, v0
	v_exp_f32_e32 v0, v0
	v_add_f32_e32 v1, v2, v38
	v_mul_f32_e32 v1, 0xbfb8aa3b, v1
	v_exp_f32_e32 v1, v1
	v_add_f32_e32 v0, 1.0, v0
	v_rcp_f32_e32 v0, v0
	v_add_f32_e32 v1, 1.0, v1
	v_rcp_f32_e32 v1, v1
	v_mul_f32_e32 v0, v0, v32
	v_mul_f32_e32 v2, 0x3fb8aa3b, v0
	v_add_f32_e32 v0, v0, v0
	v_mul_f32_e32 v16, 0x3fb8aa3b, v0
	v_rndne_f32_e32 v16, v16
	v_fmamk_f32 v17, v16, 0xbf317218, v0
	v_fmac_f32_e32 v17, 0x3102e308, v16
	v_fmamk_f32 v18, v17, 0x395133b1, v192
	v_cmp_eq_f32_e32 vcc, s15, v16
	v_cvt_i32_f32_e32 v16, v16
	v_fmaak_f32 v18, v17, v18, 0x3c0887f9
	v_fmaak_f32 v18, v17, v18, 0x3d2aaa81
	v_fmaak_f32 v18, v17, v18, 0x3e2aaaab
	v_fma_f32 v18, v17, v18, 0.5
	v_ldexp_f32 v16, 1.0, v16
	v_mul_f32_e32 v18, v17, v18
	v_cndmask_b32_e32 v16, v16, v202, vcc
	v_fmac_f32_e32 v17, v17, v18
	v_add_f32_e32 v18, -1.0, v16
	v_fmac_f32_e32 v18, v16, v17
	v_add_f32_e32 v16, v18, v18
	v_cndmask_b32_e32 v16, v18, v16, vcc
	v_cmp_nlt_f32_e32 vcc, s16, v0
	v_exp_f32_e32 v2, v2
	s_nop 0
	v_cndmask_b32_e64 v16, v201, -v16, vcc
	v_cmp_gt_f32_e32 vcc, s17, v16
	v_mul_f32_e32 v17, 0x4f800000, v16
	s_nop 0
	v_cndmask_b32_e32 v16, v16, v17, vcc
	v_sqrt_f32_e32 v17, v16
	s_nop 0
	v_add_u32_e32 v18, -1, v17
	v_fma_f32 v40, -v18, v17, v16
	v_cmp_ge_f32_e64 s[0:1], 0, v40
	v_add_u32_e32 v40, 1, v17
	s_nop 0
	v_cndmask_b32_e64 v18, v17, v18, s[0:1]
	v_fma_f32 v17, -v40, v17, v16
	v_cmp_lt_f32_e64 s[0:1], 0, v17
	s_nop 1
	v_cndmask_b32_e64 v17, v18, v40, s[0:1]
	v_mul_f32_e32 v18, 0x37800000, v17
	v_cndmask_b32_e32 v17, v17, v18, vcc
	v_cmp_class_f32_e32 vcc, v16, v193
	s_nop 1
	v_cndmask_b32_e32 v16, v17, v16, vcc
	v_cmp_ngt_f32_e32 vcc, s18, v0
	s_nop 1
	v_cndmask_b32_e32 v0, 1.0, v16, vcc
	v_mul_f32_e32 v0, v1, v0
	v_mul_f32_e32 v0, v67, v0
	ds_write_b32 v70, v2 offset:640
	ds_write_b32 v70, v0 offset:37504
	v_add_f32_e32 v0, v19, v36
	v_mul_f32_e32 v0, 0xbfb8aa3b, v0
	v_exp_f32_e32 v0, v0
	v_add_f32_e32 v1, v3, v38
	v_mul_f32_e32 v1, 0xbfb8aa3b, v1
	v_exp_f32_e32 v1, v1
	v_add_f32_e32 v0, 1.0, v0
	v_rcp_f32_e32 v0, v0
	v_add_f32_e32 v1, 1.0, v1
	v_rcp_f32_e32 v1, v1
	v_mul_f32_e32 v0, v0, v32
	v_mul_f32_e32 v2, 0x3fb8aa3b, v0
	v_add_f32_e32 v0, v0, v0
	v_mul_f32_e32 v3, 0x3fb8aa3b, v0
	v_rndne_f32_e32 v3, v3
	v_fmamk_f32 v16, v3, 0xbf317218, v0
	v_fmac_f32_e32 v16, 0x3102e308, v3
	v_fmamk_f32 v17, v16, 0x395133b1, v192
	v_cmp_eq_f32_e32 vcc, s15, v3
	v_cvt_i32_f32_e32 v3, v3
	v_fmaak_f32 v17, v16, v17, 0x3c0887f9
	v_fmaak_f32 v17, v16, v17, 0x3d2aaa81
	v_fmaak_f32 v17, v16, v17, 0x3e2aaaab
	v_fma_f32 v17, v16, v17, 0.5
	v_ldexp_f32 v3, 1.0, v3
	v_mul_f32_e32 v17, v16, v17
	v_cndmask_b32_e32 v3, v3, v202, vcc
	v_fmac_f32_e32 v16, v16, v17
	v_add_f32_e32 v17, -1.0, v3
	v_fmac_f32_e32 v17, v3, v16
	v_add_f32_e32 v3, v17, v17
	v_cndmask_b32_e32 v3, v17, v3, vcc
	v_cmp_nlt_f32_e32 vcc, s16, v0
	v_exp_f32_e32 v2, v2
	s_nop 0
	v_cndmask_b32_e64 v3, v201, -v3, vcc
	v_cmp_gt_f32_e32 vcc, s17, v3
	v_mul_f32_e32 v16, 0x4f800000, v3
	s_nop 0
	v_cndmask_b32_e32 v3, v3, v16, vcc
	v_sqrt_f32_e32 v16, v3
	s_nop 0
	v_add_u32_e32 v17, -1, v16
	v_fma_f32 v18, -v17, v16, v3
	v_cmp_ge_f32_e64 s[0:1], 0, v18
	v_add_u32_e32 v18, 1, v16
	s_nop 0
	v_cndmask_b32_e64 v17, v16, v17, s[0:1]
	v_fma_f32 v16, -v18, v16, v3
	v_cmp_lt_f32_e64 s[0:1], 0, v16
	s_nop 1
	v_cndmask_b32_e64 v16, v17, v18, s[0:1]
	v_mul_f32_e32 v17, 0x37800000, v16
	v_cndmask_b32_e32 v16, v16, v17, vcc
	v_cmp_class_f32_e32 vcc, v3, v193
	s_nop 1
	v_cndmask_b32_e32 v3, v16, v3, vcc
	v_cmp_ngt_f32_e32 vcc, s18, v0
	s_nop 1
	v_cndmask_b32_e32 v0, 1.0, v3, vcc
	v_mul_f32_e32 v0, v1, v0
	v_mul_f32_e32 v0, v51, v0
	ds_write_b32 v70, v2 offset:896
	ds_write_b32 v70, v0 offset:37760
	v_add_f32_e32 v0, v20, v36
	v_mul_f32_e32 v0, 0xbfb8aa3b, v0
	v_exp_f32_e32 v0, v0
	v_add_f32_e32 v1, v4, v38
	v_mul_f32_e32 v1, 0xbfb8aa3b, v1
	v_exp_f32_e32 v1, v1
	v_add_f32_e32 v0, 1.0, v0
	v_rcp_f32_e32 v0, v0
	v_add_f32_e32 v1, 1.0, v1
	v_rcp_f32_e32 v1, v1
	v_mul_f32_e32 v0, v0, v32
	v_mul_f32_e32 v2, 0x3fb8aa3b, v0
	v_add_f32_e32 v0, v0, v0
	v_mul_f32_e32 v3, 0x3fb8aa3b, v0
	v_rndne_f32_e32 v3, v3
	v_fmamk_f32 v4, v3, 0xbf317218, v0
	v_fmac_f32_e32 v4, 0x3102e308, v3
	v_fmamk_f32 v16, v4, 0x395133b1, v192
	v_cmp_eq_f32_e32 vcc, s15, v3
	v_cvt_i32_f32_e32 v3, v3
	v_fmaak_f32 v16, v4, v16, 0x3c0887f9
	v_fmaak_f32 v16, v4, v16, 0x3d2aaa81
	v_fmaak_f32 v16, v4, v16, 0x3e2aaaab
	v_fma_f32 v16, v4, v16, 0.5
	v_ldexp_f32 v3, 1.0, v3
	v_mul_f32_e32 v16, v4, v16
	v_cndmask_b32_e32 v3, v3, v202, vcc
	v_fmac_f32_e32 v4, v4, v16
	v_add_f32_e32 v16, -1.0, v3
	v_fmac_f32_e32 v16, v3, v4
	v_add_f32_e32 v3, v16, v16
	v_cndmask_b32_e32 v3, v16, v3, vcc
	v_cmp_nlt_f32_e32 vcc, s16, v0
	v_exp_f32_e32 v2, v2
	s_nop 0
	v_cndmask_b32_e64 v3, v201, -v3, vcc
	v_cmp_gt_f32_e32 vcc, s17, v3
	v_mul_f32_e32 v4, 0x4f800000, v3
	s_nop 0
	v_cndmask_b32_e32 v3, v3, v4, vcc
	v_sqrt_f32_e32 v4, v3
	s_nop 0
	v_add_u32_e32 v16, -1, v4
	v_fma_f32 v17, -v16, v4, v3
	v_cmp_ge_f32_e64 s[0:1], 0, v17
	v_add_u32_e32 v17, 1, v4
	s_nop 0
	v_cndmask_b32_e64 v16, v4, v16, s[0:1]
	v_fma_f32 v4, -v17, v4, v3
	v_cmp_lt_f32_e64 s[0:1], 0, v4
	s_nop 1
	v_cndmask_b32_e64 v4, v16, v17, s[0:1]
	v_mul_f32_e32 v16, 0x37800000, v4
	v_cndmask_b32_e32 v4, v4, v16, vcc
	v_cmp_class_f32_e32 vcc, v3, v193
	s_nop 1
	v_cndmask_b32_e32 v3, v4, v3, vcc
	v_cmp_ngt_f32_e32 vcc, s18, v0
	s_nop 1
	v_cndmask_b32_e32 v0, 1.0, v3, vcc
	v_mul_f32_e32 v0, v1, v0
	v_mul_f32_e32 v0, v69, v0
	ds_write_b32 v70, v2 offset:2176
	ds_write_b32 v70, v0 offset:39040
	v_add_f32_e32 v0, v21, v36
	v_mul_f32_e32 v0, 0xbfb8aa3b, v0
	v_exp_f32_e32 v0, v0
	v_add_f32_e32 v1, v5, v38
	v_mul_f32_e32 v1, 0xbfb8aa3b, v1
	v_exp_f32_e32 v1, v1
	v_add_f32_e32 v0, 1.0, v0
	v_rcp_f32_e32 v0, v0
	v_add_f32_e32 v1, 1.0, v1
	v_rcp_f32_e32 v1, v1
	v_mul_f32_e32 v0, v0, v32
	v_mul_f32_e32 v2, 0x3fb8aa3b, v0
	v_add_f32_e32 v0, v0, v0
	v_mul_f32_e32 v3, 0x3fb8aa3b, v0
	v_rndne_f32_e32 v3, v3
	v_fmamk_f32 v4, v3, 0xbf317218, v0
	v_fmac_f32_e32 v4, 0x3102e308, v3
	v_fmamk_f32 v5, v4, 0x395133b1, v192
	v_cmp_eq_f32_e32 vcc, s15, v3
	v_cvt_i32_f32_e32 v3, v3
	v_fmaak_f32 v5, v4, v5, 0x3c0887f9
	v_fmaak_f32 v5, v4, v5, 0x3d2aaa81
	v_fmaak_f32 v5, v4, v5, 0x3e2aaaab
	v_fma_f32 v5, v4, v5, 0.5
	v_ldexp_f32 v3, 1.0, v3
	v_mul_f32_e32 v5, v4, v5
	v_cndmask_b32_e32 v3, v3, v202, vcc
	v_fmac_f32_e32 v4, v4, v5
	v_add_f32_e32 v5, -1.0, v3
	v_fmac_f32_e32 v5, v3, v4
	v_add_f32_e32 v3, v5, v5
	v_cndmask_b32_e32 v3, v5, v3, vcc
	v_cmp_nlt_f32_e32 vcc, s16, v0
	v_exp_f32_e32 v2, v2
	s_nop 0
	v_cndmask_b32_e64 v3, v201, -v3, vcc
	v_cmp_gt_f32_e32 vcc, s17, v3
	v_mul_f32_e32 v4, 0x4f800000, v3
	s_nop 0
	v_cndmask_b32_e32 v3, v3, v4, vcc
	v_sqrt_f32_e32 v4, v3
	s_nop 0
	v_add_u32_e32 v5, -1, v4
	v_fma_f32 v16, -v5, v4, v3
	v_cmp_ge_f32_e64 s[0:1], 0, v16
	v_add_u32_e32 v16, 1, v4
	s_nop 0
	v_cndmask_b32_e64 v5, v4, v5, s[0:1]
	v_fma_f32 v4, -v16, v4, v3
	v_cmp_lt_f32_e64 s[0:1], 0, v4
	s_nop 1
	v_cndmask_b32_e64 v4, v5, v16, s[0:1]
	v_mul_f32_e32 v5, 0x37800000, v4
	v_cndmask_b32_e32 v4, v4, v5, vcc
	v_cmp_class_f32_e32 vcc, v3, v193
	s_nop 1
	v_cndmask_b32_e32 v3, v4, v3, vcc
	v_cmp_ngt_f32_e32 vcc, s18, v0
	s_nop 1
	v_cndmask_b32_e32 v0, 1.0, v3, vcc
	v_mul_f32_e32 v0, v1, v0
	v_mul_f32_e32 v0, v37, v0
	ds_write_b32 v70, v2 offset:2432
	ds_write_b32 v70, v0 offset:39296
	v_add_f32_e32 v0, v22, v36
	v_mul_f32_e32 v0, 0xbfb8aa3b, v0
	v_exp_f32_e32 v0, v0
	v_add_f32_e32 v1, v6, v38
	v_mul_f32_e32 v1, 0xbfb8aa3b, v1
	v_exp_f32_e32 v1, v1
	v_add_f32_e32 v0, 1.0, v0
	v_rcp_f32_e32 v0, v0
	v_add_f32_e32 v1, 1.0, v1
	v_rcp_f32_e32 v1, v1
	v_mul_f32_e32 v0, v0, v32
	v_mul_f32_e32 v2, 0x3fb8aa3b, v0
	v_add_f32_e32 v0, v0, v0
	v_mul_f32_e32 v3, 0x3fb8aa3b, v0
	v_rndne_f32_e32 v3, v3
	v_fmamk_f32 v4, v3, 0xbf317218, v0
	v_fmac_f32_e32 v4, 0x3102e308, v3
	v_fmamk_f32 v5, v4, 0x395133b1, v192
	v_cmp_eq_f32_e32 vcc, s15, v3
	v_cvt_i32_f32_e32 v3, v3
	v_fmaak_f32 v5, v4, v5, 0x3c0887f9
	v_fmaak_f32 v5, v4, v5, 0x3d2aaa81
	v_fmaak_f32 v5, v4, v5, 0x3e2aaaab
	v_fma_f32 v5, v4, v5, 0.5
	v_ldexp_f32 v3, 1.0, v3
	v_mul_f32_e32 v5, v4, v5
	v_cndmask_b32_e32 v3, v3, v202, vcc
	v_fmac_f32_e32 v4, v4, v5
	v_add_f32_e32 v5, -1.0, v3
	v_fmac_f32_e32 v5, v3, v4
	v_add_f32_e32 v3, v5, v5
	v_cndmask_b32_e32 v3, v5, v3, vcc
	v_cmp_nlt_f32_e32 vcc, s16, v0
	v_exp_f32_e32 v2, v2
	s_nop 0
	v_cndmask_b32_e64 v3, v201, -v3, vcc
	v_cmp_gt_f32_e32 vcc, s17, v3
	v_mul_f32_e32 v4, 0x4f800000, v3
	s_nop 0
	v_cndmask_b32_e32 v3, v3, v4, vcc
	v_sqrt_f32_e32 v4, v3
	s_nop 0
	v_add_u32_e32 v5, -1, v4
	v_fma_f32 v6, -v5, v4, v3
	v_cmp_ge_f32_e64 s[0:1], 0, v6
	v_add_u32_e32 v6, 1, v4
	s_nop 0
	v_cndmask_b32_e64 v5, v4, v5, s[0:1]
	v_fma_f32 v4, -v6, v4, v3
	v_cmp_lt_f32_e64 s[0:1], 0, v4
	s_nop 1
	v_cndmask_b32_e64 v4, v5, v6, s[0:1]
	v_mul_f32_e32 v5, 0x37800000, v4
	v_cndmask_b32_e32 v4, v4, v5, vcc
	v_cmp_class_f32_e32 vcc, v3, v193
	s_nop 1
	v_cndmask_b32_e32 v3, v4, v3, vcc
	v_cmp_ngt_f32_e32 vcc, s18, v0
	s_nop 1
	v_cndmask_b32_e32 v0, 1.0, v3, vcc
	v_mul_f32_e32 v0, v1, v0
	v_mul_f32_e32 v0, v53, v0
	ds_write_b32 v70, v2 offset:2688
	ds_write_b32 v70, v0 offset:39552
	v_add_f32_e32 v0, v23, v36
	v_mul_f32_e32 v0, 0xbfb8aa3b, v0
	v_exp_f32_e32 v0, v0
	v_add_f32_e32 v1, v7, v38
	v_mul_f32_e32 v1, 0xbfb8aa3b, v1
	v_exp_f32_e32 v1, v1
	v_add_f32_e32 v0, 1.0, v0
	v_rcp_f32_e32 v0, v0
	v_add_f32_e32 v1, 1.0, v1
	v_rcp_f32_e32 v1, v1
	v_mul_f32_e32 v0, v0, v32
	v_mul_f32_e32 v2, 0x3fb8aa3b, v0
	v_add_f32_e32 v0, v0, v0
	v_mul_f32_e32 v3, 0x3fb8aa3b, v0
	v_rndne_f32_e32 v3, v3
	v_fmamk_f32 v4, v3, 0xbf317218, v0
	v_fmac_f32_e32 v4, 0x3102e308, v3
	v_fmamk_f32 v5, v4, 0x395133b1, v192
	v_cmp_eq_f32_e32 vcc, s15, v3
	v_cvt_i32_f32_e32 v3, v3
	v_fmaak_f32 v5, v4, v5, 0x3c0887f9
	v_fmaak_f32 v5, v4, v5, 0x3d2aaa81
	v_fmaak_f32 v5, v4, v5, 0x3e2aaaab
	v_fma_f32 v5, v4, v5, 0.5
	v_ldexp_f32 v3, 1.0, v3
	v_mul_f32_e32 v5, v4, v5
	v_cndmask_b32_e32 v3, v3, v202, vcc
	v_fmac_f32_e32 v4, v4, v5
	v_add_f32_e32 v5, -1.0, v3
	v_fmac_f32_e32 v5, v3, v4
	v_add_f32_e32 v3, v5, v5
	v_cndmask_b32_e32 v3, v5, v3, vcc
	v_cmp_nlt_f32_e32 vcc, s16, v0
	v_exp_f32_e32 v2, v2
	s_nop 0
	v_cndmask_b32_e64 v3, v201, -v3, vcc
	v_cmp_gt_f32_e32 vcc, s17, v3
	v_mul_f32_e32 v4, 0x4f800000, v3
	s_nop 0
	v_cndmask_b32_e32 v3, v3, v4, vcc
	v_sqrt_f32_e32 v4, v3
	s_nop 0
	v_add_u32_e32 v5, -1, v4
	v_fma_f32 v6, -v5, v4, v3
	v_cmp_ge_f32_e64 s[0:1], 0, v6
	v_add_u32_e32 v6, 1, v4
	s_nop 0
	v_cndmask_b32_e64 v5, v4, v5, s[0:1]
	v_fma_f32 v4, -v6, v4, v3
	v_cmp_lt_f32_e64 s[0:1], 0, v4
	s_nop 1
	v_cndmask_b32_e64 v4, v5, v6, s[0:1]
	v_mul_f32_e32 v5, 0x37800000, v4
	v_cndmask_b32_e32 v4, v4, v5, vcc
	v_cmp_class_f32_e32 vcc, v3, v193
	s_nop 1
	v_cndmask_b32_e32 v3, v4, v3, vcc
	v_cmp_ngt_f32_e32 vcc, s18, v0
	s_nop 1
	v_cndmask_b32_e32 v0, 1.0, v3, vcc
	v_mul_f32_e32 v0, v1, v0
	v_mul_f32_e32 v0, v39, v0
	ds_write_b32 v70, v2 offset:2944
	ds_write_b32 v70, v0 offset:39808
	v_add_f32_e32 v0, v24, v36
	v_mul_f32_e32 v0, 0xbfb8aa3b, v0
	v_exp_f32_e32 v0, v0
	v_add_f32_e32 v1, v8, v38
	v_mul_f32_e32 v1, 0xbfb8aa3b, v1
	v_exp_f32_e32 v1, v1
	v_add_f32_e32 v0, 1.0, v0
	v_rcp_f32_e32 v0, v0
	v_add_f32_e32 v1, 1.0, v1
	v_rcp_f32_e32 v1, v1
	v_mul_f32_e32 v0, v0, v32
	v_mul_f32_e32 v2, 0x3fb8aa3b, v0
	v_add_f32_e32 v0, v0, v0
	v_mul_f32_e32 v3, 0x3fb8aa3b, v0
	v_rndne_f32_e32 v3, v3
	v_fmamk_f32 v4, v3, 0xbf317218, v0
	v_fmac_f32_e32 v4, 0x3102e308, v3
	v_fmamk_f32 v5, v4, 0x395133b1, v192
	v_cmp_eq_f32_e32 vcc, s15, v3
	v_cvt_i32_f32_e32 v3, v3
	v_fmaak_f32 v5, v4, v5, 0x3c0887f9
	v_fmaak_f32 v5, v4, v5, 0x3d2aaa81
	v_fmaak_f32 v5, v4, v5, 0x3e2aaaab
	v_fma_f32 v5, v4, v5, 0.5
	v_ldexp_f32 v3, 1.0, v3
	v_mul_f32_e32 v5, v4, v5
	v_cndmask_b32_e32 v3, v3, v202, vcc
	v_fmac_f32_e32 v4, v4, v5
	v_add_f32_e32 v5, -1.0, v3
	v_fmac_f32_e32 v5, v3, v4
	v_add_f32_e32 v3, v5, v5
	v_cndmask_b32_e32 v3, v5, v3, vcc
	v_cmp_nlt_f32_e32 vcc, s16, v0
	v_exp_f32_e32 v2, v2
	s_nop 0
	v_cndmask_b32_e64 v3, v201, -v3, vcc
	v_cmp_gt_f32_e32 vcc, s17, v3
	v_mul_f32_e32 v4, 0x4f800000, v3
	s_nop 0
	v_cndmask_b32_e32 v3, v3, v4, vcc
	v_sqrt_f32_e32 v4, v3
	s_nop 0
	v_add_u32_e32 v5, -1, v4
	v_fma_f32 v6, -v5, v4, v3
	v_cmp_ge_f32_e64 s[0:1], 0, v6
	v_add_u32_e32 v6, 1, v4
	s_nop 0
	v_cndmask_b32_e64 v5, v4, v5, s[0:1]
	v_fma_f32 v4, -v6, v4, v3
	v_cmp_lt_f32_e64 s[0:1], 0, v4
	s_nop 1
	v_cndmask_b32_e64 v4, v5, v6, s[0:1]
	v_mul_f32_e32 v5, 0x37800000, v4
	v_cndmask_b32_e32 v4, v4, v5, vcc
	v_cmp_class_f32_e32 vcc, v3, v193
	s_nop 1
	v_cndmask_b32_e32 v3, v4, v3, vcc
	v_cmp_ngt_f32_e32 vcc, s18, v0
	s_nop 1
	v_cndmask_b32_e32 v0, 1.0, v3, vcc
	v_mul_f32_e32 v0, v1, v0
	v_mul_f32_e32 v0, v55, v0
	ds_write_b32 v70, v2 offset:4224
	ds_write_b32 v70, v0 offset:41088
	v_add_f32_e32 v0, v25, v36
	v_mul_f32_e32 v0, 0xbfb8aa3b, v0
	v_exp_f32_e32 v0, v0
	v_add_f32_e32 v1, v9, v38
	v_mul_f32_e32 v1, 0xbfb8aa3b, v1
	v_exp_f32_e32 v1, v1
	v_add_f32_e32 v0, 1.0, v0
	v_rcp_f32_e32 v0, v0
	v_add_f32_e32 v1, 1.0, v1
	v_rcp_f32_e32 v1, v1
	v_mul_f32_e32 v0, v0, v32
	v_mul_f32_e32 v2, 0x3fb8aa3b, v0
	v_add_f32_e32 v0, v0, v0
	v_mul_f32_e32 v3, 0x3fb8aa3b, v0
	v_rndne_f32_e32 v3, v3
	v_fmamk_f32 v4, v3, 0xbf317218, v0
	v_fmac_f32_e32 v4, 0x3102e308, v3
	v_fmamk_f32 v5, v4, 0x395133b1, v192
	v_cmp_eq_f32_e32 vcc, s15, v3
	v_cvt_i32_f32_e32 v3, v3
	v_fmaak_f32 v5, v4, v5, 0x3c0887f9
	v_fmaak_f32 v5, v4, v5, 0x3d2aaa81
	v_fmaak_f32 v5, v4, v5, 0x3e2aaaab
	v_fma_f32 v5, v4, v5, 0.5
	v_ldexp_f32 v3, 1.0, v3
	v_mul_f32_e32 v5, v4, v5
	v_cndmask_b32_e32 v3, v3, v202, vcc
	v_fmac_f32_e32 v4, v4, v5
	v_add_f32_e32 v5, -1.0, v3
	v_fmac_f32_e32 v5, v3, v4
	v_add_f32_e32 v3, v5, v5
	v_cndmask_b32_e32 v3, v5, v3, vcc
	v_cmp_nlt_f32_e32 vcc, s16, v0
	v_exp_f32_e32 v2, v2
	s_nop 0
	v_cndmask_b32_e64 v3, v201, -v3, vcc
	v_cmp_gt_f32_e32 vcc, s17, v3
	v_mul_f32_e32 v4, 0x4f800000, v3
	s_nop 0
	v_cndmask_b32_e32 v3, v3, v4, vcc
	v_sqrt_f32_e32 v4, v3
	s_nop 0
	v_add_u32_e32 v5, -1, v4
	v_fma_f32 v6, -v5, v4, v3
	v_cmp_ge_f32_e64 s[0:1], 0, v6
	v_add_u32_e32 v6, 1, v4
	s_nop 0
	v_cndmask_b32_e64 v5, v4, v5, s[0:1]
	v_fma_f32 v4, -v6, v4, v3
	v_cmp_lt_f32_e64 s[0:1], 0, v4
	s_nop 1
	v_cndmask_b32_e64 v4, v5, v6, s[0:1]
	v_mul_f32_e32 v5, 0x37800000, v4
	v_cndmask_b32_e32 v4, v4, v5, vcc
	v_cmp_class_f32_e32 vcc, v3, v193
	s_nop 1
	v_cndmask_b32_e32 v3, v4, v3, vcc
	v_cmp_ngt_f32_e32 vcc, s18, v0
	s_nop 1
	v_cndmask_b32_e32 v0, 1.0, v3, vcc
	v_mul_f32_e32 v0, v1, v0
	v_mul_f32_e32 v0, v41, v0
	ds_write_b32 v70, v2 offset:4480
	ds_write_b32 v70, v0 offset:41344
	v_add_f32_e32 v0, v26, v36
	v_mul_f32_e32 v0, 0xbfb8aa3b, v0
	v_exp_f32_e32 v0, v0
	v_add_f32_e32 v1, v10, v38
	v_mul_f32_e32 v1, 0xbfb8aa3b, v1
	v_exp_f32_e32 v1, v1
	v_add_f32_e32 v0, 1.0, v0
	v_rcp_f32_e32 v0, v0
	v_add_f32_e32 v1, 1.0, v1
	v_rcp_f32_e32 v1, v1
	v_mul_f32_e32 v0, v0, v32
	v_mul_f32_e32 v2, 0x3fb8aa3b, v0
	v_add_f32_e32 v0, v0, v0
	v_mul_f32_e32 v3, 0x3fb8aa3b, v0
	v_rndne_f32_e32 v3, v3
	v_fmamk_f32 v4, v3, 0xbf317218, v0
	v_fmac_f32_e32 v4, 0x3102e308, v3
	v_fmamk_f32 v5, v4, 0x395133b1, v192
	v_cmp_eq_f32_e32 vcc, s15, v3
	v_cvt_i32_f32_e32 v3, v3
	v_fmaak_f32 v5, v4, v5, 0x3c0887f9
	v_fmaak_f32 v5, v4, v5, 0x3d2aaa81
	v_fmaak_f32 v5, v4, v5, 0x3e2aaaab
	v_fma_f32 v5, v4, v5, 0.5
	v_ldexp_f32 v3, 1.0, v3
	v_mul_f32_e32 v5, v4, v5
	v_cndmask_b32_e32 v3, v3, v202, vcc
	v_fmac_f32_e32 v4, v4, v5
	v_add_f32_e32 v5, -1.0, v3
	v_fmac_f32_e32 v5, v3, v4
	v_add_f32_e32 v3, v5, v5
	v_cndmask_b32_e32 v3, v5, v3, vcc
	v_cmp_nlt_f32_e32 vcc, s16, v0
	v_exp_f32_e32 v2, v2
	s_nop 0
	v_cndmask_b32_e64 v3, v201, -v3, vcc
	v_cmp_gt_f32_e32 vcc, s17, v3
	v_mul_f32_e32 v4, 0x4f800000, v3
	s_nop 0
	v_cndmask_b32_e32 v3, v3, v4, vcc
	v_sqrt_f32_e32 v4, v3
	s_nop 0
	v_add_u32_e32 v5, -1, v4
	v_fma_f32 v6, -v5, v4, v3
	v_cmp_ge_f32_e64 s[0:1], 0, v6
	v_add_u32_e32 v6, 1, v4
	s_nop 0
	v_cndmask_b32_e64 v5, v4, v5, s[0:1]
	v_fma_f32 v4, -v6, v4, v3
	v_cmp_lt_f32_e64 s[0:1], 0, v4
	s_nop 1
	v_cndmask_b32_e64 v4, v5, v6, s[0:1]
	v_mul_f32_e32 v5, 0x37800000, v4
	v_cndmask_b32_e32 v4, v4, v5, vcc
	v_cmp_class_f32_e32 vcc, v3, v193
	s_nop 1
	v_cndmask_b32_e32 v3, v4, v3, vcc
	v_cmp_ngt_f32_e32 vcc, s18, v0
	s_nop 1
	v_cndmask_b32_e32 v0, 1.0, v3, vcc
	v_mul_f32_e32 v0, v1, v0
	v_mul_f32_e32 v0, v57, v0
	ds_write_b32 v70, v2 offset:4736
	ds_write_b32 v70, v0 offset:41600
	v_add_f32_e32 v0, v27, v36
	v_mul_f32_e32 v0, 0xbfb8aa3b, v0
	v_exp_f32_e32 v0, v0
	v_add_f32_e32 v1, v11, v38
	v_mul_f32_e32 v1, 0xbfb8aa3b, v1
	v_exp_f32_e32 v1, v1
	v_add_f32_e32 v0, 1.0, v0
	v_rcp_f32_e32 v0, v0
	v_add_f32_e32 v1, 1.0, v1
	v_rcp_f32_e32 v1, v1
	v_mul_f32_e32 v0, v0, v32
	v_mul_f32_e32 v2, 0x3fb8aa3b, v0
	v_add_f32_e32 v0, v0, v0
	v_mul_f32_e32 v3, 0x3fb8aa3b, v0
	v_rndne_f32_e32 v3, v3
	v_fmamk_f32 v4, v3, 0xbf317218, v0
	v_fmac_f32_e32 v4, 0x3102e308, v3
	v_fmamk_f32 v5, v4, 0x395133b1, v192
	v_cmp_eq_f32_e32 vcc, s15, v3
	v_cvt_i32_f32_e32 v3, v3
	v_fmaak_f32 v5, v4, v5, 0x3c0887f9
	v_fmaak_f32 v5, v4, v5, 0x3d2aaa81
	v_fmaak_f32 v5, v4, v5, 0x3e2aaaab
	v_fma_f32 v5, v4, v5, 0.5
	v_ldexp_f32 v3, 1.0, v3
	v_mul_f32_e32 v5, v4, v5
	v_cndmask_b32_e32 v3, v3, v202, vcc
	v_fmac_f32_e32 v4, v4, v5
	v_add_f32_e32 v5, -1.0, v3
	v_fmac_f32_e32 v5, v3, v4
	v_add_f32_e32 v3, v5, v5
	v_cndmask_b32_e32 v3, v5, v3, vcc
	v_cmp_nlt_f32_e32 vcc, s16, v0
	v_exp_f32_e32 v2, v2
	s_nop 0
	v_cndmask_b32_e64 v3, v201, -v3, vcc
	v_cmp_gt_f32_e32 vcc, s17, v3
	v_mul_f32_e32 v4, 0x4f800000, v3
	s_nop 0
	v_cndmask_b32_e32 v3, v3, v4, vcc
	v_sqrt_f32_e32 v4, v3
	s_nop 0
	v_add_u32_e32 v5, -1, v4
	v_fma_f32 v6, -v5, v4, v3
	v_cmp_ge_f32_e64 s[0:1], 0, v6
	v_add_u32_e32 v6, 1, v4
	s_nop 0
	v_cndmask_b32_e64 v5, v4, v5, s[0:1]
	v_fma_f32 v4, -v6, v4, v3
	v_cmp_lt_f32_e64 s[0:1], 0, v4
	s_nop 1
	v_cndmask_b32_e64 v4, v5, v6, s[0:1]
	v_mul_f32_e32 v5, 0x37800000, v4
	v_cndmask_b32_e32 v4, v4, v5, vcc
	v_cmp_class_f32_e32 vcc, v3, v193
	s_nop 1
	v_cndmask_b32_e32 v3, v4, v3, vcc
	v_cmp_ngt_f32_e32 vcc, s18, v0
	s_nop 1
	v_cndmask_b32_e32 v0, 1.0, v3, vcc
	v_mul_f32_e32 v0, v1, v0
	v_mul_f32_e32 v0, v43, v0
	ds_write_b32 v70, v2 offset:4992
	ds_write_b32 v70, v0 offset:41856
	v_add_f32_e32 v0, v28, v36
	v_mul_f32_e32 v0, 0xbfb8aa3b, v0
	v_exp_f32_e32 v0, v0
	v_add_f32_e32 v1, v12, v38
	v_mul_f32_e32 v1, 0xbfb8aa3b, v1
	v_exp_f32_e32 v1, v1
	v_add_f32_e32 v0, 1.0, v0
	v_rcp_f32_e32 v0, v0
	v_add_f32_e32 v1, 1.0, v1
	v_rcp_f32_e32 v1, v1
	v_mul_f32_e32 v0, v0, v32
	v_mul_f32_e32 v2, 0x3fb8aa3b, v0
	v_add_f32_e32 v0, v0, v0
	v_mul_f32_e32 v3, 0x3fb8aa3b, v0
	v_rndne_f32_e32 v3, v3
	v_fmamk_f32 v4, v3, 0xbf317218, v0
	v_fmac_f32_e32 v4, 0x3102e308, v3
	v_fmamk_f32 v5, v4, 0x395133b1, v192
	v_cmp_eq_f32_e32 vcc, s15, v3
	v_cvt_i32_f32_e32 v3, v3
	v_fmaak_f32 v5, v4, v5, 0x3c0887f9
	v_fmaak_f32 v5, v4, v5, 0x3d2aaa81
	v_fmaak_f32 v5, v4, v5, 0x3e2aaaab
	v_fma_f32 v5, v4, v5, 0.5
	v_ldexp_f32 v3, 1.0, v3
	v_mul_f32_e32 v5, v4, v5
	v_cndmask_b32_e32 v3, v3, v202, vcc
	v_fmac_f32_e32 v4, v4, v5
	v_add_f32_e32 v5, -1.0, v3
	v_fmac_f32_e32 v5, v3, v4
	v_add_f32_e32 v3, v5, v5
	v_cndmask_b32_e32 v3, v5, v3, vcc
	v_cmp_nlt_f32_e32 vcc, s16, v0
	v_exp_f32_e32 v2, v2
	s_nop 0
	v_cndmask_b32_e64 v3, v201, -v3, vcc
	v_cmp_gt_f32_e32 vcc, s17, v3
	v_mul_f32_e32 v4, 0x4f800000, v3
	s_nop 0
	v_cndmask_b32_e32 v3, v3, v4, vcc
	v_sqrt_f32_e32 v4, v3
	s_nop 0
	v_add_u32_e32 v5, -1, v4
	v_fma_f32 v6, -v5, v4, v3
	v_cmp_ge_f32_e64 s[0:1], 0, v6
	v_add_u32_e32 v6, 1, v4
	s_nop 0
	v_cndmask_b32_e64 v5, v4, v5, s[0:1]
	v_fma_f32 v4, -v6, v4, v3
	v_cmp_lt_f32_e64 s[0:1], 0, v4
	s_nop 1
	v_cndmask_b32_e64 v4, v5, v6, s[0:1]
	v_mul_f32_e32 v5, 0x37800000, v4
	v_cndmask_b32_e32 v4, v4, v5, vcc
	v_cmp_class_f32_e32 vcc, v3, v193
	s_nop 1
	v_cndmask_b32_e32 v3, v4, v3, vcc
	v_cmp_ngt_f32_e32 vcc, s18, v0
	s_nop 1
	v_cndmask_b32_e32 v0, 1.0, v3, vcc
	v_mul_f32_e32 v0, v1, v0
	v_mul_f32_e32 v0, v59, v0
	ds_write_b32 v70, v2 offset:6272
	ds_write_b32 v70, v0 offset:43136
	v_add_f32_e32 v0, v29, v36
	v_mul_f32_e32 v0, 0xbfb8aa3b, v0
	v_exp_f32_e32 v0, v0
	v_add_f32_e32 v1, v13, v38
	v_mul_f32_e32 v1, 0xbfb8aa3b, v1
	v_exp_f32_e32 v1, v1
	v_add_f32_e32 v0, 1.0, v0
	v_rcp_f32_e32 v0, v0
	v_add_f32_e32 v1, 1.0, v1
	v_rcp_f32_e32 v1, v1
	v_mul_f32_e32 v0, v0, v32
	v_mul_f32_e32 v2, 0x3fb8aa3b, v0
	v_add_f32_e32 v0, v0, v0
	v_mul_f32_e32 v3, 0x3fb8aa3b, v0
	v_rndne_f32_e32 v3, v3
	v_fmamk_f32 v4, v3, 0xbf317218, v0
	v_fmac_f32_e32 v4, 0x3102e308, v3
	v_fmamk_f32 v5, v4, 0x395133b1, v192
	v_cmp_eq_f32_e32 vcc, s15, v3
	v_cvt_i32_f32_e32 v3, v3
	v_fmaak_f32 v5, v4, v5, 0x3c0887f9
	v_fmaak_f32 v5, v4, v5, 0x3d2aaa81
	v_fmaak_f32 v5, v4, v5, 0x3e2aaaab
	v_fma_f32 v5, v4, v5, 0.5
	v_ldexp_f32 v3, 1.0, v3
	v_mul_f32_e32 v5, v4, v5
	v_cndmask_b32_e32 v3, v3, v202, vcc
	v_fmac_f32_e32 v4, v4, v5
	v_add_f32_e32 v5, -1.0, v3
	v_fmac_f32_e32 v5, v3, v4
	v_add_f32_e32 v3, v5, v5
	v_cndmask_b32_e32 v3, v5, v3, vcc
	v_cmp_nlt_f32_e32 vcc, s16, v0
	v_exp_f32_e32 v2, v2
	s_nop 0
	v_cndmask_b32_e64 v3, v201, -v3, vcc
	v_cmp_gt_f32_e32 vcc, s17, v3
	v_mul_f32_e32 v4, 0x4f800000, v3
	s_nop 0
	v_cndmask_b32_e32 v3, v3, v4, vcc
	v_sqrt_f32_e32 v4, v3
	s_nop 0
	v_add_u32_e32 v5, -1, v4
	v_fma_f32 v6, -v5, v4, v3
	v_cmp_ge_f32_e64 s[0:1], 0, v6
	v_add_u32_e32 v6, 1, v4
	s_nop 0
	v_cndmask_b32_e64 v5, v4, v5, s[0:1]
	v_fma_f32 v4, -v6, v4, v3
	v_cmp_lt_f32_e64 s[0:1], 0, v4
	s_nop 1
	v_cndmask_b32_e64 v4, v5, v6, s[0:1]
	v_mul_f32_e32 v5, 0x37800000, v4
	v_cndmask_b32_e32 v4, v4, v5, vcc
	v_cmp_class_f32_e32 vcc, v3, v193
	s_nop 1
	v_cndmask_b32_e32 v3, v4, v3, vcc
	v_cmp_ngt_f32_e32 vcc, s18, v0
	s_nop 1
	v_cndmask_b32_e32 v0, 1.0, v3, vcc
	v_mul_f32_e32 v0, v1, v0
	v_mul_f32_e32 v0, v45, v0
	ds_write_b32 v70, v2 offset:6528
	ds_write_b32 v70, v0 offset:43392
	v_add_f32_e32 v0, v30, v36
	v_mul_f32_e32 v0, 0xbfb8aa3b, v0
	v_exp_f32_e32 v0, v0
	v_add_f32_e32 v1, v14, v38
	v_mul_f32_e32 v1, 0xbfb8aa3b, v1
	v_exp_f32_e32 v1, v1
	v_add_f32_e32 v0, 1.0, v0
	v_rcp_f32_e32 v0, v0
	v_add_f32_e32 v1, 1.0, v1
	v_rcp_f32_e32 v1, v1
	v_mul_f32_e32 v0, v0, v32
	v_mul_f32_e32 v2, 0x3fb8aa3b, v0
	v_add_f32_e32 v0, v0, v0
	v_mul_f32_e32 v3, 0x3fb8aa3b, v0
	v_rndne_f32_e32 v3, v3
	v_fmamk_f32 v4, v3, 0xbf317218, v0
	v_fmac_f32_e32 v4, 0x3102e308, v3
	v_fmamk_f32 v5, v4, 0x395133b1, v192
	v_cmp_eq_f32_e32 vcc, s15, v3
	v_cvt_i32_f32_e32 v3, v3
	v_fmaak_f32 v5, v4, v5, 0x3c0887f9
	v_fmaak_f32 v5, v4, v5, 0x3d2aaa81
	v_fmaak_f32 v5, v4, v5, 0x3e2aaaab
	v_fma_f32 v5, v4, v5, 0.5
	v_ldexp_f32 v3, 1.0, v3
	v_mul_f32_e32 v5, v4, v5
	v_cndmask_b32_e32 v3, v3, v202, vcc
	v_fmac_f32_e32 v4, v4, v5
	v_add_f32_e32 v5, -1.0, v3
	v_fmac_f32_e32 v5, v3, v4
	v_add_f32_e32 v3, v5, v5
	v_cndmask_b32_e32 v3, v5, v3, vcc
	v_cmp_nlt_f32_e32 vcc, s16, v0
	v_exp_f32_e32 v2, v2
	s_nop 0
	v_cndmask_b32_e64 v3, v201, -v3, vcc
	v_cmp_gt_f32_e32 vcc, s17, v3
	v_mul_f32_e32 v4, 0x4f800000, v3
	s_nop 0
	v_cndmask_b32_e32 v3, v3, v4, vcc
	v_sqrt_f32_e32 v4, v3
	s_nop 0
	v_add_u32_e32 v5, -1, v4
	v_fma_f32 v6, -v5, v4, v3
	v_cmp_ge_f32_e64 s[0:1], 0, v6
	v_add_u32_e32 v6, 1, v4
	s_nop 0
	v_cndmask_b32_e64 v5, v4, v5, s[0:1]
	v_fma_f32 v4, -v6, v4, v3
	v_cmp_lt_f32_e64 s[0:1], 0, v4
	s_nop 1
	v_cndmask_b32_e64 v4, v5, v6, s[0:1]
	v_mul_f32_e32 v5, 0x37800000, v4
	v_cndmask_b32_e32 v4, v4, v5, vcc
	v_cmp_class_f32_e32 vcc, v3, v193
	s_nop 1
	v_cndmask_b32_e32 v3, v4, v3, vcc
	v_cmp_ngt_f32_e32 vcc, s18, v0
	s_nop 1
	v_cndmask_b32_e32 v0, 1.0, v3, vcc
	v_mul_f32_e32 v0, v1, v0
	v_mul_f32_e32 v0, v35, v0
	v_add_u32_e32 v1, 0x1800, v70
	ds_write2_b32 v1, v2, v34 offset0:160 offset1:192
	ds_write_b32 v70, v0 offset:43648
	v_add_f32_e32 v0, v31, v36
	v_mul_f32_e32 v0, 0xbfb8aa3b, v0
	v_exp_f32_e32 v0, v0
	v_add_f32_e32 v1, v15, v38
	v_mul_f32_e32 v1, 0xbfb8aa3b, v1
	v_exp_f32_e32 v1, v1
	v_add_f32_e32 v0, 1.0, v0
	v_rcp_f32_e32 v0, v0
	v_add_f32_e32 v1, 1.0, v1
	v_rcp_f32_e32 v1, v1
	v_mul_f32_e32 v0, v0, v32
	v_mul_f32_e32 v2, 0x3fb8aa3b, v0
	v_add_f32_e32 v0, v0, v0
	v_mul_f32_e32 v3, 0x3fb8aa3b, v0
	v_rndne_f32_e32 v3, v3
	v_fmamk_f32 v4, v3, 0xbf317218, v0
	v_fmac_f32_e32 v4, 0x3102e308, v3
	v_fmamk_f32 v5, v4, 0x395133b1, v192
	v_cmp_eq_f32_e32 vcc, s15, v3
	v_cvt_i32_f32_e32 v3, v3
	v_fmaak_f32 v5, v4, v5, 0x3c0887f9
	v_fmaak_f32 v5, v4, v5, 0x3d2aaa81
	v_fmaak_f32 v5, v4, v5, 0x3e2aaaab
	v_fma_f32 v5, v4, v5, 0.5
	v_ldexp_f32 v3, 1.0, v3
	v_mul_f32_e32 v5, v4, v5
	v_cndmask_b32_e32 v3, v3, v202, vcc
	v_fmac_f32_e32 v4, v4, v5
	v_add_f32_e32 v5, -1.0, v3
	v_fmac_f32_e32 v5, v3, v4
	v_add_f32_e32 v3, v5, v5
	v_cndmask_b32_e32 v3, v5, v3, vcc
	v_cmp_nlt_f32_e32 vcc, s16, v0
	v_exp_f32_e32 v2, v2
	s_nop 0
	v_cndmask_b32_e64 v3, v201, -v3, vcc
	v_cmp_gt_f32_e32 vcc, s17, v3
	v_mul_f32_e32 v4, 0x4f800000, v3
	s_nop 0
	v_cndmask_b32_e32 v3, v3, v4, vcc
	v_sqrt_f32_e32 v4, v3
	s_nop 0
	v_add_u32_e32 v5, -1, v4
	v_fma_f32 v6, -v5, v4, v3
	v_cmp_ge_f32_e64 s[0:1], 0, v6
	v_add_u32_e32 v6, 1, v4
	s_nop 0
	v_cndmask_b32_e64 v5, v4, v5, s[0:1]
	v_fma_f32 v4, -v6, v4, v3
	v_cmp_lt_f32_e64 s[0:1], 0, v4
	s_nop 1
	v_cndmask_b32_e64 v4, v5, v6, s[0:1]
	v_mul_f32_e32 v5, 0x37800000, v4
	v_cndmask_b32_e32 v4, v4, v5, vcc
	v_cmp_class_f32_e32 vcc, v3, v193
	v_mov_b32_e32 v6, 1.0
	s_mov_b32 s0, 24
	v_cndmask_b32_e32 v3, v4, v3, vcc
	v_cmp_ngt_f32_e32 vcc, s18, v0
	s_nop 1
	v_cndmask_b32_e32 v0, 1.0, v3, vcc
	v_mul_f32_e32 v0, v1, v0
	v_mul_f32_e32 v0, v33, v0
	ds_write_b32 v70, v2 offset:7040
	ds_write_b32 v70, v0 offset:43904
	v_mov_b32_e32 v2, v162
	s_waitcnt lgkmcnt(0)
	s_barrier
	s_cselect_b64 vcc, -1, 0
	v_and_b32_e32 v3, 63, v2
	v_ashrrev_i32_e32 v4, 6, v2
	v_lshl_or_b32 v5, v4, 11, v3
	v_mov_b32_e32 v1, 0

.LBB0_589:
	s_or_b64 exec, exec, s[6:7]
	v_cmp_gt_u32_e64 s[0:1], 64, v65
	s_waitcnt lgkmcnt(0)
	s_barrier
	s_and_saveexec_b64 s[6:7], s[0:1]
	s_cbranch_execz .LBB0_592
	v_lshlrev_b32_e32 v0, 1, v65
	s_cmp_eq_u32 s13, 0
	s_cselect_b64 s[0:1], -1, 0
	v_sub_u32_e32 v3, 0x7f, v0
	v_cndmask_b32_e64 v3, v3, v0, s[0:1]
	v_sub_u32_e32 v4, 0x7e, v0
	v_or_b32_e32 v0, 1, v0
	v_cndmask_b32_e64 v0, v4, v0, s[0:1]
	v_lshlrev_b32_e32 v3, 2, v3
	s_add_i32 s0, 0, 0x11200
	v_lshlrev_b32_e32 v5, 2, v0
	v_add_u32_e32 v4, s0, v3
	v_add_u32_e32 v0, s0, v5
	ds_read_b32 v4, v4
	ds_read_b32 v0, v0
	v_and_b32_e32 v1, 63, v65
	v_cmp_eq_u32_e64 s[38:39], 0, v1
	s_waitcnt lgkmcnt(0)
	v_add_f32_e32 v6, v4, v0
	v_mbcnt_hi_u32_b32 v0, -1, v195
	v_and_b32_e32 v7, 64, v0
	v_add_u32_e32 v8, -1, v0
	v_cmp_lt_i32_e64 s[0:1], v8, v7
	v_add_u32_e32 v9, -2, v0
	s_nop 0
	v_cndmask_b32_e64 v8, v8, v0, s[0:1]
	v_lshlrev_b32_e32 v8, 2, v8
	ds_bpermute_b32 v8, v8, v6
	v_cmp_lt_i32_e64 s[0:1], v9, v7
	s_waitcnt lgkmcnt(0)
	v_add_f32_e32 v8, v6, v8
	v_cndmask_b32_e64 v9, v9, v0, s[0:1]
	v_cndmask_b32_e64 v8, v8, v6, s[38:39]
	v_lshlrev_b32_e32 v9, 2, v9
	ds_bpermute_b32 v9, v9, v8
	v_cmp_gt_u32_e64 s[0:1], 2, v1
	s_waitcnt lgkmcnt(0)
	v_add_f32_e32 v9, v8, v9
	v_cndmask_b32_e64 v8, v9, v8, s[0:1]
	v_add_u32_e32 v9, -4, v0
	v_cmp_lt_i32_e64 s[0:1], v9, v7
	s_nop 1
	v_cndmask_b32_e64 v9, v9, v0, s[0:1]
	v_lshlrev_b32_e32 v9, 2, v9
	ds_bpermute_b32 v9, v9, v8
	v_cmp_gt_u32_e64 s[0:1], 4, v1
	s_waitcnt lgkmcnt(0)
	v_add_f32_e32 v9, v8, v9
	v_cndmask_b32_e64 v8, v9, v8, s[0:1]
	v_add_u32_e32 v9, -8, v0
	v_cmp_lt_i32_e64 s[0:1], v9, v7
	s_nop 1
	v_cndmask_b32_e64 v9, v9, v0, s[0:1]
	v_lshlrev_b32_e32 v9, 2, v9
	ds_bpermute_b32 v9, v9, v8
	v_cmp_gt_u32_e64 s[0:1], 8, v1
	s_waitcnt lgkmcnt(0)
	v_add_f32_e32 v9, v8, v9
	v_cndmask_b32_e64 v8, v9, v8, s[0:1]
	v_add_u32_e32 v9, -16, v0
	v_cmp_lt_i32_e64 s[0:1], v9, v7
	s_nop 1
	v_cndmask_b32_e64 v9, v9, v0, s[0:1]
	v_lshlrev_b32_e32 v9, 2, v9
	ds_bpermute_b32 v9, v9, v8
	v_cmp_gt_u32_e64 s[0:1], 16, v1
	s_waitcnt lgkmcnt(0)
	v_add_f32_e32 v9, v8, v9
	v_cndmask_b32_e64 v8, v9, v8, s[0:1]
	v_subrev_u32_e32 v9, 32, v0
	v_cmp_lt_i32_e64 s[0:1], v9, v7
	s_nop 1
	v_cndmask_b32_e64 v9, v9, v0, s[0:1]
	v_lshlrev_b32_e32 v9, 2, v9
	ds_bpermute_b32 v9, v9, v8
	v_cmp_gt_u32_e64 s[0:1], 32, v1
	s_waitcnt lgkmcnt(0)
	v_add_f32_e32 v1, v8, v9
	v_cndmask_b32_e64 v8, v1, v8, s[0:1]
	v_lshl_or_b32 v1, v0, 2, v203
	s_add_i32 s0, 0, 0x11000
	ds_bpermute_b32 v1, v1, v8
	v_sub_f32_e32 v8, v8, v6
	v_add_u32_e32 v9, s0, v3
	v_add_f32_e32 v4, v4, v8
	ds_read_b32 v9, v9
	v_add_f32_e32 v6, v6, v8
	v_add_u32_e32 v8, s0, v5
	ds_read_b32 v8, v8
	s_waitcnt lgkmcnt(2)
	v_sub_f32_e32 v4, v1, v4
	s_add_i32 s0, 0, 0x11400
	s_waitcnt lgkmcnt(1)
	v_add_f32_e32 v4, v9, v4
	v_sub_f32_e32 v6, v1, v6
	v_add_u32_e32 v3, s0, v3
	s_waitcnt lgkmcnt(0)
	v_add_f32_e32 v6, v8, v6
	ds_write_b32 v3, v4
	v_add_u32_e32 v3, s0, v5
	ds_write_b32 v3, v6
	v_max_f32_e32 v3, v4, v6
	v_add_u32_e32 v4, 64, v7
	v_xor_b32_e32 v5, 32, v0
	v_cmp_lt_i32_e64 s[0:1], v5, v4
	s_nop 1
	v_cndmask_b32_e64 v5, v0, v5, s[0:1]
	v_lshlrev_b32_e32 v5, 2, v5
	ds_bpermute_b32 v5, v5, v3
	s_waitcnt lgkmcnt(0)
	v_max_f32_e32 v3, v3, v5
	v_xor_b32_e32 v5, 16, v0
	v_cmp_lt_i32_e64 s[0:1], v5, v4
	s_nop 1
	v_cndmask_b32_e64 v5, v0, v5, s[0:1]
	v_lshlrev_b32_e32 v5, 2, v5
	ds_bpermute_b32 v5, v5, v3
	s_waitcnt lgkmcnt(0)
	v_max_f32_e32 v3, v3, v5
	v_xor_b32_e32 v5, 8, v0
	v_cmp_lt_i32_e64 s[0:1], v5, v4
	s_nop 1
	v_cndmask_b32_e64 v5, v0, v5, s[0:1]
	v_lshlrev_b32_e32 v5, 2, v5
	ds_bpermute_b32 v5, v5, v3
	s_waitcnt lgkmcnt(0)
	v_max_f32_e32 v3, v3, v5
	v_xor_b32_e32 v5, 4, v0
	v_cmp_lt_i32_e64 s[0:1], v5, v4
	s_nop 1
	v_cndmask_b32_e64 v5, v0, v5, s[0:1]
	v_lshlrev_b32_e32 v5, 2, v5
	ds_bpermute_b32 v5, v5, v3
	s_waitcnt lgkmcnt(0)
	v_max_f32_e32 v3, v3, v5
	v_xor_b32_e32 v5, 2, v0
	v_cmp_lt_i32_e64 s[0:1], v5, v4
	s_nop 1
	v_cndmask_b32_e64 v5, v0, v5, s[0:1]
	v_lshlrev_b32_e32 v5, 2, v5
	ds_bpermute_b32 v5, v5, v3
	s_waitcnt lgkmcnt(0)
	v_max_f32_e32 v3, v3, v5
	v_xor_b32_e32 v5, 1, v0
	v_cmp_lt_i32_e64 s[0:1], v5, v4
	s_nop 1
	v_cndmask_b32_e64 v0, v0, v5, s[0:1]
	v_lshlrev_b32_e32 v0, 2, v0
	ds_bpermute_b32 v0, v0, v3
	s_and_b64 exec, exec, s[38:39]
	s_cbranch_execz .LBB0_592
	s_lshl_b32 s0, s2, 1
	s_ashr_i32 s1, s0, 31
	s_lshl_b64 s[0:1], s[0:1], 2
	s_add_u32 s0, s95, s0
	s_waitcnt lgkmcnt(0)
	s_nop 0
	s_nop 0
	v_readlane_b32 s4, v249, 51
	s_addc_u32 s1, s76, s1
	v_max_f32_e32 v0, v3, v0
	v_mov_b32_e32 v3, s4
	ds_write_b64 v3, v[0:1]
	global_store_dwordx2 v97, v[0:1], s[0:1]

.LBB0_717:
	s_or_b64 exec, exec, s[6:7]
	ds_write_b128 v70, v[52:55]
	ds_write_b128 v70, v[56:59] offset:4608
	ds_write_b128 v70, v[60:63] offset:9216
	ds_write_b128 v70, v[64:67] offset:13824
	s_waitcnt lgkmcnt(0)
	s_barrier
	ds_read_b128 v[32:35], v158
	ds_read_b128 v[36:39], v158 offset:4608
	s_waitcnt lgkmcnt(1)
	v_mfma_f32_32x32x16_bf16 v[80:95], v[98:101], v[32:35], 0
	s_waitcnt lgkmcnt(0)
	v_mfma_f32_32x32x16_bf16 v[48:63], v[98:101], v[36:39], 0
	ds_read_b128 v[32:35], v158 offset:9216
	ds_read_b128 v[36:39], v158 offset:13824
	s_waitcnt lgkmcnt(1)
	v_mfma_f32_32x32x16_bf16 v[64:79], v[98:101], v[32:35], 0
	s_waitcnt lgkmcnt(0)
	v_mfma_f32_32x32x16_bf16 v[32:47], v[98:101], v[36:39], 0
	ds_read_b128 v[148:151], v158 offset:32
	s_waitcnt lgkmcnt(0)
	v_mfma_f32_32x32x16_bf16 v[80:95], v[102:105], v[148:151], v[80:95]
	ds_read_b128 v[148:151], v158 offset:4640
	s_waitcnt lgkmcnt(0)
	v_mfma_f32_32x32x16_bf16 v[48:63], v[102:105], v[148:151], v[48:63]
	ds_read_b128 v[148:151], v158 offset:9248
	s_waitcnt lgkmcnt(0)
	v_mfma_f32_32x32x16_bf16 v[64:79], v[102:105], v[148:151], v[64:79]
	ds_read_b128 v[148:151], v158 offset:13856
	s_waitcnt lgkmcnt(0)
	v_mfma_f32_32x32x16_bf16 v[32:47], v[102:105], v[148:151], v[32:47]
	ds_read_b128 v[148:151], v158 offset:64
	s_waitcnt lgkmcnt(0)
	v_mfma_f32_32x32x16_bf16 v[80:95], v[106:109], v[148:151], v[80:95]
	ds_read_b128 v[148:151], v158 offset:4672
	s_waitcnt lgkmcnt(0)
	v_mfma_f32_32x32x16_bf16 v[48:63], v[106:109], v[148:151], v[48:63]
	ds_read_b128 v[148:151], v158 offset:9280
	s_waitcnt lgkmcnt(0)
	v_mfma_f32_32x32x16_bf16 v[64:79], v[106:109], v[148:151], v[64:79]
	ds_read_b128 v[148:151], v158 offset:13888
	s_waitcnt lgkmcnt(0)
	v_mfma_f32_32x32x16_bf16 v[32:47], v[106:109], v[148:151], v[32:47]
	ds_read_b128 v[148:151], v158 offset:96
	s_waitcnt lgkmcnt(0)
	v_mfma_f32_32x32x16_bf16 v[80:95], v[110:113], v[148:151], v[80:95]
	ds_read_b128 v[148:151], v158 offset:4704
	s_waitcnt lgkmcnt(0)
	v_mfma_f32_32x32x16_bf16 v[48:63], v[110:113], v[148:151], v[48:63]
	ds_read_b128 v[148:151], v158 offset:9312
	s_waitcnt lgkmcnt(0)
	v_mfma_f32_32x32x16_bf16 v[64:79], v[110:113], v[148:151], v[64:79]
	ds_read_b128 v[148:151], v158 offset:13920
	s_waitcnt lgkmcnt(0)
	v_mfma_f32_32x32x16_bf16 v[32:47], v[110:113], v[148:151], v[32:47]
	s_cmp_eq_u32 s53, 1
	s_cbranch_scc1 .Latt_nm
	s_cmp_gt_u32 s53, 2
	s_cbranch_scc1 .Latt_nm
	s_add_i32 s6, s53, s49
	v_mbcnt_hi_u32_b32 v148, -1, v195
	v_lshl_add_u32 v96, s6, 7, v183
	v_and_b32_e32 v147, 64, v148
	v_add_u32_e32 v149, 64, v147
	v_sub_u32_e32 v147, v96, v159
	v_cmp_gt_u32_e32 vcc, s58, v147
	s_or_b64 vcc, s[2:3], vcc
	v_add_u32_e32 v150, 32, v147
	v_cndmask_b32_e32 v80, v204, v80, vcc
	v_cmp_gt_u32_e32 vcc, s58, v150
	s_or_b64 vcc, s[2:3], vcc
	v_add_u32_e32 v151, 64, v147
	v_cndmask_b32_e32 v48, v204, v48, vcc
	v_cmp_gt_u32_e32 vcc, s58, v151
	s_or_b64 vcc, s[2:3], vcc
	v_add_u32_e32 v147, 0x60, v147
	v_cndmask_b32_e32 v64, v204, v64, vcc
	v_cmp_gt_u32_e32 vcc, s58, v147
	s_or_b64 vcc, s[2:3], vcc
	v_xor_b32_e32 v147, 16, v148
	v_cndmask_b32_e32 v32, v204, v32, vcc
	v_cmp_lt_i32_e32 vcc, v147, v149
	v_max3_f32 v150, v80, s59, v48
	v_max3_f32 v150, v150, v64, v32
	v_cndmask_b32_e32 v147, v148, v147, vcc
	v_lshlrev_b32_e32 v147, 2, v147
	v_mov_b32_e32 v151, v150
	v_mov_b32_e32 v255, v150
	s_nop 1
	v_permlane16_swap_b32_e32 v151, v255
	v_add_u32_e32 v187, 0x8800, v186
	v_add_u32_e32 v215, 0x9000, v186
	v_max_f32_e32 v150, v151, v255
	v_xor_b32_e32 v151, 8, v148
	v_cmp_lt_i32_e32 vcc, v151, v149
	s_nop 1
	v_cndmask_b32_e32 v151, v148, v151, vcc
	v_lshlrev_b32_e32 v208, 2, v151
	v_max_f32_dpp v150, v150, v150 row_ror:8 row_mask:0xf bank_mask:0xf
	v_xor_b32_e32 v151, 4, v148
	v_cmp_lt_i32_e32 vcc, v151, v149
	s_nop 1
	v_cndmask_b32_e32 v151, v148, v151, vcc
	v_lshlrev_b32_e32 v209, 2, v151
	v_mov_b32_dpp v151, v150 row_shl:4 row_mask:0xf bank_mask:0x5
	v_mov_b32_dpp v151, v150 row_shr:4 row_mask:0xf bank_mask:0xa
	v_max_f32_e32 v150, v150, v151
	v_xor_b32_e32 v151, 2, v148
	v_cmp_lt_i32_e32 vcc, v151, v149
	s_nop 1
	v_cndmask_b32_e32 v151, v148, v151, vcc
	v_lshlrev_b32_e32 v210, 2, v151
	v_max_f32_dpp v150, v150, v150 quad_perm:[2,3,0,1] row_mask:0xf bank_mask:0xf
	v_xor_b32_e32 v151, 1, v148
	v_cmp_lt_i32_e32 vcc, v151, v149
	v_sub_u32_e32 v149, v96, v161
	s_nop 0
	v_cndmask_b32_e32 v148, v148, v151, vcc
	v_cmp_gt_u32_e32 vcc, s58, v149
	s_or_b64 vcc, s[2:3], vcc
	v_lshlrev_b32_e32 v211, 2, v148
	v_cndmask_b32_e32 v151, v204, v81, vcc
	v_add_u32_e32 v81, 32, v149
	v_cmp_gt_u32_e32 vcc, s58, v81
	s_or_b64 vcc, s[2:3], vcc
	v_add_u32_e32 v81, 64, v149
	v_cndmask_b32_e32 v152, v204, v49, vcc
	v_cmp_gt_u32_e32 vcc, s58, v81
	s_or_b64 vcc, s[2:3], vcc
	v_max3_f32 v49, v151, s59, v152
	v_cndmask_b32_e32 v153, v204, v65, vcc
	v_add_u32_e32 v65, 0x60, v149
	v_cmp_gt_u32_e32 vcc, s58, v65
	s_or_b64 vcc, s[2:3], vcc
	v_mov_b32_dpp v148, v150 quad_perm:[1,0,3,2] row_mask:0xf bank_mask:0xf
	v_cndmask_b32_e32 v154, v204, v33, vcc
	v_max3_f32 v33, v49, v153, v154
	v_mov_b32_e32 v49, v33
	v_mov_b32_e32 v255, v33
	s_nop 1
	v_permlane16_swap_b32_e32 v49, v255
	v_max3_f32 v207, v130, v150, v148
	v_sub_f32_e32 v48, v48, v207
	v_mul_f32_e32 v48, 0x3fb8aa3b, v48
	v_max_f32_e32 v49, v49, v255
	v_sub_f32_e32 v33, v80, v207
	v_sub_f32_e32 v32, v32, v207
	v_mul_f32_e32 v32, 0x3fb8aa3b, v32
	v_sub_f32_e32 v130, v130, v207
	v_max_f32_dpp v65, v49, v49 row_ror:8 row_mask:0xf bank_mask:0xf
	s_nop 1
	v_mov_b32_dpp v80, v65 row_shl:4 row_mask:0xf bank_mask:0x5
	v_mov_b32_dpp v80, v65 row_shr:4 row_mask:0xf bank_mask:0xa
	v_exp_f32_e32 v49, v48
	v_sub_f32_e32 v48, v64, v207
	v_mul_f32_e32 v48, 0x3fb8aa3b, v48
	v_exp_f32_e32 v81, v48
	v_max_f32_e32 v64, v80, v80
	v_max_f32_e32 v64, v65, v64
	s_nop 1
	v_mov_b32_dpp v80, v64 quad_perm:[2,3,0,1] row_mask:0xf bank_mask:0xf
	v_exp_f32_e32 v65, v32
	v_mul_f32_e32 v33, 0x3fb8aa3b, v33
	v_exp_f32_e32 v33, v33
	v_max_f32_e32 v32, v80, v80
	v_max_f32_e32 v32, v64, v32
	s_nop 1
	v_mov_b32_dpp v48, v32 quad_perm:[1,0,3,2] row_mask:0xf bank_mask:0xf
	v_mul_f32_e32 v64, 0x3fb8aa3b, v130
	v_exp_f32_e32 v130, v64
	v_cvt_pk_bf16_f32 v148, v33, v49
	v_cvt_pk_bf16_f32 v149, v81, v65
	v_max3_f32 v206, v131, v32, v48
	v_sub_u32_e32 v32, v96, v169
	v_cmp_gt_u32_e32 vcc, s58, v32
	s_or_b64 vcc, s[2:3], vcc
	v_add_u32_e32 v48, 32, v32
	v_cndmask_b32_e32 v82, v204, v82, vcc
	v_cmp_gt_u32_e32 vcc, s58, v48
	s_or_b64 vcc, s[2:3], vcc
	v_add_u32_e32 v64, 64, v32
	v_cndmask_b32_e32 v50, v204, v50, vcc
	v_cmp_gt_u32_e32 vcc, s58, v64
	s_or_b64 vcc, s[2:3], vcc
	v_add_u32_e32 v32, 0x60, v32
	v_cndmask_b32_e32 v66, v204, v66, vcc
	v_cmp_gt_u32_e32 vcc, s58, v32
	s_or_b64 vcc, s[2:3], vcc
	v_max3_f32 v48, v82, s59, v50
	v_cndmask_b32_e32 v34, v204, v34, vcc
	v_max3_f32 v48, v48, v66, v34
	v_mov_b32_e32 v64, v48
	v_mov_b32_e32 v255, v48
	s_nop 1
	v_permlane16_swap_b32_e32 v64, v255
	v_sub_f32_e32 v32, v151, v206
	v_sub_f32_e32 v80, v152, v206
	v_mul_f32_e32 v32, 0x3fb8aa3b, v32
	v_exp_f32_e32 v32, v32
	v_max_f32_e32 v64, v64, v255
	v_mul_f32_e32 v48, 0x3fb8aa3b, v80
	v_sub_f32_e32 v80, v153, v206
	v_mul_f32_e32 v80, 0x3fb8aa3b, v80
	v_exp_f32_e32 v48, v48
	v_max_f32_dpp v150, v64, v64 row_ror:8 row_mask:0xf bank_mask:0xf
	v_sub_f32_e32 v64, v154, v206
	v_sub_u32_e32 v154, v96, v170
	v_cmp_gt_u32_e32 vcc, s58, v154
	s_or_b64 vcc, s[2:3], vcc
	v_mov_b32_dpp v151, v150 row_shl:4 row_mask:0xf bank_mask:0x5
	v_mov_b32_dpp v151, v150 row_shr:4 row_mask:0xf bank_mask:0xa
	v_cndmask_b32_e32 v155, v204, v83, vcc
	v_add_u32_e32 v83, 32, v154
	v_cmp_gt_u32_e32 vcc, s58, v83
	s_or_b64 vcc, s[2:3], vcc
	v_add_u32_e32 v83, 64, v154
	v_cndmask_b32_e32 v156, v204, v51, vcc
	v_cmp_gt_u32_e32 vcc, s58, v83
	s_or_b64 vcc, s[2:3], vcc
	v_max3_f32 v51, v155, s59, v156
	v_cndmask_b32_e32 v160, v204, v67, vcc
	v_add_u32_e32 v67, 0x60, v154
	v_cmp_gt_u32_e32 vcc, s58, v67
	s_or_b64 vcc, s[2:3], vcc
	s_nop 0
	v_cndmask_b32_e32 v154, v204, v35, vcc
	v_max3_f32 v35, v51, v160, v154
	v_max_f32_e32 v152, v150, v151
	v_mov_b32_e32 v51, v35
	v_mov_b32_e32 v255, v35
	s_nop 1
	v_permlane16_swap_b32_e32 v51, v255
	v_mov_b32_dpp v153, v152 quad_perm:[2,3,0,1] row_mask:0xf bank_mask:0xf
	v_mul_f32_e32 v64, 0x3fb8aa3b, v64
	v_exp_f32_e32 v80, v80
	v_exp_f32_e32 v64, v64
	v_max_f32_e32 v51, v51, v255
	v_max_f32_e32 v152, v152, v153
	s_nop 1
	v_mov_b32_dpp v153, v152 quad_perm:[1,0,3,2] row_mask:0xf bank_mask:0xf
	v_cvt_pk_bf16_f32 v150, v32, v48
	v_cvt_pk_bf16_f32 v151, v80, v64
	ds_write2_b64 v187, v[148:149], v[150:151] offset0:128 offset1:162
	v_max3_f32 v189, v132, v152, v153
	v_max_f32_dpp v67, v51, v51 row_ror:8 row_mask:0xf bank_mask:0xf
	v_sub_f32_e32 v35, v82, v189
	s_nop 1
	v_mov_b32_dpp v82, v67 row_shl:4 row_mask:0xf bank_mask:0x5
	v_mov_b32_dpp v82, v67 row_shr:4 row_mask:0xf bank_mask:0xa
	v_sub_f32_e32 v50, v50, v189
	v_mul_f32_e32 v50, 0x3fb8aa3b, v50
	v_exp_f32_e32 v51, v50
	v_sub_f32_e32 v50, v66, v189
	s_waitcnt lgkmcnt(0)
	v_max_f32_e32 v66, v82, v82
	v_max_f32_e32 v66, v67, v66
	s_nop 1
	v_mov_b32_dpp v82, v66 quad_perm:[2,3,0,1] row_mask:0xf bank_mask:0xf
	v_sub_f32_e32 v34, v34, v189
	v_mul_f32_e32 v34, 0x3fb8aa3b, v34
	v_exp_f32_e32 v67, v34
	v_mul_f32_e32 v50, 0x3fb8aa3b, v50
	v_max_f32_e32 v34, v82, v82
	v_max_f32_e32 v34, v66, v34
	v_exp_f32_e32 v83, v50
	s_nop 1
	v_mov_b32_dpp v50, v34 quad_perm:[1,0,3,2] row_mask:0xf bank_mask:0xf
	v_sub_f32_e32 v132, v132, v189
	v_mul_f32_e32 v66, 0x3fb8aa3b, v132
	v_exp_f32_e32 v132, v66
	v_mul_f32_e32 v35, 0x3fb8aa3b, v35
	v_max3_f32 v188, v133, v34, v50
	v_sub_u32_e32 v34, v96, v171
	v_cmp_gt_u32_e32 vcc, s58, v34
	s_or_b64 vcc, s[2:3], vcc
	v_add_u32_e32 v50, 32, v34
	v_cndmask_b32_e32 v84, v204, v84, vcc
	v_cmp_gt_u32_e32 vcc, s58, v50
	s_or_b64 vcc, s[2:3], vcc
	v_add_u32_e32 v66, 64, v34
	v_cndmask_b32_e32 v52, v204, v52, vcc
	v_cmp_gt_u32_e32 vcc, s58, v66
	s_or_b64 vcc, s[2:3], vcc
	v_add_u32_e32 v34, 0x60, v34
	v_cndmask_b32_e32 v68, v204, v68, vcc
	v_cmp_gt_u32_e32 vcc, s58, v34
	s_or_b64 vcc, s[2:3], vcc
	v_max3_f32 v50, v84, s59, v52
	v_cndmask_b32_e32 v150, v204, v36, vcc
	v_max3_f32 v34, v50, v68, v150
	v_mov_b32_e32 v36, v34
	v_mov_b32_e32 v255, v34
	s_nop 1
	v_permlane16_swap_b32_e32 v36, v255
	v_sub_f32_e32 v151, v154, v188
	v_sub_f32_e32 v50, v133, v188
	v_mul_f32_e32 v133, 0x3fb8aa3b, v50
	v_sub_f32_e32 v50, v155, v188
	v_max_f32_e32 v36, v36, v255
	s_nop 1
	v_mov_b32_dpp v66, v36 row_ror:8 row_mask:0xf bank_mask:0xf
	v_mul_f32_e32 v50, 0x3fb8aa3b, v50
	v_exp_f32_e32 v34, v50
	v_sub_f32_e32 v50, v156, v188
	v_sub_f32_e32 v82, v160, v188
	v_max_f32_e32 v36, v36, v66
	s_nop 1
	v_mov_b32_dpp v66, v36 row_shl:4 row_mask:0xf bank_mask:0x5
	v_mov_b32_dpp v66, v36 row_shr:4 row_mask:0xf bank_mask:0xa
	v_mul_f32_e32 v50, 0x3fb8aa3b, v50
	v_mul_f32_e32 v82, 0x3fb8aa3b, v82
	v_exp_f32_e32 v35, v35
	v_exp_f32_e32 v50, v50
	v_max_f32_e32 v152, v36, v66
	s_nop 1
	v_mov_b32_dpp v153, v152 quad_perm:[2,3,0,1] row_mask:0xf bank_mask:0xf
	v_mul_f32_e32 v36, 0x3fb8aa3b, v151
	v_exp_f32_e32 v82, v82
	v_exp_f32_e32 v66, v36
	v_cvt_pk_bf16_f32 v148, v35, v51
	v_max_f32_e32 v151, v153, v153
	v_sub_u32_e32 v153, v96, v172
	v_cmp_gt_u32_e32 vcc, s58, v153
	s_or_b64 vcc, s[2:3], vcc
	v_cvt_pk_bf16_f32 v149, v83, v67
	v_cndmask_b32_e32 v154, v204, v85, vcc
	v_add_u32_e32 v85, 32, v153
	v_cmp_gt_u32_e32 vcc, s58, v85
	s_or_b64 vcc, s[2:3], vcc
	v_add_u32_e32 v85, 64, v153
	v_cndmask_b32_e32 v155, v204, v53, vcc
	v_cmp_gt_u32_e32 vcc, s58, v85
	s_or_b64 vcc, s[2:3], vcc
	v_max3_f32 v53, v154, s59, v155
	v_cndmask_b32_e32 v156, v204, v69, vcc
	v_add_u32_e32 v69, 0x60, v153
	v_cmp_gt_u32_e32 vcc, s58, v69
	s_or_b64 vcc, s[2:3], vcc
	v_cvt_pk_bf16_f32 v36, v34, v50
	v_cndmask_b32_e32 v153, v204, v37, vcc
	v_max3_f32 v53, v53, v156, v153
	v_mov_b32_e32 v69, v53
	v_mov_b32_e32 v255, v53
	s_nop 1
	v_permlane16_swap_b32_e32 v69, v255
	s_nop 1
	v_mov_b32_dpp v69, v255 quad_perm:[0,1,2,3] row_mask:0x5 bank_mask:0xf
	v_cvt_pk_bf16_f32 v37, v82, v66
	ds_write2_b64 v187, v[148:149], v[36:37] offset0:196 offset1:230
	v_max_f32_e32 v151, v152, v151
	s_nop 1
	v_mov_b32_dpp v152, v151 quad_perm:[1,0,3,2] row_mask:0xf bank_mask:0xf
	v_max_f32_e32 v37, v69, v69
	v_max_f32_e32 v53, v53, v37
	v_sub_f32_e32 v131, v131, v206
	s_waitcnt lgkmcnt(0)
	v_max3_f32 v187, v134, v151, v152
	v_sub_f32_e32 v37, v84, v187
	v_sub_f32_e32 v52, v52, v187
	v_max_f32_dpp v69, v53, v53 row_ror:8 row_mask:0xf bank_mask:0xf
	s_nop 1
	v_mov_b32_dpp v84, v69 row_shl:4 row_mask:0xf bank_mask:0x5
	v_mov_b32_dpp v84, v69 row_shr:4 row_mask:0xf bank_mask:0xa
	v_mul_f32_e32 v52, 0x3fb8aa3b, v52
	v_exp_f32_e32 v53, v52
	v_sub_f32_e32 v52, v68, v187
	v_mul_f32_e32 v52, 0x3fb8aa3b, v52
	v_max_f32_e32 v68, v84, v84
	v_max_f32_e32 v68, v69, v68
	s_nop 1
	v_mov_b32_dpp v84, v68 quad_perm:[2,3,0,1] row_mask:0xf bank_mask:0xf
	v_exp_f32_e32 v85, v52
	v_sub_f32_e32 v52, v150, v187
	v_mul_f32_e32 v52, 0x3fb8aa3b, v52
	v_exp_f32_e32 v69, v52
	v_max_f32_e32 v52, v84, v84
	v_max_f32_e32 v52, v68, v52
	s_nop 1
	v_mov_b32_dpp v68, v52 quad_perm:[1,0,3,2] row_mask:0xf bank_mask:0xf
	v_sub_f32_e32 v36, v134, v187
	v_mul_f32_e32 v36, 0x3fb8aa3b, v36
	v_exp_f32_e32 v134, v36
	v_sub_u32_e32 v36, v96, v173
	v_cmp_gt_u32_e32 vcc, s58, v36
	v_max3_f32 v160, v135, v52, v68
	s_or_b64 vcc, s[2:3], vcc
	v_add_u32_e32 v52, 32, v36
	v_cndmask_b32_e32 v86, v204, v86, vcc
	v_cmp_gt_u32_e32 vcc, s58, v52
	s_or_b64 vcc, s[2:3], vcc
	v_add_u32_e32 v68, 64, v36
	v_cndmask_b32_e32 v54, v204, v54, vcc
	v_cmp_gt_u32_e32 vcc, s58, v68
	s_or_b64 vcc, s[2:3], vcc
	v_add_u32_e32 v36, 0x60, v36
	v_cndmask_b32_e32 v70, v204, v70, vcc
	v_cmp_gt_u32_e32 vcc, s58, v36
	s_or_b64 vcc, s[2:3], vcc
	v_max3_f32 v52, v86, s59, v54
	v_cndmask_b32_e32 v38, v204, v38, vcc
	v_max3_f32 v52, v52, v70, v38
	v_mov_b32_e32 v68, v52
	v_mov_b32_e32 v255, v52
	s_nop 1
	v_permlane16_swap_b32_e32 v68, v255
	v_sub_f32_e32 v36, v154, v160
	v_sub_u32_e32 v154, v96, v174
	v_cmp_gt_u32_e32 vcc, s58, v154
	s_or_b64 vcc, s[2:3], vcc
	v_max_f32_e32 v68, v68, v255
	v_cndmask_b32_e32 v212, v204, v87, vcc
	v_add_u32_e32 v87, 32, v154
	v_cmp_gt_u32_e32 vcc, s58, v87
	s_or_b64 vcc, s[2:3], vcc
	v_add_u32_e32 v87, 64, v154
	v_max_f32_dpp v150, v68, v68 row_ror:8 row_mask:0xf bank_mask:0xf
	v_cndmask_b32_e32 v213, v204, v55, vcc
	v_cmp_gt_u32_e32 vcc, s58, v87
	v_mov_b32_dpp v151, v150 row_shl:4 row_mask:0xf bank_mask:0x5
	v_mov_b32_dpp v151, v150 row_shr:4 row_mask:0xf bank_mask:0xa
	s_or_b64 vcc, s[2:3], vcc
	v_cndmask_b32_e32 v214, v204, v71, vcc
	v_add_u32_e32 v71, 0x60, v154
	v_cmp_gt_u32_e32 vcc, s58, v71
	s_or_b64 vcc, s[2:3], vcc
	v_max3_f32 v55, v212, s59, v213
	v_cndmask_b32_e32 v154, v204, v39, vcc
	v_max3_f32 v39, v55, v214, v154
	v_max_f32_e32 v152, v150, v151
	v_mov_b32_e32 v55, v39
	v_mov_b32_e32 v255, v39
	s_nop 1
	v_permlane16_swap_b32_e32 v55, v255
	v_sub_f32_e32 v68, v153, v160
	v_mov_b32_dpp v153, v152 quad_perm:[2,3,0,1] row_mask:0xf bank_mask:0xf
	v_sub_f32_e32 v84, v155, v160
	v_mul_f32_e32 v52, 0x3fb8aa3b, v84
	v_max_f32_e32 v55, v55, v255
	v_max_f32_e32 v152, v152, v153
	s_nop 0
	s_nop 1
	v_mov_b32_dpp v153, v152 quad_perm:[1,0,3,2] row_mask:0xf bank_mask:0xf
	v_sub_f32_e32 v84, v156, v160
	v_mul_f32_e32 v37, 0x3fb8aa3b, v37
	v_mul_f32_e32 v36, 0x3fb8aa3b, v36
	v_max3_f32 v156, v136, v152, v153
	v_max_f32_dpp v71, v55, v55 row_ror:8 row_mask:0xf bank_mask:0xf
	v_sub_f32_e32 v39, v86, v156
	s_nop 1
	v_mov_b32_dpp v86, v71 row_shl:4 row_mask:0xf bank_mask:0x5
	v_mov_b32_dpp v86, v71 row_shr:4 row_mask:0xf bank_mask:0xa
	v_sub_f32_e32 v54, v54, v156
	v_mul_f32_e32 v54, 0x3fb8aa3b, v54
	v_exp_f32_e32 v55, v54
	v_sub_f32_e32 v54, v70, v156
	v_max_f32_e32 v70, v86, v86
	v_max_f32_e32 v70, v71, v70
	s_nop 1
	v_mov_b32_dpp v86, v70 quad_perm:[2,3,0,1] row_mask:0xf bank_mask:0xf
	v_sub_f32_e32 v38, v38, v156
	v_mul_f32_e32 v38, 0x3fb8aa3b, v38
	v_exp_f32_e32 v71, v38
	v_mul_f32_e32 v54, 0x3fb8aa3b, v54
	v_max_f32_e32 v38, v86, v86
	v_max_f32_e32 v38, v70, v38
	v_exp_f32_e32 v87, v54
	s_nop 1
	v_mov_b32_dpp v54, v38 quad_perm:[1,0,3,2] row_mask:0xf bank_mask:0xf
	v_sub_f32_e32 v136, v136, v156
	v_mul_f32_e32 v84, 0x3fb8aa3b, v84
	v_mul_f32_e32 v68, 0x3fb8aa3b, v68
	v_mul_f32_e32 v70, 0x3fb8aa3b, v136
	v_max3_f32 v155, v137, v38, v54
	v_sub_u32_e32 v38, v96, v175
	v_cmp_gt_u32_e32 vcc, s58, v38
	s_or_b64 vcc, s[2:3], vcc
	v_add_u32_e32 v54, 32, v38
	v_cndmask_b32_e32 v88, v204, v88, vcc
	v_cmp_gt_u32_e32 vcc, s58, v54
	v_exp_f32_e32 v37, v37
	v_exp_f32_e32 v36, v36
	v_exp_f32_e32 v52, v52
	v_exp_f32_e32 v84, v84
	v_exp_f32_e32 v68, v68
	v_exp_f32_e32 v136, v70
	s_or_b64 vcc, s[2:3], vcc
	v_add_u32_e32 v70, 64, v38
	v_cndmask_b32_e32 v56, v204, v56, vcc
	v_cmp_gt_u32_e32 vcc, s58, v70
	s_or_b64 vcc, s[2:3], vcc
	v_add_u32_e32 v38, 0x60, v38
	v_cndmask_b32_e32 v72, v204, v72, vcc
	v_cmp_gt_u32_e32 vcc, s58, v38
	v_cvt_pk_bf16_f32 v148, v37, v53
	v_cvt_pk_bf16_f32 v149, v85, v69
	v_cvt_pk_bf16_f32 v150, v36, v52
	v_cvt_pk_bf16_f32 v151, v84, v68
	s_or_b64 vcc, s[2:3], vcc
	ds_write2_b64 v215, v[148:149], v[150:151] offset0:144 offset1:178
	v_max3_f32 v54, v88, s59, v56
	v_cndmask_b32_e32 v150, v204, v40, vcc
	v_max3_f32 v38, v54, v72, v150
	v_mov_b32_e32 v40, v38
	v_mov_b32_e32 v255, v38
	s_nop 1
	v_permlane16_swap_b32_e32 v40, v255
	v_sub_f32_e32 v151, v154, v155
	v_sub_f32_e32 v54, v137, v155
	v_mul_f32_e32 v137, 0x3fb8aa3b, v54
	v_sub_f32_e32 v54, v212, v155
	s_waitcnt lgkmcnt(0)
	v_max_f32_e32 v40, v40, v255
	s_nop 1
	v_mov_b32_dpp v70, v40 row_ror:8 row_mask:0xf bank_mask:0xf
	v_mul_f32_e32 v54, 0x3fb8aa3b, v54
	v_exp_f32_e32 v38, v54
	v_sub_f32_e32 v54, v213, v155
	v_sub_f32_e32 v86, v214, v155
	v_max_f32_e32 v40, v40, v70
	s_nop 1
	v_mov_b32_dpp v70, v40 row_shl:4 row_mask:0xf bank_mask:0x5
	v_mov_b32_dpp v70, v40 row_shr:4 row_mask:0xf bank_mask:0xa
	v_mul_f32_e32 v39, 0x3fb8aa3b, v39
	v_mul_f32_e32 v54, 0x3fb8aa3b, v54
	v_mul_f32_e32 v86, 0x3fb8aa3b, v86
	v_exp_f32_e32 v39, v39
	v_max_f32_e32 v152, v40, v70
	s_nop 1
	v_mov_b32_dpp v153, v152 quad_perm:[2,3,0,1] row_mask:0xf bank_mask:0xf
	v_mul_f32_e32 v40, 0x3fb8aa3b, v151
	v_exp_f32_e32 v54, v54
	v_exp_f32_e32 v86, v86
	v_exp_f32_e32 v70, v40
	v_max_f32_e32 v151, v153, v153
	v_sub_u32_e32 v153, v96, v176
	v_cmp_gt_u32_e32 vcc, s58, v153
	s_or_b64 vcc, s[2:3], vcc
	v_cvt_pk_bf16_f32 v148, v39, v55
	v_cndmask_b32_e32 v212, v204, v89, vcc
	v_add_u32_e32 v89, 32, v153
	v_cmp_gt_u32_e32 vcc, s58, v89
	s_or_b64 vcc, s[2:3], vcc
	v_add_u32_e32 v89, 64, v153
	v_cndmask_b32_e32 v213, v204, v57, vcc
	v_cmp_gt_u32_e32 vcc, s58, v89
	s_or_b64 vcc, s[2:3], vcc
	v_max3_f32 v57, v212, s59, v213
	v_cndmask_b32_e32 v214, v204, v73, vcc
	v_add_u32_e32 v73, 0x60, v153
	v_cmp_gt_u32_e32 vcc, s58, v73
	s_or_b64 vcc, s[2:3], vcc
	v_cvt_pk_bf16_f32 v149, v87, v71
	v_cndmask_b32_e32 v216, v204, v41, vcc
	v_max3_f32 v57, v57, v214, v216
	v_mov_b32_e32 v73, v57
	v_mov_b32_e32 v255, v57
	s_nop 1
	v_permlane16_swap_b32_e32 v73, v255
	s_nop 1
	v_mov_b32_dpp v73, v255 quad_perm:[0,1,2,3] row_mask:0x5 bank_mask:0xf
	v_cvt_pk_bf16_f32 v40, v38, v54
	v_cvt_pk_bf16_f32 v41, v86, v70
	ds_write2_b64 v215, v[148:149], v[40:41] offset0:212 offset1:246
	v_max_f32_e32 v151, v152, v151
	v_max_f32_e32 v41, v73, v73
	v_max_f32_e32 v57, v57, v41
	v_mov_b32_dpp v152, v151 quad_perm:[1,0,3,2] row_mask:0xf bank_mask:0xf
	v_sub_f32_e32 v135, v135, v160
	v_mul_f32_e32 v131, 0x3fb8aa3b, v131
	v_mul_f32_e32 v135, 0x3fb8aa3b, v135
	s_waitcnt lgkmcnt(0)
	v_max3_f32 v154, v138, v151, v152
	v_max_f32_dpp v73, v57, v57 row_ror:8 row_mask:0xf bank_mask:0xf
	v_sub_f32_e32 v41, v88, v154
	s_nop 1
	v_mov_b32_dpp v88, v73 row_shl:4 row_mask:0xf bank_mask:0x5
	v_mov_b32_dpp v88, v73 row_shr:4 row_mask:0xf bank_mask:0xa
	v_sub_f32_e32 v56, v56, v154
	v_mul_f32_e32 v56, 0x3fb8aa3b, v56
	v_exp_f32_e32 v57, v56
	v_sub_f32_e32 v56, v72, v154
	v_max_f32_e32 v72, v88, v88
	v_max_f32_e32 v72, v73, v72
	s_nop 1
	v_mov_b32_dpp v88, v72 quad_perm:[2,3,0,1] row_mask:0xf bank_mask:0xf
	v_mul_f32_e32 v56, 0x3fb8aa3b, v56
	v_exp_f32_e32 v89, v56
	v_sub_f32_e32 v56, v150, v154
	v_mul_f32_e32 v56, 0x3fb8aa3b, v56
	v_exp_f32_e32 v73, v56
	v_max_f32_e32 v56, v88, v88
	v_max_f32_e32 v56, v72, v56
	s_nop 1
	v_mov_b32_dpp v72, v56 quad_perm:[1,0,3,2] row_mask:0xf bank_mask:0xf
	v_sub_f32_e32 v40, v138, v154
	v_mul_f32_e32 v40, 0x3fb8aa3b, v40
	v_exp_f32_e32 v138, v40
	v_sub_u32_e32 v40, v96, v177
	v_cmp_gt_u32_e32 vcc, s58, v40
	v_max3_f32 v153, v139, v56, v72
	s_or_b64 vcc, s[2:3], vcc
	v_add_u32_e32 v56, 32, v40
	v_cndmask_b32_e32 v90, v204, v90, vcc
	v_cmp_gt_u32_e32 vcc, s58, v56
	s_or_b64 vcc, s[2:3], vcc
	v_add_u32_e32 v72, 64, v40
	v_cndmask_b32_e32 v58, v204, v58, vcc
	v_cmp_gt_u32_e32 vcc, s58, v72
	s_or_b64 vcc, s[2:3], vcc
	v_add_u32_e32 v40, 0x60, v40
	v_cndmask_b32_e32 v74, v204, v74, vcc
	v_cmp_gt_u32_e32 vcc, s58, v40
	s_or_b64 vcc, s[2:3], vcc
	v_max3_f32 v56, v90, s59, v58
	v_cndmask_b32_e32 v42, v204, v42, vcc
	v_max3_f32 v56, v56, v74, v42
	v_mov_b32_e32 v72, v56
	v_mov_b32_e32 v255, v56
	s_nop 1
	v_permlane16_swap_b32_e32 v72, v255
	v_sub_f32_e32 v88, v213, v153
	v_sub_u32_e32 v213, v96, v178
	v_cmp_gt_u32_e32 vcc, s58, v213
	s_or_b64 vcc, s[2:3], vcc
	v_max_f32_e32 v72, v72, v255
	v_mul_f32_e32 v56, 0x3fb8aa3b, v88
	v_sub_f32_e32 v88, v214, v153
	v_cndmask_b32_e32 v214, v204, v91, vcc
	v_add_u32_e32 v91, 32, v213
	v_cmp_gt_u32_e32 vcc, s58, v91
	s_or_b64 vcc, s[2:3], vcc
	v_add_u32_e32 v91, 64, v213
	v_max_f32_dpp v150, v72, v72 row_ror:8 row_mask:0xf bank_mask:0xf
	v_cndmask_b32_e32 v215, v204, v59, vcc
	v_cmp_gt_u32_e32 vcc, s58, v91
	v_mov_b32_dpp v151, v150 row_shl:4 row_mask:0xf bank_mask:0x5
	v_mov_b32_dpp v151, v150 row_shr:4 row_mask:0xf bank_mask:0xa
	s_or_b64 vcc, s[2:3], vcc
	v_sub_f32_e32 v72, v216, v153
	v_cndmask_b32_e32 v216, v204, v75, vcc
	v_add_u32_e32 v75, 0x60, v213
	v_cmp_gt_u32_e32 vcc, s58, v75
	s_or_b64 vcc, s[2:3], vcc
	v_max3_f32 v59, v214, s59, v215
	v_cndmask_b32_e32 v213, v204, v43, vcc
	v_max3_f32 v43, v59, v216, v213
	v_sub_f32_e32 v40, v212, v153
	v_max_f32_e32 v152, v150, v151
	v_mov_b32_e32 v59, v43
	v_mov_b32_e32 v255, v43
	s_nop 1
	v_permlane16_swap_b32_e32 v59, v255
	v_mul_f32_e32 v41, 0x3fb8aa3b, v41
	v_mul_f32_e32 v40, 0x3fb8aa3b, v40
	v_mul_f32_e32 v88, 0x3fb8aa3b, v88
	v_mul_f32_e32 v72, 0x3fb8aa3b, v72
	v_mov_b32_dpp v212, v152 quad_perm:[2,3,0,1] row_mask:0xf bank_mask:0xf
	v_exp_f32_e32 v41, v41
	v_exp_f32_e32 v40, v40
	v_exp_f32_e32 v56, v56
	v_exp_f32_e32 v88, v88
	v_exp_f32_e32 v72, v72
	v_cvt_pk_bf16_f32 v148, v41, v57
	v_cvt_pk_bf16_f32 v149, v89, v73
	v_cvt_pk_bf16_f32 v150, v40, v56
	v_cvt_pk_bf16_f32 v151, v88, v72
	v_add_u32_e32 v75, 0x9800, v186
	v_max_f32_e32 v59, v59, v255
	v_max_f32_e32 v152, v152, v212
	ds_write2_b64 v75, v[148:149], v[150:151] offset0:160 offset1:194
	s_nop 0
	v_mov_b32_dpp v212, v152 quad_perm:[1,0,3,2] row_mask:0xf bank_mask:0xf
	v_sub_f32_e32 v139, v139, v153
	v_mul_f32_e32 v139, 0x3fb8aa3b, v139
	v_exp_f32_e32 v131, v131
	s_waitcnt lgkmcnt(0)
	v_max3_f32 v152, v140, v152, v212
	v_max_f32_dpp v75, v59, v59 row_ror:8 row_mask:0xf bank_mask:0xf
	v_sub_f32_e32 v43, v90, v152
	s_nop 1
	v_mov_b32_dpp v90, v75 row_shl:4 row_mask:0xf bank_mask:0x5
	v_mov_b32_dpp v90, v75 row_shr:4 row_mask:0xf bank_mask:0xa
	v_sub_f32_e32 v58, v58, v152
	v_mul_f32_e32 v58, 0x3fb8aa3b, v58
	v_exp_f32_e32 v59, v58
	v_sub_f32_e32 v58, v74, v152
	v_max_f32_e32 v74, v90, v90
	v_max_f32_e32 v74, v75, v74
	s_nop 1
	v_mov_b32_dpp v90, v74 quad_perm:[2,3,0,1] row_mask:0xf bank_mask:0xf
	v_sub_f32_e32 v42, v42, v152
	v_mul_f32_e32 v42, 0x3fb8aa3b, v42
	v_exp_f32_e32 v75, v42
	v_mul_f32_e32 v58, 0x3fb8aa3b, v58
	v_max_f32_e32 v42, v90, v90
	v_max_f32_e32 v42, v74, v42
	v_exp_f32_e32 v91, v58
	s_nop 1
	v_mov_b32_dpp v58, v42 quad_perm:[1,0,3,2] row_mask:0xf bank_mask:0xf
	v_sub_f32_e32 v140, v140, v152
	v_mul_f32_e32 v74, 0x3fb8aa3b, v140
	v_exp_f32_e32 v140, v74
	v_mul_f32_e32 v43, 0x3fb8aa3b, v43
	v_max3_f32 v151, v141, v42, v58
	v_sub_u32_e32 v42, v96, v179
	v_cmp_gt_u32_e32 vcc, s58, v42
	s_or_b64 vcc, s[2:3], vcc
	v_add_u32_e32 v58, 32, v42
	v_cndmask_b32_e32 v92, v204, v92, vcc
	v_cmp_gt_u32_e32 vcc, s58, v58
	s_or_b64 vcc, s[2:3], vcc
	v_add_u32_e32 v74, 64, v42
	v_cndmask_b32_e32 v60, v204, v60, vcc
	v_cmp_gt_u32_e32 vcc, s58, v74
	s_or_b64 vcc, s[2:3], vcc
	v_add_u32_e32 v42, 0x60, v42
	v_cndmask_b32_e32 v76, v204, v76, vcc
	v_cmp_gt_u32_e32 vcc, s58, v42
	s_or_b64 vcc, s[2:3], vcc
	v_max3_f32 v58, v92, s59, v60
	v_cndmask_b32_e32 v44, v204, v44, vcc
	v_max3_f32 v58, v58, v76, v44
	v_mov_b32_e32 v74, v58
	v_mov_b32_e32 v255, v58
	s_nop 1
	v_permlane16_swap_b32_e32 v74, v255
	v_sub_f32_e32 v90, v215, v151
	v_sub_u32_e32 v215, v96, v180
	v_cmp_gt_u32_e32 vcc, s58, v215
	s_or_b64 vcc, s[2:3], vcc
	v_max_f32_e32 v74, v74, v255
	v_mul_f32_e32 v58, 0x3fb8aa3b, v90
	v_sub_f32_e32 v90, v216, v151
	v_cndmask_b32_e32 v216, v204, v93, vcc
	v_add_u32_e32 v93, 32, v215
	v_cmp_gt_u32_e32 vcc, s58, v93
	s_or_b64 vcc, s[2:3], vcc
	v_add_u32_e32 v93, 64, v215
	v_max_f32_dpp v150, v74, v74 row_ror:8 row_mask:0xf bank_mask:0xf
	v_cndmask_b32_e32 v217, v204, v61, vcc
	v_cmp_gt_u32_e32 vcc, s58, v93
	v_mov_b32_dpp v212, v150 row_shl:4 row_mask:0xf bank_mask:0x5
	v_mov_b32_dpp v212, v150 row_shr:4 row_mask:0xf bank_mask:0xa
	s_or_b64 vcc, s[2:3], vcc
	v_cndmask_b32_e32 v218, v204, v77, vcc
	v_add_u32_e32 v77, 0x60, v215
	v_cmp_gt_u32_e32 vcc, s58, v77
	s_or_b64 vcc, s[2:3], vcc
	v_max3_f32 v61, v216, s59, v217
	v_cndmask_b32_e32 v215, v204, v45, vcc
	v_max3_f32 v45, v61, v218, v215
	v_sub_f32_e32 v42, v214, v151
	v_sub_f32_e32 v74, v213, v151
	v_max_f32_e32 v150, v150, v212
	v_mov_b32_e32 v61, v45
	v_mov_b32_e32 v255, v45
	s_nop 1
	v_permlane16_swap_b32_e32 v61, v255
	v_mul_f32_e32 v42, 0x3fb8aa3b, v42
	v_mul_f32_e32 v90, 0x3fb8aa3b, v90
	v_mul_f32_e32 v74, 0x3fb8aa3b, v74
	v_mov_b32_dpp v214, v150 quad_perm:[2,3,0,1] row_mask:0xf bank_mask:0xf
	v_exp_f32_e32 v43, v43
	v_exp_f32_e32 v42, v42
	v_exp_f32_e32 v58, v58
	v_exp_f32_e32 v90, v90
	v_exp_f32_e32 v74, v74
	v_cvt_pk_bf16_f32 v148, v43, v59
	v_cvt_pk_bf16_f32 v149, v91, v75
	v_cvt_pk_bf16_f32 v212, v42, v58
	v_cvt_pk_bf16_f32 v213, v90, v74
	v_add_u32_e32 v77, 0x9c00, v186
	v_max_f32_e32 v61, v61, v255
	v_max_f32_e32 v150, v150, v214
	ds_write2_b64 v77, v[148:149], v[212:213] offset0:100 offset1:134
	s_nop 0
	v_mov_b32_dpp v214, v150 quad_perm:[1,0,3,2] row_mask:0xf bank_mask:0xf
	v_sub_f32_e32 v141, v141, v151
	v_mul_f32_e32 v141, 0x3fb8aa3b, v141
	v_exp_f32_e32 v133, v133
	s_waitcnt lgkmcnt(0)
	v_max3_f32 v150, v142, v150, v214
	v_max_f32_dpp v77, v61, v61 row_ror:8 row_mask:0xf bank_mask:0xf
	v_sub_f32_e32 v45, v92, v150
	s_nop 1
	v_mov_b32_dpp v92, v77 row_shl:4 row_mask:0xf bank_mask:0x5
	v_mov_b32_dpp v92, v77 row_shr:4 row_mask:0xf bank_mask:0xa
	v_sub_f32_e32 v60, v60, v150
	v_mul_f32_e32 v60, 0x3fb8aa3b, v60
	v_exp_f32_e32 v61, v60
	v_sub_f32_e32 v60, v76, v150
	v_max_f32_e32 v76, v92, v92
	v_max_f32_e32 v76, v77, v76
	s_nop 1
	v_mov_b32_dpp v92, v76 quad_perm:[2,3,0,1] row_mask:0xf bank_mask:0xf
	v_sub_f32_e32 v44, v44, v150
	v_mul_f32_e32 v44, 0x3fb8aa3b, v44
	v_exp_f32_e32 v77, v44
	v_mul_f32_e32 v60, 0x3fb8aa3b, v60
	v_max_f32_e32 v44, v92, v92
	v_max_f32_e32 v44, v76, v44
	v_exp_f32_e32 v93, v60
	s_nop 1
	v_mov_b32_dpp v60, v44 quad_perm:[1,0,3,2] row_mask:0xf bank_mask:0xf
	v_sub_f32_e32 v142, v142, v150
	v_mul_f32_e32 v76, 0x3fb8aa3b, v142
	v_exp_f32_e32 v142, v76
	v_mul_f32_e32 v45, 0x3fb8aa3b, v45
	v_max3_f32 v149, v143, v44, v60
	v_sub_u32_e32 v44, v96, v181
	v_cmp_gt_u32_e32 vcc, s58, v44
	s_or_b64 vcc, s[2:3], vcc
	v_add_u32_e32 v60, 32, v44
	v_cndmask_b32_e32 v94, v204, v94, vcc
	v_cmp_gt_u32_e32 vcc, s58, v60
	s_or_b64 vcc, s[2:3], vcc
	v_add_u32_e32 v76, 64, v44
	v_cndmask_b32_e32 v62, v204, v62, vcc
	v_cmp_gt_u32_e32 vcc, s58, v76
	s_or_b64 vcc, s[2:3], vcc
	v_add_u32_e32 v44, 0x60, v44
	v_cndmask_b32_e32 v78, v204, v78, vcc
	v_cmp_gt_u32_e32 vcc, s58, v44
	s_or_b64 vcc, s[2:3], vcc
	v_max3_f32 v60, v94, s59, v62
	v_cndmask_b32_e32 v46, v204, v46, vcc
	v_max3_f32 v60, v60, v78, v46
	v_mov_b32_e32 v76, v60
	v_mov_b32_e32 v255, v60
	s_nop 1
	v_permlane16_swap_b32_e32 v76, v255
	v_sub_u32_e32 v96, v96, v182
	v_cmp_gt_u32_e32 vcc, s58, v96
	s_or_b64 vcc, s[2:3], vcc
	v_sub_f32_e32 v92, v217, v149
	v_max_f32_e32 v76, v76, v255
	v_cndmask_b32_e32 v217, v204, v95, vcc
	v_add_u32_e32 v95, 32, v96
	v_cmp_gt_u32_e32 vcc, s58, v95
	s_or_b64 vcc, s[2:3], vcc
	v_add_u32_e32 v95, 64, v96
	v_mul_f32_e32 v60, 0x3fb8aa3b, v92
	v_sub_f32_e32 v92, v218, v149
	v_max_f32_dpp v148, v76, v76 row_ror:8 row_mask:0xf bank_mask:0xf
	v_cndmask_b32_e32 v218, v204, v63, vcc
	v_cmp_gt_u32_e32 vcc, s58, v95
	v_mov_b32_dpp v214, v148 row_shl:4 row_mask:0xf bank_mask:0x5
	v_mov_b32_dpp v214, v148 row_shr:4 row_mask:0xf bank_mask:0xa
	s_or_b64 vcc, s[2:3], vcc
	v_cndmask_b32_e32 v219, v204, v79, vcc
	v_add_u32_e32 v79, 0x60, v96
	v_cmp_gt_u32_e32 vcc, s58, v79
	s_or_b64 vcc, s[2:3], vcc
	v_max3_f32 v63, v217, s59, v218
	v_cndmask_b32_e32 v96, v204, v47, vcc
	v_max3_f32 v47, v63, v219, v96
	v_sub_f32_e32 v44, v216, v149
	v_sub_f32_e32 v76, v215, v149
	v_max_f32_e32 v148, v148, v214
	v_mov_b32_e32 v63, v47
	v_mov_b32_e32 v255, v47
	s_nop 1
	v_permlane16_swap_b32_e32 v63, v255
	v_mul_f32_e32 v44, 0x3fb8aa3b, v44
	v_mul_f32_e32 v92, 0x3fb8aa3b, v92
	v_mul_f32_e32 v76, 0x3fb8aa3b, v76
	v_mov_b32_dpp v216, v148 quad_perm:[2,3,0,1] row_mask:0xf bank_mask:0xf
	v_exp_f32_e32 v45, v45
	v_exp_f32_e32 v44, v44
	v_exp_f32_e32 v60, v60
	v_exp_f32_e32 v92, v92
	v_exp_f32_e32 v76, v76
	v_cvt_pk_bf16_f32 v212, v45, v61
	v_cvt_pk_bf16_f32 v213, v93, v77
	v_cvt_pk_bf16_f32 v214, v44, v60
	v_cvt_pk_bf16_f32 v215, v92, v76
	v_add_u32_e32 v79, 0xa000, v186
	v_max_f32_e32 v63, v63, v255
	v_max_f32_e32 v148, v148, v216
	ds_write2_b64 v79, v[212:213], v[214:215] offset0:176 offset1:210
	s_nop 0
	v_mov_b32_dpp v216, v148 quad_perm:[1,0,3,2] row_mask:0xf bank_mask:0xf
	v_sub_f32_e32 v143, v143, v149
	v_mul_f32_e32 v143, 0x3fb8aa3b, v143
	v_exp_f32_e32 v135, v135
	s_waitcnt lgkmcnt(0)
	v_max3_f32 v148, v144, v148, v216
	v_max_f32_dpp v79, v63, v63 row_ror:8 row_mask:0xf bank_mask:0xf
	v_sub_f32_e32 v47, v94, v148
	s_nop 1
	v_mov_b32_dpp v94, v79 row_shl:4 row_mask:0xf bank_mask:0x5
	v_mov_b32_dpp v94, v79 row_shr:4 row_mask:0xf bank_mask:0xa
	v_sub_f32_e32 v62, v62, v148
	v_mul_f32_e32 v62, 0x3fb8aa3b, v62
	v_exp_f32_e32 v63, v62
	v_sub_f32_e32 v62, v78, v148
	v_max_f32_e32 v78, v94, v94
	v_max_f32_e32 v78, v79, v78
	s_nop 1
	v_mov_b32_dpp v94, v78 quad_perm:[2,3,0,1] row_mask:0xf bank_mask:0xf
	v_sub_f32_e32 v46, v46, v148
	v_mul_f32_e32 v46, 0x3fb8aa3b, v46
	v_exp_f32_e32 v79, v46
	v_mul_f32_e32 v62, 0x3fb8aa3b, v62
	v_max_f32_e32 v46, v94, v94
	v_max_f32_e32 v46, v78, v46
	v_exp_f32_e32 v95, v62
	s_nop 1
	v_mov_b32_dpp v62, v46 quad_perm:[1,0,3,2] row_mask:0xf bank_mask:0xf
	v_sub_f32_e32 v144, v144, v148
	v_mul_f32_e32 v78, 0x3fb8aa3b, v144
	v_exp_f32_e32 v144, v78
	v_mul_f32_e32 v47, 0x3fb8aa3b, v47
	v_max3_f32 v147, v145, v46, v62
	v_sub_f32_e32 v78, v219, v147
	v_mul_f32_e32 v78, 0x3fb8aa3b, v78
	v_sub_f32_e32 v46, v217, v147
	v_sub_f32_e32 v62, v218, v147
	v_exp_f32_e32 v94, v78
	v_sub_f32_e32 v78, v96, v147
	v_sub_f32_e32 v145, v145, v147
	v_mul_f32_e32 v46, 0x3fb8aa3b, v46
	v_mul_f32_e32 v62, 0x3fb8aa3b, v62
	v_mul_f32_e32 v78, 0x3fb8aa3b, v78
	v_exp_f32_e32 v47, v47
	v_exp_f32_e32 v46, v46
	v_exp_f32_e32 v62, v62
	v_exp_f32_e32 v78, v78
	v_mul_f32_e32 v96, 0x3fb8aa3b, v145
	v_exp_f32_e32 v137, v137
	v_exp_f32_e32 v139, v139
	v_exp_f32_e32 v141, v141
	v_exp_f32_e32 v143, v143
	v_exp_f32_e32 v145, v96
	v_cvt_pk_bf16_f32 v208, v47, v63
	v_cvt_pk_bf16_f32 v209, v95, v79
	v_cvt_pk_bf16_f32 v210, v46, v62
	v_cvt_pk_bf16_f32 v211, v94, v78
	v_add_u32_e32 v96, 0xa400, v186
	ds_write2_b64 v96, v[208:209], v[210:211] offset0:116 offset1:150
	v_pk_mul_f32 v[14:15], v[14:15], v[144:145]
	v_pk_mul_f32 v[12:13], v[12:13], v[142:143]
	v_pk_mul_f32 v[10:11], v[10:11], v[140:141]
	v_pk_mul_f32 v[8:9], v[8:9], v[138:139]
	v_pk_mul_f32 v[6:7], v[6:7], v[136:137]
	v_pk_mul_f32 v[4:5], v[4:5], v[134:135]
	v_pk_mul_f32 v[2:3], v[2:3], v[132:133]
	v_pk_mul_f32 v[0:1], v[0:1], v[130:131]
	v_pk_mul_f32 v[30:31], v[30:31], v[144:145]
	v_pk_mul_f32 v[28:29], v[28:29], v[142:143]
	v_pk_mul_f32 v[26:27], v[26:27], v[140:141]
	v_pk_mul_f32 v[24:25], v[24:25], v[138:139]
	v_pk_mul_f32 v[22:23], v[22:23], v[136:137]
	v_pk_mul_f32 v[20:21], v[20:21], v[134:135]
	v_pk_mul_f32 v[18:19], v[18:19], v[132:133]
	v_pk_mul_f32 v[16:17], v[16:17], v[130:131]
	s_mov_b32 s2, -16
	v_mov_b32_e32 v96, v185
	v_mov_b32_e32 v208, v184

.Latt_nm:
	s_nop 7
	s_nop 7
	s_nop 7
	s_add_i32 s6, s53, s49
	v_mbcnt_hi_u32_b32 v148, -1, v195
	v_lshl_add_u32 v96, s6, 7, v183
	v_and_b32_e32 v147, 64, v148
	v_add_u32_e32 v149, 64, v147
	v_xor_b32_e32 v147, 16, v148
	v_cmp_lt_i32_e32 vcc, v147, v149
	v_max3_f32 v150, v80, s59, v48
	v_max3_f32 v150, v150, v64, v32
	v_mov_b32_e32 v151, v150
	v_mov_b32_e32 v255, v150
	s_nop 1
	v_permlane16_swap_b32_e32 v151, v255
	v_add_u32_e32 v187, 0x8800, v186
	v_add_u32_e32 v215, 0x9000, v186
	v_max_f32_e32 v150, v151, v255
	v_xor_b32_e32 v151, 8, v148
	v_cmp_lt_i32_e32 vcc, v151, v149
	s_nop 1
	v_cndmask_b32_e32 v151, v148, v151, vcc
	v_max_f32_dpp v150, v150, v150 row_ror:8 row_mask:0xf bank_mask:0xf
	v_xor_b32_e32 v151, 4, v148
	v_cmp_lt_i32_e32 vcc, v151, v149
	s_nop 1
	v_cndmask_b32_e32 v151, v148, v151, vcc
	s_nop 1
	v_mov_b32_dpp v151, v150 row_shl:4 row_mask:0xf bank_mask:0x5
	s_nop 1
	v_mov_b32_dpp v151, v150 row_shr:4 row_mask:0xf bank_mask:0xa
	v_max_f32_e32 v150, v150, v151
	v_xor_b32_e32 v151, 2, v148
	v_cmp_lt_i32_e32 vcc, v151, v149
	s_nop 1
	v_cndmask_b32_e32 v151, v148, v151, vcc
	v_max_f32_dpp v150, v150, v150 quad_perm:[2,3,0,1] row_mask:0xf bank_mask:0xf
	v_xor_b32_e32 v151, 1, v148
	v_cmp_lt_i32_e32 vcc, v151, v149
	v_sub_u32_e32 v149, v96, v161
	s_nop 0
	v_cndmask_b32_e32 v148, v148, v151, vcc
	v_mov_b32_e32 v151, v81
	v_mov_b32_e32 v152, v49
	v_max3_f32 v49, v151, s59, v152
	v_mov_b32_e32 v153, v65
	v_add_u32_e32 v65, 0x60, v149
	v_mov_b32_dpp v148, v150 quad_perm:[1,0,3,2] row_mask:0xf bank_mask:0xf
	v_mov_b32_e32 v154, v33
	v_max3_f32 v33, v49, v153, v154
	v_mov_b32_e32 v49, v33
	v_mov_b32_e32 v255, v33
	s_nop 1
	v_permlane16_swap_b32_e32 v49, v255
	v_max3_f32 v207, v130, v150, v148
	v_sub_f32_e32 v48, v48, v207
	v_mul_f32_e32 v48, 0x3fb8aa3b, v48
	v_max_f32_e32 v49, v49, v255
	v_sub_f32_e32 v33, v80, v207
	v_sub_f32_e32 v32, v32, v207
	v_mul_f32_e32 v32, 0x3fb8aa3b, v32
	v_sub_f32_e32 v130, v130, v207
	v_max_f32_dpp v65, v49, v49 row_ror:8 row_mask:0xf bank_mask:0xf
	s_nop 1
	v_mov_b32_dpp v80, v65 row_shl:4 row_mask:0xf bank_mask:0x5
	s_nop 1
	v_mov_b32_dpp v80, v65 row_shr:4 row_mask:0xf bank_mask:0xa
	v_exp_f32_e32 v49, v48
	v_sub_f32_e32 v48, v64, v207
	v_mul_f32_e32 v48, 0x3fb8aa3b, v48
	v_exp_f32_e32 v81, v48
	v_max_f32_e32 v64, v80, v80
	v_max_f32_e32 v64, v65, v64
	s_nop 1
	v_mov_b32_dpp v80, v64 quad_perm:[2,3,0,1] row_mask:0xf bank_mask:0xf
	v_exp_f32_e32 v65, v32
	v_mul_f32_e32 v33, 0x3fb8aa3b, v33
	v_exp_f32_e32 v33, v33
	v_max_f32_e32 v32, v80, v80
	v_max_f32_e32 v32, v64, v32
	s_nop 1
	v_mov_b32_dpp v48, v32 quad_perm:[1,0,3,2] row_mask:0xf bank_mask:0xf
	v_mul_f32_e32 v64, 0x3fb8aa3b, v130
	v_exp_f32_e32 v130, v64
	v_cvt_pk_bf16_f32 v148, v33, v49
	v_cvt_pk_bf16_f32 v149, v81, v65
	v_max3_f32 v206, v131, v32, v48
	v_max3_f32 v48, v82, s59, v50
	v_max3_f32 v48, v48, v66, v34
	v_mov_b32_e32 v64, v48
	v_mov_b32_e32 v255, v48
	s_nop 1
	v_permlane16_swap_b32_e32 v64, v255
	v_sub_f32_e32 v32, v151, v206
	v_sub_f32_e32 v80, v152, v206
	v_mul_f32_e32 v32, 0x3fb8aa3b, v32
	v_exp_f32_e32 v32, v32
	v_max_f32_e32 v64, v64, v255
	v_mul_f32_e32 v48, 0x3fb8aa3b, v80
	v_sub_f32_e32 v80, v153, v206
	v_mul_f32_e32 v80, 0x3fb8aa3b, v80
	v_exp_f32_e32 v48, v48
	v_max_f32_dpp v150, v64, v64 row_ror:8 row_mask:0xf bank_mask:0xf
	v_sub_f32_e32 v64, v154, v206
	v_sub_u32_e32 v154, v96, v170
	v_mov_b32_dpp v151, v150 row_shl:4 row_mask:0xf bank_mask:0x5
	s_nop 1
	v_mov_b32_dpp v151, v150 row_shr:4 row_mask:0xf bank_mask:0xa
	v_mov_b32_e32 v155, v83
	v_mov_b32_e32 v156, v51
	v_max3_f32 v51, v155, s59, v156
	v_mov_b32_e32 v160, v67
	v_add_u32_e32 v67, 0x60, v154
	v_mov_b32_e32 v154, v35
	v_max3_f32 v35, v51, v160, v154
	v_max_f32_e32 v152, v150, v151
	v_mov_b32_e32 v51, v35
	v_mov_b32_e32 v255, v35
	s_nop 1
	v_permlane16_swap_b32_e32 v51, v255
	v_mov_b32_dpp v153, v152 quad_perm:[2,3,0,1] row_mask:0xf bank_mask:0xf
	v_mul_f32_e32 v64, 0x3fb8aa3b, v64
	v_exp_f32_e32 v80, v80
	v_exp_f32_e32 v64, v64
	v_max_f32_e32 v51, v51, v255
	v_max_f32_e32 v152, v152, v153
	s_nop 1
	v_mov_b32_dpp v153, v152 quad_perm:[1,0,3,2] row_mask:0xf bank_mask:0xf
	v_cvt_pk_bf16_f32 v150, v32, v48
	v_cvt_pk_bf16_f32 v151, v80, v64
	ds_write2_b64 v187, v[148:149], v[150:151] offset0:128 offset1:162
	v_max3_f32 v189, v132, v152, v153
	v_max_f32_dpp v67, v51, v51 row_ror:8 row_mask:0xf bank_mask:0xf
	v_sub_f32_e32 v35, v82, v189
	s_nop 1
	v_mov_b32_dpp v82, v67 row_shl:4 row_mask:0xf bank_mask:0x5
	s_nop 1
	v_mov_b32_dpp v82, v67 row_shr:4 row_mask:0xf bank_mask:0xa
	v_sub_f32_e32 v50, v50, v189
	v_mul_f32_e32 v50, 0x3fb8aa3b, v50
	v_exp_f32_e32 v51, v50
	v_sub_f32_e32 v50, v66, v189
	s_waitcnt lgkmcnt(0)
	v_max_f32_e32 v66, v82, v82
	v_max_f32_e32 v66, v67, v66
	s_nop 1
	v_mov_b32_dpp v82, v66 quad_perm:[2,3,0,1] row_mask:0xf bank_mask:0xf
	v_sub_f32_e32 v34, v34, v189
	v_mul_f32_e32 v34, 0x3fb8aa3b, v34
	v_exp_f32_e32 v67, v34
	v_mul_f32_e32 v50, 0x3fb8aa3b, v50
	v_max_f32_e32 v34, v82, v82
	v_max_f32_e32 v34, v66, v34
	v_exp_f32_e32 v83, v50
	s_nop 1
	v_mov_b32_dpp v50, v34 quad_perm:[1,0,3,2] row_mask:0xf bank_mask:0xf
	v_sub_f32_e32 v132, v132, v189
	v_mul_f32_e32 v66, 0x3fb8aa3b, v132
	v_exp_f32_e32 v132, v66
	v_mul_f32_e32 v35, 0x3fb8aa3b, v35
	v_max3_f32 v188, v133, v34, v50
	v_sub_u32_e32 v34, v96, v171
	v_add_u32_e32 v66, 64, v34
	v_max3_f32 v50, v84, s59, v52
	v_mov_b32_e32 v150, v36
	v_max3_f32 v34, v50, v68, v150
	v_mov_b32_e32 v36, v34
	v_mov_b32_e32 v255, v34
	s_nop 1
	v_permlane16_swap_b32_e32 v36, v255
	v_sub_f32_e32 v151, v154, v188
	v_sub_f32_e32 v50, v133, v188
	v_mul_f32_e32 v133, 0x3fb8aa3b, v50
	v_sub_f32_e32 v50, v155, v188
	v_max_f32_e32 v36, v36, v255
	s_nop 1
	v_mov_b32_dpp v66, v36 row_ror:8 row_mask:0xf bank_mask:0xf
	v_mul_f32_e32 v50, 0x3fb8aa3b, v50
	v_exp_f32_e32 v34, v50
	v_sub_f32_e32 v50, v156, v188
	v_sub_f32_e32 v82, v160, v188
	v_max_f32_e32 v36, v36, v66
	s_nop 1
	v_mov_b32_dpp v66, v36 row_shl:4 row_mask:0xf bank_mask:0x5
	s_nop 1
	v_mov_b32_dpp v66, v36 row_shr:4 row_mask:0xf bank_mask:0xa
	v_mul_f32_e32 v50, 0x3fb8aa3b, v50
	v_mul_f32_e32 v82, 0x3fb8aa3b, v82
	v_exp_f32_e32 v35, v35
	v_exp_f32_e32 v50, v50
	v_max_f32_e32 v152, v36, v66
	s_nop 1
	v_mov_b32_dpp v153, v152 quad_perm:[2,3,0,1] row_mask:0xf bank_mask:0xf
	v_mul_f32_e32 v36, 0x3fb8aa3b, v151
	v_exp_f32_e32 v82, v82
	v_exp_f32_e32 v66, v36
	v_cvt_pk_bf16_f32 v148, v35, v51
	v_max_f32_e32 v151, v153, v153
	v_cvt_pk_bf16_f32 v149, v83, v67
	v_mov_b32_e32 v154, v85
	v_mov_b32_e32 v155, v53
	v_max3_f32 v53, v154, s59, v155
	v_mov_b32_e32 v156, v69
	v_cvt_pk_bf16_f32 v36, v34, v50
	v_mov_b32_e32 v153, v37
	v_max3_f32 v53, v53, v156, v153
	v_mov_b32_e32 v69, v53
	v_mov_b32_e32 v255, v53
	s_nop 1
	v_permlane16_swap_b32_e32 v69, v255
	s_nop 1
	v_mov_b32_dpp v69, v255 quad_perm:[0,1,2,3] row_mask:0x5 bank_mask:0xf
	v_cvt_pk_bf16_f32 v37, v82, v66
	ds_write2_b64 v187, v[148:149], v[36:37] offset0:196 offset1:230
	v_max_f32_e32 v151, v152, v151
	s_nop 1
	v_mov_b32_dpp v152, v151 quad_perm:[1,0,3,2] row_mask:0xf bank_mask:0xf
	v_max_f32_e32 v37, v69, v69
	v_max_f32_e32 v53, v53, v37
	v_sub_f32_e32 v131, v131, v206
	s_waitcnt lgkmcnt(0)
	v_max3_f32 v187, v134, v151, v152
	v_sub_f32_e32 v37, v84, v187
	v_sub_f32_e32 v52, v52, v187
	v_max_f32_dpp v69, v53, v53 row_ror:8 row_mask:0xf bank_mask:0xf
	s_nop 1
	v_mov_b32_dpp v84, v69 row_shl:4 row_mask:0xf bank_mask:0x5
	s_nop 1
	v_mov_b32_dpp v84, v69 row_shr:4 row_mask:0xf bank_mask:0xa
	v_mul_f32_e32 v52, 0x3fb8aa3b, v52
	v_exp_f32_e32 v53, v52
	v_sub_f32_e32 v52, v68, v187
	v_mul_f32_e32 v52, 0x3fb8aa3b, v52
	v_max_f32_e32 v68, v84, v84
	v_max_f32_e32 v68, v69, v68
	s_nop 1
	v_mov_b32_dpp v84, v68 quad_perm:[2,3,0,1] row_mask:0xf bank_mask:0xf
	v_exp_f32_e32 v85, v52
	v_sub_f32_e32 v52, v150, v187
	v_mul_f32_e32 v52, 0x3fb8aa3b, v52
	v_exp_f32_e32 v69, v52
	v_max_f32_e32 v52, v84, v84
	v_max_f32_e32 v52, v68, v52
	s_nop 1
	v_mov_b32_dpp v68, v52 quad_perm:[1,0,3,2] row_mask:0xf bank_mask:0xf
	v_sub_f32_e32 v36, v134, v187
	v_mul_f32_e32 v36, 0x3fb8aa3b, v36
	v_exp_f32_e32 v134, v36
	v_max3_f32 v160, v135, v52, v68
	v_max3_f32 v52, v86, s59, v54
	v_max3_f32 v52, v52, v70, v38
	v_mov_b32_e32 v68, v52
	v_mov_b32_e32 v255, v52
	s_nop 1
	v_permlane16_swap_b32_e32 v68, v255
	v_sub_f32_e32 v36, v154, v160
	v_sub_u32_e32 v154, v96, v174
	v_max_f32_e32 v68, v68, v255
	s_nop 1
	v_mov_b32_e32 v212, v87
	v_max_f32_dpp v150, v68, v68 row_ror:8 row_mask:0xf bank_mask:0xf
	v_mov_b32_e32 v213, v55
	s_nop 0
	v_mov_b32_dpp v151, v150 row_shl:4 row_mask:0xf bank_mask:0x5
	s_nop 1
	v_mov_b32_dpp v151, v150 row_shr:4 row_mask:0xf bank_mask:0xa
	v_mov_b32_e32 v214, v71
	v_add_u32_e32 v71, 0x60, v154
	v_max3_f32 v55, v212, s59, v213
	v_mov_b32_e32 v154, v39
	v_max3_f32 v39, v55, v214, v154
	v_max_f32_e32 v152, v150, v151
	v_mov_b32_e32 v55, v39
	v_mov_b32_e32 v255, v39
	s_nop 1
	v_permlane16_swap_b32_e32 v55, v255
	v_sub_f32_e32 v68, v153, v160
	v_mov_b32_dpp v153, v152 quad_perm:[2,3,0,1] row_mask:0xf bank_mask:0xf
	v_sub_f32_e32 v84, v155, v160
	v_mul_f32_e32 v52, 0x3fb8aa3b, v84
	v_max_f32_e32 v55, v55, v255
	v_max_f32_e32 v152, v152, v153
	s_nop 0
	s_nop 1
	v_mov_b32_dpp v153, v152 quad_perm:[1,0,3,2] row_mask:0xf bank_mask:0xf
	v_sub_f32_e32 v84, v156, v160
	v_mul_f32_e32 v37, 0x3fb8aa3b, v37
	v_mul_f32_e32 v36, 0x3fb8aa3b, v36
	v_max3_f32 v156, v136, v152, v153
	v_max_f32_dpp v71, v55, v55 row_ror:8 row_mask:0xf bank_mask:0xf
	v_sub_f32_e32 v39, v86, v156
	s_nop 1
	v_mov_b32_dpp v86, v71 row_shl:4 row_mask:0xf bank_mask:0x5
	s_nop 1
	v_mov_b32_dpp v86, v71 row_shr:4 row_mask:0xf bank_mask:0xa
	v_sub_f32_e32 v54, v54, v156
	v_mul_f32_e32 v54, 0x3fb8aa3b, v54
	v_exp_f32_e32 v55, v54
	v_sub_f32_e32 v54, v70, v156
	v_max_f32_e32 v70, v86, v86
	v_max_f32_e32 v70, v71, v70
	s_nop 1
	v_mov_b32_dpp v86, v70 quad_perm:[2,3,0,1] row_mask:0xf bank_mask:0xf
	v_sub_f32_e32 v38, v38, v156
	v_mul_f32_e32 v38, 0x3fb8aa3b, v38
	v_exp_f32_e32 v71, v38
	v_mul_f32_e32 v54, 0x3fb8aa3b, v54
	v_max_f32_e32 v38, v86, v86
	v_max_f32_e32 v38, v70, v38
	v_exp_f32_e32 v87, v54
	s_nop 1
	v_mov_b32_dpp v54, v38 quad_perm:[1,0,3,2] row_mask:0xf bank_mask:0xf
	v_sub_f32_e32 v136, v136, v156
	v_mul_f32_e32 v84, 0x3fb8aa3b, v84
	v_mul_f32_e32 v68, 0x3fb8aa3b, v68
	v_mul_f32_e32 v70, 0x3fb8aa3b, v136
	v_max3_f32 v155, v137, v38, v54
	v_sub_u32_e32 v38, v96, v175
	v_exp_f32_e32 v37, v37
	v_exp_f32_e32 v36, v36
	v_exp_f32_e32 v52, v52
	v_exp_f32_e32 v84, v84
	v_exp_f32_e32 v68, v68
	v_exp_f32_e32 v136, v70
	v_add_u32_e32 v70, 64, v38
	v_cvt_pk_bf16_f32 v148, v37, v53
	v_cvt_pk_bf16_f32 v149, v85, v69
	v_cvt_pk_bf16_f32 v150, v36, v52
	v_cvt_pk_bf16_f32 v151, v84, v68
	ds_write2_b64 v215, v[148:149], v[150:151] offset0:144 offset1:178
	v_max3_f32 v54, v88, s59, v56
	v_mov_b32_e32 v150, v40
	v_max3_f32 v38, v54, v72, v150
	v_mov_b32_e32 v40, v38
	v_mov_b32_e32 v255, v38
	s_nop 1
	v_permlane16_swap_b32_e32 v40, v255
	v_sub_f32_e32 v151, v154, v155
	v_sub_f32_e32 v54, v137, v155
	v_mul_f32_e32 v137, 0x3fb8aa3b, v54
	v_sub_f32_e32 v54, v212, v155
	s_waitcnt lgkmcnt(0)
	v_max_f32_e32 v40, v40, v255
	s_nop 1
	v_mov_b32_dpp v70, v40 row_ror:8 row_mask:0xf bank_mask:0xf
	v_mul_f32_e32 v54, 0x3fb8aa3b, v54
	v_exp_f32_e32 v38, v54
	v_sub_f32_e32 v54, v213, v155
	v_sub_f32_e32 v86, v214, v155
	v_max_f32_e32 v40, v40, v70
	s_nop 1
	v_mov_b32_dpp v70, v40 row_shl:4 row_mask:0xf bank_mask:0x5
	s_nop 1
	v_mov_b32_dpp v70, v40 row_shr:4 row_mask:0xf bank_mask:0xa
	v_mul_f32_e32 v39, 0x3fb8aa3b, v39
	v_mul_f32_e32 v54, 0x3fb8aa3b, v54
	v_mul_f32_e32 v86, 0x3fb8aa3b, v86
	v_exp_f32_e32 v39, v39
	v_max_f32_e32 v152, v40, v70
	s_nop 1
	v_mov_b32_dpp v153, v152 quad_perm:[2,3,0,1] row_mask:0xf bank_mask:0xf
	v_mul_f32_e32 v40, 0x3fb8aa3b, v151
	v_exp_f32_e32 v54, v54
	v_exp_f32_e32 v86, v86
	v_exp_f32_e32 v70, v40
	v_max_f32_e32 v151, v153, v153
	v_cvt_pk_bf16_f32 v148, v39, v55
	v_mov_b32_e32 v212, v89
	v_mov_b32_e32 v213, v57
	v_max3_f32 v57, v212, s59, v213
	v_mov_b32_e32 v214, v73
	v_cvt_pk_bf16_f32 v149, v87, v71
	v_mov_b32_e32 v216, v41
	v_max3_f32 v57, v57, v214, v216
	v_mov_b32_e32 v73, v57
	v_mov_b32_e32 v255, v57
	s_nop 1
	v_permlane16_swap_b32_e32 v73, v255
	s_nop 1
	v_mov_b32_dpp v73, v255 quad_perm:[0,1,2,3] row_mask:0x5 bank_mask:0xf
	v_cvt_pk_bf16_f32 v40, v38, v54
	v_cvt_pk_bf16_f32 v41, v86, v70
	ds_write2_b64 v215, v[148:149], v[40:41] offset0:212 offset1:246
	v_max_f32_e32 v151, v152, v151
	v_max_f32_e32 v41, v73, v73
	v_max_f32_e32 v57, v57, v41
	v_mov_b32_dpp v152, v151 quad_perm:[1,0,3,2] row_mask:0xf bank_mask:0xf
	v_sub_f32_e32 v135, v135, v160
	v_mul_f32_e32 v131, 0x3fb8aa3b, v131
	v_mul_f32_e32 v135, 0x3fb8aa3b, v135
	s_waitcnt lgkmcnt(0)
	v_max3_f32 v154, v138, v151, v152
	v_max_f32_dpp v73, v57, v57 row_ror:8 row_mask:0xf bank_mask:0xf
	v_sub_f32_e32 v41, v88, v154
	s_nop 1
	v_mov_b32_dpp v88, v73 row_shl:4 row_mask:0xf bank_mask:0x5
	s_nop 1
	v_mov_b32_dpp v88, v73 row_shr:4 row_mask:0xf bank_mask:0xa
	v_sub_f32_e32 v56, v56, v154
	v_mul_f32_e32 v56, 0x3fb8aa3b, v56
	v_exp_f32_e32 v57, v56
	v_sub_f32_e32 v56, v72, v154
	v_max_f32_e32 v72, v88, v88
	v_max_f32_e32 v72, v73, v72
	s_nop 1
	v_mov_b32_dpp v88, v72 quad_perm:[2,3,0,1] row_mask:0xf bank_mask:0xf
	v_mul_f32_e32 v56, 0x3fb8aa3b, v56
	v_exp_f32_e32 v89, v56
	v_sub_f32_e32 v56, v150, v154
	v_mul_f32_e32 v56, 0x3fb8aa3b, v56
	v_exp_f32_e32 v73, v56
	v_max_f32_e32 v56, v88, v88
	v_max_f32_e32 v56, v72, v56
	s_nop 1
	v_mov_b32_dpp v72, v56 quad_perm:[1,0,3,2] row_mask:0xf bank_mask:0xf
	v_sub_f32_e32 v40, v138, v154
	v_mul_f32_e32 v40, 0x3fb8aa3b, v40
	v_exp_f32_e32 v138, v40
	v_max3_f32 v153, v139, v56, v72
	v_max3_f32 v56, v90, s59, v58
	v_max3_f32 v56, v56, v74, v42
	v_mov_b32_e32 v72, v56
	v_mov_b32_e32 v255, v56
	s_nop 1
	v_permlane16_swap_b32_e32 v72, v255
	v_sub_f32_e32 v88, v213, v153
	v_max_f32_e32 v72, v72, v255
	v_mul_f32_e32 v56, 0x3fb8aa3b, v88
	v_sub_f32_e32 v88, v214, v153
	v_mov_b32_e32 v214, v91
	v_max_f32_dpp v150, v72, v72 row_ror:8 row_mask:0xf bank_mask:0xf
	v_mov_b32_e32 v215, v59
	s_nop 0
	v_mov_b32_dpp v151, v150 row_shl:4 row_mask:0xf bank_mask:0x5
	s_nop 1
	v_mov_b32_dpp v151, v150 row_shr:4 row_mask:0xf bank_mask:0xa
	v_sub_f32_e32 v72, v216, v153
	v_mov_b32_e32 v216, v75
	v_max3_f32 v59, v214, s59, v215
	v_mov_b32_e32 v213, v43
	v_max3_f32 v43, v59, v216, v213
	v_sub_f32_e32 v40, v212, v153
	v_max_f32_e32 v152, v150, v151
	v_mov_b32_e32 v59, v43
	v_mov_b32_e32 v255, v43
	s_nop 1
	v_permlane16_swap_b32_e32 v59, v255
	v_mul_f32_e32 v41, 0x3fb8aa3b, v41
	v_mul_f32_e32 v40, 0x3fb8aa3b, v40
	v_mul_f32_e32 v88, 0x3fb8aa3b, v88
	v_mul_f32_e32 v72, 0x3fb8aa3b, v72
	v_mov_b32_dpp v212, v152 quad_perm:[2,3,0,1] row_mask:0xf bank_mask:0xf
	v_exp_f32_e32 v41, v41
	v_exp_f32_e32 v40, v40
	v_exp_f32_e32 v56, v56
	v_exp_f32_e32 v88, v88
	v_exp_f32_e32 v72, v72
	v_cvt_pk_bf16_f32 v148, v41, v57
	v_cvt_pk_bf16_f32 v149, v89, v73
	v_cvt_pk_bf16_f32 v150, v40, v56
	v_cvt_pk_bf16_f32 v151, v88, v72
	v_add_u32_e32 v75, 0x9800, v186
	v_max_f32_e32 v59, v59, v255
	v_max_f32_e32 v152, v152, v212
	ds_write2_b64 v75, v[148:149], v[150:151] offset0:160 offset1:194
	s_nop 0
	v_mov_b32_dpp v212, v152 quad_perm:[1,0,3,2] row_mask:0xf bank_mask:0xf
	v_sub_f32_e32 v139, v139, v153
	v_mul_f32_e32 v139, 0x3fb8aa3b, v139
	v_exp_f32_e32 v131, v131
	s_waitcnt lgkmcnt(0)
	v_max3_f32 v152, v140, v152, v212
	v_max_f32_dpp v75, v59, v59 row_ror:8 row_mask:0xf bank_mask:0xf
	v_sub_f32_e32 v43, v90, v152
	s_nop 1
	v_mov_b32_dpp v90, v75 row_shl:4 row_mask:0xf bank_mask:0x5
	s_nop 1
	v_mov_b32_dpp v90, v75 row_shr:4 row_mask:0xf bank_mask:0xa
	v_sub_f32_e32 v58, v58, v152
	v_mul_f32_e32 v58, 0x3fb8aa3b, v58
	v_exp_f32_e32 v59, v58
	v_sub_f32_e32 v58, v74, v152
	v_max_f32_e32 v74, v90, v90
	v_max_f32_e32 v74, v75, v74
	s_nop 1
	v_mov_b32_dpp v90, v74 quad_perm:[2,3,0,1] row_mask:0xf bank_mask:0xf
	v_sub_f32_e32 v42, v42, v152
	v_mul_f32_e32 v42, 0x3fb8aa3b, v42
	v_exp_f32_e32 v75, v42
	v_mul_f32_e32 v58, 0x3fb8aa3b, v58
	v_max_f32_e32 v42, v90, v90
	v_max_f32_e32 v42, v74, v42
	v_exp_f32_e32 v91, v58
	s_nop 1
	v_mov_b32_dpp v58, v42 quad_perm:[1,0,3,2] row_mask:0xf bank_mask:0xf
	v_sub_f32_e32 v140, v140, v152
	v_mul_f32_e32 v74, 0x3fb8aa3b, v140
	v_exp_f32_e32 v140, v74
	v_mul_f32_e32 v43, 0x3fb8aa3b, v43
	v_max3_f32 v151, v141, v42, v58
	v_max3_f32 v58, v92, s59, v60
	v_max3_f32 v58, v58, v76, v44
	v_mov_b32_e32 v74, v58
	v_mov_b32_e32 v255, v58
	s_nop 1
	v_permlane16_swap_b32_e32 v74, v255
	v_sub_f32_e32 v90, v215, v151
	v_max_f32_e32 v74, v74, v255
	v_mul_f32_e32 v58, 0x3fb8aa3b, v90
	v_sub_f32_e32 v90, v216, v151
	v_mov_b32_e32 v216, v93
	v_max_f32_dpp v150, v74, v74 row_ror:8 row_mask:0xf bank_mask:0xf
	v_mov_b32_e32 v217, v61
	s_nop 0
	v_mov_b32_dpp v212, v150 row_shl:4 row_mask:0xf bank_mask:0x5
	s_nop 1
	v_mov_b32_dpp v212, v150 row_shr:4 row_mask:0xf bank_mask:0xa
	v_mov_b32_e32 v218, v77
	v_max3_f32 v61, v216, s59, v217
	v_mov_b32_e32 v215, v45
	v_max3_f32 v45, v61, v218, v215
	v_sub_f32_e32 v42, v214, v151
	v_sub_f32_e32 v74, v213, v151
	v_max_f32_e32 v150, v150, v212
	v_mov_b32_e32 v61, v45
	v_mov_b32_e32 v255, v45
	s_nop 1
	v_permlane16_swap_b32_e32 v61, v255
	v_mul_f32_e32 v42, 0x3fb8aa3b, v42
	v_mul_f32_e32 v90, 0x3fb8aa3b, v90
	v_mul_f32_e32 v74, 0x3fb8aa3b, v74
	v_mov_b32_dpp v214, v150 quad_perm:[2,3,0,1] row_mask:0xf bank_mask:0xf
	v_exp_f32_e32 v43, v43
	v_exp_f32_e32 v42, v42
	v_exp_f32_e32 v58, v58
	v_exp_f32_e32 v90, v90
	v_exp_f32_e32 v74, v74
	v_cvt_pk_bf16_f32 v148, v43, v59
	v_cvt_pk_bf16_f32 v149, v91, v75
	v_cvt_pk_bf16_f32 v212, v42, v58
	v_cvt_pk_bf16_f32 v213, v90, v74
	v_add_u32_e32 v77, 0x9c00, v186
	v_max_f32_e32 v61, v61, v255
	v_max_f32_e32 v150, v150, v214
	ds_write2_b64 v77, v[148:149], v[212:213] offset0:100 offset1:134
	s_nop 0
	v_mov_b32_dpp v214, v150 quad_perm:[1,0,3,2] row_mask:0xf bank_mask:0xf
	v_sub_f32_e32 v141, v141, v151
	v_mul_f32_e32 v141, 0x3fb8aa3b, v141
	v_exp_f32_e32 v133, v133
	s_waitcnt lgkmcnt(0)
	v_max3_f32 v150, v142, v150, v214
	v_max_f32_dpp v77, v61, v61 row_ror:8 row_mask:0xf bank_mask:0xf
	v_sub_f32_e32 v45, v92, v150
	s_nop 1
	v_mov_b32_dpp v92, v77 row_shl:4 row_mask:0xf bank_mask:0x5
	s_nop 1
	v_mov_b32_dpp v92, v77 row_shr:4 row_mask:0xf bank_mask:0xa
	v_sub_f32_e32 v60, v60, v150
	v_mul_f32_e32 v60, 0x3fb8aa3b, v60
	v_exp_f32_e32 v61, v60
	v_sub_f32_e32 v60, v76, v150
	v_max_f32_e32 v76, v92, v92
	v_max_f32_e32 v76, v77, v76
	s_nop 1
	v_mov_b32_dpp v92, v76 quad_perm:[2,3,0,1] row_mask:0xf bank_mask:0xf
	v_sub_f32_e32 v44, v44, v150
	v_mul_f32_e32 v44, 0x3fb8aa3b, v44
	v_exp_f32_e32 v77, v44
	v_mul_f32_e32 v60, 0x3fb8aa3b, v60
	v_max_f32_e32 v44, v92, v92
	v_max_f32_e32 v44, v76, v44
	v_exp_f32_e32 v93, v60
	s_nop 1
	v_mov_b32_dpp v60, v44 quad_perm:[1,0,3,2] row_mask:0xf bank_mask:0xf
	v_sub_f32_e32 v142, v142, v150
	v_mul_f32_e32 v76, 0x3fb8aa3b, v142
	v_exp_f32_e32 v142, v76
	v_mul_f32_e32 v45, 0x3fb8aa3b, v45
	v_max3_f32 v149, v143, v44, v60
	v_max3_f32 v60, v94, s59, v62
	v_max3_f32 v60, v60, v78, v46
	v_mov_b32_e32 v76, v60
	v_mov_b32_e32 v255, v60
	s_nop 1
	v_permlane16_swap_b32_e32 v76, v255
	v_sub_f32_e32 v92, v217, v149
	v_max_f32_e32 v76, v76, v255
	v_mov_b32_e32 v217, v95
	v_mul_f32_e32 v60, 0x3fb8aa3b, v92
	v_sub_f32_e32 v92, v218, v149
	v_max_f32_dpp v148, v76, v76 row_ror:8 row_mask:0xf bank_mask:0xf
	v_mov_b32_e32 v218, v63
	s_nop 0
	v_mov_b32_dpp v214, v148 row_shl:4 row_mask:0xf bank_mask:0x5
	s_nop 1
	v_mov_b32_dpp v214, v148 row_shr:4 row_mask:0xf bank_mask:0xa
	v_mov_b32_e32 v219, v79
	v_max3_f32 v63, v217, s59, v218
	v_mov_b32_e32 v96, v47
	v_max3_f32 v47, v63, v219, v96
	v_sub_f32_e32 v44, v216, v149
	v_sub_f32_e32 v76, v215, v149
	v_max_f32_e32 v148, v148, v214
	v_mov_b32_e32 v63, v47
	v_mov_b32_e32 v255, v47
	s_nop 1
	v_permlane16_swap_b32_e32 v63, v255
	v_mul_f32_e32 v44, 0x3fb8aa3b, v44
	v_mul_f32_e32 v92, 0x3fb8aa3b, v92
	v_mul_f32_e32 v76, 0x3fb8aa3b, v76
	v_mov_b32_dpp v216, v148 quad_perm:[2,3,0,1] row_mask:0xf bank_mask:0xf
	v_exp_f32_e32 v45, v45
	v_exp_f32_e32 v44, v44
	v_exp_f32_e32 v60, v60
	v_exp_f32_e32 v92, v92
	v_exp_f32_e32 v76, v76
	v_cvt_pk_bf16_f32 v212, v45, v61
	v_cvt_pk_bf16_f32 v213, v93, v77
	v_cvt_pk_bf16_f32 v214, v44, v60
	v_cvt_pk_bf16_f32 v215, v92, v76
	v_add_u32_e32 v79, 0xa000, v186
	v_max_f32_e32 v63, v63, v255
	v_max_f32_e32 v148, v148, v216
	ds_write2_b64 v79, v[212:213], v[214:215] offset0:176 offset1:210
	s_nop 0
	v_mov_b32_dpp v216, v148 quad_perm:[1,0,3,2] row_mask:0xf bank_mask:0xf
	v_sub_f32_e32 v143, v143, v149
	v_mul_f32_e32 v143, 0x3fb8aa3b, v143
	v_exp_f32_e32 v135, v135
	s_waitcnt lgkmcnt(0)
	v_max3_f32 v148, v144, v148, v216
	v_max_f32_dpp v79, v63, v63 row_ror:8 row_mask:0xf bank_mask:0xf
	v_sub_f32_e32 v47, v94, v148
	s_nop 1
	v_mov_b32_dpp v94, v79 row_shl:4 row_mask:0xf bank_mask:0x5
	s_nop 1
	v_mov_b32_dpp v94, v79 row_shr:4 row_mask:0xf bank_mask:0xa
	v_sub_f32_e32 v62, v62, v148
	v_mul_f32_e32 v62, 0x3fb8aa3b, v62
	v_exp_f32_e32 v63, v62
	v_sub_f32_e32 v62, v78, v148
	v_max_f32_e32 v78, v94, v94
	v_max_f32_e32 v78, v79, v78
	s_nop 1
	v_mov_b32_dpp v94, v78 quad_perm:[2,3,0,1] row_mask:0xf bank_mask:0xf
	v_sub_f32_e32 v46, v46, v148
	v_mul_f32_e32 v46, 0x3fb8aa3b, v46
	v_exp_f32_e32 v79, v46
	v_mul_f32_e32 v62, 0x3fb8aa3b, v62
	v_max_f32_e32 v46, v94, v94
	v_max_f32_e32 v46, v78, v46
	v_exp_f32_e32 v95, v62
	s_nop 1
	v_mov_b32_dpp v62, v46 quad_perm:[1,0,3,2] row_mask:0xf bank_mask:0xf
	v_sub_f32_e32 v144, v144, v148
	v_mul_f32_e32 v78, 0x3fb8aa3b, v144
	v_exp_f32_e32 v144, v78
	v_mul_f32_e32 v47, 0x3fb8aa3b, v47
	v_max3_f32 v147, v145, v46, v62
	v_sub_f32_e32 v78, v219, v147
	v_mul_f32_e32 v78, 0x3fb8aa3b, v78
	v_sub_f32_e32 v46, v217, v147
	v_sub_f32_e32 v62, v218, v147
	v_exp_f32_e32 v94, v78
	v_sub_f32_e32 v78, v96, v147
	v_sub_f32_e32 v145, v145, v147
	v_mul_f32_e32 v46, 0x3fb8aa3b, v46
	v_mul_f32_e32 v62, 0x3fb8aa3b, v62
	v_mul_f32_e32 v78, 0x3fb8aa3b, v78
	v_exp_f32_e32 v47, v47
	v_exp_f32_e32 v46, v46
	v_exp_f32_e32 v62, v62
	v_exp_f32_e32 v78, v78
	v_mul_f32_e32 v96, 0x3fb8aa3b, v145
	v_exp_f32_e32 v137, v137
	v_exp_f32_e32 v139, v139
	v_exp_f32_e32 v141, v141
	v_exp_f32_e32 v143, v143
	v_exp_f32_e32 v145, v96
	v_cvt_pk_bf16_f32 v208, v47, v63
	v_cvt_pk_bf16_f32 v209, v95, v79
	v_cvt_pk_bf16_f32 v210, v46, v62
	v_cvt_pk_bf16_f32 v211, v94, v78
	v_add_u32_e32 v96, 0xa400, v186
	ds_write2_b64 v96, v[208:209], v[210:211] offset0:116 offset1:150
	v_pk_mul_f32 v[14:15], v[14:15], v[144:145]
	v_pk_mul_f32 v[12:13], v[12:13], v[142:143]
	v_pk_mul_f32 v[10:11], v[10:11], v[140:141]
	v_pk_mul_f32 v[8:9], v[8:9], v[138:139]
	v_pk_mul_f32 v[6:7], v[6:7], v[136:137]
	v_pk_mul_f32 v[4:5], v[4:5], v[134:135]
	v_pk_mul_f32 v[2:3], v[2:3], v[132:133]
	v_pk_mul_f32 v[0:1], v[0:1], v[130:131]
	v_pk_mul_f32 v[30:31], v[30:31], v[144:145]
	v_pk_mul_f32 v[28:29], v[28:29], v[142:143]
	v_pk_mul_f32 v[26:27], v[26:27], v[140:141]
	v_pk_mul_f32 v[24:25], v[24:25], v[138:139]
	v_pk_mul_f32 v[22:23], v[22:23], v[136:137]
	v_pk_mul_f32 v[20:21], v[20:21], v[134:135]
	v_pk_mul_f32 v[18:19], v[18:19], v[132:133]
	v_pk_mul_f32 v[16:17], v[16:17], v[130:131]
	s_mov_b32 s2, -16
	v_mov_b32_e32 v96, v185
	v_mov_b32_e32 v208, v184
	s_branch .Latt_join

.Lrg20_i:
	s_or_b64 exec, exec, s[0:1]
	s_waitcnt vmcnt(0)
	s_nop 0
	v_mov_b32_e32 v9, v207
	v_mov_b32_e32 v10, v208
	v_mov_b32_e32 v11, v209
	v_lshlrev_b32_e32 v54, 16, v206
	v_and_b32_e32 v55, 0xffff0000, v206
	v_lshlrev_b32_e32 v8, 16, v9
	v_and_b32_e32 v9, 0xffff0000, v9
	v_lshlrev_b32_e32 v12, 16, v10
	v_and_b32_e32 v13, 0xffff0000, v10
	v_lshlrev_b32_e32 v10, 16, v11
	v_and_b32_e32 v11, 0xffff0000, v11
	v_pk_fma_f32 v[14:15], v[46:47], v[10:11], v[6:7]
	v_pk_fma_f32 v[12:13], v[44:45], v[12:13], v[4:5]
	v_pk_fma_f32 v[10:11], v[42:43], v[8:9], v[2:3]
	v_pk_fma_f32 v[8:9], v[40:41], v[54:55], v[0:1]
	v_mov_b32_e32 v55, v211
	v_mov_b32_e32 v56, v212
	v_mov_b32_e32 v57, v213
	v_lshlrev_b32_e32 v58, 16, v210
	v_and_b32_e32 v59, 0xffff0000, v210
	v_lshlrev_b32_e32 v54, 16, v55
	v_and_b32_e32 v55, 0xffff0000, v55
	v_lshlrev_b32_e32 v60, 16, v56
	v_and_b32_e32 v61, 0xffff0000, v56
	v_lshlrev_b32_e32 v56, 16, v57
	v_and_b32_e32 v57, 0xffff0000, v57
	v_pk_fma_f32 v[14:15], v[38:39], v[56:57], v[14:15]
	v_pk_fma_f32 v[12:13], v[36:37], v[60:61], v[12:13]
	v_pk_fma_f32 v[10:11], v[34:35], v[54:55], v[10:11]
	v_pk_fma_f32 v[8:9], v[32:33], v[58:59], v[8:9]
	v_mov_b32_e32 v55, v215
	v_mov_b32_e32 v56, v216
	v_mov_b32_e32 v57, v217
	v_lshlrev_b32_e32 v58, 16, v214
	v_and_b32_e32 v59, 0xffff0000, v214
	v_lshlrev_b32_e32 v54, 16, v55
	v_and_b32_e32 v55, 0xffff0000, v55
	v_lshlrev_b32_e32 v60, 16, v56
	v_and_b32_e32 v61, 0xffff0000, v56
	v_lshlrev_b32_e32 v56, 16, v57
	v_and_b32_e32 v57, 0xffff0000, v57
	v_pk_fma_f32 v[14:15], v[30:31], v[56:57], v[14:15]
	v_pk_fma_f32 v[12:13], v[28:29], v[60:61], v[12:13]
	v_pk_fma_f32 v[10:11], v[26:27], v[54:55], v[10:11]
	v_pk_fma_f32 v[8:9], v[24:25], v[58:59], v[8:9]
	v_mov_b32_e32 v55, v219
	v_mov_b32_e32 v56, v220
	v_mov_b32_e32 v57, v221
	v_lshlrev_b32_e32 v58, 16, v218
	v_and_b32_e32 v59, 0xffff0000, v218
	v_lshlrev_b32_e32 v54, 16, v55
	v_and_b32_e32 v55, 0xffff0000, v55
	v_lshlrev_b32_e32 v60, 16, v56
	v_and_b32_e32 v61, 0xffff0000, v56
	v_lshlrev_b32_e32 v56, 16, v57
	v_and_b32_e32 v57, 0xffff0000, v57
	v_pk_fma_f32 v[14:15], v[22:23], v[56:57], v[14:15]
	v_pk_fma_f32 v[12:13], v[20:21], v[60:61], v[12:13]
	v_pk_fma_f32 v[10:11], v[18:19], v[54:55], v[10:11]
	v_pk_fma_f32 v[8:9], v[16:17], v[58:59], v[8:9]
	v_lshl_add_u32 v53, v50, 2, 0
	v_lshl_add_u32 v54, v52, 8, v53
	v_lshlrev_b32_e32 v50, 1, v50
	ds_write_b128 v54, v[8:11] offset:36864
	ds_write_b128 v54, v[12:15] offset:36880
	v_add_u32_e32 v54, 32, v52
	v_sub_u32_e32 v50, v53, v50
	v_add_u32_e32 v55, s68, v54
	v_cvt_pk_bf16_f32 v8, v8, v9
	v_cvt_pk_bf16_f32 v9, v10, v11
	v_cvt_pk_bf16_f32 v10, v12, v13
	v_cvt_pk_bf16_f32 v11, v14, v15
	v_mad_u64_u32 v[12:13], s[0:1], v52, s3, v[50:51]
	v_add_u32_e32 v56, -2, v55
	ds_write_b128 v12, v[8:11]
	v_cmp_lt_i32_e32 vcc, 1, v55
	v_cmp_gt_u32_e64 s[0:1], s39, v56
	v_mov_b64_e32 v[14:15], v[6:7]
	s_and_b64 s[42:43], vcc, s[0:1]
	v_mov_b64_e32 v[12:13], v[4:5]
	v_mov_b64_e32 v[10:11], v[2:3]
	v_mov_b64_e32 v[8:9], v[0:1]
	v_mov_b32_e32 v206, 0
	v_mov_b32_e32 v207, 0
	v_mov_b32_e32 v208, 0
	v_mov_b32_e32 v209, 0
	s_and_saveexec_b64 s[0:1], s[42:43]
	s_cbranch_execz .Lrg21_i
	v_add_u32_e32 v8, s38, v56
	v_mad_u64_u32 v[8:9], s[42:43], v8, s74, v[48:49]
	global_load_dwordx4 v[206:209], v[8:9], off

.Lrg24_i:
	s_or_b64 exec, exec, s[0:1]
	s_waitcnt vmcnt(0)
	s_nop 0
	v_mov_b32_e32 v9, v207
	v_mov_b32_e32 v10, v208
	v_mov_b32_e32 v11, v209
	v_lshlrev_b32_e32 v56, 16, v206
	v_and_b32_e32 v57, 0xffff0000, v206
	v_lshlrev_b32_e32 v8, 16, v9
	v_and_b32_e32 v9, 0xffff0000, v9
	v_lshlrev_b32_e32 v12, 16, v10
	v_and_b32_e32 v13, 0xffff0000, v10
	v_lshlrev_b32_e32 v10, 16, v11
	v_and_b32_e32 v11, 0xffff0000, v11
	v_pk_fma_f32 v[14:15], v[46:47], v[10:11], v[6:7]
	v_pk_fma_f32 v[12:13], v[44:45], v[12:13], v[4:5]
	v_pk_fma_f32 v[10:11], v[42:43], v[8:9], v[2:3]
	v_pk_fma_f32 v[8:9], v[40:41], v[56:57], v[0:1]
	v_mov_b32_e32 v57, v211
	v_mov_b32_e32 v58, v212
	v_mov_b32_e32 v59, v213
	v_lshlrev_b32_e32 v60, 16, v210
	v_and_b32_e32 v61, 0xffff0000, v210
	v_lshlrev_b32_e32 v56, 16, v57
	v_and_b32_e32 v57, 0xffff0000, v57
	v_lshlrev_b32_e32 v62, 16, v58
	v_and_b32_e32 v63, 0xffff0000, v58
	v_lshlrev_b32_e32 v58, 16, v59
	v_and_b32_e32 v59, 0xffff0000, v59
	v_pk_fma_f32 v[14:15], v[38:39], v[58:59], v[14:15]
	v_pk_fma_f32 v[12:13], v[36:37], v[62:63], v[12:13]
	v_pk_fma_f32 v[10:11], v[34:35], v[56:57], v[10:11]
	v_pk_fma_f32 v[8:9], v[32:33], v[60:61], v[8:9]
	v_mov_b32_e32 v57, v215
	v_mov_b32_e32 v58, v216
	v_mov_b32_e32 v59, v217
	v_lshlrev_b32_e32 v60, 16, v214
	v_and_b32_e32 v61, 0xffff0000, v214
	v_lshlrev_b32_e32 v56, 16, v57
	v_and_b32_e32 v57, 0xffff0000, v57
	v_lshlrev_b32_e32 v62, 16, v58
	v_and_b32_e32 v63, 0xffff0000, v58
	v_lshlrev_b32_e32 v58, 16, v59
	v_and_b32_e32 v59, 0xffff0000, v59
	v_pk_fma_f32 v[14:15], v[30:31], v[58:59], v[14:15]
	v_pk_fma_f32 v[12:13], v[28:29], v[62:63], v[12:13]
	v_pk_fma_f32 v[10:11], v[26:27], v[56:57], v[10:11]
	v_pk_fma_f32 v[8:9], v[24:25], v[60:61], v[8:9]
	v_mov_b32_e32 v57, v219
	v_mov_b32_e32 v58, v220
	v_mov_b32_e32 v59, v221
	v_lshlrev_b32_e32 v60, 16, v218
	v_and_b32_e32 v61, 0xffff0000, v218
	v_lshlrev_b32_e32 v56, 16, v57
	v_and_b32_e32 v57, 0xffff0000, v57
	v_lshlrev_b32_e32 v62, 16, v58
	v_and_b32_e32 v63, 0xffff0000, v58
	v_lshlrev_b32_e32 v58, 16, v59
	v_and_b32_e32 v59, 0xffff0000, v59
	v_pk_fma_f32 v[14:15], v[22:23], v[58:59], v[14:15]
	v_pk_fma_f32 v[12:13], v[20:21], v[62:63], v[12:13]
	v_pk_fma_f32 v[10:11], v[18:19], v[56:57], v[10:11]
	v_pk_fma_f32 v[8:9], v[16:17], v[60:61], v[8:9]
	v_lshl_add_u32 v55, v54, 8, v53
	ds_write_b128 v55, v[8:11] offset:36864
	ds_write_b128 v55, v[12:15] offset:36880
	v_cvt_pk_bf16_f32 v8, v8, v9
	v_cvt_pk_bf16_f32 v9, v10, v11
	v_cvt_pk_bf16_f32 v10, v12, v13
	v_mad_u64_u32 v[12:13], s[0:1], v54, s3, v[50:51]
	v_add_u32_e32 v54, 64, v52
	v_add_u32_e32 v55, s68, v54
	v_cvt_pk_bf16_f32 v11, v14, v15
	v_add_u32_e32 v56, -2, v55
	ds_write_b128 v12, v[8:11]
	v_cmp_lt_i32_e32 vcc, 1, v55
	v_cmp_gt_u32_e64 s[0:1], s39, v56
	v_mov_b64_e32 v[14:15], v[6:7]
	s_and_b64 s[42:43], vcc, s[0:1]
	v_mov_b64_e32 v[12:13], v[4:5]
	v_mov_b64_e32 v[10:11], v[2:3]
	v_mov_b64_e32 v[8:9], v[0:1]
	v_mov_b32_e32 v206, 0
	v_mov_b32_e32 v207, 0
	v_mov_b32_e32 v208, 0
	v_mov_b32_e32 v209, 0
	s_and_saveexec_b64 s[0:1], s[42:43]
	s_cbranch_execz .Lrg25_i
	v_add_u32_e32 v8, s38, v56
	v_mad_u64_u32 v[8:9], s[42:43], v8, s74, v[48:49]
	global_load_dwordx4 v[206:209], v[8:9], off

.Lrg28_i:
	s_or_b64 exec, exec, s[0:1]
	s_waitcnt vmcnt(0)
	s_nop 0
	v_mov_b32_e32 v9, v207
	v_mov_b32_e32 v10, v208
	v_mov_b32_e32 v11, v209
	v_lshlrev_b32_e32 v56, 16, v206
	v_and_b32_e32 v57, 0xffff0000, v206
	v_lshlrev_b32_e32 v8, 16, v9
	v_and_b32_e32 v9, 0xffff0000, v9
	v_lshlrev_b32_e32 v12, 16, v10
	v_and_b32_e32 v13, 0xffff0000, v10
	v_lshlrev_b32_e32 v10, 16, v11
	v_and_b32_e32 v11, 0xffff0000, v11
	v_pk_fma_f32 v[14:15], v[46:47], v[10:11], v[6:7]
	v_pk_fma_f32 v[12:13], v[44:45], v[12:13], v[4:5]
	v_pk_fma_f32 v[10:11], v[42:43], v[8:9], v[2:3]
	v_pk_fma_f32 v[8:9], v[40:41], v[56:57], v[0:1]
	v_mov_b32_e32 v57, v211
	v_mov_b32_e32 v58, v212
	v_mov_b32_e32 v59, v213
	v_lshlrev_b32_e32 v60, 16, v210
	v_and_b32_e32 v61, 0xffff0000, v210
	v_lshlrev_b32_e32 v56, 16, v57
	v_and_b32_e32 v57, 0xffff0000, v57
	v_lshlrev_b32_e32 v62, 16, v58
	v_and_b32_e32 v63, 0xffff0000, v58
	v_lshlrev_b32_e32 v58, 16, v59
	v_and_b32_e32 v59, 0xffff0000, v59
	v_pk_fma_f32 v[14:15], v[38:39], v[58:59], v[14:15]
	v_pk_fma_f32 v[12:13], v[36:37], v[62:63], v[12:13]
	v_pk_fma_f32 v[10:11], v[34:35], v[56:57], v[10:11]
	v_pk_fma_f32 v[8:9], v[32:33], v[60:61], v[8:9]
	v_mov_b32_e32 v57, v215
	v_mov_b32_e32 v58, v216
	v_mov_b32_e32 v59, v217
	v_lshlrev_b32_e32 v60, 16, v214
	v_and_b32_e32 v61, 0xffff0000, v214
	v_lshlrev_b32_e32 v56, 16, v57
	v_and_b32_e32 v57, 0xffff0000, v57
	v_lshlrev_b32_e32 v62, 16, v58
	v_and_b32_e32 v63, 0xffff0000, v58
	v_lshlrev_b32_e32 v58, 16, v59
	v_and_b32_e32 v59, 0xffff0000, v59
	v_pk_fma_f32 v[14:15], v[30:31], v[58:59], v[14:15]
	v_pk_fma_f32 v[12:13], v[28:29], v[62:63], v[12:13]
	v_pk_fma_f32 v[10:11], v[26:27], v[56:57], v[10:11]
	v_pk_fma_f32 v[8:9], v[24:25], v[60:61], v[8:9]
	v_mov_b32_e32 v57, v219
	v_mov_b32_e32 v58, v220
	v_mov_b32_e32 v59, v221
	v_lshlrev_b32_e32 v60, 16, v218
	v_and_b32_e32 v61, 0xffff0000, v218
	v_lshlrev_b32_e32 v56, 16, v57
	v_and_b32_e32 v57, 0xffff0000, v57
	v_lshlrev_b32_e32 v62, 16, v58
	v_and_b32_e32 v63, 0xffff0000, v58
	v_lshlrev_b32_e32 v58, 16, v59
	v_and_b32_e32 v59, 0xffff0000, v59
	v_pk_fma_f32 v[14:15], v[22:23], v[58:59], v[14:15]
	v_pk_fma_f32 v[12:13], v[20:21], v[62:63], v[12:13]
	v_pk_fma_f32 v[10:11], v[18:19], v[56:57], v[10:11]
	v_pk_fma_f32 v[8:9], v[16:17], v[60:61], v[8:9]
	v_lshl_add_u32 v55, v54, 8, v53
	ds_write_b128 v55, v[8:11] offset:36864
	ds_write_b128 v55, v[12:15] offset:36880
	v_cvt_pk_bf16_f32 v8, v8, v9
	v_cvt_pk_bf16_f32 v9, v10, v11
	v_cvt_pk_bf16_f32 v10, v12, v13
	v_cvt_pk_bf16_f32 v11, v14, v15
	v_mad_u64_u32 v[12:13], s[0:1], v54, s3, v[50:51]
	ds_write_b128 v12, v[8:11]
	v_add_u32_e32 v8, 0x60, v52
	v_add_u32_e32 v9, s68, v8
	v_add_u32_e32 v10, -2, v9
	v_cmp_lt_i32_e32 vcc, 1, v9
	v_cmp_gt_u32_e64 s[0:1], s39, v10
	s_and_b64 s[42:43], vcc, s[0:1]
	v_mov_b32_e32 v206, 0
	v_mov_b32_e32 v207, 0
	v_mov_b32_e32 v208, 0
	v_mov_b32_e32 v209, 0
	s_and_saveexec_b64 s[0:1], s[42:43]
	s_cbranch_execz .Lrg29_i
	v_add_u32_e32 v10, s38, v10
	v_mad_u64_u32 v[10:11], s[42:43], v10, s74, v[48:49]
	global_load_dwordx4 v[206:209], v[10:11], off

.Lrg32_i:
	s_or_b64 exec, exec, s[0:1]
	s_waitcnt vmcnt(0)
	s_nop 0
	v_mov_b32_e32 v11, v207
	v_mov_b32_e32 v12, v208
	v_mov_b32_e32 v13, v209
	v_lshlrev_b32_e32 v14, 16, v206
	v_and_b32_e32 v15, 0xffff0000, v206
	v_lshlrev_b32_e32 v10, 16, v11
	v_and_b32_e32 v11, 0xffff0000, v11
	v_lshlrev_b32_e32 v54, 16, v12
	v_and_b32_e32 v55, 0xffff0000, v12
	v_lshlrev_b32_e32 v12, 16, v13
	v_and_b32_e32 v13, 0xffff0000, v13
	v_pk_fma_f32 v[6:7], v[46:47], v[12:13], v[6:7]
	v_pk_fma_f32 v[4:5], v[44:45], v[54:55], v[4:5]
	v_pk_fma_f32 v[2:3], v[42:43], v[10:11], v[2:3]
	v_pk_fma_f32 v[0:1], v[40:41], v[14:15], v[0:1]
	v_mov_b32_e32 v11, v211
	v_mov_b32_e32 v12, v212
	v_mov_b32_e32 v13, v213
	v_lshlrev_b32_e32 v14, 16, v210
	v_and_b32_e32 v15, 0xffff0000, v210
	v_lshlrev_b32_e32 v10, 16, v11
	v_and_b32_e32 v11, 0xffff0000, v11
	v_lshlrev_b32_e32 v40, 16, v12
	v_and_b32_e32 v41, 0xffff0000, v12
	v_lshlrev_b32_e32 v12, 16, v13
	v_and_b32_e32 v13, 0xffff0000, v13
	v_pk_fma_f32 v[6:7], v[38:39], v[12:13], v[6:7]
	v_pk_fma_f32 v[4:5], v[36:37], v[40:41], v[4:5]
	v_pk_fma_f32 v[2:3], v[34:35], v[10:11], v[2:3]
	v_pk_fma_f32 v[0:1], v[32:33], v[14:15], v[0:1]
	v_mov_b32_e32 v11, v215
	v_mov_b32_e32 v12, v216
	v_mov_b32_e32 v13, v217
	v_lshlrev_b32_e32 v14, 16, v214
	v_and_b32_e32 v15, 0xffff0000, v214
	v_lshlrev_b32_e32 v10, 16, v11
	v_and_b32_e32 v11, 0xffff0000, v11
	v_lshlrev_b32_e32 v32, 16, v12
	v_and_b32_e32 v33, 0xffff0000, v12
	v_lshlrev_b32_e32 v12, 16, v13
	v_and_b32_e32 v13, 0xffff0000, v13
	v_pk_fma_f32 v[6:7], v[30:31], v[12:13], v[6:7]
	v_pk_fma_f32 v[4:5], v[28:29], v[32:33], v[4:5]
	v_pk_fma_f32 v[2:3], v[26:27], v[10:11], v[2:3]
	v_pk_fma_f32 v[0:1], v[24:25], v[14:15], v[0:1]
	v_mov_b32_e32 v11, v219
	v_mov_b32_e32 v12, v220
	v_mov_b32_e32 v13, v221
	v_lshlrev_b32_e32 v14, 16, v218
	v_and_b32_e32 v15, 0xffff0000, v218
	v_lshlrev_b32_e32 v10, 16, v11
	v_and_b32_e32 v11, 0xffff0000, v11
	v_lshlrev_b32_e32 v24, 16, v12
	v_and_b32_e32 v25, 0xffff0000, v12
	v_lshlrev_b32_e32 v12, 16, v13
	v_and_b32_e32 v13, 0xffff0000, v13
	v_pk_fma_f32 v[6:7], v[22:23], v[12:13], v[6:7]
	v_pk_fma_f32 v[4:5], v[20:21], v[24:25], v[4:5]
	v_pk_fma_f32 v[2:3], v[18:19], v[10:11], v[2:3]
	v_pk_fma_f32 v[0:1], v[16:17], v[14:15], v[0:1]
	v_lshl_add_u32 v10, v8, 8, v53
	ds_write_b128 v10, v[0:3] offset:36864
	ds_write_b128 v10, v[4:7] offset:36880
	v_cvt_pk_bf16_f32 v0, v0, v1
	v_cvt_pk_bf16_f32 v1, v2, v3
	v_cvt_pk_bf16_f32 v2, v4, v5
	v_mad_u64_u32 v[4:5], s[0:1], v8, s3, v[50:51]
	s_lshl_b32 s69, s2, 12
	v_readlane_b32 s0, v248, 24
	s_or_b32 s4, s69, s0
	v_readlane_b32 s16, v251, 4
	s_lshl_b64 s[2:3], s[4:5], 2
	v_readlane_b32 s26, v251, 14
	v_readlane_b32 s27, v251, 15
	s_add_u32 s0, s26, s2
	v_readlane_b32 s30, v251, 18
	s_addc_u32 s1, s27, s3
	v_and_b32_e32 v9, 63, v51
	v_cvt_pk_bf16_f32 v3, v6, v7
	v_ashrrev_i32_e32 v66, 6, v51
	v_readlane_b32 s31, v251, 19
	s_add_u32 s2, s30, s2
	ds_write_b128 v4, v[0:3]
	s_addc_u32 s3, s31, s3
	v_mul_u32_u24_e32 v1, 0x90, v9
	v_lshlrev_b32_e32 v2, 2, v66
	s_add_i32 s73, 0, 0x4800
	v_lshl_or_b32 v0, v66, 7, v9
	v_add3_u32 v1, v1, v2, s73
	s_mov_b32 s4, 0
	v_readlane_b32 s17, v251, 5
	v_readlane_b32 s18, v251, 6
	v_readlane_b32 s19, v251, 7
	v_readlane_b32 s20, v251, 8
	v_readlane_b32 s21, v251, 9
	v_readlane_b32 s22, v251, 10
	v_readlane_b32 s23, v251, 11
	v_readlane_b32 s24, v251, 12
	v_readlane_b32 s25, v251, 13
	v_readlane_b32 s28, v251, 16
	v_readlane_b32 s29, v251, 17

.LBB0_859:
	v_add_u32_e32 v67, v65, v64
	ds_read_b128 v[76:79], v65 offset:18432
	ds_read_b128 v[80:83], v67
	s_add_i32 s0, s0, 32
	s_cmp_lt_u32 s0, 48
	s_waitcnt lgkmcnt(0)
	v_mfma_f32_32x32x16_bf16 v[48:63], v[80:83], v[76:79], v[48:63]
	ds_read_b128 v[76:79], v65 offset:23040
	s_waitcnt lgkmcnt(0)
	v_mfma_f32_32x32x16_bf16 v[16:31], v[80:83], v[76:79], v[16:31]
	ds_read_b128 v[76:79], v65 offset:27648
	s_waitcnt lgkmcnt(0)
	v_mfma_f32_32x32x16_bf16 v[32:47], v[80:83], v[76:79], v[32:47]
	ds_read_b128 v[76:79], v65 offset:32256
	ds_read_b128 v[84:87], v65 offset:18464
	s_waitcnt lgkmcnt(1)
	v_mfma_f32_32x32x16_bf16 v[0:15], v[80:83], v[76:79], v[0:15]
	ds_read_b128 v[76:79], v67 offset:32
	ds_read_b128 v[80:83], v65 offset:23072
	s_waitcnt lgkmcnt(0)
	v_mfma_f32_32x32x16_bf16 v[16:31], v[76:79], v[80:83], v[16:31]
	ds_read_b128 v[80:83], v65 offset:27680
	s_waitcnt lgkmcnt(0)
	v_mfma_f32_32x32x16_bf16 v[32:47], v[76:79], v[80:83], v[32:47]
	ds_read_b128 v[80:83], v65 offset:32288
	v_add_u32_e32 v65, 64, v65
	v_mfma_f32_32x32x16_bf16 v[48:63], v[76:79], v[84:87], v[48:63]
	s_waitcnt lgkmcnt(0)
	v_mfma_f32_32x32x16_bf16 v[0:15], v[76:79], v[80:83], v[0:15]
	s_cbranch_scc1 .LBB0_859
	v_and_b32_e32 v141, 63, v72
	v_or_b32_e32 v140, s13, v141
	v_readlane_b32 s0, v249, 15
	v_lshlrev_b32_e32 v96, 3, v140
	v_readlane_b32 s1, v249, 16
	v_readlane_b32 s16, v251, 20
	v_lshlrev_b32_e32 v69, 11, v66
	v_lshl_add_u64 v[64:65], s[0:1], 0, v[96:97]
	v_readlane_b32 s0, v248, 25
	s_or_b32 s3, s13, s0
	v_or_b32_e32 v96, s3, v74
	v_lshlrev_b64 v[66:67], 2, v[96:97]
	v_readlane_b32 s18, v251, 22
	v_readlane_b32 s19, v251, 23
	s_barrier
	s_nop 0
	v_lshl_add_u64 v[70:71], s[18:19], 0, v[66:67]
	v_readlane_b32 s100, v251, 16
	v_readlane_b32 s101, v251, 17
	s_nop 1
	v_lshl_add_u64 v[220:221], s[100:101], 0, v[66:67]
	v_readlane_b32 s100, v251, 20
	v_readlane_b32 s101, v251, 21
	s_nop 1
	v_lshl_add_u64 v[222:223], s[100:101], 0, v[66:67]
	global_load_dword v224, v[220:221], off
	global_load_dword v225, v[222:223], off
	global_load_dword v226, v[70:71], off offset:128
	global_load_dword v227, v[222:223], off offset:128
	global_load_dword v228, v[220:221], off offset:128
	global_load_dword v70, v[70:71], off
	s_mov_b32 s4, 0x3f2aaaab
	s_mov_b32 s8, 0x3f317218
	v_readlane_b32 s40, v251, 4
	v_readlane_b32 s52, v251, 16
	v_readlane_b32 s53, v251, 17
	v_readlane_b32 s17, v251, 21
	s_mov_b32 s9, 0x7f800000
	s_mov_b32 s10, 0x33800000
	v_readlane_b32 s20, v251, 24
	s_mov_b32 s20, 0x43000000
	v_readlane_b32 s21, v251, 25
	s_mov_b32 s21, 0x42b17217
	v_readlane_b32 s22, v251, 26
	s_mov_b32 s22, 0xf800000
	v_readlane_b32 s23, v251, 27
	s_mov_b32 s23, 0xc1880000
	v_add_u32_e32 v96, s3, v74
	s_mov_b32 s2, 0
	s_cmp_eq_u32 s12, 0
	v_readlane_b32 s24, v251, 28
	v_readlane_b32 s25, v251, 29
	v_readlane_b32 s26, v251, 30
	v_readlane_b32 s27, v251, 31
	v_readlane_b32 s28, v251, 32
	v_readlane_b32 s29, v251, 33
	v_readlane_b32 s30, v251, 34
	v_readlane_b32 s31, v251, 35
	v_readlane_b32 s41, v251, 5
	v_readlane_b32 s42, v251, 6
	v_readlane_b32 s43, v251, 7
	v_readlane_b32 s44, v251, 8
	v_readlane_b32 s45, v251, 9
	v_readlane_b32 s46, v251, 10
	v_readlane_b32 s47, v251, 11
	v_readlane_b32 s48, v251, 12
	v_readlane_b32 s49, v251, 13
	v_readlane_b32 s50, v251, 14
	v_readlane_b32 s51, v251, 15
	v_readlane_b32 s54, v251, 18
	v_readlane_b32 s55, v251, 19
	s_waitcnt vmcnt(0)
	v_mul_f32_e32 v70, 0xbfb8aa3b, v70
	v_exp_f32_e32 v73, v70
	s_nop 0
	v_add_f32_e32 v75, 1.0, v73
	v_add_f32_e32 v70, -1.0, v75
	v_sub_f32_e32 v71, v70, v75
	v_add_f32_e32 v71, 1.0, v71
	v_sub_f32_e32 v70, v73, v70
	v_add_f32_e32 v76, v70, v71
	v_frexp_mant_f32_e32 v70, v75
	v_cmp_gt_f32_e32 vcc, s4, v70
	v_cvt_f64_f32_e32 v[70:71], v75
	v_frexp_exp_i32_f64_e32 v70, v[70:71]
	v_subbrev_co_u32_e32 v82, vcc, 0, v70, vcc
	v_sub_u32_e32 v70, 0, v82
	v_ldexp_f32 v71, v75, v70
	v_add_f32_e32 v75, -1.0, v71
	v_add_f32_e32 v77, 1.0, v71
	v_ldexp_f32 v70, v76, v70
	v_add_f32_e32 v76, 1.0, v75
	v_add_f32_e32 v78, -1.0, v77
	v_sub_f32_e32 v76, v71, v76
	v_sub_f32_e32 v71, v71, v78
	v_add_f32_e32 v76, v70, v76
	v_add_f32_e32 v70, v70, v71
	v_add_f32_e32 v83, v77, v70
	v_rcp_f32_e32 v85, v83
	v_sub_f32_e32 v71, v83, v77
	v_sub_f32_e32 v84, v70, v71
	v_add_f32_e32 v71, v75, v76
	v_sub_f32_e32 v70, v71, v75
	v_mul_f32_e32 v86, v71, v85
	v_sub_f32_e32 v75, v76, v70
	v_mul_f32_e32 v76, v83, v86
	v_fma_f32 v78, v86, v83, -v76
	v_fmac_f32_e32 v78, v86, v84
	v_add_f32_e32 v70, v76, v78
	v_sub_f32_e32 v77, v71, v70
	v_pk_add_f32 v[80:81], v[70:71], v[76:77] neg_lo:[0,1] neg_hi:[0,1]
	v_mov_b32_e32 v79, v70
	v_pk_add_f32 v[70:71], v[80:81], v[78:79] neg_lo:[0,1] neg_hi:[0,1]
	v_cmp_neq_f32_e32 vcc, s9, v73
	v_add_f32_e32 v71, v75, v71
	v_add_f32_e32 v70, v70, v71
	v_add_f32_e32 v71, v77, v70
	v_mul_f32_e32 v75, v85, v71
	v_mul_f32_e32 v76, v83, v75
	v_fma_f32 v78, v75, v83, -v76
	v_fmac_f32_e32 v78, v75, v84
	v_sub_f32_e32 v77, v77, v71
	v_add_f32_e32 v83, v70, v77
	v_add_f32_e32 v70, v76, v78
	v_sub_f32_e32 v77, v71, v70
	v_pk_add_f32 v[80:81], v[70:71], v[76:77] neg_lo:[0,1] neg_hi:[0,1]
	v_mov_b32_e32 v79, v70
	v_pk_add_f32 v[70:71], v[80:81], v[78:79] neg_lo:[0,1] neg_hi:[0,1]
	v_add_f32_e32 v71, v83, v71
	v_add_f32_e32 v70, v70, v71
	v_add_f32_e32 v71, v86, v75
	v_add_f32_e32 v70, v77, v70
	v_sub_f32_e32 v76, v71, v86
	v_mul_f32_e32 v70, v85, v70
	v_sub_f32_e32 v75, v75, v76
	v_add_f32_e32 v75, v75, v70
	v_add_f32_e32 v76, v71, v75
	v_mul_f32_e32 v78, v76, v76
	v_fmamk_f32 v70, v78, 0x3e9b6dac, v191
	v_fmaak_f32 v169, v78, v70, 0x3f2aaada
	v_cvt_f32_i32_e32 v70, v82
	v_sub_f32_e32 v71, v76, v71
	v_sub_f32_e32 v71, v75, v71
	v_ldexp_f32 v75, v71, 1
	v_mul_f32_e32 v71, v76, v78
	v_pk_mul_f32 v[78:79], v[70:71], v[168:169]
	v_ldexp_f32 v77, v76, 1
	v_fma_f32 v76, v70, s8, -v78
	v_fmac_f32_e32 v76, 0xb102e308, v70
	v_pk_add_f32 v[70:71], v[78:79], v[76:77]
	v_mov_b32_e32 v80, v78
	v_sub_f32_e32 v77, v71, v77
	v_sub_f32_e32 v77, v79, v77
	v_add_f32_e32 v81, v75, v77
	v_pk_add_f32 v[78:79], v[70:71], v[78:79] neg_lo:[0,1] neg_hi:[0,1]
	v_pk_add_f32 v[82:83], v[70:71], v[80:81]
	v_mov_b32_e32 v77, v70
	v_mov_b32_e32 v79, v83
	v_pk_add_f32 v[84:85], v[76:77], v[78:79] neg_lo:[0,1] neg_hi:[0,1]
	v_pk_add_f32 v[76:77], v[76:77], v[78:79]
	v_mov_b32_e32 v80, v81
	v_pk_add_f32 v[78:79], v[76:77], v[70:71] op_sel:[1,0] op_sel_hi:[0,1] neg_lo:[0,1] neg_hi:[0,1]
	v_pk_add_f32 v[86:87], v[82:83], v[78:79] op_sel_hi:[1,0] neg_lo:[0,1] neg_hi:[0,1]
	v_mov_b32_e32 v82, v83
	v_mov_b32_e32 v83, v77
	v_pk_mov_b32 v[78:79], v[70:71], v[78:79] op_sel:[1,0]
	v_mov_b32_e32 v81, v70
	v_pk_add_f32 v[78:79], v[82:83], v[78:79] neg_lo:[0,1] neg_hi:[0,1]
	v_mov_b32_e32 v86, v84
	v_pk_add_f32 v[70:71], v[80:81], v[78:79] neg_lo:[0,1] neg_hi:[0,1]
	v_mov_b32_e32 v85, v77
	v_pk_add_f32 v[78:79], v[86:87], v[70:71]
	v_pk_add_f32 v[80:81], v[78:79], v[78:79] op_sel:[0,1] op_sel_hi:[1,0]
	v_pk_add_f32 v[76:77], v[76:77], v[80:81] op_sel:[1,0] op_sel_hi:[0,1]
	v_mov_b32_e32 v79, v76
	v_pk_add_f32 v[82:83], v[78:79], v[84:85] neg_lo:[0,1] neg_hi:[0,1]
	v_mov_b32_e32 v71, v80
	v_sub_f32_e32 v75, v78, v82
	v_pk_add_f32 v[70:71], v[70:71], v[82:83] neg_lo:[0,1] neg_hi:[0,1]
	v_sub_f32_e32 v75, v84, v75
	v_add_f32_e32 v70, v70, v75
	v_add_f32_e32 v70, v70, v71
	v_add_f32_e32 v70, v76, v70
	v_lshl_add_u64 v[76:77], s[52:53], 0, v[66:67]
	v_mov_b32_e32 v77, v224
	v_lshl_add_u64 v[66:67], s[16:17], 0, v[66:67]
	v_mov_b32_e32 v76, v225
	v_cndmask_b32_e32 v70, v199, v70, vcc
	v_cmp_ngt_f32_e32 vcc, -1.0, v73
	s_waitcnt vmcnt(1)
	v_add_f32_e32 v48, v48, v77
	v_mul_f32_e32 v48, 0xbfb8aa3b, v48
	v_exp_f32_e32 v48, v48
	v_cndmask_b32_e32 v70, v200, v70, vcc
	v_cmp_neq_f32_e32 vcc, -1.0, v73
	s_waitcnt vmcnt(0)
	v_add_f32_e32 v32, v32, v76
	v_add_f32_e32 v48, 1.0, v48
	v_rcp_f32_e32 v48, v48
	v_cndmask_b32_e32 v70, v201, v70, vcc
	v_cmp_lt_f32_e64 vcc, |v73|, s10
	v_mul_f32_e32 v32, 0xbfb8aa3b, v32
	v_exp_f32_e32 v32, v32
	v_cndmask_b32_e32 v70, v70, v73, vcc
	v_mul_f32_e32 v75, 0xc1000000, v70
	v_mul_f32_e32 v48, v48, v75
	v_mul_f32_e32 v66, 0x3fb8aa3b, v48
	v_add_f32_e32 v48, v48, v48
	v_exp_f32_e32 v70, v66
	v_mul_f32_e32 v66, 0x3fb8aa3b, v48
	v_rndne_f32_e32 v66, v66
	v_fmamk_f32 v67, v66, 0xbf317218, v48
	v_fmac_f32_e32 v67, 0x3102e308, v66
	v_fmamk_f32 v71, v67, 0x395133b1, v192
	v_cmp_eq_f32_e32 vcc, s20, v66
	v_cvt_i32_f32_e32 v66, v66
	v_fmaak_f32 v71, v67, v71, 0x3c0887f9
	v_fmaak_f32 v71, v67, v71, 0x3d2aaa81
	v_fmaak_f32 v71, v67, v71, 0x3e2aaaab
	v_fma_f32 v71, v67, v71, 0.5
	v_ldexp_f32 v66, 1.0, v66
	v_mul_f32_e32 v71, v67, v71
	v_cndmask_b32_e32 v66, v66, v202, vcc
	v_fmac_f32_e32 v67, v67, v71
	v_add_f32_e32 v71, -1.0, v66
	v_fmac_f32_e32 v71, v66, v67
	v_add_f32_e32 v66, v71, v71
	v_cndmask_b32_e32 v66, v71, v66, vcc
	v_cmp_nlt_f32_e32 vcc, s21, v48
	v_add_f32_e32 v32, 1.0, v32
	v_rcp_f32_e32 v32, v32
	v_cndmask_b32_e64 v66, v201, -v66, vcc
	v_cmp_gt_f32_e32 vcc, s22, v66
	v_mul_f32_e32 v67, 0x4f800000, v66
	v_add_f32_e32 v33, v33, v76
	v_cndmask_b32_e32 v66, v66, v67, vcc
	v_sqrt_f32_e32 v67, v66
	v_mul_f32_e32 v33, 0xbfb8aa3b, v33
	v_exp_f32_e32 v33, v33
	v_add_f32_e32 v34, v34, v76
	v_add_u32_e32 v71, -1, v67
	v_fma_f32 v73, -v71, v67, v66
	v_cmp_ge_f32_e64 s[0:1], 0, v73
	v_add_u32_e32 v73, 1, v67
	v_add_f32_e32 v33, 1.0, v33
	v_cndmask_b32_e64 v71, v67, v71, s[0:1]
	v_fma_f32 v67, -v73, v67, v66
	v_cmp_lt_f32_e64 s[0:1], 0, v67
	v_rcp_f32_e32 v33, v33
	v_mul_f32_e32 v34, 0xbfb8aa3b, v34
	v_cndmask_b32_e64 v67, v71, v73, s[0:1]
	v_mul_f32_e32 v71, 0x37800000, v67
	v_cndmask_b32_e32 v67, v67, v71, vcc
	v_cmp_class_f32_e32 vcc, v66, v193
	v_exp_f32_e32 v34, v34
	s_nop 0
	v_cndmask_b32_e32 v66, v67, v66, vcc
	v_cmp_ngt_f32_e32 vcc, s23, v48
	v_add_f32_e32 v34, 1.0, v34
	v_rcp_f32_e32 v34, v34
	v_cndmask_b32_e32 v48, 1.0, v66, vcc
	v_mul_f32_e32 v48, v32, v48
	v_and_b32_e32 v32, 0x100, v68
	v_or3_b32 v32, v69, v74, v32
	v_lshl_add_u32 v73, v32, 2, 0
	v_add_u32_e32 v32, 0x9000, v73
	ds_read2_b32 v[66:67], v32 offset1:32
	s_waitcnt lgkmcnt(0)
	v_mul_f32_e32 v48, v66, v48
	ds_write_b32 v73, v70
	ds_write_b32 v73, v48 offset:36864
	v_add_f32_e32 v48, v49, v77
	v_mul_f32_e32 v48, 0xbfb8aa3b, v48
	v_exp_f32_e32 v48, v48
	s_nop 0
	v_add_f32_e32 v48, 1.0, v48
	v_rcp_f32_e32 v48, v48
	s_nop 0
	v_mul_f32_e32 v48, v48, v75
	v_mul_f32_e32 v49, 0x3fb8aa3b, v48
	v_add_f32_e32 v48, v48, v48
	v_exp_f32_e32 v66, v49
	v_mul_f32_e32 v49, 0x3fb8aa3b, v48
	v_rndne_f32_e32 v49, v49
	v_fmamk_f32 v68, v49, 0xbf317218, v48
	v_fmac_f32_e32 v68, 0x3102e308, v49
	v_fmamk_f32 v69, v68, 0x395133b1, v192
	v_cmp_eq_f32_e32 vcc, s20, v49
	v_cvt_i32_f32_e32 v49, v49
	v_fmaak_f32 v69, v68, v69, 0x3c0887f9
	v_fmaak_f32 v69, v68, v69, 0x3d2aaa81
	v_fmaak_f32 v69, v68, v69, 0x3e2aaaab
	v_fma_f32 v69, v68, v69, 0.5
	v_ldexp_f32 v49, 1.0, v49
	v_mul_f32_e32 v69, v68, v69
	v_cndmask_b32_e32 v49, v49, v202, vcc
	v_fmac_f32_e32 v68, v68, v69
	v_add_f32_e32 v69, -1.0, v49
	v_fmac_f32_e32 v69, v49, v68
	v_add_f32_e32 v49, v69, v69
	v_cndmask_b32_e32 v49, v69, v49, vcc
	v_cmp_nlt_f32_e32 vcc, s21, v48
	s_nop 1
	v_cndmask_b32_e64 v49, v201, -v49, vcc
	v_cmp_gt_f32_e32 vcc, s22, v49
	v_mul_f32_e32 v68, 0x4f800000, v49
	s_nop 0
	v_cndmask_b32_e32 v49, v49, v68, vcc
	v_sqrt_f32_e32 v68, v49
	s_nop 0
	v_add_u32_e32 v69, -1, v68
	v_fma_f32 v70, -v69, v68, v49
	v_cmp_ge_f32_e64 s[0:1], 0, v70
	v_add_u32_e32 v70, 1, v68
	s_nop 0
	v_cndmask_b32_e64 v69, v68, v69, s[0:1]
	v_fma_f32 v68, -v70, v68, v49
	v_cmp_lt_f32_e64 s[0:1], 0, v68
	s_nop 1
	v_cndmask_b32_e64 v68, v69, v70, s[0:1]
	v_mul_f32_e32 v69, 0x37800000, v68
	v_cndmask_b32_e32 v68, v68, v69, vcc
	v_cmp_class_f32_e32 vcc, v49, v193
	s_nop 1
	v_cndmask_b32_e32 v49, v68, v49, vcc
	v_cmp_ngt_f32_e32 vcc, s23, v48
	s_nop 1
	v_cndmask_b32_e32 v48, 1.0, v49, vcc
	v_mul_f32_e32 v33, v33, v48
	ds_read2_b32 v[48:49], v32 offset0:64 offset1:96
	s_waitcnt lgkmcnt(0)
	v_mul_f32_e32 v33, v48, v33
	ds_write_b32 v73, v66 offset:256
	ds_write_b32 v73, v33 offset:37120
	v_add_f32_e32 v33, v50, v77
	v_mul_f32_e32 v33, 0xbfb8aa3b, v33
	v_exp_f32_e32 v33, v33
	s_nop 0
	v_add_f32_e32 v33, 1.0, v33
	v_rcp_f32_e32 v33, v33
	s_nop 0
	v_mul_f32_e32 v33, v33, v75
	v_mul_f32_e32 v48, 0x3fb8aa3b, v33
	v_add_f32_e32 v33, v33, v33
	v_mul_f32_e32 v50, 0x3fb8aa3b, v33
	v_rndne_f32_e32 v50, v50
	v_fmamk_f32 v66, v50, 0xbf317218, v33
	v_fmac_f32_e32 v66, 0x3102e308, v50
	v_fmamk_f32 v68, v66, 0x395133b1, v192
	v_cmp_eq_f32_e32 vcc, s20, v50
	v_cvt_i32_f32_e32 v50, v50
	v_fmaak_f32 v68, v66, v68, 0x3c0887f9
	v_fmaak_f32 v68, v66, v68, 0x3d2aaa81
	v_fmaak_f32 v68, v66, v68, 0x3e2aaaab
	v_fma_f32 v68, v66, v68, 0.5
	v_ldexp_f32 v50, 1.0, v50
	v_mul_f32_e32 v68, v66, v68
	v_cndmask_b32_e32 v50, v50, v202, vcc
	v_fmac_f32_e32 v66, v66, v68
	v_add_f32_e32 v68, -1.0, v50
	v_fmac_f32_e32 v68, v50, v66
	v_add_f32_e32 v50, v68, v68
	v_cndmask_b32_e32 v50, v68, v50, vcc
	v_cmp_nlt_f32_e32 vcc, s21, v33
	v_exp_f32_e32 v48, v48
	s_nop 0
	v_cndmask_b32_e64 v50, v201, -v50, vcc
	v_cmp_gt_f32_e32 vcc, s22, v50
	v_mul_f32_e32 v66, 0x4f800000, v50
	s_nop 0
	v_cndmask_b32_e32 v50, v50, v66, vcc
	v_sqrt_f32_e32 v66, v50
	s_nop 0
	v_add_u32_e32 v68, -1, v66
	v_fma_f32 v69, -v68, v66, v50
	v_cmp_ge_f32_e64 s[0:1], 0, v69
	v_add_u32_e32 v69, 1, v66
	s_nop 0
	v_cndmask_b32_e64 v68, v66, v68, s[0:1]
	v_fma_f32 v66, -v69, v66, v50
	v_cmp_lt_f32_e64 s[0:1], 0, v66
	s_nop 1
	v_cndmask_b32_e64 v66, v68, v69, s[0:1]
	v_mul_f32_e32 v68, 0x37800000, v66
	v_cndmask_b32_e32 v66, v66, v68, vcc
	ds_read2_b32 v[68:69], v32 offset0:128 offset1:160
	v_cmp_class_f32_e32 vcc, v50, v193
	s_nop 1
	v_cndmask_b32_e32 v50, v66, v50, vcc
	v_cmp_ngt_f32_e32 vcc, s23, v33
	s_nop 1
	v_cndmask_b32_e32 v33, 1.0, v50, vcc
	v_mul_f32_e32 v33, v34, v33
	s_waitcnt lgkmcnt(0)
	v_mul_f32_e32 v33, v68, v33
	ds_write_b32 v73, v48 offset:512
	ds_write_b32 v73, v33 offset:37376
	v_add_f32_e32 v33, v51, v77
	v_mul_f32_e32 v33, 0xbfb8aa3b, v33
	v_exp_f32_e32 v33, v33
	v_add_f32_e32 v34, v35, v76
	v_mul_f32_e32 v34, 0xbfb8aa3b, v34
	v_exp_f32_e32 v34, v34
	v_add_f32_e32 v33, 1.0, v33
	v_rcp_f32_e32 v33, v33
	v_add_f32_e32 v34, 1.0, v34
	v_rcp_f32_e32 v34, v34
	v_mul_f32_e32 v33, v33, v75
	v_mul_f32_e32 v35, 0x3fb8aa3b, v33
	v_add_f32_e32 v33, v33, v33
	v_mul_f32_e32 v48, 0x3fb8aa3b, v33
	v_rndne_f32_e32 v48, v48
	v_fmamk_f32 v50, v48, 0xbf317218, v33
	v_fmac_f32_e32 v50, 0x3102e308, v48
	v_fmamk_f32 v51, v50, 0x395133b1, v192
	v_cmp_eq_f32_e32 vcc, s20, v48
	v_cvt_i32_f32_e32 v48, v48
	v_fmaak_f32 v51, v50, v51, 0x3c0887f9
	v_fmaak_f32 v51, v50, v51, 0x3d2aaa81
	v_fmaak_f32 v51, v50, v51, 0x3e2aaaab
	v_fma_f32 v51, v50, v51, 0.5
	v_ldexp_f32 v48, 1.0, v48
	v_mul_f32_e32 v51, v50, v51
	v_cndmask_b32_e32 v48, v48, v202, vcc
	v_fmac_f32_e32 v50, v50, v51
	v_add_f32_e32 v51, -1.0, v48
	v_fmac_f32_e32 v51, v48, v50
	v_add_f32_e32 v48, v51, v51
	v_cndmask_b32_e32 v48, v51, v48, vcc
	v_cmp_nlt_f32_e32 vcc, s21, v33
	v_exp_f32_e32 v35, v35
	s_nop 0
	v_cndmask_b32_e64 v48, v201, -v48, vcc
	v_cmp_gt_f32_e32 vcc, s22, v48
	v_mul_f32_e32 v50, 0x4f800000, v48
	s_nop 0
	v_cndmask_b32_e32 v48, v48, v50, vcc
	v_sqrt_f32_e32 v50, v48
	s_nop 0
	v_add_u32_e32 v51, -1, v50
	v_fma_f32 v66, -v51, v50, v48
	v_cmp_ge_f32_e64 s[0:1], 0, v66
	v_add_u32_e32 v66, 1, v50
	s_nop 0
	v_cndmask_b32_e64 v51, v50, v51, s[0:1]
	v_fma_f32 v50, -v66, v50, v48
	v_cmp_lt_f32_e64 s[0:1], 0, v50
	s_nop 1
	v_cndmask_b32_e64 v50, v51, v66, s[0:1]
	v_mul_f32_e32 v51, 0x37800000, v50
	v_cndmask_b32_e32 v50, v50, v51, vcc
	v_cmp_class_f32_e32 vcc, v48, v193
	s_nop 1
	v_cndmask_b32_e32 v48, v50, v48, vcc
	ds_read2_b32 v[50:51], v32 offset0:192 offset1:224
	v_cmp_ngt_f32_e32 vcc, s23, v33
	s_nop 1
	v_cndmask_b32_e32 v33, 1.0, v48, vcc
	v_mul_f32_e32 v33, v34, v33
	s_waitcnt lgkmcnt(0)
	v_mul_f32_e32 v32, v50, v33
	ds_write_b32 v73, v35 offset:768
	ds_write_b32 v73, v32 offset:37632
	v_add_f32_e32 v32, v52, v77
	v_mul_f32_e32 v32, 0xbfb8aa3b, v32
	v_exp_f32_e32 v32, v32
	v_add_f32_e32 v33, v36, v76
	v_mul_f32_e32 v33, 0xbfb8aa3b, v33
	v_exp_f32_e32 v33, v33
	v_add_f32_e32 v32, 1.0, v32
	v_rcp_f32_e32 v32, v32
	v_add_f32_e32 v33, 1.0, v33
	v_rcp_f32_e32 v33, v33
	v_mul_f32_e32 v32, v32, v75
	v_mul_f32_e32 v34, 0x3fb8aa3b, v32
	v_add_f32_e32 v32, v32, v32
	v_mul_f32_e32 v35, 0x3fb8aa3b, v32
	v_rndne_f32_e32 v35, v35
	v_fmamk_f32 v36, v35, 0xbf317218, v32
	v_fmac_f32_e32 v36, 0x3102e308, v35
	v_fmamk_f32 v48, v36, 0x395133b1, v192
	v_cmp_eq_f32_e32 vcc, s20, v35
	v_cvt_i32_f32_e32 v35, v35
	v_fmaak_f32 v48, v36, v48, 0x3c0887f9
	v_fmaak_f32 v48, v36, v48, 0x3d2aaa81
	v_fmaak_f32 v48, v36, v48, 0x3e2aaaab
	v_fma_f32 v48, v36, v48, 0.5
	v_ldexp_f32 v35, 1.0, v35
	v_mul_f32_e32 v48, v36, v48
	v_cndmask_b32_e32 v35, v35, v202, vcc
	v_fmac_f32_e32 v36, v36, v48
	v_add_f32_e32 v48, -1.0, v35
	v_fmac_f32_e32 v48, v35, v36
	v_add_f32_e32 v35, v48, v48
	v_cndmask_b32_e32 v35, v48, v35, vcc
	v_cmp_nlt_f32_e32 vcc, s21, v32
	v_exp_f32_e32 v34, v34
	s_nop 0
	v_cndmask_b32_e64 v35, v201, -v35, vcc
	v_cmp_gt_f32_e32 vcc, s22, v35
	v_mul_f32_e32 v36, 0x4f800000, v35
	s_nop 0
	v_cndmask_b32_e32 v35, v35, v36, vcc
	v_sqrt_f32_e32 v36, v35
	s_nop 0
	v_add_u32_e32 v48, -1, v36
	v_fma_f32 v50, -v48, v36, v35
	v_cmp_ge_f32_e64 s[0:1], 0, v50
	v_add_u32_e32 v50, 1, v36
	s_nop 0
	v_cndmask_b32_e64 v48, v36, v48, s[0:1]
	v_fma_f32 v36, -v50, v36, v35
	v_cmp_lt_f32_e64 s[0:1], 0, v36
	s_nop 1
	v_cndmask_b32_e64 v36, v48, v50, s[0:1]
	v_mul_f32_e32 v48, 0x37800000, v36
	v_cndmask_b32_e32 v36, v36, v48, vcc
	v_cmp_class_f32_e32 vcc, v35, v193
	s_nop 1
	v_cndmask_b32_e32 v35, v36, v35, vcc
	v_cmp_ngt_f32_e32 vcc, s23, v32
	s_nop 1
	v_cndmask_b32_e32 v32, 1.0, v35, vcc
	v_mul_f32_e32 v33, v33, v32
	v_add_u32_e32 v32, 0x9800, v73
	ds_read2_b32 v[70:71], v32 offset1:32
	s_waitcnt lgkmcnt(0)
	v_mul_f32_e32 v33, v70, v33
	ds_write_b32 v73, v34 offset:2048
	ds_write_b32 v73, v33 offset:38912
	v_add_f32_e32 v33, v53, v77
	v_mul_f32_e32 v33, 0xbfb8aa3b, v33
	v_exp_f32_e32 v33, v33
	v_add_f32_e32 v34, v37, v76
	v_mul_f32_e32 v34, 0xbfb8aa3b, v34
	v_exp_f32_e32 v34, v34
	v_add_f32_e32 v33, 1.0, v33
	v_rcp_f32_e32 v33, v33
	v_add_f32_e32 v34, 1.0, v34
	v_rcp_f32_e32 v34, v34
	v_mul_f32_e32 v33, v33, v75
	v_mul_f32_e32 v35, 0x3fb8aa3b, v33
	v_add_f32_e32 v33, v33, v33
	v_mul_f32_e32 v36, 0x3fb8aa3b, v33
	v_rndne_f32_e32 v36, v36
	v_fmamk_f32 v37, v36, 0xbf317218, v33
	v_fmac_f32_e32 v37, 0x3102e308, v36
	v_fmamk_f32 v48, v37, 0x395133b1, v192
	v_cmp_eq_f32_e32 vcc, s20, v36
	v_cvt_i32_f32_e32 v36, v36
	v_fmaak_f32 v48, v37, v48, 0x3c0887f9
	v_fmaak_f32 v48, v37, v48, 0x3d2aaa81
	v_fmaak_f32 v48, v37, v48, 0x3e2aaaab
	v_fma_f32 v48, v37, v48, 0.5
	v_ldexp_f32 v36, 1.0, v36
	v_mul_f32_e32 v48, v37, v48
	v_cndmask_b32_e32 v36, v36, v202, vcc
	v_fmac_f32_e32 v37, v37, v48
	v_add_f32_e32 v48, -1.0, v36
	v_fmac_f32_e32 v48, v36, v37
	v_add_f32_e32 v36, v48, v48
	v_cndmask_b32_e32 v36, v48, v36, vcc
	v_cmp_nlt_f32_e32 vcc, s21, v33
	v_exp_f32_e32 v35, v35
	s_nop 0
	v_cndmask_b32_e64 v36, v201, -v36, vcc
	v_cmp_gt_f32_e32 vcc, s22, v36
	v_mul_f32_e32 v37, 0x4f800000, v36
	s_nop 0
	v_cndmask_b32_e32 v36, v36, v37, vcc
	v_sqrt_f32_e32 v37, v36
	s_nop 0
	v_add_u32_e32 v48, -1, v37
	v_fma_f32 v50, -v48, v37, v36
	v_cmp_ge_f32_e64 s[0:1], 0, v50
	v_add_u32_e32 v50, 1, v37
	s_nop 0
	v_cndmask_b32_e64 v48, v37, v48, s[0:1]
	v_fma_f32 v37, -v50, v37, v36
	v_cmp_lt_f32_e64 s[0:1], 0, v37
	s_nop 1
	v_cndmask_b32_e64 v37, v48, v50, s[0:1]
	v_mul_f32_e32 v48, 0x37800000, v37
	v_cndmask_b32_e32 v37, v37, v48, vcc
	v_cmp_class_f32_e32 vcc, v36, v193
	s_nop 1
	v_cndmask_b32_e32 v36, v37, v36, vcc
	v_cmp_ngt_f32_e32 vcc, s23, v33
	s_nop 1
	v_cndmask_b32_e32 v33, 1.0, v36, vcc
	ds_read2_b32 v[36:37], v32 offset0:64 offset1:96
	v_mul_f32_e32 v33, v34, v33
	v_add_f32_e32 v34, v38, v76
	v_mul_f32_e32 v34, 0xbfb8aa3b, v34
	v_exp_f32_e32 v34, v34
	s_waitcnt lgkmcnt(0)
	v_mul_f32_e32 v33, v36, v33
	ds_write_b32 v73, v35 offset:2304
	ds_write_b32 v73, v33 offset:39168
	v_add_f32_e32 v33, v54, v77
	v_mul_f32_e32 v33, 0xbfb8aa3b, v33
	v_exp_f32_e32 v33, v33
	v_add_f32_e32 v34, 1.0, v34
	v_rcp_f32_e32 v34, v34
	ds_read2_b32 v[52:53], v32 offset0:128 offset1:160
	v_add_f32_e32 v33, 1.0, v33
	v_rcp_f32_e32 v33, v33
	s_nop 0
	v_mul_f32_e32 v33, v33, v75
	v_mul_f32_e32 v35, 0x3fb8aa3b, v33
	v_add_f32_e32 v33, v33, v33
	v_mul_f32_e32 v36, 0x3fb8aa3b, v33
	v_rndne_f32_e32 v36, v36
	v_fmamk_f32 v38, v36, 0xbf317218, v33
	v_fmac_f32_e32 v38, 0x3102e308, v36
	v_fmamk_f32 v48, v38, 0x395133b1, v192
	v_cmp_eq_f32_e32 vcc, s20, v36
	v_cvt_i32_f32_e32 v36, v36
	v_fmaak_f32 v48, v38, v48, 0x3c0887f9
	v_fmaak_f32 v48, v38, v48, 0x3d2aaa81
	v_fmaak_f32 v48, v38, v48, 0x3e2aaaab
	v_fma_f32 v48, v38, v48, 0.5
	v_ldexp_f32 v36, 1.0, v36
	v_mul_f32_e32 v48, v38, v48
	v_cndmask_b32_e32 v36, v36, v202, vcc
	v_fmac_f32_e32 v38, v38, v48
	v_add_f32_e32 v48, -1.0, v36
	v_fmac_f32_e32 v48, v36, v38
	v_add_f32_e32 v36, v48, v48
	v_cndmask_b32_e32 v36, v48, v36, vcc
	v_cmp_nlt_f32_e32 vcc, s21, v33
	v_exp_f32_e32 v35, v35
	s_nop 0
	v_cndmask_b32_e64 v36, v201, -v36, vcc
	v_cmp_gt_f32_e32 vcc, s22, v36
	v_mul_f32_e32 v38, 0x4f800000, v36
	s_nop 0
	v_cndmask_b32_e32 v36, v36, v38, vcc
	v_sqrt_f32_e32 v38, v36
	s_nop 0
	v_add_u32_e32 v48, -1, v38
	v_fma_f32 v50, -v48, v38, v36
	v_cmp_ge_f32_e64 s[0:1], 0, v50
	v_add_u32_e32 v50, 1, v38
	s_nop 0
	v_cndmask_b32_e64 v48, v38, v48, s[0:1]
	v_fma_f32 v38, -v50, v38, v36
	v_cmp_lt_f32_e64 s[0:1], 0, v38
	s_nop 1
	v_cndmask_b32_e64 v38, v48, v50, s[0:1]
	v_mul_f32_e32 v48, 0x37800000, v38
	v_cndmask_b32_e32 v38, v38, v48, vcc
	v_cmp_class_f32_e32 vcc, v36, v193
	s_nop 1
	v_cndmask_b32_e32 v36, v38, v36, vcc
	v_cmp_ngt_f32_e32 vcc, s23, v33
	s_nop 1
	v_cndmask_b32_e32 v33, 1.0, v36, vcc
	v_mul_f32_e32 v33, v34, v33
	s_waitcnt lgkmcnt(0)
	v_mul_f32_e32 v33, v52, v33
	ds_write_b32 v73, v35 offset:2560
	ds_write_b32 v73, v33 offset:39424
	v_add_f32_e32 v33, v55, v77
	v_mul_f32_e32 v33, 0xbfb8aa3b, v33
	v_exp_f32_e32 v33, v33
	v_add_f32_e32 v34, v39, v76
	v_mul_f32_e32 v34, 0xbfb8aa3b, v34
	v_exp_f32_e32 v34, v34
	v_add_f32_e32 v33, 1.0, v33
	v_rcp_f32_e32 v33, v33
	v_add_f32_e32 v34, 1.0, v34
	v_rcp_f32_e32 v34, v34
	v_mul_f32_e32 v33, v33, v75
	v_mul_f32_e32 v35, 0x3fb8aa3b, v33
	v_add_f32_e32 v33, v33, v33
	v_mul_f32_e32 v36, 0x3fb8aa3b, v33
	v_rndne_f32_e32 v36, v36
	v_fmamk_f32 v38, v36, 0xbf317218, v33
	v_fmac_f32_e32 v38, 0x3102e308, v36
	v_fmamk_f32 v39, v38, 0x395133b1, v192
	v_cmp_eq_f32_e32 vcc, s20, v36
	v_cvt_i32_f32_e32 v36, v36
	v_fmaak_f32 v39, v38, v39, 0x3c0887f9
	v_fmaak_f32 v39, v38, v39, 0x3d2aaa81
	v_fmaak_f32 v39, v38, v39, 0x3e2aaaab
	v_fma_f32 v39, v38, v39, 0.5
	v_ldexp_f32 v36, 1.0, v36
	v_mul_f32_e32 v39, v38, v39
	v_cndmask_b32_e32 v36, v36, v202, vcc
	v_fmac_f32_e32 v38, v38, v39
	v_add_f32_e32 v39, -1.0, v36
	v_fmac_f32_e32 v39, v36, v38
	v_add_f32_e32 v36, v39, v39
	v_cndmask_b32_e32 v36, v39, v36, vcc
	v_cmp_nlt_f32_e32 vcc, s21, v33
	v_exp_f32_e32 v35, v35
	s_nop 0
	v_cndmask_b32_e64 v36, v201, -v36, vcc
	v_cmp_gt_f32_e32 vcc, s22, v36
	v_mul_f32_e32 v38, 0x4f800000, v36
	s_nop 0
	v_cndmask_b32_e32 v36, v36, v38, vcc
	v_sqrt_f32_e32 v38, v36
	s_nop 0
	v_add_u32_e32 v39, -1, v38
	v_fma_f32 v48, -v39, v38, v36
	v_cmp_ge_f32_e64 s[0:1], 0, v48
	v_add_u32_e32 v48, 1, v38
	s_nop 0
	v_cndmask_b32_e64 v39, v38, v39, s[0:1]
	v_fma_f32 v38, -v48, v38, v36
	v_cmp_lt_f32_e64 s[0:1], 0, v38
	s_nop 1
	v_cndmask_b32_e64 v38, v39, v48, s[0:1]
	v_mul_f32_e32 v39, 0x37800000, v38
	v_cndmask_b32_e32 v38, v38, v39, vcc
	v_cmp_class_f32_e32 vcc, v36, v193
	s_nop 1
	v_cndmask_b32_e32 v36, v38, v36, vcc
	ds_read2_b32 v[38:39], v32 offset0:192 offset1:224
	v_cmp_ngt_f32_e32 vcc, s23, v33
	s_nop 1
	v_cndmask_b32_e32 v33, 1.0, v36, vcc
	v_mul_f32_e32 v33, v34, v33
	s_waitcnt lgkmcnt(0)
	v_mul_f32_e32 v32, v38, v33
	ds_write_b32 v73, v35 offset:2816
	ds_write_b32 v73, v32 offset:39680
	v_add_f32_e32 v32, v56, v77
	v_mul_f32_e32 v32, 0xbfb8aa3b, v32
	v_exp_f32_e32 v32, v32
	v_add_f32_e32 v33, v40, v76
	v_mul_f32_e32 v33, 0xbfb8aa3b, v33
	v_exp_f32_e32 v33, v33
	v_add_f32_e32 v32, 1.0, v32
	v_rcp_f32_e32 v32, v32
	v_add_f32_e32 v33, 1.0, v33
	v_rcp_f32_e32 v33, v33
	v_mul_f32_e32 v32, v32, v75
	v_mul_f32_e32 v34, 0x3fb8aa3b, v32
	v_add_f32_e32 v32, v32, v32
	v_mul_f32_e32 v35, 0x3fb8aa3b, v32
	v_rndne_f32_e32 v35, v35
	v_fmamk_f32 v36, v35, 0xbf317218, v32
	v_fmac_f32_e32 v36, 0x3102e308, v35
	v_fmamk_f32 v38, v36, 0x395133b1, v192
	v_cmp_eq_f32_e32 vcc, s20, v35
	v_cvt_i32_f32_e32 v35, v35
	v_fmaak_f32 v38, v36, v38, 0x3c0887f9
	v_fmaak_f32 v38, v36, v38, 0x3d2aaa81
	v_fmaak_f32 v38, v36, v38, 0x3e2aaaab
	v_fma_f32 v38, v36, v38, 0.5
	v_ldexp_f32 v35, 1.0, v35
	v_mul_f32_e32 v38, v36, v38
	v_cndmask_b32_e32 v35, v35, v202, vcc
	v_fmac_f32_e32 v36, v36, v38
	v_add_f32_e32 v38, -1.0, v35
	v_fmac_f32_e32 v38, v35, v36
	v_add_f32_e32 v35, v38, v38
	v_cndmask_b32_e32 v35, v38, v35, vcc
	v_cmp_nlt_f32_e32 vcc, s21, v32
	v_exp_f32_e32 v34, v34
	s_nop 0
	v_cndmask_b32_e64 v35, v201, -v35, vcc
	v_cmp_gt_f32_e32 vcc, s22, v35
	v_mul_f32_e32 v36, 0x4f800000, v35
	s_nop 0
	v_cndmask_b32_e32 v35, v35, v36, vcc
	v_sqrt_f32_e32 v36, v35
	s_nop 0
	v_add_u32_e32 v38, -1, v36
	v_fma_f32 v40, -v38, v36, v35
	v_cmp_ge_f32_e64 s[0:1], 0, v40
	v_add_u32_e32 v40, 1, v36
	s_nop 0
	v_cndmask_b32_e64 v38, v36, v38, s[0:1]
	v_fma_f32 v36, -v40, v36, v35
	v_cmp_lt_f32_e64 s[0:1], 0, v36
	s_nop 1
	v_cndmask_b32_e64 v36, v38, v40, s[0:1]
	v_mul_f32_e32 v38, 0x37800000, v36
	v_cndmask_b32_e32 v36, v36, v38, vcc
	v_cmp_class_f32_e32 vcc, v35, v193
	s_nop 1
	v_cndmask_b32_e32 v35, v36, v35, vcc
	v_cmp_ngt_f32_e32 vcc, s23, v32
	s_nop 1
	v_cndmask_b32_e32 v32, 1.0, v35, vcc
	v_mul_f32_e32 v33, v33, v32
	v_add_u32_e32 v32, 0xa000, v73
	ds_read2_b32 v[54:55], v32 offset1:32
	s_waitcnt lgkmcnt(0)
	v_mul_f32_e32 v33, v54, v33
	ds_write_b32 v73, v34 offset:4096
	ds_write_b32 v73, v33 offset:40960
	v_add_f32_e32 v33, v57, v77
	v_mul_f32_e32 v33, 0xbfb8aa3b, v33
	v_exp_f32_e32 v33, v33
	v_add_f32_e32 v34, v41, v76
	v_mul_f32_e32 v34, 0xbfb8aa3b, v34
	v_exp_f32_e32 v34, v34
	v_add_f32_e32 v33, 1.0, v33
	v_rcp_f32_e32 v33, v33
	v_add_f32_e32 v34, 1.0, v34
	v_rcp_f32_e32 v34, v34
	v_mul_f32_e32 v33, v33, v75
	v_mul_f32_e32 v35, 0x3fb8aa3b, v33
	v_add_f32_e32 v33, v33, v33
	v_mul_f32_e32 v36, 0x3fb8aa3b, v33
	v_rndne_f32_e32 v36, v36
	v_fmamk_f32 v38, v36, 0xbf317218, v33
	v_fmac_f32_e32 v38, 0x3102e308, v36
	v_fmamk_f32 v40, v38, 0x395133b1, v192
	v_cmp_eq_f32_e32 vcc, s20, v36
	v_cvt_i32_f32_e32 v36, v36
	v_fmaak_f32 v40, v38, v40, 0x3c0887f9
	v_fmaak_f32 v40, v38, v40, 0x3d2aaa81
	v_fmaak_f32 v40, v38, v40, 0x3e2aaaab
	v_fma_f32 v40, v38, v40, 0.5
	v_ldexp_f32 v36, 1.0, v36
	v_mul_f32_e32 v40, v38, v40
	v_cndmask_b32_e32 v36, v36, v202, vcc
	v_fmac_f32_e32 v38, v38, v40
	v_add_f32_e32 v40, -1.0, v36
	v_fmac_f32_e32 v40, v36, v38
	v_add_f32_e32 v36, v40, v40
	v_cndmask_b32_e32 v36, v40, v36, vcc
	v_cmp_nlt_f32_e32 vcc, s21, v33
	v_exp_f32_e32 v35, v35
	s_nop 0
	v_cndmask_b32_e64 v36, v201, -v36, vcc
	v_cmp_gt_f32_e32 vcc, s22, v36
	v_mul_f32_e32 v38, 0x4f800000, v36
	s_nop 0
	v_cndmask_b32_e32 v36, v36, v38, vcc
	v_sqrt_f32_e32 v38, v36
	s_nop 0
	v_add_u32_e32 v40, -1, v38
	v_fma_f32 v41, -v40, v38, v36
	v_cmp_ge_f32_e64 s[0:1], 0, v41
	v_add_u32_e32 v41, 1, v38
	s_nop 0
	v_cndmask_b32_e64 v40, v38, v40, s[0:1]
	v_fma_f32 v38, -v41, v38, v36
	v_cmp_lt_f32_e64 s[0:1], 0, v38
	s_nop 1
	v_cndmask_b32_e64 v38, v40, v41, s[0:1]
	v_mul_f32_e32 v40, 0x37800000, v38
	v_cndmask_b32_e32 v38, v38, v40, vcc
	ds_read2_b32 v[40:41], v32 offset0:64 offset1:96
	v_cmp_class_f32_e32 vcc, v36, v193
	s_nop 1
	v_cndmask_b32_e32 v36, v38, v36, vcc
	v_cmp_ngt_f32_e32 vcc, s23, v33
	s_nop 1
	v_cndmask_b32_e32 v33, 1.0, v36, vcc
	v_mul_f32_e32 v33, v34, v33
	s_waitcnt lgkmcnt(0)
	v_mul_f32_e32 v33, v40, v33
	ds_write_b32 v73, v35 offset:4352
	ds_write_b32 v73, v33 offset:41216
	v_add_f32_e32 v33, v58, v77
	v_mul_f32_e32 v33, 0xbfb8aa3b, v33
	v_exp_f32_e32 v33, v33
	v_add_f32_e32 v34, v42, v76
	v_mul_f32_e32 v34, 0xbfb8aa3b, v34
	v_exp_f32_e32 v34, v34
	v_add_f32_e32 v33, 1.0, v33
	v_rcp_f32_e32 v33, v33
	ds_read2_b32 v[56:57], v32 offset0:128 offset1:160
	v_add_f32_e32 v34, 1.0, v34
	v_rcp_f32_e32 v34, v34
	v_mul_f32_e32 v33, v33, v75
	v_mul_f32_e32 v35, 0x3fb8aa3b, v33
	v_add_f32_e32 v33, v33, v33
	v_mul_f32_e32 v36, 0x3fb8aa3b, v33
	v_rndne_f32_e32 v36, v36
	v_fmamk_f32 v38, v36, 0xbf317218, v33
	v_fmac_f32_e32 v38, 0x3102e308, v36
	v_fmamk_f32 v40, v38, 0x395133b1, v192
	v_cmp_eq_f32_e32 vcc, s20, v36
	v_cvt_i32_f32_e32 v36, v36
	v_fmaak_f32 v40, v38, v40, 0x3c0887f9
	v_fmaak_f32 v40, v38, v40, 0x3d2aaa81
	v_fmaak_f32 v40, v38, v40, 0x3e2aaaab
	v_fma_f32 v40, v38, v40, 0.5
	v_ldexp_f32 v36, 1.0, v36
	v_mul_f32_e32 v40, v38, v40
	v_cndmask_b32_e32 v36, v36, v202, vcc
	v_fmac_f32_e32 v38, v38, v40
	v_add_f32_e32 v40, -1.0, v36
	v_fmac_f32_e32 v40, v36, v38
	v_add_f32_e32 v36, v40, v40
	v_cndmask_b32_e32 v36, v40, v36, vcc
	v_cmp_nlt_f32_e32 vcc, s21, v33
	v_exp_f32_e32 v35, v35
	s_nop 0
	v_cndmask_b32_e64 v36, v201, -v36, vcc
	v_cmp_gt_f32_e32 vcc, s22, v36
	v_mul_f32_e32 v38, 0x4f800000, v36
	s_nop 0
	v_cndmask_b32_e32 v36, v36, v38, vcc
	v_sqrt_f32_e32 v38, v36
	s_nop 0
	v_add_u32_e32 v40, -1, v38
	v_fma_f32 v42, -v40, v38, v36
	v_cmp_ge_f32_e64 s[0:1], 0, v42
	v_add_u32_e32 v42, 1, v38
	s_nop 0
	v_cndmask_b32_e64 v40, v38, v40, s[0:1]
	v_fma_f32 v38, -v42, v38, v36
	v_cmp_lt_f32_e64 s[0:1], 0, v38
	s_nop 1
	v_cndmask_b32_e64 v38, v40, v42, s[0:1]
	v_mul_f32_e32 v40, 0x37800000, v38
	v_cndmask_b32_e32 v38, v38, v40, vcc
	v_cmp_class_f32_e32 vcc, v36, v193
	s_nop 1
	v_cndmask_b32_e32 v36, v38, v36, vcc
	v_cmp_ngt_f32_e32 vcc, s23, v33
	s_nop 1
	v_cndmask_b32_e32 v33, 1.0, v36, vcc
	v_mul_f32_e32 v33, v34, v33
	s_waitcnt lgkmcnt(0)
	v_mul_f32_e32 v33, v56, v33
	ds_write_b32 v73, v35 offset:4608
	ds_write_b32 v73, v33 offset:41472
	v_add_f32_e32 v33, v59, v77
	v_mul_f32_e32 v33, 0xbfb8aa3b, v33
	v_exp_f32_e32 v33, v33
	v_add_f32_e32 v34, v43, v76
	v_mul_f32_e32 v34, 0xbfb8aa3b, v34
	v_exp_f32_e32 v34, v34
	v_add_f32_e32 v33, 1.0, v33
	v_rcp_f32_e32 v33, v33
	v_add_f32_e32 v34, 1.0, v34
	v_rcp_f32_e32 v34, v34
	v_mul_f32_e32 v33, v33, v75
	v_mul_f32_e32 v35, 0x3fb8aa3b, v33
	v_add_f32_e32 v33, v33, v33
	v_mul_f32_e32 v36, 0x3fb8aa3b, v33
	v_rndne_f32_e32 v36, v36
	v_fmamk_f32 v38, v36, 0xbf317218, v33
	v_fmac_f32_e32 v38, 0x3102e308, v36
	v_fmamk_f32 v40, v38, 0x395133b1, v192
	v_cmp_eq_f32_e32 vcc, s20, v36
	v_cvt_i32_f32_e32 v36, v36
	v_fmaak_f32 v40, v38, v40, 0x3c0887f9
	v_fmaak_f32 v40, v38, v40, 0x3d2aaa81
	v_fmaak_f32 v40, v38, v40, 0x3e2aaaab
	v_fma_f32 v40, v38, v40, 0.5
	v_ldexp_f32 v36, 1.0, v36
	v_mul_f32_e32 v40, v38, v40
	v_cndmask_b32_e32 v36, v36, v202, vcc
	v_fmac_f32_e32 v38, v38, v40
	v_add_f32_e32 v40, -1.0, v36
	v_fmac_f32_e32 v40, v36, v38
	v_add_f32_e32 v36, v40, v40
	v_cndmask_b32_e32 v36, v40, v36, vcc
	v_cmp_nlt_f32_e32 vcc, s21, v33
	v_exp_f32_e32 v35, v35
	s_nop 0
	v_cndmask_b32_e64 v36, v201, -v36, vcc
	v_cmp_gt_f32_e32 vcc, s22, v36
	v_mul_f32_e32 v38, 0x4f800000, v36
	s_nop 0
	v_cndmask_b32_e32 v36, v36, v38, vcc
	v_sqrt_f32_e32 v38, v36
	s_nop 0
	v_add_u32_e32 v40, -1, v38
	v_fma_f32 v42, -v40, v38, v36
	v_cmp_ge_f32_e64 s[0:1], 0, v42
	v_add_u32_e32 v42, 1, v38
	s_nop 0
	v_cndmask_b32_e64 v40, v38, v40, s[0:1]
	v_fma_f32 v38, -v42, v38, v36
	v_cmp_lt_f32_e64 s[0:1], 0, v38
	s_nop 1
	v_cndmask_b32_e64 v38, v40, v42, s[0:1]
	v_mul_f32_e32 v40, 0x37800000, v38
	ds_read2_b32 v[42:43], v32 offset0:192 offset1:224
	v_cndmask_b32_e32 v38, v38, v40, vcc
	v_cmp_class_f32_e32 vcc, v36, v193
	s_nop 1
	v_cndmask_b32_e32 v36, v38, v36, vcc
	v_cmp_ngt_f32_e32 vcc, s23, v33
	s_nop 1
	v_cndmask_b32_e32 v33, 1.0, v36, vcc
	v_mul_f32_e32 v33, v34, v33
	s_waitcnt lgkmcnt(0)
	v_mul_f32_e32 v32, v42, v33
	ds_write_b32 v73, v35 offset:4864
	ds_write_b32 v73, v32 offset:41728
	v_add_f32_e32 v32, v60, v77
	v_mul_f32_e32 v32, 0xbfb8aa3b, v32
	v_exp_f32_e32 v32, v32
	v_add_f32_e32 v33, v44, v76
	v_mul_f32_e32 v33, 0xbfb8aa3b, v33
	v_exp_f32_e32 v33, v33
	v_add_f32_e32 v32, 1.0, v32
	v_rcp_f32_e32 v32, v32
	v_add_f32_e32 v33, 1.0, v33
	v_rcp_f32_e32 v33, v33
	v_mul_f32_e32 v32, v32, v75
	v_mul_f32_e32 v34, 0x3fb8aa3b, v32
	v_add_f32_e32 v32, v32, v32
	v_mul_f32_e32 v35, 0x3fb8aa3b, v32
	v_rndne_f32_e32 v35, v35
	v_fmamk_f32 v36, v35, 0xbf317218, v32
	v_fmac_f32_e32 v36, 0x3102e308, v35
	v_fmamk_f32 v38, v36, 0x395133b1, v192
	v_cmp_eq_f32_e32 vcc, s20, v35
	v_cvt_i32_f32_e32 v35, v35
	v_fmaak_f32 v38, v36, v38, 0x3c0887f9
	v_fmaak_f32 v38, v36, v38, 0x3d2aaa81
	v_fmaak_f32 v38, v36, v38, 0x3e2aaaab
	v_fma_f32 v38, v36, v38, 0.5
	v_ldexp_f32 v35, 1.0, v35
	v_mul_f32_e32 v38, v36, v38
	v_cndmask_b32_e32 v35, v35, v202, vcc
	v_fmac_f32_e32 v36, v36, v38
	v_add_f32_e32 v38, -1.0, v35
	v_fmac_f32_e32 v38, v35, v36
	v_add_f32_e32 v35, v38, v38
	v_cndmask_b32_e32 v35, v38, v35, vcc
	v_cmp_nlt_f32_e32 vcc, s21, v32
	v_exp_f32_e32 v34, v34
	s_nop 0
	v_cndmask_b32_e64 v35, v201, -v35, vcc
	v_cmp_gt_f32_e32 vcc, s22, v35
	v_mul_f32_e32 v36, 0x4f800000, v35
	s_nop 0
	v_cndmask_b32_e32 v35, v35, v36, vcc
	v_sqrt_f32_e32 v36, v35
	s_nop 0
	v_add_u32_e32 v38, -1, v36
	v_fma_f32 v40, -v38, v36, v35
	v_cmp_ge_f32_e64 s[0:1], 0, v40
	v_add_u32_e32 v40, 1, v36
	s_nop 0
	v_cndmask_b32_e64 v38, v36, v38, s[0:1]
	v_fma_f32 v36, -v40, v36, v35
	v_cmp_lt_f32_e64 s[0:1], 0, v36
	s_nop 1
	v_cndmask_b32_e64 v36, v38, v40, s[0:1]
	v_mul_f32_e32 v38, 0x37800000, v36
	v_cndmask_b32_e32 v36, v36, v38, vcc
	v_cmp_class_f32_e32 vcc, v35, v193
	s_nop 1
	v_cndmask_b32_e32 v35, v36, v35, vcc
	v_cmp_ngt_f32_e32 vcc, s23, v32
	s_nop 1
	v_cndmask_b32_e32 v32, 1.0, v35, vcc
	v_mul_f32_e32 v32, v33, v32
	v_add_u32_e32 v33, 0xa800, v73
	ds_read2_b32 v[58:59], v33 offset1:32
	s_waitcnt lgkmcnt(0)
	v_mul_f32_e32 v32, v58, v32
	ds_write_b32 v73, v34 offset:6144
	ds_write_b32 v73, v32 offset:43008
	v_add_f32_e32 v32, v61, v77
	v_mul_f32_e32 v32, 0xbfb8aa3b, v32
	v_exp_f32_e32 v32, v32
	v_add_f32_e32 v34, v45, v76
	v_mul_f32_e32 v34, 0xbfb8aa3b, v34
	v_exp_f32_e32 v34, v34
	v_add_f32_e32 v32, 1.0, v32
	v_rcp_f32_e32 v32, v32
	ds_read2_b32 v[44:45], v33 offset0:64 offset1:96
	v_add_f32_e32 v34, 1.0, v34
	v_rcp_f32_e32 v34, v34
	v_mul_f32_e32 v32, v32, v75
	v_mul_f32_e32 v35, 0x3fb8aa3b, v32
	v_add_f32_e32 v32, v32, v32
	v_mul_f32_e32 v36, 0x3fb8aa3b, v32
	v_rndne_f32_e32 v36, v36
	v_fmamk_f32 v38, v36, 0xbf317218, v32
	v_fmac_f32_e32 v38, 0x3102e308, v36
	v_fmamk_f32 v40, v38, 0x395133b1, v192
	v_cmp_eq_f32_e32 vcc, s20, v36
	v_cvt_i32_f32_e32 v36, v36
	v_fmaak_f32 v40, v38, v40, 0x3c0887f9
	v_fmaak_f32 v40, v38, v40, 0x3d2aaa81
	v_fmaak_f32 v40, v38, v40, 0x3e2aaaab
	v_fma_f32 v40, v38, v40, 0.5
	v_ldexp_f32 v36, 1.0, v36
	v_mul_f32_e32 v40, v38, v40
	v_cndmask_b32_e32 v36, v36, v202, vcc
	v_fmac_f32_e32 v38, v38, v40
	v_add_f32_e32 v40, -1.0, v36
	v_fmac_f32_e32 v40, v36, v38
	v_add_f32_e32 v36, v40, v40
	v_cndmask_b32_e32 v36, v40, v36, vcc
	v_cmp_nlt_f32_e32 vcc, s21, v32
	v_exp_f32_e32 v35, v35
	s_nop 0
	v_cndmask_b32_e64 v36, v201, -v36, vcc
	v_cmp_gt_f32_e32 vcc, s22, v36
	v_mul_f32_e32 v38, 0x4f800000, v36
	s_nop 0
	v_cndmask_b32_e32 v36, v36, v38, vcc
	v_sqrt_f32_e32 v38, v36
	s_nop 0
	v_add_u32_e32 v40, -1, v38
	v_fma_f32 v42, -v40, v38, v36
	v_cmp_ge_f32_e64 s[0:1], 0, v42
	v_add_u32_e32 v42, 1, v38
	s_nop 0
	v_cndmask_b32_e64 v40, v38, v40, s[0:1]
	v_fma_f32 v38, -v42, v38, v36
	v_cmp_lt_f32_e64 s[0:1], 0, v38
	s_nop 1
	v_cndmask_b32_e64 v38, v40, v42, s[0:1]
	v_mul_f32_e32 v40, 0x37800000, v38
	v_cndmask_b32_e32 v38, v38, v40, vcc
	v_cmp_class_f32_e32 vcc, v36, v193
	s_nop 1
	v_cndmask_b32_e32 v36, v38, v36, vcc
	v_cmp_ngt_f32_e32 vcc, s23, v32
	s_nop 1
	v_cndmask_b32_e32 v32, 1.0, v36, vcc
	v_mul_f32_e32 v32, v34, v32
	s_waitcnt lgkmcnt(0)
	v_mul_f32_e32 v32, v44, v32
	ds_write_b32 v73, v35 offset:6400
	ds_write_b32 v73, v32 offset:43264
	v_add_f32_e32 v32, v62, v77
	v_mul_f32_e32 v32, 0xbfb8aa3b, v32
	v_exp_f32_e32 v32, v32
	v_add_f32_e32 v34, v46, v76
	v_mul_f32_e32 v34, 0xbfb8aa3b, v34
	v_exp_f32_e32 v34, v34
	v_add_f32_e32 v32, 1.0, v32
	v_rcp_f32_e32 v32, v32
	v_add_f32_e32 v34, 1.0, v34
	v_rcp_f32_e32 v34, v34
	v_mul_f32_e32 v32, v32, v75
	v_mul_f32_e32 v35, 0x3fb8aa3b, v32
	v_add_f32_e32 v32, v32, v32
	v_exp_f32_e32 v36, v35
	v_mul_f32_e32 v35, 0x3fb8aa3b, v32
	v_rndne_f32_e32 v35, v35
	v_fmamk_f32 v38, v35, 0xbf317218, v32
	v_fmac_f32_e32 v38, 0x3102e308, v35
	v_fmamk_f32 v40, v38, 0x395133b1, v192
	v_cmp_eq_f32_e32 vcc, s20, v35
	v_cvt_i32_f32_e32 v35, v35
	v_fmaak_f32 v40, v38, v40, 0x3c0887f9
	v_fmaak_f32 v40, v38, v40, 0x3d2aaa81
	v_fmaak_f32 v40, v38, v40, 0x3e2aaaab
	v_fma_f32 v40, v38, v40, 0.5
	v_ldexp_f32 v35, 1.0, v35
	v_mul_f32_e32 v40, v38, v40
	v_cndmask_b32_e32 v35, v35, v202, vcc
	v_fmac_f32_e32 v38, v38, v40
	v_add_f32_e32 v40, -1.0, v35
	v_fmac_f32_e32 v40, v35, v38
	v_add_f32_e32 v35, v40, v40
	v_cndmask_b32_e32 v35, v40, v35, vcc
	v_cmp_nlt_f32_e32 vcc, s21, v32
	s_nop 1
	v_cndmask_b32_e64 v35, v201, -v35, vcc
	v_cmp_gt_f32_e32 vcc, s22, v35
	v_mul_f32_e32 v38, 0x4f800000, v35
	s_nop 0
	v_cndmask_b32_e32 v35, v35, v38, vcc
	v_sqrt_f32_e32 v38, v35
	s_nop 0
	v_add_u32_e32 v40, -1, v38
	v_fma_f32 v42, -v40, v38, v35
	v_cmp_ge_f32_e64 s[0:1], 0, v42
	v_add_u32_e32 v42, 1, v38
	s_nop 0
	v_cndmask_b32_e64 v40, v38, v40, s[0:1]
	v_fma_f32 v38, -v42, v38, v35
	v_cmp_lt_f32_e64 s[0:1], 0, v38
	s_nop 1
	v_cndmask_b32_e64 v38, v40, v42, s[0:1]
	v_mul_f32_e32 v40, 0x37800000, v38
	v_cndmask_b32_e32 v38, v38, v40, vcc
	v_cmp_class_f32_e32 vcc, v35, v193
	s_nop 1
	v_cndmask_b32_e32 v35, v38, v35, vcc
	v_cmp_ngt_f32_e32 vcc, s23, v32
	s_nop 1
	v_cndmask_b32_e32 v32, 1.0, v35, vcc
	v_mul_f32_e32 v32, v34, v32
	ds_read2_b32 v[34:35], v33 offset0:128 offset1:160
	s_waitcnt lgkmcnt(0)
	v_mul_f32_e32 v32, v34, v32
	ds_write_b32 v73, v36 offset:6656
	ds_write_b32 v73, v32 offset:43520
	v_add_f32_e32 v32, v63, v77
	v_mul_f32_e32 v32, 0xbfb8aa3b, v32
	v_exp_f32_e32 v32, v32
	v_add_f32_e32 v34, v47, v76
	v_mul_f32_e32 v34, 0xbfb8aa3b, v34
	v_exp_f32_e32 v34, v34
	v_add_f32_e32 v32, 1.0, v32
	v_rcp_f32_e32 v32, v32
	v_lshlrev_b64 v[46:47], 2, v[96:97]
	v_add_f32_e32 v34, 1.0, v34
	v_rcp_f32_e32 v36, v34
	v_mul_f32_e32 v32, v32, v75
	v_mul_f32_e32 v34, 0x3fb8aa3b, v32
	v_add_f32_e32 v32, v32, v32
	v_mul_f32_e32 v38, 0x3fb8aa3b, v32
	v_rndne_f32_e32 v38, v38
	v_fmamk_f32 v40, v38, 0xbf317218, v32
	v_fmac_f32_e32 v40, 0x3102e308, v38
	v_fmamk_f32 v42, v40, 0x395133b1, v192
	v_cmp_eq_f32_e32 vcc, s20, v38
	v_cvt_i32_f32_e32 v38, v38
	v_fmaak_f32 v42, v40, v42, 0x3c0887f9
	v_fmaak_f32 v42, v40, v42, 0x3d2aaa81
	v_fmaak_f32 v42, v40, v42, 0x3e2aaaab
	v_fma_f32 v42, v40, v42, 0.5
	v_ldexp_f32 v38, 1.0, v38
	v_mul_f32_e32 v42, v40, v42
	v_cndmask_b32_e32 v38, v38, v202, vcc
	v_fmac_f32_e32 v40, v40, v42
	v_add_f32_e32 v42, -1.0, v38
	v_fmac_f32_e32 v42, v38, v40
	v_add_f32_e32 v38, v42, v42
	v_cndmask_b32_e32 v38, v42, v38, vcc
	v_cmp_nlt_f32_e32 vcc, s21, v32
	v_lshl_add_u64 v[60:61], s[18:19], 0, v[46:47]
	v_exp_f32_e32 v34, v34
	v_cndmask_b32_e64 v38, v201, -v38, vcc
	v_cmp_gt_f32_e32 vcc, s22, v38
	v_mul_f32_e32 v40, 0x4f800000, v38
	s_nop 0
	v_cndmask_b32_e32 v38, v38, v40, vcc
	v_sqrt_f32_e32 v40, v38
	s_nop 0
	v_add_u32_e32 v42, -1, v40
	v_fma_f32 v44, -v42, v40, v38
	v_cmp_ge_f32_e64 s[0:1], 0, v44
	v_add_u32_e32 v44, 1, v40
	s_nop 0
	v_cndmask_b32_e64 v42, v40, v42, s[0:1]
	v_fma_f32 v40, -v44, v40, v38
	v_cmp_lt_f32_e64 s[0:1], 0, v40
	s_nop 1
	v_cndmask_b32_e64 v40, v42, v44, s[0:1]
	v_mul_f32_e32 v42, 0x37800000, v40
	v_cndmask_b32_e32 v40, v40, v42, vcc
	v_cmp_class_f32_e32 vcc, v38, v193
	s_nop 1
	v_cndmask_b32_e32 v38, v40, v38, vcc
	v_cmp_ngt_f32_e32 vcc, s23, v32
	s_nop 1
	v_cndmask_b32_e32 v32, 1.0, v38, vcc
	v_mul_f32_e32 v36, v36, v32
	ds_read2_b32 v[32:33], v33 offset0:192 offset1:224
	s_waitcnt lgkmcnt(0)
	v_mul_f32_e32 v32, v32, v36
	ds_write_b32 v73, v32 offset:43776
	s_waitcnt vmcnt(0)
	v_mul_f32_e32 v32, 0xbfb8aa3b, v226
	v_exp_f32_e32 v32, v32
	s_nop 0
	v_add_f32_e32 v36, 1.0, v32
	v_add_f32_e32 v38, -1.0, v36
	v_sub_f32_e32 v40, v38, v36
	v_add_f32_e32 v40, 1.0, v40
	v_sub_f32_e32 v38, v32, v38
	v_add_f32_e32 v38, v38, v40
	v_frexp_mant_f32_e32 v40, v36
	v_cvt_f64_f32_e32 v[60:61], v36
	v_cmp_gt_f32_e32 vcc, s4, v40
	v_frexp_exp_i32_f64_e32 v40, v[60:61]
	s_mul_i32 s4, s11, 0x24000
	v_subbrev_co_u32_e32 v40, vcc, 0, v40, vcc
	v_sub_u32_e32 v42, 0, v40
	v_ldexp_f32 v36, v36, v42
	v_ldexp_f32 v38, v38, v42
	v_add_f32_e32 v42, -1.0, v36
	v_add_f32_e32 v48, 1.0, v36
	v_add_f32_e32 v44, 1.0, v42
	v_add_f32_e32 v50, -1.0, v48
	v_sub_f32_e32 v44, v36, v44
	v_sub_f32_e32 v36, v36, v50
	v_add_f32_e32 v36, v38, v36
	v_add_f32_e32 v44, v38, v44
	v_add_f32_e32 v38, v48, v36
	v_sub_f32_e32 v48, v38, v48
	v_sub_f32_e32 v36, v36, v48
	v_rcp_f32_e32 v48, v38
	v_add_f32_e32 v61, v42, v44
	v_sub_f32_e32 v42, v61, v42
	v_sub_f32_e32 v42, v44, v42
	v_mul_f32_e32 v44, v61, v48
	v_mul_f32_e32 v62, v38, v44
	v_fma_f32 v74, v44, v38, -v62
	v_fmac_f32_e32 v74, v44, v36
	v_add_f32_e32 v60, v62, v74
	v_sub_f32_e32 v63, v61, v60
	v_pk_add_f32 v[76:77], v[60:61], v[62:63] neg_lo:[0,1] neg_hi:[0,1]
	v_mov_b32_e32 v75, v60
	v_pk_add_f32 v[60:61], v[76:77], v[74:75] neg_lo:[0,1] neg_hi:[0,1]
	v_cmp_neq_f32_e32 vcc, s9, v32
	v_add_f32_e32 v42, v42, v61
	v_add_f32_e32 v42, v60, v42
	v_add_f32_e32 v61, v63, v42
	v_mul_f32_e32 v50, v48, v61
	v_mul_f32_e32 v62, v38, v50
	v_fma_f32 v74, v50, v38, -v62
	v_fmac_f32_e32 v74, v50, v36
	v_add_f32_e32 v60, v62, v74
	v_sub_f32_e32 v36, v63, v61
	v_sub_f32_e32 v63, v61, v60
	v_pk_add_f32 v[76:77], v[60:61], v[62:63] neg_lo:[0,1] neg_hi:[0,1]
	v_mov_b32_e32 v75, v60
	v_add_f32_e32 v36, v42, v36
	v_pk_add_f32 v[60:61], v[76:77], v[74:75] neg_lo:[0,1] neg_hi:[0,1]
	v_add_f32_e32 v38, v44, v50
	v_add_f32_e32 v36, v36, v61
	v_add_f32_e32 v36, v60, v36
	v_add_f32_e32 v36, v63, v36
	v_sub_f32_e32 v42, v38, v44
	v_mul_f32_e32 v36, v48, v36
	v_sub_f32_e32 v42, v50, v42
	v_add_f32_e32 v36, v42, v36
	v_add_f32_e32 v42, v38, v36
	v_cvt_f32_i32_e32 v60, v40
	v_mul_f32_e32 v44, v42, v42
	v_fmamk_f32 v48, v44, 0x3e9b6dac, v191
	v_fmaak_f32 v169, v44, v48, 0x3f2aaada
	v_mul_f32_e32 v61, v42, v44
	v_pk_mul_f32 v[74:75], v[60:61], v[168:169]
	v_ldexp_f32 v63, v42, 1
	v_fma_f32 v62, v60, s8, -v74
	v_fmac_f32_e32 v62, 0xb102e308, v60
	v_sub_f32_e32 v38, v42, v38
	v_pk_add_f32 v[60:61], v[74:75], v[62:63]
	v_sub_f32_e32 v36, v36, v38
	v_sub_f32_e32 v38, v61, v63
	v_ldexp_f32 v36, v36, 1
	v_sub_f32_e32 v38, v75, v38
	v_add_f32_e32 v77, v36, v38
	v_mov_b32_e32 v76, v74
	v_pk_add_f32 v[74:75], v[60:61], v[74:75] neg_lo:[0,1] neg_hi:[0,1]
	v_pk_add_f32 v[78:79], v[60:61], v[76:77]
	v_mov_b32_e32 v63, v60
	v_mov_b32_e32 v75, v79
	v_pk_add_f32 v[80:81], v[62:63], v[74:75] neg_lo:[0,1] neg_hi:[0,1]
	v_pk_add_f32 v[62:63], v[62:63], v[74:75]
	v_mov_b32_e32 v76, v77
	v_pk_add_f32 v[74:75], v[62:63], v[60:61] op_sel:[1,0] op_sel_hi:[0,1] neg_lo:[0,1] neg_hi:[0,1]
	v_pk_add_f32 v[82:83], v[78:79], v[74:75] op_sel_hi:[1,0] neg_lo:[0,1] neg_hi:[0,1]
	v_mov_b32_e32 v78, v79
	v_mov_b32_e32 v79, v63
	v_pk_mov_b32 v[74:75], v[60:61], v[74:75] op_sel:[1,0]
	v_mov_b32_e32 v77, v60
	v_pk_add_f32 v[74:75], v[78:79], v[74:75] neg_lo:[0,1] neg_hi:[0,1]
	v_mov_b32_e32 v82, v80
	v_pk_add_f32 v[60:61], v[76:77], v[74:75] neg_lo:[0,1] neg_hi:[0,1]
	v_mov_b32_e32 v81, v63
	v_pk_add_f32 v[74:75], v[82:83], v[60:61]
	v_pk_add_f32 v[76:77], v[74:75], v[74:75] op_sel:[0,1] op_sel_hi:[1,0]
	v_pk_add_f32 v[62:63], v[62:63], v[76:77] op_sel:[1,0] op_sel_hi:[0,1]
	v_mov_b32_e32 v75, v62
	v_pk_add_f32 v[78:79], v[74:75], v[80:81] neg_lo:[0,1] neg_hi:[0,1]
	v_mov_b32_e32 v61, v76
	v_sub_f32_e32 v36, v74, v78
	v_pk_add_f32 v[60:61], v[60:61], v[78:79] neg_lo:[0,1] neg_hi:[0,1]
	v_sub_f32_e32 v36, v80, v36
	v_add_f32_e32 v36, v60, v36
	v_add_f32_e32 v36, v36, v61
	v_add_f32_e32 v36, v62, v36
	v_cndmask_b32_e32 v36, v199, v36, vcc
	v_cmp_ngt_f32_e32 vcc, -1.0, v32
	v_lshl_add_u64 v[60:61], s[52:53], 0, v[46:47]
	v_lshl_add_u64 v[46:47], s[16:17], 0, v[46:47]
	v_cndmask_b32_e32 v36, v200, v36, vcc
	v_cmp_neq_f32_e32 vcc, -1.0, v32
	v_mov_b32_e32 v38, v227
	s_waitcnt vmcnt(0)
	v_add_f32_e32 v0, v0, v38
	v_cndmask_b32_e32 v36, v201, v36, vcc
	v_cmp_lt_f32_e64 vcc, |v32|, s10
	v_mul_f32_e32 v0, 0xbfb8aa3b, v0
	v_exp_f32_e32 v0, v0
	v_cndmask_b32_e32 v32, v36, v32, vcc
	v_mov_b32_e32 v36, v228
	v_mul_f32_e32 v32, 0xc1000000, v32
	v_add_f32_e32 v0, 1.0, v0
	v_rcp_f32_e32 v0, v0
	v_add_f32_e32 v1, v1, v38
	v_mul_f32_e32 v1, 0xbfb8aa3b, v1
	v_exp_f32_e32 v1, v1
	s_waitcnt vmcnt(0)
	v_add_f32_e32 v16, v16, v36
	v_mul_f32_e32 v16, 0xbfb8aa3b, v16
	v_exp_f32_e32 v16, v16
	v_add_f32_e32 v1, 1.0, v1
	v_rcp_f32_e32 v1, v1
	v_add_f32_e32 v16, 1.0, v16
	v_rcp_f32_e32 v16, v16
	s_nop 0
	v_mul_f32_e32 v16, v16, v32
	v_mul_f32_e32 v40, 0x3fb8aa3b, v16
	v_add_f32_e32 v16, v16, v16
	v_mul_f32_e32 v42, 0x3fb8aa3b, v16
	v_rndne_f32_e32 v42, v42
	v_fmamk_f32 v44, v42, 0xbf317218, v16
	v_fmac_f32_e32 v44, 0x3102e308, v42
	v_fmamk_f32 v46, v44, 0x395133b1, v192
	v_cmp_eq_f32_e32 vcc, s20, v42
	v_cvt_i32_f32_e32 v42, v42
	v_fmaak_f32 v46, v44, v46, 0x3c0887f9
	v_fmaak_f32 v46, v44, v46, 0x3d2aaa81
	v_fmaak_f32 v46, v44, v46, 0x3e2aaaab
	v_fma_f32 v46, v44, v46, 0.5
	v_ldexp_f32 v42, 1.0, v42
	v_mul_f32_e32 v46, v44, v46
	v_cndmask_b32_e32 v42, v42, v202, vcc
	v_fmac_f32_e32 v44, v44, v46
	v_add_f32_e32 v46, -1.0, v42
	v_fmac_f32_e32 v46, v42, v44
	v_add_f32_e32 v42, v46, v46
	v_cndmask_b32_e32 v42, v46, v42, vcc
	v_cmp_nlt_f32_e32 vcc, s21, v16
	v_exp_f32_e32 v40, v40
	s_nop 0
	v_cndmask_b32_e64 v42, v201, -v42, vcc
	v_cmp_gt_f32_e32 vcc, s22, v42
	v_mul_f32_e32 v44, 0x4f800000, v42
	s_nop 0
	v_cndmask_b32_e32 v42, v42, v44, vcc
	v_sqrt_f32_e32 v44, v42
	s_nop 0
	v_add_u32_e32 v46, -1, v44
	v_fma_f32 v47, -v46, v44, v42
	v_cmp_ge_f32_e64 s[0:1], 0, v47
	v_add_u32_e32 v47, 1, v44
	s_nop 0
	v_cndmask_b32_e64 v46, v44, v46, s[0:1]
	v_fma_f32 v44, -v47, v44, v42
	v_cmp_lt_f32_e64 s[0:1], 0, v44
	s_nop 1
	v_cndmask_b32_e64 v44, v46, v47, s[0:1]
	v_mul_f32_e32 v46, 0x37800000, v44
	v_cndmask_b32_e32 v44, v44, v46, vcc
	v_cmp_class_f32_e32 vcc, v42, v193
	s_nop 1
	v_cndmask_b32_e32 v42, v44, v42, vcc
	v_cmp_ngt_f32_e32 vcc, s23, v16
	s_nop 1
	v_cndmask_b32_e32 v16, 1.0, v42, vcc
	v_mul_f32_e32 v0, v0, v16
	v_mul_f32_e32 v0, v67, v0
	ds_write_b32 v73, v40 offset:128
	ds_write_b32 v73, v0 offset:36992
	v_add_f32_e32 v0, v17, v36
	v_mul_f32_e32 v0, 0xbfb8aa3b, v0
	v_exp_f32_e32 v0, v0
	s_nop 0
	v_add_f32_e32 v0, 1.0, v0
	v_rcp_f32_e32 v0, v0
	s_nop 0
	v_mul_f32_e32 v0, v0, v32
	v_mul_f32_e32 v16, 0x3fb8aa3b, v0
	v_add_f32_e32 v0, v0, v0
	v_mul_f32_e32 v17, 0x3fb8aa3b, v0
	v_rndne_f32_e32 v17, v17
	v_fmamk_f32 v40, v17, 0xbf317218, v0
	v_fmac_f32_e32 v40, 0x3102e308, v17
	v_fmamk_f32 v42, v40, 0x395133b1, v192
	v_cmp_eq_f32_e32 vcc, s20, v17
	v_cvt_i32_f32_e32 v17, v17
	v_fmaak_f32 v42, v40, v42, 0x3c0887f9
	v_fmaak_f32 v42, v40, v42, 0x3d2aaa81
	v_fmaak_f32 v42, v40, v42, 0x3e2aaaab
	v_fma_f32 v42, v40, v42, 0.5
	v_ldexp_f32 v17, 1.0, v17
	v_mul_f32_e32 v42, v40, v42
	v_cndmask_b32_e32 v17, v17, v202, vcc
	v_fmac_f32_e32 v40, v40, v42
	v_add_f32_e32 v42, -1.0, v17
	v_fmac_f32_e32 v42, v17, v40
	v_add_f32_e32 v17, v42, v42
	v_cndmask_b32_e32 v17, v42, v17, vcc
	v_cmp_nlt_f32_e32 vcc, s21, v0
	v_exp_f32_e32 v16, v16
	s_nop 0
	v_cndmask_b32_e64 v17, v201, -v17, vcc
	v_cmp_gt_f32_e32 vcc, s22, v17
	v_mul_f32_e32 v40, 0x4f800000, v17
	s_nop 0
	v_cndmask_b32_e32 v17, v17, v40, vcc
	v_sqrt_f32_e32 v40, v17
	s_nop 0
	v_add_u32_e32 v42, -1, v40
	v_fma_f32 v44, -v42, v40, v17
	v_cmp_ge_f32_e64 s[0:1], 0, v44
	v_add_u32_e32 v44, 1, v40
	s_nop 0
	v_cndmask_b32_e64 v42, v40, v42, s[0:1]
	v_fma_f32 v40, -v44, v40, v17
	v_cmp_lt_f32_e64 s[0:1], 0, v40
	s_nop 1
	v_cndmask_b32_e64 v40, v42, v44, s[0:1]
	v_mul_f32_e32 v42, 0x37800000, v40
	v_cndmask_b32_e32 v40, v40, v42, vcc
	v_cmp_class_f32_e32 vcc, v17, v193
	s_nop 1
	v_cndmask_b32_e32 v17, v40, v17, vcc
	v_cmp_ngt_f32_e32 vcc, s23, v0
	s_nop 1
	v_cndmask_b32_e32 v0, 1.0, v17, vcc
	v_mul_f32_e32 v0, v1, v0
	v_mul_f32_e32 v0, v49, v0
	ds_write_b32 v73, v16 offset:384
	ds_write_b32 v73, v0 offset:37248
	v_add_f32_e32 v0, v18, v36
	v_mul_f32_e32 v0, 0xbfb8aa3b, v0
	v_exp_f32_e32 v0, v0
	v_add_f32_e32 v1, v2, v38
	v_mul_f32_e32 v1, 0xbfb8aa3b, v1
	v_exp_f32_e32 v1, v1
	v_add_f32_e32 v0, 1.0, v0
	v_rcp_f32_e32 v0, v0
	v_add_f32_e32 v1, 1.0, v1
	v_rcp_f32_e32 v1, v1
	v_mul_f32_e32 v0, v0, v32
	v_mul_f32_e32 v2, 0x3fb8aa3b, v0
	v_add_f32_e32 v0, v0, v0
	v_mul_f32_e32 v16, 0x3fb8aa3b, v0
	v_rndne_f32_e32 v16, v16
	v_fmamk_f32 v17, v16, 0xbf317218, v0
	v_fmac_f32_e32 v17, 0x3102e308, v16
	v_fmamk_f32 v18, v17, 0x395133b1, v192
	v_cmp_eq_f32_e32 vcc, s20, v16
	v_cvt_i32_f32_e32 v16, v16
	v_fmaak_f32 v18, v17, v18, 0x3c0887f9
	v_fmaak_f32 v18, v17, v18, 0x3d2aaa81
	v_fmaak_f32 v18, v17, v18, 0x3e2aaaab
	v_fma_f32 v18, v17, v18, 0.5
	v_ldexp_f32 v16, 1.0, v16
	v_mul_f32_e32 v18, v17, v18
	v_cndmask_b32_e32 v16, v16, v202, vcc
	v_fmac_f32_e32 v17, v17, v18
	v_add_f32_e32 v18, -1.0, v16
	v_fmac_f32_e32 v18, v16, v17
	v_add_f32_e32 v16, v18, v18
	v_cndmask_b32_e32 v16, v18, v16, vcc
	v_cmp_nlt_f32_e32 vcc, s21, v0
	v_exp_f32_e32 v2, v2
	s_nop 0
	v_cndmask_b32_e64 v16, v201, -v16, vcc
	v_cmp_gt_f32_e32 vcc, s22, v16
	v_mul_f32_e32 v17, 0x4f800000, v16
	s_nop 0
	v_cndmask_b32_e32 v16, v16, v17, vcc
	v_sqrt_f32_e32 v17, v16
	s_nop 0
	v_add_u32_e32 v18, -1, v17
	v_fma_f32 v40, -v18, v17, v16
	v_cmp_ge_f32_e64 s[0:1], 0, v40
	v_add_u32_e32 v40, 1, v17
	s_nop 0
	v_cndmask_b32_e64 v18, v17, v18, s[0:1]
	v_fma_f32 v17, -v40, v17, v16
	v_cmp_lt_f32_e64 s[0:1], 0, v17
	s_nop 1
	v_cndmask_b32_e64 v17, v18, v40, s[0:1]
	v_mul_f32_e32 v18, 0x37800000, v17
	v_cndmask_b32_e32 v17, v17, v18, vcc
	v_cmp_class_f32_e32 vcc, v16, v193
	s_nop 1
	v_cndmask_b32_e32 v16, v17, v16, vcc
	v_cmp_ngt_f32_e32 vcc, s23, v0
	s_nop 1
	v_cndmask_b32_e32 v0, 1.0, v16, vcc
	v_mul_f32_e32 v0, v1, v0
	v_mul_f32_e32 v0, v69, v0
	ds_write_b32 v73, v2 offset:640
	ds_write_b32 v73, v0 offset:37504
	v_add_f32_e32 v0, v19, v36
	v_mul_f32_e32 v0, 0xbfb8aa3b, v0
	v_exp_f32_e32 v0, v0
	v_add_f32_e32 v1, v3, v38
	v_mul_f32_e32 v1, 0xbfb8aa3b, v1
	v_exp_f32_e32 v1, v1
	v_add_f32_e32 v0, 1.0, v0
	v_rcp_f32_e32 v0, v0
	v_add_f32_e32 v1, 1.0, v1
	v_rcp_f32_e32 v1, v1
	v_mul_f32_e32 v0, v0, v32
	v_mul_f32_e32 v2, 0x3fb8aa3b, v0
	v_add_f32_e32 v0, v0, v0
	v_mul_f32_e32 v3, 0x3fb8aa3b, v0
	v_rndne_f32_e32 v3, v3
	v_fmamk_f32 v16, v3, 0xbf317218, v0
	v_fmac_f32_e32 v16, 0x3102e308, v3
	v_fmamk_f32 v17, v16, 0x395133b1, v192
	v_cmp_eq_f32_e32 vcc, s20, v3
	v_cvt_i32_f32_e32 v3, v3
	v_fmaak_f32 v17, v16, v17, 0x3c0887f9
	v_fmaak_f32 v17, v16, v17, 0x3d2aaa81
	v_fmaak_f32 v17, v16, v17, 0x3e2aaaab
	v_fma_f32 v17, v16, v17, 0.5
	v_ldexp_f32 v3, 1.0, v3
	v_mul_f32_e32 v17, v16, v17
	v_cndmask_b32_e32 v3, v3, v202, vcc
	v_fmac_f32_e32 v16, v16, v17
	v_add_f32_e32 v17, -1.0, v3
	v_fmac_f32_e32 v17, v3, v16
	v_add_f32_e32 v3, v17, v17
	v_cndmask_b32_e32 v3, v17, v3, vcc
	v_cmp_nlt_f32_e32 vcc, s21, v0
	v_exp_f32_e32 v2, v2
	s_nop 0
	v_cndmask_b32_e64 v3, v201, -v3, vcc
	v_cmp_gt_f32_e32 vcc, s22, v3
	v_mul_f32_e32 v16, 0x4f800000, v3
	s_nop 0
	v_cndmask_b32_e32 v3, v3, v16, vcc
	v_sqrt_f32_e32 v16, v3
	s_nop 0
	v_add_u32_e32 v17, -1, v16
	v_fma_f32 v18, -v17, v16, v3
	v_cmp_ge_f32_e64 s[0:1], 0, v18
	v_add_u32_e32 v18, 1, v16
	s_nop 0
	v_cndmask_b32_e64 v17, v16, v17, s[0:1]
	v_fma_f32 v16, -v18, v16, v3
	v_cmp_lt_f32_e64 s[0:1], 0, v16
	s_nop 1
	v_cndmask_b32_e64 v16, v17, v18, s[0:1]
	v_mul_f32_e32 v17, 0x37800000, v16
	v_cndmask_b32_e32 v16, v16, v17, vcc
	v_cmp_class_f32_e32 vcc, v3, v193
	s_nop 1
	v_cndmask_b32_e32 v3, v16, v3, vcc
	v_cmp_ngt_f32_e32 vcc, s23, v0
	s_nop 1
	v_cndmask_b32_e32 v0, 1.0, v3, vcc
	v_mul_f32_e32 v0, v1, v0
	v_mul_f32_e32 v0, v51, v0
	ds_write_b32 v73, v2 offset:896
	ds_write_b32 v73, v0 offset:37760
	v_add_f32_e32 v0, v20, v36
	v_mul_f32_e32 v0, 0xbfb8aa3b, v0
	v_exp_f32_e32 v0, v0
	v_add_f32_e32 v1, v4, v38
	v_mul_f32_e32 v1, 0xbfb8aa3b, v1
	v_exp_f32_e32 v1, v1
	v_add_f32_e32 v0, 1.0, v0
	v_rcp_f32_e32 v0, v0
	v_add_f32_e32 v1, 1.0, v1
	v_rcp_f32_e32 v1, v1
	v_mul_f32_e32 v0, v0, v32
	v_mul_f32_e32 v2, 0x3fb8aa3b, v0
	v_add_f32_e32 v0, v0, v0
	v_mul_f32_e32 v3, 0x3fb8aa3b, v0
	v_rndne_f32_e32 v3, v3
	v_fmamk_f32 v4, v3, 0xbf317218, v0
	v_fmac_f32_e32 v4, 0x3102e308, v3
	v_fmamk_f32 v16, v4, 0x395133b1, v192
	v_cmp_eq_f32_e32 vcc, s20, v3
	v_cvt_i32_f32_e32 v3, v3
	v_fmaak_f32 v16, v4, v16, 0x3c0887f9
	v_fmaak_f32 v16, v4, v16, 0x3d2aaa81
	v_fmaak_f32 v16, v4, v16, 0x3e2aaaab
	v_fma_f32 v16, v4, v16, 0.5
	v_ldexp_f32 v3, 1.0, v3
	v_mul_f32_e32 v16, v4, v16
	v_cndmask_b32_e32 v3, v3, v202, vcc
	v_fmac_f32_e32 v4, v4, v16
	v_add_f32_e32 v16, -1.0, v3
	v_fmac_f32_e32 v16, v3, v4
	v_add_f32_e32 v3, v16, v16
	v_cndmask_b32_e32 v3, v16, v3, vcc
	v_cmp_nlt_f32_e32 vcc, s21, v0
	v_exp_f32_e32 v2, v2
	s_nop 0
	v_cndmask_b32_e64 v3, v201, -v3, vcc
	v_cmp_gt_f32_e32 vcc, s22, v3
	v_mul_f32_e32 v4, 0x4f800000, v3
	s_nop 0
	v_cndmask_b32_e32 v3, v3, v4, vcc
	v_sqrt_f32_e32 v4, v3
	s_nop 0
	v_add_u32_e32 v16, -1, v4
	v_fma_f32 v17, -v16, v4, v3
	v_cmp_ge_f32_e64 s[0:1], 0, v17
	v_add_u32_e32 v17, 1, v4
	s_nop 0
	v_cndmask_b32_e64 v16, v4, v16, s[0:1]
	v_fma_f32 v4, -v17, v4, v3
	v_cmp_lt_f32_e64 s[0:1], 0, v4
	s_nop 1
	v_cndmask_b32_e64 v4, v16, v17, s[0:1]
	v_mul_f32_e32 v16, 0x37800000, v4
	v_cndmask_b32_e32 v4, v4, v16, vcc
	v_cmp_class_f32_e32 vcc, v3, v193
	s_nop 1
	v_cndmask_b32_e32 v3, v4, v3, vcc
	v_cmp_ngt_f32_e32 vcc, s23, v0
	s_nop 1
	v_cndmask_b32_e32 v0, 1.0, v3, vcc
	v_mul_f32_e32 v0, v1, v0
	v_mul_f32_e32 v0, v71, v0
	ds_write_b32 v73, v2 offset:2176
	ds_write_b32 v73, v0 offset:39040
	v_add_f32_e32 v0, v21, v36
	v_mul_f32_e32 v0, 0xbfb8aa3b, v0
	v_exp_f32_e32 v0, v0
	v_add_f32_e32 v1, v5, v38
	v_mul_f32_e32 v1, 0xbfb8aa3b, v1
	v_exp_f32_e32 v1, v1
	v_add_f32_e32 v0, 1.0, v0
	v_rcp_f32_e32 v0, v0
	v_add_f32_e32 v1, 1.0, v1
	v_rcp_f32_e32 v1, v1
	v_mul_f32_e32 v0, v0, v32
	v_mul_f32_e32 v2, 0x3fb8aa3b, v0
	v_add_f32_e32 v0, v0, v0
	v_mul_f32_e32 v3, 0x3fb8aa3b, v0
	v_rndne_f32_e32 v3, v3
	v_fmamk_f32 v4, v3, 0xbf317218, v0
	v_fmac_f32_e32 v4, 0x3102e308, v3
	v_fmamk_f32 v5, v4, 0x395133b1, v192
	v_cmp_eq_f32_e32 vcc, s20, v3
	v_cvt_i32_f32_e32 v3, v3
	v_fmaak_f32 v5, v4, v5, 0x3c0887f9
	v_fmaak_f32 v5, v4, v5, 0x3d2aaa81
	v_fmaak_f32 v5, v4, v5, 0x3e2aaaab
	v_fma_f32 v5, v4, v5, 0.5
	v_ldexp_f32 v3, 1.0, v3
	v_mul_f32_e32 v5, v4, v5
	v_cndmask_b32_e32 v3, v3, v202, vcc
	v_fmac_f32_e32 v4, v4, v5
	v_add_f32_e32 v5, -1.0, v3
	v_fmac_f32_e32 v5, v3, v4
	v_add_f32_e32 v3, v5, v5
	v_cndmask_b32_e32 v3, v5, v3, vcc
	v_cmp_nlt_f32_e32 vcc, s21, v0
	v_exp_f32_e32 v2, v2
	s_nop 0
	v_cndmask_b32_e64 v3, v201, -v3, vcc
	v_cmp_gt_f32_e32 vcc, s22, v3
	v_mul_f32_e32 v4, 0x4f800000, v3
	s_nop 0
	v_cndmask_b32_e32 v3, v3, v4, vcc
	v_sqrt_f32_e32 v4, v3
	s_nop 0
	v_add_u32_e32 v5, -1, v4
	v_fma_f32 v16, -v5, v4, v3
	v_cmp_ge_f32_e64 s[0:1], 0, v16
	v_add_u32_e32 v16, 1, v4
	s_nop 0
	v_cndmask_b32_e64 v5, v4, v5, s[0:1]
	v_fma_f32 v4, -v16, v4, v3
	v_cmp_lt_f32_e64 s[0:1], 0, v4
	s_nop 1
	v_cndmask_b32_e64 v4, v5, v16, s[0:1]
	v_mul_f32_e32 v5, 0x37800000, v4
	v_cndmask_b32_e32 v4, v4, v5, vcc
	v_cmp_class_f32_e32 vcc, v3, v193
	s_nop 1
	v_cndmask_b32_e32 v3, v4, v3, vcc
	v_cmp_ngt_f32_e32 vcc, s23, v0
	s_nop 1
	v_cndmask_b32_e32 v0, 1.0, v3, vcc
	v_mul_f32_e32 v0, v1, v0
	v_mul_f32_e32 v0, v37, v0
	ds_write_b32 v73, v2 offset:2432
	ds_write_b32 v73, v0 offset:39296
	v_add_f32_e32 v0, v22, v36
	v_mul_f32_e32 v0, 0xbfb8aa3b, v0
	v_exp_f32_e32 v0, v0
	v_add_f32_e32 v1, v6, v38
	v_mul_f32_e32 v1, 0xbfb8aa3b, v1
	v_exp_f32_e32 v1, v1
	v_add_f32_e32 v0, 1.0, v0
	v_rcp_f32_e32 v0, v0
	v_add_f32_e32 v1, 1.0, v1
	v_rcp_f32_e32 v1, v1
	v_mul_f32_e32 v0, v0, v32
	v_mul_f32_e32 v2, 0x3fb8aa3b, v0
	v_add_f32_e32 v0, v0, v0
	v_mul_f32_e32 v3, 0x3fb8aa3b, v0
	v_rndne_f32_e32 v3, v3
	v_fmamk_f32 v4, v3, 0xbf317218, v0
	v_fmac_f32_e32 v4, 0x3102e308, v3
	v_fmamk_f32 v5, v4, 0x395133b1, v192
	v_cmp_eq_f32_e32 vcc, s20, v3
	v_cvt_i32_f32_e32 v3, v3
	v_fmaak_f32 v5, v4, v5, 0x3c0887f9
	v_fmaak_f32 v5, v4, v5, 0x3d2aaa81
	v_fmaak_f32 v5, v4, v5, 0x3e2aaaab
	v_fma_f32 v5, v4, v5, 0.5
	v_ldexp_f32 v3, 1.0, v3
	v_mul_f32_e32 v5, v4, v5
	v_cndmask_b32_e32 v3, v3, v202, vcc
	v_fmac_f32_e32 v4, v4, v5
	v_add_f32_e32 v5, -1.0, v3
	v_fmac_f32_e32 v5, v3, v4
	v_add_f32_e32 v3, v5, v5
	v_cndmask_b32_e32 v3, v5, v3, vcc
	v_cmp_nlt_f32_e32 vcc, s21, v0
	v_exp_f32_e32 v2, v2
	s_nop 0
	v_cndmask_b32_e64 v3, v201, -v3, vcc
	v_cmp_gt_f32_e32 vcc, s22, v3
	v_mul_f32_e32 v4, 0x4f800000, v3
	s_nop 0
	v_cndmask_b32_e32 v3, v3, v4, vcc
	v_sqrt_f32_e32 v4, v3
	s_nop 0
	v_add_u32_e32 v5, -1, v4
	v_fma_f32 v6, -v5, v4, v3
	v_cmp_ge_f32_e64 s[0:1], 0, v6
	v_add_u32_e32 v6, 1, v4
	s_nop 0
	v_cndmask_b32_e64 v5, v4, v5, s[0:1]
	v_fma_f32 v4, -v6, v4, v3
	v_cmp_lt_f32_e64 s[0:1], 0, v4
	s_nop 1
	v_cndmask_b32_e64 v4, v5, v6, s[0:1]
	v_mul_f32_e32 v5, 0x37800000, v4
	v_cndmask_b32_e32 v4, v4, v5, vcc
	v_cmp_class_f32_e32 vcc, v3, v193
	s_nop 1
	v_cndmask_b32_e32 v3, v4, v3, vcc
	v_cmp_ngt_f32_e32 vcc, s23, v0
	s_nop 1
	v_cndmask_b32_e32 v0, 1.0, v3, vcc
	v_mul_f32_e32 v0, v1, v0
	v_mul_f32_e32 v0, v53, v0
	ds_write_b32 v73, v2 offset:2688
	ds_write_b32 v73, v0 offset:39552
	v_add_f32_e32 v0, v23, v36
	v_mul_f32_e32 v0, 0xbfb8aa3b, v0
	v_exp_f32_e32 v0, v0
	v_add_f32_e32 v1, v7, v38
	v_mul_f32_e32 v1, 0xbfb8aa3b, v1
	v_exp_f32_e32 v1, v1
	v_add_f32_e32 v0, 1.0, v0
	v_rcp_f32_e32 v0, v0
	v_add_f32_e32 v1, 1.0, v1
	v_rcp_f32_e32 v1, v1
	v_mul_f32_e32 v0, v0, v32
	v_mul_f32_e32 v2, 0x3fb8aa3b, v0
	v_add_f32_e32 v0, v0, v0
	v_mul_f32_e32 v3, 0x3fb8aa3b, v0
	v_rndne_f32_e32 v3, v3
	v_fmamk_f32 v4, v3, 0xbf317218, v0
	v_fmac_f32_e32 v4, 0x3102e308, v3
	v_fmamk_f32 v5, v4, 0x395133b1, v192
	v_cmp_eq_f32_e32 vcc, s20, v3
	v_cvt_i32_f32_e32 v3, v3
	v_fmaak_f32 v5, v4, v5, 0x3c0887f9
	v_fmaak_f32 v5, v4, v5, 0x3d2aaa81
	v_fmaak_f32 v5, v4, v5, 0x3e2aaaab
	v_fma_f32 v5, v4, v5, 0.5
	v_ldexp_f32 v3, 1.0, v3
	v_mul_f32_e32 v5, v4, v5
	v_cndmask_b32_e32 v3, v3, v202, vcc
	v_fmac_f32_e32 v4, v4, v5
	v_add_f32_e32 v5, -1.0, v3
	v_fmac_f32_e32 v5, v3, v4
	v_add_f32_e32 v3, v5, v5
	v_cndmask_b32_e32 v3, v5, v3, vcc
	v_cmp_nlt_f32_e32 vcc, s21, v0
	v_exp_f32_e32 v2, v2
	s_nop 0
	v_cndmask_b32_e64 v3, v201, -v3, vcc
	v_cmp_gt_f32_e32 vcc, s22, v3
	v_mul_f32_e32 v4, 0x4f800000, v3
	s_nop 0
	v_cndmask_b32_e32 v3, v3, v4, vcc
	v_sqrt_f32_e32 v4, v3
	s_nop 0
	v_add_u32_e32 v5, -1, v4
	v_fma_f32 v6, -v5, v4, v3
	v_cmp_ge_f32_e64 s[0:1], 0, v6
	v_add_u32_e32 v6, 1, v4
	s_nop 0
	v_cndmask_b32_e64 v5, v4, v5, s[0:1]
	v_fma_f32 v4, -v6, v4, v3
	v_cmp_lt_f32_e64 s[0:1], 0, v4
	s_nop 1
	v_cndmask_b32_e64 v4, v5, v6, s[0:1]
	v_mul_f32_e32 v5, 0x37800000, v4
	v_cndmask_b32_e32 v4, v4, v5, vcc
	v_cmp_class_f32_e32 vcc, v3, v193
	s_nop 1
	v_cndmask_b32_e32 v3, v4, v3, vcc
	v_cmp_ngt_f32_e32 vcc, s23, v0
	s_nop 1
	v_cndmask_b32_e32 v0, 1.0, v3, vcc
	v_mul_f32_e32 v0, v1, v0
	v_mul_f32_e32 v0, v39, v0
	ds_write_b32 v73, v2 offset:2944
	ds_write_b32 v73, v0 offset:39808
	v_add_f32_e32 v0, v24, v36
	v_mul_f32_e32 v0, 0xbfb8aa3b, v0
	v_exp_f32_e32 v0, v0
	v_add_f32_e32 v1, v8, v38
	v_mul_f32_e32 v1, 0xbfb8aa3b, v1
	v_exp_f32_e32 v1, v1
	v_add_f32_e32 v0, 1.0, v0
	v_rcp_f32_e32 v0, v0
	v_add_f32_e32 v1, 1.0, v1
	v_rcp_f32_e32 v1, v1
	v_mul_f32_e32 v0, v0, v32
	v_mul_f32_e32 v2, 0x3fb8aa3b, v0
	v_add_f32_e32 v0, v0, v0
	v_mul_f32_e32 v3, 0x3fb8aa3b, v0
	v_rndne_f32_e32 v3, v3
	v_fmamk_f32 v4, v3, 0xbf317218, v0
	v_fmac_f32_e32 v4, 0x3102e308, v3
	v_fmamk_f32 v5, v4, 0x395133b1, v192
	v_cmp_eq_f32_e32 vcc, s20, v3
	v_cvt_i32_f32_e32 v3, v3
	v_fmaak_f32 v5, v4, v5, 0x3c0887f9
	v_fmaak_f32 v5, v4, v5, 0x3d2aaa81
	v_fmaak_f32 v5, v4, v5, 0x3e2aaaab
	v_fma_f32 v5, v4, v5, 0.5
	v_ldexp_f32 v3, 1.0, v3
	v_mul_f32_e32 v5, v4, v5
	v_cndmask_b32_e32 v3, v3, v202, vcc
	v_fmac_f32_e32 v4, v4, v5
	v_add_f32_e32 v5, -1.0, v3
	v_fmac_f32_e32 v5, v3, v4
	v_add_f32_e32 v3, v5, v5
	v_cndmask_b32_e32 v3, v5, v3, vcc
	v_cmp_nlt_f32_e32 vcc, s21, v0
	v_exp_f32_e32 v2, v2
	s_nop 0
	v_cndmask_b32_e64 v3, v201, -v3, vcc
	v_cmp_gt_f32_e32 vcc, s22, v3
	v_mul_f32_e32 v4, 0x4f800000, v3
	s_nop 0
	v_cndmask_b32_e32 v3, v3, v4, vcc
	v_sqrt_f32_e32 v4, v3
	s_nop 0
	v_add_u32_e32 v5, -1, v4
	v_fma_f32 v6, -v5, v4, v3
	v_cmp_ge_f32_e64 s[0:1], 0, v6
	v_add_u32_e32 v6, 1, v4
	s_nop 0
	v_cndmask_b32_e64 v5, v4, v5, s[0:1]
	v_fma_f32 v4, -v6, v4, v3
	v_cmp_lt_f32_e64 s[0:1], 0, v4
	s_nop 1
	v_cndmask_b32_e64 v4, v5, v6, s[0:1]
	v_mul_f32_e32 v5, 0x37800000, v4
	v_cndmask_b32_e32 v4, v4, v5, vcc
	v_cmp_class_f32_e32 vcc, v3, v193
	s_nop 1
	v_cndmask_b32_e32 v3, v4, v3, vcc
	v_cmp_ngt_f32_e32 vcc, s23, v0
	s_nop 1
	v_cndmask_b32_e32 v0, 1.0, v3, vcc
	v_mul_f32_e32 v0, v1, v0
	v_mul_f32_e32 v0, v55, v0
	ds_write_b32 v73, v2 offset:4224
	ds_write_b32 v73, v0 offset:41088
	v_add_f32_e32 v0, v25, v36
	v_mul_f32_e32 v0, 0xbfb8aa3b, v0
	v_exp_f32_e32 v0, v0
	v_add_f32_e32 v1, v9, v38
	v_mul_f32_e32 v1, 0xbfb8aa3b, v1
	v_exp_f32_e32 v1, v1
	v_add_f32_e32 v0, 1.0, v0
	v_rcp_f32_e32 v0, v0
	v_add_f32_e32 v1, 1.0, v1
	v_rcp_f32_e32 v1, v1
	v_mul_f32_e32 v0, v0, v32
	v_mul_f32_e32 v2, 0x3fb8aa3b, v0
	v_add_f32_e32 v0, v0, v0
	v_mul_f32_e32 v3, 0x3fb8aa3b, v0
	v_rndne_f32_e32 v3, v3
	v_fmamk_f32 v4, v3, 0xbf317218, v0
	v_fmac_f32_e32 v4, 0x3102e308, v3
	v_fmamk_f32 v5, v4, 0x395133b1, v192
	v_cmp_eq_f32_e32 vcc, s20, v3
	v_cvt_i32_f32_e32 v3, v3
	v_fmaak_f32 v5, v4, v5, 0x3c0887f9
	v_fmaak_f32 v5, v4, v5, 0x3d2aaa81
	v_fmaak_f32 v5, v4, v5, 0x3e2aaaab
	v_fma_f32 v5, v4, v5, 0.5
	v_ldexp_f32 v3, 1.0, v3
	v_mul_f32_e32 v5, v4, v5
	v_cndmask_b32_e32 v3, v3, v202, vcc
	v_fmac_f32_e32 v4, v4, v5
	v_add_f32_e32 v5, -1.0, v3
	v_fmac_f32_e32 v5, v3, v4
	v_add_f32_e32 v3, v5, v5
	v_cndmask_b32_e32 v3, v5, v3, vcc
	v_cmp_nlt_f32_e32 vcc, s21, v0
	v_exp_f32_e32 v2, v2
	s_nop 0
	v_cndmask_b32_e64 v3, v201, -v3, vcc
	v_cmp_gt_f32_e32 vcc, s22, v3
	v_mul_f32_e32 v4, 0x4f800000, v3
	s_nop 0
	v_cndmask_b32_e32 v3, v3, v4, vcc
	v_sqrt_f32_e32 v4, v3
	s_nop 0
	v_add_u32_e32 v5, -1, v4
	v_fma_f32 v6, -v5, v4, v3
	v_cmp_ge_f32_e64 s[0:1], 0, v6
	v_add_u32_e32 v6, 1, v4
	s_nop 0
	v_cndmask_b32_e64 v5, v4, v5, s[0:1]
	v_fma_f32 v4, -v6, v4, v3
	v_cmp_lt_f32_e64 s[0:1], 0, v4
	s_nop 1
	v_cndmask_b32_e64 v4, v5, v6, s[0:1]
	v_mul_f32_e32 v5, 0x37800000, v4
	v_cndmask_b32_e32 v4, v4, v5, vcc
	v_cmp_class_f32_e32 vcc, v3, v193
	s_nop 1
	v_cndmask_b32_e32 v3, v4, v3, vcc
	v_cmp_ngt_f32_e32 vcc, s23, v0
	s_nop 1
	v_cndmask_b32_e32 v0, 1.0, v3, vcc
	v_mul_f32_e32 v0, v1, v0
	v_mul_f32_e32 v0, v41, v0
	ds_write_b32 v73, v2 offset:4480
	ds_write_b32 v73, v0 offset:41344
	v_add_f32_e32 v0, v26, v36
	v_mul_f32_e32 v0, 0xbfb8aa3b, v0
	v_exp_f32_e32 v0, v0
	v_add_f32_e32 v1, v10, v38
	v_mul_f32_e32 v1, 0xbfb8aa3b, v1
	v_exp_f32_e32 v1, v1
	v_add_f32_e32 v0, 1.0, v0
	v_rcp_f32_e32 v0, v0
	v_add_f32_e32 v1, 1.0, v1
	v_rcp_f32_e32 v1, v1
	v_mul_f32_e32 v0, v0, v32
	v_mul_f32_e32 v2, 0x3fb8aa3b, v0
	v_add_f32_e32 v0, v0, v0
	v_mul_f32_e32 v3, 0x3fb8aa3b, v0
	v_rndne_f32_e32 v3, v3
	v_fmamk_f32 v4, v3, 0xbf317218, v0
	v_fmac_f32_e32 v4, 0x3102e308, v3
	v_fmamk_f32 v5, v4, 0x395133b1, v192
	v_cmp_eq_f32_e32 vcc, s20, v3
	v_cvt_i32_f32_e32 v3, v3
	v_fmaak_f32 v5, v4, v5, 0x3c0887f9
	v_fmaak_f32 v5, v4, v5, 0x3d2aaa81
	v_fmaak_f32 v5, v4, v5, 0x3e2aaaab
	v_fma_f32 v5, v4, v5, 0.5
	v_ldexp_f32 v3, 1.0, v3
	v_mul_f32_e32 v5, v4, v5
	v_cndmask_b32_e32 v3, v3, v202, vcc
	v_fmac_f32_e32 v4, v4, v5
	v_add_f32_e32 v5, -1.0, v3
	v_fmac_f32_e32 v5, v3, v4
	v_add_f32_e32 v3, v5, v5
	v_cndmask_b32_e32 v3, v5, v3, vcc
	v_cmp_nlt_f32_e32 vcc, s21, v0
	v_exp_f32_e32 v2, v2
	s_nop 0
	v_cndmask_b32_e64 v3, v201, -v3, vcc
	v_cmp_gt_f32_e32 vcc, s22, v3
	v_mul_f32_e32 v4, 0x4f800000, v3
	s_nop 0
	v_cndmask_b32_e32 v3, v3, v4, vcc
	v_sqrt_f32_e32 v4, v3
	s_nop 0
	v_add_u32_e32 v5, -1, v4
	v_fma_f32 v6, -v5, v4, v3
	v_cmp_ge_f32_e64 s[0:1], 0, v6
	v_add_u32_e32 v6, 1, v4
	s_nop 0
	v_cndmask_b32_e64 v5, v4, v5, s[0:1]
	v_fma_f32 v4, -v6, v4, v3
	v_cmp_lt_f32_e64 s[0:1], 0, v4
	s_nop 1
	v_cndmask_b32_e64 v4, v5, v6, s[0:1]
	v_mul_f32_e32 v5, 0x37800000, v4
	v_cndmask_b32_e32 v4, v4, v5, vcc
	v_cmp_class_f32_e32 vcc, v3, v193
	s_nop 1
	v_cndmask_b32_e32 v3, v4, v3, vcc
	v_cmp_ngt_f32_e32 vcc, s23, v0
	s_nop 1
	v_cndmask_b32_e32 v0, 1.0, v3, vcc
	v_mul_f32_e32 v0, v1, v0
	v_mul_f32_e32 v0, v57, v0
	ds_write_b32 v73, v2 offset:4736
	ds_write_b32 v73, v0 offset:41600
	v_add_f32_e32 v0, v27, v36
	v_mul_f32_e32 v0, 0xbfb8aa3b, v0
	v_exp_f32_e32 v0, v0
	v_add_f32_e32 v1, v11, v38
	v_mul_f32_e32 v1, 0xbfb8aa3b, v1
	v_exp_f32_e32 v1, v1
	v_add_f32_e32 v0, 1.0, v0
	v_rcp_f32_e32 v0, v0
	v_add_f32_e32 v1, 1.0, v1
	v_rcp_f32_e32 v1, v1
	v_mul_f32_e32 v0, v0, v32
	v_mul_f32_e32 v2, 0x3fb8aa3b, v0
	v_add_f32_e32 v0, v0, v0
	v_mul_f32_e32 v3, 0x3fb8aa3b, v0
	v_rndne_f32_e32 v3, v3
	v_fmamk_f32 v4, v3, 0xbf317218, v0
	v_fmac_f32_e32 v4, 0x3102e308, v3
	v_fmamk_f32 v5, v4, 0x395133b1, v192
	v_cmp_eq_f32_e32 vcc, s20, v3
	v_cvt_i32_f32_e32 v3, v3
	v_fmaak_f32 v5, v4, v5, 0x3c0887f9
	v_fmaak_f32 v5, v4, v5, 0x3d2aaa81
	v_fmaak_f32 v5, v4, v5, 0x3e2aaaab
	v_fma_f32 v5, v4, v5, 0.5
	v_ldexp_f32 v3, 1.0, v3
	v_mul_f32_e32 v5, v4, v5
	v_cndmask_b32_e32 v3, v3, v202, vcc
	v_fmac_f32_e32 v4, v4, v5
	v_add_f32_e32 v5, -1.0, v3
	v_fmac_f32_e32 v5, v3, v4
	v_add_f32_e32 v3, v5, v5
	v_cndmask_b32_e32 v3, v5, v3, vcc
	v_cmp_nlt_f32_e32 vcc, s21, v0
	v_exp_f32_e32 v2, v2
	s_nop 0
	v_cndmask_b32_e64 v3, v201, -v3, vcc
	v_cmp_gt_f32_e32 vcc, s22, v3
	v_mul_f32_e32 v4, 0x4f800000, v3
	s_nop 0
	v_cndmask_b32_e32 v3, v3, v4, vcc
	v_sqrt_f32_e32 v4, v3
	s_nop 0
	v_add_u32_e32 v5, -1, v4
	v_fma_f32 v6, -v5, v4, v3
	v_cmp_ge_f32_e64 s[0:1], 0, v6
	v_add_u32_e32 v6, 1, v4
	s_nop 0
	v_cndmask_b32_e64 v5, v4, v5, s[0:1]
	v_fma_f32 v4, -v6, v4, v3
	v_cmp_lt_f32_e64 s[0:1], 0, v4
	s_nop 1
	v_cndmask_b32_e64 v4, v5, v6, s[0:1]
	v_mul_f32_e32 v5, 0x37800000, v4
	v_cndmask_b32_e32 v4, v4, v5, vcc
	v_cmp_class_f32_e32 vcc, v3, v193
	s_nop 1
	v_cndmask_b32_e32 v3, v4, v3, vcc
	v_cmp_ngt_f32_e32 vcc, s23, v0
	s_nop 1
	v_cndmask_b32_e32 v0, 1.0, v3, vcc
	v_mul_f32_e32 v0, v1, v0
	v_mul_f32_e32 v0, v43, v0
	ds_write_b32 v73, v2 offset:4992
	ds_write_b32 v73, v0 offset:41856
	v_add_f32_e32 v0, v28, v36
	v_mul_f32_e32 v0, 0xbfb8aa3b, v0
	v_exp_f32_e32 v0, v0
	v_add_f32_e32 v1, v12, v38
	v_mul_f32_e32 v1, 0xbfb8aa3b, v1
	v_exp_f32_e32 v1, v1
	v_add_f32_e32 v0, 1.0, v0
	v_rcp_f32_e32 v0, v0
	v_add_f32_e32 v1, 1.0, v1
	v_rcp_f32_e32 v1, v1
	v_mul_f32_e32 v0, v0, v32
	v_mul_f32_e32 v2, 0x3fb8aa3b, v0
	v_add_f32_e32 v0, v0, v0
	v_mul_f32_e32 v3, 0x3fb8aa3b, v0
	v_rndne_f32_e32 v3, v3
	v_fmamk_f32 v4, v3, 0xbf317218, v0
	v_fmac_f32_e32 v4, 0x3102e308, v3
	v_fmamk_f32 v5, v4, 0x395133b1, v192
	v_cmp_eq_f32_e32 vcc, s20, v3
	v_cvt_i32_f32_e32 v3, v3
	v_fmaak_f32 v5, v4, v5, 0x3c0887f9
	v_fmaak_f32 v5, v4, v5, 0x3d2aaa81
	v_fmaak_f32 v5, v4, v5, 0x3e2aaaab
	v_fma_f32 v5, v4, v5, 0.5
	v_ldexp_f32 v3, 1.0, v3
	v_mul_f32_e32 v5, v4, v5
	v_cndmask_b32_e32 v3, v3, v202, vcc
	v_fmac_f32_e32 v4, v4, v5
	v_add_f32_e32 v5, -1.0, v3
	v_fmac_f32_e32 v5, v3, v4
	v_add_f32_e32 v3, v5, v5
	v_cndmask_b32_e32 v3, v5, v3, vcc
	v_cmp_nlt_f32_e32 vcc, s21, v0
	v_exp_f32_e32 v2, v2
	s_nop 0
	v_cndmask_b32_e64 v3, v201, -v3, vcc
	v_cmp_gt_f32_e32 vcc, s22, v3
	v_mul_f32_e32 v4, 0x4f800000, v3
	s_nop 0
	v_cndmask_b32_e32 v3, v3, v4, vcc
	v_sqrt_f32_e32 v4, v3
	s_nop 0
	v_add_u32_e32 v5, -1, v4
	v_fma_f32 v6, -v5, v4, v3
	v_cmp_ge_f32_e64 s[0:1], 0, v6
	v_add_u32_e32 v6, 1, v4
	s_nop 0
	v_cndmask_b32_e64 v5, v4, v5, s[0:1]
	v_fma_f32 v4, -v6, v4, v3
	v_cmp_lt_f32_e64 s[0:1], 0, v4
	s_nop 1
	v_cndmask_b32_e64 v4, v5, v6, s[0:1]
	v_mul_f32_e32 v5, 0x37800000, v4
	v_cndmask_b32_e32 v4, v4, v5, vcc
	v_cmp_class_f32_e32 vcc, v3, v193
	s_nop 1
	v_cndmask_b32_e32 v3, v4, v3, vcc
	v_cmp_ngt_f32_e32 vcc, s23, v0
	s_nop 1
	v_cndmask_b32_e32 v0, 1.0, v3, vcc
	v_mul_f32_e32 v0, v1, v0
	v_mul_f32_e32 v0, v59, v0
	ds_write_b32 v73, v2 offset:6272
	ds_write_b32 v73, v0 offset:43136
	v_add_f32_e32 v0, v29, v36
	v_mul_f32_e32 v0, 0xbfb8aa3b, v0
	v_exp_f32_e32 v0, v0
	v_add_f32_e32 v1, v13, v38
	v_mul_f32_e32 v1, 0xbfb8aa3b, v1
	v_exp_f32_e32 v1, v1
	v_add_f32_e32 v0, 1.0, v0
	v_rcp_f32_e32 v0, v0
	v_add_f32_e32 v1, 1.0, v1
	v_rcp_f32_e32 v1, v1
	v_mul_f32_e32 v0, v0, v32
	v_mul_f32_e32 v2, 0x3fb8aa3b, v0
	v_add_f32_e32 v0, v0, v0
	v_mul_f32_e32 v3, 0x3fb8aa3b, v0
	v_rndne_f32_e32 v3, v3
	v_fmamk_f32 v4, v3, 0xbf317218, v0
	v_fmac_f32_e32 v4, 0x3102e308, v3
	v_fmamk_f32 v5, v4, 0x395133b1, v192
	v_cmp_eq_f32_e32 vcc, s20, v3
	v_cvt_i32_f32_e32 v3, v3
	v_fmaak_f32 v5, v4, v5, 0x3c0887f9
	v_fmaak_f32 v5, v4, v5, 0x3d2aaa81
	v_fmaak_f32 v5, v4, v5, 0x3e2aaaab
	v_fma_f32 v5, v4, v5, 0.5
	v_ldexp_f32 v3, 1.0, v3
	v_mul_f32_e32 v5, v4, v5
	v_cndmask_b32_e32 v3, v3, v202, vcc
	v_fmac_f32_e32 v4, v4, v5
	v_add_f32_e32 v5, -1.0, v3
	v_fmac_f32_e32 v5, v3, v4
	v_add_f32_e32 v3, v5, v5
	v_cndmask_b32_e32 v3, v5, v3, vcc
	v_cmp_nlt_f32_e32 vcc, s21, v0
	v_exp_f32_e32 v2, v2
	s_nop 0
	v_cndmask_b32_e64 v3, v201, -v3, vcc
	v_cmp_gt_f32_e32 vcc, s22, v3
	v_mul_f32_e32 v4, 0x4f800000, v3
	s_nop 0
	v_cndmask_b32_e32 v3, v3, v4, vcc
	v_sqrt_f32_e32 v4, v3
	s_nop 0
	v_add_u32_e32 v5, -1, v4
	v_fma_f32 v6, -v5, v4, v3
	v_cmp_ge_f32_e64 s[0:1], 0, v6
	v_add_u32_e32 v6, 1, v4
	s_nop 0
	v_cndmask_b32_e64 v5, v4, v5, s[0:1]
	v_fma_f32 v4, -v6, v4, v3
	v_cmp_lt_f32_e64 s[0:1], 0, v4
	s_nop 1
	v_cndmask_b32_e64 v4, v5, v6, s[0:1]
	v_mul_f32_e32 v5, 0x37800000, v4
	v_cndmask_b32_e32 v4, v4, v5, vcc
	v_cmp_class_f32_e32 vcc, v3, v193
	s_nop 1
	v_cndmask_b32_e32 v3, v4, v3, vcc
	v_cmp_ngt_f32_e32 vcc, s23, v0
	s_nop 1
	v_cndmask_b32_e32 v0, 1.0, v3, vcc
	v_mul_f32_e32 v0, v1, v0
	v_mul_f32_e32 v0, v45, v0
	ds_write_b32 v73, v2 offset:6528
	ds_write_b32 v73, v0 offset:43392
	v_add_f32_e32 v0, v30, v36
	v_mul_f32_e32 v0, 0xbfb8aa3b, v0
	v_exp_f32_e32 v0, v0
	v_add_f32_e32 v1, v14, v38
	v_mul_f32_e32 v1, 0xbfb8aa3b, v1
	v_exp_f32_e32 v1, v1
	v_add_f32_e32 v0, 1.0, v0
	v_rcp_f32_e32 v0, v0
	v_add_f32_e32 v1, 1.0, v1
	v_rcp_f32_e32 v1, v1
	v_mul_f32_e32 v0, v0, v32
	v_mul_f32_e32 v2, 0x3fb8aa3b, v0
	v_add_f32_e32 v0, v0, v0
	v_mul_f32_e32 v3, 0x3fb8aa3b, v0
	v_rndne_f32_e32 v3, v3
	v_fmamk_f32 v4, v3, 0xbf317218, v0
	v_fmac_f32_e32 v4, 0x3102e308, v3
	v_fmamk_f32 v5, v4, 0x395133b1, v192
	v_cmp_eq_f32_e32 vcc, s20, v3
	v_cvt_i32_f32_e32 v3, v3
	v_fmaak_f32 v5, v4, v5, 0x3c0887f9
	v_fmaak_f32 v5, v4, v5, 0x3d2aaa81
	v_fmaak_f32 v5, v4, v5, 0x3e2aaaab
	v_fma_f32 v5, v4, v5, 0.5
	v_ldexp_f32 v3, 1.0, v3
	v_mul_f32_e32 v5, v4, v5
	v_cndmask_b32_e32 v3, v3, v202, vcc
	v_fmac_f32_e32 v4, v4, v5
	v_add_f32_e32 v5, -1.0, v3
	v_fmac_f32_e32 v5, v3, v4
	v_add_f32_e32 v3, v5, v5
	v_cndmask_b32_e32 v3, v5, v3, vcc
	v_cmp_nlt_f32_e32 vcc, s21, v0
	v_exp_f32_e32 v2, v2
	s_nop 0
	v_cndmask_b32_e64 v3, v201, -v3, vcc
	v_cmp_gt_f32_e32 vcc, s22, v3
	v_mul_f32_e32 v4, 0x4f800000, v3
	s_nop 0
	v_cndmask_b32_e32 v3, v3, v4, vcc
	v_sqrt_f32_e32 v4, v3
	s_nop 0
	v_add_u32_e32 v5, -1, v4
	v_fma_f32 v6, -v5, v4, v3
	v_cmp_ge_f32_e64 s[0:1], 0, v6
	v_add_u32_e32 v6, 1, v4
	s_nop 0
	v_cndmask_b32_e64 v5, v4, v5, s[0:1]
	v_fma_f32 v4, -v6, v4, v3
	v_cmp_lt_f32_e64 s[0:1], 0, v4
	s_nop 1
	v_cndmask_b32_e64 v4, v5, v6, s[0:1]
	v_mul_f32_e32 v5, 0x37800000, v4
	v_cndmask_b32_e32 v4, v4, v5, vcc
	v_cmp_class_f32_e32 vcc, v3, v193
	s_nop 1
	v_cndmask_b32_e32 v3, v4, v3, vcc
	v_cmp_ngt_f32_e32 vcc, s23, v0
	s_nop 1
	v_cndmask_b32_e32 v0, 1.0, v3, vcc
	v_mul_f32_e32 v0, v1, v0
	v_mul_f32_e32 v0, v35, v0
	v_add_u32_e32 v1, 0x1800, v73
	ds_write2_b32 v1, v2, v34 offset0:160 offset1:192
	ds_write_b32 v73, v0 offset:43648
	v_add_f32_e32 v0, v31, v36
	v_mul_f32_e32 v0, 0xbfb8aa3b, v0
	v_exp_f32_e32 v0, v0
	v_add_f32_e32 v1, v15, v38
	v_mul_f32_e32 v1, 0xbfb8aa3b, v1
	v_exp_f32_e32 v1, v1
	v_add_f32_e32 v0, 1.0, v0
	v_rcp_f32_e32 v0, v0
	v_add_f32_e32 v1, 1.0, v1
	v_rcp_f32_e32 v1, v1
	v_mul_f32_e32 v0, v0, v32
	v_mul_f32_e32 v2, 0x3fb8aa3b, v0
	v_add_f32_e32 v0, v0, v0
	v_mul_f32_e32 v3, 0x3fb8aa3b, v0
	v_rndne_f32_e32 v3, v3
	v_fmamk_f32 v4, v3, 0xbf317218, v0
	v_fmac_f32_e32 v4, 0x3102e308, v3
	v_fmamk_f32 v5, v4, 0x395133b1, v192
	v_cmp_eq_f32_e32 vcc, s20, v3
	v_cvt_i32_f32_e32 v3, v3
	v_fmaak_f32 v5, v4, v5, 0x3c0887f9
	v_fmaak_f32 v5, v4, v5, 0x3d2aaa81
	v_fmaak_f32 v5, v4, v5, 0x3e2aaaab
	v_fma_f32 v5, v4, v5, 0.5
	v_ldexp_f32 v3, 1.0, v3
	v_mul_f32_e32 v5, v4, v5
	v_cndmask_b32_e32 v3, v3, v202, vcc
	v_fmac_f32_e32 v4, v4, v5
	v_add_f32_e32 v5, -1.0, v3
	v_fmac_f32_e32 v5, v3, v4
	v_add_f32_e32 v3, v5, v5
	v_cndmask_b32_e32 v3, v5, v3, vcc
	v_cmp_nlt_f32_e32 vcc, s21, v0
	v_exp_f32_e32 v2, v2
	s_nop 0
	v_cndmask_b32_e64 v3, v201, -v3, vcc
	v_cmp_gt_f32_e32 vcc, s22, v3
	v_mul_f32_e32 v4, 0x4f800000, v3
	s_nop 0
	v_cndmask_b32_e32 v3, v3, v4, vcc
	v_sqrt_f32_e32 v4, v3
	s_nop 0
	v_add_u32_e32 v5, -1, v4
	v_fma_f32 v6, -v5, v4, v3
	v_cmp_ge_f32_e64 s[0:1], 0, v6
	v_add_u32_e32 v6, 1, v4
	s_nop 0
	v_cndmask_b32_e64 v5, v4, v5, s[0:1]
	v_fma_f32 v4, -v6, v4, v3
	v_cmp_lt_f32_e64 s[0:1], 0, v4
	s_nop 1
	v_cndmask_b32_e64 v4, v5, v6, s[0:1]
	v_mul_f32_e32 v5, 0x37800000, v4
	v_cndmask_b32_e32 v4, v4, v5, vcc
	v_cmp_class_f32_e32 vcc, v3, v193
	s_nop 1
	v_cndmask_b32_e32 v3, v4, v3, vcc
	v_cmp_ngt_f32_e32 vcc, s23, v0
	s_nop 1
	v_cndmask_b32_e32 v0, 1.0, v3, vcc
	v_mul_f32_e32 v0, v1, v0
	v_mul_f32_e32 v0, v33, v0
	ds_write_b32 v73, v2 offset:7040
	ds_write_b32 v73, v0 offset:43904
	s_waitcnt lgkmcnt(0)
	s_barrier
	s_cbranch_scc1 .LBB0_866
	v_lshl_add_u64 v[0:1], v[64:65], 0, s[4:5]
	global_load_dwordx2 v[98:99], v[0:1], off
	s_cmp_eq_u32 s12, 1
	s_waitcnt vmcnt(0)
	v_fmac_f32_e32 v99, 0, v98
	s_cbranch_scc1 .LBB0_867
	v_add_co_u32_e32 v0, vcc, 0x1000, v0
	s_cmp_eq_u32 s12, 2
	s_nop 0
	v_addc_co_u32_e32 v1, vcc, 0, v1, vcc
	global_load_dwordx2 v[0:1], v[0:1], off
	s_waitcnt vmcnt(0)
	v_fmac_f32_e32 v1, v99, v0
	s_cbranch_scc1 .LBB0_865
	v_readlane_b32 s0, v248, 32
	s_mul_i32 s46, s11, 36
	s_add_i32 s0, s0, s75
	s_mov_b32 s47, s5
	s_sub_i32 s0, s0, s70
	s_lshl_b64 s[44:45], s[46:47], 12
	v_readlane_b32 s1, v249, 45
	s_add_u32 s44, s1, s44
	v_readlane_b32 s1, v249, 46
	v_add_lshl_u32 v96, s13, v141, 3
	s_addc_u32 s45, s1, s45
	v_lshl_add_u64 v[2:3], s[44:45], 0, v[96:97]
	s_mov_b64 s[8:9], 0x1000

.Lrg36_i:
	s_or_b64 exec, exec, s[0:1]
	s_waitcnt vmcnt(0)
	s_nop 0
	v_mov_b32_e32 v9, v207
	v_mov_b32_e32 v10, v208
	v_mov_b32_e32 v11, v209
	v_lshlrev_b32_e32 v54, 16, v206
	v_and_b32_e32 v55, 0xffff0000, v206
	v_lshlrev_b32_e32 v8, 16, v9
	v_and_b32_e32 v9, 0xffff0000, v9
	v_lshlrev_b32_e32 v12, 16, v10
	v_and_b32_e32 v13, 0xffff0000, v10
	v_lshlrev_b32_e32 v10, 16, v11
	v_and_b32_e32 v11, 0xffff0000, v11
	v_pk_fma_f32 v[14:15], v[46:47], v[10:11], v[6:7]
	v_pk_fma_f32 v[12:13], v[44:45], v[12:13], v[4:5]
	v_pk_fma_f32 v[10:11], v[42:43], v[8:9], v[2:3]
	v_pk_fma_f32 v[8:9], v[40:41], v[54:55], v[0:1]
	v_mov_b32_e32 v55, v211
	v_mov_b32_e32 v56, v212
	v_mov_b32_e32 v57, v213
	v_lshlrev_b32_e32 v58, 16, v210
	v_and_b32_e32 v59, 0xffff0000, v210
	v_lshlrev_b32_e32 v54, 16, v55
	v_and_b32_e32 v55, 0xffff0000, v55
	v_lshlrev_b32_e32 v60, 16, v56
	v_and_b32_e32 v61, 0xffff0000, v56
	v_lshlrev_b32_e32 v56, 16, v57
	v_and_b32_e32 v57, 0xffff0000, v57
	v_pk_fma_f32 v[14:15], v[38:39], v[56:57], v[14:15]
	v_pk_fma_f32 v[12:13], v[36:37], v[60:61], v[12:13]
	v_pk_fma_f32 v[10:11], v[34:35], v[54:55], v[10:11]
	v_pk_fma_f32 v[8:9], v[32:33], v[58:59], v[8:9]
	v_mov_b32_e32 v55, v215
	v_mov_b32_e32 v56, v216
	v_mov_b32_e32 v57, v217
	v_lshlrev_b32_e32 v58, 16, v214
	v_and_b32_e32 v59, 0xffff0000, v214
	v_lshlrev_b32_e32 v54, 16, v55
	v_and_b32_e32 v55, 0xffff0000, v55
	v_lshlrev_b32_e32 v60, 16, v56
	v_and_b32_e32 v61, 0xffff0000, v56
	v_lshlrev_b32_e32 v56, 16, v57
	v_and_b32_e32 v57, 0xffff0000, v57
	v_pk_fma_f32 v[14:15], v[30:31], v[56:57], v[14:15]
	v_pk_fma_f32 v[12:13], v[28:29], v[60:61], v[12:13]
	v_pk_fma_f32 v[10:11], v[26:27], v[54:55], v[10:11]
	v_pk_fma_f32 v[8:9], v[24:25], v[58:59], v[8:9]
	v_mov_b32_e32 v55, v219
	v_mov_b32_e32 v56, v220
	v_mov_b32_e32 v57, v221
	v_lshlrev_b32_e32 v58, 16, v218
	v_and_b32_e32 v59, 0xffff0000, v218
	v_lshlrev_b32_e32 v54, 16, v55
	v_and_b32_e32 v55, 0xffff0000, v55
	v_lshlrev_b32_e32 v60, 16, v56
	v_and_b32_e32 v61, 0xffff0000, v56
	v_lshlrev_b32_e32 v56, 16, v57
	v_and_b32_e32 v57, 0xffff0000, v57
	v_pk_fma_f32 v[14:15], v[22:23], v[56:57], v[14:15]
	v_pk_fma_f32 v[12:13], v[20:21], v[60:61], v[12:13]
	v_pk_fma_f32 v[10:11], v[18:19], v[54:55], v[10:11]
	v_pk_fma_f32 v[8:9], v[16:17], v[58:59], v[8:9]
	v_lshl_add_u32 v53, v50, 2, 0
	v_lshl_add_u32 v54, v52, 8, v53
	v_lshlrev_b32_e32 v50, 1, v50
	ds_write_b128 v54, v[8:11] offset:36864
	ds_write_b128 v54, v[12:15] offset:36880
	v_add_u32_e32 v54, 32, v52
	v_sub_u32_e32 v50, v53, v50
	v_add_u32_e32 v55, s68, v54
	v_cvt_pk_bf16_f32 v8, v8, v9
	v_cvt_pk_bf16_f32 v9, v10, v11
	v_cvt_pk_bf16_f32 v10, v12, v13
	v_cvt_pk_bf16_f32 v11, v14, v15
	v_mad_u64_u32 v[12:13], s[0:1], v52, s8, v[50:51]
	v_add_u32_e32 v56, -2, v55
	ds_write_b128 v12, v[8:11]
	v_cmp_lt_i32_e32 vcc, 1, v55
	v_cmp_gt_u32_e64 s[0:1], s39, v56
	v_mov_b64_e32 v[14:15], v[6:7]
	s_and_b64 s[2:3], vcc, s[0:1]
	v_mov_b64_e32 v[12:13], v[4:5]
	v_mov_b64_e32 v[10:11], v[2:3]
	v_mov_b64_e32 v[8:9], v[0:1]
	v_mov_b32_e32 v206, 0
	v_mov_b32_e32 v207, 0
	v_mov_b32_e32 v208, 0
	v_mov_b32_e32 v209, 0
	s_and_saveexec_b64 s[0:1], s[2:3]
	s_cbranch_execz .Lrg37_i
	v_add_u32_e32 v8, s38, v56
	v_mad_u64_u32 v[8:9], s[2:3], v8, s74, v[48:49]
	global_load_dwordx4 v[206:209], v[8:9], off

.Lrg40_i:
	s_or_b64 exec, exec, s[0:1]
	s_waitcnt vmcnt(0)
	s_nop 0
	v_mov_b32_e32 v9, v207
	v_mov_b32_e32 v10, v208
	v_mov_b32_e32 v11, v209
	v_lshlrev_b32_e32 v56, 16, v206
	v_and_b32_e32 v57, 0xffff0000, v206
	v_lshlrev_b32_e32 v8, 16, v9
	v_and_b32_e32 v9, 0xffff0000, v9
	v_lshlrev_b32_e32 v12, 16, v10
	v_and_b32_e32 v13, 0xffff0000, v10
	v_lshlrev_b32_e32 v10, 16, v11
	v_and_b32_e32 v11, 0xffff0000, v11
	v_pk_fma_f32 v[14:15], v[46:47], v[10:11], v[6:7]
	v_pk_fma_f32 v[12:13], v[44:45], v[12:13], v[4:5]
	v_pk_fma_f32 v[10:11], v[42:43], v[8:9], v[2:3]
	v_pk_fma_f32 v[8:9], v[40:41], v[56:57], v[0:1]
	v_mov_b32_e32 v57, v211
	v_mov_b32_e32 v58, v212
	v_mov_b32_e32 v59, v213
	v_lshlrev_b32_e32 v60, 16, v210
	v_and_b32_e32 v61, 0xffff0000, v210
	v_lshlrev_b32_e32 v56, 16, v57
	v_and_b32_e32 v57, 0xffff0000, v57
	v_lshlrev_b32_e32 v62, 16, v58
	v_and_b32_e32 v63, 0xffff0000, v58
	v_lshlrev_b32_e32 v58, 16, v59
	v_and_b32_e32 v59, 0xffff0000, v59
	v_pk_fma_f32 v[14:15], v[38:39], v[58:59], v[14:15]
	v_pk_fma_f32 v[12:13], v[36:37], v[62:63], v[12:13]
	v_pk_fma_f32 v[10:11], v[34:35], v[56:57], v[10:11]
	v_pk_fma_f32 v[8:9], v[32:33], v[60:61], v[8:9]
	v_mov_b32_e32 v57, v215
	v_mov_b32_e32 v58, v216
	v_mov_b32_e32 v59, v217
	v_lshlrev_b32_e32 v60, 16, v214
	v_and_b32_e32 v61, 0xffff0000, v214
	v_lshlrev_b32_e32 v56, 16, v57
	v_and_b32_e32 v57, 0xffff0000, v57
	v_lshlrev_b32_e32 v62, 16, v58
	v_and_b32_e32 v63, 0xffff0000, v58
	v_lshlrev_b32_e32 v58, 16, v59
	v_and_b32_e32 v59, 0xffff0000, v59
	v_pk_fma_f32 v[14:15], v[30:31], v[58:59], v[14:15]
	v_pk_fma_f32 v[12:13], v[28:29], v[62:63], v[12:13]
	v_pk_fma_f32 v[10:11], v[26:27], v[56:57], v[10:11]
	v_pk_fma_f32 v[8:9], v[24:25], v[60:61], v[8:9]
	v_mov_b32_e32 v57, v219
	v_mov_b32_e32 v58, v220
	v_mov_b32_e32 v59, v221
	v_lshlrev_b32_e32 v60, 16, v218
	v_and_b32_e32 v61, 0xffff0000, v218
	v_lshlrev_b32_e32 v56, 16, v57
	v_and_b32_e32 v57, 0xffff0000, v57
	v_lshlrev_b32_e32 v62, 16, v58
	v_and_b32_e32 v63, 0xffff0000, v58
	v_lshlrev_b32_e32 v58, 16, v59
	v_and_b32_e32 v59, 0xffff0000, v59
	v_pk_fma_f32 v[14:15], v[22:23], v[58:59], v[14:15]
	v_pk_fma_f32 v[12:13], v[20:21], v[62:63], v[12:13]
	v_pk_fma_f32 v[10:11], v[18:19], v[56:57], v[10:11]
	v_pk_fma_f32 v[8:9], v[16:17], v[60:61], v[8:9]
	v_lshl_add_u32 v55, v54, 8, v53
	ds_write_b128 v55, v[8:11] offset:36864
	ds_write_b128 v55, v[12:15] offset:36880
	v_cvt_pk_bf16_f32 v8, v8, v9
	v_cvt_pk_bf16_f32 v9, v10, v11
	v_cvt_pk_bf16_f32 v10, v12, v13
	v_mad_u64_u32 v[12:13], s[0:1], v54, s8, v[50:51]
	v_add_u32_e32 v54, 64, v52
	v_add_u32_e32 v55, s68, v54
	v_cvt_pk_bf16_f32 v11, v14, v15
	v_add_u32_e32 v56, -2, v55
	ds_write_b128 v12, v[8:11]
	v_cmp_lt_i32_e32 vcc, 1, v55
	v_cmp_gt_u32_e64 s[0:1], s39, v56
	v_mov_b64_e32 v[14:15], v[6:7]
	s_and_b64 s[2:3], vcc, s[0:1]
	v_mov_b64_e32 v[12:13], v[4:5]
	v_mov_b64_e32 v[10:11], v[2:3]
	v_mov_b64_e32 v[8:9], v[0:1]
	v_mov_b32_e32 v206, 0
	v_mov_b32_e32 v207, 0
	v_mov_b32_e32 v208, 0
	v_mov_b32_e32 v209, 0
	s_and_saveexec_b64 s[0:1], s[2:3]
	s_cbranch_execz .Lrg41_i
	v_add_u32_e32 v8, s38, v56
	v_mad_u64_u32 v[8:9], s[2:3], v8, s74, v[48:49]
	global_load_dwordx4 v[206:209], v[8:9], off

.Lrg44_i:
	s_or_b64 exec, exec, s[0:1]
	s_waitcnt vmcnt(0)
	s_nop 0
	v_mov_b32_e32 v9, v207
	v_mov_b32_e32 v10, v208
	v_mov_b32_e32 v11, v209
	v_lshlrev_b32_e32 v56, 16, v206
	v_and_b32_e32 v57, 0xffff0000, v206
	v_lshlrev_b32_e32 v8, 16, v9
	v_and_b32_e32 v9, 0xffff0000, v9
	v_lshlrev_b32_e32 v12, 16, v10
	v_and_b32_e32 v13, 0xffff0000, v10
	v_lshlrev_b32_e32 v10, 16, v11
	v_and_b32_e32 v11, 0xffff0000, v11
	v_pk_fma_f32 v[14:15], v[46:47], v[10:11], v[6:7]
	v_pk_fma_f32 v[12:13], v[44:45], v[12:13], v[4:5]
	v_pk_fma_f32 v[10:11], v[42:43], v[8:9], v[2:3]
	v_pk_fma_f32 v[8:9], v[40:41], v[56:57], v[0:1]
	v_mov_b32_e32 v57, v211
	v_mov_b32_e32 v58, v212
	v_mov_b32_e32 v59, v213
	v_lshlrev_b32_e32 v60, 16, v210
	v_and_b32_e32 v61, 0xffff0000, v210
	v_lshlrev_b32_e32 v56, 16, v57
	v_and_b32_e32 v57, 0xffff0000, v57
	v_lshlrev_b32_e32 v62, 16, v58
	v_and_b32_e32 v63, 0xffff0000, v58
	v_lshlrev_b32_e32 v58, 16, v59
	v_and_b32_e32 v59, 0xffff0000, v59
	v_pk_fma_f32 v[14:15], v[38:39], v[58:59], v[14:15]
	v_pk_fma_f32 v[12:13], v[36:37], v[62:63], v[12:13]
	v_pk_fma_f32 v[10:11], v[34:35], v[56:57], v[10:11]
	v_pk_fma_f32 v[8:9], v[32:33], v[60:61], v[8:9]
	v_mov_b32_e32 v57, v215
	v_mov_b32_e32 v58, v216
	v_mov_b32_e32 v59, v217
	v_lshlrev_b32_e32 v60, 16, v214
	v_and_b32_e32 v61, 0xffff0000, v214
	v_lshlrev_b32_e32 v56, 16, v57
	v_and_b32_e32 v57, 0xffff0000, v57
	v_lshlrev_b32_e32 v62, 16, v58
	v_and_b32_e32 v63, 0xffff0000, v58
	v_lshlrev_b32_e32 v58, 16, v59
	v_and_b32_e32 v59, 0xffff0000, v59
	v_pk_fma_f32 v[14:15], v[30:31], v[58:59], v[14:15]
	v_pk_fma_f32 v[12:13], v[28:29], v[62:63], v[12:13]
	v_pk_fma_f32 v[10:11], v[26:27], v[56:57], v[10:11]
	v_pk_fma_f32 v[8:9], v[24:25], v[60:61], v[8:9]
	v_mov_b32_e32 v57, v219
	v_mov_b32_e32 v58, v220
	v_mov_b32_e32 v59, v221
	v_lshlrev_b32_e32 v60, 16, v218
	v_and_b32_e32 v61, 0xffff0000, v218
	v_lshlrev_b32_e32 v56, 16, v57
	v_and_b32_e32 v57, 0xffff0000, v57
	v_lshlrev_b32_e32 v62, 16, v58
	v_and_b32_e32 v63, 0xffff0000, v58
	v_lshlrev_b32_e32 v58, 16, v59
	v_and_b32_e32 v59, 0xffff0000, v59
	v_pk_fma_f32 v[14:15], v[22:23], v[58:59], v[14:15]
	v_pk_fma_f32 v[12:13], v[20:21], v[62:63], v[12:13]
	v_pk_fma_f32 v[10:11], v[18:19], v[56:57], v[10:11]
	v_pk_fma_f32 v[8:9], v[16:17], v[60:61], v[8:9]
	v_lshl_add_u32 v55, v54, 8, v53
	ds_write_b128 v55, v[8:11] offset:36864
	ds_write_b128 v55, v[12:15] offset:36880
	v_cvt_pk_bf16_f32 v8, v8, v9
	v_cvt_pk_bf16_f32 v9, v10, v11
	v_cvt_pk_bf16_f32 v10, v12, v13
	v_cvt_pk_bf16_f32 v11, v14, v15
	v_mad_u64_u32 v[12:13], s[0:1], v54, s8, v[50:51]
	ds_write_b128 v12, v[8:11]
	v_add_u32_e32 v8, 0x60, v52
	v_add_u32_e32 v9, s68, v8
	v_add_u32_e32 v10, -2, v9
	v_cmp_lt_i32_e32 vcc, 1, v9
	v_cmp_gt_u32_e64 s[0:1], s39, v10
	s_and_b64 s[2:3], vcc, s[0:1]
	v_mov_b32_e32 v206, 0
	v_mov_b32_e32 v207, 0
	v_mov_b32_e32 v208, 0
	v_mov_b32_e32 v209, 0
	s_and_saveexec_b64 s[0:1], s[2:3]
	s_cbranch_execz .Lrg45_i
	v_add_u32_e32 v10, s38, v10
	v_mad_u64_u32 v[10:11], s[2:3], v10, s74, v[48:49]
	global_load_dwordx4 v[206:209], v[10:11], off

.Lrg48_i:
	s_or_b64 exec, exec, s[0:1]
	s_waitcnt vmcnt(0)
	s_nop 0
	v_mov_b32_e32 v11, v207
	v_mov_b32_e32 v12, v208
	v_mov_b32_e32 v13, v209
	v_lshlrev_b32_e32 v14, 16, v206
	v_and_b32_e32 v15, 0xffff0000, v206
	v_lshlrev_b32_e32 v10, 16, v11
	v_and_b32_e32 v11, 0xffff0000, v11
	v_lshlrev_b32_e32 v54, 16, v12
	v_and_b32_e32 v55, 0xffff0000, v12
	v_lshlrev_b32_e32 v12, 16, v13
	v_and_b32_e32 v13, 0xffff0000, v13
	v_pk_fma_f32 v[6:7], v[46:47], v[12:13], v[6:7]
	v_pk_fma_f32 v[4:5], v[44:45], v[54:55], v[4:5]
	v_pk_fma_f32 v[2:3], v[42:43], v[10:11], v[2:3]
	v_pk_fma_f32 v[0:1], v[40:41], v[14:15], v[0:1]
	v_mov_b32_e32 v11, v211
	v_mov_b32_e32 v12, v212
	v_mov_b32_e32 v13, v213
	v_lshlrev_b32_e32 v14, 16, v210
	v_and_b32_e32 v15, 0xffff0000, v210
	v_lshlrev_b32_e32 v10, 16, v11
	v_and_b32_e32 v11, 0xffff0000, v11
	v_lshlrev_b32_e32 v40, 16, v12
	v_and_b32_e32 v41, 0xffff0000, v12
	v_lshlrev_b32_e32 v12, 16, v13
	v_and_b32_e32 v13, 0xffff0000, v13
	v_pk_fma_f32 v[6:7], v[38:39], v[12:13], v[6:7]
	v_pk_fma_f32 v[4:5], v[36:37], v[40:41], v[4:5]
	v_pk_fma_f32 v[2:3], v[34:35], v[10:11], v[2:3]
	v_pk_fma_f32 v[0:1], v[32:33], v[14:15], v[0:1]
	v_mov_b32_e32 v11, v215
	v_mov_b32_e32 v12, v216
	v_mov_b32_e32 v13, v217
	v_lshlrev_b32_e32 v14, 16, v214
	v_and_b32_e32 v15, 0xffff0000, v214
	v_lshlrev_b32_e32 v10, 16, v11
	v_and_b32_e32 v11, 0xffff0000, v11
	v_lshlrev_b32_e32 v32, 16, v12
	v_and_b32_e32 v33, 0xffff0000, v12
	v_lshlrev_b32_e32 v12, 16, v13
	v_and_b32_e32 v13, 0xffff0000, v13
	v_pk_fma_f32 v[6:7], v[30:31], v[12:13], v[6:7]
	v_pk_fma_f32 v[4:5], v[28:29], v[32:33], v[4:5]
	v_pk_fma_f32 v[2:3], v[26:27], v[10:11], v[2:3]
	v_pk_fma_f32 v[0:1], v[24:25], v[14:15], v[0:1]
	v_mov_b32_e32 v11, v219
	v_mov_b32_e32 v12, v220
	v_mov_b32_e32 v13, v221
	v_lshlrev_b32_e32 v14, 16, v218
	v_and_b32_e32 v15, 0xffff0000, v218
	v_lshlrev_b32_e32 v10, 16, v11
	v_and_b32_e32 v11, 0xffff0000, v11
	v_lshlrev_b32_e32 v24, 16, v12
	v_and_b32_e32 v25, 0xffff0000, v12
	v_lshlrev_b32_e32 v12, 16, v13
	v_and_b32_e32 v13, 0xffff0000, v13
	v_pk_fma_f32 v[6:7], v[22:23], v[12:13], v[6:7]
	v_pk_fma_f32 v[4:5], v[20:21], v[24:25], v[4:5]
	v_pk_fma_f32 v[2:3], v[18:19], v[10:11], v[2:3]
	v_pk_fma_f32 v[0:1], v[16:17], v[14:15], v[0:1]
	v_lshl_add_u32 v10, v8, 8, v53
	ds_write_b128 v10, v[0:3] offset:36864
	ds_write_b128 v10, v[4:7] offset:36880
	v_cvt_pk_bf16_f32 v0, v0, v1
	v_cvt_pk_bf16_f32 v1, v2, v3
	v_cvt_pk_bf16_f32 v2, v4, v5
	v_mad_u64_u32 v[4:5], s[0:1], v8, s8, v[50:51]
	v_readlane_b32 s0, v248, 26
	s_or_b32 s0, s69, s0
	s_mov_b32 s1, s5
	v_readlane_b32 s16, v251, 4
	s_lshl_b64 s[2:3], s[0:1], 2
	v_readlane_b32 s26, v251, 14
	v_readlane_b32 s27, v251, 15
	s_add_u32 s0, s26, s2
	v_and_b32_e32 v9, 63, v51
	v_cvt_pk_bf16_f32 v3, v6, v7
	v_ashrrev_i32_e32 v96, 6, v51
	v_readlane_b32 s30, v251, 18
	s_addc_u32 s1, s27, s3
	ds_write_b128 v4, v[0:3]
	v_readlane_b32 s31, v251, 19
	s_add_u32 s2, s30, s2
	v_mul_u32_u24_e32 v1, 0x90, v9
	v_lshlrev_b32_e32 v2, 2, v96
	s_addc_u32 s3, s31, s3
	v_lshl_or_b32 v0, v96, 7, v9
	v_add3_u32 v1, v1, v2, s73
	s_mov_b32 s38, 0
	v_readlane_b32 s17, v251, 5
	v_readlane_b32 s18, v251, 6
	v_readlane_b32 s19, v251, 7
	v_readlane_b32 s20, v251, 8
	v_readlane_b32 s21, v251, 9
	v_readlane_b32 s22, v251, 10
	v_readlane_b32 s23, v251, 11
	v_readlane_b32 s24, v251, 12
	v_readlane_b32 s25, v251, 13
	v_readlane_b32 s28, v251, 16
	v_readlane_b32 s29, v251, 17

.LBB0_908:
	v_add_u32_e32 v137, v135, v134
	ds_read_b128 v[146:149], v135 offset:18432
	ds_read_b128 v[150:153], v137
	s_add_i32 s0, s0, 32
	s_cmp_lt_u32 s0, 48
	s_waitcnt lgkmcnt(0)
	v_mfma_f32_32x32x16_bf16 v[48:63], v[150:153], v[146:149], v[48:63]
	ds_read_b128 v[146:149], v135 offset:23040
	s_waitcnt lgkmcnt(0)
	v_mfma_f32_32x32x16_bf16 v[16:31], v[150:153], v[146:149], v[16:31]
	ds_read_b128 v[146:149], v135 offset:27648
	s_waitcnt lgkmcnt(0)
	v_mfma_f32_32x32x16_bf16 v[32:47], v[150:153], v[146:149], v[32:47]
	ds_read_b128 v[146:149], v135 offset:32256
	ds_read_b128 v[154:157], v135 offset:18464
	s_waitcnt lgkmcnt(1)
	v_mfma_f32_32x32x16_bf16 v[0:15], v[150:153], v[146:149], v[0:15]
	ds_read_b128 v[146:149], v137 offset:32
	ds_read_b128 v[150:153], v135 offset:23072
	s_waitcnt lgkmcnt(0)
	v_mfma_f32_32x32x16_bf16 v[16:31], v[146:149], v[150:153], v[16:31]
	ds_read_b128 v[150:153], v135 offset:27680
	s_waitcnt lgkmcnt(0)
	v_mfma_f32_32x32x16_bf16 v[32:47], v[146:149], v[150:153], v[32:47]
	ds_read_b128 v[150:153], v135 offset:32288
	v_add_u32_e32 v135, 64, v135
	v_mfma_f32_32x32x16_bf16 v[48:63], v[146:149], v[154:157], v[48:63]
	s_waitcnt lgkmcnt(0)
	v_mfma_f32_32x32x16_bf16 v[0:15], v[146:149], v[150:153], v[0:15]
	s_cbranch_scc1 .LBB0_908
	s_cmp_gt_u32 s12, 1
	v_readlane_b32 s0, v248, 27
	s_cselect_b32 s2, 19, 1
	s_or_b32 s3, s13, s0
	v_lshlrev_b32_e32 v137, 11, v96
	v_or_b32_e32 v96, s3, v145
	v_readlane_b32 s16, v251, 20
	v_lshlrev_b64 v[134:135], 2, v[96:97]
	v_readlane_b32 s18, v251, 22
	v_readlane_b32 s19, v251, 23
	s_barrier
	s_nop 0
	v_lshl_add_u64 v[138:139], s[18:19], 0, v[134:135]
	v_readlane_b32 s100, v251, 16
	v_readlane_b32 s101, v251, 17
	s_nop 1
	v_lshl_add_u64 v[220:221], s[100:101], 0, v[134:135]
	v_readlane_b32 s100, v251, 20
	v_readlane_b32 s101, v251, 21
	s_nop 1
	v_lshl_add_u64 v[222:223], s[100:101], 0, v[134:135]
	global_load_dword v224, v[220:221], off
	global_load_dword v225, v[222:223], off
	global_load_dword v226, v[138:139], off offset:128
	global_load_dword v227, v[222:223], off offset:128
	global_load_dword v228, v[220:221], off offset:128
	global_load_dword v96, v[138:139], off
	s_mov_b32 s8, 0x3f2aaaab
	s_mov_b32 s9, 0x3f317218
	s_mov_b32 s10, 0x7f800000
	v_readlane_b32 s20, v251, 24
	s_mov_b32 s20, 0x33800000
	v_readlane_b32 s40, v251, 4
	v_readlane_b32 s52, v251, 16
	v_readlane_b32 s53, v251, 17
	v_readlane_b32 s17, v251, 21
	v_readlane_b32 s21, v251, 25
	s_mov_b32 s21, 0x43000000
	v_readlane_b32 s22, v251, 26
	s_mov_b32 s22, 0x42b17217
	v_readlane_b32 s23, v251, 27
	s_mov_b32 s23, 0xf800000
	v_readlane_b32 s24, v251, 28
	s_mov_b32 s24, 0xc1880000
	v_readlane_b32 s30, v251, 34
	v_readlane_b32 s31, v251, 35
	v_readlane_b32 s25, v251, 29
	v_readlane_b32 s27, v251, 31
	v_readlane_b32 s28, v251, 32
	v_readlane_b32 s29, v251, 33
	v_readlane_b32 s30, v248, 2
	s_cmp_eq_u32 s2, s12
	v_readlane_b32 s31, v248, 3
	s_mov_b32 s28, 0x4800000
	s_movk_i32 s29, 0x47ff
	s_mov_b32 s25, 0x85000
	v_readlane_b32 s27, v248, 10
	v_readlane_b32 s26, v251, 30
	v_readlane_b32 s41, v251, 5
	v_readlane_b32 s42, v251, 6
	v_readlane_b32 s43, v251, 7
	v_readlane_b32 s44, v251, 8
	v_readlane_b32 s45, v251, 9
	v_readlane_b32 s46, v251, 10
	v_readlane_b32 s47, v251, 11
	v_readlane_b32 s48, v251, 12
	v_readlane_b32 s49, v251, 13
	v_readlane_b32 s50, v251, 14
	v_readlane_b32 s51, v251, 15
	v_readlane_b32 s54, v251, 18
	v_readlane_b32 s55, v251, 19
	s_waitcnt vmcnt(0)
	v_mul_f32_e32 v96, 0xbfb8aa3b, v96
	v_exp_f32_e32 v96, v96
	s_nop 0
	v_add_f32_e32 v144, 1.0, v96
	v_add_f32_e32 v138, -1.0, v144
	v_sub_f32_e32 v139, v138, v144
	v_add_f32_e32 v139, 1.0, v139
	v_sub_f32_e32 v138, v96, v138
	v_add_f32_e32 v146, v138, v139
	v_frexp_mant_f32_e32 v138, v144
	v_cmp_gt_f32_e32 vcc, s8, v138
	v_cvt_f64_f32_e32 v[138:139], v144
	v_frexp_exp_i32_f64_e32 v138, v[138:139]
	v_subbrev_co_u32_e32 v152, vcc, 0, v138, vcc
	v_sub_u32_e32 v138, 0, v152
	v_ldexp_f32 v139, v144, v138
	v_add_f32_e32 v144, -1.0, v139
	v_add_f32_e32 v147, 1.0, v139
	v_ldexp_f32 v138, v146, v138
	v_add_f32_e32 v146, 1.0, v144
	v_add_f32_e32 v148, -1.0, v147
	v_sub_f32_e32 v146, v139, v146
	v_sub_f32_e32 v139, v139, v148
	v_add_f32_e32 v146, v138, v146
	v_add_f32_e32 v138, v138, v139
	v_add_f32_e32 v153, v147, v138
	v_rcp_f32_e32 v155, v153
	v_sub_f32_e32 v139, v153, v147
	v_sub_f32_e32 v154, v138, v139
	v_add_f32_e32 v139, v144, v146
	v_sub_f32_e32 v138, v139, v144
	v_mul_f32_e32 v156, v139, v155
	v_sub_f32_e32 v144, v146, v138
	v_mul_f32_e32 v146, v153, v156
	v_fma_f32 v148, v156, v153, -v146
	v_fmac_f32_e32 v148, v156, v154
	v_add_f32_e32 v138, v146, v148
	v_sub_f32_e32 v147, v139, v138
	v_pk_add_f32 v[150:151], v[138:139], v[146:147] neg_lo:[0,1] neg_hi:[0,1]
	v_mov_b32_e32 v149, v138
	v_pk_add_f32 v[138:139], v[150:151], v[148:149] neg_lo:[0,1] neg_hi:[0,1]
	v_cmp_neq_f32_e32 vcc, s10, v96
	v_add_f32_e32 v139, v144, v139
	v_add_f32_e32 v138, v138, v139
	v_add_f32_e32 v139, v147, v138
	v_mul_f32_e32 v144, v155, v139
	v_mul_f32_e32 v146, v153, v144
	v_fma_f32 v148, v144, v153, -v146
	v_fmac_f32_e32 v148, v144, v154
	v_sub_f32_e32 v147, v147, v139
	v_add_f32_e32 v153, v138, v147
	v_add_f32_e32 v138, v146, v148
	v_sub_f32_e32 v147, v139, v138
	v_pk_add_f32 v[150:151], v[138:139], v[146:147] neg_lo:[0,1] neg_hi:[0,1]
	v_mov_b32_e32 v149, v138
	v_pk_add_f32 v[138:139], v[150:151], v[148:149] neg_lo:[0,1] neg_hi:[0,1]
	v_add_f32_e32 v139, v153, v139
	v_add_f32_e32 v138, v138, v139
	v_add_f32_e32 v139, v156, v144
	v_add_f32_e32 v138, v147, v138
	v_sub_f32_e32 v146, v139, v156
	v_mul_f32_e32 v138, v155, v138
	v_sub_f32_e32 v144, v144, v146
	v_add_f32_e32 v144, v144, v138
	v_add_f32_e32 v146, v139, v144
	v_mul_f32_e32 v148, v146, v146
	v_fmamk_f32 v138, v148, 0x3e9b6dac, v191
	v_fmaak_f32 v169, v148, v138, 0x3f2aaada
	v_cvt_f32_i32_e32 v138, v152
	v_sub_f32_e32 v139, v146, v139
	v_sub_f32_e32 v139, v144, v139
	v_ldexp_f32 v144, v139, 1
	v_mul_f32_e32 v139, v146, v148
	v_pk_mul_f32 v[148:149], v[138:139], v[168:169]
	v_ldexp_f32 v147, v146, 1
	v_fma_f32 v146, v138, s9, -v148
	v_fmac_f32_e32 v146, 0xb102e308, v138
	v_pk_add_f32 v[138:139], v[148:149], v[146:147]
	v_mov_b32_e32 v150, v148
	v_sub_f32_e32 v147, v139, v147
	v_sub_f32_e32 v147, v149, v147
	v_add_f32_e32 v151, v144, v147
	v_pk_add_f32 v[148:149], v[138:139], v[148:149] neg_lo:[0,1] neg_hi:[0,1]
	v_pk_add_f32 v[152:153], v[138:139], v[150:151]
	v_mov_b32_e32 v147, v138
	v_mov_b32_e32 v149, v153
	v_pk_add_f32 v[154:155], v[146:147], v[148:149] neg_lo:[0,1] neg_hi:[0,1]
	v_pk_add_f32 v[146:147], v[146:147], v[148:149]
	v_mov_b32_e32 v150, v151
	v_pk_add_f32 v[148:149], v[146:147], v[138:139] op_sel:[1,0] op_sel_hi:[0,1] neg_lo:[0,1] neg_hi:[0,1]
	v_pk_add_f32 v[156:157], v[152:153], v[148:149] op_sel_hi:[1,0] neg_lo:[0,1] neg_hi:[0,1]
	v_mov_b32_e32 v152, v153
	v_mov_b32_e32 v153, v147
	v_pk_mov_b32 v[148:149], v[138:139], v[148:149] op_sel:[1,0]
	v_mov_b32_e32 v151, v138
	v_pk_add_f32 v[148:149], v[152:153], v[148:149] neg_lo:[0,1] neg_hi:[0,1]
	v_mov_b32_e32 v156, v154
	v_pk_add_f32 v[138:139], v[150:151], v[148:149] neg_lo:[0,1] neg_hi:[0,1]
	v_mov_b32_e32 v155, v147
	v_pk_add_f32 v[148:149], v[156:157], v[138:139]
	v_pk_add_f32 v[150:151], v[148:149], v[148:149] op_sel:[0,1] op_sel_hi:[1,0]
	v_pk_add_f32 v[146:147], v[146:147], v[150:151] op_sel:[1,0] op_sel_hi:[0,1]
	v_mov_b32_e32 v149, v146
	v_pk_add_f32 v[152:153], v[148:149], v[154:155] neg_lo:[0,1] neg_hi:[0,1]
	v_mov_b32_e32 v139, v150
	v_sub_f32_e32 v144, v148, v152
	v_pk_add_f32 v[138:139], v[138:139], v[152:153] neg_lo:[0,1] neg_hi:[0,1]
	v_sub_f32_e32 v144, v154, v144
	v_add_f32_e32 v138, v138, v144
	v_add_f32_e32 v138, v138, v139
	v_add_f32_e32 v138, v146, v138
	v_cndmask_b32_e32 v138, v199, v138, vcc
	v_cmp_ngt_f32_e32 vcc, -1.0, v96
	s_nop 1
	v_cndmask_b32_e32 v138, v200, v138, vcc
	v_cmp_neq_f32_e32 vcc, -1.0, v96
	s_nop 1
	v_cndmask_b32_e32 v138, v201, v138, vcc
	v_cmp_lt_f32_e64 vcc, |v96|, s20
	s_nop 1
	v_cndmask_b32_e32 v96, v138, v96, vcc
	v_lshl_add_u64 v[138:139], s[52:53], 0, v[134:135]
	v_mov_b32_e32 v147, v224
	v_lshl_add_u64 v[134:135], s[16:17], 0, v[134:135]
	v_mov_b32_e32 v146, v225
	v_mul_f32_e32 v96, 0xc1000000, v96
	s_waitcnt vmcnt(1)
	v_add_f32_e32 v48, v48, v147
	v_mul_f32_e32 v48, 0xbfb8aa3b, v48
	v_exp_f32_e32 v48, v48
	s_waitcnt vmcnt(0)
	v_add_f32_e32 v32, v32, v146
	v_mul_f32_e32 v32, 0xbfb8aa3b, v32
	v_exp_f32_e32 v32, v32
	v_add_f32_e32 v48, 1.0, v48
	v_rcp_f32_e32 v48, v48
	v_add_f32_e32 v33, v33, v146
	v_add_f32_e32 v32, 1.0, v32
	v_rcp_f32_e32 v32, v32
	v_mul_f32_e32 v48, v48, v96
	v_mul_f32_e32 v134, 0x3fb8aa3b, v48
	v_add_f32_e32 v48, v48, v48
	v_exp_f32_e32 v138, v134
	v_mul_f32_e32 v134, 0x3fb8aa3b, v48
	v_rndne_f32_e32 v134, v134
	v_fmamk_f32 v135, v134, 0xbf317218, v48
	v_fmac_f32_e32 v135, 0x3102e308, v134
	v_fmamk_f32 v139, v135, 0x395133b1, v192
	v_cmp_eq_f32_e32 vcc, s21, v134
	v_cvt_i32_f32_e32 v134, v134
	v_fmaak_f32 v139, v135, v139, 0x3c0887f9
	v_fmaak_f32 v139, v135, v139, 0x3d2aaa81
	v_fmaak_f32 v139, v135, v139, 0x3e2aaaab
	v_fma_f32 v139, v135, v139, 0.5
	v_ldexp_f32 v134, 1.0, v134
	v_mul_f32_e32 v139, v135, v139
	v_cndmask_b32_e32 v134, v134, v202, vcc
	v_fmac_f32_e32 v135, v135, v139
	v_add_f32_e32 v139, -1.0, v134
	v_fmac_f32_e32 v139, v134, v135
	v_add_f32_e32 v134, v139, v139
	v_cndmask_b32_e32 v134, v139, v134, vcc
	v_cmp_nlt_f32_e32 vcc, s22, v48
	v_mul_f32_e32 v33, 0xbfb8aa3b, v33
	v_exp_f32_e32 v33, v33
	v_cndmask_b32_e64 v134, v201, -v134, vcc
	v_cmp_gt_f32_e32 vcc, s23, v134
	v_mul_f32_e32 v135, 0x4f800000, v134
	v_add_f32_e32 v33, 1.0, v33
	v_cndmask_b32_e32 v134, v134, v135, vcc
	v_sqrt_f32_e32 v135, v134
	v_rcp_f32_e32 v33, v33
	v_add_f32_e32 v34, v34, v146
	v_mul_f32_e32 v34, 0xbfb8aa3b, v34
	v_add_u32_e32 v139, -1, v135
	v_fma_f32 v144, -v139, v135, v134
	v_cmp_ge_f32_e64 s[0:1], 0, v144
	v_add_u32_e32 v144, 1, v135
	v_exp_f32_e32 v34, v34
	v_cndmask_b32_e64 v139, v135, v139, s[0:1]
	v_fma_f32 v135, -v144, v135, v134
	v_cmp_lt_f32_e64 s[0:1], 0, v135
	v_add_f32_e32 v34, 1.0, v34
	v_rcp_f32_e32 v34, v34
	v_cndmask_b32_e64 v135, v139, v144, s[0:1]
	v_mul_f32_e32 v139, 0x37800000, v135
	v_cndmask_b32_e32 v135, v135, v139, vcc
	v_cmp_class_f32_e32 vcc, v134, v193
	s_nop 1
	v_cndmask_b32_e32 v134, v135, v134, vcc
	v_cmp_ngt_f32_e32 vcc, s24, v48
	s_nop 1
	v_cndmask_b32_e32 v48, 1.0, v134, vcc
	v_mul_f32_e32 v48, v32, v48
	v_and_b32_e32 v32, 0x100, v136
	v_or3_b32 v32, v137, v145, v32
	v_lshl_add_u32 v144, v32, 2, 0
	v_add_u32_e32 v32, 0x9000, v144
	ds_read2_b32 v[134:135], v32 offset1:32
	s_waitcnt lgkmcnt(0)
	v_mul_f32_e32 v48, v134, v48
	ds_write_b32 v144, v138
	ds_write_b32 v144, v48 offset:36864
	v_add_f32_e32 v48, v49, v147
	v_mul_f32_e32 v48, 0xbfb8aa3b, v48
	v_exp_f32_e32 v48, v48
	s_nop 0
	v_add_f32_e32 v48, 1.0, v48
	v_rcp_f32_e32 v48, v48
	s_nop 0
	v_mul_f32_e32 v48, v48, v96
	v_mul_f32_e32 v49, 0x3fb8aa3b, v48
	v_add_f32_e32 v48, v48, v48
	v_exp_f32_e32 v134, v49
	v_mul_f32_e32 v49, 0x3fb8aa3b, v48
	v_rndne_f32_e32 v49, v49
	v_fmamk_f32 v136, v49, 0xbf317218, v48
	v_fmac_f32_e32 v136, 0x3102e308, v49
	v_fmamk_f32 v137, v136, 0x395133b1, v192
	v_cmp_eq_f32_e32 vcc, s21, v49
	v_cvt_i32_f32_e32 v49, v49
	v_fmaak_f32 v137, v136, v137, 0x3c0887f9
	v_fmaak_f32 v137, v136, v137, 0x3d2aaa81
	v_fmaak_f32 v137, v136, v137, 0x3e2aaaab
	v_fma_f32 v137, v136, v137, 0.5
	v_ldexp_f32 v49, 1.0, v49
	v_mul_f32_e32 v137, v136, v137
	v_cndmask_b32_e32 v49, v49, v202, vcc
	v_fmac_f32_e32 v136, v136, v137
	v_add_f32_e32 v137, -1.0, v49
	v_fmac_f32_e32 v137, v49, v136
	v_add_f32_e32 v49, v137, v137
	v_cndmask_b32_e32 v49, v137, v49, vcc
	v_cmp_nlt_f32_e32 vcc, s22, v48
	s_nop 1
	v_cndmask_b32_e64 v49, v201, -v49, vcc
	v_cmp_gt_f32_e32 vcc, s23, v49
	v_mul_f32_e32 v136, 0x4f800000, v49
	s_nop 0
	v_cndmask_b32_e32 v49, v49, v136, vcc
	v_sqrt_f32_e32 v136, v49
	s_nop 0
	v_add_u32_e32 v137, -1, v136
	v_fma_f32 v138, -v137, v136, v49
	v_cmp_ge_f32_e64 s[0:1], 0, v138
	v_add_u32_e32 v138, 1, v136
	s_nop 0
	v_cndmask_b32_e64 v137, v136, v137, s[0:1]
	v_fma_f32 v136, -v138, v136, v49
	v_cmp_lt_f32_e64 s[0:1], 0, v136
	s_nop 1
	v_cndmask_b32_e64 v136, v137, v138, s[0:1]
	v_mul_f32_e32 v137, 0x37800000, v136
	v_cndmask_b32_e32 v136, v136, v137, vcc
	v_cmp_class_f32_e32 vcc, v49, v193
	s_nop 1
	v_cndmask_b32_e32 v49, v136, v49, vcc
	v_cmp_ngt_f32_e32 vcc, s24, v48
	s_nop 1
	v_cndmask_b32_e32 v48, 1.0, v49, vcc
	v_mul_f32_e32 v33, v33, v48
	ds_read2_b32 v[48:49], v32 offset0:64 offset1:96
	s_waitcnt lgkmcnt(0)
	v_mul_f32_e32 v33, v48, v33
	ds_write_b32 v144, v134 offset:256
	ds_write_b32 v144, v33 offset:37120
	v_add_f32_e32 v33, v50, v147
	v_mul_f32_e32 v33, 0xbfb8aa3b, v33
	v_exp_f32_e32 v33, v33
	s_nop 0
	v_add_f32_e32 v33, 1.0, v33
	v_rcp_f32_e32 v33, v33
	s_nop 0
	v_mul_f32_e32 v33, v33, v96
	v_mul_f32_e32 v48, 0x3fb8aa3b, v33
	v_add_f32_e32 v33, v33, v33
	v_mul_f32_e32 v50, 0x3fb8aa3b, v33
	v_rndne_f32_e32 v50, v50
	v_fmamk_f32 v134, v50, 0xbf317218, v33
	v_fmac_f32_e32 v134, 0x3102e308, v50
	v_fmamk_f32 v136, v134, 0x395133b1, v192
	v_cmp_eq_f32_e32 vcc, s21, v50
	v_cvt_i32_f32_e32 v50, v50
	v_fmaak_f32 v136, v134, v136, 0x3c0887f9
	v_fmaak_f32 v136, v134, v136, 0x3d2aaa81
	v_fmaak_f32 v136, v134, v136, 0x3e2aaaab
	v_fma_f32 v136, v134, v136, 0.5
	v_ldexp_f32 v50, 1.0, v50
	v_mul_f32_e32 v136, v134, v136
	v_cndmask_b32_e32 v50, v50, v202, vcc
	v_fmac_f32_e32 v134, v134, v136
	v_add_f32_e32 v136, -1.0, v50
	v_fmac_f32_e32 v136, v50, v134
	v_add_f32_e32 v50, v136, v136
	v_cndmask_b32_e32 v50, v136, v50, vcc
	v_cmp_nlt_f32_e32 vcc, s22, v33
	v_exp_f32_e32 v48, v48
	s_nop 0
	v_cndmask_b32_e64 v50, v201, -v50, vcc
	v_cmp_gt_f32_e32 vcc, s23, v50
	v_mul_f32_e32 v134, 0x4f800000, v50
	s_nop 0
	v_cndmask_b32_e32 v50, v50, v134, vcc
	v_sqrt_f32_e32 v134, v50
	s_nop 0
	v_add_u32_e32 v136, -1, v134
	v_fma_f32 v137, -v136, v134, v50
	v_cmp_ge_f32_e64 s[0:1], 0, v137
	v_add_u32_e32 v137, 1, v134
	s_nop 0
	v_cndmask_b32_e64 v136, v134, v136, s[0:1]
	v_fma_f32 v134, -v137, v134, v50
	v_cmp_lt_f32_e64 s[0:1], 0, v134
	s_nop 1
	v_cndmask_b32_e64 v134, v136, v137, s[0:1]
	v_mul_f32_e32 v136, 0x37800000, v134
	v_cndmask_b32_e32 v134, v134, v136, vcc
	ds_read2_b32 v[136:137], v32 offset0:128 offset1:160
	v_cmp_class_f32_e32 vcc, v50, v193
	s_nop 1
	v_cndmask_b32_e32 v50, v134, v50, vcc
	v_cmp_ngt_f32_e32 vcc, s24, v33
	s_nop 1
	v_cndmask_b32_e32 v33, 1.0, v50, vcc
	v_mul_f32_e32 v33, v34, v33
	s_waitcnt lgkmcnt(0)
	v_mul_f32_e32 v33, v136, v33
	ds_write_b32 v144, v48 offset:512
	ds_write_b32 v144, v33 offset:37376
	v_add_f32_e32 v33, v51, v147
	v_mul_f32_e32 v33, 0xbfb8aa3b, v33
	v_exp_f32_e32 v33, v33
	v_add_f32_e32 v34, v35, v146
	v_mul_f32_e32 v34, 0xbfb8aa3b, v34
	v_exp_f32_e32 v34, v34
	v_add_f32_e32 v33, 1.0, v33
	v_rcp_f32_e32 v33, v33
	v_add_f32_e32 v34, 1.0, v34
	v_rcp_f32_e32 v34, v34
	v_mul_f32_e32 v33, v33, v96
	v_mul_f32_e32 v35, 0x3fb8aa3b, v33
	v_add_f32_e32 v33, v33, v33
	v_mul_f32_e32 v48, 0x3fb8aa3b, v33
	v_rndne_f32_e32 v48, v48
	v_fmamk_f32 v50, v48, 0xbf317218, v33
	v_fmac_f32_e32 v50, 0x3102e308, v48
	v_fmamk_f32 v51, v50, 0x395133b1, v192
	v_cmp_eq_f32_e32 vcc, s21, v48
	v_cvt_i32_f32_e32 v48, v48
	v_fmaak_f32 v51, v50, v51, 0x3c0887f9
	v_fmaak_f32 v51, v50, v51, 0x3d2aaa81
	v_fmaak_f32 v51, v50, v51, 0x3e2aaaab
	v_fma_f32 v51, v50, v51, 0.5
	v_ldexp_f32 v48, 1.0, v48
	v_mul_f32_e32 v51, v50, v51
	v_cndmask_b32_e32 v48, v48, v202, vcc
	v_fmac_f32_e32 v50, v50, v51
	v_add_f32_e32 v51, -1.0, v48
	v_fmac_f32_e32 v51, v48, v50
	v_add_f32_e32 v48, v51, v51
	v_cndmask_b32_e32 v48, v51, v48, vcc
	v_cmp_nlt_f32_e32 vcc, s22, v33
	v_exp_f32_e32 v35, v35
	s_nop 0
	v_cndmask_b32_e64 v48, v201, -v48, vcc
	v_cmp_gt_f32_e32 vcc, s23, v48
	v_mul_f32_e32 v50, 0x4f800000, v48
	s_nop 0
	v_cndmask_b32_e32 v48, v48, v50, vcc
	v_sqrt_f32_e32 v50, v48
	s_nop 0
	v_add_u32_e32 v51, -1, v50
	v_fma_f32 v134, -v51, v50, v48
	v_cmp_ge_f32_e64 s[0:1], 0, v134
	v_add_u32_e32 v134, 1, v50
	s_nop 0
	v_cndmask_b32_e64 v51, v50, v51, s[0:1]
	v_fma_f32 v50, -v134, v50, v48
	v_cmp_lt_f32_e64 s[0:1], 0, v50
	s_nop 1
	v_cndmask_b32_e64 v50, v51, v134, s[0:1]
	v_mul_f32_e32 v51, 0x37800000, v50
	v_cndmask_b32_e32 v50, v50, v51, vcc
	v_cmp_class_f32_e32 vcc, v48, v193
	s_nop 1
	v_cndmask_b32_e32 v48, v50, v48, vcc
	ds_read2_b32 v[50:51], v32 offset0:192 offset1:224
	v_cmp_ngt_f32_e32 vcc, s24, v33
	s_nop 1
	v_cndmask_b32_e32 v33, 1.0, v48, vcc
	v_mul_f32_e32 v33, v34, v33
	s_waitcnt lgkmcnt(0)
	v_mul_f32_e32 v32, v50, v33
	ds_write_b32 v144, v35 offset:768
	ds_write_b32 v144, v32 offset:37632
	v_add_f32_e32 v32, v52, v147
	v_mul_f32_e32 v32, 0xbfb8aa3b, v32
	v_exp_f32_e32 v32, v32
	v_add_f32_e32 v33, v36, v146
	v_mul_f32_e32 v33, 0xbfb8aa3b, v33
	v_exp_f32_e32 v33, v33
	v_add_f32_e32 v32, 1.0, v32
	v_rcp_f32_e32 v32, v32
	v_add_f32_e32 v33, 1.0, v33
	v_rcp_f32_e32 v33, v33
	v_mul_f32_e32 v32, v32, v96
	v_mul_f32_e32 v34, 0x3fb8aa3b, v32
	v_add_f32_e32 v32, v32, v32
	v_mul_f32_e32 v35, 0x3fb8aa3b, v32
	v_rndne_f32_e32 v35, v35
	v_fmamk_f32 v36, v35, 0xbf317218, v32
	v_fmac_f32_e32 v36, 0x3102e308, v35
	v_fmamk_f32 v48, v36, 0x395133b1, v192
	v_cmp_eq_f32_e32 vcc, s21, v35
	v_cvt_i32_f32_e32 v35, v35
	v_fmaak_f32 v48, v36, v48, 0x3c0887f9
	v_fmaak_f32 v48, v36, v48, 0x3d2aaa81
	v_fmaak_f32 v48, v36, v48, 0x3e2aaaab
	v_fma_f32 v48, v36, v48, 0.5
	v_ldexp_f32 v35, 1.0, v35
	v_mul_f32_e32 v48, v36, v48
	v_cndmask_b32_e32 v35, v35, v202, vcc
	v_fmac_f32_e32 v36, v36, v48
	v_add_f32_e32 v48, -1.0, v35
	v_fmac_f32_e32 v48, v35, v36
	v_add_f32_e32 v35, v48, v48
	v_cndmask_b32_e32 v35, v48, v35, vcc
	v_cmp_nlt_f32_e32 vcc, s22, v32
	v_exp_f32_e32 v34, v34
	s_nop 0
	v_cndmask_b32_e64 v35, v201, -v35, vcc
	v_cmp_gt_f32_e32 vcc, s23, v35
	v_mul_f32_e32 v36, 0x4f800000, v35
	s_nop 0
	v_cndmask_b32_e32 v35, v35, v36, vcc
	v_sqrt_f32_e32 v36, v35
	s_nop 0
	v_add_u32_e32 v48, -1, v36
	v_fma_f32 v50, -v48, v36, v35
	v_cmp_ge_f32_e64 s[0:1], 0, v50
	v_add_u32_e32 v50, 1, v36
	s_nop 0
	v_cndmask_b32_e64 v48, v36, v48, s[0:1]
	v_fma_f32 v36, -v50, v36, v35
	v_cmp_lt_f32_e64 s[0:1], 0, v36
	s_nop 1
	v_cndmask_b32_e64 v36, v48, v50, s[0:1]
	v_mul_f32_e32 v48, 0x37800000, v36
	v_cndmask_b32_e32 v36, v36, v48, vcc
	v_cmp_class_f32_e32 vcc, v35, v193
	s_nop 1
	v_cndmask_b32_e32 v35, v36, v35, vcc
	v_cmp_ngt_f32_e32 vcc, s24, v32
	s_nop 1
	v_cndmask_b32_e32 v32, 1.0, v35, vcc
	v_mul_f32_e32 v33, v33, v32
	v_add_u32_e32 v32, 0x9800, v144
	ds_read2_b32 v[138:139], v32 offset1:32
	s_waitcnt lgkmcnt(0)
	v_mul_f32_e32 v33, v138, v33
	ds_write_b32 v144, v34 offset:2048
	ds_write_b32 v144, v33 offset:38912
	v_add_f32_e32 v33, v53, v147
	v_mul_f32_e32 v33, 0xbfb8aa3b, v33
	v_exp_f32_e32 v33, v33
	v_add_f32_e32 v34, v37, v146
	v_mul_f32_e32 v34, 0xbfb8aa3b, v34
	v_exp_f32_e32 v34, v34
	v_add_f32_e32 v33, 1.0, v33
	v_rcp_f32_e32 v33, v33
	v_add_f32_e32 v34, 1.0, v34
	v_rcp_f32_e32 v34, v34
	v_mul_f32_e32 v33, v33, v96
	v_mul_f32_e32 v35, 0x3fb8aa3b, v33
	v_add_f32_e32 v33, v33, v33
	v_mul_f32_e32 v36, 0x3fb8aa3b, v33
	v_rndne_f32_e32 v36, v36
	v_fmamk_f32 v37, v36, 0xbf317218, v33
	v_fmac_f32_e32 v37, 0x3102e308, v36
	v_fmamk_f32 v48, v37, 0x395133b1, v192
	v_cmp_eq_f32_e32 vcc, s21, v36
	v_cvt_i32_f32_e32 v36, v36
	v_fmaak_f32 v48, v37, v48, 0x3c0887f9
	v_fmaak_f32 v48, v37, v48, 0x3d2aaa81
	v_fmaak_f32 v48, v37, v48, 0x3e2aaaab
	v_fma_f32 v48, v37, v48, 0.5
	v_ldexp_f32 v36, 1.0, v36
	v_mul_f32_e32 v48, v37, v48
	v_cndmask_b32_e32 v36, v36, v202, vcc
	v_fmac_f32_e32 v37, v37, v48
	v_add_f32_e32 v48, -1.0, v36
	v_fmac_f32_e32 v48, v36, v37
	v_add_f32_e32 v36, v48, v48
	v_cndmask_b32_e32 v36, v48, v36, vcc
	v_cmp_nlt_f32_e32 vcc, s22, v33
	v_exp_f32_e32 v35, v35
	s_nop 0
	v_cndmask_b32_e64 v36, v201, -v36, vcc
	v_cmp_gt_f32_e32 vcc, s23, v36
	v_mul_f32_e32 v37, 0x4f800000, v36
	s_nop 0
	v_cndmask_b32_e32 v36, v36, v37, vcc
	v_sqrt_f32_e32 v37, v36
	s_nop 0
	v_add_u32_e32 v48, -1, v37
	v_fma_f32 v50, -v48, v37, v36
	v_cmp_ge_f32_e64 s[0:1], 0, v50
	v_add_u32_e32 v50, 1, v37
	s_nop 0
	v_cndmask_b32_e64 v48, v37, v48, s[0:1]
	v_fma_f32 v37, -v50, v37, v36
	v_cmp_lt_f32_e64 s[0:1], 0, v37
	s_nop 1
	v_cndmask_b32_e64 v37, v48, v50, s[0:1]
	v_mul_f32_e32 v48, 0x37800000, v37
	v_cndmask_b32_e32 v37, v37, v48, vcc
	v_cmp_class_f32_e32 vcc, v36, v193
	s_nop 1
	v_cndmask_b32_e32 v36, v37, v36, vcc
	v_cmp_ngt_f32_e32 vcc, s24, v33
	s_nop 1
	v_cndmask_b32_e32 v33, 1.0, v36, vcc
	ds_read2_b32 v[36:37], v32 offset0:64 offset1:96
	v_mul_f32_e32 v33, v34, v33
	v_add_f32_e32 v34, v38, v146
	v_mul_f32_e32 v34, 0xbfb8aa3b, v34
	v_exp_f32_e32 v34, v34
	s_waitcnt lgkmcnt(0)
	v_mul_f32_e32 v33, v36, v33
	ds_write_b32 v144, v35 offset:2304
	ds_write_b32 v144, v33 offset:39168
	v_add_f32_e32 v33, v54, v147
	v_mul_f32_e32 v33, 0xbfb8aa3b, v33
	v_exp_f32_e32 v33, v33
	v_add_f32_e32 v34, 1.0, v34
	v_rcp_f32_e32 v34, v34
	ds_read2_b32 v[52:53], v32 offset0:128 offset1:160
	v_add_f32_e32 v33, 1.0, v33
	v_rcp_f32_e32 v33, v33
	s_nop 0
	v_mul_f32_e32 v33, v33, v96
	v_mul_f32_e32 v35, 0x3fb8aa3b, v33
	v_add_f32_e32 v33, v33, v33
	v_mul_f32_e32 v36, 0x3fb8aa3b, v33
	v_rndne_f32_e32 v36, v36
	v_fmamk_f32 v38, v36, 0xbf317218, v33
	v_fmac_f32_e32 v38, 0x3102e308, v36
	v_fmamk_f32 v48, v38, 0x395133b1, v192
	v_cmp_eq_f32_e32 vcc, s21, v36
	v_cvt_i32_f32_e32 v36, v36
	v_fmaak_f32 v48, v38, v48, 0x3c0887f9
	v_fmaak_f32 v48, v38, v48, 0x3d2aaa81
	v_fmaak_f32 v48, v38, v48, 0x3e2aaaab
	v_fma_f32 v48, v38, v48, 0.5
	v_ldexp_f32 v36, 1.0, v36
	v_mul_f32_e32 v48, v38, v48
	v_cndmask_b32_e32 v36, v36, v202, vcc
	v_fmac_f32_e32 v38, v38, v48
	v_add_f32_e32 v48, -1.0, v36
	v_fmac_f32_e32 v48, v36, v38
	v_add_f32_e32 v36, v48, v48
	v_cndmask_b32_e32 v36, v48, v36, vcc
	v_cmp_nlt_f32_e32 vcc, s22, v33
	v_exp_f32_e32 v35, v35
	s_nop 0
	v_cndmask_b32_e64 v36, v201, -v36, vcc
	v_cmp_gt_f32_e32 vcc, s23, v36
	v_mul_f32_e32 v38, 0x4f800000, v36
	s_nop 0
	v_cndmask_b32_e32 v36, v36, v38, vcc
	v_sqrt_f32_e32 v38, v36
	s_nop 0
	v_add_u32_e32 v48, -1, v38
	v_fma_f32 v50, -v48, v38, v36
	v_cmp_ge_f32_e64 s[0:1], 0, v50
	v_add_u32_e32 v50, 1, v38
	s_nop 0
	v_cndmask_b32_e64 v48, v38, v48, s[0:1]
	v_fma_f32 v38, -v50, v38, v36
	v_cmp_lt_f32_e64 s[0:1], 0, v38
	s_nop 1
	v_cndmask_b32_e64 v38, v48, v50, s[0:1]
	v_mul_f32_e32 v48, 0x37800000, v38
	v_cndmask_b32_e32 v38, v38, v48, vcc
	v_cmp_class_f32_e32 vcc, v36, v193
	s_nop 1
	v_cndmask_b32_e32 v36, v38, v36, vcc
	v_cmp_ngt_f32_e32 vcc, s24, v33
	s_nop 1
	v_cndmask_b32_e32 v33, 1.0, v36, vcc
	v_mul_f32_e32 v33, v34, v33
	s_waitcnt lgkmcnt(0)
	v_mul_f32_e32 v33, v52, v33
	ds_write_b32 v144, v35 offset:2560
	ds_write_b32 v144, v33 offset:39424
	v_add_f32_e32 v33, v55, v147
	v_mul_f32_e32 v33, 0xbfb8aa3b, v33
	v_exp_f32_e32 v33, v33
	v_add_f32_e32 v34, v39, v146
	v_mul_f32_e32 v34, 0xbfb8aa3b, v34
	v_exp_f32_e32 v34, v34
	v_add_f32_e32 v33, 1.0, v33
	v_rcp_f32_e32 v33, v33
	v_add_f32_e32 v34, 1.0, v34
	v_rcp_f32_e32 v34, v34
	v_mul_f32_e32 v33, v33, v96
	v_mul_f32_e32 v35, 0x3fb8aa3b, v33
	v_add_f32_e32 v33, v33, v33
	v_mul_f32_e32 v36, 0x3fb8aa3b, v33
	v_rndne_f32_e32 v36, v36
	v_fmamk_f32 v38, v36, 0xbf317218, v33
	v_fmac_f32_e32 v38, 0x3102e308, v36
	v_fmamk_f32 v39, v38, 0x395133b1, v192
	v_cmp_eq_f32_e32 vcc, s21, v36
	v_cvt_i32_f32_e32 v36, v36
	v_fmaak_f32 v39, v38, v39, 0x3c0887f9
	v_fmaak_f32 v39, v38, v39, 0x3d2aaa81
	v_fmaak_f32 v39, v38, v39, 0x3e2aaaab
	v_fma_f32 v39, v38, v39, 0.5
	v_ldexp_f32 v36, 1.0, v36
	v_mul_f32_e32 v39, v38, v39
	v_cndmask_b32_e32 v36, v36, v202, vcc
	v_fmac_f32_e32 v38, v38, v39
	v_add_f32_e32 v39, -1.0, v36
	v_fmac_f32_e32 v39, v36, v38
	v_add_f32_e32 v36, v39, v39
	v_cndmask_b32_e32 v36, v39, v36, vcc
	v_cmp_nlt_f32_e32 vcc, s22, v33
	v_exp_f32_e32 v35, v35
	s_nop 0
	v_cndmask_b32_e64 v36, v201, -v36, vcc
	v_cmp_gt_f32_e32 vcc, s23, v36
	v_mul_f32_e32 v38, 0x4f800000, v36
	s_nop 0
	v_cndmask_b32_e32 v36, v36, v38, vcc
	v_sqrt_f32_e32 v38, v36
	s_nop 0
	v_add_u32_e32 v39, -1, v38
	v_fma_f32 v48, -v39, v38, v36
	v_cmp_ge_f32_e64 s[0:1], 0, v48
	v_add_u32_e32 v48, 1, v38
	s_nop 0
	v_cndmask_b32_e64 v39, v38, v39, s[0:1]
	v_fma_f32 v38, -v48, v38, v36
	v_cmp_lt_f32_e64 s[0:1], 0, v38
	s_nop 1
	v_cndmask_b32_e64 v38, v39, v48, s[0:1]
	v_mul_f32_e32 v39, 0x37800000, v38
	v_cndmask_b32_e32 v38, v38, v39, vcc
	v_cmp_class_f32_e32 vcc, v36, v193
	s_nop 1
	v_cndmask_b32_e32 v36, v38, v36, vcc
	ds_read2_b32 v[38:39], v32 offset0:192 offset1:224
	v_cmp_ngt_f32_e32 vcc, s24, v33
	s_nop 1
	v_cndmask_b32_e32 v33, 1.0, v36, vcc
	v_mul_f32_e32 v33, v34, v33
	s_waitcnt lgkmcnt(0)
	v_mul_f32_e32 v32, v38, v33
	ds_write_b32 v144, v35 offset:2816
	ds_write_b32 v144, v32 offset:39680
	v_add_f32_e32 v32, v56, v147
	v_mul_f32_e32 v32, 0xbfb8aa3b, v32
	v_exp_f32_e32 v32, v32
	v_add_f32_e32 v33, v40, v146
	v_mul_f32_e32 v33, 0xbfb8aa3b, v33
	v_exp_f32_e32 v33, v33
	v_add_f32_e32 v32, 1.0, v32
	v_rcp_f32_e32 v32, v32
	v_add_f32_e32 v33, 1.0, v33
	v_rcp_f32_e32 v33, v33
	v_mul_f32_e32 v32, v32, v96
	v_mul_f32_e32 v34, 0x3fb8aa3b, v32
	v_add_f32_e32 v32, v32, v32
	v_mul_f32_e32 v35, 0x3fb8aa3b, v32
	v_rndne_f32_e32 v35, v35
	v_fmamk_f32 v36, v35, 0xbf317218, v32
	v_fmac_f32_e32 v36, 0x3102e308, v35
	v_fmamk_f32 v38, v36, 0x395133b1, v192
	v_cmp_eq_f32_e32 vcc, s21, v35
	v_cvt_i32_f32_e32 v35, v35
	v_fmaak_f32 v38, v36, v38, 0x3c0887f9
	v_fmaak_f32 v38, v36, v38, 0x3d2aaa81
	v_fmaak_f32 v38, v36, v38, 0x3e2aaaab
	v_fma_f32 v38, v36, v38, 0.5
	v_ldexp_f32 v35, 1.0, v35
	v_mul_f32_e32 v38, v36, v38
	v_cndmask_b32_e32 v35, v35, v202, vcc
	v_fmac_f32_e32 v36, v36, v38
	v_add_f32_e32 v38, -1.0, v35
	v_fmac_f32_e32 v38, v35, v36
	v_add_f32_e32 v35, v38, v38
	v_cndmask_b32_e32 v35, v38, v35, vcc
	v_cmp_nlt_f32_e32 vcc, s22, v32
	v_exp_f32_e32 v34, v34
	s_nop 0
	v_cndmask_b32_e64 v35, v201, -v35, vcc
	v_cmp_gt_f32_e32 vcc, s23, v35
	v_mul_f32_e32 v36, 0x4f800000, v35
	s_nop 0
	v_cndmask_b32_e32 v35, v35, v36, vcc
	v_sqrt_f32_e32 v36, v35
	s_nop 0
	v_add_u32_e32 v38, -1, v36
	v_fma_f32 v40, -v38, v36, v35
	v_cmp_ge_f32_e64 s[0:1], 0, v40
	v_add_u32_e32 v40, 1, v36
	s_nop 0
	v_cndmask_b32_e64 v38, v36, v38, s[0:1]
	v_fma_f32 v36, -v40, v36, v35
	v_cmp_lt_f32_e64 s[0:1], 0, v36
	s_nop 1
	v_cndmask_b32_e64 v36, v38, v40, s[0:1]
	v_mul_f32_e32 v38, 0x37800000, v36
	v_cndmask_b32_e32 v36, v36, v38, vcc
	v_cmp_class_f32_e32 vcc, v35, v193
	s_nop 1
	v_cndmask_b32_e32 v35, v36, v35, vcc
	v_cmp_ngt_f32_e32 vcc, s24, v32
	s_nop 1
	v_cndmask_b32_e32 v32, 1.0, v35, vcc
	v_mul_f32_e32 v33, v33, v32
	v_add_u32_e32 v32, 0xa000, v144
	ds_read2_b32 v[54:55], v32 offset1:32
	s_waitcnt lgkmcnt(0)
	v_mul_f32_e32 v33, v54, v33
	ds_write_b32 v144, v34 offset:4096
	ds_write_b32 v144, v33 offset:40960
	v_add_f32_e32 v33, v57, v147
	v_mul_f32_e32 v33, 0xbfb8aa3b, v33
	v_exp_f32_e32 v33, v33
	v_add_f32_e32 v34, v41, v146
	v_mul_f32_e32 v34, 0xbfb8aa3b, v34
	v_exp_f32_e32 v34, v34
	v_add_f32_e32 v33, 1.0, v33
	v_rcp_f32_e32 v33, v33
	v_add_f32_e32 v34, 1.0, v34
	v_rcp_f32_e32 v34, v34
	v_mul_f32_e32 v33, v33, v96
	v_mul_f32_e32 v35, 0x3fb8aa3b, v33
	v_add_f32_e32 v33, v33, v33
	v_mul_f32_e32 v36, 0x3fb8aa3b, v33
	v_rndne_f32_e32 v36, v36
	v_fmamk_f32 v38, v36, 0xbf317218, v33
	v_fmac_f32_e32 v38, 0x3102e308, v36
	v_fmamk_f32 v40, v38, 0x395133b1, v192
	v_cmp_eq_f32_e32 vcc, s21, v36
	v_cvt_i32_f32_e32 v36, v36
	v_fmaak_f32 v40, v38, v40, 0x3c0887f9
	v_fmaak_f32 v40, v38, v40, 0x3d2aaa81
	v_fmaak_f32 v40, v38, v40, 0x3e2aaaab
	v_fma_f32 v40, v38, v40, 0.5
	v_ldexp_f32 v36, 1.0, v36
	v_mul_f32_e32 v40, v38, v40
	v_cndmask_b32_e32 v36, v36, v202, vcc
	v_fmac_f32_e32 v38, v38, v40
	v_add_f32_e32 v40, -1.0, v36
	v_fmac_f32_e32 v40, v36, v38
	v_add_f32_e32 v36, v40, v40
	v_cndmask_b32_e32 v36, v40, v36, vcc
	v_cmp_nlt_f32_e32 vcc, s22, v33
	v_exp_f32_e32 v35, v35
	s_nop 0
	v_cndmask_b32_e64 v36, v201, -v36, vcc
	v_cmp_gt_f32_e32 vcc, s23, v36
	v_mul_f32_e32 v38, 0x4f800000, v36
	s_nop 0
	v_cndmask_b32_e32 v36, v36, v38, vcc
	v_sqrt_f32_e32 v38, v36
	s_nop 0
	v_add_u32_e32 v40, -1, v38
	v_fma_f32 v41, -v40, v38, v36
	v_cmp_ge_f32_e64 s[0:1], 0, v41
	v_add_u32_e32 v41, 1, v38
	s_nop 0
	v_cndmask_b32_e64 v40, v38, v40, s[0:1]
	v_fma_f32 v38, -v41, v38, v36
	v_cmp_lt_f32_e64 s[0:1], 0, v38
	s_nop 1
	v_cndmask_b32_e64 v38, v40, v41, s[0:1]
	v_mul_f32_e32 v40, 0x37800000, v38
	v_cndmask_b32_e32 v38, v38, v40, vcc
	ds_read2_b32 v[40:41], v32 offset0:64 offset1:96
	v_cmp_class_f32_e32 vcc, v36, v193
	s_nop 1
	v_cndmask_b32_e32 v36, v38, v36, vcc
	v_cmp_ngt_f32_e32 vcc, s24, v33
	s_nop 1
	v_cndmask_b32_e32 v33, 1.0, v36, vcc
	v_mul_f32_e32 v33, v34, v33
	s_waitcnt lgkmcnt(0)
	v_mul_f32_e32 v33, v40, v33
	ds_write_b32 v144, v35 offset:4352
	ds_write_b32 v144, v33 offset:41216
	v_add_f32_e32 v33, v58, v147
	v_mul_f32_e32 v33, 0xbfb8aa3b, v33
	v_exp_f32_e32 v33, v33
	v_add_f32_e32 v34, v42, v146
	v_mul_f32_e32 v34, 0xbfb8aa3b, v34
	v_exp_f32_e32 v34, v34
	v_add_f32_e32 v33, 1.0, v33
	v_rcp_f32_e32 v33, v33
	ds_read2_b32 v[56:57], v32 offset0:128 offset1:160
	v_add_f32_e32 v34, 1.0, v34
	v_rcp_f32_e32 v34, v34
	v_mul_f32_e32 v33, v33, v96
	v_mul_f32_e32 v35, 0x3fb8aa3b, v33
	v_add_f32_e32 v33, v33, v33
	v_mul_f32_e32 v36, 0x3fb8aa3b, v33
	v_rndne_f32_e32 v36, v36
	v_fmamk_f32 v38, v36, 0xbf317218, v33
	v_fmac_f32_e32 v38, 0x3102e308, v36
	v_fmamk_f32 v40, v38, 0x395133b1, v192
	v_cmp_eq_f32_e32 vcc, s21, v36
	v_cvt_i32_f32_e32 v36, v36
	v_fmaak_f32 v40, v38, v40, 0x3c0887f9
	v_fmaak_f32 v40, v38, v40, 0x3d2aaa81
	v_fmaak_f32 v40, v38, v40, 0x3e2aaaab
	v_fma_f32 v40, v38, v40, 0.5
	v_ldexp_f32 v36, 1.0, v36
	v_mul_f32_e32 v40, v38, v40
	v_cndmask_b32_e32 v36, v36, v202, vcc
	v_fmac_f32_e32 v38, v38, v40
	v_add_f32_e32 v40, -1.0, v36
	v_fmac_f32_e32 v40, v36, v38
	v_add_f32_e32 v36, v40, v40
	v_cndmask_b32_e32 v36, v40, v36, vcc
	v_cmp_nlt_f32_e32 vcc, s22, v33
	v_exp_f32_e32 v35, v35
	s_nop 0
	v_cndmask_b32_e64 v36, v201, -v36, vcc
	v_cmp_gt_f32_e32 vcc, s23, v36
	v_mul_f32_e32 v38, 0x4f800000, v36
	s_nop 0
	v_cndmask_b32_e32 v36, v36, v38, vcc
	v_sqrt_f32_e32 v38, v36
	s_nop 0
	v_add_u32_e32 v40, -1, v38
	v_fma_f32 v42, -v40, v38, v36
	v_cmp_ge_f32_e64 s[0:1], 0, v42
	v_add_u32_e32 v42, 1, v38
	s_nop 0
	v_cndmask_b32_e64 v40, v38, v40, s[0:1]
	v_fma_f32 v38, -v42, v38, v36
	v_cmp_lt_f32_e64 s[0:1], 0, v38
	s_nop 1
	v_cndmask_b32_e64 v38, v40, v42, s[0:1]
	v_mul_f32_e32 v40, 0x37800000, v38
	v_cndmask_b32_e32 v38, v38, v40, vcc
	v_cmp_class_f32_e32 vcc, v36, v193
	s_nop 1
	v_cndmask_b32_e32 v36, v38, v36, vcc
	v_cmp_ngt_f32_e32 vcc, s24, v33
	s_nop 1
	v_cndmask_b32_e32 v33, 1.0, v36, vcc
	v_mul_f32_e32 v33, v34, v33
	s_waitcnt lgkmcnt(0)
	v_mul_f32_e32 v33, v56, v33
	ds_write_b32 v144, v35 offset:4608
	ds_write_b32 v144, v33 offset:41472
	v_add_f32_e32 v33, v59, v147
	v_mul_f32_e32 v33, 0xbfb8aa3b, v33
	v_exp_f32_e32 v33, v33
	v_add_f32_e32 v34, v43, v146
	v_mul_f32_e32 v34, 0xbfb8aa3b, v34
	v_exp_f32_e32 v34, v34
	v_add_f32_e32 v33, 1.0, v33
	v_rcp_f32_e32 v33, v33
	v_add_f32_e32 v34, 1.0, v34
	v_rcp_f32_e32 v34, v34
	v_mul_f32_e32 v33, v33, v96
	v_mul_f32_e32 v35, 0x3fb8aa3b, v33
	v_add_f32_e32 v33, v33, v33
	v_mul_f32_e32 v36, 0x3fb8aa3b, v33
	v_rndne_f32_e32 v36, v36
	v_fmamk_f32 v38, v36, 0xbf317218, v33
	v_fmac_f32_e32 v38, 0x3102e308, v36
	v_fmamk_f32 v40, v38, 0x395133b1, v192
	v_cmp_eq_f32_e32 vcc, s21, v36
	v_cvt_i32_f32_e32 v36, v36
	v_fmaak_f32 v40, v38, v40, 0x3c0887f9
	v_fmaak_f32 v40, v38, v40, 0x3d2aaa81
	v_fmaak_f32 v40, v38, v40, 0x3e2aaaab
	v_fma_f32 v40, v38, v40, 0.5
	v_ldexp_f32 v36, 1.0, v36
	v_mul_f32_e32 v40, v38, v40
	v_cndmask_b32_e32 v36, v36, v202, vcc
	v_fmac_f32_e32 v38, v38, v40
	v_add_f32_e32 v40, -1.0, v36
	v_fmac_f32_e32 v40, v36, v38
	v_add_f32_e32 v36, v40, v40
	v_cndmask_b32_e32 v36, v40, v36, vcc
	v_cmp_nlt_f32_e32 vcc, s22, v33
	v_exp_f32_e32 v35, v35
	s_nop 0
	v_cndmask_b32_e64 v36, v201, -v36, vcc
	v_cmp_gt_f32_e32 vcc, s23, v36
	v_mul_f32_e32 v38, 0x4f800000, v36
	s_nop 0
	v_cndmask_b32_e32 v36, v36, v38, vcc
	v_sqrt_f32_e32 v38, v36
	s_nop 0
	v_add_u32_e32 v40, -1, v38
	v_fma_f32 v42, -v40, v38, v36
	v_cmp_ge_f32_e64 s[0:1], 0, v42
	v_add_u32_e32 v42, 1, v38
	s_nop 0
	v_cndmask_b32_e64 v40, v38, v40, s[0:1]
	v_fma_f32 v38, -v42, v38, v36
	v_cmp_lt_f32_e64 s[0:1], 0, v38
	s_nop 1
	v_cndmask_b32_e64 v38, v40, v42, s[0:1]
	v_mul_f32_e32 v40, 0x37800000, v38
	ds_read2_b32 v[42:43], v32 offset0:192 offset1:224
	v_cndmask_b32_e32 v38, v38, v40, vcc
	v_cmp_class_f32_e32 vcc, v36, v193
	s_nop 1
	v_cndmask_b32_e32 v36, v38, v36, vcc
	v_cmp_ngt_f32_e32 vcc, s24, v33
	s_nop 1
	v_cndmask_b32_e32 v33, 1.0, v36, vcc
	v_mul_f32_e32 v33, v34, v33
	s_waitcnt lgkmcnt(0)
	v_mul_f32_e32 v32, v42, v33
	ds_write_b32 v144, v35 offset:4864
	ds_write_b32 v144, v32 offset:41728
	v_add_f32_e32 v32, v60, v147
	v_mul_f32_e32 v32, 0xbfb8aa3b, v32
	v_exp_f32_e32 v32, v32
	v_add_f32_e32 v33, v44, v146
	v_mul_f32_e32 v33, 0xbfb8aa3b, v33
	v_exp_f32_e32 v33, v33
	v_add_f32_e32 v32, 1.0, v32
	v_rcp_f32_e32 v32, v32
	v_add_f32_e32 v33, 1.0, v33
	v_rcp_f32_e32 v33, v33
	v_mul_f32_e32 v32, v32, v96
	v_mul_f32_e32 v34, 0x3fb8aa3b, v32
	v_add_f32_e32 v32, v32, v32
	v_mul_f32_e32 v35, 0x3fb8aa3b, v32
	v_rndne_f32_e32 v35, v35
	v_fmamk_f32 v36, v35, 0xbf317218, v32
	v_fmac_f32_e32 v36, 0x3102e308, v35
	v_fmamk_f32 v38, v36, 0x395133b1, v192
	v_cmp_eq_f32_e32 vcc, s21, v35
	v_cvt_i32_f32_e32 v35, v35
	v_fmaak_f32 v38, v36, v38, 0x3c0887f9
	v_fmaak_f32 v38, v36, v38, 0x3d2aaa81
	v_fmaak_f32 v38, v36, v38, 0x3e2aaaab
	v_fma_f32 v38, v36, v38, 0.5
	v_ldexp_f32 v35, 1.0, v35
	v_mul_f32_e32 v38, v36, v38
	v_cndmask_b32_e32 v35, v35, v202, vcc
	v_fmac_f32_e32 v36, v36, v38
	v_add_f32_e32 v38, -1.0, v35
	v_fmac_f32_e32 v38, v35, v36
	v_add_f32_e32 v35, v38, v38
	v_cndmask_b32_e32 v35, v38, v35, vcc
	v_cmp_nlt_f32_e32 vcc, s22, v32
	v_exp_f32_e32 v34, v34
	s_nop 0
	v_cndmask_b32_e64 v35, v201, -v35, vcc
	v_cmp_gt_f32_e32 vcc, s23, v35
	v_mul_f32_e32 v36, 0x4f800000, v35
	s_nop 0
	v_cndmask_b32_e32 v35, v35, v36, vcc
	v_sqrt_f32_e32 v36, v35
	s_nop 0
	v_add_u32_e32 v38, -1, v36
	v_fma_f32 v40, -v38, v36, v35
	v_cmp_ge_f32_e64 s[0:1], 0, v40
	v_add_u32_e32 v40, 1, v36
	s_nop 0
	v_cndmask_b32_e64 v38, v36, v38, s[0:1]
	v_fma_f32 v36, -v40, v36, v35
	v_cmp_lt_f32_e64 s[0:1], 0, v36
	s_nop 1
	v_cndmask_b32_e64 v36, v38, v40, s[0:1]
	v_mul_f32_e32 v38, 0x37800000, v36
	v_cndmask_b32_e32 v36, v36, v38, vcc
	v_cmp_class_f32_e32 vcc, v35, v193
	s_nop 1
	v_cndmask_b32_e32 v35, v36, v35, vcc
	v_cmp_ngt_f32_e32 vcc, s24, v32
	s_nop 1
	v_cndmask_b32_e32 v32, 1.0, v35, vcc
	v_mul_f32_e32 v32, v33, v32
	v_add_u32_e32 v33, 0xa800, v144
	ds_read2_b32 v[58:59], v33 offset1:32
	s_waitcnt lgkmcnt(0)
	v_mul_f32_e32 v32, v58, v32
	ds_write_b32 v144, v34 offset:6144
	ds_write_b32 v144, v32 offset:43008
	v_add_f32_e32 v32, v61, v147
	v_mul_f32_e32 v32, 0xbfb8aa3b, v32
	v_exp_f32_e32 v32, v32
	v_add_f32_e32 v34, v45, v146
	v_mul_f32_e32 v34, 0xbfb8aa3b, v34
	v_exp_f32_e32 v34, v34
	v_add_f32_e32 v32, 1.0, v32
	v_rcp_f32_e32 v32, v32
	ds_read2_b32 v[44:45], v33 offset0:64 offset1:96
	v_add_f32_e32 v34, 1.0, v34
	v_rcp_f32_e32 v34, v34
	v_mul_f32_e32 v32, v32, v96
	v_mul_f32_e32 v35, 0x3fb8aa3b, v32
	v_add_f32_e32 v32, v32, v32
	v_mul_f32_e32 v36, 0x3fb8aa3b, v32
	v_rndne_f32_e32 v36, v36
	v_fmamk_f32 v38, v36, 0xbf317218, v32
	v_fmac_f32_e32 v38, 0x3102e308, v36
	v_fmamk_f32 v40, v38, 0x395133b1, v192
	v_cmp_eq_f32_e32 vcc, s21, v36
	v_cvt_i32_f32_e32 v36, v36
	v_fmaak_f32 v40, v38, v40, 0x3c0887f9
	v_fmaak_f32 v40, v38, v40, 0x3d2aaa81
	v_fmaak_f32 v40, v38, v40, 0x3e2aaaab
	v_fma_f32 v40, v38, v40, 0.5
	v_ldexp_f32 v36, 1.0, v36
	v_mul_f32_e32 v40, v38, v40
	v_cndmask_b32_e32 v36, v36, v202, vcc
	v_fmac_f32_e32 v38, v38, v40
	v_add_f32_e32 v40, -1.0, v36
	v_fmac_f32_e32 v40, v36, v38
	v_add_f32_e32 v36, v40, v40
	v_cndmask_b32_e32 v36, v40, v36, vcc
	v_cmp_nlt_f32_e32 vcc, s22, v32
	v_exp_f32_e32 v35, v35
	s_nop 0
	v_cndmask_b32_e64 v36, v201, -v36, vcc
	v_cmp_gt_f32_e32 vcc, s23, v36
	v_mul_f32_e32 v38, 0x4f800000, v36
	s_nop 0
	v_cndmask_b32_e32 v36, v36, v38, vcc
	v_sqrt_f32_e32 v38, v36
	s_nop 0
	v_add_u32_e32 v40, -1, v38
	v_fma_f32 v42, -v40, v38, v36
	v_cmp_ge_f32_e64 s[0:1], 0, v42
	v_add_u32_e32 v42, 1, v38
	s_nop 0
	v_cndmask_b32_e64 v40, v38, v40, s[0:1]
	v_fma_f32 v38, -v42, v38, v36
	v_cmp_lt_f32_e64 s[0:1], 0, v38
	s_nop 1
	v_cndmask_b32_e64 v38, v40, v42, s[0:1]
	v_mul_f32_e32 v40, 0x37800000, v38
	v_cndmask_b32_e32 v38, v38, v40, vcc
	v_cmp_class_f32_e32 vcc, v36, v193
	s_nop 1
	v_cndmask_b32_e32 v36, v38, v36, vcc
	v_cmp_ngt_f32_e32 vcc, s24, v32
	s_nop 1
	v_cndmask_b32_e32 v32, 1.0, v36, vcc
	v_mul_f32_e32 v32, v34, v32
	s_waitcnt lgkmcnt(0)
	v_mul_f32_e32 v32, v44, v32
	ds_write_b32 v144, v35 offset:6400
	ds_write_b32 v144, v32 offset:43264
	v_add_f32_e32 v32, v62, v147
	v_mul_f32_e32 v32, 0xbfb8aa3b, v32
	v_exp_f32_e32 v32, v32
	v_add_f32_e32 v34, v46, v146
	v_mul_f32_e32 v34, 0xbfb8aa3b, v34
	v_exp_f32_e32 v34, v34
	v_add_f32_e32 v32, 1.0, v32
	v_rcp_f32_e32 v32, v32
	v_add_f32_e32 v34, 1.0, v34
	v_rcp_f32_e32 v34, v34
	v_mul_f32_e32 v32, v32, v96
	v_mul_f32_e32 v35, 0x3fb8aa3b, v32
	v_add_f32_e32 v32, v32, v32
	v_exp_f32_e32 v36, v35
	v_mul_f32_e32 v35, 0x3fb8aa3b, v32
	v_rndne_f32_e32 v35, v35
	v_fmamk_f32 v38, v35, 0xbf317218, v32
	v_fmac_f32_e32 v38, 0x3102e308, v35
	v_fmamk_f32 v40, v38, 0x395133b1, v192
	v_cmp_eq_f32_e32 vcc, s21, v35
	v_cvt_i32_f32_e32 v35, v35
	v_fmaak_f32 v40, v38, v40, 0x3c0887f9
	v_fmaak_f32 v40, v38, v40, 0x3d2aaa81
	v_fmaak_f32 v40, v38, v40, 0x3e2aaaab
	v_fma_f32 v40, v38, v40, 0.5
	v_ldexp_f32 v35, 1.0, v35
	v_mul_f32_e32 v40, v38, v40
	v_cndmask_b32_e32 v35, v35, v202, vcc
	v_fmac_f32_e32 v38, v38, v40
	v_add_f32_e32 v40, -1.0, v35
	v_fmac_f32_e32 v40, v35, v38
	v_add_f32_e32 v35, v40, v40
	v_cndmask_b32_e32 v35, v40, v35, vcc
	v_cmp_nlt_f32_e32 vcc, s22, v32
	s_nop 1
	v_cndmask_b32_e64 v35, v201, -v35, vcc
	v_cmp_gt_f32_e32 vcc, s23, v35
	v_mul_f32_e32 v38, 0x4f800000, v35
	s_nop 0
	v_cndmask_b32_e32 v35, v35, v38, vcc
	v_sqrt_f32_e32 v38, v35
	s_nop 0
	v_add_u32_e32 v40, -1, v38
	v_fma_f32 v42, -v40, v38, v35
	v_cmp_ge_f32_e64 s[0:1], 0, v42
	v_add_u32_e32 v42, 1, v38
	s_nop 0
	v_cndmask_b32_e64 v40, v38, v40, s[0:1]
	v_fma_f32 v38, -v42, v38, v35
	v_cmp_lt_f32_e64 s[0:1], 0, v38
	s_nop 1
	v_cndmask_b32_e64 v38, v40, v42, s[0:1]
	v_mul_f32_e32 v40, 0x37800000, v38
	v_cndmask_b32_e32 v38, v38, v40, vcc
	v_cmp_class_f32_e32 vcc, v35, v193
	s_nop 1
	v_cndmask_b32_e32 v35, v38, v35, vcc
	v_cmp_ngt_f32_e32 vcc, s24, v32
	s_nop 1
	v_cndmask_b32_e32 v32, 1.0, v35, vcc
	v_mul_f32_e32 v32, v34, v32
	ds_read2_b32 v[34:35], v33 offset0:128 offset1:160
	s_waitcnt lgkmcnt(0)
	v_mul_f32_e32 v32, v34, v32
	ds_write_b32 v144, v36 offset:6656
	ds_write_b32 v144, v32 offset:43520
	v_add_f32_e32 v32, v63, v147
	v_mul_f32_e32 v32, 0xbfb8aa3b, v32
	v_exp_f32_e32 v32, v32
	v_add_f32_e32 v34, v47, v146
	v_mul_f32_e32 v34, 0xbfb8aa3b, v34
	v_exp_f32_e32 v34, v34
	v_add_f32_e32 v32, 1.0, v32
	v_rcp_f32_e32 v32, v32
	v_add_f32_e32 v34, 1.0, v34
	v_rcp_f32_e32 v36, v34
	v_mul_f32_e32 v32, v32, v96
	v_mul_f32_e32 v34, 0x3fb8aa3b, v32
	v_add_f32_e32 v32, v32, v32
	v_mul_f32_e32 v38, 0x3fb8aa3b, v32
	v_rndne_f32_e32 v38, v38
	v_fmamk_f32 v40, v38, 0xbf317218, v32
	v_fmac_f32_e32 v40, 0x3102e308, v38
	v_fmamk_f32 v42, v40, 0x395133b1, v192
	v_cmp_eq_f32_e32 vcc, s21, v38
	v_cvt_i32_f32_e32 v38, v38
	v_fmaak_f32 v42, v40, v42, 0x3c0887f9
	v_fmaak_f32 v42, v40, v42, 0x3d2aaa81
	v_fmaak_f32 v42, v40, v42, 0x3e2aaaab
	v_fma_f32 v42, v40, v42, 0.5
	v_ldexp_f32 v38, 1.0, v38
	v_mul_f32_e32 v42, v40, v42
	v_cndmask_b32_e32 v38, v38, v202, vcc
	v_fmac_f32_e32 v40, v40, v42
	v_add_f32_e32 v42, -1.0, v38
	v_fmac_f32_e32 v42, v38, v40
	v_add_f32_e32 v38, v42, v42
	v_cndmask_b32_e32 v38, v42, v38, vcc
	v_cmp_nlt_f32_e32 vcc, s22, v32
	v_add_u32_e32 v96, s3, v145
	v_lshlrev_b64 v[46:47], 2, v[96:97]
	v_cndmask_b32_e64 v38, v201, -v38, vcc
	v_cmp_gt_f32_e32 vcc, s23, v38
	v_mul_f32_e32 v40, 0x4f800000, v38
	v_lshl_add_u64 v[60:61], s[18:19], 0, v[46:47]
	v_cndmask_b32_e32 v38, v38, v40, vcc
	v_sqrt_f32_e32 v40, v38
	v_exp_f32_e32 v34, v34
	s_movk_i32 s18, 0x1600
	s_mov_b32 s19, 0x2c000
	v_add_u32_e32 v42, -1, v40
	v_fma_f32 v44, -v42, v40, v38
	v_cmp_ge_f32_e64 s[0:1], 0, v44
	v_add_u32_e32 v44, 1, v40
	s_nop 0
	v_cndmask_b32_e64 v42, v40, v42, s[0:1]
	v_fma_f32 v40, -v44, v40, v38
	v_cmp_lt_f32_e64 s[0:1], 0, v40
	s_nop 1
	v_cndmask_b32_e64 v40, v42, v44, s[0:1]
	v_mul_f32_e32 v42, 0x37800000, v40
	v_cndmask_b32_e32 v40, v40, v42, vcc
	v_cmp_class_f32_e32 vcc, v38, v193
	s_nop 1
	v_cndmask_b32_e32 v38, v40, v38, vcc
	v_cmp_ngt_f32_e32 vcc, s24, v32
	s_nop 1
	v_cndmask_b32_e32 v32, 1.0, v38, vcc
	v_mul_f32_e32 v36, v36, v32
	ds_read2_b32 v[32:33], v33 offset0:192 offset1:224
	s_waitcnt lgkmcnt(0)
	v_mul_f32_e32 v32, v32, v36
	ds_write_b32 v144, v32 offset:43776
	s_waitcnt vmcnt(0)
	v_mul_f32_e32 v32, 0xbfb8aa3b, v226
	v_exp_f32_e32 v32, v32
	s_nop 0
	v_add_f32_e32 v36, 1.0, v32
	v_add_f32_e32 v38, -1.0, v36
	v_sub_f32_e32 v40, v38, v36
	v_add_f32_e32 v40, 1.0, v40
	v_sub_f32_e32 v38, v32, v38
	v_add_f32_e32 v38, v38, v40
	v_frexp_mant_f32_e32 v40, v36
	v_cvt_f64_f32_e32 v[60:61], v36
	v_cmp_gt_f32_e32 vcc, s8, v40
	v_frexp_exp_i32_f64_e32 v40, v[60:61]
	s_nop 0
	v_subbrev_co_u32_e32 v40, vcc, 0, v40, vcc
	v_sub_u32_e32 v42, 0, v40
	v_ldexp_f32 v36, v36, v42
	v_ldexp_f32 v38, v38, v42
	v_add_f32_e32 v42, -1.0, v36
	v_add_f32_e32 v48, 1.0, v36
	v_add_f32_e32 v44, 1.0, v42
	v_add_f32_e32 v50, -1.0, v48
	v_sub_f32_e32 v44, v36, v44
	v_sub_f32_e32 v36, v36, v50
	v_add_f32_e32 v36, v38, v36
	v_add_f32_e32 v44, v38, v44
	v_add_f32_e32 v38, v48, v36
	v_sub_f32_e32 v48, v38, v48
	v_sub_f32_e32 v36, v36, v48
	v_rcp_f32_e32 v48, v38
	v_add_f32_e32 v61, v42, v44
	v_sub_f32_e32 v42, v61, v42
	v_sub_f32_e32 v42, v44, v42
	v_mul_f32_e32 v44, v61, v48
	v_mul_f32_e32 v62, v38, v44
	v_fma_f32 v146, v44, v38, -v62
	v_fmac_f32_e32 v146, v44, v36
	v_add_f32_e32 v60, v62, v146
	v_sub_f32_e32 v63, v61, v60
	v_pk_add_f32 v[148:149], v[60:61], v[62:63] neg_lo:[0,1] neg_hi:[0,1]
	v_mov_b32_e32 v147, v60
	v_pk_add_f32 v[60:61], v[148:149], v[146:147] neg_lo:[0,1] neg_hi:[0,1]
	v_cmp_neq_f32_e32 vcc, s10, v32
	v_add_f32_e32 v42, v42, v61
	v_add_f32_e32 v42, v60, v42
	v_add_f32_e32 v61, v63, v42
	v_mul_f32_e32 v50, v48, v61
	v_mul_f32_e32 v62, v38, v50
	v_fma_f32 v146, v50, v38, -v62
	v_fmac_f32_e32 v146, v50, v36
	v_add_f32_e32 v60, v62, v146
	v_sub_f32_e32 v36, v63, v61
	v_sub_f32_e32 v63, v61, v60
	v_pk_add_f32 v[148:149], v[60:61], v[62:63] neg_lo:[0,1] neg_hi:[0,1]
	v_mov_b32_e32 v147, v60
	v_add_f32_e32 v36, v42, v36
	v_pk_add_f32 v[60:61], v[148:149], v[146:147] neg_lo:[0,1] neg_hi:[0,1]
	v_add_f32_e32 v38, v44, v50
	v_add_f32_e32 v36, v36, v61
	v_add_f32_e32 v36, v60, v36
	v_add_f32_e32 v36, v63, v36
	v_sub_f32_e32 v42, v38, v44
	v_mul_f32_e32 v36, v48, v36
	v_sub_f32_e32 v42, v50, v42
	v_add_f32_e32 v36, v42, v36
	v_add_f32_e32 v42, v38, v36
	v_cvt_f32_i32_e32 v60, v40
	v_mul_f32_e32 v44, v42, v42
	v_fmamk_f32 v48, v44, 0x3e9b6dac, v191
	v_fmaak_f32 v169, v44, v48, 0x3f2aaada
	v_mul_f32_e32 v61, v42, v44
	v_pk_mul_f32 v[146:147], v[60:61], v[168:169]
	v_ldexp_f32 v63, v42, 1
	v_fma_f32 v62, v60, s9, -v146
	v_fmac_f32_e32 v62, 0xb102e308, v60
	v_sub_f32_e32 v38, v42, v38
	v_pk_add_f32 v[60:61], v[146:147], v[62:63]
	v_sub_f32_e32 v36, v36, v38
	v_sub_f32_e32 v38, v61, v63
	v_ldexp_f32 v36, v36, 1
	v_sub_f32_e32 v38, v147, v38
	v_add_f32_e32 v149, v36, v38
	v_mov_b32_e32 v148, v146
	v_pk_add_f32 v[146:147], v[60:61], v[146:147] neg_lo:[0,1] neg_hi:[0,1]
	v_pk_add_f32 v[150:151], v[60:61], v[148:149]
	v_mov_b32_e32 v63, v60
	v_mov_b32_e32 v147, v151
	v_pk_add_f32 v[152:153], v[62:63], v[146:147] neg_lo:[0,1] neg_hi:[0,1]
	v_pk_add_f32 v[62:63], v[62:63], v[146:147]
	v_mov_b32_e32 v148, v149
	v_pk_add_f32 v[146:147], v[62:63], v[60:61] op_sel:[1,0] op_sel_hi:[0,1] neg_lo:[0,1] neg_hi:[0,1]
	v_pk_add_f32 v[154:155], v[150:151], v[146:147] op_sel_hi:[1,0] neg_lo:[0,1] neg_hi:[0,1]
	v_mov_b32_e32 v150, v151
	v_mov_b32_e32 v151, v63
	v_pk_mov_b32 v[146:147], v[60:61], v[146:147] op_sel:[1,0]
	v_mov_b32_e32 v149, v60
	v_pk_add_f32 v[146:147], v[150:151], v[146:147] neg_lo:[0,1] neg_hi:[0,1]
	v_mov_b32_e32 v154, v152
	v_pk_add_f32 v[60:61], v[148:149], v[146:147] neg_lo:[0,1] neg_hi:[0,1]
	v_mov_b32_e32 v153, v63
	v_pk_add_f32 v[146:147], v[154:155], v[60:61]
	v_readlane_b32 s10, v248, 33
	v_pk_add_f32 v[148:149], v[146:147], v[146:147] op_sel:[0,1] op_sel_hi:[1,0]
	v_pk_add_f32 v[62:63], v[62:63], v[148:149] op_sel:[1,0] op_sel_hi:[0,1]
	v_mov_b32_e32 v147, v62
	v_pk_add_f32 v[150:151], v[146:147], v[152:153] neg_lo:[0,1] neg_hi:[0,1]
	v_mov_b32_e32 v61, v148
	v_sub_f32_e32 v36, v146, v150
	v_pk_add_f32 v[60:61], v[60:61], v[150:151] neg_lo:[0,1] neg_hi:[0,1]
	v_sub_f32_e32 v36, v152, v36
	v_add_f32_e32 v36, v60, v36
	v_add_f32_e32 v36, v36, v61
	v_add_f32_e32 v36, v62, v36
	v_cndmask_b32_e32 v36, v199, v36, vcc
	v_cmp_ngt_f32_e32 vcc, -1.0, v32
	v_lshl_add_u64 v[60:61], s[52:53], 0, v[46:47]
	v_lshl_add_u64 v[46:47], s[16:17], 0, v[46:47]
	v_cndmask_b32_e32 v36, v200, v36, vcc
	v_cmp_neq_f32_e32 vcc, -1.0, v32
	v_mov_b32_e32 v38, v227
	s_mov_b64 s[16:17], s[82:83]
	v_cndmask_b32_e32 v36, v201, v36, vcc
	v_cmp_lt_f32_e64 vcc, |v32|, s20
	s_mov_b32 s20, 0x58000
	s_waitcnt vmcnt(0)
	v_add_f32_e32 v0, v0, v38
	v_cndmask_b32_e32 v32, v36, v32, vcc
	v_mov_b32_e32 v36, v228
	v_mul_f32_e32 v32, 0xc1000000, v32
	v_mul_f32_e32 v0, 0xbfb8aa3b, v0
	v_exp_f32_e32 v0, v0
	v_add_f32_e32 v1, v1, v38
	v_mul_f32_e32 v1, 0xbfb8aa3b, v1
	v_exp_f32_e32 v1, v1
	v_add_f32_e32 v0, 1.0, v0
	v_rcp_f32_e32 v0, v0
	v_add_f32_e32 v1, 1.0, v1
	v_rcp_f32_e32 v1, v1
	s_waitcnt vmcnt(0)
	v_add_f32_e32 v16, v16, v36
	v_mul_f32_e32 v16, 0xbfb8aa3b, v16
	v_exp_f32_e32 v16, v16
	s_nop 0
	v_add_f32_e32 v16, 1.0, v16
	v_rcp_f32_e32 v16, v16
	s_nop 0
	v_mul_f32_e32 v16, v16, v32
	v_mul_f32_e32 v40, 0x3fb8aa3b, v16
	v_add_f32_e32 v16, v16, v16
	v_mul_f32_e32 v42, 0x3fb8aa3b, v16
	v_rndne_f32_e32 v42, v42
	v_fmamk_f32 v44, v42, 0xbf317218, v16
	v_fmac_f32_e32 v44, 0x3102e308, v42
	v_fmamk_f32 v46, v44, 0x395133b1, v192
	v_cmp_eq_f32_e32 vcc, s21, v42
	v_cvt_i32_f32_e32 v42, v42
	v_fmaak_f32 v46, v44, v46, 0x3c0887f9
	v_fmaak_f32 v46, v44, v46, 0x3d2aaa81
	v_fmaak_f32 v46, v44, v46, 0x3e2aaaab
	v_fma_f32 v46, v44, v46, 0.5
	v_ldexp_f32 v42, 1.0, v42
	v_mul_f32_e32 v46, v44, v46
	v_cndmask_b32_e32 v42, v42, v202, vcc
	v_fmac_f32_e32 v44, v44, v46
	v_add_f32_e32 v46, -1.0, v42
	v_fmac_f32_e32 v46, v42, v44
	v_add_f32_e32 v42, v46, v46
	v_cndmask_b32_e32 v42, v46, v42, vcc
	v_cmp_nlt_f32_e32 vcc, s22, v16
	v_exp_f32_e32 v40, v40
	s_nop 0
	v_cndmask_b32_e64 v42, v201, -v42, vcc
	v_cmp_gt_f32_e32 vcc, s23, v42
	v_mul_f32_e32 v44, 0x4f800000, v42
	s_nop 0
	v_cndmask_b32_e32 v42, v42, v44, vcc
	v_sqrt_f32_e32 v44, v42
	s_nop 0
	v_add_u32_e32 v46, -1, v44
	v_fma_f32 v47, -v46, v44, v42
	v_cmp_ge_f32_e64 s[0:1], 0, v47
	v_add_u32_e32 v47, 1, v44
	s_nop 0
	v_cndmask_b32_e64 v46, v44, v46, s[0:1]
	v_fma_f32 v44, -v47, v44, v42
	v_cmp_lt_f32_e64 s[0:1], 0, v44
	s_nop 1
	v_cndmask_b32_e64 v44, v46, v47, s[0:1]
	v_mul_f32_e32 v46, 0x37800000, v44
	v_cndmask_b32_e32 v44, v44, v46, vcc
	v_cmp_class_f32_e32 vcc, v42, v193
	s_nop 1
	v_cndmask_b32_e32 v42, v44, v42, vcc
	v_cmp_ngt_f32_e32 vcc, s24, v16
	s_nop 1
	v_cndmask_b32_e32 v16, 1.0, v42, vcc
	v_mul_f32_e32 v0, v0, v16
	v_mul_f32_e32 v0, v135, v0
	ds_write_b32 v144, v40 offset:128
	ds_write_b32 v144, v0 offset:36992
	v_add_f32_e32 v0, v17, v36
	v_mul_f32_e32 v0, 0xbfb8aa3b, v0
	v_exp_f32_e32 v0, v0
	s_nop 0
	v_add_f32_e32 v0, 1.0, v0
	v_rcp_f32_e32 v0, v0
	s_nop 0
	v_mul_f32_e32 v0, v0, v32
	v_mul_f32_e32 v16, 0x3fb8aa3b, v0
	v_add_f32_e32 v0, v0, v0
	v_mul_f32_e32 v17, 0x3fb8aa3b, v0
	v_rndne_f32_e32 v17, v17
	v_fmamk_f32 v40, v17, 0xbf317218, v0
	v_fmac_f32_e32 v40, 0x3102e308, v17
	v_fmamk_f32 v42, v40, 0x395133b1, v192
	v_cmp_eq_f32_e32 vcc, s21, v17
	v_cvt_i32_f32_e32 v17, v17
	v_fmaak_f32 v42, v40, v42, 0x3c0887f9
	v_fmaak_f32 v42, v40, v42, 0x3d2aaa81
	v_fmaak_f32 v42, v40, v42, 0x3e2aaaab
	v_fma_f32 v42, v40, v42, 0.5
	v_ldexp_f32 v17, 1.0, v17
	v_mul_f32_e32 v42, v40, v42
	v_cndmask_b32_e32 v17, v17, v202, vcc
	v_fmac_f32_e32 v40, v40, v42
	v_add_f32_e32 v42, -1.0, v17
	v_fmac_f32_e32 v42, v17, v40
	v_add_f32_e32 v17, v42, v42
	v_cndmask_b32_e32 v17, v42, v17, vcc
	v_cmp_nlt_f32_e32 vcc, s22, v0
	v_exp_f32_e32 v16, v16
	s_nop 0
	v_cndmask_b32_e64 v17, v201, -v17, vcc
	v_cmp_gt_f32_e32 vcc, s23, v17
	v_mul_f32_e32 v40, 0x4f800000, v17
	s_nop 0
	v_cndmask_b32_e32 v17, v17, v40, vcc
	v_sqrt_f32_e32 v40, v17
	s_nop 0
	v_add_u32_e32 v42, -1, v40
	v_fma_f32 v44, -v42, v40, v17
	v_cmp_ge_f32_e64 s[0:1], 0, v44
	v_add_u32_e32 v44, 1, v40
	s_nop 0
	v_cndmask_b32_e64 v42, v40, v42, s[0:1]
	v_fma_f32 v40, -v44, v40, v17
	v_cmp_lt_f32_e64 s[0:1], 0, v40
	s_nop 1
	v_cndmask_b32_e64 v40, v42, v44, s[0:1]
	v_mul_f32_e32 v42, 0x37800000, v40
	v_cndmask_b32_e32 v40, v40, v42, vcc
	v_cmp_class_f32_e32 vcc, v17, v193
	s_nop 1
	v_cndmask_b32_e32 v17, v40, v17, vcc
	v_cmp_ngt_f32_e32 vcc, s24, v0
	s_nop 1
	v_cndmask_b32_e32 v0, 1.0, v17, vcc
	v_mul_f32_e32 v0, v1, v0
	v_mul_f32_e32 v0, v49, v0
	ds_write_b32 v144, v16 offset:384
	ds_write_b32 v144, v0 offset:37248
	v_add_f32_e32 v0, v18, v36
	v_mul_f32_e32 v0, 0xbfb8aa3b, v0
	v_exp_f32_e32 v0, v0
	v_add_f32_e32 v1, v2, v38
	v_mul_f32_e32 v1, 0xbfb8aa3b, v1
	v_exp_f32_e32 v1, v1
	v_add_f32_e32 v0, 1.0, v0
	v_rcp_f32_e32 v0, v0
	v_add_f32_e32 v1, 1.0, v1
	v_rcp_f32_e32 v1, v1
	v_mul_f32_e32 v0, v0, v32
	v_mul_f32_e32 v2, 0x3fb8aa3b, v0
	v_add_f32_e32 v0, v0, v0
	v_mul_f32_e32 v16, 0x3fb8aa3b, v0
	v_rndne_f32_e32 v16, v16
	v_fmamk_f32 v17, v16, 0xbf317218, v0
	v_fmac_f32_e32 v17, 0x3102e308, v16
	v_fmamk_f32 v18, v17, 0x395133b1, v192
	v_cmp_eq_f32_e32 vcc, s21, v16
	v_cvt_i32_f32_e32 v16, v16
	v_fmaak_f32 v18, v17, v18, 0x3c0887f9
	v_fmaak_f32 v18, v17, v18, 0x3d2aaa81
	v_fmaak_f32 v18, v17, v18, 0x3e2aaaab
	v_fma_f32 v18, v17, v18, 0.5
	v_ldexp_f32 v16, 1.0, v16
	v_mul_f32_e32 v18, v17, v18
	v_cndmask_b32_e32 v16, v16, v202, vcc
	v_fmac_f32_e32 v17, v17, v18
	v_add_f32_e32 v18, -1.0, v16
	v_fmac_f32_e32 v18, v16, v17
	v_add_f32_e32 v16, v18, v18
	v_cndmask_b32_e32 v16, v18, v16, vcc
	v_cmp_nlt_f32_e32 vcc, s22, v0
	v_exp_f32_e32 v2, v2
	s_nop 0
	v_cndmask_b32_e64 v16, v201, -v16, vcc
	v_cmp_gt_f32_e32 vcc, s23, v16
	v_mul_f32_e32 v17, 0x4f800000, v16
	s_nop 0
	v_cndmask_b32_e32 v16, v16, v17, vcc
	v_sqrt_f32_e32 v17, v16
	s_nop 0
	v_add_u32_e32 v18, -1, v17
	v_fma_f32 v40, -v18, v17, v16
	v_cmp_ge_f32_e64 s[0:1], 0, v40
	v_add_u32_e32 v40, 1, v17
	s_nop 0
	v_cndmask_b32_e64 v18, v17, v18, s[0:1]
	v_fma_f32 v17, -v40, v17, v16
	v_cmp_lt_f32_e64 s[0:1], 0, v17
	s_nop 1
	v_cndmask_b32_e64 v17, v18, v40, s[0:1]
	v_mul_f32_e32 v18, 0x37800000, v17
	v_cndmask_b32_e32 v17, v17, v18, vcc
	v_cmp_class_f32_e32 vcc, v16, v193
	s_nop 1
	v_cndmask_b32_e32 v16, v17, v16, vcc
	v_cmp_ngt_f32_e32 vcc, s24, v0
	s_nop 1
	v_cndmask_b32_e32 v0, 1.0, v16, vcc
	v_mul_f32_e32 v0, v1, v0
	v_mul_f32_e32 v0, v137, v0
	ds_write_b32 v144, v2 offset:640
	ds_write_b32 v144, v0 offset:37504
	v_add_f32_e32 v0, v19, v36
	v_mul_f32_e32 v0, 0xbfb8aa3b, v0
	v_exp_f32_e32 v0, v0
	v_add_f32_e32 v1, v3, v38
	v_mul_f32_e32 v1, 0xbfb8aa3b, v1
	v_exp_f32_e32 v1, v1
	v_add_f32_e32 v0, 1.0, v0
	v_rcp_f32_e32 v0, v0
	v_add_f32_e32 v1, 1.0, v1
	v_rcp_f32_e32 v1, v1
	v_mul_f32_e32 v0, v0, v32
	v_mul_f32_e32 v2, 0x3fb8aa3b, v0
	v_add_f32_e32 v0, v0, v0
	v_mul_f32_e32 v3, 0x3fb8aa3b, v0
	v_rndne_f32_e32 v3, v3
	v_fmamk_f32 v16, v3, 0xbf317218, v0
	v_fmac_f32_e32 v16, 0x3102e308, v3
	v_fmamk_f32 v17, v16, 0x395133b1, v192
	v_cmp_eq_f32_e32 vcc, s21, v3
	v_cvt_i32_f32_e32 v3, v3
	v_fmaak_f32 v17, v16, v17, 0x3c0887f9
	v_fmaak_f32 v17, v16, v17, 0x3d2aaa81
	v_fmaak_f32 v17, v16, v17, 0x3e2aaaab
	v_fma_f32 v17, v16, v17, 0.5
	v_ldexp_f32 v3, 1.0, v3
	v_mul_f32_e32 v17, v16, v17
	v_cndmask_b32_e32 v3, v3, v202, vcc
	v_fmac_f32_e32 v16, v16, v17
	v_add_f32_e32 v17, -1.0, v3
	v_fmac_f32_e32 v17, v3, v16
	v_add_f32_e32 v3, v17, v17
	v_cndmask_b32_e32 v3, v17, v3, vcc
	v_cmp_nlt_f32_e32 vcc, s22, v0
	v_exp_f32_e32 v2, v2
	s_nop 0
	v_cndmask_b32_e64 v3, v201, -v3, vcc
	v_cmp_gt_f32_e32 vcc, s23, v3
	v_mul_f32_e32 v16, 0x4f800000, v3
	s_nop 0
	v_cndmask_b32_e32 v3, v3, v16, vcc
	v_sqrt_f32_e32 v16, v3
	s_nop 0
	v_add_u32_e32 v17, -1, v16
	v_fma_f32 v18, -v17, v16, v3
	v_cmp_ge_f32_e64 s[0:1], 0, v18
	v_add_u32_e32 v18, 1, v16
	s_nop 0
	v_cndmask_b32_e64 v17, v16, v17, s[0:1]
	v_fma_f32 v16, -v18, v16, v3
	v_cmp_lt_f32_e64 s[0:1], 0, v16
	s_nop 1
	v_cndmask_b32_e64 v16, v17, v18, s[0:1]
	v_mul_f32_e32 v17, 0x37800000, v16
	v_cndmask_b32_e32 v16, v16, v17, vcc
	v_cmp_class_f32_e32 vcc, v3, v193
	s_nop 1
	v_cndmask_b32_e32 v3, v16, v3, vcc
	v_cmp_ngt_f32_e32 vcc, s24, v0
	s_nop 1
	v_cndmask_b32_e32 v0, 1.0, v3, vcc
	v_mul_f32_e32 v0, v1, v0
	v_mul_f32_e32 v0, v51, v0
	ds_write_b32 v144, v2 offset:896
	ds_write_b32 v144, v0 offset:37760
	v_add_f32_e32 v0, v20, v36
	v_mul_f32_e32 v0, 0xbfb8aa3b, v0
	v_exp_f32_e32 v0, v0
	v_add_f32_e32 v1, v4, v38
	v_mul_f32_e32 v1, 0xbfb8aa3b, v1
	v_exp_f32_e32 v1, v1
	v_add_f32_e32 v0, 1.0, v0
	v_rcp_f32_e32 v0, v0
	v_add_f32_e32 v1, 1.0, v1
	v_rcp_f32_e32 v1, v1
	v_mul_f32_e32 v0, v0, v32
	v_mul_f32_e32 v2, 0x3fb8aa3b, v0
	v_add_f32_e32 v0, v0, v0
	v_mul_f32_e32 v3, 0x3fb8aa3b, v0
	v_rndne_f32_e32 v3, v3
	v_fmamk_f32 v4, v3, 0xbf317218, v0
	v_fmac_f32_e32 v4, 0x3102e308, v3
	v_fmamk_f32 v16, v4, 0x395133b1, v192
	v_cmp_eq_f32_e32 vcc, s21, v3
	v_cvt_i32_f32_e32 v3, v3
	v_fmaak_f32 v16, v4, v16, 0x3c0887f9
	v_fmaak_f32 v16, v4, v16, 0x3d2aaa81
	v_fmaak_f32 v16, v4, v16, 0x3e2aaaab
	v_fma_f32 v16, v4, v16, 0.5
	v_ldexp_f32 v3, 1.0, v3
	v_mul_f32_e32 v16, v4, v16
	v_cndmask_b32_e32 v3, v3, v202, vcc
	v_fmac_f32_e32 v4, v4, v16
	v_add_f32_e32 v16, -1.0, v3
	v_fmac_f32_e32 v16, v3, v4
	v_add_f32_e32 v3, v16, v16
	v_cndmask_b32_e32 v3, v16, v3, vcc
	v_cmp_nlt_f32_e32 vcc, s22, v0
	v_exp_f32_e32 v2, v2
	s_nop 0
	v_cndmask_b32_e64 v3, v201, -v3, vcc
	v_cmp_gt_f32_e32 vcc, s23, v3
	v_mul_f32_e32 v4, 0x4f800000, v3
	s_nop 0
	v_cndmask_b32_e32 v3, v3, v4, vcc
	v_sqrt_f32_e32 v4, v3
	s_nop 0
	v_add_u32_e32 v16, -1, v4
	v_fma_f32 v17, -v16, v4, v3
	v_cmp_ge_f32_e64 s[0:1], 0, v17
	v_add_u32_e32 v17, 1, v4
	s_nop 0
	v_cndmask_b32_e64 v16, v4, v16, s[0:1]
	v_fma_f32 v4, -v17, v4, v3
	v_cmp_lt_f32_e64 s[0:1], 0, v4
	s_nop 1
	v_cndmask_b32_e64 v4, v16, v17, s[0:1]
	v_mul_f32_e32 v16, 0x37800000, v4
	v_cndmask_b32_e32 v4, v4, v16, vcc
	v_cmp_class_f32_e32 vcc, v3, v193
	s_nop 1
	v_cndmask_b32_e32 v3, v4, v3, vcc
	v_cmp_ngt_f32_e32 vcc, s24, v0
	s_nop 1
	v_cndmask_b32_e32 v0, 1.0, v3, vcc
	v_mul_f32_e32 v0, v1, v0
	v_mul_f32_e32 v0, v139, v0
	ds_write_b32 v144, v2 offset:2176
	ds_write_b32 v144, v0 offset:39040
	v_add_f32_e32 v0, v21, v36
	v_mul_f32_e32 v0, 0xbfb8aa3b, v0
	v_exp_f32_e32 v0, v0
	v_add_f32_e32 v1, v5, v38
	v_mul_f32_e32 v1, 0xbfb8aa3b, v1
	v_exp_f32_e32 v1, v1
	v_add_f32_e32 v0, 1.0, v0
	v_rcp_f32_e32 v0, v0
	v_add_f32_e32 v1, 1.0, v1
	v_rcp_f32_e32 v1, v1
	v_mul_f32_e32 v0, v0, v32
	v_mul_f32_e32 v2, 0x3fb8aa3b, v0
	v_add_f32_e32 v0, v0, v0
	v_mul_f32_e32 v3, 0x3fb8aa3b, v0
	v_rndne_f32_e32 v3, v3
	v_fmamk_f32 v4, v3, 0xbf317218, v0
	v_fmac_f32_e32 v4, 0x3102e308, v3
	v_fmamk_f32 v5, v4, 0x395133b1, v192
	v_cmp_eq_f32_e32 vcc, s21, v3
	v_cvt_i32_f32_e32 v3, v3
	v_fmaak_f32 v5, v4, v5, 0x3c0887f9
	v_fmaak_f32 v5, v4, v5, 0x3d2aaa81
	v_fmaak_f32 v5, v4, v5, 0x3e2aaaab
	v_fma_f32 v5, v4, v5, 0.5
	v_ldexp_f32 v3, 1.0, v3
	v_mul_f32_e32 v5, v4, v5
	v_cndmask_b32_e32 v3, v3, v202, vcc
	v_fmac_f32_e32 v4, v4, v5
	v_add_f32_e32 v5, -1.0, v3
	v_fmac_f32_e32 v5, v3, v4
	v_add_f32_e32 v3, v5, v5
	v_cndmask_b32_e32 v3, v5, v3, vcc
	v_cmp_nlt_f32_e32 vcc, s22, v0
	v_exp_f32_e32 v2, v2
	s_nop 0
	v_cndmask_b32_e64 v3, v201, -v3, vcc
	v_cmp_gt_f32_e32 vcc, s23, v3
	v_mul_f32_e32 v4, 0x4f800000, v3
	s_nop 0
	v_cndmask_b32_e32 v3, v3, v4, vcc
	v_sqrt_f32_e32 v4, v3
	s_nop 0
	v_add_u32_e32 v5, -1, v4
	v_fma_f32 v16, -v5, v4, v3
	v_cmp_ge_f32_e64 s[0:1], 0, v16
	v_add_u32_e32 v16, 1, v4
	s_nop 0
	v_cndmask_b32_e64 v5, v4, v5, s[0:1]
	v_fma_f32 v4, -v16, v4, v3
	v_cmp_lt_f32_e64 s[0:1], 0, v4
	s_nop 1
	v_cndmask_b32_e64 v4, v5, v16, s[0:1]
	v_mul_f32_e32 v5, 0x37800000, v4
	v_cndmask_b32_e32 v4, v4, v5, vcc
	v_cmp_class_f32_e32 vcc, v3, v193
	s_nop 1
	v_cndmask_b32_e32 v3, v4, v3, vcc
	v_cmp_ngt_f32_e32 vcc, s24, v0
	s_nop 1
	v_cndmask_b32_e32 v0, 1.0, v3, vcc
	v_mul_f32_e32 v0, v1, v0
	v_mul_f32_e32 v0, v37, v0
	ds_write_b32 v144, v2 offset:2432
	ds_write_b32 v144, v0 offset:39296
	v_add_f32_e32 v0, v22, v36
	v_mul_f32_e32 v0, 0xbfb8aa3b, v0
	v_exp_f32_e32 v0, v0
	v_add_f32_e32 v1, v6, v38
	v_mul_f32_e32 v1, 0xbfb8aa3b, v1
	v_exp_f32_e32 v1, v1
	v_add_f32_e32 v0, 1.0, v0
	v_rcp_f32_e32 v0, v0
	v_add_f32_e32 v1, 1.0, v1
	v_rcp_f32_e32 v1, v1
	v_mul_f32_e32 v0, v0, v32
	v_mul_f32_e32 v2, 0x3fb8aa3b, v0
	v_add_f32_e32 v0, v0, v0
	v_mul_f32_e32 v3, 0x3fb8aa3b, v0
	v_rndne_f32_e32 v3, v3
	v_fmamk_f32 v4, v3, 0xbf317218, v0
	v_fmac_f32_e32 v4, 0x3102e308, v3
	v_fmamk_f32 v5, v4, 0x395133b1, v192
	v_cmp_eq_f32_e32 vcc, s21, v3
	v_cvt_i32_f32_e32 v3, v3
	v_fmaak_f32 v5, v4, v5, 0x3c0887f9
	v_fmaak_f32 v5, v4, v5, 0x3d2aaa81
	v_fmaak_f32 v5, v4, v5, 0x3e2aaaab
	v_fma_f32 v5, v4, v5, 0.5
	v_ldexp_f32 v3, 1.0, v3
	v_mul_f32_e32 v5, v4, v5
	v_cndmask_b32_e32 v3, v3, v202, vcc
	v_fmac_f32_e32 v4, v4, v5
	v_add_f32_e32 v5, -1.0, v3
	v_fmac_f32_e32 v5, v3, v4
	v_add_f32_e32 v3, v5, v5
	v_cndmask_b32_e32 v3, v5, v3, vcc
	v_cmp_nlt_f32_e32 vcc, s22, v0
	v_exp_f32_e32 v2, v2
	s_nop 0
	v_cndmask_b32_e64 v3, v201, -v3, vcc
	v_cmp_gt_f32_e32 vcc, s23, v3
	v_mul_f32_e32 v4, 0x4f800000, v3
	s_nop 0
	v_cndmask_b32_e32 v3, v3, v4, vcc
	v_sqrt_f32_e32 v4, v3
	s_nop 0
	v_add_u32_e32 v5, -1, v4
	v_fma_f32 v6, -v5, v4, v3
	v_cmp_ge_f32_e64 s[0:1], 0, v6
	v_add_u32_e32 v6, 1, v4
	s_nop 0
	v_cndmask_b32_e64 v5, v4, v5, s[0:1]
	v_fma_f32 v4, -v6, v4, v3
	v_cmp_lt_f32_e64 s[0:1], 0, v4
	s_nop 1
	v_cndmask_b32_e64 v4, v5, v6, s[0:1]
	v_mul_f32_e32 v5, 0x37800000, v4
	v_cndmask_b32_e32 v4, v4, v5, vcc
	v_cmp_class_f32_e32 vcc, v3, v193
	s_nop 1
	v_cndmask_b32_e32 v3, v4, v3, vcc
	v_cmp_ngt_f32_e32 vcc, s24, v0
	s_nop 1
	v_cndmask_b32_e32 v0, 1.0, v3, vcc
	v_mul_f32_e32 v0, v1, v0
	v_mul_f32_e32 v0, v53, v0
	ds_write_b32 v144, v2 offset:2688
	ds_write_b32 v144, v0 offset:39552
	v_add_f32_e32 v0, v23, v36
	v_mul_f32_e32 v0, 0xbfb8aa3b, v0
	v_exp_f32_e32 v0, v0
	v_add_f32_e32 v1, v7, v38
	v_mul_f32_e32 v1, 0xbfb8aa3b, v1
	v_exp_f32_e32 v1, v1
	v_add_f32_e32 v0, 1.0, v0
	v_rcp_f32_e32 v0, v0
	v_add_f32_e32 v1, 1.0, v1
	v_rcp_f32_e32 v1, v1
	v_mul_f32_e32 v0, v0, v32
	v_mul_f32_e32 v2, 0x3fb8aa3b, v0
	v_add_f32_e32 v0, v0, v0
	v_mul_f32_e32 v3, 0x3fb8aa3b, v0
	v_rndne_f32_e32 v3, v3
	v_fmamk_f32 v4, v3, 0xbf317218, v0
	v_fmac_f32_e32 v4, 0x3102e308, v3
	v_fmamk_f32 v5, v4, 0x395133b1, v192
	v_cmp_eq_f32_e32 vcc, s21, v3
	v_cvt_i32_f32_e32 v3, v3
	v_fmaak_f32 v5, v4, v5, 0x3c0887f9
	v_fmaak_f32 v5, v4, v5, 0x3d2aaa81
	v_fmaak_f32 v5, v4, v5, 0x3e2aaaab
	v_fma_f32 v5, v4, v5, 0.5
	v_ldexp_f32 v3, 1.0, v3
	v_mul_f32_e32 v5, v4, v5
	v_cndmask_b32_e32 v3, v3, v202, vcc
	v_fmac_f32_e32 v4, v4, v5
	v_add_f32_e32 v5, -1.0, v3
	v_fmac_f32_e32 v5, v3, v4
	v_add_f32_e32 v3, v5, v5
	v_cndmask_b32_e32 v3, v5, v3, vcc
	v_cmp_nlt_f32_e32 vcc, s22, v0
	v_exp_f32_e32 v2, v2
	s_nop 0
	v_cndmask_b32_e64 v3, v201, -v3, vcc
	v_cmp_gt_f32_e32 vcc, s23, v3
	v_mul_f32_e32 v4, 0x4f800000, v3
	s_nop 0
	v_cndmask_b32_e32 v3, v3, v4, vcc
	v_sqrt_f32_e32 v4, v3
	s_nop 0
	v_add_u32_e32 v5, -1, v4
	v_fma_f32 v6, -v5, v4, v3
	v_cmp_ge_f32_e64 s[0:1], 0, v6
	v_add_u32_e32 v6, 1, v4
	s_nop 0
	v_cndmask_b32_e64 v5, v4, v5, s[0:1]
	v_fma_f32 v4, -v6, v4, v3
	v_cmp_lt_f32_e64 s[0:1], 0, v4
	s_nop 1
	v_cndmask_b32_e64 v4, v5, v6, s[0:1]
	v_mul_f32_e32 v5, 0x37800000, v4
	v_cndmask_b32_e32 v4, v4, v5, vcc
	v_cmp_class_f32_e32 vcc, v3, v193
	s_nop 1
	v_cndmask_b32_e32 v3, v4, v3, vcc
	v_cmp_ngt_f32_e32 vcc, s24, v0
	s_nop 1
	v_cndmask_b32_e32 v0, 1.0, v3, vcc
	v_mul_f32_e32 v0, v1, v0
	v_mul_f32_e32 v0, v39, v0
	ds_write_b32 v144, v2 offset:2944
	ds_write_b32 v144, v0 offset:39808
	v_add_f32_e32 v0, v24, v36
	v_mul_f32_e32 v0, 0xbfb8aa3b, v0
	v_exp_f32_e32 v0, v0
	v_add_f32_e32 v1, v8, v38
	v_mul_f32_e32 v1, 0xbfb8aa3b, v1
	v_exp_f32_e32 v1, v1
	v_add_f32_e32 v0, 1.0, v0
	v_rcp_f32_e32 v0, v0
	v_add_f32_e32 v1, 1.0, v1
	v_rcp_f32_e32 v1, v1
	v_mul_f32_e32 v0, v0, v32
	v_mul_f32_e32 v2, 0x3fb8aa3b, v0
	v_add_f32_e32 v0, v0, v0
	v_mul_f32_e32 v3, 0x3fb8aa3b, v0
	v_rndne_f32_e32 v3, v3
	v_fmamk_f32 v4, v3, 0xbf317218, v0
	v_fmac_f32_e32 v4, 0x3102e308, v3
	v_fmamk_f32 v5, v4, 0x395133b1, v192
	v_cmp_eq_f32_e32 vcc, s21, v3
	v_cvt_i32_f32_e32 v3, v3
	v_fmaak_f32 v5, v4, v5, 0x3c0887f9
	v_fmaak_f32 v5, v4, v5, 0x3d2aaa81
	v_fmaak_f32 v5, v4, v5, 0x3e2aaaab
	v_fma_f32 v5, v4, v5, 0.5
	v_ldexp_f32 v3, 1.0, v3
	v_mul_f32_e32 v5, v4, v5
	v_cndmask_b32_e32 v3, v3, v202, vcc
	v_fmac_f32_e32 v4, v4, v5
	v_add_f32_e32 v5, -1.0, v3
	v_fmac_f32_e32 v5, v3, v4
	v_add_f32_e32 v3, v5, v5
	v_cndmask_b32_e32 v3, v5, v3, vcc
	v_cmp_nlt_f32_e32 vcc, s22, v0
	v_exp_f32_e32 v2, v2
	s_nop 0
	v_cndmask_b32_e64 v3, v201, -v3, vcc
	v_cmp_gt_f32_e32 vcc, s23, v3
	v_mul_f32_e32 v4, 0x4f800000, v3
	s_nop 0
	v_cndmask_b32_e32 v3, v3, v4, vcc
	v_sqrt_f32_e32 v4, v3
	s_nop 0
	v_add_u32_e32 v5, -1, v4
	v_fma_f32 v6, -v5, v4, v3
	v_cmp_ge_f32_e64 s[0:1], 0, v6
	v_add_u32_e32 v6, 1, v4
	s_nop 0
	v_cndmask_b32_e64 v5, v4, v5, s[0:1]
	v_fma_f32 v4, -v6, v4, v3
	v_cmp_lt_f32_e64 s[0:1], 0, v4
	s_nop 1
	v_cndmask_b32_e64 v4, v5, v6, s[0:1]
	v_mul_f32_e32 v5, 0x37800000, v4
	v_cndmask_b32_e32 v4, v4, v5, vcc
	v_cmp_class_f32_e32 vcc, v3, v193
	s_nop 1
	v_cndmask_b32_e32 v3, v4, v3, vcc
	v_cmp_ngt_f32_e32 vcc, s24, v0
	s_nop 1
	v_cndmask_b32_e32 v0, 1.0, v3, vcc
	v_mul_f32_e32 v0, v1, v0
	v_mul_f32_e32 v0, v55, v0
	ds_write_b32 v144, v2 offset:4224
	ds_write_b32 v144, v0 offset:41088
	v_add_f32_e32 v0, v25, v36
	v_mul_f32_e32 v0, 0xbfb8aa3b, v0
	v_exp_f32_e32 v0, v0
	v_add_f32_e32 v1, v9, v38
	v_mul_f32_e32 v1, 0xbfb8aa3b, v1
	v_exp_f32_e32 v1, v1
	v_add_f32_e32 v0, 1.0, v0
	v_rcp_f32_e32 v0, v0
	v_add_f32_e32 v1, 1.0, v1
	v_rcp_f32_e32 v1, v1
	v_mul_f32_e32 v0, v0, v32
	v_mul_f32_e32 v2, 0x3fb8aa3b, v0
	v_add_f32_e32 v0, v0, v0
	v_mul_f32_e32 v3, 0x3fb8aa3b, v0
	v_rndne_f32_e32 v3, v3
	v_fmamk_f32 v4, v3, 0xbf317218, v0
	v_fmac_f32_e32 v4, 0x3102e308, v3
	v_fmamk_f32 v5, v4, 0x395133b1, v192
	v_cmp_eq_f32_e32 vcc, s21, v3
	v_cvt_i32_f32_e32 v3, v3
	v_fmaak_f32 v5, v4, v5, 0x3c0887f9
	v_fmaak_f32 v5, v4, v5, 0x3d2aaa81
	v_fmaak_f32 v5, v4, v5, 0x3e2aaaab
	v_fma_f32 v5, v4, v5, 0.5
	v_ldexp_f32 v3, 1.0, v3
	v_mul_f32_e32 v5, v4, v5
	v_cndmask_b32_e32 v3, v3, v202, vcc
	v_fmac_f32_e32 v4, v4, v5
	v_add_f32_e32 v5, -1.0, v3
	v_fmac_f32_e32 v5, v3, v4
	v_add_f32_e32 v3, v5, v5
	v_cndmask_b32_e32 v3, v5, v3, vcc
	v_cmp_nlt_f32_e32 vcc, s22, v0
	v_exp_f32_e32 v2, v2
	s_nop 0
	v_cndmask_b32_e64 v3, v201, -v3, vcc
	v_cmp_gt_f32_e32 vcc, s23, v3
	v_mul_f32_e32 v4, 0x4f800000, v3
	s_nop 0
	v_cndmask_b32_e32 v3, v3, v4, vcc
	v_sqrt_f32_e32 v4, v3
	s_nop 0
	v_add_u32_e32 v5, -1, v4
	v_fma_f32 v6, -v5, v4, v3
	v_cmp_ge_f32_e64 s[0:1], 0, v6
	v_add_u32_e32 v6, 1, v4
	s_nop 0
	v_cndmask_b32_e64 v5, v4, v5, s[0:1]
	v_fma_f32 v4, -v6, v4, v3
	v_cmp_lt_f32_e64 s[0:1], 0, v4
	s_nop 1
	v_cndmask_b32_e64 v4, v5, v6, s[0:1]
	v_mul_f32_e32 v5, 0x37800000, v4
	v_cndmask_b32_e32 v4, v4, v5, vcc
	v_cmp_class_f32_e32 vcc, v3, v193
	s_nop 1
	v_cndmask_b32_e32 v3, v4, v3, vcc
	v_cmp_ngt_f32_e32 vcc, s24, v0
	s_nop 1
	v_cndmask_b32_e32 v0, 1.0, v3, vcc
	v_mul_f32_e32 v0, v1, v0
	v_mul_f32_e32 v0, v41, v0
	ds_write_b32 v144, v2 offset:4480
	ds_write_b32 v144, v0 offset:41344
	v_add_f32_e32 v0, v26, v36
	v_mul_f32_e32 v0, 0xbfb8aa3b, v0
	v_exp_f32_e32 v0, v0
	v_add_f32_e32 v1, v10, v38
	v_mul_f32_e32 v1, 0xbfb8aa3b, v1
	v_exp_f32_e32 v1, v1
	v_add_f32_e32 v0, 1.0, v0
	v_rcp_f32_e32 v0, v0
	v_add_f32_e32 v1, 1.0, v1
	v_rcp_f32_e32 v1, v1
	v_mul_f32_e32 v0, v0, v32
	v_mul_f32_e32 v2, 0x3fb8aa3b, v0
	v_add_f32_e32 v0, v0, v0
	v_mul_f32_e32 v3, 0x3fb8aa3b, v0
	v_rndne_f32_e32 v3, v3
	v_fmamk_f32 v4, v3, 0xbf317218, v0
	v_fmac_f32_e32 v4, 0x3102e308, v3
	v_fmamk_f32 v5, v4, 0x395133b1, v192
	v_cmp_eq_f32_e32 vcc, s21, v3
	v_cvt_i32_f32_e32 v3, v3
	v_fmaak_f32 v5, v4, v5, 0x3c0887f9
	v_fmaak_f32 v5, v4, v5, 0x3d2aaa81
	v_fmaak_f32 v5, v4, v5, 0x3e2aaaab
	v_fma_f32 v5, v4, v5, 0.5
	v_ldexp_f32 v3, 1.0, v3
	v_mul_f32_e32 v5, v4, v5
	v_cndmask_b32_e32 v3, v3, v202, vcc
	v_fmac_f32_e32 v4, v4, v5
	v_add_f32_e32 v5, -1.0, v3
	v_fmac_f32_e32 v5, v3, v4
	v_add_f32_e32 v3, v5, v5
	v_cndmask_b32_e32 v3, v5, v3, vcc
	v_cmp_nlt_f32_e32 vcc, s22, v0
	v_exp_f32_e32 v2, v2
	s_nop 0
	v_cndmask_b32_e64 v3, v201, -v3, vcc
	v_cmp_gt_f32_e32 vcc, s23, v3
	v_mul_f32_e32 v4, 0x4f800000, v3
	s_nop 0
	v_cndmask_b32_e32 v3, v3, v4, vcc
	v_sqrt_f32_e32 v4, v3
	s_nop 0
	v_add_u32_e32 v5, -1, v4
	v_fma_f32 v6, -v5, v4, v3
	v_cmp_ge_f32_e64 s[0:1], 0, v6
	v_add_u32_e32 v6, 1, v4
	s_nop 0
	v_cndmask_b32_e64 v5, v4, v5, s[0:1]
	v_fma_f32 v4, -v6, v4, v3
	v_cmp_lt_f32_e64 s[0:1], 0, v4
	s_nop 1
	v_cndmask_b32_e64 v4, v5, v6, s[0:1]
	v_mul_f32_e32 v5, 0x37800000, v4
	v_cndmask_b32_e32 v4, v4, v5, vcc
	v_cmp_class_f32_e32 vcc, v3, v193
	s_nop 1
	v_cndmask_b32_e32 v3, v4, v3, vcc
	v_cmp_ngt_f32_e32 vcc, s24, v0
	s_nop 1
	v_cndmask_b32_e32 v0, 1.0, v3, vcc
	v_mul_f32_e32 v0, v1, v0
	v_mul_f32_e32 v0, v57, v0
	ds_write_b32 v144, v2 offset:4736
	ds_write_b32 v144, v0 offset:41600
	v_add_f32_e32 v0, v27, v36
	v_mul_f32_e32 v0, 0xbfb8aa3b, v0
	v_exp_f32_e32 v0, v0
	v_add_f32_e32 v1, v11, v38
	v_mul_f32_e32 v1, 0xbfb8aa3b, v1
	v_exp_f32_e32 v1, v1
	v_add_f32_e32 v0, 1.0, v0
	v_rcp_f32_e32 v0, v0
	v_add_f32_e32 v1, 1.0, v1
	v_rcp_f32_e32 v1, v1
	v_mul_f32_e32 v0, v0, v32
	v_mul_f32_e32 v2, 0x3fb8aa3b, v0
	v_add_f32_e32 v0, v0, v0
	v_mul_f32_e32 v3, 0x3fb8aa3b, v0
	v_rndne_f32_e32 v3, v3
	v_fmamk_f32 v4, v3, 0xbf317218, v0
	v_fmac_f32_e32 v4, 0x3102e308, v3
	v_fmamk_f32 v5, v4, 0x395133b1, v192
	v_cmp_eq_f32_e32 vcc, s21, v3
	v_cvt_i32_f32_e32 v3, v3
	v_fmaak_f32 v5, v4, v5, 0x3c0887f9
	v_fmaak_f32 v5, v4, v5, 0x3d2aaa81
	v_fmaak_f32 v5, v4, v5, 0x3e2aaaab
	v_fma_f32 v5, v4, v5, 0.5
	v_ldexp_f32 v3, 1.0, v3
	v_mul_f32_e32 v5, v4, v5
	v_cndmask_b32_e32 v3, v3, v202, vcc
	v_fmac_f32_e32 v4, v4, v5
	v_add_f32_e32 v5, -1.0, v3
	v_fmac_f32_e32 v5, v3, v4
	v_add_f32_e32 v3, v5, v5
	v_cndmask_b32_e32 v3, v5, v3, vcc
	v_cmp_nlt_f32_e32 vcc, s22, v0
	v_exp_f32_e32 v2, v2
	s_nop 0
	v_cndmask_b32_e64 v3, v201, -v3, vcc
	v_cmp_gt_f32_e32 vcc, s23, v3
	v_mul_f32_e32 v4, 0x4f800000, v3
	s_nop 0
	v_cndmask_b32_e32 v3, v3, v4, vcc
	v_sqrt_f32_e32 v4, v3
	s_nop 0
	v_add_u32_e32 v5, -1, v4
	v_fma_f32 v6, -v5, v4, v3
	v_cmp_ge_f32_e64 s[0:1], 0, v6
	v_add_u32_e32 v6, 1, v4
	s_nop 0
	v_cndmask_b32_e64 v5, v4, v5, s[0:1]
	v_fma_f32 v4, -v6, v4, v3
	v_cmp_lt_f32_e64 s[0:1], 0, v4
	s_nop 1
	v_cndmask_b32_e64 v4, v5, v6, s[0:1]
	v_mul_f32_e32 v5, 0x37800000, v4
	v_cndmask_b32_e32 v4, v4, v5, vcc
	v_cmp_class_f32_e32 vcc, v3, v193
	s_nop 1
	v_cndmask_b32_e32 v3, v4, v3, vcc
	v_cmp_ngt_f32_e32 vcc, s24, v0
	s_nop 1
	v_cndmask_b32_e32 v0, 1.0, v3, vcc
	v_mul_f32_e32 v0, v1, v0
	v_mul_f32_e32 v0, v43, v0
	ds_write_b32 v144, v2 offset:4992
	ds_write_b32 v144, v0 offset:41856
	v_add_f32_e32 v0, v28, v36
	v_mul_f32_e32 v0, 0xbfb8aa3b, v0
	v_exp_f32_e32 v0, v0
	v_add_f32_e32 v1, v12, v38
	v_mul_f32_e32 v1, 0xbfb8aa3b, v1
	v_exp_f32_e32 v1, v1
	v_add_f32_e32 v0, 1.0, v0
	v_rcp_f32_e32 v0, v0
	v_add_f32_e32 v1, 1.0, v1
	v_rcp_f32_e32 v1, v1
	v_mul_f32_e32 v0, v0, v32
	v_mul_f32_e32 v2, 0x3fb8aa3b, v0
	v_add_f32_e32 v0, v0, v0
	v_mul_f32_e32 v3, 0x3fb8aa3b, v0
	v_rndne_f32_e32 v3, v3
	v_fmamk_f32 v4, v3, 0xbf317218, v0
	v_fmac_f32_e32 v4, 0x3102e308, v3
	v_fmamk_f32 v5, v4, 0x395133b1, v192
	v_cmp_eq_f32_e32 vcc, s21, v3
	v_cvt_i32_f32_e32 v3, v3
	v_fmaak_f32 v5, v4, v5, 0x3c0887f9
	v_fmaak_f32 v5, v4, v5, 0x3d2aaa81
	v_fmaak_f32 v5, v4, v5, 0x3e2aaaab
	v_fma_f32 v5, v4, v5, 0.5
	v_ldexp_f32 v3, 1.0, v3
	v_mul_f32_e32 v5, v4, v5
	v_cndmask_b32_e32 v3, v3, v202, vcc
	v_fmac_f32_e32 v4, v4, v5
	v_add_f32_e32 v5, -1.0, v3
	v_fmac_f32_e32 v5, v3, v4
	v_add_f32_e32 v3, v5, v5
	v_cndmask_b32_e32 v3, v5, v3, vcc
	v_cmp_nlt_f32_e32 vcc, s22, v0
	v_exp_f32_e32 v2, v2
	s_nop 0
	v_cndmask_b32_e64 v3, v201, -v3, vcc
	v_cmp_gt_f32_e32 vcc, s23, v3
	v_mul_f32_e32 v4, 0x4f800000, v3
	s_nop 0
	v_cndmask_b32_e32 v3, v3, v4, vcc
	v_sqrt_f32_e32 v4, v3
	s_nop 0
	v_add_u32_e32 v5, -1, v4
	v_fma_f32 v6, -v5, v4, v3
	v_cmp_ge_f32_e64 s[0:1], 0, v6
	v_add_u32_e32 v6, 1, v4
	s_nop 0
	v_cndmask_b32_e64 v5, v4, v5, s[0:1]
	v_fma_f32 v4, -v6, v4, v3
	v_cmp_lt_f32_e64 s[0:1], 0, v4
	s_nop 1
	v_cndmask_b32_e64 v4, v5, v6, s[0:1]
	v_mul_f32_e32 v5, 0x37800000, v4
	v_cndmask_b32_e32 v4, v4, v5, vcc
	v_cmp_class_f32_e32 vcc, v3, v193
	s_nop 1
	v_cndmask_b32_e32 v3, v4, v3, vcc
	v_cmp_ngt_f32_e32 vcc, s24, v0
	s_nop 1
	v_cndmask_b32_e32 v0, 1.0, v3, vcc
	v_mul_f32_e32 v0, v1, v0
	v_mul_f32_e32 v0, v59, v0
	ds_write_b32 v144, v2 offset:6272
	ds_write_b32 v144, v0 offset:43136
	v_add_f32_e32 v0, v29, v36
	v_mul_f32_e32 v0, 0xbfb8aa3b, v0
	v_exp_f32_e32 v0, v0
	v_add_f32_e32 v1, v13, v38
	v_mul_f32_e32 v1, 0xbfb8aa3b, v1
	v_exp_f32_e32 v1, v1
	v_add_f32_e32 v0, 1.0, v0
	v_rcp_f32_e32 v0, v0
	v_add_f32_e32 v1, 1.0, v1
	v_rcp_f32_e32 v1, v1
	v_mul_f32_e32 v0, v0, v32
	v_mul_f32_e32 v2, 0x3fb8aa3b, v0
	v_add_f32_e32 v0, v0, v0
	v_mul_f32_e32 v3, 0x3fb8aa3b, v0
	v_rndne_f32_e32 v3, v3
	v_fmamk_f32 v4, v3, 0xbf317218, v0
	v_fmac_f32_e32 v4, 0x3102e308, v3
	v_fmamk_f32 v5, v4, 0x395133b1, v192
	v_cmp_eq_f32_e32 vcc, s21, v3
	v_cvt_i32_f32_e32 v3, v3
	v_fmaak_f32 v5, v4, v5, 0x3c0887f9
	v_fmaak_f32 v5, v4, v5, 0x3d2aaa81
	v_fmaak_f32 v5, v4, v5, 0x3e2aaaab
	v_fma_f32 v5, v4, v5, 0.5
	v_ldexp_f32 v3, 1.0, v3
	v_mul_f32_e32 v5, v4, v5
	v_cndmask_b32_e32 v3, v3, v202, vcc
	v_fmac_f32_e32 v4, v4, v5
	v_add_f32_e32 v5, -1.0, v3
	v_fmac_f32_e32 v5, v3, v4
	v_add_f32_e32 v3, v5, v5
	v_cndmask_b32_e32 v3, v5, v3, vcc
	v_cmp_nlt_f32_e32 vcc, s22, v0
	v_exp_f32_e32 v2, v2
	s_nop 0
	v_cndmask_b32_e64 v3, v201, -v3, vcc
	v_cmp_gt_f32_e32 vcc, s23, v3
	v_mul_f32_e32 v4, 0x4f800000, v3
	s_nop 0
	v_cndmask_b32_e32 v3, v3, v4, vcc
	v_sqrt_f32_e32 v4, v3
	s_nop 0
	v_add_u32_e32 v5, -1, v4
	v_fma_f32 v6, -v5, v4, v3
	v_cmp_ge_f32_e64 s[0:1], 0, v6
	v_add_u32_e32 v6, 1, v4
	s_nop 0
	v_cndmask_b32_e64 v5, v4, v5, s[0:1]
	v_fma_f32 v4, -v6, v4, v3
	v_cmp_lt_f32_e64 s[0:1], 0, v4
	s_nop 1
	v_cndmask_b32_e64 v4, v5, v6, s[0:1]
	v_mul_f32_e32 v5, 0x37800000, v4
	v_cndmask_b32_e32 v4, v4, v5, vcc
	v_cmp_class_f32_e32 vcc, v3, v193
	s_nop 1
	v_cndmask_b32_e32 v3, v4, v3, vcc
	v_cmp_ngt_f32_e32 vcc, s24, v0
	s_nop 1
	v_cndmask_b32_e32 v0, 1.0, v3, vcc
	v_mul_f32_e32 v0, v1, v0
	v_mul_f32_e32 v0, v45, v0
	ds_write_b32 v144, v2 offset:6528
	ds_write_b32 v144, v0 offset:43392
	v_add_f32_e32 v0, v30, v36
	v_mul_f32_e32 v0, 0xbfb8aa3b, v0
	v_exp_f32_e32 v0, v0
	v_add_f32_e32 v1, v14, v38
	v_mul_f32_e32 v1, 0xbfb8aa3b, v1
	v_exp_f32_e32 v1, v1
	v_add_f32_e32 v0, 1.0, v0
	v_rcp_f32_e32 v0, v0
	v_add_f32_e32 v1, 1.0, v1
	v_rcp_f32_e32 v1, v1
	v_mul_f32_e32 v0, v0, v32
	v_mul_f32_e32 v2, 0x3fb8aa3b, v0
	v_add_f32_e32 v0, v0, v0
	v_mul_f32_e32 v3, 0x3fb8aa3b, v0
	v_rndne_f32_e32 v3, v3
	v_fmamk_f32 v4, v3, 0xbf317218, v0
	v_fmac_f32_e32 v4, 0x3102e308, v3
	v_fmamk_f32 v5, v4, 0x395133b1, v192
	v_cmp_eq_f32_e32 vcc, s21, v3
	v_cvt_i32_f32_e32 v3, v3
	v_fmaak_f32 v5, v4, v5, 0x3c0887f9
	v_fmaak_f32 v5, v4, v5, 0x3d2aaa81
	v_fmaak_f32 v5, v4, v5, 0x3e2aaaab
	v_fma_f32 v5, v4, v5, 0.5
	v_ldexp_f32 v3, 1.0, v3
	v_mul_f32_e32 v5, v4, v5
	v_cndmask_b32_e32 v3, v3, v202, vcc
	v_fmac_f32_e32 v4, v4, v5
	v_add_f32_e32 v5, -1.0, v3
	v_fmac_f32_e32 v5, v3, v4
	v_add_f32_e32 v3, v5, v5
	v_cndmask_b32_e32 v3, v5, v3, vcc
	v_cmp_nlt_f32_e32 vcc, s22, v0
	v_exp_f32_e32 v2, v2
	s_nop 0
	v_cndmask_b32_e64 v3, v201, -v3, vcc
	v_cmp_gt_f32_e32 vcc, s23, v3
	v_mul_f32_e32 v4, 0x4f800000, v3
	s_nop 0
	v_cndmask_b32_e32 v3, v3, v4, vcc
	v_sqrt_f32_e32 v4, v3
	s_nop 0
	v_add_u32_e32 v5, -1, v4
	v_fma_f32 v6, -v5, v4, v3
	v_cmp_ge_f32_e64 s[0:1], 0, v6
	v_add_u32_e32 v6, 1, v4
	s_nop 0
	v_cndmask_b32_e64 v5, v4, v5, s[0:1]
	v_fma_f32 v4, -v6, v4, v3
	v_cmp_lt_f32_e64 s[0:1], 0, v4
	s_nop 1
	v_cndmask_b32_e64 v4, v5, v6, s[0:1]
	v_mul_f32_e32 v5, 0x37800000, v4
	v_cndmask_b32_e32 v4, v4, v5, vcc
	v_cmp_class_f32_e32 vcc, v3, v193
	s_nop 1
	v_cndmask_b32_e32 v3, v4, v3, vcc
	v_cmp_ngt_f32_e32 vcc, s24, v0
	s_nop 1
	v_cndmask_b32_e32 v0, 1.0, v3, vcc
	v_mul_f32_e32 v0, v1, v0
	v_mul_f32_e32 v0, v35, v0
	v_add_u32_e32 v1, 0x1800, v144
	ds_write2_b32 v1, v2, v34 offset0:160 offset1:192
	ds_write_b32 v144, v0 offset:43648
	v_add_f32_e32 v0, v31, v36
	v_mul_f32_e32 v0, 0xbfb8aa3b, v0
	v_exp_f32_e32 v0, v0
	v_add_f32_e32 v1, v15, v38
	v_mul_f32_e32 v1, 0xbfb8aa3b, v1
	v_exp_f32_e32 v1, v1
	v_add_f32_e32 v0, 1.0, v0
	v_rcp_f32_e32 v0, v0
	v_add_f32_e32 v1, 1.0, v1
	v_rcp_f32_e32 v1, v1
	v_mul_f32_e32 v0, v0, v32
	v_mul_f32_e32 v2, 0x3fb8aa3b, v0
	v_add_f32_e32 v0, v0, v0
	v_mul_f32_e32 v3, 0x3fb8aa3b, v0
	v_rndne_f32_e32 v3, v3
	v_fmamk_f32 v4, v3, 0xbf317218, v0
	v_fmac_f32_e32 v4, 0x3102e308, v3
	v_fmamk_f32 v5, v4, 0x395133b1, v192
	v_cmp_eq_f32_e32 vcc, s21, v3
	v_cvt_i32_f32_e32 v3, v3
	v_fmaak_f32 v5, v4, v5, 0x3c0887f9
	v_fmaak_f32 v5, v4, v5, 0x3d2aaa81
	v_fmaak_f32 v5, v4, v5, 0x3e2aaaab
	v_fma_f32 v5, v4, v5, 0.5
	v_ldexp_f32 v3, 1.0, v3
	v_mul_f32_e32 v5, v4, v5
	v_cndmask_b32_e32 v3, v3, v202, vcc
	v_fmac_f32_e32 v4, v4, v5
	v_add_f32_e32 v5, -1.0, v3
	v_fmac_f32_e32 v5, v3, v4
	v_add_f32_e32 v3, v5, v5
	v_cndmask_b32_e32 v3, v5, v3, vcc
	v_cmp_nlt_f32_e32 vcc, s22, v0
	v_exp_f32_e32 v2, v2
	s_mov_b32 s21, 0x84000
	v_cndmask_b32_e64 v3, v201, -v3, vcc
	v_cmp_gt_f32_e32 vcc, s23, v3
	v_mul_f32_e32 v4, 0x4f800000, v3
	s_mov_b32 s22, 0x2d000
	v_cndmask_b32_e32 v3, v3, v4, vcc
	v_sqrt_f32_e32 v4, v3
	s_mov_b32 s23, 0x59000
	v_add_u32_e32 v5, -1, v4
	v_fma_f32 v6, -v5, v4, v3
	v_cmp_ge_f32_e64 s[0:1], 0, v6
	v_add_u32_e32 v6, 1, v4
	s_nop 0
	v_cndmask_b32_e64 v5, v4, v5, s[0:1]
	v_fma_f32 v4, -v6, v4, v3
	v_cmp_lt_f32_e64 s[0:1], 0, v4
	s_nop 1
	v_cndmask_b32_e64 v4, v5, v6, s[0:1]
	v_mul_f32_e32 v5, 0x37800000, v4
	v_cndmask_b32_e32 v4, v4, v5, vcc
	v_cmp_class_f32_e32 vcc, v3, v193
	v_mov_b32_e32 v5, 0
	s_nop 0
	v_cndmask_b32_e32 v3, v4, v3, vcc
	v_cmp_ngt_f32_e32 vcc, s24, v0
	v_readlane_b32 s24, v248, 7
	s_nop 0
	v_cndmask_b32_e32 v0, 1.0, v3, vcc
	v_mul_f32_e32 v0, v1, v0
	v_mul_f32_e32 v0, v33, v0
	ds_write_b32 v144, v2 offset:7040
	ds_write_b32 v144, v0 offset:43904
	v_mov_b32_e32 v0, 0
	s_waitcnt lgkmcnt(0)
	s_barrier
	s_cbranch_scc1 .LBB0_915
	v_lshl_add_u64 v[2:3], v[64:65], 0, s[4:5]
	v_add_co_u32_e32 v4, vcc, 0x13000, v2
	s_sub_i32 s0, s2, s12
	s_nop 0
	v_addc_co_u32_e32 v5, vcc, 0, v3, vcc
	global_load_dwordx2 v[4:5], v[4:5], off
	s_cmp_eq_u32 s0, 1
	s_waitcnt vmcnt(0)
	v_fmac_f32_e32 v5, 0, v4
	s_cbranch_scc1 .LBB0_915
	v_add_co_u32_e32 v2, vcc, 0x12000, v2
	s_cmp_eq_u32 s0, 2
	s_nop 0
	v_addc_co_u32_e32 v3, vcc, 0, v3, vcc
	global_load_dwordx2 v[2:3], v[2:3], off
	s_waitcnt vmcnt(0)
	v_fmac_f32_e32 v3, v5, v2
	s_cbranch_scc1 .LBB0_914
	s_mul_i32 s1, s11, 36
	s_add_i32 s2, s1, 36
	s_ashr_i32 s3, s2, 31
	s_lshl_b64 s[2:3], s[2:3], 12
	v_readlane_b32 s1, v249, 47
	s_add_u32 s2, s1, s2
	v_readlane_b32 s1, v249, 48
	v_add_lshl_u32 v96, s13, v141, 3
	s_addc_u32 s3, s1, s3
	v_lshl_add_u64 v[4:5], s[2:3], 0, v[96:97]
	s_add_i32 s0, s0, -2

.LBB0_921:
	s_or_b64 exec, exec, s[0:1]
	v_readlane_b32 s0, v249, 31
	v_lshlrev_b32_e32 v7, 5, v143
	v_lshlrev_b32_e32 v96, 1, v140
	v_readlane_b32 s1, v249, 32
	v_or_b32_e32 v4, 31, v7
	v_lshl_or_b32 v23, v4, 8, v142
	v_lshl_add_u64 v[2:3], s[0:1], 0, v[96:97]
	v_add_u32_e32 v4, s7, v4
	v_add_u32_e32 v23, 0, v23
	v_mad_i64_i32 v[26:27], s[0:1], v4, s74, v[2:3]
	ds_read2st64_b32 v[24:25], v23 offset1:144
	v_or_b32_e32 v134, 31, v7
	v_add_u32_e32 v134, s7, v134
	v_mad_i64_i32 v[136:137], s[0:1], v134, s74, v[2:3]
	global_load_ushort v144, v[136:137], off
	v_or_b32_e32 v134, 30, v7
	v_add_u32_e32 v134, s7, v134
	v_mad_i64_i32 v[136:137], s[0:1], v134, s74, v[2:3]
	global_load_ushort v145, v[136:137], off
	v_or_b32_e32 v134, 29, v7
	v_add_u32_e32 v134, s7, v134
	v_mad_i64_i32 v[136:137], s[0:1], v134, s74, v[2:3]
	global_load_ushort v146, v[136:137], off
	v_or_b32_e32 v134, 28, v7
	v_add_u32_e32 v134, s7, v134
	v_mad_i64_i32 v[136:137], s[0:1], v134, s74, v[2:3]
	global_load_ushort v147, v[136:137], off
	v_or_b32_e32 v134, 27, v7
	v_add_u32_e32 v134, s7, v134
	v_mad_i64_i32 v[136:137], s[0:1], v134, s74, v[2:3]
	global_load_ushort v148, v[136:137], off
	v_or_b32_e32 v134, 26, v7
	v_add_u32_e32 v134, s7, v134
	v_mad_i64_i32 v[136:137], s[0:1], v134, s74, v[2:3]
	global_load_ushort v149, v[136:137], off
	v_or_b32_e32 v134, 25, v7
	v_add_u32_e32 v134, s7, v134
	v_mad_i64_i32 v[136:137], s[0:1], v134, s74, v[2:3]
	global_load_ushort v150, v[136:137], off
	v_or_b32_e32 v134, 24, v7
	v_add_u32_e32 v134, s7, v134
	v_mad_i64_i32 v[136:137], s[0:1], v134, s74, v[2:3]
	global_load_ushort v151, v[136:137], off
	v_or_b32_e32 v134, 23, v7
	v_add_u32_e32 v134, s7, v134
	v_mad_i64_i32 v[136:137], s[0:1], v134, s74, v[2:3]
	global_load_ushort v152, v[136:137], off
	v_or_b32_e32 v134, 22, v7
	v_add_u32_e32 v134, s7, v134
	v_mad_i64_i32 v[136:137], s[0:1], v134, s74, v[2:3]
	global_load_ushort v153, v[136:137], off
	v_or_b32_e32 v134, 21, v7
	v_add_u32_e32 v134, s7, v134
	v_mad_i64_i32 v[136:137], s[0:1], v134, s74, v[2:3]
	global_load_ushort v154, v[136:137], off
	v_or_b32_e32 v134, 20, v7
	v_add_u32_e32 v134, s7, v134
	v_mad_i64_i32 v[136:137], s[0:1], v134, s74, v[2:3]
	global_load_ushort v155, v[136:137], off
	v_or_b32_e32 v134, 19, v7
	v_add_u32_e32 v134, s7, v134
	v_mad_i64_i32 v[136:137], s[0:1], v134, s74, v[2:3]
	global_load_ushort v156, v[136:137], off
	v_or_b32_e32 v134, 18, v7
	v_add_u32_e32 v134, s7, v134
	v_mad_i64_i32 v[136:137], s[0:1], v134, s74, v[2:3]
	global_load_ushort v157, v[136:137], off
	v_or_b32_e32 v134, 17, v7
	v_add_u32_e32 v134, s7, v134
	v_mad_i64_i32 v[136:137], s[0:1], v134, s74, v[2:3]
	global_load_ushort v158, v[136:137], off
	v_or_b32_e32 v134, 16, v7
	v_add_u32_e32 v134, s7, v134
	v_mad_i64_i32 v[136:137], s[0:1], v134, s74, v[2:3]
	global_load_ushort v159, v[136:137], off
	v_or_b32_e32 v134, 15, v7
	v_add_u32_e32 v134, s7, v134
	v_mad_i64_i32 v[136:137], s[0:1], v134, s74, v[2:3]
	global_load_ushort v160, v[136:137], off
	v_or_b32_e32 v134, 14, v7
	v_add_u32_e32 v134, s7, v134
	v_mad_i64_i32 v[136:137], s[0:1], v134, s74, v[2:3]
	global_load_ushort v161, v[136:137], off
	v_or_b32_e32 v134, 13, v7
	v_add_u32_e32 v134, s7, v134
	v_mad_i64_i32 v[136:137], s[0:1], v134, s74, v[2:3]
	global_load_ushort v169, v[136:137], off
	v_or_b32_e32 v134, 12, v7
	v_add_u32_e32 v134, s7, v134
	v_mad_i64_i32 v[136:137], s[0:1], v134, s74, v[2:3]
	global_load_ushort v170, v[136:137], off
	v_or_b32_e32 v134, 11, v7
	v_add_u32_e32 v134, s7, v134
	v_mad_i64_i32 v[136:137], s[0:1], v134, s74, v[2:3]
	global_load_ushort v171, v[136:137], off
	v_or_b32_e32 v134, 10, v7
	v_add_u32_e32 v134, s7, v134
	v_mad_i64_i32 v[136:137], s[0:1], v134, s74, v[2:3]
	global_load_ushort v172, v[136:137], off
	v_or_b32_e32 v134, 9, v7
	v_add_u32_e32 v134, s7, v134
	v_mad_i64_i32 v[136:137], s[0:1], v134, s74, v[2:3]
	global_load_ushort v173, v[136:137], off
	v_or_b32_e32 v134, 8, v7
	v_add_u32_e32 v134, s7, v134
	v_mad_i64_i32 v[136:137], s[0:1], v134, s74, v[2:3]
	global_load_ushort v174, v[136:137], off
	v_or_b32_e32 v134, 7, v7
	v_add_u32_e32 v134, s7, v134
	v_mad_i64_i32 v[136:137], s[0:1], v134, s74, v[2:3]
	global_load_ushort v175, v[136:137], off
	v_or_b32_e32 v134, 6, v7
	v_add_u32_e32 v134, s7, v134
	v_mad_i64_i32 v[136:137], s[0:1], v134, s74, v[2:3]
	global_load_ushort v176, v[136:137], off
	v_or_b32_e32 v134, 5, v7
	v_add_u32_e32 v134, s7, v134
	v_mad_i64_i32 v[136:137], s[0:1], v134, s74, v[2:3]
	global_load_ushort v177, v[136:137], off
	v_or_b32_e32 v134, 4, v7
	v_add_u32_e32 v134, s7, v134
	v_mad_i64_i32 v[136:137], s[0:1], v134, s74, v[2:3]
	global_load_ushort v178, v[136:137], off
	v_or_b32_e32 v134, 3, v7
	v_add_u32_e32 v134, s7, v134
	v_mad_i64_i32 v[136:137], s[0:1], v134, s74, v[2:3]
	global_load_ushort v179, v[136:137], off
	v_or_b32_e32 v134, 2, v7
	v_add_u32_e32 v134, s7, v134
	v_mad_i64_i32 v[136:137], s[0:1], v134, s74, v[2:3]
	global_load_ushort v180, v[136:137], off
	v_or_b32_e32 v134, 1, v7
	v_add_u32_e32 v134, s7, v134
	v_mad_i64_i32 v[136:137], s[0:1], v134, s74, v[2:3]
	global_load_ushort v181, v[136:137], off
	v_or_b32_e32 v134, 0, v7
	v_add_u32_e32 v134, s7, v134
	v_mad_i64_i32 v[136:137], s[0:1], v134, s74, v[2:3]
	global_load_ushort v182, v[136:137], off
	v_fma_f32 v6, v99, v102, v66
	v_fmac_f32_e32 v67, v6, v103
	v_fma_f32 v8, v67, v104, v68
	v_fmac_f32_e32 v69, v8, v105
	v_fma_f32 v9, v69, v106, v70
	v_fmac_f32_e32 v71, v9, v107
	v_fma_f32 v10, v71, v108, v72
	v_fmac_f32_e32 v73, v10, v109
	v_fma_f32 v11, v73, v110, v74
	v_fmac_f32_e32 v75, v11, v111
	v_fma_f32 v12, v75, v112, v76
	v_fmac_f32_e32 v77, v12, v113
	v_fma_f32 v13, v77, v114, v78
	v_fmac_f32_e32 v79, v13, v115
	v_fma_f32 v14, v79, v116, v80
	v_fmac_f32_e32 v81, v14, v117
	v_fma_f32 v15, v81, v118, v82
	v_fmac_f32_e32 v83, v15, v119
	v_fma_f32 v16, v83, v120, v84
	v_fmac_f32_e32 v85, v16, v121
	v_fma_f32 v17, v85, v122, v86
	v_fmac_f32_e32 v87, v17, v123
	v_fma_f32 v18, v87, v124, v88
	v_fmac_f32_e32 v89, v18, v125
	v_fma_f32 v19, v89, v126, v90
	v_fmac_f32_e32 v91, v19, v127
	v_fma_f32 v20, v91, v128, v92
	v_fmac_f32_e32 v93, v20, v129
	v_fma_f32 v21, v93, v130, v94
	v_fmac_f32_e32 v95, v21, v131
	v_fma_f32 v22, v95, v132, v100
	v_fmac_f32_e32 v101, v22, v133
	s_waitcnt lgkmcnt(0)
	v_fmac_f32_e32 v25, v5, v24
	v_ashrrev_i32_e32 v5, 31, v4
	v_add_f32_e32 v24, v101, v25
	v_lshl_add_u64 v[0:1], s[64:65], 0, v[96:97]
	v_lshlrev_b64 v[4:5], 10, v[4:5]
	v_lshl_add_u64 v[4:5], v[0:1], 0, v[4:5]
	s_waitcnt vmcnt(0)
	v_lshlrev_b32_e32 v23, 16, v144
	v_mul_f32_e32 v26, 0x3d372713, v23
	v_mul_f32_e32 v26, v26, v23
	v_fma_f32 v26, v26, v23, v23
	v_mul_f32_e32 v26, 0x3f4c422a, v26
	v_add_f32_e32 v26, v26, v26
	v_mul_f32_e32 v26, 0xbfb8aa3b, v26
	v_exp_f32_e32 v26, v26
	s_nop 0
	v_add_f32_e32 v26, 1.0, v26
	v_rcp_f32_e32 v26, v26
	s_nop 0
	v_mul_f32_e32 v23, v26, v23
	v_mul_f32_e32 v23, v24, v23
	v_cvt_pk_bf16_f32 v23, v23, s0
	global_store_short v[4:5], v23, off
	v_or_b32_e32 v23, 30, v7
	v_lshl_or_b32 v4, v23, 8, v142
	v_add_u32_e32 v4, 0, v4
	ds_read2st64_b32 v[4:5], v4 offset1:144
	v_add_u32_e32 v24, s7, v23
	v_mad_i64_i32 v[26:27], s[0:1], v24, s74, v[2:3]
	s_waitcnt lgkmcnt(0)
	v_fmac_f32_e32 v5, v25, v4
	v_ashrrev_i32_e32 v25, 31, v24
	v_add_f32_e32 v22, v22, v5
	v_lshlrev_b32_e32 v4, 16, v145
	v_mul_f32_e32 v23, 0x3d372713, v4
	v_mul_f32_e32 v23, v23, v4
	v_fma_f32 v23, v23, v4, v4
	v_mul_f32_e32 v23, 0x3f4c422a, v23
	v_add_f32_e32 v23, v23, v23
	v_mul_f32_e32 v23, 0xbfb8aa3b, v23
	v_exp_f32_e32 v23, v23
	s_nop 0
	v_add_f32_e32 v23, 1.0, v23
	v_rcp_f32_e32 v23, v23
	s_nop 0
	v_mul_f32_e32 v4, v23, v4
	v_mul_f32_e32 v4, v22, v4
	v_lshlrev_b64 v[22:23], 10, v[24:25]
	v_cvt_pk_bf16_f32 v4, v4, s0
	v_lshl_add_u64 v[22:23], v[0:1], 0, v[22:23]
	global_store_short v[22:23], v4, off
	v_or_b32_e32 v4, 29, v7
	v_lshl_or_b32 v22, v4, 8, v142
	v_add_u32_e32 v22, 0, v22
	ds_read2st64_b32 v[22:23], v22 offset1:144
	v_add_u32_e32 v4, s7, v4
	v_mad_i64_i32 v[24:25], s[0:1], v4, s74, v[2:3]
	s_waitcnt lgkmcnt(0)
	v_fmac_f32_e32 v23, v5, v22
	v_ashrrev_i32_e32 v5, 31, v4
	v_add_f32_e32 v24, v95, v23
	v_lshlrev_b64 v[4:5], 10, v[4:5]
	v_lshl_add_u64 v[4:5], v[0:1], 0, v[4:5]
	v_lshlrev_b32_e32 v22, 16, v146
	v_mul_f32_e32 v25, 0x3d372713, v22
	v_mul_f32_e32 v25, v25, v22
	v_fma_f32 v25, v25, v22, v22
	v_mul_f32_e32 v25, 0x3f4c422a, v25
	v_add_f32_e32 v25, v25, v25
	v_mul_f32_e32 v25, 0xbfb8aa3b, v25
	v_exp_f32_e32 v25, v25
	s_nop 0
	v_add_f32_e32 v25, 1.0, v25
	v_rcp_f32_e32 v25, v25
	s_nop 0
	v_mul_f32_e32 v22, v25, v22
	v_mul_f32_e32 v22, v24, v22
	v_cvt_pk_bf16_f32 v22, v22, s0
	global_store_short v[4:5], v22, off
	v_or_b32_e32 v22, 28, v7
	v_lshl_or_b32 v4, v22, 8, v142
	v_add_u32_e32 v4, 0, v4
	ds_read2st64_b32 v[4:5], v4 offset1:144
	v_add_u32_e32 v22, s7, v22
	v_mad_i64_i32 v[24:25], s[0:1], v22, s74, v[2:3]
	s_waitcnt lgkmcnt(0)
	v_fmac_f32_e32 v5, v23, v4
	v_ashrrev_i32_e32 v23, 31, v22
	v_add_f32_e32 v21, v21, v5
	v_lshlrev_b64 v[22:23], 10, v[22:23]
	v_lshl_add_u64 v[22:23], v[0:1], 0, v[22:23]
	v_lshlrev_b32_e32 v4, 16, v147
	v_mul_f32_e32 v24, 0x3d372713, v4
	v_mul_f32_e32 v24, v24, v4
	v_fma_f32 v24, v24, v4, v4
	v_mul_f32_e32 v24, 0x3f4c422a, v24
	v_add_f32_e32 v24, v24, v24
	v_mul_f32_e32 v24, 0xbfb8aa3b, v24
	v_exp_f32_e32 v24, v24
	s_nop 0
	v_add_f32_e32 v24, 1.0, v24
	v_rcp_f32_e32 v24, v24
	s_nop 0
	v_mul_f32_e32 v4, v24, v4
	v_mul_f32_e32 v4, v21, v4
	v_cvt_pk_bf16_f32 v4, v4, s0
	global_store_short v[22:23], v4, off
	v_or_b32_e32 v4, 27, v7
	v_lshl_or_b32 v21, v4, 8, v142
	v_add_u32_e32 v4, s7, v4
	v_add_u32_e32 v21, 0, v21
	v_mad_i64_i32 v[24:25], s[0:1], v4, s74, v[2:3]
	ds_read2st64_b32 v[22:23], v21 offset1:144
	s_waitcnt lgkmcnt(0)
	v_fmac_f32_e32 v23, v5, v22
	v_ashrrev_i32_e32 v5, 31, v4
	v_add_f32_e32 v22, v93, v23
	v_lshlrev_b64 v[4:5], 10, v[4:5]
	v_lshl_add_u64 v[4:5], v[0:1], 0, v[4:5]
	v_lshlrev_b32_e32 v21, 16, v148
	v_mul_f32_e32 v24, 0x3d372713, v21
	v_mul_f32_e32 v24, v24, v21
	v_fma_f32 v24, v24, v21, v21
	v_mul_f32_e32 v24, 0x3f4c422a, v24
	v_add_f32_e32 v24, v24, v24
	v_mul_f32_e32 v24, 0xbfb8aa3b, v24
	v_exp_f32_e32 v24, v24
	s_nop 0
	v_add_f32_e32 v24, 1.0, v24
	v_rcp_f32_e32 v24, v24
	s_nop 0
	v_mul_f32_e32 v21, v24, v21
	v_mul_f32_e32 v21, v22, v21
	v_cvt_pk_bf16_f32 v21, v21, s0
	global_store_short v[4:5], v21, off
	v_or_b32_e32 v21, 26, v7
	v_lshl_or_b32 v4, v21, 8, v142
	v_add_u32_e32 v4, 0, v4
	ds_read2st64_b32 v[4:5], v4 offset1:144
	v_add_u32_e32 v22, s7, v21
	v_mad_i64_i32 v[24:25], s[0:1], v22, s74, v[2:3]
	s_waitcnt lgkmcnt(0)
	v_fmac_f32_e32 v5, v23, v4
	v_ashrrev_i32_e32 v23, 31, v22
	v_add_f32_e32 v20, v20, v5
	v_lshlrev_b32_e32 v4, 16, v149
	v_mul_f32_e32 v21, 0x3d372713, v4
	v_mul_f32_e32 v21, v21, v4
	v_fma_f32 v21, v21, v4, v4
	v_mul_f32_e32 v21, 0x3f4c422a, v21
	v_add_f32_e32 v21, v21, v21
	v_mul_f32_e32 v21, 0xbfb8aa3b, v21
	v_exp_f32_e32 v21, v21
	s_nop 0
	v_add_f32_e32 v21, 1.0, v21
	v_rcp_f32_e32 v21, v21
	s_nop 0
	v_mul_f32_e32 v4, v21, v4
	v_mul_f32_e32 v4, v20, v4
	v_lshlrev_b64 v[20:21], 10, v[22:23]
	v_cvt_pk_bf16_f32 v4, v4, s0
	v_lshl_add_u64 v[20:21], v[0:1], 0, v[20:21]
	global_store_short v[20:21], v4, off
	v_or_b32_e32 v4, 25, v7
	v_lshl_or_b32 v20, v4, 8, v142
	v_add_u32_e32 v20, 0, v20
	ds_read2st64_b32 v[20:21], v20 offset1:144
	v_add_u32_e32 v4, s7, v4
	v_mad_i64_i32 v[22:23], s[0:1], v4, s74, v[2:3]
	s_waitcnt lgkmcnt(0)
	v_fmac_f32_e32 v21, v5, v20
	v_ashrrev_i32_e32 v5, 31, v4
	v_add_f32_e32 v22, v91, v21
	v_lshlrev_b64 v[4:5], 10, v[4:5]
	v_lshl_add_u64 v[4:5], v[0:1], 0, v[4:5]
	v_lshlrev_b32_e32 v20, 16, v150
	v_mul_f32_e32 v23, 0x3d372713, v20
	v_mul_f32_e32 v23, v23, v20
	v_fma_f32 v23, v23, v20, v20
	v_mul_f32_e32 v23, 0x3f4c422a, v23
	v_add_f32_e32 v23, v23, v23
	v_mul_f32_e32 v23, 0xbfb8aa3b, v23
	v_exp_f32_e32 v23, v23
	s_nop 0
	v_add_f32_e32 v23, 1.0, v23
	v_rcp_f32_e32 v23, v23
	s_nop 0
	v_mul_f32_e32 v20, v23, v20
	v_mul_f32_e32 v20, v22, v20
	v_cvt_pk_bf16_f32 v20, v20, s0
	global_store_short v[4:5], v20, off
	v_or_b32_e32 v20, 24, v7
	v_lshl_or_b32 v4, v20, 8, v142
	v_add_u32_e32 v4, 0, v4
	ds_read2st64_b32 v[4:5], v4 offset1:144
	v_add_u32_e32 v20, s7, v20
	v_mad_i64_i32 v[22:23], s[0:1], v20, s74, v[2:3]
	s_waitcnt lgkmcnt(0)
	v_fmac_f32_e32 v5, v21, v4
	v_ashrrev_i32_e32 v21, 31, v20
	v_add_f32_e32 v19, v19, v5
	v_lshlrev_b64 v[20:21], 10, v[20:21]
	v_lshl_add_u64 v[20:21], v[0:1], 0, v[20:21]
	v_lshlrev_b32_e32 v4, 16, v151
	v_mul_f32_e32 v22, 0x3d372713, v4
	v_mul_f32_e32 v22, v22, v4
	v_fma_f32 v22, v22, v4, v4
	v_mul_f32_e32 v22, 0x3f4c422a, v22
	v_add_f32_e32 v22, v22, v22
	v_mul_f32_e32 v22, 0xbfb8aa3b, v22
	v_exp_f32_e32 v22, v22
	s_nop 0
	v_add_f32_e32 v22, 1.0, v22
	v_rcp_f32_e32 v22, v22
	s_nop 0
	v_mul_f32_e32 v4, v22, v4
	v_mul_f32_e32 v4, v19, v4
	v_cvt_pk_bf16_f32 v4, v4, s0
	global_store_short v[20:21], v4, off
	v_or_b32_e32 v4, 23, v7
	v_lshl_or_b32 v19, v4, 8, v142
	v_add_u32_e32 v4, s7, v4
	v_add_u32_e32 v19, 0, v19
	v_mad_i64_i32 v[22:23], s[0:1], v4, s74, v[2:3]
	ds_read2st64_b32 v[20:21], v19 offset1:144
	s_waitcnt lgkmcnt(0)
	v_fmac_f32_e32 v21, v5, v20
	v_ashrrev_i32_e32 v5, 31, v4
	v_add_f32_e32 v20, v89, v21
	v_lshlrev_b64 v[4:5], 10, v[4:5]
	v_lshl_add_u64 v[4:5], v[0:1], 0, v[4:5]
	v_lshlrev_b32_e32 v19, 16, v152
	v_mul_f32_e32 v22, 0x3d372713, v19
	v_mul_f32_e32 v22, v22, v19
	v_fma_f32 v22, v22, v19, v19
	v_mul_f32_e32 v22, 0x3f4c422a, v22
	v_add_f32_e32 v22, v22, v22
	v_mul_f32_e32 v22, 0xbfb8aa3b, v22
	v_exp_f32_e32 v22, v22
	s_nop 0
	v_add_f32_e32 v22, 1.0, v22
	v_rcp_f32_e32 v22, v22
	s_nop 0
	v_mul_f32_e32 v19, v22, v19
	v_mul_f32_e32 v19, v20, v19
	v_cvt_pk_bf16_f32 v19, v19, s0
	global_store_short v[4:5], v19, off
	v_or_b32_e32 v19, 22, v7
	v_lshl_or_b32 v4, v19, 8, v142
	v_add_u32_e32 v4, 0, v4
	ds_read2st64_b32 v[4:5], v4 offset1:144
	v_add_u32_e32 v20, s7, v19
	v_mad_i64_i32 v[22:23], s[0:1], v20, s74, v[2:3]
	s_waitcnt lgkmcnt(0)
	v_fmac_f32_e32 v5, v21, v4
	v_ashrrev_i32_e32 v21, 31, v20
	v_add_f32_e32 v18, v18, v5
	v_lshlrev_b32_e32 v4, 16, v153
	v_mul_f32_e32 v19, 0x3d372713, v4
	v_mul_f32_e32 v19, v19, v4
	v_fma_f32 v19, v19, v4, v4
	v_mul_f32_e32 v19, 0x3f4c422a, v19
	v_add_f32_e32 v19, v19, v19
	v_mul_f32_e32 v19, 0xbfb8aa3b, v19
	v_exp_f32_e32 v19, v19
	s_nop 0
	v_add_f32_e32 v19, 1.0, v19
	v_rcp_f32_e32 v19, v19
	s_nop 0
	v_mul_f32_e32 v4, v19, v4
	v_mul_f32_e32 v4, v18, v4
	v_lshlrev_b64 v[18:19], 10, v[20:21]
	v_cvt_pk_bf16_f32 v4, v4, s0
	v_lshl_add_u64 v[18:19], v[0:1], 0, v[18:19]
	global_store_short v[18:19], v4, off
	v_or_b32_e32 v4, 21, v7
	v_lshl_or_b32 v18, v4, 8, v142
	v_add_u32_e32 v18, 0, v18
	ds_read2st64_b32 v[18:19], v18 offset1:144
	v_add_u32_e32 v4, s7, v4
	v_mad_i64_i32 v[20:21], s[0:1], v4, s74, v[2:3]
	s_waitcnt lgkmcnt(0)
	v_fmac_f32_e32 v19, v5, v18
	v_ashrrev_i32_e32 v5, 31, v4
	v_add_f32_e32 v20, v87, v19
	v_lshlrev_b64 v[4:5], 10, v[4:5]
	v_lshl_add_u64 v[4:5], v[0:1], 0, v[4:5]
	v_lshlrev_b32_e32 v18, 16, v154
	v_mul_f32_e32 v21, 0x3d372713, v18
	v_mul_f32_e32 v21, v21, v18
	v_fma_f32 v21, v21, v18, v18
	v_mul_f32_e32 v21, 0x3f4c422a, v21
	v_add_f32_e32 v21, v21, v21
	v_mul_f32_e32 v21, 0xbfb8aa3b, v21
	v_exp_f32_e32 v21, v21
	s_nop 0
	v_add_f32_e32 v21, 1.0, v21
	v_rcp_f32_e32 v21, v21
	s_nop 0
	v_mul_f32_e32 v18, v21, v18
	v_mul_f32_e32 v18, v20, v18
	v_cvt_pk_bf16_f32 v18, v18, s0
	global_store_short v[4:5], v18, off
	v_or_b32_e32 v18, 20, v7
	v_lshl_or_b32 v4, v18, 8, v142
	v_add_u32_e32 v4, 0, v4
	ds_read2st64_b32 v[4:5], v4 offset1:144
	v_add_u32_e32 v18, s7, v18
	v_mad_i64_i32 v[20:21], s[0:1], v18, s74, v[2:3]
	s_waitcnt lgkmcnt(0)
	v_fmac_f32_e32 v5, v19, v4
	v_ashrrev_i32_e32 v19, 31, v18
	v_add_f32_e32 v17, v17, v5
	v_lshlrev_b64 v[18:19], 10, v[18:19]
	v_lshl_add_u64 v[18:19], v[0:1], 0, v[18:19]
	v_lshlrev_b32_e32 v4, 16, v155
	v_mul_f32_e32 v20, 0x3d372713, v4
	v_mul_f32_e32 v20, v20, v4
	v_fma_f32 v20, v20, v4, v4
	v_mul_f32_e32 v20, 0x3f4c422a, v20
	v_add_f32_e32 v20, v20, v20
	v_mul_f32_e32 v20, 0xbfb8aa3b, v20
	v_exp_f32_e32 v20, v20
	s_nop 0
	v_add_f32_e32 v20, 1.0, v20
	v_rcp_f32_e32 v20, v20
	s_nop 0
	v_mul_f32_e32 v4, v20, v4
	v_mul_f32_e32 v4, v17, v4
	v_cvt_pk_bf16_f32 v4, v4, s0
	global_store_short v[18:19], v4, off
	v_or_b32_e32 v4, 19, v7
	v_lshl_or_b32 v17, v4, 8, v142
	v_add_u32_e32 v4, s7, v4
	v_add_u32_e32 v17, 0, v17
	v_mad_i64_i32 v[20:21], s[0:1], v4, s74, v[2:3]
	ds_read2st64_b32 v[18:19], v17 offset1:144
	s_waitcnt lgkmcnt(0)
	v_fmac_f32_e32 v19, v5, v18
	v_ashrrev_i32_e32 v5, 31, v4
	v_add_f32_e32 v18, v85, v19
	v_lshlrev_b64 v[4:5], 10, v[4:5]
	v_lshl_add_u64 v[4:5], v[0:1], 0, v[4:5]
	v_lshlrev_b32_e32 v17, 16, v156
	v_mul_f32_e32 v20, 0x3d372713, v17
	v_mul_f32_e32 v20, v20, v17
	v_fma_f32 v20, v20, v17, v17
	v_mul_f32_e32 v20, 0x3f4c422a, v20
	v_add_f32_e32 v20, v20, v20
	v_mul_f32_e32 v20, 0xbfb8aa3b, v20
	v_exp_f32_e32 v20, v20
	s_nop 0
	v_add_f32_e32 v20, 1.0, v20
	v_rcp_f32_e32 v20, v20
	s_nop 0
	v_mul_f32_e32 v17, v20, v17
	v_mul_f32_e32 v17, v18, v17
	v_cvt_pk_bf16_f32 v17, v17, s0
	global_store_short v[4:5], v17, off
	v_or_b32_e32 v17, 18, v7
	v_lshl_or_b32 v4, v17, 8, v142
	v_add_u32_e32 v4, 0, v4
	ds_read2st64_b32 v[4:5], v4 offset1:144
	v_add_u32_e32 v18, s7, v17
	v_mad_i64_i32 v[20:21], s[0:1], v18, s74, v[2:3]
	s_waitcnt lgkmcnt(0)
	v_fmac_f32_e32 v5, v19, v4
	v_ashrrev_i32_e32 v19, 31, v18
	v_add_f32_e32 v16, v16, v5
	v_lshlrev_b32_e32 v4, 16, v157
	v_mul_f32_e32 v17, 0x3d372713, v4
	v_mul_f32_e32 v17, v17, v4
	v_fma_f32 v17, v17, v4, v4
	v_mul_f32_e32 v17, 0x3f4c422a, v17
	v_add_f32_e32 v17, v17, v17
	v_mul_f32_e32 v17, 0xbfb8aa3b, v17
	v_exp_f32_e32 v17, v17
	s_nop 0
	v_add_f32_e32 v17, 1.0, v17
	v_rcp_f32_e32 v17, v17
	s_nop 0
	v_mul_f32_e32 v4, v17, v4
	v_mul_f32_e32 v4, v16, v4
	v_lshlrev_b64 v[16:17], 10, v[18:19]
	v_cvt_pk_bf16_f32 v4, v4, s0
	v_lshl_add_u64 v[16:17], v[0:1], 0, v[16:17]
	global_store_short v[16:17], v4, off
	v_or_b32_e32 v4, 17, v7
	v_lshl_or_b32 v16, v4, 8, v142
	v_add_u32_e32 v16, 0, v16
	ds_read2st64_b32 v[16:17], v16 offset1:144
	v_add_u32_e32 v4, s7, v4
	v_mad_i64_i32 v[18:19], s[0:1], v4, s74, v[2:3]
	s_waitcnt lgkmcnt(0)
	v_fmac_f32_e32 v17, v5, v16
	v_ashrrev_i32_e32 v5, 31, v4
	v_add_f32_e32 v18, v83, v17
	v_lshlrev_b64 v[4:5], 10, v[4:5]
	v_lshl_add_u64 v[4:5], v[0:1], 0, v[4:5]
	v_lshlrev_b32_e32 v16, 16, v158
	v_mul_f32_e32 v19, 0x3d372713, v16
	v_mul_f32_e32 v19, v19, v16
	v_fma_f32 v19, v19, v16, v16
	v_mul_f32_e32 v19, 0x3f4c422a, v19
	v_add_f32_e32 v19, v19, v19
	v_mul_f32_e32 v19, 0xbfb8aa3b, v19
	v_exp_f32_e32 v19, v19
	s_nop 0
	v_add_f32_e32 v19, 1.0, v19
	v_rcp_f32_e32 v19, v19
	s_nop 0
	v_mul_f32_e32 v16, v19, v16
	v_mul_f32_e32 v16, v18, v16
	v_cvt_pk_bf16_f32 v16, v16, s0
	global_store_short v[4:5], v16, off
	v_or_b32_e32 v16, 16, v7
	v_lshl_or_b32 v4, v16, 8, v142
	v_add_u32_e32 v4, 0, v4
	ds_read2st64_b32 v[4:5], v4 offset1:144
	v_add_u32_e32 v16, s7, v16
	v_mad_i64_i32 v[18:19], s[0:1], v16, s74, v[2:3]
	s_waitcnt lgkmcnt(0)
	v_fmac_f32_e32 v5, v17, v4
	v_ashrrev_i32_e32 v17, 31, v16
	v_add_f32_e32 v15, v15, v5
	v_lshlrev_b64 v[16:17], 10, v[16:17]
	v_lshl_add_u64 v[16:17], v[0:1], 0, v[16:17]
	v_lshlrev_b32_e32 v4, 16, v159
	v_mul_f32_e32 v18, 0x3d372713, v4
	v_mul_f32_e32 v18, v18, v4
	v_fma_f32 v18, v18, v4, v4
	v_mul_f32_e32 v18, 0x3f4c422a, v18
	v_add_f32_e32 v18, v18, v18
	v_mul_f32_e32 v18, 0xbfb8aa3b, v18
	v_exp_f32_e32 v18, v18
	s_nop 0
	v_add_f32_e32 v18, 1.0, v18
	v_rcp_f32_e32 v18, v18
	s_nop 0
	v_mul_f32_e32 v4, v18, v4
	v_mul_f32_e32 v4, v15, v4
	v_cvt_pk_bf16_f32 v4, v4, s0
	global_store_short v[16:17], v4, off
	v_or_b32_e32 v4, 15, v7
	v_lshl_or_b32 v15, v4, 8, v142
	v_add_u32_e32 v4, s7, v4
	v_add_u32_e32 v15, 0, v15
	v_mad_i64_i32 v[18:19], s[0:1], v4, s74, v[2:3]
	ds_read2st64_b32 v[16:17], v15 offset1:144
	s_waitcnt lgkmcnt(0)
	v_fmac_f32_e32 v17, v5, v16
	v_ashrrev_i32_e32 v5, 31, v4
	v_add_f32_e32 v16, v81, v17
	v_lshlrev_b64 v[4:5], 10, v[4:5]
	v_lshl_add_u64 v[4:5], v[0:1], 0, v[4:5]
	v_lshlrev_b32_e32 v15, 16, v160
	v_mul_f32_e32 v18, 0x3d372713, v15
	v_mul_f32_e32 v18, v18, v15
	v_fma_f32 v18, v18, v15, v15
	v_mul_f32_e32 v18, 0x3f4c422a, v18
	v_add_f32_e32 v18, v18, v18
	v_mul_f32_e32 v18, 0xbfb8aa3b, v18
	v_exp_f32_e32 v18, v18
	s_nop 0
	v_add_f32_e32 v18, 1.0, v18
	v_rcp_f32_e32 v18, v18
	s_nop 0
	v_mul_f32_e32 v15, v18, v15
	v_mul_f32_e32 v15, v16, v15
	v_cvt_pk_bf16_f32 v15, v15, s0
	global_store_short v[4:5], v15, off
	v_or_b32_e32 v15, 14, v7
	v_lshl_or_b32 v4, v15, 8, v142
	v_add_u32_e32 v4, 0, v4
	ds_read2st64_b32 v[4:5], v4 offset1:144
	v_add_u32_e32 v16, s7, v15
	v_mad_i64_i32 v[18:19], s[0:1], v16, s74, v[2:3]
	s_waitcnt lgkmcnt(0)
	v_fmac_f32_e32 v5, v17, v4
	v_ashrrev_i32_e32 v17, 31, v16
	v_add_f32_e32 v14, v14, v5
	v_lshlrev_b32_e32 v4, 16, v161
	v_mul_f32_e32 v15, 0x3d372713, v4
	v_mul_f32_e32 v15, v15, v4
	v_fma_f32 v15, v15, v4, v4
	v_mul_f32_e32 v15, 0x3f4c422a, v15
	v_add_f32_e32 v15, v15, v15
	v_mul_f32_e32 v15, 0xbfb8aa3b, v15
	v_exp_f32_e32 v15, v15
	s_nop 0
	v_add_f32_e32 v15, 1.0, v15
	v_rcp_f32_e32 v15, v15
	s_nop 0
	v_mul_f32_e32 v4, v15, v4
	v_mul_f32_e32 v4, v14, v4
	v_lshlrev_b64 v[14:15], 10, v[16:17]
	v_cvt_pk_bf16_f32 v4, v4, s0
	v_lshl_add_u64 v[14:15], v[0:1], 0, v[14:15]
	global_store_short v[14:15], v4, off
	v_or_b32_e32 v4, 13, v7
	v_lshl_or_b32 v14, v4, 8, v142
	v_add_u32_e32 v14, 0, v14
	ds_read2st64_b32 v[14:15], v14 offset1:144
	v_add_u32_e32 v4, s7, v4
	v_mad_i64_i32 v[16:17], s[0:1], v4, s74, v[2:3]
	s_waitcnt lgkmcnt(0)
	v_fmac_f32_e32 v15, v5, v14
	v_ashrrev_i32_e32 v5, 31, v4
	v_add_f32_e32 v16, v79, v15
	v_lshlrev_b64 v[4:5], 10, v[4:5]
	v_lshl_add_u64 v[4:5], v[0:1], 0, v[4:5]
	v_lshlrev_b32_e32 v14, 16, v169
	v_mul_f32_e32 v17, 0x3d372713, v14
	v_mul_f32_e32 v17, v17, v14
	v_fma_f32 v17, v17, v14, v14
	v_mul_f32_e32 v17, 0x3f4c422a, v17
	v_add_f32_e32 v17, v17, v17
	v_mul_f32_e32 v17, 0xbfb8aa3b, v17
	v_exp_f32_e32 v17, v17
	s_nop 0
	v_add_f32_e32 v17, 1.0, v17
	v_rcp_f32_e32 v17, v17
	s_nop 0
	v_mul_f32_e32 v14, v17, v14
	v_mul_f32_e32 v14, v16, v14
	v_cvt_pk_bf16_f32 v14, v14, s0
	global_store_short v[4:5], v14, off
	v_or_b32_e32 v14, 12, v7
	v_lshl_or_b32 v4, v14, 8, v142
	v_add_u32_e32 v4, 0, v4
	ds_read2st64_b32 v[4:5], v4 offset1:144
	v_add_u32_e32 v14, s7, v14
	v_mad_i64_i32 v[16:17], s[0:1], v14, s74, v[2:3]
	s_waitcnt lgkmcnt(0)
	v_fmac_f32_e32 v5, v15, v4
	v_ashrrev_i32_e32 v15, 31, v14
	v_add_f32_e32 v13, v13, v5
	v_lshlrev_b64 v[14:15], 10, v[14:15]
	v_lshl_add_u64 v[14:15], v[0:1], 0, v[14:15]
	v_lshlrev_b32_e32 v4, 16, v170
	v_mul_f32_e32 v16, 0x3d372713, v4
	v_mul_f32_e32 v16, v16, v4
	v_fma_f32 v16, v16, v4, v4
	v_mul_f32_e32 v16, 0x3f4c422a, v16
	v_add_f32_e32 v16, v16, v16
	v_mul_f32_e32 v16, 0xbfb8aa3b, v16
	v_exp_f32_e32 v16, v16
	s_nop 0
	v_add_f32_e32 v16, 1.0, v16
	v_rcp_f32_e32 v16, v16
	s_nop 0
	v_mul_f32_e32 v4, v16, v4
	v_mul_f32_e32 v4, v13, v4
	v_cvt_pk_bf16_f32 v4, v4, s0
	global_store_short v[14:15], v4, off
	v_or_b32_e32 v4, 11, v7
	v_lshl_or_b32 v13, v4, 8, v142
	v_add_u32_e32 v4, s7, v4
	v_add_u32_e32 v13, 0, v13
	v_mad_i64_i32 v[16:17], s[0:1], v4, s74, v[2:3]
	ds_read2st64_b32 v[14:15], v13 offset1:144
	s_waitcnt lgkmcnt(0)
	v_fmac_f32_e32 v15, v5, v14
	v_ashrrev_i32_e32 v5, 31, v4
	v_add_f32_e32 v14, v77, v15
	v_lshlrev_b64 v[4:5], 10, v[4:5]
	v_lshl_add_u64 v[4:5], v[0:1], 0, v[4:5]
	v_lshlrev_b32_e32 v13, 16, v171
	v_mul_f32_e32 v16, 0x3d372713, v13
	v_mul_f32_e32 v16, v16, v13
	v_fma_f32 v16, v16, v13, v13
	v_mul_f32_e32 v16, 0x3f4c422a, v16
	v_add_f32_e32 v16, v16, v16
	v_mul_f32_e32 v16, 0xbfb8aa3b, v16
	v_exp_f32_e32 v16, v16
	s_nop 0
	v_add_f32_e32 v16, 1.0, v16
	v_rcp_f32_e32 v16, v16
	s_nop 0
	v_mul_f32_e32 v13, v16, v13
	v_mul_f32_e32 v13, v14, v13
	v_cvt_pk_bf16_f32 v13, v13, s0
	global_store_short v[4:5], v13, off
	v_or_b32_e32 v13, 10, v7
	v_lshl_or_b32 v4, v13, 8, v142
	v_add_u32_e32 v4, 0, v4
	ds_read2st64_b32 v[4:5], v4 offset1:144
	v_add_u32_e32 v14, s7, v13
	v_mad_i64_i32 v[16:17], s[0:1], v14, s74, v[2:3]
	s_waitcnt lgkmcnt(0)
	v_fmac_f32_e32 v5, v15, v4
	v_ashrrev_i32_e32 v15, 31, v14
	v_add_f32_e32 v12, v12, v5
	v_lshlrev_b32_e32 v4, 16, v172
	v_mul_f32_e32 v13, 0x3d372713, v4
	v_mul_f32_e32 v13, v13, v4
	v_fma_f32 v13, v13, v4, v4
	v_mul_f32_e32 v13, 0x3f4c422a, v13
	v_add_f32_e32 v13, v13, v13
	v_mul_f32_e32 v13, 0xbfb8aa3b, v13
	v_exp_f32_e32 v13, v13
	s_nop 0
	v_add_f32_e32 v13, 1.0, v13
	v_rcp_f32_e32 v13, v13
	s_nop 0
	v_mul_f32_e32 v4, v13, v4
	v_mul_f32_e32 v4, v12, v4
	v_lshlrev_b64 v[12:13], 10, v[14:15]
	v_cvt_pk_bf16_f32 v4, v4, s0
	v_lshl_add_u64 v[12:13], v[0:1], 0, v[12:13]
	global_store_short v[12:13], v4, off
	v_or_b32_e32 v4, 9, v7
	v_lshl_or_b32 v12, v4, 8, v142
	v_add_u32_e32 v12, 0, v12
	ds_read2st64_b32 v[12:13], v12 offset1:144
	v_add_u32_e32 v4, s7, v4
	v_mad_i64_i32 v[14:15], s[0:1], v4, s74, v[2:3]
	s_waitcnt lgkmcnt(0)
	v_fmac_f32_e32 v13, v5, v12
	v_ashrrev_i32_e32 v5, 31, v4
	v_add_f32_e32 v14, v75, v13
	v_lshlrev_b64 v[4:5], 10, v[4:5]
	v_lshl_add_u64 v[4:5], v[0:1], 0, v[4:5]
	v_lshlrev_b32_e32 v12, 16, v173
	v_mul_f32_e32 v15, 0x3d372713, v12
	v_mul_f32_e32 v15, v15, v12
	v_fma_f32 v15, v15, v12, v12
	v_mul_f32_e32 v15, 0x3f4c422a, v15
	v_add_f32_e32 v15, v15, v15
	v_mul_f32_e32 v15, 0xbfb8aa3b, v15
	v_exp_f32_e32 v15, v15
	s_nop 0
	v_add_f32_e32 v15, 1.0, v15
	v_rcp_f32_e32 v15, v15
	s_nop 0
	v_mul_f32_e32 v12, v15, v12
	v_mul_f32_e32 v12, v14, v12
	v_cvt_pk_bf16_f32 v12, v12, s0
	global_store_short v[4:5], v12, off
	v_or_b32_e32 v12, 8, v7
	v_lshl_or_b32 v4, v12, 8, v142
	v_add_u32_e32 v4, 0, v4
	ds_read2st64_b32 v[4:5], v4 offset1:144
	v_add_u32_e32 v12, s7, v12
	v_mad_i64_i32 v[14:15], s[0:1], v12, s74, v[2:3]
	s_waitcnt lgkmcnt(0)
	v_fmac_f32_e32 v5, v13, v4
	v_ashrrev_i32_e32 v13, 31, v12
	v_add_f32_e32 v11, v11, v5
	v_lshlrev_b64 v[12:13], 10, v[12:13]
	v_lshl_add_u64 v[12:13], v[0:1], 0, v[12:13]
	v_lshlrev_b32_e32 v4, 16, v174
	v_mul_f32_e32 v14, 0x3d372713, v4
	v_mul_f32_e32 v14, v14, v4
	v_fma_f32 v14, v14, v4, v4
	v_mul_f32_e32 v14, 0x3f4c422a, v14
	v_add_f32_e32 v14, v14, v14
	v_mul_f32_e32 v14, 0xbfb8aa3b, v14
	v_exp_f32_e32 v14, v14
	s_nop 0
	v_add_f32_e32 v14, 1.0, v14
	v_rcp_f32_e32 v14, v14
	s_nop 0
	v_mul_f32_e32 v4, v14, v4
	v_mul_f32_e32 v4, v11, v4
	v_cvt_pk_bf16_f32 v4, v4, s0
	global_store_short v[12:13], v4, off
	v_or_b32_e32 v4, 7, v7
	v_lshl_or_b32 v11, v4, 8, v142
	v_add_u32_e32 v4, s7, v4
	v_add_u32_e32 v11, 0, v11
	v_mad_i64_i32 v[14:15], s[0:1], v4, s74, v[2:3]
	ds_read2st64_b32 v[12:13], v11 offset1:144
	s_waitcnt lgkmcnt(0)
	v_fmac_f32_e32 v13, v5, v12
	v_ashrrev_i32_e32 v5, 31, v4
	v_add_f32_e32 v12, v73, v13
	v_lshlrev_b64 v[4:5], 10, v[4:5]
	v_lshl_add_u64 v[4:5], v[0:1], 0, v[4:5]
	v_lshlrev_b32_e32 v11, 16, v175
	v_mul_f32_e32 v14, 0x3d372713, v11
	v_mul_f32_e32 v14, v14, v11
	v_fma_f32 v14, v14, v11, v11
	v_mul_f32_e32 v14, 0x3f4c422a, v14
	v_add_f32_e32 v14, v14, v14
	v_mul_f32_e32 v14, 0xbfb8aa3b, v14
	v_exp_f32_e32 v14, v14
	s_nop 0
	v_add_f32_e32 v14, 1.0, v14
	v_rcp_f32_e32 v14, v14
	s_nop 0
	v_mul_f32_e32 v11, v14, v11
	v_mul_f32_e32 v11, v12, v11
	v_cvt_pk_bf16_f32 v11, v11, s0
	global_store_short v[4:5], v11, off
	v_or_b32_e32 v11, 6, v7
	v_lshl_or_b32 v4, v11, 8, v142
	v_add_u32_e32 v4, 0, v4
	ds_read2st64_b32 v[4:5], v4 offset1:144
	v_add_u32_e32 v12, s7, v11
	v_mad_i64_i32 v[14:15], s[0:1], v12, s74, v[2:3]
	s_waitcnt lgkmcnt(0)
	v_fmac_f32_e32 v5, v13, v4
	v_ashrrev_i32_e32 v13, 31, v12
	v_add_f32_e32 v10, v10, v5
	v_lshlrev_b32_e32 v4, 16, v176
	v_mul_f32_e32 v11, 0x3d372713, v4
	v_mul_f32_e32 v11, v11, v4
	v_fma_f32 v11, v11, v4, v4
	v_mul_f32_e32 v11, 0x3f4c422a, v11
	v_add_f32_e32 v11, v11, v11
	v_mul_f32_e32 v11, 0xbfb8aa3b, v11
	v_exp_f32_e32 v11, v11
	s_nop 0
	v_add_f32_e32 v11, 1.0, v11
	v_rcp_f32_e32 v11, v11
	s_nop 0
	v_mul_f32_e32 v4, v11, v4
	v_mul_f32_e32 v4, v10, v4
	v_lshlrev_b64 v[10:11], 10, v[12:13]
	v_cvt_pk_bf16_f32 v4, v4, s0
	v_lshl_add_u64 v[10:11], v[0:1], 0, v[10:11]
	global_store_short v[10:11], v4, off
	v_or_b32_e32 v4, 5, v7
	v_lshl_or_b32 v10, v4, 8, v142
	v_add_u32_e32 v10, 0, v10
	ds_read2st64_b32 v[10:11], v10 offset1:144
	v_add_u32_e32 v4, s7, v4
	v_mad_i64_i32 v[12:13], s[0:1], v4, s74, v[2:3]
	s_waitcnt lgkmcnt(0)
	v_fmac_f32_e32 v11, v5, v10
	v_ashrrev_i32_e32 v5, 31, v4
	v_add_f32_e32 v12, v71, v11
	v_lshlrev_b64 v[4:5], 10, v[4:5]
	v_lshl_add_u64 v[4:5], v[0:1], 0, v[4:5]
	v_lshlrev_b32_e32 v10, 16, v177
	v_mul_f32_e32 v13, 0x3d372713, v10
	v_mul_f32_e32 v13, v13, v10
	v_fma_f32 v13, v13, v10, v10
	v_mul_f32_e32 v13, 0x3f4c422a, v13
	v_add_f32_e32 v13, v13, v13
	v_mul_f32_e32 v13, 0xbfb8aa3b, v13
	v_exp_f32_e32 v13, v13
	s_nop 0
	v_add_f32_e32 v13, 1.0, v13
	v_rcp_f32_e32 v13, v13
	s_nop 0
	v_mul_f32_e32 v10, v13, v10
	v_mul_f32_e32 v10, v12, v10
	v_cvt_pk_bf16_f32 v10, v10, s0
	global_store_short v[4:5], v10, off
	v_or_b32_e32 v10, 4, v7
	v_lshl_or_b32 v4, v10, 8, v142
	v_add_u32_e32 v4, 0, v4
	ds_read2st64_b32 v[4:5], v4 offset1:144
	v_add_u32_e32 v10, s7, v10
	v_mad_i64_i32 v[12:13], s[0:1], v10, s74, v[2:3]
	s_waitcnt lgkmcnt(0)
	v_fmac_f32_e32 v5, v11, v4
	v_ashrrev_i32_e32 v11, 31, v10
	v_add_f32_e32 v9, v9, v5
	v_lshlrev_b64 v[10:11], 10, v[10:11]
	v_lshl_add_u64 v[10:11], v[0:1], 0, v[10:11]
	v_lshlrev_b32_e32 v4, 16, v178
	v_mul_f32_e32 v12, 0x3d372713, v4
	v_mul_f32_e32 v12, v12, v4
	v_fma_f32 v12, v12, v4, v4
	v_mul_f32_e32 v12, 0x3f4c422a, v12
	v_add_f32_e32 v12, v12, v12
	v_mul_f32_e32 v12, 0xbfb8aa3b, v12
	v_exp_f32_e32 v12, v12
	s_nop 0
	v_add_f32_e32 v12, 1.0, v12
	v_rcp_f32_e32 v12, v12
	s_nop 0
	v_mul_f32_e32 v4, v12, v4
	v_mul_f32_e32 v4, v9, v4
	v_cvt_pk_bf16_f32 v4, v4, s0
	global_store_short v[10:11], v4, off
	v_or_b32_e32 v4, 3, v7
	v_lshl_or_b32 v9, v4, 8, v142
	v_add_u32_e32 v4, s7, v4
	v_add_u32_e32 v9, 0, v9
	v_mad_i64_i32 v[12:13], s[0:1], v4, s74, v[2:3]
	ds_read2st64_b32 v[10:11], v9 offset1:144
	s_waitcnt lgkmcnt(0)
	v_fmac_f32_e32 v11, v5, v10
	v_ashrrev_i32_e32 v5, 31, v4
	v_add_f32_e32 v10, v69, v11
	v_lshlrev_b64 v[4:5], 10, v[4:5]
	v_lshl_add_u64 v[4:5], v[0:1], 0, v[4:5]
	v_lshlrev_b32_e32 v9, 16, v179
	v_mul_f32_e32 v12, 0x3d372713, v9
	v_mul_f32_e32 v12, v12, v9
	v_fma_f32 v12, v12, v9, v9
	v_mul_f32_e32 v12, 0x3f4c422a, v12
	v_add_f32_e32 v12, v12, v12
	v_mul_f32_e32 v12, 0xbfb8aa3b, v12
	v_exp_f32_e32 v12, v12
	s_nop 0
	v_add_f32_e32 v12, 1.0, v12
	v_rcp_f32_e32 v12, v12
	s_nop 0
	v_mul_f32_e32 v9, v12, v9
	v_mul_f32_e32 v9, v10, v9
	v_cvt_pk_bf16_f32 v9, v9, s0
	global_store_short v[4:5], v9, off
	v_or_b32_e32 v9, 2, v7
	v_lshl_or_b32 v4, v9, 8, v142
	v_add_u32_e32 v4, 0, v4
	ds_read2st64_b32 v[4:5], v4 offset1:144
	v_add_u32_e32 v10, s7, v9
	v_mad_i64_i32 v[12:13], s[0:1], v10, s74, v[2:3]
	s_waitcnt lgkmcnt(0)
	v_fmac_f32_e32 v5, v11, v4
	v_ashrrev_i32_e32 v11, 31, v10
	v_add_f32_e32 v8, v8, v5
	v_lshlrev_b32_e32 v4, 16, v180
	v_mul_f32_e32 v9, 0x3d372713, v4
	v_mul_f32_e32 v9, v9, v4
	v_fma_f32 v9, v9, v4, v4
	v_mul_f32_e32 v9, 0x3f4c422a, v9
	v_add_f32_e32 v9, v9, v9
	v_mul_f32_e32 v9, 0xbfb8aa3b, v9
	v_exp_f32_e32 v9, v9
	s_nop 0
	v_add_f32_e32 v9, 1.0, v9
	v_rcp_f32_e32 v9, v9
	s_nop 0
	v_mul_f32_e32 v4, v9, v4
	v_mul_f32_e32 v4, v8, v4
	v_lshlrev_b64 v[8:9], 10, v[10:11]
	v_cvt_pk_bf16_f32 v4, v4, s0
	v_lshl_add_u64 v[8:9], v[0:1], 0, v[8:9]
	global_store_short v[8:9], v4, off
	v_or_b32_e32 v4, 1, v7
	v_lshl_or_b32 v8, v4, 8, v142
	v_add_u32_e32 v8, 0, v8
	ds_read2st64_b32 v[8:9], v8 offset1:144
	v_add_u32_e32 v4, s7, v4
	v_mad_i64_i32 v[10:11], s[0:1], v4, s74, v[2:3]
	s_waitcnt lgkmcnt(0)
	v_fmac_f32_e32 v9, v5, v8
	v_ashrrev_i32_e32 v5, 31, v4
	v_add_f32_e32 v10, v67, v9
	v_lshlrev_b64 v[4:5], 10, v[4:5]
	v_lshl_add_u64 v[4:5], v[0:1], 0, v[4:5]
	v_lshlrev_b32_e32 v8, 16, v181
	v_mul_f32_e32 v11, 0x3d372713, v8
	v_mul_f32_e32 v11, v11, v8
	v_fma_f32 v11, v11, v8, v8
	v_mul_f32_e32 v11, 0x3f4c422a, v11
	v_add_f32_e32 v11, v11, v11
	v_mul_f32_e32 v11, 0xbfb8aa3b, v11
	v_exp_f32_e32 v11, v11
	s_nop 0
	v_add_f32_e32 v11, 1.0, v11
	v_rcp_f32_e32 v11, v11
	s_nop 0
	v_mul_f32_e32 v8, v11, v8
	v_mul_f32_e32 v8, v10, v8
	v_cvt_pk_bf16_f32 v8, v8, s0
	global_store_short v[4:5], v8, off
	v_add_u32_e32 v8, s7, v7
	v_mad_i64_i32 v[2:3], s[0:1], v8, s74, v[2:3]
	ds_read2st64_b32 v[4:5], v98 offset1:144
	s_waitcnt lgkmcnt(0)
	v_fmac_f32_e32 v5, v9, v4
	v_add_f32_e32 v3, v6, v5
	v_ashrrev_i32_e32 v9, 31, v8
	v_lshlrev_b32_e32 v2, 16, v182
	v_mul_f32_e32 v4, 0x3d372713, v2
	v_mul_f32_e32 v4, v4, v2
	v_fma_f32 v4, v4, v2, v2
	v_mul_f32_e32 v4, 0x3f4c422a, v4
	v_add_f32_e32 v4, v4, v4
	v_mul_f32_e32 v4, 0xbfb8aa3b, v4
	v_exp_f32_e32 v4, v4
	s_nop 0
	v_add_f32_e32 v4, 1.0, v4
	v_rcp_f32_e32 v4, v4
	s_nop 0
	v_mul_f32_e32 v2, v4, v2
	v_mul_f32_e32 v2, v3, v2
	v_cvt_pk_bf16_f32 v4, v2, s0
	v_lshlrev_b64 v[2:3], 10, v[8:9]
	v_lshl_add_u64 v[0:1], v[0:1], 0, v[2:3]
	s_mov_b64 s[0:1], 0
	global_store_short v[0:1], v4, off

.LBB0_933:
	s_or_b64 exec, exec, s[0:1]
	s_xor_b64 s[54:55], s[6:7], -1
	s_waitcnt lgkmcnt(0)
	s_barrier
	s_and_saveexec_b64 s[0:1], s[40:41]
	s_xor_b64 s[0:1], exec, s[0:1]
	v_mbcnt_hi_u32_b32 v105, -1, v195
	v_and_b32_e32 v0, 64, v105
	s_andn2_saveexec_b64 s[0:1], s[0:1]
	s_cbranch_execz .LBB0_937
	v_cndmask_b32_e64 v0, v134, v133, s[6:7]
	v_cndmask_b32_e64 v1, v135, v136, s[6:7]
	v_lshlrev_b32_e32 v2, 2, v0
	v_add_u32_e32 v0, s11, v2
	v_lshlrev_b32_e32 v1, 2, v1
	ds_read_b32 v3, v0
	v_add_u32_e32 v0, s11, v1
	ds_read_b32 v0, v0
	v_add_u32_e32 v5, -1, v196
	v_add_u32_e32 v7, -2, v196
	v_readlane_b32 s4, v249, 51
	v_mov_b32_e32 v105, v196
	s_waitcnt lgkmcnt(0)
	v_add_f32_e32 v4, v3, v0
	v_and_b32_e32 v0, 64, v196
	v_cmp_lt_i32_e32 vcc, v5, v0
	s_nop 1
	v_cndmask_b32_e32 v5, v5, v196, vcc
	v_lshlrev_b32_e32 v5, 2, v5
	ds_bpermute_b32 v6, v5, v4
	v_cmp_lt_i32_e32 vcc, v7, v0
	s_waitcnt lgkmcnt(0)
	v_add_f32_e32 v6, v4, v6
	v_cndmask_b32_e32 v7, v7, v196, vcc
	v_cndmask_b32_e64 v6, v6, v4, s[42:43]
	v_lshlrev_b32_e32 v7, 2, v7
	ds_bpermute_b32 v8, v7, v6
	s_waitcnt lgkmcnt(0)
	v_add_f32_e32 v8, v6, v8
	v_cndmask_b32_e64 v6, v8, v6, s[44:45]
	v_add_u32_e32 v8, -4, v196
	v_cmp_lt_i32_e32 vcc, v8, v0
	s_nop 1
	v_cndmask_b32_e32 v8, v8, v196, vcc
	v_lshlrev_b32_e32 v8, 2, v8
	ds_bpermute_b32 v9, v8, v6
	s_waitcnt lgkmcnt(0)
	v_add_f32_e32 v9, v6, v9
	v_cndmask_b32_e64 v6, v9, v6, s[46:47]
	v_add_u32_e32 v9, -8, v196
	v_cmp_lt_i32_e32 vcc, v9, v0
	s_nop 1
	v_cndmask_b32_e32 v9, v9, v196, vcc
	v_lshlrev_b32_e32 v9, 2, v9
	ds_bpermute_b32 v10, v9, v6
	s_waitcnt lgkmcnt(0)
	v_add_f32_e32 v10, v6, v10
	v_cndmask_b32_e64 v6, v10, v6, s[48:49]
	v_add_u32_e32 v10, -16, v196
	v_cmp_lt_i32_e32 vcc, v10, v0
	s_nop 1
	v_cndmask_b32_e32 v10, v10, v196, vcc
	v_lshlrev_b32_e32 v10, 2, v10
	ds_bpermute_b32 v11, v10, v6
	s_waitcnt lgkmcnt(0)
	v_add_f32_e32 v11, v6, v11
	v_cndmask_b32_e64 v6, v11, v6, s[50:51]
	v_subrev_u32_e32 v11, 32, v196
	v_cmp_lt_i32_e32 vcc, v11, v0
	s_nop 1
	v_cndmask_b32_e32 v11, v11, v196, vcc
	v_lshlrev_b32_e32 v11, 2, v11
	ds_bpermute_b32 v12, v11, v6
	s_waitcnt lgkmcnt(0)
	v_add_f32_e32 v12, v6, v12
	v_cndmask_b32_e64 v6, v12, v6, s[52:53]
	v_sub_f32_e32 v6, v6, v4
	v_add_f32_e32 v3, v3, v6
	v_add_f32_e32 v4, v4, v6
	v_add_u32_e32 v6, s73, v2
	v_add_u32_e32 v12, s73, v1
	ds_read_b32 v6, v6
	ds_read_b32 v12, v12
	s_waitcnt lgkmcnt(1)
	v_sub_f32_e32 v6, v6, v3
	s_waitcnt lgkmcnt(0)
	v_sub_f32_e32 v12, v12, v4
	v_max_f32_e32 v13, v6, v12
	ds_bpermute_b32 v14, v5, v13
	s_waitcnt lgkmcnt(0)
	v_max_f32_e32 v14, v13, v14
	v_cndmask_b32_e64 v13, v14, v13, s[42:43]
	ds_bpermute_b32 v7, v7, v13
	s_waitcnt lgkmcnt(0)
	v_max_f32_e32 v7, v13, v7
	v_cndmask_b32_e64 v7, v7, v13, s[44:45]
	ds_bpermute_b32 v8, v8, v7
	s_waitcnt lgkmcnt(0)
	v_max_f32_e32 v8, v7, v8
	v_cndmask_b32_e64 v7, v8, v7, s[46:47]
	ds_bpermute_b32 v8, v9, v7
	s_waitcnt lgkmcnt(0)
	v_max_f32_e32 v8, v7, v8
	v_cndmask_b32_e64 v7, v8, v7, s[48:49]
	ds_bpermute_b32 v8, v10, v7
	s_waitcnt lgkmcnt(0)
	v_max_f32_e32 v8, v7, v8
	v_cndmask_b32_e64 v7, v8, v7, s[50:51]
	ds_bpermute_b32 v8, v11, v7
	v_max_f32_e32 v9, v7, v7
	s_waitcnt lgkmcnt(0)
	v_max_f32_e32 v8, v9, v8
	v_cndmask_b32_e64 v7, v8, v7, s[52:53]
	ds_bpermute_b32 v5, v5, v7
	v_add_u32_e32 v8, s4, v2
	ds_write_b32 v8, v3
	v_add_u32_e32 v3, s4, v1
	s_add_i32 s4, 0, 0x11400
	ds_write_b32 v3, v4
	v_add_u32_e32 v3, s4, v2
	s_waitcnt lgkmcnt(2)
	v_cndmask_b32_e64 v5, v5, v205, s[42:43]
	ds_write_b32 v3, v6
	v_add_u32_e32 v3, s4, v1
	s_add_i32 s4, 0, 0x11600
	ds_write_b32 v3, v12
	s_waitcnt vmcnt(0)
	v_max3_f32 v3, v96, v5, v6
	v_add_u32_e32 v2, s4, v2
	ds_write_b32 v2, v3
	v_max_f32_e32 v2, v7, v7
	v_max_f32_e32 v3, v96, v96
	v_max_f32_e32 v2, v3, v2
	v_add_u32_e32 v1, s4, v1
	ds_write_b32 v1, v2

.LBB0_1103:
	s_or_b64 exec, exec, s[0:1]
	s_waitcnt lgkmcnt(0)
	s_barrier
	ds_read_b128 v[0:3], v138
	ds_read_b128 v[16:19], v138 offset:8704
	ds_read_b128 v[32:35], v138 offset:17408
	ds_read_b128 v[48:51], v138 offset:26112
	s_waitcnt lgkmcnt(3)
	v_mfma_f32_32x32x16_bf16 v[0:15], v[64:67], v[0:3], 0
	s_waitcnt lgkmcnt(2)
	v_mfma_f32_32x32x16_bf16 v[16:31], v[64:67], v[16:19], 0
	s_waitcnt lgkmcnt(1)
	v_mfma_f32_32x32x16_bf16 v[32:47], v[64:67], v[32:35], 0
	s_waitcnt lgkmcnt(0)
	v_mfma_f32_32x32x16_bf16 v[48:63], v[64:67], v[48:51], 0
	ds_read_b128 v[98:101], v138 offset:32
	s_waitcnt lgkmcnt(0)
	v_mfma_f32_32x32x16_bf16 v[0:15], v[68:71], v[98:101], v[0:15]
	ds_read_b128 v[98:101], v138 offset:8736
	s_waitcnt lgkmcnt(0)
	v_mfma_f32_32x32x16_bf16 v[16:31], v[68:71], v[98:101], v[16:31]
	ds_read_b128 v[98:101], v138 offset:17440
	s_waitcnt lgkmcnt(0)
	v_mfma_f32_32x32x16_bf16 v[32:47], v[68:71], v[98:101], v[32:47]
	ds_read_b128 v[98:101], v138 offset:26144
	s_waitcnt lgkmcnt(0)
	v_mfma_f32_32x32x16_bf16 v[48:63], v[68:71], v[98:101], v[48:63]
	ds_read_b128 v[98:101], v138 offset:64
	s_waitcnt lgkmcnt(0)
	v_mfma_f32_32x32x16_bf16 v[0:15], v[72:75], v[98:101], v[0:15]
	ds_read_b128 v[98:101], v138 offset:8768
	s_waitcnt lgkmcnt(0)
	v_mfma_f32_32x32x16_bf16 v[16:31], v[72:75], v[98:101], v[16:31]
	ds_read_b128 v[98:101], v138 offset:17472
	s_waitcnt lgkmcnt(0)
	v_mfma_f32_32x32x16_bf16 v[32:47], v[72:75], v[98:101], v[32:47]
	ds_read_b128 v[98:101], v138 offset:26176
	s_waitcnt lgkmcnt(0)
	v_mfma_f32_32x32x16_bf16 v[48:63], v[72:75], v[98:101], v[48:63]
	ds_read_b128 v[98:101], v138 offset:96
	s_waitcnt lgkmcnt(0)
	v_mfma_f32_32x32x16_bf16 v[0:15], v[76:79], v[98:101], v[0:15]
	ds_read_b128 v[98:101], v138 offset:8800
	s_waitcnt lgkmcnt(0)
	v_mfma_f32_32x32x16_bf16 v[16:31], v[76:79], v[98:101], v[16:31]
	ds_read_b128 v[98:101], v138 offset:17504
	s_waitcnt lgkmcnt(0)
	v_mfma_f32_32x32x16_bf16 v[32:47], v[76:79], v[98:101], v[32:47]
	ds_read_b128 v[98:101], v138 offset:26208
	s_waitcnt lgkmcnt(0)
	v_mfma_f32_32x32x16_bf16 v[48:63], v[76:79], v[98:101], v[48:63]
	ds_read_b128 v[98:101], v138 offset:128
	s_waitcnt lgkmcnt(0)
	v_mfma_f32_32x32x16_bf16 v[0:15], v[80:83], v[98:101], v[0:15]
	ds_read_b128 v[98:101], v138 offset:8832
	s_waitcnt lgkmcnt(0)
	v_mfma_f32_32x32x16_bf16 v[16:31], v[80:83], v[98:101], v[16:31]
	ds_read_b128 v[98:101], v138 offset:17536
	s_waitcnt lgkmcnt(0)
	v_mfma_f32_32x32x16_bf16 v[32:47], v[80:83], v[98:101], v[32:47]
	ds_read_b128 v[98:101], v138 offset:26240
	s_waitcnt lgkmcnt(0)
	v_mfma_f32_32x32x16_bf16 v[48:63], v[80:83], v[98:101], v[48:63]
	ds_read_b128 v[98:101], v138 offset:160
	s_waitcnt lgkmcnt(0)
	v_mfma_f32_32x32x16_bf16 v[0:15], v[84:87], v[98:101], v[0:15]
	ds_read_b128 v[98:101], v138 offset:8864
	s_waitcnt lgkmcnt(0)
	v_mfma_f32_32x32x16_bf16 v[16:31], v[84:87], v[98:101], v[16:31]
	ds_read_b128 v[98:101], v138 offset:17568
	s_waitcnt lgkmcnt(0)
	v_mfma_f32_32x32x16_bf16 v[32:47], v[84:87], v[98:101], v[32:47]
	ds_read_b128 v[98:101], v138 offset:26272
	s_waitcnt lgkmcnt(0)
	v_mfma_f32_32x32x16_bf16 v[48:63], v[84:87], v[98:101], v[48:63]
	ds_read_b128 v[98:101], v138 offset:192
	s_waitcnt lgkmcnt(0)
	v_mfma_f32_32x32x16_bf16 v[0:15], v[88:91], v[98:101], v[0:15]
	ds_read_b128 v[98:101], v138 offset:8896
	s_waitcnt lgkmcnt(0)
	v_mfma_f32_32x32x16_bf16 v[16:31], v[88:91], v[98:101], v[16:31]
	ds_read_b128 v[98:101], v138 offset:17600
	s_waitcnt lgkmcnt(0)
	v_mfma_f32_32x32x16_bf16 v[32:47], v[88:91], v[98:101], v[32:47]
	ds_read_b128 v[98:101], v138 offset:26304
	s_waitcnt lgkmcnt(0)
	v_mfma_f32_32x32x16_bf16 v[48:63], v[88:91], v[98:101], v[48:63]
	ds_read_b128 v[98:101], v138 offset:224
	s_waitcnt lgkmcnt(0)
	v_mfma_f32_32x32x16_bf16 v[0:15], v[92:95], v[98:101], v[0:15]
	ds_read_b128 v[98:101], v138 offset:8928
	s_waitcnt lgkmcnt(0)
	v_mfma_f32_32x32x16_bf16 v[16:31], v[92:95], v[98:101], v[16:31]
	ds_read_b128 v[98:101], v138 offset:17632
	s_waitcnt lgkmcnt(0)
	v_mfma_f32_32x32x16_bf16 v[32:47], v[92:95], v[98:101], v[32:47]
	ds_read_b128 v[98:101], v138 offset:26336
	s_waitcnt lgkmcnt(0)
	v_mfma_f32_32x32x16_bf16 v[48:63], v[92:95], v[98:101], v[48:63]
	s_waitcnt vmcnt(0)
	s_nop 0
	v_mov_b32_e32 v119, v162
	v_ashrrev_i32_e32 v96, 3, v128
	v_lshlrev_b32_e32 v96, 2, v96
	v_and_b32_e32 v96, -16, v96
	v_add_u32_e32 v96, v139, v96
	ds_read_b128 v[106:109], v96
	ds_read_b128 v[98:101], v96 offset:32
	ds_read_b128 v[102:105], v96 offset:64
	ds_read_b128 v[110:113], v96 offset:96
	s_movk_i32 s0, 0x400
	s_waitcnt lgkmcnt(0)
	s_barrier
	s_nop 0
	v_cmp_gt_i32_e32 vcc, s0, v119
	s_and_saveexec_b64 s[0:1], vcc
	s_cbranch_execz .LBB0_1106
	v_and_b32_e32 v118, 31, v119
	v_lshl_add_u32 v120, v118, 3, 0
	s_mov_b64 s[6:7], 0

.LBB0_1107:
	ds_read_b128 v[100:103], v98
	ds_read_b128 v[104:107], v96
	s_add_i32 s0, s0, 32
	s_cmpk_lt_u32 s0, 0x70
	s_waitcnt lgkmcnt(0)
	v_mfma_f32_32x32x16_bf16 v[0:15], v[100:103], v[104:107], v[0:15]
	ds_read_b128 v[104:107], v96 offset:8704
	s_waitcnt lgkmcnt(0)
	v_mfma_f32_32x32x16_bf16 v[16:31], v[100:103], v[104:107], v[16:31]
	ds_read_b128 v[104:107], v96 offset:17408
	s_waitcnt lgkmcnt(0)
	v_mfma_f32_32x32x16_bf16 v[32:47], v[100:103], v[104:107], v[32:47]
	ds_read_b128 v[104:107], v96 offset:26112
	s_waitcnt lgkmcnt(0)
	v_mfma_f32_32x32x16_bf16 v[48:63], v[100:103], v[104:107], v[48:63]
	ds_read_b128 v[100:103], v98 offset:32
	ds_read_b128 v[104:107], v96 offset:32
	v_add_u32_e32 v98, 64, v98
	s_waitcnt lgkmcnt(0)
	v_mfma_f32_32x32x16_bf16 v[0:15], v[100:103], v[104:107], v[0:15]
	ds_read_b128 v[104:107], v96 offset:8736
	s_waitcnt lgkmcnt(0)
	v_mfma_f32_32x32x16_bf16 v[16:31], v[100:103], v[104:107], v[16:31]
	ds_read_b128 v[104:107], v96 offset:17440
	s_waitcnt lgkmcnt(0)
	v_mfma_f32_32x32x16_bf16 v[32:47], v[100:103], v[104:107], v[32:47]
	ds_read_b128 v[104:107], v96 offset:26144
	v_add_u32_e32 v96, 64, v96
	s_waitcnt lgkmcnt(0)
	v_mfma_f32_32x32x16_bf16 v[48:63], v[100:103], v[104:107], v[48:63]
	s_cbranch_scc1 .LBB0_1107
	s_nop 0
	s_mov_b64 s[0:1], -1
	v_ashrrev_i32_e32 v98, 3, v128
	v_and_b32_e32 v98, -4, v98
	v_and_b32_e32 v103, 31, v128
	v_add_u32_e32 v105, v98, v129
	v_lshlrev_b32_e32 v96, 2, v103
	v_lshl_add_u64 v[98:99], s[56:57], 0, v[96:97]
	v_add_u32_e32 v100, s61, v105
	v_or_b32_e32 v96, 1, v105
	v_or_b32_e32 v102, 2, v105
	s_andn2_b64 vcc, exec, s[54:55]
	v_lshlrev_b32_e32 v237, 2, v105
	v_ashrrev_i32_e32 v101, 31, v100
	v_lshlrev_b32_e32 v236, 2, v96
	v_add_u32_e32 v104, s61, v96
	v_lshlrev_b32_e32 v235, 2, v102
	v_add_u32_e32 v102, s61, v102
	v_or_b32_e32 v234, 3, v105
	s_cbranch_vccnz .LBB0_1110
	s_add_i32 s0, 0, 0x11e00
	s_add_i32 s1, 0, 0x12200
	v_add_u32_e32 v238, s0, v237
	v_add_u32_e32 v239, s1, v237
	ds_read_b32 v96, v238
	ds_read_b32 v105, v239
	v_mov_b32_e32 v110, v0
	v_mov_b32_e32 v111, v16
	v_or_b32_e32 v103, s75, v103
	s_waitcnt lgkmcnt(1)
	v_max_f32_e64 v96, |v96|, |v96|
	s_waitcnt lgkmcnt(0)
	v_max_f32_e32 v96, v96, v105
	v_div_scale_f32 v105, s[6:7], v96, v96, 1.0
	v_rcp_f32_e32 v106, v105
	v_readlane_b32 s6, v249, 7
	v_readlane_b32 s7, v249, 8
	v_readlane_b32 s12, v251, 20
	v_fma_f32 v107, -v105, v106, 1.0
	v_fmac_f32_e32 v106, v107, v106
	v_div_scale_f32 v107, vcc, 1.0, v96, 1.0
	v_mul_f32_e32 v108, v107, v106
	v_fma_f32 v109, -v105, v108, v107
	v_fmac_f32_e32 v108, v109, v106
	v_fma_f32 v105, -v105, v108, v107
	v_div_fmas_f32 v105, v105, v106, v108
	v_lshlrev_b64 v[106:107], 11, v[100:101]
	v_lshl_add_u64 v[106:107], v[98:99], 0, v[106:107]
	global_load_dword v108, v[106:107], off
	global_load_dword v109, v[106:107], off offset:128
	global_load_dword v112, v[106:107], off offset:256
	global_load_dword v113, v[106:107], off offset:384
	v_div_fixup_f32 v96, v105, v96, 1.0
	v_mov_b32_e32 v106, v32
	v_mov_b32_e32 v107, v48
	v_readlane_b32 s18, v251, 26
	v_readlane_b32 s19, v251, 27
	v_readlane_b32 s14, v251, 22
	v_readlane_b32 s15, v251, 23
	v_readlane_b32 s16, v251, 24
	v_readlane_b32 s17, v251, 25
	v_readlane_b32 s20, v251, 28
	v_readlane_b32 s21, v251, 29
	v_readlane_b32 s22, v251, 30
	v_readlane_b32 s23, v251, 31
	v_readlane_b32 s25, v251, 33
	v_readlane_b32 s14, v248, 4
	s_mov_b64 s[16:17], s[82:83]
	s_mov_b32 s25, 0x85000
	s_mov_b32 s23, 0x59000
	s_mov_b32 s22, 0x2d000
	s_mov_b32 s21, 0x84000
	s_mov_b32 s20, 0x58000
	s_movk_i32 s29, 0x47ff
	s_mov_b32 s28, 0x4800000
	v_readlane_b32 s15, v248, 5
	v_readlane_b32 s13, v251, 21
	v_readlane_b32 s24, v251, 32
	v_readlane_b32 s26, v251, 34
	v_readlane_b32 s27, v251, 35
	s_waitcnt vmcnt(2)
	v_pk_fma_f32 v[110:111], v[110:111], v[96:97], v[108:109] op_sel_hi:[1,0,1]
	v_pk_mul_f32 v[108:109], v[110:111], v[110:111]
	s_waitcnt vmcnt(0)
	v_pk_fma_f32 v[124:125], v[106:107], v[96:97], v[112:113] op_sel_hi:[1,0,1]
	v_add_f32_e32 v96, v108, v109
	v_pk_mul_f32 v[106:107], v[124:125], v[124:125]
	v_add_f32_e32 v96, v96, v106
	v_add_f32_e32 v96, v96, v107
	v_mov_b32_e32 v105, v96
	v_mov_b32_e32 v255, v96
	s_nop 1
	v_permlane16_swap_b32_e32 v105, v255
	s_nop 1
	v_mov_b32_dpp v105, v255 quad_perm:[0,1,2,3] row_mask:0x5 bank_mask:0xf
	v_mov_b64_e32 v[106:107], s[6:7]
	v_mad_i64_i32 v[108:109], s[6:7], v100, s74, v[106:107]
	v_lshl_add_u64 v[126:127], v[108:109], 0, s[96:97]
	v_add_f32_e32 v96, v96, v105
	s_nop 1
	v_mov_b32_dpp v105, v96 row_ror:8 row_mask:0xf bank_mask:0xf
	v_lshlrev_b64 v[108:109], 10, v[100:101]
	v_lshl_add_u64 v[112:113], s[66:67], 0, v[108:109]
	v_add_f32_e32 v96, v96, v105
	s_nop 1
	v_mov_b32_dpp v105, v96 row_shl:4 row_mask:0xf bank_mask:0x5
	v_mov_b32_dpp v105, v96 row_shr:4 row_mask:0xf bank_mask:0xa
	s_nop 0
	v_add_f32_e32 v96, v96, v105
	s_nop 1
	v_mov_b32_dpp v105, v96 quad_perm:[2,3,0,1] row_mask:0xf bank_mask:0xf
	v_add_f32_e32 v96, v96, v105
	s_nop 1
	v_add_f32_dpp v96, v96, v96 quad_perm:[1,0,3,2] row_mask:0xf bank_mask:0xf
	v_fmamk_f32 v96, v96, 0x3c000000, v163
	v_cmp_gt_f32_e32 vcc, s86, v96
	v_mul_f32_e32 v105, 0x4b800000, v96
	s_nop 0
	v_cndmask_b32_e32 v96, v96, v105, vcc
	v_rsq_f32_e32 v96, v96
	s_nop 0
	v_mul_f32_e32 v105, 0x45800000, v96
	v_cndmask_b32_e32 v105, v96, v105, vcc
	v_lshlrev_b32_e32 v96, 1, v103
	v_lshl_add_u64 v[108:109], v[126:127], 0, v[96:97]
	global_load_ushort v108, v[108:109], off
	v_mov_b32_e32 v109, v97
	v_mul_f32_e32 v110, v110, v105
	v_lshl_add_u64 v[122:123], v[112:113], 0, v[96:97]
	v_or_b32_e32 v112, 64, v96
	v_mov_b32_e32 v113, v97
	s_waitcnt vmcnt(0)
	v_lshlrev_b32_e32 v108, 16, v108
	v_mul_f32_e32 v108, 0xbfb8aa3b, v108
	v_exp_f32_e32 v108, v108
	s_nop 0
	v_add_f32_e32 v108, 1.0, v108
	v_rcp_f32_e32 v118, v108
	v_or_b32_e32 v108, s34, v103
	v_lshl_add_u64 v[108:109], v[108:109], 2, s[18:19]
	global_load_dword v119, v[108:109], off
	s_waitcnt vmcnt(0)
	v_mul_f32_e32 v110, v119, v110
	v_mul_f32_e32 v110, v118, v110
	v_cvt_pk_bf16_f32 v110, v110, s0
	v_lshl_add_u64 v[118:119], v[126:127], 0, v[112:113]
	global_store_short v[122:123], v110, off
	global_load_ushort v110, v[118:119], off
	v_mul_f32_e32 v119, v111, v105
	v_mov_b32_e32 v111, v97
	s_waitcnt vmcnt(0)
	v_lshlrev_b32_e32 v110, 16, v110
	v_mul_f32_e32 v110, 0xbfb8aa3b, v110
	v_exp_f32_e32 v110, v110
	s_nop 0
	v_add_f32_e32 v110, 1.0, v110
	v_rcp_f32_e32 v118, v110
	v_add_u32_e32 v110, s34, v103
	v_lshl_add_u64 v[110:111], v[110:111], 2, s[18:19]
	global_load_dword v103, v[110:111], off offset:128
	s_mov_b32 s19, 0x2c000
	s_movk_i32 s18, 0x1600
	s_waitcnt vmcnt(0)
	v_mul_f32_e32 v103, v103, v119
	v_mul_f32_e32 v103, v118, v103
	v_or_b32_e32 v118, 0x80, v96
	v_mov_b32_e32 v119, v97
	v_cvt_pk_bf16_f32 v103, v103, s0
	v_lshl_add_u64 v[120:121], v[126:127], 0, v[118:119]
	global_store_short v[122:123], v103, off offset:64
	global_load_ushort v103, v[120:121], off
	v_mul_f32_e32 v120, v124, v105
	global_load_dword v121, v[110:111], off offset:256
	global_load_dword v124, v[110:111], off offset:384
	v_mul_f32_e32 v105, v125, v105
	s_waitcnt vmcnt(2)
	v_lshlrev_b32_e32 v103, 16, v103
	v_mul_f32_e32 v103, 0xbfb8aa3b, v103
	v_exp_f32_e32 v103, v103
	s_waitcnt vmcnt(1)
	v_mul_f32_e32 v120, v121, v120
	v_mov_b32_e32 v121, v97
	s_waitcnt vmcnt(0)
	v_mul_f32_e32 v105, v124, v105
	v_add_f32_e32 v103, 1.0, v103
	v_rcp_f32_e32 v103, v103
	s_nop 0
	v_mul_f32_e32 v103, v120, v103
	v_or_b32_e32 v120, 0xc0, v96
	v_cvt_pk_bf16_f32 v103, v103, s0
	v_lshl_add_u64 v[126:127], v[126:127], 0, v[120:121]
	global_store_short v[122:123], v103, off offset:128
	global_load_ushort v103, v[126:127], off
	s_waitcnt vmcnt(0)
	v_lshlrev_b32_e32 v103, 16, v103
	v_mul_f32_e32 v103, 0xbfb8aa3b, v103
	v_exp_f32_e32 v103, v103
	s_nop 0
	v_add_f32_e32 v103, 1.0, v103
	v_rcp_f32_e32 v103, v103
	s_nop 0
	v_mul_f32_e32 v103, v105, v103
	v_cvt_pk_bf16_f32 v103, v103, s0
	global_store_short v[122:123], v103, off offset:192
	v_add_u32_e32 v103, s0, v236
	v_add_u32_e32 v105, s1, v236
	ds_read_b32 v103, v103
	ds_read_b32 v105, v105
	v_mov_b32_e32 v242, v1
	v_mov_b32_e32 v243, v17
	s_waitcnt lgkmcnt(1)
	v_max_f32_e64 v103, |v103|, |v103|
	s_waitcnt lgkmcnt(0)
	v_max_f32_e32 v103, v103, v105
	v_div_scale_f32 v105, s[6:7], v103, v103, 1.0
	v_rcp_f32_e32 v122, v105
	s_nop 0
	v_fma_f32 v123, -v105, v122, 1.0
	v_fmac_f32_e32 v122, v123, v122
	v_div_scale_f32 v123, vcc, 1.0, v103, 1.0
	v_mul_f32_e32 v124, v123, v122
	v_fma_f32 v125, -v105, v124, v123
	v_fmac_f32_e32 v124, v125, v122
	v_fma_f32 v105, -v105, v124, v123
	v_div_fmas_f32 v105, v105, v122, v124
	v_div_fixup_f32 v122, v105, v103, 1.0
	v_ashrrev_i32_e32 v105, 31, v104
	v_lshlrev_b64 v[124:125], 11, v[104:105]
	v_lshl_add_u64 v[124:125], v[98:99], 0, v[124:125]
	global_load_dword v126, v[124:125], off
	global_load_dword v127, v[124:125], off offset:128
	global_load_dword v244, v[124:125], off offset:256
	global_load_dword v245, v[124:125], off offset:384
	v_mov_b32_e32 v124, v33
	v_mov_b32_e32 v125, v49
	s_waitcnt vmcnt(2)
	v_pk_fma_f32 v[126:127], v[242:243], v[122:123], v[126:127] op_sel_hi:[1,0,1]
	v_pk_mul_f32 v[242:243], v[126:127], v[126:127]
	s_waitcnt vmcnt(0)
	v_pk_fma_f32 v[124:125], v[124:125], v[122:123], v[244:245] op_sel_hi:[1,0,1]
	v_add_f32_e32 v103, v242, v243
	v_pk_mul_f32 v[122:123], v[124:125], v[124:125]
	v_add_f32_e32 v103, v103, v122
	v_add_f32_e32 v103, v103, v123
	v_mov_b32_e32 v122, v103
	v_mov_b32_e32 v255, v103
	s_nop 1
	v_permlane16_swap_b32_e32 v122, v255
	s_nop 1
	v_mov_b32_dpp v122, v255 quad_perm:[0,1,2,3] row_mask:0x5 bank_mask:0xf
	s_nop 0
	v_add_f32_e32 v103, v103, v122
	s_nop 1
	v_mov_b32_dpp v122, v103 row_ror:8 row_mask:0xf bank_mask:0xf
	s_nop 0
	v_add_f32_e32 v103, v103, v122
	s_nop 1
	v_mov_b32_dpp v122, v103 row_shl:4 row_mask:0xf bank_mask:0x5
	v_mov_b32_dpp v122, v103 row_shr:4 row_mask:0xf bank_mask:0xa
	s_nop 0
	v_add_f32_e32 v103, v103, v122
	s_nop 1
	v_mov_b32_dpp v122, v103 quad_perm:[2,3,0,1] row_mask:0xf bank_mask:0xf
	v_add_f32_e32 v103, v103, v122
	s_nop 1
	v_add_f32_dpp v103, v103, v103 quad_perm:[1,0,3,2] row_mask:0xf bank_mask:0xf
	v_fmamk_f32 v103, v103, 0x3c000000, v163
	v_cmp_gt_f32_e32 vcc, s86, v103
	v_mul_f32_e32 v122, 0x4b800000, v103
	s_nop 0
	v_cndmask_b32_e32 v103, v103, v122, vcc
	v_rsq_f32_e32 v103, v103
	s_nop 0
	v_mul_f32_e32 v122, 0x45800000, v103
	v_cndmask_b32_e32 v103, v103, v122, vcc
	v_mad_i64_i32 v[122:123], s[6:7], v104, s74, v[106:107]
	v_lshl_add_u64 v[242:243], v[122:123], 0, s[96:97]
	v_lshl_add_u64 v[244:245], v[242:243], 0, v[96:97]
	v_lshlrev_b64 v[122:123], 10, v[104:105]
	global_load_ushort v105, v[244:245], off
	v_mul_f32_e32 v126, v126, v103
	global_load_dword v244, v[108:109], off
	v_lshl_add_u64 v[122:123], s[66:67], 0, v[122:123]
	v_lshl_add_u64 v[122:123], v[122:123], 0, v[96:97]
	v_mul_f32_e32 v124, v124, v103
	s_waitcnt vmcnt(1)
	v_lshlrev_b32_e32 v105, 16, v105
	v_mul_f32_e32 v105, 0xbfb8aa3b, v105
	v_exp_f32_e32 v105, v105
	s_waitcnt vmcnt(0)
	v_mul_f32_e32 v126, v244, v126
	v_lshl_add_u64 v[244:245], v[242:243], 0, v[112:113]
	v_add_f32_e32 v105, 1.0, v105
	v_rcp_f32_e32 v105, v105
	s_nop 0
	v_mul_f32_e32 v105, v105, v126
	v_cvt_pk_bf16_f32 v105, v105, s0
	global_store_short v[122:123], v105, off
	global_load_ushort v105, v[244:245], off
	v_mul_f32_e32 v126, v127, v103
	global_load_dword v127, v[110:111], off offset:128
	v_mul_f32_e32 v103, v125, v103
	s_waitcnt vmcnt(1)
	v_lshlrev_b32_e32 v105, 16, v105
	v_mul_f32_e32 v105, 0xbfb8aa3b, v105
	v_exp_f32_e32 v105, v105
	s_waitcnt vmcnt(0)
	v_mul_f32_e32 v126, v127, v126
	v_add_f32_e32 v105, 1.0, v105
	v_rcp_f32_e32 v105, v105
	s_nop 0
	v_mul_f32_e32 v105, v105, v126
	v_cvt_pk_bf16_f32 v105, v105, s0
	v_lshl_add_u64 v[126:127], v[242:243], 0, v[118:119]
	global_store_short v[122:123], v105, off offset:64
	global_load_ushort v105, v[126:127], off
	s_waitcnt vmcnt(0)
	v_lshlrev_b32_e32 v105, 16, v105
	global_load_dword v126, v[110:111], off offset:256
	v_mul_f32_e32 v105, 0xbfb8aa3b, v105
	v_exp_f32_e32 v105, v105
	s_waitcnt vmcnt(0)
	v_mul_f32_e32 v124, v126, v124
	v_add_f32_e32 v105, 1.0, v105
	v_rcp_f32_e32 v105, v105
	v_lshl_add_u64 v[126:127], v[242:243], 0, v[120:121]
	v_mul_f32_e32 v105, v124, v105
	v_cvt_pk_bf16_f32 v105, v105, s0
	global_store_short v[122:123], v105, off offset:128
	global_load_ushort v105, v[126:127], off
	s_waitcnt vmcnt(0)
	v_lshlrev_b32_e32 v105, 16, v105
	global_load_dword v124, v[110:111], off offset:384
	v_mul_f32_e32 v105, 0xbfb8aa3b, v105
	v_exp_f32_e32 v105, v105
	s_waitcnt vmcnt(0)
	v_mul_f32_e32 v103, v124, v103
	v_add_f32_e32 v105, 1.0, v105
	v_rcp_f32_e32 v105, v105
	s_nop 0
	v_mul_f32_e32 v103, v103, v105
	v_cvt_pk_bf16_f32 v103, v103, s0
	global_store_short v[122:123], v103, off offset:192
	v_add_u32_e32 v103, s0, v235
	v_add_u32_e32 v105, s1, v235
	ds_read_b32 v103, v103
	ds_read_b32 v105, v105
	v_mov_b32_e32 v242, v2
	v_mov_b32_e32 v243, v18
	s_waitcnt lgkmcnt(1)
	v_max_f32_e64 v103, |v103|, |v103|
	s_waitcnt lgkmcnt(0)
	v_max_f32_e32 v103, v103, v105
	v_div_scale_f32 v105, s[6:7], v103, v103, 1.0
	v_rcp_f32_e32 v122, v105
	s_nop 0
	v_fma_f32 v123, -v105, v122, 1.0
	v_fmac_f32_e32 v122, v123, v122
	v_div_scale_f32 v123, vcc, 1.0, v103, 1.0
	v_mul_f32_e32 v124, v123, v122
	v_fma_f32 v125, -v105, v124, v123
	v_fmac_f32_e32 v124, v125, v122
	v_fma_f32 v105, -v105, v124, v123
	v_div_fmas_f32 v105, v105, v122, v124
	v_div_fixup_f32 v122, v105, v103, 1.0
	v_ashrrev_i32_e32 v103, 31, v102
	v_lshlrev_b64 v[124:125], 11, v[102:103]
	v_lshl_add_u64 v[124:125], v[98:99], 0, v[124:125]
	global_load_dword v126, v[124:125], off
	global_load_dword v127, v[124:125], off offset:128
	global_load_dword v244, v[124:125], off offset:256
	global_load_dword v245, v[124:125], off offset:384
	v_mov_b32_e32 v124, v34
	v_mov_b32_e32 v125, v50
	s_waitcnt vmcnt(2)
	v_pk_fma_f32 v[126:127], v[242:243], v[122:123], v[126:127] op_sel_hi:[1,0,1]
	v_pk_mul_f32 v[242:243], v[126:127], v[126:127]
	s_waitcnt vmcnt(0)
	v_pk_fma_f32 v[124:125], v[124:125], v[122:123], v[244:245] op_sel_hi:[1,0,1]
	v_add_f32_e32 v105, v242, v243
	v_pk_mul_f32 v[122:123], v[124:125], v[124:125]
	v_add_f32_e32 v105, v105, v122
	v_add_f32_e32 v105, v105, v123
	v_mov_b32_e32 v122, v105
	v_mov_b32_e32 v255, v105
	s_nop 1
	v_permlane16_swap_b32_e32 v122, v255
	s_nop 1
	v_mov_b32_dpp v122, v255 quad_perm:[0,1,2,3] row_mask:0x5 bank_mask:0xf
	s_nop 0
	v_add_f32_e32 v105, v105, v122
	s_nop 1
	v_mov_b32_dpp v122, v105 row_ror:8 row_mask:0xf bank_mask:0xf
	s_nop 0
	v_add_f32_e32 v105, v105, v122
	s_nop 1
	v_mov_b32_dpp v122, v105 row_shl:4 row_mask:0xf bank_mask:0x5
	v_mov_b32_dpp v122, v105 row_shr:4 row_mask:0xf bank_mask:0xa
	s_nop 0
	v_add_f32_e32 v105, v105, v122
	s_nop 1
	v_mov_b32_dpp v122, v105 quad_perm:[2,3,0,1] row_mask:0xf bank_mask:0xf
	v_add_f32_e32 v105, v105, v122
	s_nop 1
	v_add_f32_dpp v105, v105, v105 quad_perm:[1,0,3,2] row_mask:0xf bank_mask:0xf
	v_fmamk_f32 v105, v105, 0x3c000000, v163
	v_cmp_gt_f32_e32 vcc, s86, v105
	v_mul_f32_e32 v122, 0x4b800000, v105
	s_nop 0
	v_cndmask_b32_e32 v105, v105, v122, vcc
	v_rsq_f32_e32 v105, v105
	s_nop 0
	v_mul_f32_e32 v122, 0x45800000, v105
	v_cndmask_b32_e32 v105, v105, v122, vcc
	v_mad_i64_i32 v[122:123], s[6:7], v102, s74, v[106:107]
	v_lshl_add_u64 v[242:243], v[122:123], 0, s[96:97]
	v_lshl_add_u64 v[244:245], v[242:243], 0, v[96:97]
	v_lshlrev_b64 v[122:123], 10, v[102:103]
	global_load_ushort v103, v[244:245], off
	v_mul_f32_e32 v126, v126, v105
	global_load_dword v244, v[108:109], off
	v_lshl_add_u64 v[122:123], s[66:67], 0, v[122:123]
	v_lshl_add_u64 v[122:123], v[122:123], 0, v[96:97]
	v_mul_f32_e32 v124, v124, v105
	s_waitcnt vmcnt(1)
	v_lshlrev_b32_e32 v103, 16, v103
	v_mul_f32_e32 v103, 0xbfb8aa3b, v103
	v_exp_f32_e32 v103, v103
	s_waitcnt vmcnt(0)
	v_mul_f32_e32 v126, v244, v126
	v_lshl_add_u64 v[244:245], v[242:243], 0, v[112:113]
	v_add_f32_e32 v103, 1.0, v103
	v_rcp_f32_e32 v103, v103
	s_nop 0
	v_mul_f32_e32 v103, v103, v126
	v_cvt_pk_bf16_f32 v103, v103, s0
	global_store_short v[122:123], v103, off
	global_load_ushort v103, v[244:245], off
	v_mul_f32_e32 v126, v127, v105
	global_load_dword v127, v[110:111], off offset:128
	v_mul_f32_e32 v105, v125, v105
	s_waitcnt vmcnt(1)
	v_lshlrev_b32_e32 v103, 16, v103
	v_mul_f32_e32 v103, 0xbfb8aa3b, v103
	v_exp_f32_e32 v103, v103
	s_waitcnt vmcnt(0)
	v_mul_f32_e32 v126, v127, v126
	v_add_f32_e32 v103, 1.0, v103
	v_rcp_f32_e32 v103, v103
	s_nop 0
	v_mul_f32_e32 v103, v103, v126
	v_cvt_pk_bf16_f32 v103, v103, s0
	v_lshl_add_u64 v[126:127], v[242:243], 0, v[118:119]
	global_store_short v[122:123], v103, off offset:64
	global_load_ushort v103, v[126:127], off
	s_waitcnt vmcnt(0)
	v_lshlrev_b32_e32 v103, 16, v103
	global_load_dword v126, v[110:111], off offset:256
	v_mul_f32_e32 v103, 0xbfb8aa3b, v103
	v_exp_f32_e32 v103, v103
	s_waitcnt vmcnt(0)
	v_mul_f32_e32 v124, v126, v124
	v_add_f32_e32 v103, 1.0, v103
	v_rcp_f32_e32 v103, v103
	v_lshl_add_u64 v[126:127], v[242:243], 0, v[120:121]
	v_mul_f32_e32 v103, v124, v103
	v_cvt_pk_bf16_f32 v103, v103, s0
	global_store_short v[122:123], v103, off offset:128
	global_load_ushort v103, v[126:127], off
	s_waitcnt vmcnt(0)
	v_lshlrev_b32_e32 v103, 16, v103
	global_load_dword v124, v[110:111], off offset:384
	v_mul_f32_e32 v103, 0xbfb8aa3b, v103
	v_exp_f32_e32 v103, v103
	s_waitcnt vmcnt(0)
	v_mul_f32_e32 v105, v124, v105
	v_add_f32_e32 v103, 1.0, v103
	v_rcp_f32_e32 v103, v103
	s_nop 0
	v_mul_f32_e32 v103, v105, v103
	v_cvt_pk_bf16_f32 v103, v103, s0
	global_store_short v[122:123], v103, off offset:192
	v_lshlrev_b32_e32 v103, 2, v234
	v_add_u32_e32 v105, s0, v103
	v_add_u32_e32 v103, s1, v103
	ds_read_b32 v105, v105
	ds_read_b32 v103, v103
	v_add_u32_e32 v126, s61, v234
	v_ashrrev_i32_e32 v127, 31, v126
	v_mov_b32_e32 v244, v3
	s_waitcnt lgkmcnt(1)
	v_max_f32_e64 v105, |v105|, |v105|
	s_waitcnt lgkmcnt(0)
	v_max_f32_e32 v103, v105, v103
	v_div_scale_f32 v105, s[0:1], v103, v103, 1.0
	v_rcp_f32_e32 v122, v105
	v_mov_b32_e32 v245, v19
	v_fma_f32 v123, -v105, v122, 1.0
	v_fmac_f32_e32 v122, v123, v122
	v_div_scale_f32 v123, vcc, 1.0, v103, 1.0
	v_mul_f32_e32 v124, v123, v122
	v_fma_f32 v125, -v105, v124, v123
	v_fmac_f32_e32 v124, v125, v122
	v_fma_f32 v105, -v105, v124, v123
	v_div_fmas_f32 v105, v105, v122, v124
	v_lshlrev_b64 v[124:125], 11, v[126:127]
	v_lshl_add_u64 v[124:125], v[98:99], 0, v[124:125]
	global_load_dword v242, v[124:125], off
	global_load_dword v243, v[124:125], off offset:128
	global_load_dword v246, v[124:125], off offset:256
	global_load_dword v247, v[124:125], off offset:384
	v_div_fixup_f32 v122, v105, v103, 1.0
	v_mov_b32_e32 v124, v35
	v_mov_b32_e32 v125, v51
	s_waitcnt vmcnt(2)
	v_pk_fma_f32 v[242:243], v[244:245], v[122:123], v[242:243] op_sel_hi:[1,0,1]
	v_pk_mul_f32 v[244:245], v[242:243], v[242:243]
	s_waitcnt vmcnt(0)
	v_pk_fma_f32 v[124:125], v[124:125], v[122:123], v[246:247] op_sel_hi:[1,0,1]
	v_add_f32_e32 v103, v244, v245
	v_pk_mul_f32 v[122:123], v[124:125], v[124:125]
	v_add_f32_e32 v103, v103, v122
	v_add_f32_e32 v103, v103, v123
	v_mov_b32_e32 v105, v103
	v_mov_b32_e32 v255, v103
	s_nop 1
	v_permlane16_swap_b32_e32 v105, v255
	s_nop 1
	v_mov_b32_dpp v105, v255 quad_perm:[0,1,2,3] row_mask:0x5 bank_mask:0xf
	v_mad_i64_i32 v[122:123], s[0:1], v126, s74, v[106:107]
	v_lshl_add_u64 v[244:245], v[122:123], 0, s[96:97]
	v_lshlrev_b64 v[122:123], 10, v[126:127]
	v_add_f32_e32 v103, v103, v105
	s_nop 1
	v_mov_b32_dpp v105, v103 row_ror:8 row_mask:0xf bank_mask:0xf
	v_lshl_add_u64 v[126:127], v[244:245], 0, v[96:97]
	v_lshl_add_u64 v[122:123], s[66:67], 0, v[122:123]
	v_lshl_add_u64 v[122:123], v[122:123], 0, v[96:97]
	v_add_f32_e32 v103, v103, v105
	s_nop 1
	v_mov_b32_dpp v105, v103 row_shl:4 row_mask:0xf bank_mask:0x5
	v_mov_b32_dpp v105, v103 row_shr:4 row_mask:0xf bank_mask:0xa
	s_nop 0
	v_add_f32_e32 v103, v103, v105
	s_nop 1
	v_mov_b32_dpp v105, v103 quad_perm:[2,3,0,1] row_mask:0xf bank_mask:0xf
	v_add_f32_e32 v103, v103, v105
	s_nop 1
	v_add_f32_dpp v103, v103, v103 quad_perm:[1,0,3,2] row_mask:0xf bank_mask:0xf
	v_fmamk_f32 v103, v103, 0x3c000000, v163
	v_cmp_gt_f32_e32 vcc, s86, v103
	v_mul_f32_e32 v105, 0x4b800000, v103
	s_nop 0
	v_cndmask_b32_e32 v103, v103, v105, vcc
	v_rsq_f32_e32 v103, v103
	s_nop 0
	v_mul_f32_e32 v105, 0x45800000, v103
	v_cndmask_b32_e32 v103, v103, v105, vcc
	global_load_ushort v105, v[126:127], off
	v_mul_f32_e32 v126, v242, v103
	global_load_dword v127, v[108:109], off
	v_mul_f32_e32 v124, v124, v103
	s_waitcnt vmcnt(1)
	v_lshlrev_b32_e32 v105, 16, v105
	v_mul_f32_e32 v105, 0xbfb8aa3b, v105
	v_exp_f32_e32 v105, v105
	s_waitcnt vmcnt(0)
	v_mul_f32_e32 v126, v127, v126
	v_add_f32_e32 v105, 1.0, v105
	v_rcp_f32_e32 v105, v105
	s_nop 0
	v_mul_f32_e32 v105, v105, v126
	v_cvt_pk_bf16_f32 v105, v105, s0
	v_lshl_add_u64 v[126:127], v[244:245], 0, v[112:113]
	global_store_short v[122:123], v105, off
	global_load_ushort v105, v[126:127], off
	v_mul_f32_e32 v126, v243, v103
	global_load_dword v127, v[110:111], off offset:128
	v_mul_f32_e32 v103, v125, v103
	s_waitcnt vmcnt(1)
	v_lshlrev_b32_e32 v105, 16, v105
	v_mul_f32_e32 v105, 0xbfb8aa3b, v105
	v_exp_f32_e32 v105, v105
	s_waitcnt vmcnt(0)
	v_mul_f32_e32 v126, v127, v126
	v_add_f32_e32 v105, 1.0, v105
	v_rcp_f32_e32 v105, v105
	s_nop 0
	v_mul_f32_e32 v105, v105, v126
	v_cvt_pk_bf16_f32 v105, v105, s0
	v_lshl_add_u64 v[126:127], v[244:245], 0, v[118:119]
	global_store_short v[122:123], v105, off offset:64
	global_load_ushort v105, v[126:127], off
	s_waitcnt vmcnt(0)
	v_lshlrev_b32_e32 v105, 16, v105
	global_load_dword v126, v[110:111], off offset:256
	v_mul_f32_e32 v105, 0xbfb8aa3b, v105
	v_exp_f32_e32 v105, v105
	s_waitcnt vmcnt(0)
	v_mul_f32_e32 v124, v126, v124
	v_add_f32_e32 v105, 1.0, v105
	v_rcp_f32_e32 v105, v105
	v_lshl_add_u64 v[126:127], v[244:245], 0, v[120:121]
	v_mul_f32_e32 v105, v124, v105
	v_cvt_pk_bf16_f32 v105, v105, s0
	global_store_short v[122:123], v105, off offset:128
	global_load_ushort v105, v[126:127], off
	s_waitcnt vmcnt(0)
	v_lshlrev_b32_e32 v105, 16, v105
	global_load_dword v124, v[110:111], off offset:384
	v_mul_f32_e32 v105, 0xbfb8aa3b, v105
	v_exp_f32_e32 v105, v105
	s_waitcnt vmcnt(0)
	v_mul_f32_e32 v103, v124, v103
	v_add_f32_e32 v105, 1.0, v105
	v_rcp_f32_e32 v105, v105
	s_nop 0
	v_mul_f32_e32 v103, v103, v105
	v_cvt_pk_bf16_f32 v103, v103, s0
	global_store_short v[122:123], v103, off offset:192
	ds_read_b32 v103, v238 offset:32
	ds_read_b32 v105, v239 offset:32
	v_add_u32_e32 v126, 8, v100
	v_ashrrev_i32_e32 v127, 31, v126
	v_mov_b32_e32 v244, v4
	s_waitcnt lgkmcnt(1)
	v_max_f32_e64 v103, |v103|, |v103|
	s_waitcnt lgkmcnt(0)
	v_max_f32_e32 v103, v103, v105
	v_div_scale_f32 v105, s[0:1], v103, v103, 1.0
	v_rcp_f32_e32 v122, v105
	v_mov_b32_e32 v245, v20
	v_fma_f32 v123, -v105, v122, 1.0
	v_fmac_f32_e32 v122, v123, v122
	v_div_scale_f32 v123, vcc, 1.0, v103, 1.0
	v_mul_f32_e32 v124, v123, v122
	v_fma_f32 v125, -v105, v124, v123
	v_fmac_f32_e32 v124, v125, v122
	v_fma_f32 v105, -v105, v124, v123
	v_div_fmas_f32 v105, v105, v122, v124
	v_lshlrev_b64 v[124:125], 11, v[126:127]
	v_lshl_add_u64 v[124:125], v[98:99], 0, v[124:125]
	global_load_dword v242, v[124:125], off
	global_load_dword v243, v[124:125], off offset:128
	global_load_dword v246, v[124:125], off offset:256
	global_load_dword v247, v[124:125], off offset:384
	v_div_fixup_f32 v122, v105, v103, 1.0
	v_mov_b32_e32 v124, v36
	v_mov_b32_e32 v125, v52
	s_waitcnt vmcnt(2)
	v_pk_fma_f32 v[242:243], v[244:245], v[122:123], v[242:243] op_sel_hi:[1,0,1]
	v_pk_mul_f32 v[244:245], v[242:243], v[242:243]
	s_waitcnt vmcnt(0)
	v_pk_fma_f32 v[124:125], v[124:125], v[122:123], v[246:247] op_sel_hi:[1,0,1]
	v_add_f32_e32 v103, v244, v245
	v_pk_mul_f32 v[122:123], v[124:125], v[124:125]
	v_add_f32_e32 v103, v103, v122
	v_add_f32_e32 v103, v103, v123
	v_mov_b32_e32 v105, v103
	v_mov_b32_e32 v255, v103
	s_nop 1
	v_permlane16_swap_b32_e32 v105, v255
	s_nop 1
	v_mov_b32_dpp v105, v255 quad_perm:[0,1,2,3] row_mask:0x5 bank_mask:0xf
	v_mad_i64_i32 v[122:123], s[0:1], v126, s74, v[106:107]
	v_lshl_add_u64 v[244:245], v[122:123], 0, s[96:97]
	v_lshlrev_b64 v[122:123], 10, v[126:127]
	v_add_f32_e32 v103, v103, v105
	s_nop 1
	v_mov_b32_dpp v105, v103 row_ror:8 row_mask:0xf bank_mask:0xf
	v_lshl_add_u64 v[126:127], v[244:245], 0, v[96:97]
	v_lshl_add_u64 v[122:123], s[66:67], 0, v[122:123]
	v_lshl_add_u64 v[122:123], v[122:123], 0, v[96:97]
	v_add_f32_e32 v103, v103, v105
	s_nop 1
	v_mov_b32_dpp v105, v103 row_shl:4 row_mask:0xf bank_mask:0x5
	v_mov_b32_dpp v105, v103 row_shr:4 row_mask:0xf bank_mask:0xa
	s_nop 0
	v_add_f32_e32 v103, v103, v105
	s_nop 1
	v_mov_b32_dpp v105, v103 quad_perm:[2,3,0,1] row_mask:0xf bank_mask:0xf
	v_add_f32_e32 v103, v103, v105
	s_nop 1
	v_add_f32_dpp v103, v103, v103 quad_perm:[1,0,3,2] row_mask:0xf bank_mask:0xf
	v_fmamk_f32 v103, v103, 0x3c000000, v163
	v_cmp_gt_f32_e32 vcc, s86, v103
	v_mul_f32_e32 v105, 0x4b800000, v103
	s_nop 0
	v_cndmask_b32_e32 v103, v103, v105, vcc
	v_rsq_f32_e32 v103, v103
	s_nop 0
	v_mul_f32_e32 v105, 0x45800000, v103
	v_cndmask_b32_e32 v103, v103, v105, vcc
	global_load_ushort v105, v[126:127], off
	v_mul_f32_e32 v126, v242, v103
	global_load_dword v127, v[108:109], off
	v_mul_f32_e32 v124, v124, v103
	s_waitcnt vmcnt(1)
	v_lshlrev_b32_e32 v105, 16, v105
	v_mul_f32_e32 v105, 0xbfb8aa3b, v105
	v_exp_f32_e32 v105, v105
	s_waitcnt vmcnt(0)
	v_mul_f32_e32 v126, v127, v126
	v_add_f32_e32 v105, 1.0, v105
	v_rcp_f32_e32 v105, v105
	s_nop 0
	v_mul_f32_e32 v105, v105, v126
	v_cvt_pk_bf16_f32 v105, v105, s0
	v_lshl_add_u64 v[126:127], v[244:245], 0, v[112:113]
	global_store_short v[122:123], v105, off
	global_load_ushort v105, v[126:127], off
	v_mul_f32_e32 v126, v243, v103
	global_load_dword v127, v[110:111], off offset:128
	v_mul_f32_e32 v103, v125, v103
	s_waitcnt vmcnt(1)
	v_lshlrev_b32_e32 v105, 16, v105
	v_mul_f32_e32 v105, 0xbfb8aa3b, v105
	v_exp_f32_e32 v105, v105
	s_waitcnt vmcnt(0)
	v_mul_f32_e32 v126, v127, v126
	v_add_f32_e32 v105, 1.0, v105
	v_rcp_f32_e32 v105, v105
	s_nop 0
	v_mul_f32_e32 v105, v105, v126
	v_cvt_pk_bf16_f32 v105, v105, s0
	v_lshl_add_u64 v[126:127], v[244:245], 0, v[118:119]
	global_store_short v[122:123], v105, off offset:64
	global_load_ushort v105, v[126:127], off
	s_waitcnt vmcnt(0)
	v_lshlrev_b32_e32 v105, 16, v105
	global_load_dword v126, v[110:111], off offset:256
	v_mul_f32_e32 v105, 0xbfb8aa3b, v105
	v_exp_f32_e32 v105, v105
	s_waitcnt vmcnt(0)
	v_mul_f32_e32 v124, v126, v124
	v_add_f32_e32 v105, 1.0, v105
	v_rcp_f32_e32 v105, v105
	v_lshl_add_u64 v[126:127], v[244:245], 0, v[120:121]
	v_mul_f32_e32 v105, v124, v105
	v_cvt_pk_bf16_f32 v105, v105, s0
	global_store_short v[122:123], v105, off offset:128
	global_load_ushort v105, v[126:127], off
	s_waitcnt vmcnt(0)
	v_lshlrev_b32_e32 v105, 16, v105
	global_load_dword v124, v[110:111], off offset:384
	v_mul_f32_e32 v105, 0xbfb8aa3b, v105
	v_exp_f32_e32 v105, v105
	s_waitcnt vmcnt(0)
	v_mul_f32_e32 v103, v124, v103
	v_add_f32_e32 v105, 1.0, v105
	v_rcp_f32_e32 v105, v105
	s_nop 0
	v_mul_f32_e32 v103, v103, v105
	v_cvt_pk_bf16_f32 v103, v103, s0
	global_store_short v[122:123], v103, off offset:192
	ds_read_b32 v103, v238 offset:36
	ds_read_b32 v105, v239 offset:36
	v_add_u32_e32 v126, 9, v100
	v_ashrrev_i32_e32 v127, 31, v126
	v_mov_b32_e32 v244, v5
	s_waitcnt lgkmcnt(1)
	v_max_f32_e64 v103, |v103|, |v103|
	s_waitcnt lgkmcnt(0)
	v_max_f32_e32 v103, v103, v105
	v_div_scale_f32 v105, s[0:1], v103, v103, 1.0
	v_rcp_f32_e32 v122, v105
	v_mov_b32_e32 v245, v21
	v_fma_f32 v123, -v105, v122, 1.0
	v_fmac_f32_e32 v122, v123, v122
	v_div_scale_f32 v123, vcc, 1.0, v103, 1.0
	v_mul_f32_e32 v124, v123, v122
	v_fma_f32 v125, -v105, v124, v123
	v_fmac_f32_e32 v124, v125, v122
	v_fma_f32 v105, -v105, v124, v123
	v_div_fmas_f32 v105, v105, v122, v124
	v_lshlrev_b64 v[124:125], 11, v[126:127]
	v_lshl_add_u64 v[124:125], v[98:99], 0, v[124:125]
	global_load_dword v242, v[124:125], off
	global_load_dword v243, v[124:125], off offset:128
	global_load_dword v246, v[124:125], off offset:256
	global_load_dword v247, v[124:125], off offset:384
	v_div_fixup_f32 v122, v105, v103, 1.0
	v_mov_b32_e32 v124, v37
	v_mov_b32_e32 v125, v53
	s_waitcnt vmcnt(2)
	v_pk_fma_f32 v[242:243], v[244:245], v[122:123], v[242:243] op_sel_hi:[1,0,1]
	v_pk_mul_f32 v[244:245], v[242:243], v[242:243]
	s_waitcnt vmcnt(0)
	v_pk_fma_f32 v[124:125], v[124:125], v[122:123], v[246:247] op_sel_hi:[1,0,1]
	v_add_f32_e32 v103, v244, v245
	v_pk_mul_f32 v[122:123], v[124:125], v[124:125]
	v_add_f32_e32 v103, v103, v122
	v_add_f32_e32 v103, v103, v123
	v_mov_b32_e32 v105, v103
	v_mov_b32_e32 v255, v103
	s_nop 1
	v_permlane16_swap_b32_e32 v105, v255
	s_nop 1
	v_mov_b32_dpp v105, v255 quad_perm:[0,1,2,3] row_mask:0x5 bank_mask:0xf
	v_mad_i64_i32 v[122:123], s[0:1], v126, s74, v[106:107]
	v_lshl_add_u64 v[244:245], v[122:123], 0, s[96:97]
	v_lshlrev_b64 v[122:123], 10, v[126:127]
	v_add_f32_e32 v103, v103, v105
	s_nop 1
	v_mov_b32_dpp v105, v103 row_ror:8 row_mask:0xf bank_mask:0xf
	v_lshl_add_u64 v[126:127], v[244:245], 0, v[96:97]
	v_lshl_add_u64 v[122:123], s[66:67], 0, v[122:123]
	v_lshl_add_u64 v[122:123], v[122:123], 0, v[96:97]
	v_add_f32_e32 v103, v103, v105
	s_nop 1
	v_mov_b32_dpp v105, v103 row_shl:4 row_mask:0xf bank_mask:0x5
	v_mov_b32_dpp v105, v103 row_shr:4 row_mask:0xf bank_mask:0xa
	s_nop 0
	v_add_f32_e32 v103, v103, v105
	s_nop 1
	v_mov_b32_dpp v105, v103 quad_perm:[2,3,0,1] row_mask:0xf bank_mask:0xf
	v_add_f32_e32 v103, v103, v105
	s_nop 1
	v_add_f32_dpp v103, v103, v103 quad_perm:[1,0,3,2] row_mask:0xf bank_mask:0xf
	v_fmamk_f32 v103, v103, 0x3c000000, v163
	v_cmp_gt_f32_e32 vcc, s86, v103
	v_mul_f32_e32 v105, 0x4b800000, v103
	s_nop 0
	v_cndmask_b32_e32 v103, v103, v105, vcc
	v_rsq_f32_e32 v103, v103
	s_nop 0
	v_mul_f32_e32 v105, 0x45800000, v103
	v_cndmask_b32_e32 v103, v103, v105, vcc
	global_load_ushort v105, v[126:127], off
	v_mul_f32_e32 v126, v242, v103
	global_load_dword v127, v[108:109], off
	v_mul_f32_e32 v124, v124, v103
	s_waitcnt vmcnt(1)
	v_lshlrev_b32_e32 v105, 16, v105
	v_mul_f32_e32 v105, 0xbfb8aa3b, v105
	v_exp_f32_e32 v105, v105
	s_waitcnt vmcnt(0)
	v_mul_f32_e32 v126, v127, v126
	v_add_f32_e32 v105, 1.0, v105
	v_rcp_f32_e32 v105, v105
	s_nop 0
	v_mul_f32_e32 v105, v105, v126
	v_cvt_pk_bf16_f32 v105, v105, s0
	v_lshl_add_u64 v[126:127], v[244:245], 0, v[112:113]
	global_store_short v[122:123], v105, off
	global_load_ushort v105, v[126:127], off
	v_mul_f32_e32 v126, v243, v103
	global_load_dword v127, v[110:111], off offset:128
	v_mul_f32_e32 v103, v125, v103
	s_waitcnt vmcnt(1)
	v_lshlrev_b32_e32 v105, 16, v105
	v_mul_f32_e32 v105, 0xbfb8aa3b, v105
	v_exp_f32_e32 v105, v105
	s_waitcnt vmcnt(0)
	v_mul_f32_e32 v126, v127, v126
	v_add_f32_e32 v105, 1.0, v105
	v_rcp_f32_e32 v105, v105
	s_nop 0
	v_mul_f32_e32 v105, v105, v126
	v_cvt_pk_bf16_f32 v105, v105, s0
	v_lshl_add_u64 v[126:127], v[244:245], 0, v[118:119]
	global_store_short v[122:123], v105, off offset:64
	global_load_ushort v105, v[126:127], off
	s_waitcnt vmcnt(0)
	v_lshlrev_b32_e32 v105, 16, v105
	global_load_dword v126, v[110:111], off offset:256
	v_mul_f32_e32 v105, 0xbfb8aa3b, v105
	v_exp_f32_e32 v105, v105
	s_waitcnt vmcnt(0)
	v_mul_f32_e32 v124, v126, v124
	v_add_f32_e32 v105, 1.0, v105
	v_rcp_f32_e32 v105, v105
	v_lshl_add_u64 v[126:127], v[244:245], 0, v[120:121]
	v_mul_f32_e32 v105, v124, v105
	v_cvt_pk_bf16_f32 v105, v105, s0
	global_store_short v[122:123], v105, off offset:128
	global_load_ushort v105, v[126:127], off
	s_waitcnt vmcnt(0)
	v_lshlrev_b32_e32 v105, 16, v105
	global_load_dword v124, v[110:111], off offset:384
	v_mul_f32_e32 v105, 0xbfb8aa3b, v105
	v_exp_f32_e32 v105, v105
	s_waitcnt vmcnt(0)
	v_mul_f32_e32 v103, v124, v103
	v_add_f32_e32 v105, 1.0, v105
	v_rcp_f32_e32 v105, v105
	s_nop 0
	v_mul_f32_e32 v103, v103, v105
	v_cvt_pk_bf16_f32 v103, v103, s0
	global_store_short v[122:123], v103, off offset:192
	ds_read_b32 v103, v238 offset:40
	ds_read_b32 v105, v239 offset:40
	v_add_u32_e32 v126, 10, v100
	v_ashrrev_i32_e32 v127, 31, v126
	v_mov_b32_e32 v244, v6
	s_waitcnt lgkmcnt(1)
	v_max_f32_e64 v103, |v103|, |v103|
	s_waitcnt lgkmcnt(0)
	v_max_f32_e32 v103, v103, v105
	v_div_scale_f32 v105, s[0:1], v103, v103, 1.0
	v_rcp_f32_e32 v122, v105
	v_mov_b32_e32 v245, v22
	v_fma_f32 v123, -v105, v122, 1.0
	v_fmac_f32_e32 v122, v123, v122
	v_div_scale_f32 v123, vcc, 1.0, v103, 1.0
	v_mul_f32_e32 v124, v123, v122
	v_fma_f32 v125, -v105, v124, v123
	v_fmac_f32_e32 v124, v125, v122
	v_fma_f32 v105, -v105, v124, v123
	v_div_fmas_f32 v105, v105, v122, v124
	v_lshlrev_b64 v[124:125], 11, v[126:127]
	v_lshl_add_u64 v[124:125], v[98:99], 0, v[124:125]
	global_load_dword v242, v[124:125], off
	global_load_dword v243, v[124:125], off offset:128
	global_load_dword v246, v[124:125], off offset:256
	global_load_dword v247, v[124:125], off offset:384
	v_div_fixup_f32 v122, v105, v103, 1.0
	v_mov_b32_e32 v124, v38
	v_mov_b32_e32 v125, v54
	s_waitcnt vmcnt(2)
	v_pk_fma_f32 v[242:243], v[244:245], v[122:123], v[242:243] op_sel_hi:[1,0,1]
	v_pk_mul_f32 v[244:245], v[242:243], v[242:243]
	s_waitcnt vmcnt(0)
	v_pk_fma_f32 v[124:125], v[124:125], v[122:123], v[246:247] op_sel_hi:[1,0,1]
	v_add_f32_e32 v103, v244, v245
	v_pk_mul_f32 v[122:123], v[124:125], v[124:125]
	v_add_f32_e32 v103, v103, v122
	v_add_f32_e32 v103, v103, v123
	v_mov_b32_e32 v105, v103
	v_mov_b32_e32 v255, v103
	s_nop 1
	v_permlane16_swap_b32_e32 v105, v255
	s_nop 1
	v_mov_b32_dpp v105, v255 quad_perm:[0,1,2,3] row_mask:0x5 bank_mask:0xf
	v_mad_i64_i32 v[122:123], s[0:1], v126, s74, v[106:107]
	v_lshl_add_u64 v[244:245], v[122:123], 0, s[96:97]
	v_lshlrev_b64 v[122:123], 10, v[126:127]
	v_add_f32_e32 v103, v103, v105
	s_nop 1
	v_mov_b32_dpp v105, v103 row_ror:8 row_mask:0xf bank_mask:0xf
	v_lshl_add_u64 v[126:127], v[244:245], 0, v[96:97]
	v_lshl_add_u64 v[122:123], s[66:67], 0, v[122:123]
	v_lshl_add_u64 v[122:123], v[122:123], 0, v[96:97]
	v_add_f32_e32 v103, v103, v105
	s_nop 1
	v_mov_b32_dpp v105, v103 row_shl:4 row_mask:0xf bank_mask:0x5
	v_mov_b32_dpp v105, v103 row_shr:4 row_mask:0xf bank_mask:0xa
	s_nop 0
	v_add_f32_e32 v103, v103, v105
	s_nop 1
	v_mov_b32_dpp v105, v103 quad_perm:[2,3,0,1] row_mask:0xf bank_mask:0xf
	v_add_f32_e32 v103, v103, v105
	s_nop 1
	v_add_f32_dpp v103, v103, v103 quad_perm:[1,0,3,2] row_mask:0xf bank_mask:0xf
	v_fmamk_f32 v103, v103, 0x3c000000, v163
	v_cmp_gt_f32_e32 vcc, s86, v103
	v_mul_f32_e32 v105, 0x4b800000, v103
	s_nop 0
	v_cndmask_b32_e32 v103, v103, v105, vcc
	v_rsq_f32_e32 v103, v103
	s_nop 0
	v_mul_f32_e32 v105, 0x45800000, v103
	v_cndmask_b32_e32 v103, v103, v105, vcc
	global_load_ushort v105, v[126:127], off
	v_mul_f32_e32 v126, v242, v103
	global_load_dword v127, v[108:109], off
	v_mul_f32_e32 v124, v124, v103
	s_waitcnt vmcnt(1)
	v_lshlrev_b32_e32 v105, 16, v105
	v_mul_f32_e32 v105, 0xbfb8aa3b, v105
	v_exp_f32_e32 v105, v105
	s_waitcnt vmcnt(0)
	v_mul_f32_e32 v126, v127, v126
	v_add_f32_e32 v105, 1.0, v105
	v_rcp_f32_e32 v105, v105
	s_nop 0
	v_mul_f32_e32 v105, v105, v126
	v_cvt_pk_bf16_f32 v105, v105, s0
	v_lshl_add_u64 v[126:127], v[244:245], 0, v[112:113]
	global_store_short v[122:123], v105, off
	global_load_ushort v105, v[126:127], off
	v_mul_f32_e32 v126, v243, v103
	global_load_dword v127, v[110:111], off offset:128
	v_mul_f32_e32 v103, v125, v103
	s_waitcnt vmcnt(1)
	v_lshlrev_b32_e32 v105, 16, v105
	v_mul_f32_e32 v105, 0xbfb8aa3b, v105
	v_exp_f32_e32 v105, v105
	s_waitcnt vmcnt(0)
	v_mul_f32_e32 v126, v127, v126
	v_add_f32_e32 v105, 1.0, v105
	v_rcp_f32_e32 v105, v105
	s_nop 0
	v_mul_f32_e32 v105, v105, v126
	v_cvt_pk_bf16_f32 v105, v105, s0
	v_lshl_add_u64 v[126:127], v[244:245], 0, v[118:119]
	global_store_short v[122:123], v105, off offset:64
	global_load_ushort v105, v[126:127], off
	s_waitcnt vmcnt(0)
	v_lshlrev_b32_e32 v105, 16, v105
	global_load_dword v126, v[110:111], off offset:256
	v_mul_f32_e32 v105, 0xbfb8aa3b, v105
	v_exp_f32_e32 v105, v105
	s_waitcnt vmcnt(0)
	v_mul_f32_e32 v124, v126, v124
	v_add_f32_e32 v105, 1.0, v105
	v_rcp_f32_e32 v105, v105
	v_lshl_add_u64 v[126:127], v[244:245], 0, v[120:121]
	v_mul_f32_e32 v105, v124, v105
	v_cvt_pk_bf16_f32 v105, v105, s0
	global_store_short v[122:123], v105, off offset:128
	global_load_ushort v105, v[126:127], off
	s_waitcnt vmcnt(0)
	v_lshlrev_b32_e32 v105, 16, v105
	global_load_dword v124, v[110:111], off offset:384
	v_mul_f32_e32 v105, 0xbfb8aa3b, v105
	v_exp_f32_e32 v105, v105
	s_waitcnt vmcnt(0)
	v_mul_f32_e32 v103, v124, v103
	v_add_f32_e32 v105, 1.0, v105
	v_rcp_f32_e32 v105, v105
	s_nop 0
	v_mul_f32_e32 v103, v103, v105
	v_cvt_pk_bf16_f32 v103, v103, s0
	global_store_short v[122:123], v103, off offset:192
	ds_read_b32 v103, v238 offset:44
	ds_read_b32 v105, v239 offset:44
	v_add_u32_e32 v126, 11, v100
	v_ashrrev_i32_e32 v127, 31, v126
	v_mov_b32_e32 v244, v7
	s_waitcnt lgkmcnt(1)
	v_max_f32_e64 v103, |v103|, |v103|
	s_waitcnt lgkmcnt(0)
	v_max_f32_e32 v103, v103, v105
	v_div_scale_f32 v105, s[0:1], v103, v103, 1.0
	v_rcp_f32_e32 v122, v105
	v_mov_b32_e32 v245, v23
	v_fma_f32 v123, -v105, v122, 1.0
	v_fmac_f32_e32 v122, v123, v122
	v_div_scale_f32 v123, vcc, 1.0, v103, 1.0
	v_mul_f32_e32 v124, v123, v122
	v_fma_f32 v125, -v105, v124, v123
	v_fmac_f32_e32 v124, v125, v122
	v_fma_f32 v105, -v105, v124, v123
	v_div_fmas_f32 v105, v105, v122, v124
	v_lshlrev_b64 v[124:125], 11, v[126:127]
	v_lshl_add_u64 v[124:125], v[98:99], 0, v[124:125]
	global_load_dword v242, v[124:125], off
	global_load_dword v243, v[124:125], off offset:128
	global_load_dword v246, v[124:125], off offset:256
	global_load_dword v247, v[124:125], off offset:384
	v_div_fixup_f32 v122, v105, v103, 1.0
	v_mov_b32_e32 v124, v39
	v_mov_b32_e32 v125, v55
	s_waitcnt vmcnt(2)
	v_pk_fma_f32 v[242:243], v[244:245], v[122:123], v[242:243] op_sel_hi:[1,0,1]
	v_pk_mul_f32 v[244:245], v[242:243], v[242:243]
	s_waitcnt vmcnt(0)
	v_pk_fma_f32 v[124:125], v[124:125], v[122:123], v[246:247] op_sel_hi:[1,0,1]
	v_add_f32_e32 v103, v244, v245
	v_pk_mul_f32 v[122:123], v[124:125], v[124:125]
	v_add_f32_e32 v103, v103, v122
	v_add_f32_e32 v103, v103, v123
	v_mov_b32_e32 v105, v103
	v_mov_b32_e32 v255, v103
	s_nop 1
	v_permlane16_swap_b32_e32 v105, v255
	s_nop 1
	v_mov_b32_dpp v105, v255 quad_perm:[0,1,2,3] row_mask:0x5 bank_mask:0xf
	v_mad_i64_i32 v[122:123], s[0:1], v126, s74, v[106:107]
	v_lshl_add_u64 v[244:245], v[122:123], 0, s[96:97]
	v_lshlrev_b64 v[122:123], 10, v[126:127]
	v_add_f32_e32 v103, v103, v105
	s_nop 1
	v_mov_b32_dpp v105, v103 row_ror:8 row_mask:0xf bank_mask:0xf
	v_lshl_add_u64 v[126:127], v[244:245], 0, v[96:97]
	v_lshl_add_u64 v[122:123], s[66:67], 0, v[122:123]
	v_lshl_add_u64 v[122:123], v[122:123], 0, v[96:97]
	v_add_f32_e32 v103, v103, v105
	s_nop 1
	v_mov_b32_dpp v105, v103 row_shl:4 row_mask:0xf bank_mask:0x5
	v_mov_b32_dpp v105, v103 row_shr:4 row_mask:0xf bank_mask:0xa
	s_nop 0
	v_add_f32_e32 v103, v103, v105
	s_nop 1
	v_mov_b32_dpp v105, v103 quad_perm:[2,3,0,1] row_mask:0xf bank_mask:0xf
	v_add_f32_e32 v103, v103, v105
	s_nop 1
	v_add_f32_dpp v103, v103, v103 quad_perm:[1,0,3,2] row_mask:0xf bank_mask:0xf
	v_fmamk_f32 v103, v103, 0x3c000000, v163
	v_cmp_gt_f32_e32 vcc, s86, v103
	v_mul_f32_e32 v105, 0x4b800000, v103
	s_nop 0
	v_cndmask_b32_e32 v103, v103, v105, vcc
	v_rsq_f32_e32 v103, v103
	s_nop 0
	v_mul_f32_e32 v105, 0x45800000, v103
	v_cndmask_b32_e32 v103, v103, v105, vcc
	global_load_ushort v105, v[126:127], off
	v_mul_f32_e32 v126, v242, v103
	global_load_dword v127, v[108:109], off
	v_mul_f32_e32 v124, v124, v103
	s_waitcnt vmcnt(1)
	v_lshlrev_b32_e32 v105, 16, v105
	v_mul_f32_e32 v105, 0xbfb8aa3b, v105
	v_exp_f32_e32 v105, v105
	s_waitcnt vmcnt(0)
	v_mul_f32_e32 v126, v127, v126
	v_add_f32_e32 v105, 1.0, v105
	v_rcp_f32_e32 v105, v105
	s_nop 0
	v_mul_f32_e32 v105, v105, v126
	v_cvt_pk_bf16_f32 v105, v105, s0
	v_lshl_add_u64 v[126:127], v[244:245], 0, v[112:113]
	global_store_short v[122:123], v105, off
	global_load_ushort v105, v[126:127], off
	v_mul_f32_e32 v126, v243, v103
	global_load_dword v127, v[110:111], off offset:128
	v_mul_f32_e32 v103, v125, v103
	s_waitcnt vmcnt(1)
	v_lshlrev_b32_e32 v105, 16, v105
	v_mul_f32_e32 v105, 0xbfb8aa3b, v105
	v_exp_f32_e32 v105, v105
	s_waitcnt vmcnt(0)
	v_mul_f32_e32 v126, v127, v126
	v_add_f32_e32 v105, 1.0, v105
	v_rcp_f32_e32 v105, v105
	s_nop 0
	v_mul_f32_e32 v105, v105, v126
	v_cvt_pk_bf16_f32 v105, v105, s0
	v_lshl_add_u64 v[126:127], v[244:245], 0, v[118:119]
	global_store_short v[122:123], v105, off offset:64
	global_load_ushort v105, v[126:127], off
	s_waitcnt vmcnt(0)
	v_lshlrev_b32_e32 v105, 16, v105
	global_load_dword v126, v[110:111], off offset:256
	v_mul_f32_e32 v105, 0xbfb8aa3b, v105
	v_exp_f32_e32 v105, v105
	s_waitcnt vmcnt(0)
	v_mul_f32_e32 v124, v126, v124
	v_add_f32_e32 v105, 1.0, v105
	v_rcp_f32_e32 v105, v105
	v_lshl_add_u64 v[126:127], v[244:245], 0, v[120:121]
	v_mul_f32_e32 v105, v124, v105
	v_cvt_pk_bf16_f32 v105, v105, s0
	global_store_short v[122:123], v105, off offset:128
	global_load_ushort v105, v[126:127], off
	s_waitcnt vmcnt(0)
	v_lshlrev_b32_e32 v105, 16, v105
	global_load_dword v124, v[110:111], off offset:384
	v_mul_f32_e32 v105, 0xbfb8aa3b, v105
	v_exp_f32_e32 v105, v105
	s_waitcnt vmcnt(0)
	v_mul_f32_e32 v103, v124, v103
	v_add_f32_e32 v105, 1.0, v105
	v_rcp_f32_e32 v105, v105
	s_nop 0
	v_mul_f32_e32 v103, v103, v105
	v_cvt_pk_bf16_f32 v103, v103, s0
	global_store_short v[122:123], v103, off offset:192
	ds_read_b32 v103, v238 offset:64
	ds_read_b32 v105, v239 offset:64
	v_add_u32_e32 v126, 16, v100
	v_ashrrev_i32_e32 v127, 31, v126
	v_mov_b32_e32 v244, v8
	s_waitcnt lgkmcnt(1)
	v_max_f32_e64 v103, |v103|, |v103|
	s_waitcnt lgkmcnt(0)
	v_max_f32_e32 v103, v103, v105
	v_div_scale_f32 v105, s[0:1], v103, v103, 1.0
	v_rcp_f32_e32 v122, v105
	v_mov_b32_e32 v245, v24
	v_fma_f32 v123, -v105, v122, 1.0
	v_fmac_f32_e32 v122, v123, v122
	v_div_scale_f32 v123, vcc, 1.0, v103, 1.0
	v_mul_f32_e32 v124, v123, v122
	v_fma_f32 v125, -v105, v124, v123
	v_fmac_f32_e32 v124, v125, v122
	v_fma_f32 v105, -v105, v124, v123
	v_div_fmas_f32 v105, v105, v122, v124
	v_lshlrev_b64 v[124:125], 11, v[126:127]
	v_lshl_add_u64 v[124:125], v[98:99], 0, v[124:125]
	global_load_dword v242, v[124:125], off
	global_load_dword v243, v[124:125], off offset:128
	global_load_dword v246, v[124:125], off offset:256
	global_load_dword v247, v[124:125], off offset:384
	v_div_fixup_f32 v122, v105, v103, 1.0
	v_mov_b32_e32 v124, v40
	v_mov_b32_e32 v125, v56
	s_waitcnt vmcnt(2)
	v_pk_fma_f32 v[242:243], v[244:245], v[122:123], v[242:243] op_sel_hi:[1,0,1]
	v_pk_mul_f32 v[244:245], v[242:243], v[242:243]
	s_waitcnt vmcnt(0)
	v_pk_fma_f32 v[124:125], v[124:125], v[122:123], v[246:247] op_sel_hi:[1,0,1]
	v_add_f32_e32 v103, v244, v245
	v_pk_mul_f32 v[122:123], v[124:125], v[124:125]
	v_add_f32_e32 v103, v103, v122
	v_add_f32_e32 v103, v103, v123
	v_mov_b32_e32 v105, v103
	v_mov_b32_e32 v255, v103
	s_nop 1
	v_permlane16_swap_b32_e32 v105, v255
	s_nop 1
	v_mov_b32_dpp v105, v255 quad_perm:[0,1,2,3] row_mask:0x5 bank_mask:0xf
	v_mad_i64_i32 v[122:123], s[0:1], v126, s74, v[106:107]
	v_lshl_add_u64 v[244:245], v[122:123], 0, s[96:97]
	v_lshlrev_b64 v[122:123], 10, v[126:127]
	v_add_f32_e32 v103, v103, v105
	s_nop 1
	v_mov_b32_dpp v105, v103 row_ror:8 row_mask:0xf bank_mask:0xf
	v_lshl_add_u64 v[126:127], v[244:245], 0, v[96:97]
	v_lshl_add_u64 v[122:123], s[66:67], 0, v[122:123]
	v_lshl_add_u64 v[122:123], v[122:123], 0, v[96:97]
	v_add_f32_e32 v103, v103, v105
	s_nop 1
	v_mov_b32_dpp v105, v103 row_shl:4 row_mask:0xf bank_mask:0x5
	v_mov_b32_dpp v105, v103 row_shr:4 row_mask:0xf bank_mask:0xa
	s_nop 0
	v_add_f32_e32 v103, v103, v105
	s_nop 1
	v_mov_b32_dpp v105, v103 quad_perm:[2,3,0,1] row_mask:0xf bank_mask:0xf
	v_add_f32_e32 v103, v103, v105
	s_nop 1
	v_add_f32_dpp v103, v103, v103 quad_perm:[1,0,3,2] row_mask:0xf bank_mask:0xf
	v_fmamk_f32 v103, v103, 0x3c000000, v163
	v_cmp_gt_f32_e32 vcc, s86, v103
	v_mul_f32_e32 v105, 0x4b800000, v103
	s_nop 0
	v_cndmask_b32_e32 v103, v103, v105, vcc
	v_rsq_f32_e32 v103, v103
	s_nop 0
	v_mul_f32_e32 v105, 0x45800000, v103
	v_cndmask_b32_e32 v103, v103, v105, vcc
	global_load_ushort v105, v[126:127], off
	v_mul_f32_e32 v126, v242, v103
	global_load_dword v127, v[108:109], off
	v_mul_f32_e32 v124, v124, v103
	s_waitcnt vmcnt(1)
	v_lshlrev_b32_e32 v105, 16, v105
	v_mul_f32_e32 v105, 0xbfb8aa3b, v105
	v_exp_f32_e32 v105, v105
	s_waitcnt vmcnt(0)
	v_mul_f32_e32 v126, v127, v126
	v_add_f32_e32 v105, 1.0, v105
	v_rcp_f32_e32 v105, v105
	s_nop 0
	v_mul_f32_e32 v105, v105, v126
	v_cvt_pk_bf16_f32 v105, v105, s0
	v_lshl_add_u64 v[126:127], v[244:245], 0, v[112:113]
	global_store_short v[122:123], v105, off
	global_load_ushort v105, v[126:127], off
	v_mul_f32_e32 v126, v243, v103
	global_load_dword v127, v[110:111], off offset:128
	v_mul_f32_e32 v103, v125, v103
	s_waitcnt vmcnt(1)
	v_lshlrev_b32_e32 v105, 16, v105
	v_mul_f32_e32 v105, 0xbfb8aa3b, v105
	v_exp_f32_e32 v105, v105
	s_waitcnt vmcnt(0)
	v_mul_f32_e32 v126, v127, v126
	v_add_f32_e32 v105, 1.0, v105
	v_rcp_f32_e32 v105, v105
	s_nop 0
	v_mul_f32_e32 v105, v105, v126
	v_cvt_pk_bf16_f32 v105, v105, s0
	v_lshl_add_u64 v[126:127], v[244:245], 0, v[118:119]
	global_store_short v[122:123], v105, off offset:64
	global_load_ushort v105, v[126:127], off
	s_waitcnt vmcnt(0)
	v_lshlrev_b32_e32 v105, 16, v105
	global_load_dword v126, v[110:111], off offset:256
	v_mul_f32_e32 v105, 0xbfb8aa3b, v105
	v_exp_f32_e32 v105, v105
	s_waitcnt vmcnt(0)
	v_mul_f32_e32 v124, v126, v124
	v_add_f32_e32 v105, 1.0, v105
	v_rcp_f32_e32 v105, v105
	v_lshl_add_u64 v[126:127], v[244:245], 0, v[120:121]
	v_mul_f32_e32 v105, v124, v105
	v_cvt_pk_bf16_f32 v105, v105, s0
	global_store_short v[122:123], v105, off offset:128
	global_load_ushort v105, v[126:127], off
	s_waitcnt vmcnt(0)
	v_lshlrev_b32_e32 v105, 16, v105
	global_load_dword v124, v[110:111], off offset:384
	v_mul_f32_e32 v105, 0xbfb8aa3b, v105
	v_exp_f32_e32 v105, v105
	s_waitcnt vmcnt(0)
	v_mul_f32_e32 v103, v124, v103
	v_add_f32_e32 v105, 1.0, v105
	v_rcp_f32_e32 v105, v105
	s_nop 0
	v_mul_f32_e32 v103, v103, v105
	v_cvt_pk_bf16_f32 v103, v103, s0
	global_store_short v[122:123], v103, off offset:192
	ds_read_b32 v103, v238 offset:68
	ds_read_b32 v105, v239 offset:68
	v_add_u32_e32 v126, 17, v100
	v_ashrrev_i32_e32 v127, 31, v126
	v_mov_b32_e32 v244, v9
	s_waitcnt lgkmcnt(1)
	v_max_f32_e64 v103, |v103|, |v103|
	s_waitcnt lgkmcnt(0)
	v_max_f32_e32 v103, v103, v105
	v_div_scale_f32 v105, s[0:1], v103, v103, 1.0
	v_rcp_f32_e32 v122, v105
	v_mov_b32_e32 v245, v25
	v_fma_f32 v123, -v105, v122, 1.0
	v_fmac_f32_e32 v122, v123, v122
	v_div_scale_f32 v123, vcc, 1.0, v103, 1.0
	v_mul_f32_e32 v124, v123, v122
	v_fma_f32 v125, -v105, v124, v123
	v_fmac_f32_e32 v124, v125, v122
	v_fma_f32 v105, -v105, v124, v123
	v_div_fmas_f32 v105, v105, v122, v124
	v_lshlrev_b64 v[124:125], 11, v[126:127]
	v_lshl_add_u64 v[124:125], v[98:99], 0, v[124:125]
	global_load_dword v242, v[124:125], off
	global_load_dword v243, v[124:125], off offset:128
	global_load_dword v246, v[124:125], off offset:256
	global_load_dword v247, v[124:125], off offset:384
	v_div_fixup_f32 v122, v105, v103, 1.0
	v_mov_b32_e32 v124, v41
	v_mov_b32_e32 v125, v57
	s_waitcnt vmcnt(2)
	v_pk_fma_f32 v[242:243], v[244:245], v[122:123], v[242:243] op_sel_hi:[1,0,1]
	v_pk_mul_f32 v[244:245], v[242:243], v[242:243]
	s_waitcnt vmcnt(0)
	v_pk_fma_f32 v[124:125], v[124:125], v[122:123], v[246:247] op_sel_hi:[1,0,1]
	v_add_f32_e32 v103, v244, v245
	v_pk_mul_f32 v[122:123], v[124:125], v[124:125]
	v_add_f32_e32 v103, v103, v122
	v_add_f32_e32 v103, v103, v123
	v_mov_b32_e32 v105, v103
	v_mov_b32_e32 v255, v103
	s_nop 1
	v_permlane16_swap_b32_e32 v105, v255
	s_nop 1
	v_mov_b32_dpp v105, v255 quad_perm:[0,1,2,3] row_mask:0x5 bank_mask:0xf
	v_mad_i64_i32 v[122:123], s[0:1], v126, s74, v[106:107]
	v_lshl_add_u64 v[244:245], v[122:123], 0, s[96:97]
	v_lshlrev_b64 v[122:123], 10, v[126:127]
	v_add_f32_e32 v103, v103, v105
	s_nop 1
	v_mov_b32_dpp v105, v103 row_ror:8 row_mask:0xf bank_mask:0xf
	v_lshl_add_u64 v[126:127], v[244:245], 0, v[96:97]
	v_lshl_add_u64 v[122:123], s[66:67], 0, v[122:123]
	v_lshl_add_u64 v[122:123], v[122:123], 0, v[96:97]
	v_add_f32_e32 v103, v103, v105
	s_nop 1
	v_mov_b32_dpp v105, v103 row_shl:4 row_mask:0xf bank_mask:0x5
	v_mov_b32_dpp v105, v103 row_shr:4 row_mask:0xf bank_mask:0xa
	s_nop 0
	v_add_f32_e32 v103, v103, v105
	s_nop 1
	v_mov_b32_dpp v105, v103 quad_perm:[2,3,0,1] row_mask:0xf bank_mask:0xf
	v_add_f32_e32 v103, v103, v105
	s_nop 1
	v_add_f32_dpp v103, v103, v103 quad_perm:[1,0,3,2] row_mask:0xf bank_mask:0xf
	v_fmamk_f32 v103, v103, 0x3c000000, v163
	v_cmp_gt_f32_e32 vcc, s86, v103
	v_mul_f32_e32 v105, 0x4b800000, v103
	s_nop 0
	v_cndmask_b32_e32 v103, v103, v105, vcc
	v_rsq_f32_e32 v103, v103
	s_nop 0
	v_mul_f32_e32 v105, 0x45800000, v103
	v_cndmask_b32_e32 v103, v103, v105, vcc
	global_load_ushort v105, v[126:127], off
	v_mul_f32_e32 v126, v242, v103
	global_load_dword v127, v[108:109], off
	v_mul_f32_e32 v124, v124, v103
	s_waitcnt vmcnt(1)
	v_lshlrev_b32_e32 v105, 16, v105
	v_mul_f32_e32 v105, 0xbfb8aa3b, v105
	v_exp_f32_e32 v105, v105
	s_waitcnt vmcnt(0)
	v_mul_f32_e32 v126, v127, v126
	v_add_f32_e32 v105, 1.0, v105
	v_rcp_f32_e32 v105, v105
	s_nop 0
	v_mul_f32_e32 v105, v105, v126
	v_cvt_pk_bf16_f32 v105, v105, s0
	v_lshl_add_u64 v[126:127], v[244:245], 0, v[112:113]
	global_store_short v[122:123], v105, off
	global_load_ushort v105, v[126:127], off
	v_mul_f32_e32 v126, v243, v103
	global_load_dword v127, v[110:111], off offset:128
	v_mul_f32_e32 v103, v125, v103
	s_waitcnt vmcnt(1)
	v_lshlrev_b32_e32 v105, 16, v105
	v_mul_f32_e32 v105, 0xbfb8aa3b, v105
	v_exp_f32_e32 v105, v105
	s_waitcnt vmcnt(0)
	v_mul_f32_e32 v126, v127, v126
	v_add_f32_e32 v105, 1.0, v105
	v_rcp_f32_e32 v105, v105
	s_nop 0
	v_mul_f32_e32 v105, v105, v126
	v_cvt_pk_bf16_f32 v105, v105, s0
	v_lshl_add_u64 v[126:127], v[244:245], 0, v[118:119]
	global_store_short v[122:123], v105, off offset:64
	global_load_ushort v105, v[126:127], off
	s_waitcnt vmcnt(0)
	v_lshlrev_b32_e32 v105, 16, v105
	global_load_dword v126, v[110:111], off offset:256
	v_mul_f32_e32 v105, 0xbfb8aa3b, v105
	v_exp_f32_e32 v105, v105
	s_waitcnt vmcnt(0)
	v_mul_f32_e32 v124, v126, v124
	v_add_f32_e32 v105, 1.0, v105
	v_rcp_f32_e32 v105, v105
	v_lshl_add_u64 v[126:127], v[244:245], 0, v[120:121]
	v_mul_f32_e32 v105, v124, v105
	v_cvt_pk_bf16_f32 v105, v105, s0
	global_store_short v[122:123], v105, off offset:128
	global_load_ushort v105, v[126:127], off
	s_waitcnt vmcnt(0)
	v_lshlrev_b32_e32 v105, 16, v105
	global_load_dword v124, v[110:111], off offset:384
	v_mul_f32_e32 v105, 0xbfb8aa3b, v105
	v_exp_f32_e32 v105, v105
	s_waitcnt vmcnt(0)
	v_mul_f32_e32 v103, v124, v103
	v_add_f32_e32 v105, 1.0, v105
	v_rcp_f32_e32 v105, v105
	s_nop 0
	v_mul_f32_e32 v103, v103, v105
	v_cvt_pk_bf16_f32 v103, v103, s0
	global_store_short v[122:123], v103, off offset:192
	ds_read_b32 v103, v238 offset:72
	ds_read_b32 v105, v239 offset:72
	v_add_u32_e32 v126, 18, v100
	v_ashrrev_i32_e32 v127, 31, v126
	v_mov_b32_e32 v244, v10
	s_waitcnt lgkmcnt(1)
	v_max_f32_e64 v103, |v103|, |v103|
	s_waitcnt lgkmcnt(0)
	v_max_f32_e32 v103, v103, v105
	v_div_scale_f32 v105, s[0:1], v103, v103, 1.0
	v_rcp_f32_e32 v122, v105
	v_mov_b32_e32 v245, v26
	v_fma_f32 v123, -v105, v122, 1.0
	v_fmac_f32_e32 v122, v123, v122
	v_div_scale_f32 v123, vcc, 1.0, v103, 1.0
	v_mul_f32_e32 v124, v123, v122
	v_fma_f32 v125, -v105, v124, v123
	v_fmac_f32_e32 v124, v125, v122
	v_fma_f32 v105, -v105, v124, v123
	v_div_fmas_f32 v105, v105, v122, v124
	v_lshlrev_b64 v[124:125], 11, v[126:127]
	v_lshl_add_u64 v[124:125], v[98:99], 0, v[124:125]
	global_load_dword v242, v[124:125], off
	global_load_dword v243, v[124:125], off offset:128
	global_load_dword v246, v[124:125], off offset:256
	global_load_dword v247, v[124:125], off offset:384
	v_div_fixup_f32 v122, v105, v103, 1.0
	v_mov_b32_e32 v124, v42
	v_mov_b32_e32 v125, v58
	s_waitcnt vmcnt(2)
	v_pk_fma_f32 v[242:243], v[244:245], v[122:123], v[242:243] op_sel_hi:[1,0,1]
	v_pk_mul_f32 v[244:245], v[242:243], v[242:243]
	s_waitcnt vmcnt(0)
	v_pk_fma_f32 v[124:125], v[124:125], v[122:123], v[246:247] op_sel_hi:[1,0,1]
	v_add_f32_e32 v103, v244, v245
	v_pk_mul_f32 v[122:123], v[124:125], v[124:125]
	v_add_f32_e32 v103, v103, v122
	v_add_f32_e32 v103, v103, v123
	v_mov_b32_e32 v105, v103
	v_mov_b32_e32 v255, v103
	s_nop 1
	v_permlane16_swap_b32_e32 v105, v255
	s_nop 1
	v_mov_b32_dpp v105, v255 quad_perm:[0,1,2,3] row_mask:0x5 bank_mask:0xf
	v_mad_i64_i32 v[122:123], s[0:1], v126, s74, v[106:107]
	v_lshl_add_u64 v[244:245], v[122:123], 0, s[96:97]
	v_lshlrev_b64 v[122:123], 10, v[126:127]
	v_add_f32_e32 v103, v103, v105
	s_nop 1
	v_mov_b32_dpp v105, v103 row_ror:8 row_mask:0xf bank_mask:0xf
	v_lshl_add_u64 v[126:127], v[244:245], 0, v[96:97]
	v_lshl_add_u64 v[122:123], s[66:67], 0, v[122:123]
	v_lshl_add_u64 v[122:123], v[122:123], 0, v[96:97]
	v_add_f32_e32 v103, v103, v105
	s_nop 1
	v_mov_b32_dpp v105, v103 row_shl:4 row_mask:0xf bank_mask:0x5
	v_mov_b32_dpp v105, v103 row_shr:4 row_mask:0xf bank_mask:0xa
	s_nop 0
	v_add_f32_e32 v103, v103, v105
	s_nop 1
	v_mov_b32_dpp v105, v103 quad_perm:[2,3,0,1] row_mask:0xf bank_mask:0xf
	v_add_f32_e32 v103, v103, v105
	s_nop 1
	v_add_f32_dpp v103, v103, v103 quad_perm:[1,0,3,2] row_mask:0xf bank_mask:0xf
	v_fmamk_f32 v103, v103, 0x3c000000, v163
	v_cmp_gt_f32_e32 vcc, s86, v103
	v_mul_f32_e32 v105, 0x4b800000, v103
	s_nop 0
	v_cndmask_b32_e32 v103, v103, v105, vcc
	v_rsq_f32_e32 v103, v103
	s_nop 0
	v_mul_f32_e32 v105, 0x45800000, v103
	v_cndmask_b32_e32 v103, v103, v105, vcc
	global_load_ushort v105, v[126:127], off
	v_mul_f32_e32 v126, v242, v103
	global_load_dword v127, v[108:109], off
	v_mul_f32_e32 v124, v124, v103
	s_waitcnt vmcnt(1)
	v_lshlrev_b32_e32 v105, 16, v105
	v_mul_f32_e32 v105, 0xbfb8aa3b, v105
	v_exp_f32_e32 v105, v105
	s_waitcnt vmcnt(0)
	v_mul_f32_e32 v126, v127, v126
	v_add_f32_e32 v105, 1.0, v105
	v_rcp_f32_e32 v105, v105
	s_nop 0
	v_mul_f32_e32 v105, v105, v126
	v_cvt_pk_bf16_f32 v105, v105, s0
	v_lshl_add_u64 v[126:127], v[244:245], 0, v[112:113]
	global_store_short v[122:123], v105, off
	global_load_ushort v105, v[126:127], off
	v_mul_f32_e32 v126, v243, v103
	global_load_dword v127, v[110:111], off offset:128
	v_mul_f32_e32 v103, v125, v103
	s_waitcnt vmcnt(1)
	v_lshlrev_b32_e32 v105, 16, v105
	v_mul_f32_e32 v105, 0xbfb8aa3b, v105
	v_exp_f32_e32 v105, v105
	s_waitcnt vmcnt(0)
	v_mul_f32_e32 v126, v127, v126
	v_add_f32_e32 v105, 1.0, v105
	v_rcp_f32_e32 v105, v105
	s_nop 0
	v_mul_f32_e32 v105, v105, v126
	v_cvt_pk_bf16_f32 v105, v105, s0
	v_lshl_add_u64 v[126:127], v[244:245], 0, v[118:119]
	global_store_short v[122:123], v105, off offset:64
	global_load_ushort v105, v[126:127], off
	s_waitcnt vmcnt(0)
	v_lshlrev_b32_e32 v105, 16, v105
	global_load_dword v126, v[110:111], off offset:256
	v_mul_f32_e32 v105, 0xbfb8aa3b, v105
	v_exp_f32_e32 v105, v105
	s_waitcnt vmcnt(0)
	v_mul_f32_e32 v124, v126, v124
	v_add_f32_e32 v105, 1.0, v105
	v_rcp_f32_e32 v105, v105
	v_lshl_add_u64 v[126:127], v[244:245], 0, v[120:121]
	v_mul_f32_e32 v105, v124, v105
	v_cvt_pk_bf16_f32 v105, v105, s0
	global_store_short v[122:123], v105, off offset:128
	global_load_ushort v105, v[126:127], off
	s_waitcnt vmcnt(0)
	v_lshlrev_b32_e32 v105, 16, v105
	global_load_dword v124, v[110:111], off offset:384
	v_mul_f32_e32 v105, 0xbfb8aa3b, v105
	v_exp_f32_e32 v105, v105
	s_waitcnt vmcnt(0)
	v_mul_f32_e32 v103, v124, v103
	v_add_f32_e32 v105, 1.0, v105
	v_rcp_f32_e32 v105, v105
	s_nop 0
	v_mul_f32_e32 v103, v103, v105
	v_cvt_pk_bf16_f32 v103, v103, s0
	global_store_short v[122:123], v103, off offset:192
	ds_read_b32 v103, v238 offset:76
	ds_read_b32 v105, v239 offset:76
	v_add_u32_e32 v126, 19, v100
	v_ashrrev_i32_e32 v127, 31, v126
	v_mov_b32_e32 v244, v11
	s_waitcnt lgkmcnt(1)
	v_max_f32_e64 v103, |v103|, |v103|
	s_waitcnt lgkmcnt(0)
	v_max_f32_e32 v103, v103, v105
	v_div_scale_f32 v105, s[0:1], v103, v103, 1.0
	v_rcp_f32_e32 v122, v105
	v_mov_b32_e32 v245, v27
	v_fma_f32 v123, -v105, v122, 1.0
	v_fmac_f32_e32 v122, v123, v122
	v_div_scale_f32 v123, vcc, 1.0, v103, 1.0
	v_mul_f32_e32 v124, v123, v122
	v_fma_f32 v125, -v105, v124, v123
	v_fmac_f32_e32 v124, v125, v122
	v_fma_f32 v105, -v105, v124, v123
	v_div_fmas_f32 v105, v105, v122, v124
	v_lshlrev_b64 v[124:125], 11, v[126:127]
	v_lshl_add_u64 v[124:125], v[98:99], 0, v[124:125]
	global_load_dword v242, v[124:125], off
	global_load_dword v243, v[124:125], off offset:128
	global_load_dword v246, v[124:125], off offset:256
	global_load_dword v247, v[124:125], off offset:384
	v_div_fixup_f32 v122, v105, v103, 1.0
	v_mov_b32_e32 v124, v43
	v_mov_b32_e32 v125, v59
	s_waitcnt vmcnt(2)
	v_pk_fma_f32 v[242:243], v[244:245], v[122:123], v[242:243] op_sel_hi:[1,0,1]
	v_pk_mul_f32 v[244:245], v[242:243], v[242:243]
	s_waitcnt vmcnt(0)
	v_pk_fma_f32 v[124:125], v[124:125], v[122:123], v[246:247] op_sel_hi:[1,0,1]
	v_add_f32_e32 v103, v244, v245
	v_pk_mul_f32 v[122:123], v[124:125], v[124:125]
	v_add_f32_e32 v103, v103, v122
	v_add_f32_e32 v103, v103, v123
	v_mov_b32_e32 v105, v103
	v_mov_b32_e32 v255, v103
	s_nop 1
	v_permlane16_swap_b32_e32 v105, v255
	s_nop 1
	v_mov_b32_dpp v105, v255 quad_perm:[0,1,2,3] row_mask:0x5 bank_mask:0xf
	v_mad_i64_i32 v[122:123], s[0:1], v126, s74, v[106:107]
	v_lshl_add_u64 v[244:245], v[122:123], 0, s[96:97]
	v_lshlrev_b64 v[122:123], 10, v[126:127]
	v_add_f32_e32 v103, v103, v105
	s_nop 1
	v_mov_b32_dpp v105, v103 row_ror:8 row_mask:0xf bank_mask:0xf
	v_lshl_add_u64 v[126:127], v[244:245], 0, v[96:97]
	v_lshl_add_u64 v[122:123], s[66:67], 0, v[122:123]
	v_lshl_add_u64 v[122:123], v[122:123], 0, v[96:97]
	v_add_f32_e32 v103, v103, v105
	s_nop 1
	v_mov_b32_dpp v105, v103 row_shl:4 row_mask:0xf bank_mask:0x5
	v_mov_b32_dpp v105, v103 row_shr:4 row_mask:0xf bank_mask:0xa
	s_nop 0
	v_add_f32_e32 v103, v103, v105
	s_nop 1
	v_mov_b32_dpp v105, v103 quad_perm:[2,3,0,1] row_mask:0xf bank_mask:0xf
	v_add_f32_e32 v103, v103, v105
	s_nop 1
	v_add_f32_dpp v103, v103, v103 quad_perm:[1,0,3,2] row_mask:0xf bank_mask:0xf
	v_fmamk_f32 v103, v103, 0x3c000000, v163
	v_cmp_gt_f32_e32 vcc, s86, v103
	v_mul_f32_e32 v105, 0x4b800000, v103
	s_nop 0
	v_cndmask_b32_e32 v103, v103, v105, vcc
	v_rsq_f32_e32 v103, v103
	s_nop 0
	v_mul_f32_e32 v105, 0x45800000, v103
	v_cndmask_b32_e32 v103, v103, v105, vcc
	global_load_ushort v105, v[126:127], off
	v_mul_f32_e32 v126, v242, v103
	global_load_dword v127, v[108:109], off
	v_mul_f32_e32 v124, v124, v103
	s_waitcnt vmcnt(1)
	v_lshlrev_b32_e32 v105, 16, v105
	v_mul_f32_e32 v105, 0xbfb8aa3b, v105
	v_exp_f32_e32 v105, v105
	s_waitcnt vmcnt(0)
	v_mul_f32_e32 v126, v127, v126
	v_add_f32_e32 v105, 1.0, v105
	v_rcp_f32_e32 v105, v105
	s_nop 0
	v_mul_f32_e32 v105, v105, v126
	v_cvt_pk_bf16_f32 v105, v105, s0
	v_lshl_add_u64 v[126:127], v[244:245], 0, v[112:113]
	global_store_short v[122:123], v105, off
	global_load_ushort v105, v[126:127], off
	v_mul_f32_e32 v126, v243, v103
	global_load_dword v127, v[110:111], off offset:128
	v_mul_f32_e32 v103, v125, v103
	s_waitcnt vmcnt(1)
	v_lshlrev_b32_e32 v105, 16, v105
	v_mul_f32_e32 v105, 0xbfb8aa3b, v105
	v_exp_f32_e32 v105, v105
	s_waitcnt vmcnt(0)
	v_mul_f32_e32 v126, v127, v126
	v_add_f32_e32 v105, 1.0, v105
	v_rcp_f32_e32 v105, v105
	s_nop 0
	v_mul_f32_e32 v105, v105, v126
	v_cvt_pk_bf16_f32 v105, v105, s0
	v_lshl_add_u64 v[126:127], v[244:245], 0, v[118:119]
	global_store_short v[122:123], v105, off offset:64
	global_load_ushort v105, v[126:127], off
	s_waitcnt vmcnt(0)
	v_lshlrev_b32_e32 v105, 16, v105
	global_load_dword v126, v[110:111], off offset:256
	v_mul_f32_e32 v105, 0xbfb8aa3b, v105
	v_exp_f32_e32 v105, v105
	s_waitcnt vmcnt(0)
	v_mul_f32_e32 v124, v126, v124
	v_add_f32_e32 v105, 1.0, v105
	v_rcp_f32_e32 v105, v105
	v_lshl_add_u64 v[126:127], v[244:245], 0, v[120:121]
	v_mul_f32_e32 v105, v124, v105
	v_cvt_pk_bf16_f32 v105, v105, s0
	global_store_short v[122:123], v105, off offset:128
	global_load_ushort v105, v[126:127], off
	s_waitcnt vmcnt(0)
	v_lshlrev_b32_e32 v105, 16, v105
	global_load_dword v124, v[110:111], off offset:384
	v_mul_f32_e32 v105, 0xbfb8aa3b, v105
	v_exp_f32_e32 v105, v105
	s_waitcnt vmcnt(0)
	v_mul_f32_e32 v103, v124, v103
	v_add_f32_e32 v105, 1.0, v105
	v_rcp_f32_e32 v105, v105
	s_nop 0
	v_mul_f32_e32 v103, v103, v105
	v_cvt_pk_bf16_f32 v103, v103, s0
	global_store_short v[122:123], v103, off offset:192
	ds_read_b32 v103, v238 offset:96
	ds_read_b32 v105, v239 offset:96
	v_add_u32_e32 v126, 24, v100
	v_ashrrev_i32_e32 v127, 31, v126
	v_mov_b32_e32 v244, v12
	s_waitcnt lgkmcnt(1)
	v_max_f32_e64 v103, |v103|, |v103|
	s_waitcnt lgkmcnt(0)
	v_max_f32_e32 v103, v103, v105
	v_div_scale_f32 v105, s[0:1], v103, v103, 1.0
	v_rcp_f32_e32 v122, v105
	v_mov_b32_e32 v245, v28
	v_fma_f32 v123, -v105, v122, 1.0
	v_fmac_f32_e32 v122, v123, v122
	v_div_scale_f32 v123, vcc, 1.0, v103, 1.0
	v_mul_f32_e32 v124, v123, v122
	v_fma_f32 v125, -v105, v124, v123
	v_fmac_f32_e32 v124, v125, v122
	v_fma_f32 v105, -v105, v124, v123
	v_div_fmas_f32 v105, v105, v122, v124
	v_lshlrev_b64 v[124:125], 11, v[126:127]
	v_lshl_add_u64 v[124:125], v[98:99], 0, v[124:125]
	global_load_dword v242, v[124:125], off
	global_load_dword v243, v[124:125], off offset:128
	global_load_dword v246, v[124:125], off offset:256
	global_load_dword v247, v[124:125], off offset:384
	v_div_fixup_f32 v122, v105, v103, 1.0
	v_mov_b32_e32 v124, v44
	v_mov_b32_e32 v125, v60
	s_waitcnt vmcnt(2)
	v_pk_fma_f32 v[242:243], v[244:245], v[122:123], v[242:243] op_sel_hi:[1,0,1]
	v_pk_mul_f32 v[244:245], v[242:243], v[242:243]
	s_waitcnt vmcnt(0)
	v_pk_fma_f32 v[124:125], v[124:125], v[122:123], v[246:247] op_sel_hi:[1,0,1]
	v_add_f32_e32 v103, v244, v245
	v_pk_mul_f32 v[122:123], v[124:125], v[124:125]
	v_add_f32_e32 v103, v103, v122
	v_add_f32_e32 v103, v103, v123
	v_mov_b32_e32 v105, v103
	v_mov_b32_e32 v255, v103
	s_nop 1
	v_permlane16_swap_b32_e32 v105, v255
	s_nop 1
	v_mov_b32_dpp v105, v255 quad_perm:[0,1,2,3] row_mask:0x5 bank_mask:0xf
	v_mad_i64_i32 v[122:123], s[0:1], v126, s74, v[106:107]
	v_lshl_add_u64 v[244:245], v[122:123], 0, s[96:97]
	v_lshlrev_b64 v[122:123], 10, v[126:127]
	v_add_f32_e32 v103, v103, v105
	s_nop 1
	v_mov_b32_dpp v105, v103 row_ror:8 row_mask:0xf bank_mask:0xf
	v_lshl_add_u64 v[126:127], v[244:245], 0, v[96:97]
	v_lshl_add_u64 v[122:123], s[66:67], 0, v[122:123]
	v_lshl_add_u64 v[122:123], v[122:123], 0, v[96:97]
	v_add_f32_e32 v103, v103, v105
	s_nop 1
	v_mov_b32_dpp v105, v103 row_shl:4 row_mask:0xf bank_mask:0x5
	v_mov_b32_dpp v105, v103 row_shr:4 row_mask:0xf bank_mask:0xa
	s_nop 0
	v_add_f32_e32 v103, v103, v105
	s_nop 1
	v_mov_b32_dpp v105, v103 quad_perm:[2,3,0,1] row_mask:0xf bank_mask:0xf
	v_add_f32_e32 v103, v103, v105
	s_nop 1
	v_add_f32_dpp v103, v103, v103 quad_perm:[1,0,3,2] row_mask:0xf bank_mask:0xf
	v_fmamk_f32 v103, v103, 0x3c000000, v163
	v_cmp_gt_f32_e32 vcc, s86, v103
	v_mul_f32_e32 v105, 0x4b800000, v103
	s_nop 0
	v_cndmask_b32_e32 v103, v103, v105, vcc
	v_rsq_f32_e32 v103, v103
	s_nop 0
	v_mul_f32_e32 v105, 0x45800000, v103
	v_cndmask_b32_e32 v103, v103, v105, vcc
	global_load_ushort v105, v[126:127], off
	v_mul_f32_e32 v126, v242, v103
	global_load_dword v127, v[108:109], off
	v_mul_f32_e32 v124, v124, v103
	s_waitcnt vmcnt(1)
	v_lshlrev_b32_e32 v105, 16, v105
	v_mul_f32_e32 v105, 0xbfb8aa3b, v105
	v_exp_f32_e32 v105, v105
	s_waitcnt vmcnt(0)
	v_mul_f32_e32 v126, v127, v126
	v_add_f32_e32 v105, 1.0, v105
	v_rcp_f32_e32 v105, v105
	s_nop 0
	v_mul_f32_e32 v105, v105, v126
	v_cvt_pk_bf16_f32 v105, v105, s0
	v_lshl_add_u64 v[126:127], v[244:245], 0, v[112:113]
	global_store_short v[122:123], v105, off
	global_load_ushort v105, v[126:127], off
	v_mul_f32_e32 v126, v243, v103
	global_load_dword v127, v[110:111], off offset:128
	v_mul_f32_e32 v103, v125, v103
	s_waitcnt vmcnt(1)
	v_lshlrev_b32_e32 v105, 16, v105
	v_mul_f32_e32 v105, 0xbfb8aa3b, v105
	v_exp_f32_e32 v105, v105
	s_waitcnt vmcnt(0)
	v_mul_f32_e32 v126, v127, v126
	v_add_f32_e32 v105, 1.0, v105
	v_rcp_f32_e32 v105, v105
	s_nop 0
	v_mul_f32_e32 v105, v105, v126
	v_cvt_pk_bf16_f32 v105, v105, s0
	v_lshl_add_u64 v[126:127], v[244:245], 0, v[118:119]
	global_store_short v[122:123], v105, off offset:64
	global_load_ushort v105, v[126:127], off
	s_waitcnt vmcnt(0)
	v_lshlrev_b32_e32 v105, 16, v105
	global_load_dword v126, v[110:111], off offset:256
	v_mul_f32_e32 v105, 0xbfb8aa3b, v105
	v_exp_f32_e32 v105, v105
	s_waitcnt vmcnt(0)
	v_mul_f32_e32 v124, v126, v124
	v_add_f32_e32 v105, 1.0, v105
	v_rcp_f32_e32 v105, v105
	v_lshl_add_u64 v[126:127], v[244:245], 0, v[120:121]
	v_mul_f32_e32 v105, v124, v105
	v_cvt_pk_bf16_f32 v105, v105, s0
	global_store_short v[122:123], v105, off offset:128
	global_load_ushort v105, v[126:127], off
	s_waitcnt vmcnt(0)
	v_lshlrev_b32_e32 v105, 16, v105
	global_load_dword v124, v[110:111], off offset:384
	v_mul_f32_e32 v105, 0xbfb8aa3b, v105
	v_exp_f32_e32 v105, v105
	s_waitcnt vmcnt(0)
	v_mul_f32_e32 v103, v124, v103
	v_add_f32_e32 v105, 1.0, v105
	v_rcp_f32_e32 v105, v105
	s_nop 0
	v_mul_f32_e32 v103, v103, v105
	v_cvt_pk_bf16_f32 v103, v103, s0
	global_store_short v[122:123], v103, off offset:192
	ds_read_b32 v103, v238 offset:100
	ds_read_b32 v105, v239 offset:100
	v_add_u32_e32 v126, 25, v100
	v_ashrrev_i32_e32 v127, 31, v126
	v_mov_b32_e32 v244, v13
	s_waitcnt lgkmcnt(1)
	v_max_f32_e64 v103, |v103|, |v103|
	s_waitcnt lgkmcnt(0)
	v_max_f32_e32 v103, v103, v105
	v_div_scale_f32 v105, s[0:1], v103, v103, 1.0
	v_rcp_f32_e32 v122, v105
	v_mov_b32_e32 v245, v29
	v_fma_f32 v123, -v105, v122, 1.0
	v_fmac_f32_e32 v122, v123, v122
	v_div_scale_f32 v123, vcc, 1.0, v103, 1.0
	v_mul_f32_e32 v124, v123, v122
	v_fma_f32 v125, -v105, v124, v123
	v_fmac_f32_e32 v124, v125, v122
	v_fma_f32 v105, -v105, v124, v123
	v_div_fmas_f32 v105, v105, v122, v124
	v_lshlrev_b64 v[124:125], 11, v[126:127]
	v_lshl_add_u64 v[124:125], v[98:99], 0, v[124:125]
	global_load_dword v242, v[124:125], off
	global_load_dword v243, v[124:125], off offset:128
	global_load_dword v246, v[124:125], off offset:256
	global_load_dword v247, v[124:125], off offset:384
	v_div_fixup_f32 v122, v105, v103, 1.0
	v_mov_b32_e32 v124, v45
	v_mov_b32_e32 v125, v61
	s_waitcnt vmcnt(2)
	v_pk_fma_f32 v[242:243], v[244:245], v[122:123], v[242:243] op_sel_hi:[1,0,1]
	v_pk_mul_f32 v[244:245], v[242:243], v[242:243]
	s_waitcnt vmcnt(0)
	v_pk_fma_f32 v[124:125], v[124:125], v[122:123], v[246:247] op_sel_hi:[1,0,1]
	v_add_f32_e32 v103, v244, v245
	v_pk_mul_f32 v[122:123], v[124:125], v[124:125]
	v_add_f32_e32 v103, v103, v122
	v_add_f32_e32 v103, v103, v123
	v_mov_b32_e32 v105, v103
	v_mov_b32_e32 v255, v103
	s_nop 1
	v_permlane16_swap_b32_e32 v105, v255
	s_nop 1
	v_mov_b32_dpp v105, v255 quad_perm:[0,1,2,3] row_mask:0x5 bank_mask:0xf
	v_mad_i64_i32 v[122:123], s[0:1], v126, s74, v[106:107]
	v_lshl_add_u64 v[244:245], v[122:123], 0, s[96:97]
	v_lshlrev_b64 v[122:123], 10, v[126:127]
	v_add_f32_e32 v103, v103, v105
	s_nop 1
	v_mov_b32_dpp v105, v103 row_ror:8 row_mask:0xf bank_mask:0xf
	v_lshl_add_u64 v[126:127], v[244:245], 0, v[96:97]
	v_lshl_add_u64 v[122:123], s[66:67], 0, v[122:123]
	v_lshl_add_u64 v[122:123], v[122:123], 0, v[96:97]
	v_add_f32_e32 v103, v103, v105
	s_nop 1
	v_mov_b32_dpp v105, v103 row_shl:4 row_mask:0xf bank_mask:0x5
	v_mov_b32_dpp v105, v103 row_shr:4 row_mask:0xf bank_mask:0xa
	s_nop 0
	v_add_f32_e32 v103, v103, v105
	s_nop 1
	v_mov_b32_dpp v105, v103 quad_perm:[2,3,0,1] row_mask:0xf bank_mask:0xf
	v_add_f32_e32 v103, v103, v105
	s_nop 1
	v_add_f32_dpp v103, v103, v103 quad_perm:[1,0,3,2] row_mask:0xf bank_mask:0xf
	v_fmamk_f32 v103, v103, 0x3c000000, v163
	v_cmp_gt_f32_e32 vcc, s86, v103
	v_mul_f32_e32 v105, 0x4b800000, v103
	s_nop 0
	v_cndmask_b32_e32 v103, v103, v105, vcc
	v_rsq_f32_e32 v103, v103
	s_nop 0
	v_mul_f32_e32 v105, 0x45800000, v103
	v_cndmask_b32_e32 v103, v103, v105, vcc
	global_load_ushort v105, v[126:127], off
	v_mul_f32_e32 v126, v242, v103
	global_load_dword v127, v[108:109], off
	v_mul_f32_e32 v124, v124, v103
	s_waitcnt vmcnt(1)
	v_lshlrev_b32_e32 v105, 16, v105
	v_mul_f32_e32 v105, 0xbfb8aa3b, v105
	v_exp_f32_e32 v105, v105
	s_waitcnt vmcnt(0)
	v_mul_f32_e32 v126, v127, v126
	v_add_f32_e32 v105, 1.0, v105
	v_rcp_f32_e32 v105, v105
	s_nop 0
	v_mul_f32_e32 v105, v105, v126
	v_cvt_pk_bf16_f32 v105, v105, s0
	v_lshl_add_u64 v[126:127], v[244:245], 0, v[112:113]
	global_store_short v[122:123], v105, off
	global_load_ushort v105, v[126:127], off
	v_mul_f32_e32 v126, v243, v103
	global_load_dword v127, v[110:111], off offset:128
	v_mul_f32_e32 v103, v125, v103
	s_waitcnt vmcnt(1)
	v_lshlrev_b32_e32 v105, 16, v105
	v_mul_f32_e32 v105, 0xbfb8aa3b, v105
	v_exp_f32_e32 v105, v105
	s_waitcnt vmcnt(0)
	v_mul_f32_e32 v126, v127, v126
	v_add_f32_e32 v105, 1.0, v105
	v_rcp_f32_e32 v105, v105
	s_nop 0
	v_mul_f32_e32 v105, v105, v126
	v_cvt_pk_bf16_f32 v105, v105, s0
	v_lshl_add_u64 v[126:127], v[244:245], 0, v[118:119]
	global_store_short v[122:123], v105, off offset:64
	global_load_ushort v105, v[126:127], off
	s_waitcnt vmcnt(0)
	v_lshlrev_b32_e32 v105, 16, v105
	global_load_dword v126, v[110:111], off offset:256
	v_mul_f32_e32 v105, 0xbfb8aa3b, v105
	v_exp_f32_e32 v105, v105
	s_waitcnt vmcnt(0)
	v_mul_f32_e32 v124, v126, v124
	v_add_f32_e32 v105, 1.0, v105
	v_rcp_f32_e32 v105, v105
	v_lshl_add_u64 v[126:127], v[244:245], 0, v[120:121]
	v_mul_f32_e32 v105, v124, v105
	v_cvt_pk_bf16_f32 v105, v105, s0
	global_store_short v[122:123], v105, off offset:128
	global_load_ushort v105, v[126:127], off
	s_waitcnt vmcnt(0)
	v_lshlrev_b32_e32 v105, 16, v105
	global_load_dword v124, v[110:111], off offset:384
	v_mul_f32_e32 v105, 0xbfb8aa3b, v105
	v_exp_f32_e32 v105, v105
	s_waitcnt vmcnt(0)
	v_mul_f32_e32 v103, v124, v103
	v_add_f32_e32 v105, 1.0, v105
	v_rcp_f32_e32 v105, v105
	s_nop 0
	v_mul_f32_e32 v103, v103, v105
	v_cvt_pk_bf16_f32 v103, v103, s0
	global_store_short v[122:123], v103, off offset:192
	ds_read_b32 v103, v238 offset:104
	ds_read_b32 v105, v239 offset:104
	v_add_u32_e32 v126, 26, v100
	v_ashrrev_i32_e32 v127, 31, v126
	v_mov_b32_e32 v244, v14
	s_waitcnt lgkmcnt(1)
	v_max_f32_e64 v103, |v103|, |v103|
	s_waitcnt lgkmcnt(0)
	v_max_f32_e32 v103, v103, v105
	v_div_scale_f32 v105, s[0:1], v103, v103, 1.0
	v_rcp_f32_e32 v122, v105
	v_mov_b32_e32 v245, v30
	v_fma_f32 v123, -v105, v122, 1.0
	v_fmac_f32_e32 v122, v123, v122
	v_div_scale_f32 v123, vcc, 1.0, v103, 1.0
	v_mul_f32_e32 v124, v123, v122
	v_fma_f32 v125, -v105, v124, v123
	v_fmac_f32_e32 v124, v125, v122
	v_fma_f32 v105, -v105, v124, v123
	v_div_fmas_f32 v105, v105, v122, v124
	v_lshlrev_b64 v[124:125], 11, v[126:127]
	v_lshl_add_u64 v[124:125], v[98:99], 0, v[124:125]
	global_load_dword v242, v[124:125], off
	global_load_dword v243, v[124:125], off offset:128
	global_load_dword v246, v[124:125], off offset:256
	global_load_dword v247, v[124:125], off offset:384
	v_div_fixup_f32 v122, v105, v103, 1.0
	v_mov_b32_e32 v124, v46
	v_mov_b32_e32 v125, v62
	s_waitcnt vmcnt(2)
	v_pk_fma_f32 v[242:243], v[244:245], v[122:123], v[242:243] op_sel_hi:[1,0,1]
	v_pk_mul_f32 v[244:245], v[242:243], v[242:243]
	s_waitcnt vmcnt(0)
	v_pk_fma_f32 v[124:125], v[124:125], v[122:123], v[246:247] op_sel_hi:[1,0,1]
	v_add_f32_e32 v103, v244, v245
	v_pk_mul_f32 v[122:123], v[124:125], v[124:125]
	v_add_f32_e32 v103, v103, v122
	v_add_f32_e32 v103, v103, v123
	v_mov_b32_e32 v105, v103
	v_mov_b32_e32 v255, v103
	s_nop 1
	v_permlane16_swap_b32_e32 v105, v255
	s_nop 1
	v_mov_b32_dpp v105, v255 quad_perm:[0,1,2,3] row_mask:0x5 bank_mask:0xf
	v_mad_i64_i32 v[122:123], s[0:1], v126, s74, v[106:107]
	v_lshl_add_u64 v[244:245], v[122:123], 0, s[96:97]
	v_lshlrev_b64 v[122:123], 10, v[126:127]
	v_add_f32_e32 v103, v103, v105
	s_nop 1
	v_mov_b32_dpp v105, v103 row_ror:8 row_mask:0xf bank_mask:0xf
	v_lshl_add_u64 v[126:127], v[244:245], 0, v[96:97]
	v_lshl_add_u64 v[122:123], s[66:67], 0, v[122:123]
	v_lshl_add_u64 v[122:123], v[122:123], 0, v[96:97]
	v_add_f32_e32 v103, v103, v105
	s_nop 1
	v_mov_b32_dpp v105, v103 row_shl:4 row_mask:0xf bank_mask:0x5
	v_mov_b32_dpp v105, v103 row_shr:4 row_mask:0xf bank_mask:0xa
	s_nop 0
	v_add_f32_e32 v103, v103, v105
	s_nop 1
	v_mov_b32_dpp v105, v103 quad_perm:[2,3,0,1] row_mask:0xf bank_mask:0xf
	v_add_f32_e32 v103, v103, v105
	s_nop 1
	v_add_f32_dpp v103, v103, v103 quad_perm:[1,0,3,2] row_mask:0xf bank_mask:0xf
	v_fmamk_f32 v103, v103, 0x3c000000, v163
	v_cmp_gt_f32_e32 vcc, s86, v103
	v_mul_f32_e32 v105, 0x4b800000, v103
	s_nop 0
	v_cndmask_b32_e32 v103, v103, v105, vcc
	v_rsq_f32_e32 v103, v103
	s_nop 0
	v_mul_f32_e32 v105, 0x45800000, v103
	v_cndmask_b32_e32 v103, v103, v105, vcc
	global_load_ushort v105, v[126:127], off
	v_mul_f32_e32 v126, v242, v103
	global_load_dword v127, v[108:109], off
	v_mul_f32_e32 v124, v124, v103
	s_waitcnt vmcnt(1)
	v_lshlrev_b32_e32 v105, 16, v105
	v_mul_f32_e32 v105, 0xbfb8aa3b, v105
	v_exp_f32_e32 v105, v105
	s_waitcnt vmcnt(0)
	v_mul_f32_e32 v126, v127, v126
	v_add_f32_e32 v105, 1.0, v105
	v_rcp_f32_e32 v105, v105
	s_nop 0
	v_mul_f32_e32 v105, v105, v126
	v_cvt_pk_bf16_f32 v105, v105, s0
	v_lshl_add_u64 v[126:127], v[244:245], 0, v[112:113]
	global_store_short v[122:123], v105, off
	global_load_ushort v105, v[126:127], off
	v_mul_f32_e32 v126, v243, v103
	global_load_dword v127, v[110:111], off offset:128
	v_mul_f32_e32 v103, v125, v103
	s_waitcnt vmcnt(1)
	v_lshlrev_b32_e32 v105, 16, v105
	v_mul_f32_e32 v105, 0xbfb8aa3b, v105
	v_exp_f32_e32 v105, v105
	s_waitcnt vmcnt(0)
	v_mul_f32_e32 v126, v127, v126
	v_add_f32_e32 v105, 1.0, v105
	v_rcp_f32_e32 v105, v105
	s_nop 0
	v_mul_f32_e32 v105, v105, v126
	v_cvt_pk_bf16_f32 v105, v105, s0
	v_lshl_add_u64 v[126:127], v[244:245], 0, v[118:119]
	global_store_short v[122:123], v105, off offset:64
	global_load_ushort v105, v[126:127], off
	s_waitcnt vmcnt(0)
	v_lshlrev_b32_e32 v105, 16, v105
	global_load_dword v126, v[110:111], off offset:256
	v_mul_f32_e32 v105, 0xbfb8aa3b, v105
	v_exp_f32_e32 v105, v105
	s_waitcnt vmcnt(0)
	v_mul_f32_e32 v124, v126, v124
	v_add_f32_e32 v105, 1.0, v105
	v_rcp_f32_e32 v105, v105
	v_lshl_add_u64 v[126:127], v[244:245], 0, v[120:121]
	v_mul_f32_e32 v105, v124, v105
	v_cvt_pk_bf16_f32 v105, v105, s0
	global_store_short v[122:123], v105, off offset:128
	global_load_ushort v105, v[126:127], off
	s_waitcnt vmcnt(0)
	v_lshlrev_b32_e32 v105, 16, v105
	global_load_dword v124, v[110:111], off offset:384
	v_mul_f32_e32 v105, 0xbfb8aa3b, v105
	v_exp_f32_e32 v105, v105
	s_waitcnt vmcnt(0)
	v_mul_f32_e32 v103, v124, v103
	v_add_f32_e32 v105, 1.0, v105
	v_rcp_f32_e32 v105, v105
	s_nop 0
	v_mul_f32_e32 v103, v103, v105
	v_cvt_pk_bf16_f32 v103, v103, s0
	global_store_short v[122:123], v103, off offset:192
	v_add_u32_e32 v122, 27, v100
	v_ashrrev_i32_e32 v123, 31, v122
	v_lshlrev_b64 v[124:125], 11, v[122:123]
	v_lshl_add_u64 v[124:125], v[98:99], 0, v[124:125]
	global_load_dword v126, v[124:125], off
	global_load_dword v127, v[124:125], off offset:128
	global_load_dword v242, v[124:125], off offset:256
	global_load_dword v243, v[124:125], off offset:384
	v_mad_i64_i32 v[106:107], s[0:1], v122, s74, v[106:107]
	v_lshl_add_u64 v[106:107], v[106:107], 0, s[96:97]
	v_lshl_add_u64 v[124:125], v[106:107], 0, v[96:97]
	global_load_ushort v103, v[124:125], off
	v_lshl_add_u64 v[112:113], v[106:107], 0, v[112:113]
	v_lshl_add_u64 v[118:119], v[106:107], 0, v[118:119]
	v_lshl_add_u64 v[106:107], v[106:107], 0, v[120:121]
	global_load_ushort v105, v[112:113], off
	global_load_ushort v118, v[118:119], off
	global_load_ushort v119, v[106:107], off
	global_load_dword v120, v[108:109], off
	global_load_dword v121, v[110:111], off offset:128
	global_load_dword v124, v[110:111], off offset:256
	global_load_dword v125, v[110:111], off offset:384
	ds_read_b32 v109, v239 offset:108
	ds_read_b32 v110, v238 offset:108
	v_mov_b32_e32 v106, v15
	v_mov_b32_e32 v107, v31
	v_mov_b32_e32 v108, v47
	s_waitcnt lgkmcnt(1)
	s_waitcnt lgkmcnt(0)
	v_max_f32_e64 v110, |v110|, |v110|
	v_max_f32_e32 v110, v110, v109
	v_div_scale_f32 v111, s[0:1], v110, v110, 1.0
	v_rcp_f32_e32 v112, v111
	v_div_scale_f32 v113, vcc, 1.0, v110, 1.0
	v_mov_b32_e32 v109, v63
	v_fma_f32 v238, -v111, v112, 1.0
	v_fmac_f32_e32 v112, v238, v112
	v_mul_f32_e32 v238, v113, v112
	v_fma_f32 v239, -v111, v238, v113
	v_fmac_f32_e32 v238, v239, v112
	v_fma_f32 v111, -v111, v238, v113
	v_div_fmas_f32 v111, v111, v112, v238
	v_div_fixup_f32 v110, v111, v110, 1.0
	s_waitcnt vmcnt(10)
	v_pk_fma_f32 v[106:107], v[106:107], v[110:111], v[126:127] op_sel_hi:[1,0,1]
	s_waitcnt vmcnt(8)
	v_pk_fma_f32 v[108:109], v[108:109], v[110:111], v[242:243] op_sel_hi:[1,0,1]
	v_pk_mul_f32 v[110:111], v[106:107], v[106:107]
	v_pk_mul_f32 v[112:113], v[108:109], v[108:109]
	v_add_f32_e32 v110, v110, v111
	v_add_f32_e32 v110, v110, v112
	v_add_f32_e32 v112, v110, v113
	v_mov_b32_e32 v113, v112
	v_mov_b32_e32 v255, v112
	s_nop 1
	v_permlane16_swap_b32_e32 v113, v255
	v_lshlrev_b64 v[110:111], 10, v[122:123]
	v_lshl_add_u64 v[110:111], s[66:67], 0, v[110:111]
	v_lshl_add_u64 v[110:111], v[110:111], 0, v[96:97]
	s_waitcnt vmcnt(7)
	v_lshlrev_b32_e32 v96, 16, v103
	v_add_f32_e32 v103, v113, v255
	s_nop 1
	v_mov_b32_dpp v112, v103 row_ror:8 row_mask:0xf bank_mask:0xf
	s_waitcnt vmcnt(5)
	v_lshlrev_b32_e32 v113, 16, v118
	s_waitcnt vmcnt(4)
	v_lshlrev_b32_e32 v118, 16, v119
	v_lshlrev_b32_e32 v105, 16, v105
	v_mul_f32_e32 v96, 0xbfb8aa3b, v96
	v_add_f32_e32 v103, v103, v112
	s_nop 1
	v_mov_b32_dpp v112, v103 row_shl:4 row_mask:0xf bank_mask:0x5
	v_mov_b32_dpp v112, v103 row_shr:4 row_mask:0xf bank_mask:0xa
	v_mul_f32_e32 v113, 0xbfb8aa3b, v113
	v_mul_f32_e32 v118, 0xbfb8aa3b, v118
	v_mul_f32_e32 v105, 0xbfb8aa3b, v105
	v_exp_f32_e32 v96, v96
	v_add_f32_e32 v103, v103, v112
	s_nop 1
	v_mov_b32_dpp v112, v103 quad_perm:[2,3,0,1] row_mask:0xf bank_mask:0xf
	v_exp_f32_e32 v113, v113
	v_exp_f32_e32 v118, v118
	v_exp_f32_e32 v105, v105
	v_add_f32_e32 v96, 1.0, v96
	v_add_f32_e32 v103, v103, v112
	v_add_f32_e32 v113, 1.0, v113
	v_add_f32_e32 v118, 1.0, v118
	v_add_f32_e32 v105, 1.0, v105
	v_rcp_f32_e32 v96, v96
	v_add_f32_dpp v103, v103, v103 quad_perm:[1,0,3,2] row_mask:0xf bank_mask:0xf
	v_fmamk_f32 v103, v103, 0x3c000000, v163
	v_mul_f32_e32 v112, 0x4b800000, v103
	v_cmp_gt_f32_e32 vcc, s86, v103
	v_rcp_f32_e32 v105, v105
	s_nop 0
	v_cndmask_b32_e32 v103, v103, v112, vcc
	v_rsq_f32_e32 v103, v103
	v_rcp_f32_e32 v112, v113
	v_rcp_f32_e32 v113, v118
	v_mul_f32_e32 v118, 0x45800000, v103
	v_cndmask_b32_e32 v103, v103, v118, vcc
	v_mul_f32_e32 v106, v106, v103
	v_mul_f32_e32 v107, v107, v103
	v_mul_f32_e32 v108, v108, v103
	v_mul_f32_e32 v103, v109, v103
	s_waitcnt vmcnt(3)
	v_mul_f32_e32 v106, v120, v106
	s_waitcnt vmcnt(2)
	v_mul_f32_e32 v107, v121, v107
	s_waitcnt vmcnt(1)
	v_mul_f32_e32 v108, v124, v108
	s_waitcnt vmcnt(0)
	v_mul_f32_e32 v103, v125, v103
	v_mul_f32_e32 v96, v96, v106
	v_mul_f32_e32 v105, v105, v107
	v_mul_f32_e32 v106, v108, v112
	v_mul_f32_e32 v103, v103, v113
	v_cvt_pk_bf16_f32 v96, v96, s0
	v_cvt_pk_bf16_f32 v105, v105, s0
	v_cvt_pk_bf16_f32 v106, v106, s0
	v_cvt_pk_bf16_f32 v103, v103, s0
	global_store_short v[110:111], v96, off
	global_store_short v[110:111], v105, off offset:64
	global_store_short v[110:111], v106, off offset:128
	global_store_short v[110:111], v103, off offset:192
	s_cbranch_execnz .LBB0_927
	s_branch .LBB0_1111

.LBB0_1111:
	s_add_i32 s6, 0, 0x12200
	s_add_i32 s4, 0, 0x11e00
	v_add_u32_e32 v106, s6, v237
	v_add_u32_e32 v96, s4, v237
	ds_read_b32 v103, v106
	ds_read_b32 v105, v96
	s_waitcnt lgkmcnt(1)
	s_waitcnt lgkmcnt(0)
	v_max_f32_e64 v105, |v105|, |v105|
	v_max_f32_e32 v103, v105, v103
	v_div_scale_f32 v105, s[0:1], v103, v103, 1.0
	v_rcp_f32_e32 v107, v105
	v_div_scale_f32 v108, vcc, 1.0, v103, 1.0
	v_fma_f32 v109, -v105, v107, 1.0
	v_fmac_f32_e32 v107, v109, v107
	v_mul_f32_e32 v109, v108, v107
	v_fma_f32 v110, -v105, v109, v108
	v_fmac_f32_e32 v109, v110, v107
	v_fma_f32 v105, -v105, v109, v108
	v_div_fmas_f32 v105, v105, v107, v109
	v_div_fixup_f32 v103, v105, v103, 1.0
	v_lshlrev_b64 v[108:109], 11, v[100:101]
	v_lshl_add_u64 v[108:109], v[98:99], 0, v[108:109]
	v_mul_f32_e32 v0, v0, v103
	global_store_dword v[108:109], v0, off
	v_mul_f32_e32 v0, v16, v103
	global_store_dword v[108:109], v0, off offset:128
	v_mul_f32_e32 v0, v32, v103
	global_store_dword v[108:109], v0, off offset:256
	v_mul_f32_e32 v0, v48, v103
	global_store_dword v[108:109], v0, off offset:384
	v_add_u32_e32 v0, s4, v236
	v_add_u32_e32 v16, s6, v236
	ds_read_b32 v16, v16
	ds_read_b32 v0, v0
	v_ashrrev_i32_e32 v105, 31, v104
	v_lshlrev_b64 v[104:105], 11, v[104:105]
	v_lshl_add_u64 v[104:105], v[98:99], 0, v[104:105]
	s_waitcnt lgkmcnt(1)
	s_waitcnt lgkmcnt(0)
	v_max_f32_e64 v0, |v0|, |v0|
	v_max_f32_e32 v0, v0, v16
	v_div_scale_f32 v16, s[0:1], v0, v0, 1.0
	v_rcp_f32_e32 v32, v16
	v_div_scale_f32 v48, vcc, 1.0, v0, 1.0
	v_fma_f32 v101, -v16, v32, 1.0
	v_fmac_f32_e32 v32, v101, v32
	v_mul_f32_e32 v101, v48, v32
	v_fma_f32 v103, -v16, v101, v48
	v_fmac_f32_e32 v101, v103, v32
	v_fma_f32 v16, -v16, v101, v48
	v_div_fmas_f32 v16, v16, v32, v101
	v_div_fixup_f32 v0, v16, v0, 1.0
	v_mul_f32_e32 v1, v1, v0
	global_store_dword v[104:105], v1, off
	v_mul_f32_e32 v1, v17, v0
	global_store_dword v[104:105], v1, off offset:128
	v_mul_f32_e32 v1, v33, v0
	v_mul_f32_e32 v0, v49, v0
	global_store_dword v[104:105], v1, off offset:256
	global_store_dword v[104:105], v0, off offset:384
	v_add_u32_e32 v0, s4, v235
	v_add_u32_e32 v1, s6, v235
	ds_read_b32 v1, v1
	ds_read_b32 v0, v0
	v_ashrrev_i32_e32 v103, 31, v102
	s_waitcnt lgkmcnt(1)
	s_waitcnt lgkmcnt(0)
	v_max_f32_e64 v0, |v0|, |v0|
	v_max_f32_e32 v0, v0, v1
	v_div_scale_f32 v1, s[0:1], v0, v0, 1.0
	v_rcp_f32_e32 v16, v1
	v_div_scale_f32 v17, vcc, 1.0, v0, 1.0
	v_fma_f32 v32, -v1, v16, 1.0
	v_fmac_f32_e32 v16, v32, v16
	v_mul_f32_e32 v32, v17, v16
	v_fma_f32 v33, -v1, v32, v17
	v_fmac_f32_e32 v32, v33, v16
	v_fma_f32 v1, -v1, v32, v17
	v_div_fmas_f32 v1, v1, v16, v32
	v_div_fixup_f32 v16, v1, v0, 1.0
	v_lshlrev_b64 v[0:1], 11, v[102:103]
	v_lshl_add_u64 v[0:1], v[98:99], 0, v[0:1]
	v_mul_f32_e32 v2, v2, v16
	global_store_dword v[0:1], v2, off
	v_mul_f32_e32 v2, v18, v16
	global_store_dword v[0:1], v2, off offset:128
	v_mul_f32_e32 v2, v34, v16
	global_store_dword v[0:1], v2, off offset:256
	v_mul_f32_e32 v2, v50, v16
	global_store_dword v[0:1], v2, off offset:384
	v_lshlrev_b32_e32 v0, 2, v234
	v_add_u32_e32 v1, s4, v0
	v_add_u32_e32 v0, s6, v0
	ds_read_b32 v0, v0
	ds_read_b32 v1, v1
	s_waitcnt lgkmcnt(1)
	s_waitcnt lgkmcnt(0)
	v_max_f32_e64 v1, |v1|, |v1|
	v_max_f32_e32 v0, v1, v0
	v_div_scale_f32 v1, s[0:1], v0, v0, 1.0
	v_rcp_f32_e32 v2, v1
	v_div_scale_f32 v16, vcc, 1.0, v0, 1.0
	v_fma_f32 v17, -v1, v2, 1.0
	v_fmac_f32_e32 v2, v17, v2
	v_mul_f32_e32 v17, v16, v2
	v_fma_f32 v18, -v1, v17, v16
	v_fmac_f32_e32 v17, v18, v2
	v_fma_f32 v1, -v1, v17, v16
	v_div_fmas_f32 v1, v1, v2, v17
	v_div_fixup_f32 v2, v1, v0, 1.0
	v_add_u32_e32 v0, s61, v234
	v_ashrrev_i32_e32 v1, 31, v0
	v_lshlrev_b64 v[0:1], 11, v[0:1]
	v_lshl_add_u64 v[0:1], v[98:99], 0, v[0:1]
	v_mul_f32_e32 v3, v3, v2
	global_store_dword v[0:1], v3, off
	v_mul_f32_e32 v3, v19, v2
	global_store_dword v[0:1], v3, off offset:128
	v_mul_f32_e32 v3, v35, v2
	v_mul_f32_e32 v2, v51, v2
	global_store_dword v[0:1], v3, off offset:256
	global_store_dword v[0:1], v2, off offset:384
	ds_read_b32 v0, v96 offset:32
	ds_read_b32 v1, v106 offset:32
	s_waitcnt lgkmcnt(1)
	v_max_f32_e64 v0, |v0|, |v0|
	s_waitcnt lgkmcnt(0)
	v_max_f32_e32 v0, v0, v1
	v_div_scale_f32 v1, s[0:1], v0, v0, 1.0
	v_rcp_f32_e32 v2, v1
	s_nop 0
	v_fma_f32 v3, -v1, v2, 1.0
	v_fmac_f32_e32 v2, v3, v2
	v_div_scale_f32 v3, vcc, 1.0, v0, 1.0
	v_mul_f32_e32 v16, v3, v2
	v_fma_f32 v17, -v1, v16, v3
	v_fmac_f32_e32 v16, v17, v2
	v_fma_f32 v1, -v1, v16, v3
	v_div_fmas_f32 v1, v1, v2, v16
	v_div_fixup_f32 v2, v1, v0, 1.0
	v_add_u32_e32 v0, 8, v100
	v_ashrrev_i32_e32 v1, 31, v0
	v_lshlrev_b64 v[0:1], 11, v[0:1]
	v_lshl_add_u64 v[0:1], v[98:99], 0, v[0:1]
	v_mul_f32_e32 v3, v4, v2
	global_store_dword v[0:1], v3, off
	v_mul_f32_e32 v3, v20, v2
	global_store_dword v[0:1], v3, off offset:128
	v_mul_f32_e32 v3, v36, v2
	v_mul_f32_e32 v2, v52, v2
	global_store_dword v[0:1], v3, off offset:256
	global_store_dword v[0:1], v2, off offset:384
	ds_read_b32 v0, v96 offset:36
	ds_read_b32 v1, v106 offset:36
	s_waitcnt lgkmcnt(1)
	v_max_f32_e64 v0, |v0|, |v0|
	s_waitcnt lgkmcnt(0)
	v_max_f32_e32 v0, v0, v1
	v_div_scale_f32 v1, s[0:1], v0, v0, 1.0
	v_rcp_f32_e32 v2, v1
	s_nop 0
	v_fma_f32 v3, -v1, v2, 1.0
	v_fmac_f32_e32 v2, v3, v2
	v_div_scale_f32 v3, vcc, 1.0, v0, 1.0
	v_mul_f32_e32 v4, v3, v2
	v_fma_f32 v16, -v1, v4, v3
	v_fmac_f32_e32 v4, v16, v2
	v_fma_f32 v1, -v1, v4, v3
	v_div_fmas_f32 v1, v1, v2, v4
	v_div_fixup_f32 v2, v1, v0, 1.0
	v_add_u32_e32 v0, 9, v100
	v_ashrrev_i32_e32 v1, 31, v0
	v_lshlrev_b64 v[0:1], 11, v[0:1]
	v_lshl_add_u64 v[0:1], v[98:99], 0, v[0:1]
	v_mul_f32_e32 v3, v5, v2
	global_store_dword v[0:1], v3, off
	v_mul_f32_e32 v3, v21, v2
	global_store_dword v[0:1], v3, off offset:128
	v_mul_f32_e32 v3, v37, v2
	v_mul_f32_e32 v2, v53, v2
	global_store_dword v[0:1], v3, off offset:256
	global_store_dword v[0:1], v2, off offset:384
	ds_read_b32 v0, v96 offset:40
	ds_read_b32 v1, v106 offset:40
	s_waitcnt lgkmcnt(1)
	v_max_f32_e64 v0, |v0|, |v0|
	s_waitcnt lgkmcnt(0)
	v_max_f32_e32 v0, v0, v1
	v_div_scale_f32 v1, s[0:1], v0, v0, 1.0
	v_rcp_f32_e32 v2, v1
	s_nop 0
	v_fma_f32 v3, -v1, v2, 1.0
	v_fmac_f32_e32 v2, v3, v2
	v_div_scale_f32 v3, vcc, 1.0, v0, 1.0
	v_mul_f32_e32 v4, v3, v2
	v_fma_f32 v5, -v1, v4, v3
	v_fmac_f32_e32 v4, v5, v2
	v_fma_f32 v1, -v1, v4, v3
	v_div_fmas_f32 v1, v1, v2, v4
	v_div_fixup_f32 v2, v1, v0, 1.0
	v_add_u32_e32 v0, 10, v100
	v_ashrrev_i32_e32 v1, 31, v0
	v_lshlrev_b64 v[0:1], 11, v[0:1]
	v_lshl_add_u64 v[0:1], v[98:99], 0, v[0:1]
	v_mul_f32_e32 v3, v6, v2
	global_store_dword v[0:1], v3, off
	v_mul_f32_e32 v3, v22, v2
	global_store_dword v[0:1], v3, off offset:128
	v_mul_f32_e32 v3, v38, v2
	v_mul_f32_e32 v2, v54, v2
	global_store_dword v[0:1], v3, off offset:256
	global_store_dword v[0:1], v2, off offset:384
	ds_read_b32 v0, v96 offset:44
	ds_read_b32 v1, v106 offset:44
	s_waitcnt lgkmcnt(1)
	v_max_f32_e64 v0, |v0|, |v0|
	s_waitcnt lgkmcnt(0)
	v_max_f32_e32 v0, v0, v1
	v_div_scale_f32 v1, s[0:1], v0, v0, 1.0
	v_rcp_f32_e32 v2, v1
	s_nop 0
	v_fma_f32 v3, -v1, v2, 1.0
	v_fmac_f32_e32 v2, v3, v2
	v_div_scale_f32 v3, vcc, 1.0, v0, 1.0
	v_mul_f32_e32 v4, v3, v2
	v_fma_f32 v5, -v1, v4, v3
	v_fmac_f32_e32 v4, v5, v2
	v_fma_f32 v1, -v1, v4, v3
	v_div_fmas_f32 v1, v1, v2, v4
	v_div_fixup_f32 v2, v1, v0, 1.0
	v_add_u32_e32 v0, 11, v100
	v_ashrrev_i32_e32 v1, 31, v0
	v_lshlrev_b64 v[0:1], 11, v[0:1]
	v_lshl_add_u64 v[0:1], v[98:99], 0, v[0:1]
	v_mul_f32_e32 v3, v7, v2
	global_store_dword v[0:1], v3, off
	v_mul_f32_e32 v3, v23, v2
	global_store_dword v[0:1], v3, off offset:128
	v_mul_f32_e32 v3, v39, v2
	v_mul_f32_e32 v2, v55, v2
	global_store_dword v[0:1], v3, off offset:256
	global_store_dword v[0:1], v2, off offset:384
	ds_read_b32 v0, v96 offset:64
	ds_read_b32 v1, v106 offset:64
	s_waitcnt lgkmcnt(1)
	v_max_f32_e64 v0, |v0|, |v0|
	s_waitcnt lgkmcnt(0)
	v_max_f32_e32 v0, v0, v1
	v_div_scale_f32 v1, s[0:1], v0, v0, 1.0
	v_rcp_f32_e32 v2, v1
	s_nop 0
	v_fma_f32 v3, -v1, v2, 1.0
	v_fmac_f32_e32 v2, v3, v2
	v_div_scale_f32 v3, vcc, 1.0, v0, 1.0
	v_mul_f32_e32 v4, v3, v2
	v_fma_f32 v5, -v1, v4, v3
	v_fmac_f32_e32 v4, v5, v2
	v_fma_f32 v1, -v1, v4, v3
	v_div_fmas_f32 v1, v1, v2, v4
	v_div_fixup_f32 v2, v1, v0, 1.0
	v_add_u32_e32 v0, 16, v100
	v_ashrrev_i32_e32 v1, 31, v0
	v_lshlrev_b64 v[0:1], 11, v[0:1]
	v_lshl_add_u64 v[0:1], v[98:99], 0, v[0:1]
	v_mul_f32_e32 v3, v8, v2
	global_store_dword v[0:1], v3, off
	v_mul_f32_e32 v3, v24, v2
	global_store_dword v[0:1], v3, off offset:128
	v_mul_f32_e32 v3, v40, v2
	v_mul_f32_e32 v2, v56, v2
	global_store_dword v[0:1], v3, off offset:256
	global_store_dword v[0:1], v2, off offset:384
	ds_read_b32 v0, v96 offset:68
	ds_read_b32 v1, v106 offset:68
	s_waitcnt lgkmcnt(1)
	v_max_f32_e64 v0, |v0|, |v0|
	s_waitcnt lgkmcnt(0)
	v_max_f32_e32 v0, v0, v1
	v_div_scale_f32 v1, s[0:1], v0, v0, 1.0
	v_rcp_f32_e32 v2, v1
	s_nop 0
	v_fma_f32 v3, -v1, v2, 1.0
	v_fmac_f32_e32 v2, v3, v2
	v_div_scale_f32 v3, vcc, 1.0, v0, 1.0
	v_mul_f32_e32 v4, v3, v2
	v_fma_f32 v5, -v1, v4, v3
	v_fmac_f32_e32 v4, v5, v2
	v_fma_f32 v1, -v1, v4, v3
	v_div_fmas_f32 v1, v1, v2, v4
	v_div_fixup_f32 v2, v1, v0, 1.0
	v_add_u32_e32 v0, 17, v100
	v_ashrrev_i32_e32 v1, 31, v0
	v_lshlrev_b64 v[0:1], 11, v[0:1]
	v_lshl_add_u64 v[0:1], v[98:99], 0, v[0:1]
	v_mul_f32_e32 v3, v9, v2
	global_store_dword v[0:1], v3, off
	v_mul_f32_e32 v3, v25, v2
	global_store_dword v[0:1], v3, off offset:128
	v_mul_f32_e32 v3, v41, v2
	v_mul_f32_e32 v2, v57, v2
	global_store_dword v[0:1], v3, off offset:256
	global_store_dword v[0:1], v2, off offset:384
	ds_read_b32 v0, v96 offset:72
	ds_read_b32 v1, v106 offset:72
	s_waitcnt lgkmcnt(1)
	v_max_f32_e64 v0, |v0|, |v0|
	s_waitcnt lgkmcnt(0)
	v_max_f32_e32 v0, v0, v1
	v_div_scale_f32 v1, s[0:1], v0, v0, 1.0
	v_rcp_f32_e32 v2, v1
	s_nop 0
	v_fma_f32 v3, -v1, v2, 1.0
	v_fmac_f32_e32 v2, v3, v2
	v_div_scale_f32 v3, vcc, 1.0, v0, 1.0
	v_mul_f32_e32 v4, v3, v2
	v_fma_f32 v5, -v1, v4, v3
	v_fmac_f32_e32 v4, v5, v2
	v_fma_f32 v1, -v1, v4, v3
	v_div_fmas_f32 v1, v1, v2, v4
	v_div_fixup_f32 v2, v1, v0, 1.0
	v_add_u32_e32 v0, 18, v100
	v_ashrrev_i32_e32 v1, 31, v0
	v_lshlrev_b64 v[0:1], 11, v[0:1]
	v_lshl_add_u64 v[0:1], v[98:99], 0, v[0:1]
	v_mul_f32_e32 v3, v10, v2
	global_store_dword v[0:1], v3, off
	v_mul_f32_e32 v3, v26, v2
	global_store_dword v[0:1], v3, off offset:128
	v_mul_f32_e32 v3, v42, v2
	v_mul_f32_e32 v2, v58, v2
	global_store_dword v[0:1], v3, off offset:256
	global_store_dword v[0:1], v2, off offset:384
	ds_read_b32 v0, v96 offset:76
	ds_read_b32 v1, v106 offset:76
	s_waitcnt lgkmcnt(1)
	v_max_f32_e64 v0, |v0|, |v0|
	s_waitcnt lgkmcnt(0)
	v_max_f32_e32 v0, v0, v1
	v_div_scale_f32 v1, s[0:1], v0, v0, 1.0
	v_rcp_f32_e32 v2, v1
	s_nop 0
	v_fma_f32 v3, -v1, v2, 1.0
	v_fmac_f32_e32 v2, v3, v2
	v_div_scale_f32 v3, vcc, 1.0, v0, 1.0
	v_mul_f32_e32 v4, v3, v2
	v_fma_f32 v5, -v1, v4, v3
	v_fmac_f32_e32 v4, v5, v2
	v_fma_f32 v1, -v1, v4, v3
	v_div_fmas_f32 v1, v1, v2, v4
	v_div_fixup_f32 v2, v1, v0, 1.0
	v_add_u32_e32 v0, 19, v100
	v_ashrrev_i32_e32 v1, 31, v0
	v_lshlrev_b64 v[0:1], 11, v[0:1]
	v_lshl_add_u64 v[0:1], v[98:99], 0, v[0:1]
	v_mul_f32_e32 v3, v11, v2
	global_store_dword v[0:1], v3, off
	v_mul_f32_e32 v3, v27, v2
	global_store_dword v[0:1], v3, off offset:128
	v_mul_f32_e32 v3, v43, v2
	v_mul_f32_e32 v2, v59, v2
	global_store_dword v[0:1], v3, off offset:256
	global_store_dword v[0:1], v2, off offset:384
	ds_read_b32 v0, v96 offset:96
	ds_read_b32 v1, v106 offset:96
	s_waitcnt lgkmcnt(1)
	v_max_f32_e64 v0, |v0|, |v0|
	s_waitcnt lgkmcnt(0)
	v_max_f32_e32 v0, v0, v1
	v_div_scale_f32 v1, s[0:1], v0, v0, 1.0
	v_rcp_f32_e32 v2, v1
	s_nop 0
	v_fma_f32 v3, -v1, v2, 1.0
	v_fmac_f32_e32 v2, v3, v2
	v_div_scale_f32 v3, vcc, 1.0, v0, 1.0
	v_mul_f32_e32 v4, v3, v2
	v_fma_f32 v5, -v1, v4, v3
	v_fmac_f32_e32 v4, v5, v2
	v_fma_f32 v1, -v1, v4, v3
	v_div_fmas_f32 v1, v1, v2, v4
	v_div_fixup_f32 v2, v1, v0, 1.0
	v_add_u32_e32 v0, 24, v100
	v_ashrrev_i32_e32 v1, 31, v0
	v_lshlrev_b64 v[0:1], 11, v[0:1]
	v_lshl_add_u64 v[0:1], v[98:99], 0, v[0:1]
	v_mul_f32_e32 v3, v12, v2
	global_store_dword v[0:1], v3, off
	v_mul_f32_e32 v3, v28, v2
	global_store_dword v[0:1], v3, off offset:128
	v_mul_f32_e32 v3, v44, v2
	v_mul_f32_e32 v2, v60, v2
	global_store_dword v[0:1], v3, off offset:256
	global_store_dword v[0:1], v2, off offset:384
	ds_read_b32 v0, v96 offset:100
	ds_read_b32 v1, v106 offset:100
	s_waitcnt lgkmcnt(1)
	v_max_f32_e64 v0, |v0|, |v0|
	s_waitcnt lgkmcnt(0)
	v_max_f32_e32 v0, v0, v1
	v_div_scale_f32 v1, s[0:1], v0, v0, 1.0
	v_rcp_f32_e32 v2, v1
	s_nop 0
	v_fma_f32 v3, -v1, v2, 1.0
	v_fmac_f32_e32 v2, v3, v2
	v_div_scale_f32 v3, vcc, 1.0, v0, 1.0
	v_mul_f32_e32 v4, v3, v2
	v_fma_f32 v5, -v1, v4, v3
	v_fmac_f32_e32 v4, v5, v2
	v_fma_f32 v1, -v1, v4, v3
	v_div_fmas_f32 v1, v1, v2, v4
	v_div_fixup_f32 v2, v1, v0, 1.0
	v_add_u32_e32 v0, 25, v100
	v_ashrrev_i32_e32 v1, 31, v0
	v_lshlrev_b64 v[0:1], 11, v[0:1]
	v_lshl_add_u64 v[0:1], v[98:99], 0, v[0:1]
	v_mul_f32_e32 v3, v13, v2
	global_store_dword v[0:1], v3, off
	v_mul_f32_e32 v3, v29, v2
	global_store_dword v[0:1], v3, off offset:128
	v_mul_f32_e32 v3, v45, v2
	v_mul_f32_e32 v2, v61, v2
	global_store_dword v[0:1], v3, off offset:256
	global_store_dword v[0:1], v2, off offset:384
	ds_read_b32 v0, v96 offset:104
	ds_read_b32 v1, v106 offset:104
	s_waitcnt lgkmcnt(1)
	v_max_f32_e64 v0, |v0|, |v0|
	s_waitcnt lgkmcnt(0)
	v_max_f32_e32 v0, v0, v1
	v_div_scale_f32 v1, s[0:1], v0, v0, 1.0
	v_rcp_f32_e32 v2, v1
	s_nop 0
	v_fma_f32 v3, -v1, v2, 1.0
	v_fmac_f32_e32 v2, v3, v2
	v_div_scale_f32 v3, vcc, 1.0, v0, 1.0
	v_mul_f32_e32 v4, v3, v2
	v_fma_f32 v5, -v1, v4, v3
	v_fmac_f32_e32 v4, v5, v2
	v_fma_f32 v1, -v1, v4, v3
	v_div_fmas_f32 v1, v1, v2, v4
	v_div_fixup_f32 v2, v1, v0, 1.0
	v_add_u32_e32 v0, 26, v100
	v_ashrrev_i32_e32 v1, 31, v0
	v_lshlrev_b64 v[0:1], 11, v[0:1]
	v_lshl_add_u64 v[0:1], v[98:99], 0, v[0:1]
	v_mul_f32_e32 v3, v14, v2
	global_store_dword v[0:1], v3, off
	v_mul_f32_e32 v3, v30, v2
	global_store_dword v[0:1], v3, off offset:128
	v_mul_f32_e32 v3, v46, v2
	v_mul_f32_e32 v2, v62, v2
	global_store_dword v[0:1], v3, off offset:256
	global_store_dword v[0:1], v2, off offset:384
	ds_read_b32 v0, v106 offset:108
	ds_read_b32 v1, v96 offset:108
	s_waitcnt lgkmcnt(1)
	s_waitcnt lgkmcnt(0)
	v_max_f32_e64 v1, |v1|, |v1|
	v_max_f32_e32 v1, v1, v0
	v_div_scale_f32 v2, s[0:1], v1, v1, 1.0
	v_rcp_f32_e32 v3, v2
	v_div_scale_f32 v4, vcc, 1.0, v1, 1.0
	v_add_u32_e32 v0, 27, v100
	v_fma_f32 v5, -v2, v3, 1.0
	v_fmac_f32_e32 v3, v5, v3
	v_mul_f32_e32 v5, v4, v3
	v_fma_f32 v6, -v2, v5, v4
	v_fmac_f32_e32 v5, v6, v3
	v_fma_f32 v2, -v2, v5, v4
	v_div_fmas_f32 v2, v2, v3, v5
	v_div_fixup_f32 v2, v2, v1, 1.0
	v_ashrrev_i32_e32 v1, 31, v0
	v_lshlrev_b64 v[0:1], 11, v[0:1]
	v_lshl_add_u64 v[0:1], v[98:99], 0, v[0:1]
	v_mul_f32_e32 v3, v15, v2
	global_store_dword v[0:1], v3, off
	v_mul_f32_e32 v3, v31, v2
	global_store_dword v[0:1], v3, off offset:128
	v_mul_f32_e32 v3, v47, v2
	v_mul_f32_e32 v2, v63, v2
	global_store_dword v[0:1], v3, off offset:256
	global_store_dword v[0:1], v2, off offset:384
	s_branch .LBB0_927
